# baseline (speedup 1.0000x reference)
; __device__ __forceinline__ void gemm_run(int tid, f32x16 (&acc)[2][2], GRegs& g, const GOp& o, int K, unsigned char* smem) {
;     ...
;   const int nk = K >> 6;
; #pragma unroll
;   for (int i = 0; i < 4; i++) {
;     *(u32x4*)(sbuf + (r0 + i * 32) * LDK + sg * 8) = g.a[i];
;     *(u32x4*)(sbuf + 128 * LDK + (r0 + i * 32) * LDK + sg * 8) = g.b[i];
;   }
;   if (nk > 1) {
; #pragma unroll
;     for (int i = 0; i < 4; i++) {
;       g.a[i] = *(const u32x4*)(Ap + (size_t)i * 32 * o.lda + 64);
;       g.b[i] = *(const u32x4*)(Bp + o.bs.o[i] + 64);
;     }
;   }
;   __syncthreads();
;   const int lane = tid & 63, fr = lane & 31, fh = lane >> 5;
;   for (int k = 0; k < nk; k++) {
;     bf16r* cur = sbuf + (k & 1) * (256 * LDK);
;     bf16r* nxt = sbuf + ((k & 1) ^ 1) * (256 * LDK);
;     const bf16r* As = cur + (wm * 64 + fr) * LDK + fh * 8;
;     const bf16r* Bs = cur + 128 * LDK + (wn * 64 + fr) * LDK + fh * 8;
;     const bool wr = (k + 1 < nk), ld = (k + 2 < nk);
;     bf16x8 fa[2][2], fb[2][2];
;     fa[0][0] = *(const bf16x8*)(As);
;     fa[0][1] = *(const bf16x8*)(As + 32 * LDK);
;     fb[0][0] = *(const bf16x8*)(Bs);
;     fb[0][1] = *(const bf16x8*)(Bs + 32 * LDK);
; #pragma unroll
;     for (int i = 0; i < 4; i++) {
;       if (wr) {
;         *(u32x4*)(nxt + (r0 + i * 32) * LDK + sg * 8) = g.a[i];
;         *(u32x4*)(nxt + 128 * LDK + (r0 + i * 32) * LDK + sg * 8) = g.b[i];
;       }
;       if (ld) {
;         g.a[i] = *(const u32x4*)(Ap + (size_t)i * 32 * o.lda + (k + 2) * 64);
;         g.b[i] = *(const u32x4*)(Bp + o.bs.o[i] + (k + 2) * 64);
;       }
;       if (i < 3) {
;         fa[(i + 1) & 1][0] = *(const bf16x8*)(As + (i + 1) * 16);
;         fa[(i + 1) & 1][1] = *(const bf16x8*)(As + 32 * LDK + (i + 1) * 16);
;         fb[(i + 1) & 1][0] = *(const bf16x8*)(Bs + (i + 1) * 16);
;         fb[(i + 1) & 1][1] = *(const bf16x8*)(Bs + 32 * LDK + (i + 1) * 16);
;       }
;       __builtin_amdgcn_sched_barrier(0);
;       __builtin_amdgcn_s_setprio(1);
;       acc[0][0] = __builtin_amdgcn_mfma_f32_32x32x16_bf16(fa[i & 1][0], fb[i & 1][0], acc[0][0], 0, 0, 0);
;       acc[0][1] = __builtin_amdgcn_mfma_f32_32x32x16_bf16(fa[i & 1][0], fb[i & 1][1], acc[0][1], 0, 0, 0);
;       acc[1][0] = __builtin_amdgcn_mfma_f32_32x32x16_bf16(fa[i & 1][1], fb[i & 1][0], acc[1][0], 0, 0, 0);
.LBB0_147:
	s_ashr_i32 s7, s6, 31
	s_lshl_b64 s[0:1], s[6:7], 18
	s_ashr_i32 s9, s8, 31
	s_waitcnt vmcnt(7)
	ds_write_b128 v100, v[64:67]
	s_waitcnt vmcnt(6)
	ds_write_b128 v100, v[68:71] offset:18432
	s_waitcnt vmcnt(5)
	ds_write_b128 v100, v[72:75] offset:4608
	s_waitcnt vmcnt(4)
	ds_write_b128 v100, v[76:79] offset:23040
	s_waitcnt vmcnt(3)
	ds_write_b128 v100, v[80:83] offset:9216
	s_waitcnt vmcnt(2)
	ds_write_b128 v100, v[84:87] offset:27648
	s_waitcnt vmcnt(1)
	ds_write_b128 v100, v[88:91] offset:13824
	s_waitcnt vmcnt(0)
	ds_write_b128 v100, v[92:95] offset:32256
	v_lshl_add_u64 v[64:65], v[102:103], 0, s[0:1]
	s_lshl_b64 s[4:5], s[8:9], 18
	v_add_co_u32_e32 v72, vcc, s96, v64
	v_lshl_add_u64 v[106:107], v[98:99], 0, s[4:5]
	s_nop 0
	v_addc_co_u32_e32 v73, vcc, 0, v65, vcc
	v_add_co_u32_e32 v76, vcc, s96, v106
	global_load_dwordx4 v[0:3], v[64:65], off offset:128
	global_load_dwordx4 v[4:7], v[106:107], off offset:128
	v_addc_co_u32_e32 v77, vcc, 0, v107, vcc
	v_add_co_u32_e32 v80, vcc, s97, v64
	global_load_dwordx4 v[66:69], v[72:73], off offset:128
	global_load_dwordx4 v[110:113], v[76:77], off offset:128
	v_addc_co_u32_e32 v81, vcc, 0, v65, vcc
	v_add_co_u32_e32 v84, vcc, s97, v106
	s_nop 1
	v_addc_co_u32_e32 v85, vcc, 0, v107, vcc
	v_add_co_u32_e32 v88, vcc, s42, v64
	global_load_dwordx4 v[114:117], v[80:81], off offset:128
	global_load_dwordx4 v[118:121], v[84:85], off offset:128
	v_addc_co_u32_e32 v89, vcc, 0, v65, vcc
	v_add_co_u32_e32 v92, vcc, s42, v106
	s_nop 1
	v_addc_co_u32_e32 v93, vcc, 0, v107, vcc
	global_load_dwordx4 v[122:125], v[88:89], off offset:128
	global_load_dwordx4 v[126:129], v[92:93], off offset:128
	s_waitcnt lgkmcnt(0)
	s_barrier
	global_load_dwordx4 v[130:133], v[64:65], off offset:256
	global_load_dwordx4 v[134:137], v[106:107], off offset:256
	ds_read_b128 v[8:11], v104
	ds_read_b128 v[32:35], v104 offset:4608
	ds_read_b128 v[12:15], v101 offset:18432
	ds_read_b128 v[36:39], v101 offset:23040
	s_waitcnt vmcnt(9)
	ds_write_b128 v100, v[0:3] offset:36864
	s_waitcnt vmcnt(8)
	ds_write_b128 v100, v[4:7] offset:55296
	ds_read_b128 v[138:141], v104 offset:32
	ds_read_b128 v[142:145], v104 offset:4640
	ds_read_b128 v[146:149], v101 offset:18464
	ds_read_b128 v[150:153], v101 offset:23072
	s_waitcnt lgkmcnt(7)
	v_mfma_f32_32x32x16_bf16 v[16:31], v[8:11], v[12:15], 0
	s_waitcnt lgkmcnt(6)
	v_mfma_f32_32x32x16_bf16 v[48:63], v[8:11], v[36:39], 0
	v_mfma_f32_32x32x16_bf16 v[0:15], v[32:35], v[12:15], 0
	v_mfma_f32_32x32x16_bf16 v[32:47], v[32:35], v[36:39], 0
	global_load_dwordx4 v[154:157], v[72:73], off offset:256
	global_load_dwordx4 v[158:161], v[76:77], off offset:256
	s_waitcnt vmcnt(9)
	ds_write_b128 v100, v[66:69] offset:41472
	s_waitcnt vmcnt(8)
	ds_write_b128 v100, v[110:113] offset:59904
	ds_read_b128 v[66:69], v104 offset:64
	ds_read_b128 v[110:113], v104 offset:4672
	ds_read_b128 v[162:165], v101 offset:18496
	ds_read_b128 v[166:169], v101 offset:23104
	s_waitcnt lgkmcnt(7)
	v_mfma_f32_32x32x16_bf16 v[16:31], v[138:141], v[146:149], v[16:31]
	s_waitcnt lgkmcnt(6)
	v_mfma_f32_32x32x16_bf16 v[48:63], v[138:141], v[150:153], v[48:63]
	v_mfma_f32_32x32x16_bf16 v[0:15], v[142:145], v[146:149], v[0:15]
	v_mfma_f32_32x32x16_bf16 v[32:47], v[142:145], v[150:153], v[32:47]
	global_load_dwordx4 v[138:141], v[80:81], off offset:256
	global_load_dwordx4 v[142:145], v[84:85], off offset:256
	s_waitcnt vmcnt(9)
	ds_write_b128 v100, v[114:117] offset:46080
	s_waitcnt vmcnt(8)
	ds_write_b128 v100, v[118:121] offset:64512
	ds_read_b128 v[114:117], v104 offset:96
	ds_read_b128 v[118:121], v104 offset:4704
	ds_read_b128 v[146:149], v101 offset:18528
	ds_read_b128 v[150:153], v101 offset:23136
	s_waitcnt lgkmcnt(7)
	v_mfma_f32_32x32x16_bf16 v[16:31], v[66:69], v[162:165], v[16:31]
	s_waitcnt lgkmcnt(6)
	v_mfma_f32_32x32x16_bf16 v[48:63], v[66:69], v[166:169], v[48:63]
	v_mfma_f32_32x32x16_bf16 v[0:15], v[110:113], v[162:165], v[0:15]
	v_mfma_f32_32x32x16_bf16 v[32:47], v[110:113], v[166:169], v[32:47]
	global_load_dwordx4 v[66:69], v[88:89], off offset:256
	global_load_dwordx4 v[110:113], v[92:93], off offset:256
	s_waitcnt vmcnt(9)
	ds_write_b128 v100, v[122:125] offset:50688
	s_waitcnt vmcnt(8)
	ds_write_b128 v105, v[126:129] offset:13824
	s_waitcnt lgkmcnt(3)
	v_mfma_f32_32x32x16_bf16 v[16:31], v[114:117], v[146:149], v[16:31]
	s_waitcnt lgkmcnt(2)
	v_mfma_f32_32x32x16_bf16 v[48:63], v[114:117], v[150:153], v[48:63]
	v_mfma_f32_32x32x16_bf16 v[0:15], v[118:121], v[146:149], v[0:15]
	v_mfma_f32_32x32x16_bf16 v[32:47], v[118:121], v[150:153], v[32:47]
	s_waitcnt lgkmcnt(0)
	s_barrier
; __device__ __forceinline__ void gemm_run(int tid, f32x16 (&acc)[2][2], GRegs& g, const GOp& o, int K, unsigned char* smem) {
;     ...
;   for (int k = 0; k < nk; k++) {
;     bf16r* cur = sbuf + (k & 1) * (256 * LDK);
;     bf16r* nxt = sbuf + ((k & 1) ^ 1) * (256 * LDK);
;     const bf16r* As = cur + (wm * 64 + fr) * LDK + fh * 8;
;     const bf16r* Bs = cur + 128 * LDK + (wn * 64 + fr) * LDK + fh * 8;
;     const bool wr = (k + 1 < nk), ld = (k + 2 < nk);
;     bf16x8 fa[2][2], fb[2][2];
;     fa[0][0] = *(const bf16x8*)(As);
;     fa[0][1] = *(const bf16x8*)(As + 32 * LDK);
;     fb[0][0] = *(const bf16x8*)(Bs);
;     fb[0][1] = *(const bf16x8*)(Bs + 32 * LDK);
; #pragma unroll
;     for (int i = 0; i < 4; i++) {
;       if (wr) {
;         *(u32x4*)(nxt + (r0 + i * 32) * LDK + sg * 8) = g.a[i];
;         *(u32x4*)(nxt + 128 * LDK + (r0 + i * 32) * LDK + sg * 8) = g.b[i];
;       }
;       if (ld) {
;         g.a[i] = *(const u32x4*)(Ap + (size_t)i * 32 * o.lda + (k + 2) * 64);
;         g.b[i] = *(const u32x4*)(Bp + o.bs.o[i] + (k + 2) * 64);
;       }
;       if (i < 3) {
;         fa[(i + 1) & 1][0] = *(const bf16x8*)(As + (i + 1) * 16);
;         fa[(i + 1) & 1][1] = *(const bf16x8*)(As + 32 * LDK + (i + 1) * 16);
;         fb[(i + 1) & 1][0] = *(const bf16x8*)(Bs + (i + 1) * 16);
;         fb[(i + 1) & 1][1] = *(const bf16x8*)(Bs + 32 * LDK + (i + 1) * 16);
;       }
;       __builtin_amdgcn_sched_barrier(0);
;       __builtin_amdgcn_s_setprio(1);
;       acc[0][0] = __builtin_amdgcn_mfma_f32_32x32x16_bf16(fa[i & 1][0], fb[i & 1][0], acc[0][0], 0, 0, 0);
;       acc[0][1] = __builtin_amdgcn_mfma_f32_32x32x16_bf16(fa[i & 1][0], fb[i & 1][1], acc[0][1], 0, 0, 0);
;       acc[1][0] = __builtin_amdgcn_mfma_f32_32x32x16_bf16(fa[i & 1][1], fb[i & 1][0], acc[1][0], 0, 0, 0);
;       acc[1][1] = __builtin_amdgcn_mfma_f32_32x32x16_bf16(fa[i & 1][1], fb[i & 1][1], acc[1][1], 0, 0, 0);
;       __builtin_amdgcn_s_setprio(0);
;     }
;     __syncthreads();
	global_load_dwordx4 v[114:117], v[64:65], off offset:384
	global_load_dwordx4 v[118:121], v[106:107], off offset:384
	ds_read_b128 v[122:125], v104 offset:36864
	ds_read_b128 v[126:129], v104 offset:41472
	ds_read_b128 v[146:149], v101 offset:55296
	ds_read_b128 v[150:153], v101 offset:59904
	s_waitcnt vmcnt(9)
	ds_write_b128 v100, v[130:133]
	s_waitcnt vmcnt(8)
	ds_write_b128 v100, v[134:137] offset:18432
	ds_read_b128 v[130:133], v104 offset:36896
	ds_read_b128 v[134:137], v104 offset:41504
	ds_read_b128 v[162:165], v101 offset:55328
	ds_read_b128 v[166:169], v101 offset:59936
	s_waitcnt lgkmcnt(7)
	v_mfma_f32_32x32x16_bf16 v[16:31], v[122:125], v[146:149], v[16:31]
	s_waitcnt lgkmcnt(6)
	v_mfma_f32_32x32x16_bf16 v[48:63], v[122:125], v[150:153], v[48:63]
	v_mfma_f32_32x32x16_bf16 v[0:15], v[126:129], v[146:149], v[0:15]
	v_mfma_f32_32x32x16_bf16 v[32:47], v[126:129], v[150:153], v[32:47]
	global_load_dwordx4 v[122:125], v[72:73], off offset:384
	global_load_dwordx4 v[126:129], v[76:77], off offset:384
	s_waitcnt vmcnt(9)
	ds_write_b128 v100, v[154:157] offset:4608
	s_waitcnt vmcnt(8)
	ds_write_b128 v100, v[158:161] offset:23040
	ds_read_b128 v[146:149], v104 offset:36928
	ds_read_b128 v[150:153], v104 offset:41536
	ds_read_b128 v[154:157], v101 offset:55360
	ds_read_b128 v[158:161], v101 offset:59968
	s_waitcnt lgkmcnt(7)
	v_mfma_f32_32x32x16_bf16 v[16:31], v[130:133], v[162:165], v[16:31]
	s_waitcnt lgkmcnt(6)
	v_mfma_f32_32x32x16_bf16 v[48:63], v[130:133], v[166:169], v[48:63]
	v_mfma_f32_32x32x16_bf16 v[0:15], v[134:137], v[162:165], v[0:15]
	v_mfma_f32_32x32x16_bf16 v[32:47], v[134:137], v[166:169], v[32:47]
	global_load_dwordx4 v[130:133], v[80:81], off offset:384
	global_load_dwordx4 v[134:137], v[84:85], off offset:384
	s_waitcnt vmcnt(9)
	ds_write_b128 v100, v[138:141] offset:9216
	s_waitcnt vmcnt(8)
	ds_write_b128 v100, v[142:145] offset:27648
	ds_read_b128 v[138:141], v104 offset:36960
	ds_read_b128 v[142:145], v104 offset:41568
	ds_read_b128 v[162:165], v101 offset:55392
	ds_read_b128 v[166:169], v101 offset:60000
	s_waitcnt lgkmcnt(7)
	v_mfma_f32_32x32x16_bf16 v[16:31], v[146:149], v[154:157], v[16:31]
	s_waitcnt lgkmcnt(6)
	v_mfma_f32_32x32x16_bf16 v[48:63], v[146:149], v[158:161], v[48:63]
	v_mfma_f32_32x32x16_bf16 v[0:15], v[150:153], v[154:157], v[0:15]
	v_mfma_f32_32x32x16_bf16 v[32:47], v[150:153], v[158:161], v[32:47]
	global_load_dwordx4 v[146:149], v[88:89], off offset:384
	global_load_dwordx4 v[150:153], v[92:93], off offset:384
	s_waitcnt vmcnt(9)
	ds_write_b128 v100, v[66:69] offset:13824
	s_waitcnt vmcnt(8)
	ds_write_b128 v100, v[110:113] offset:32256
	s_waitcnt lgkmcnt(3)
	v_mfma_f32_32x32x16_bf16 v[16:31], v[138:141], v[162:165], v[16:31]
	s_waitcnt lgkmcnt(2)
	v_mfma_f32_32x32x16_bf16 v[48:63], v[138:141], v[166:169], v[48:63]
	v_mfma_f32_32x32x16_bf16 v[0:15], v[142:145], v[162:165], v[0:15]
	v_mfma_f32_32x32x16_bf16 v[32:47], v[142:145], v[166:169], v[32:47]
	s_waitcnt lgkmcnt(0)
	s_barrier
	global_load_dwordx4 v[66:69], v[64:65], off offset:512
	global_load_dwordx4 v[110:113], v[106:107], off offset:512
	ds_read_b128 v[138:141], v104
	ds_read_b128 v[142:145], v104 offset:4608
	ds_read_b128 v[154:157], v101 offset:18432
	ds_read_b128 v[158:161], v101 offset:23040
	s_waitcnt vmcnt(9)
	ds_write_b128 v100, v[114:117] offset:36864
	s_waitcnt vmcnt(8)
	ds_write_b128 v100, v[118:121] offset:55296
	ds_read_b128 v[114:117], v104 offset:32
	ds_read_b128 v[118:121], v104 offset:4640
	ds_read_b128 v[162:165], v101 offset:18464
	ds_read_b128 v[166:169], v101 offset:23072
	s_waitcnt lgkmcnt(7)
	v_mfma_f32_32x32x16_bf16 v[16:31], v[138:141], v[154:157], v[16:31]
	s_waitcnt lgkmcnt(6)
	v_mfma_f32_32x32x16_bf16 v[48:63], v[138:141], v[158:161], v[48:63]
	v_mfma_f32_32x32x16_bf16 v[0:15], v[142:145], v[154:157], v[0:15]
	v_mfma_f32_32x32x16_bf16 v[32:47], v[142:145], v[158:161], v[32:47]
	global_load_dwordx4 v[138:141], v[72:73], off offset:512
	global_load_dwordx4 v[142:145], v[76:77], off offset:512
	s_waitcnt vmcnt(9)
	ds_write_b128 v100, v[122:125] offset:41472
	s_waitcnt vmcnt(8)
	ds_write_b128 v100, v[126:129] offset:59904
	ds_read_b128 v[122:125], v104 offset:64
	ds_read_b128 v[126:129], v104 offset:4672
	ds_read_b128 v[154:157], v101 offset:18496
	ds_read_b128 v[158:161], v101 offset:23104
	s_waitcnt lgkmcnt(7)
	v_mfma_f32_32x32x16_bf16 v[16:31], v[114:117], v[162:165], v[16:31]
	s_waitcnt lgkmcnt(6)
	v_mfma_f32_32x32x16_bf16 v[48:63], v[114:117], v[166:169], v[48:63]
	v_mfma_f32_32x32x16_bf16 v[0:15], v[118:121], v[162:165], v[0:15]
	v_mfma_f32_32x32x16_bf16 v[32:47], v[118:121], v[166:169], v[32:47]
	global_load_dwordx4 v[114:117], v[80:81], off offset:512
	global_load_dwordx4 v[118:121], v[84:85], off offset:512
	s_waitcnt vmcnt(9)
	ds_write_b128 v100, v[130:133] offset:46080
	s_waitcnt vmcnt(8)
	ds_write_b128 v100, v[134:137] offset:64512
	ds_read_b128 v[130:133], v104 offset:96
	ds_read_b128 v[134:137], v104 offset:4704
	ds_read_b128 v[162:165], v101 offset:18528
	ds_read_b128 v[166:169], v101 offset:23136
	s_waitcnt lgkmcnt(7)
	v_mfma_f32_32x32x16_bf16 v[16:31], v[122:125], v[154:157], v[16:31]
	s_waitcnt lgkmcnt(6)
	v_mfma_f32_32x32x16_bf16 v[48:63], v[122:125], v[158:161], v[48:63]
	v_mfma_f32_32x32x16_bf16 v[0:15], v[126:129], v[154:157], v[0:15]
	v_mfma_f32_32x32x16_bf16 v[32:47], v[126:129], v[158:161], v[32:47]
	global_load_dwordx4 v[122:125], v[88:89], off offset:512
	global_load_dwordx4 v[126:129], v[92:93], off offset:512
	s_waitcnt vmcnt(9)
	ds_write_b128 v100, v[146:149] offset:50688
	s_waitcnt vmcnt(8)
	ds_write_b128 v105, v[150:153] offset:13824
	s_waitcnt lgkmcnt(3)
	v_mfma_f32_32x32x16_bf16 v[16:31], v[130:133], v[162:165], v[16:31]
	s_waitcnt lgkmcnt(2)
	v_mfma_f32_32x32x16_bf16 v[48:63], v[130:133], v[166:169], v[48:63]
	v_mfma_f32_32x32x16_bf16 v[0:15], v[134:137], v[162:165], v[0:15]
	v_mfma_f32_32x32x16_bf16 v[32:47], v[134:137], v[166:169], v[32:47]
	s_waitcnt lgkmcnt(0)
	s_barrier
; __device__ __forceinline__ void gemm_run(int tid, f32x16 (&acc)[2][2], GRegs& g, const GOp& o, int K, unsigned char* smem) {
;     ...
;   for (int k = 0; k < nk; k++) {
;     bf16r* cur = sbuf + (k & 1) * (256 * LDK);
;     bf16r* nxt = sbuf + ((k & 1) ^ 1) * (256 * LDK);
;     const bf16r* As = cur + (wm * 64 + fr) * LDK + fh * 8;
;     const bf16r* Bs = cur + 128 * LDK + (wn * 64 + fr) * LDK + fh * 8;
;     const bool wr = (k + 1 < nk), ld = (k + 2 < nk);
;     bf16x8 fa[2][2], fb[2][2];
;     fa[0][0] = *(const bf16x8*)(As);
;     fa[0][1] = *(const bf16x8*)(As + 32 * LDK);
;     fb[0][0] = *(const bf16x8*)(Bs);
;     fb[0][1] = *(const bf16x8*)(Bs + 32 * LDK);
; #pragma unroll
;     for (int i = 0; i < 4; i++) {
;       if (wr) {
;         *(u32x4*)(nxt + (r0 + i * 32) * LDK + sg * 8) = g.a[i];
;         *(u32x4*)(nxt + 128 * LDK + (r0 + i * 32) * LDK + sg * 8) = g.b[i];
;       }
;       if (ld) {
;         g.a[i] = *(const u32x4*)(Ap + (size_t)i * 32 * o.lda + (k + 2) * 64);
;         g.b[i] = *(const u32x4*)(Bp + o.bs.o[i] + (k + 2) * 64);
;       }
;       if (i < 3) {
;         fa[(i + 1) & 1][0] = *(const bf16x8*)(As + (i + 1) * 16);
;         fa[(i + 1) & 1][1] = *(const bf16x8*)(As + 32 * LDK + (i + 1) * 16);
;         fb[(i + 1) & 1][0] = *(const bf16x8*)(Bs + (i + 1) * 16);
;         fb[(i + 1) & 1][1] = *(const bf16x8*)(Bs + 32 * LDK + (i + 1) * 16);
;       }
;       __builtin_amdgcn_sched_barrier(0);
;       __builtin_amdgcn_s_setprio(1);
;       acc[0][0] = __builtin_amdgcn_mfma_f32_32x32x16_bf16(fa[i & 1][0], fb[i & 1][0], acc[0][0], 0, 0, 0);
;       acc[0][1] = __builtin_amdgcn_mfma_f32_32x32x16_bf16(fa[i & 1][0], fb[i & 1][1], acc[0][1], 0, 0, 0);
;       acc[1][0] = __builtin_amdgcn_mfma_f32_32x32x16_bf16(fa[i & 1][1], fb[i & 1][0], acc[1][0], 0, 0, 0);
;       acc[1][1] = __builtin_amdgcn_mfma_f32_32x32x16_bf16(fa[i & 1][1], fb[i & 1][1], acc[1][1], 0, 0, 0);
;       __builtin_amdgcn_s_setprio(0);
;     }
;     __syncthreads();
	global_load_dwordx4 v[130:133], v[64:65], off offset:640
	global_load_dwordx4 v[134:137], v[106:107], off offset:640
	ds_read_b128 v[146:149], v104 offset:36864
	ds_read_b128 v[150:153], v104 offset:41472
	ds_read_b128 v[154:157], v101 offset:55296
	ds_read_b128 v[158:161], v101 offset:59904
	s_waitcnt vmcnt(9)
	ds_write_b128 v100, v[66:69]
	s_waitcnt vmcnt(8)
	ds_write_b128 v100, v[110:113] offset:18432
	ds_read_b128 v[66:69], v104 offset:36896
	ds_read_b128 v[110:113], v104 offset:41504
	ds_read_b128 v[162:165], v101 offset:55328
	ds_read_b128 v[166:169], v101 offset:59936
	s_waitcnt lgkmcnt(7)
	v_mfma_f32_32x32x16_bf16 v[16:31], v[146:149], v[154:157], v[16:31]
	s_waitcnt lgkmcnt(6)
	v_mfma_f32_32x32x16_bf16 v[48:63], v[146:149], v[158:161], v[48:63]
	v_mfma_f32_32x32x16_bf16 v[0:15], v[150:153], v[154:157], v[0:15]
	v_mfma_f32_32x32x16_bf16 v[32:47], v[150:153], v[158:161], v[32:47]
	global_load_dwordx4 v[146:149], v[72:73], off offset:640
	global_load_dwordx4 v[150:153], v[76:77], off offset:640
	s_waitcnt vmcnt(9)
	ds_write_b128 v100, v[138:141] offset:4608
	s_waitcnt vmcnt(8)
	ds_write_b128 v100, v[142:145] offset:23040
	ds_read_b128 v[138:141], v104 offset:36928
	ds_read_b128 v[142:145], v104 offset:41536
	ds_read_b128 v[154:157], v101 offset:55360
	ds_read_b128 v[158:161], v101 offset:59968
	s_waitcnt lgkmcnt(7)
	v_mfma_f32_32x32x16_bf16 v[16:31], v[66:69], v[162:165], v[16:31]
	s_waitcnt lgkmcnt(6)
	v_mfma_f32_32x32x16_bf16 v[48:63], v[66:69], v[166:169], v[48:63]
	v_mfma_f32_32x32x16_bf16 v[0:15], v[110:113], v[162:165], v[0:15]
	v_mfma_f32_32x32x16_bf16 v[32:47], v[110:113], v[166:169], v[32:47]
	global_load_dwordx4 v[66:69], v[80:81], off offset:640
	global_load_dwordx4 v[110:113], v[84:85], off offset:640
	s_waitcnt vmcnt(9)
	ds_write_b128 v100, v[114:117] offset:9216
	s_waitcnt vmcnt(8)
	ds_write_b128 v100, v[118:121] offset:27648
	ds_read_b128 v[114:117], v104 offset:36960
	ds_read_b128 v[118:121], v104 offset:41568
	ds_read_b128 v[162:165], v101 offset:55392
	ds_read_b128 v[166:169], v101 offset:60000
	s_waitcnt lgkmcnt(7)
	v_mfma_f32_32x32x16_bf16 v[16:31], v[138:141], v[154:157], v[16:31]
	s_waitcnt lgkmcnt(6)
	v_mfma_f32_32x32x16_bf16 v[48:63], v[138:141], v[158:161], v[48:63]
	v_mfma_f32_32x32x16_bf16 v[0:15], v[142:145], v[154:157], v[0:15]
	v_mfma_f32_32x32x16_bf16 v[32:47], v[142:145], v[158:161], v[32:47]
	global_load_dwordx4 v[138:141], v[88:89], off offset:640
	global_load_dwordx4 v[142:145], v[92:93], off offset:640
	s_waitcnt vmcnt(9)
	ds_write_b128 v100, v[122:125] offset:13824
	s_waitcnt vmcnt(8)
	ds_write_b128 v100, v[126:129] offset:32256
	s_waitcnt lgkmcnt(3)
	v_mfma_f32_32x32x16_bf16 v[16:31], v[114:117], v[162:165], v[16:31]
	s_waitcnt lgkmcnt(2)
	v_mfma_f32_32x32x16_bf16 v[48:63], v[114:117], v[166:169], v[48:63]
	v_mfma_f32_32x32x16_bf16 v[0:15], v[118:121], v[162:165], v[0:15]
	v_mfma_f32_32x32x16_bf16 v[32:47], v[118:121], v[166:169], v[32:47]
	s_waitcnt lgkmcnt(0)
	s_barrier
	global_load_dwordx4 v[114:117], v[64:65], off offset:768
	global_load_dwordx4 v[118:121], v[106:107], off offset:768
	ds_read_b128 v[122:125], v104
	ds_read_b128 v[126:129], v104 offset:4608
	ds_read_b128 v[154:157], v101 offset:18432
	ds_read_b128 v[158:161], v101 offset:23040
	s_waitcnt vmcnt(9)
	ds_write_b128 v100, v[130:133] offset:36864
	s_waitcnt vmcnt(8)
	ds_write_b128 v100, v[134:137] offset:55296
	ds_read_b128 v[130:133], v104 offset:32
	ds_read_b128 v[134:137], v104 offset:4640
	ds_read_b128 v[162:165], v101 offset:18464
	ds_read_b128 v[166:169], v101 offset:23072
	s_waitcnt lgkmcnt(7)
	v_mfma_f32_32x32x16_bf16 v[16:31], v[122:125], v[154:157], v[16:31]
	s_waitcnt lgkmcnt(6)
	v_mfma_f32_32x32x16_bf16 v[48:63], v[122:125], v[158:161], v[48:63]
	v_mfma_f32_32x32x16_bf16 v[0:15], v[126:129], v[154:157], v[0:15]
	v_mfma_f32_32x32x16_bf16 v[32:47], v[126:129], v[158:161], v[32:47]
	global_load_dwordx4 v[122:125], v[72:73], off offset:768
	global_load_dwordx4 v[126:129], v[76:77], off offset:768
	s_waitcnt vmcnt(9)
	ds_write_b128 v100, v[146:149] offset:41472
	s_waitcnt vmcnt(8)
	ds_write_b128 v100, v[150:153] offset:59904
	ds_read_b128 v[146:149], v104 offset:64
	ds_read_b128 v[150:153], v104 offset:4672
	ds_read_b128 v[154:157], v101 offset:18496
	ds_read_b128 v[158:161], v101 offset:23104
	s_waitcnt lgkmcnt(7)
	v_mfma_f32_32x32x16_bf16 v[16:31], v[130:133], v[162:165], v[16:31]
	s_waitcnt lgkmcnt(6)
	v_mfma_f32_32x32x16_bf16 v[48:63], v[130:133], v[166:169], v[48:63]
	v_mfma_f32_32x32x16_bf16 v[0:15], v[134:137], v[162:165], v[0:15]
	v_mfma_f32_32x32x16_bf16 v[32:47], v[134:137], v[166:169], v[32:47]
	global_load_dwordx4 v[130:133], v[80:81], off offset:768
	global_load_dwordx4 v[134:137], v[84:85], off offset:768
	s_waitcnt vmcnt(9)
	ds_write_b128 v100, v[66:69] offset:46080
	s_waitcnt vmcnt(8)
	ds_write_b128 v100, v[110:113] offset:64512
	ds_read_b128 v[66:69], v104 offset:96
	ds_read_b128 v[110:113], v104 offset:4704
	ds_read_b128 v[162:165], v101 offset:18528
	ds_read_b128 v[166:169], v101 offset:23136
	s_waitcnt lgkmcnt(7)
	v_mfma_f32_32x32x16_bf16 v[16:31], v[146:149], v[154:157], v[16:31]
	s_waitcnt lgkmcnt(6)
	v_mfma_f32_32x32x16_bf16 v[48:63], v[146:149], v[158:161], v[48:63]
	v_mfma_f32_32x32x16_bf16 v[0:15], v[150:153], v[154:157], v[0:15]
	v_mfma_f32_32x32x16_bf16 v[32:47], v[150:153], v[158:161], v[32:47]
	global_load_dwordx4 v[146:149], v[88:89], off offset:768
	global_load_dwordx4 v[150:153], v[92:93], off offset:768
	s_waitcnt vmcnt(9)
	ds_write_b128 v100, v[138:141] offset:50688
	s_waitcnt vmcnt(8)
	ds_write_b128 v105, v[142:145] offset:13824
	s_waitcnt lgkmcnt(3)
	v_mfma_f32_32x32x16_bf16 v[16:31], v[66:69], v[162:165], v[16:31]
	s_waitcnt lgkmcnt(2)
	v_mfma_f32_32x32x16_bf16 v[48:63], v[66:69], v[166:169], v[48:63]
	v_mfma_f32_32x32x16_bf16 v[0:15], v[110:113], v[162:165], v[0:15]
	v_mfma_f32_32x32x16_bf16 v[32:47], v[110:113], v[166:169], v[32:47]
	s_waitcnt lgkmcnt(0)
	s_barrier
; __device__ __forceinline__ void gemm_run(int tid, f32x16 (&acc)[2][2], GRegs& g, const GOp& o, int K, unsigned char* smem) {
;     ...
;   for (int k = 0; k < nk; k++) {
;     bf16r* cur = sbuf + (k & 1) * (256 * LDK);
;     bf16r* nxt = sbuf + ((k & 1) ^ 1) * (256 * LDK);
;     const bf16r* As = cur + (wm * 64 + fr) * LDK + fh * 8;
;     const bf16r* Bs = cur + 128 * LDK + (wn * 64 + fr) * LDK + fh * 8;
;     const bool wr = (k + 1 < nk), ld = (k + 2 < nk);
;     bf16x8 fa[2][2], fb[2][2];
;     fa[0][0] = *(const bf16x8*)(As);
;     fa[0][1] = *(const bf16x8*)(As + 32 * LDK);
;     fb[0][0] = *(const bf16x8*)(Bs);
;     fb[0][1] = *(const bf16x8*)(Bs + 32 * LDK);
; #pragma unroll
;     for (int i = 0; i < 4; i++) {
;       if (wr) {
;         *(u32x4*)(nxt + (r0 + i * 32) * LDK + sg * 8) = g.a[i];
;         *(u32x4*)(nxt + 128 * LDK + (r0 + i * 32) * LDK + sg * 8) = g.b[i];
;       }
;       if (ld) {
;         g.a[i] = *(const u32x4*)(Ap + (size_t)i * 32 * o.lda + (k + 2) * 64);
;         g.b[i] = *(const u32x4*)(Bp + o.bs.o[i] + (k + 2) * 64);
;       }
;       if (i < 3) {
;         fa[(i + 1) & 1][0] = *(const bf16x8*)(As + (i + 1) * 16);
;         fa[(i + 1) & 1][1] = *(const bf16x8*)(As + 32 * LDK + (i + 1) * 16);
;         fb[(i + 1) & 1][0] = *(const bf16x8*)(Bs + (i + 1) * 16);
;         fb[(i + 1) & 1][1] = *(const bf16x8*)(Bs + 32 * LDK + (i + 1) * 16);
;       }
;       __builtin_amdgcn_sched_barrier(0);
;       __builtin_amdgcn_s_setprio(1);
;       acc[0][0] = __builtin_amdgcn_mfma_f32_32x32x16_bf16(fa[i & 1][0], fb[i & 1][0], acc[0][0], 0, 0, 0);
;       acc[0][1] = __builtin_amdgcn_mfma_f32_32x32x16_bf16(fa[i & 1][0], fb[i & 1][1], acc[0][1], 0, 0, 0);
;       acc[1][0] = __builtin_amdgcn_mfma_f32_32x32x16_bf16(fa[i & 1][1], fb[i & 1][0], acc[1][0], 0, 0, 0);
;       acc[1][1] = __builtin_amdgcn_mfma_f32_32x32x16_bf16(fa[i & 1][1], fb[i & 1][1], acc[1][1], 0, 0, 0);
;       __builtin_amdgcn_s_setprio(0);
;     }
;     __syncthreads();
	global_load_dwordx4 v[66:69], v[64:65], off offset:896
	global_load_dwordx4 v[110:113], v[106:107], off offset:896
	ds_read_b128 v[138:141], v104 offset:36864
	ds_read_b128 v[142:145], v104 offset:41472
	ds_read_b128 v[154:157], v101 offset:55296
	ds_read_b128 v[158:161], v101 offset:59904
	s_waitcnt vmcnt(9)
	ds_write_b128 v100, v[114:117]
	s_waitcnt vmcnt(8)
	ds_write_b128 v100, v[118:121] offset:18432
	ds_read_b128 v[114:117], v104 offset:36896
	ds_read_b128 v[118:121], v104 offset:41504
	ds_read_b128 v[162:165], v101 offset:55328
	ds_read_b128 v[166:169], v101 offset:59936
	s_waitcnt lgkmcnt(7)
	v_mfma_f32_32x32x16_bf16 v[16:31], v[138:141], v[154:157], v[16:31]
	s_waitcnt lgkmcnt(6)
	v_mfma_f32_32x32x16_bf16 v[48:63], v[138:141], v[158:161], v[48:63]
	v_mfma_f32_32x32x16_bf16 v[0:15], v[142:145], v[154:157], v[0:15]
	v_mfma_f32_32x32x16_bf16 v[32:47], v[142:145], v[158:161], v[32:47]
	global_load_dwordx4 v[138:141], v[72:73], off offset:896
	global_load_dwordx4 v[142:145], v[76:77], off offset:896
	s_waitcnt vmcnt(9)
	ds_write_b128 v100, v[122:125] offset:4608
	s_waitcnt vmcnt(8)
	ds_write_b128 v100, v[126:129] offset:23040
	ds_read_b128 v[122:125], v104 offset:36928
	ds_read_b128 v[126:129], v104 offset:41536
	ds_read_b128 v[154:157], v101 offset:55360
	ds_read_b128 v[158:161], v101 offset:59968
	s_waitcnt lgkmcnt(7)
	v_mfma_f32_32x32x16_bf16 v[16:31], v[114:117], v[162:165], v[16:31]
	s_waitcnt lgkmcnt(6)
	v_mfma_f32_32x32x16_bf16 v[48:63], v[114:117], v[166:169], v[48:63]
	v_mfma_f32_32x32x16_bf16 v[0:15], v[118:121], v[162:165], v[0:15]
	v_mfma_f32_32x32x16_bf16 v[32:47], v[118:121], v[166:169], v[32:47]
	global_load_dwordx4 v[114:117], v[80:81], off offset:896
	global_load_dwordx4 v[118:121], v[84:85], off offset:896
	s_waitcnt vmcnt(9)
	ds_write_b128 v100, v[130:133] offset:9216
	s_waitcnt vmcnt(8)
	ds_write_b128 v100, v[134:137] offset:27648
	ds_read_b128 v[130:133], v104 offset:36960
	ds_read_b128 v[134:137], v104 offset:41568
	ds_read_b128 v[162:165], v101 offset:55392
	ds_read_b128 v[166:169], v101 offset:60000
	s_waitcnt lgkmcnt(7)
	v_mfma_f32_32x32x16_bf16 v[16:31], v[122:125], v[154:157], v[16:31]
	s_waitcnt lgkmcnt(6)
	v_mfma_f32_32x32x16_bf16 v[48:63], v[122:125], v[158:161], v[48:63]
	v_mfma_f32_32x32x16_bf16 v[0:15], v[126:129], v[154:157], v[0:15]
	v_mfma_f32_32x32x16_bf16 v[32:47], v[126:129], v[158:161], v[32:47]
	global_load_dwordx4 v[122:125], v[88:89], off offset:896
	global_load_dwordx4 v[126:129], v[92:93], off offset:896
	s_waitcnt vmcnt(9)
	ds_write_b128 v100, v[146:149] offset:13824
	s_waitcnt vmcnt(8)
	ds_write_b128 v100, v[150:153] offset:32256
	s_waitcnt lgkmcnt(3)
	v_mfma_f32_32x32x16_bf16 v[16:31], v[130:133], v[162:165], v[16:31]
	s_waitcnt lgkmcnt(2)
	v_mfma_f32_32x32x16_bf16 v[48:63], v[130:133], v[166:169], v[48:63]
	v_mfma_f32_32x32x16_bf16 v[0:15], v[134:137], v[162:165], v[0:15]
	v_mfma_f32_32x32x16_bf16 v[32:47], v[134:137], v[166:169], v[32:47]
	s_waitcnt lgkmcnt(0)
	s_barrier
	global_load_dwordx4 v[130:133], v[64:65], off offset:1024
	global_load_dwordx4 v[134:137], v[106:107], off offset:1024
	ds_read_b128 v[146:149], v104
	ds_read_b128 v[150:153], v104 offset:4608
	ds_read_b128 v[154:157], v101 offset:18432
	ds_read_b128 v[158:161], v101 offset:23040
	s_waitcnt vmcnt(9)
	ds_write_b128 v100, v[66:69] offset:36864
	s_waitcnt vmcnt(8)
	ds_write_b128 v100, v[110:113] offset:55296
	ds_read_b128 v[66:69], v104 offset:32
	ds_read_b128 v[110:113], v104 offset:4640
	ds_read_b128 v[162:165], v101 offset:18464
	ds_read_b128 v[166:169], v101 offset:23072
	s_waitcnt lgkmcnt(7)
	v_mfma_f32_32x32x16_bf16 v[16:31], v[146:149], v[154:157], v[16:31]
	s_waitcnt lgkmcnt(6)
	v_mfma_f32_32x32x16_bf16 v[48:63], v[146:149], v[158:161], v[48:63]
	v_mfma_f32_32x32x16_bf16 v[0:15], v[150:153], v[154:157], v[0:15]
	v_mfma_f32_32x32x16_bf16 v[32:47], v[150:153], v[158:161], v[32:47]
	global_load_dwordx4 v[146:149], v[72:73], off offset:1024
	global_load_dwordx4 v[150:153], v[76:77], off offset:1024
	s_waitcnt vmcnt(9)
	ds_write_b128 v100, v[138:141] offset:41472
	s_waitcnt vmcnt(8)
	ds_write_b128 v100, v[142:145] offset:59904
	ds_read_b128 v[138:141], v104 offset:64
	ds_read_b128 v[142:145], v104 offset:4672
	ds_read_b128 v[154:157], v101 offset:18496
	ds_read_b128 v[158:161], v101 offset:23104
	s_waitcnt lgkmcnt(7)
	v_mfma_f32_32x32x16_bf16 v[16:31], v[66:69], v[162:165], v[16:31]
	s_waitcnt lgkmcnt(6)
	v_mfma_f32_32x32x16_bf16 v[48:63], v[66:69], v[166:169], v[48:63]
	v_mfma_f32_32x32x16_bf16 v[0:15], v[110:113], v[162:165], v[0:15]
	v_mfma_f32_32x32x16_bf16 v[32:47], v[110:113], v[166:169], v[32:47]
	global_load_dwordx4 v[66:69], v[80:81], off offset:1024
	global_load_dwordx4 v[110:113], v[84:85], off offset:1024
	s_waitcnt vmcnt(9)
	ds_write_b128 v100, v[114:117] offset:46080
	s_waitcnt vmcnt(8)
	ds_write_b128 v100, v[118:121] offset:64512
	ds_read_b128 v[114:117], v104 offset:96
	ds_read_b128 v[118:121], v104 offset:4704
	ds_read_b128 v[162:165], v101 offset:18528
	ds_read_b128 v[166:169], v101 offset:23136
	s_waitcnt lgkmcnt(7)
	v_mfma_f32_32x32x16_bf16 v[16:31], v[138:141], v[154:157], v[16:31]
	s_waitcnt lgkmcnt(6)
	v_mfma_f32_32x32x16_bf16 v[48:63], v[138:141], v[158:161], v[48:63]
	v_mfma_f32_32x32x16_bf16 v[0:15], v[142:145], v[154:157], v[0:15]
	v_mfma_f32_32x32x16_bf16 v[32:47], v[142:145], v[158:161], v[32:47]
	global_load_dwordx4 v[138:141], v[88:89], off offset:1024
	global_load_dwordx4 v[142:145], v[92:93], off offset:1024
	s_waitcnt vmcnt(9)
	ds_write_b128 v100, v[122:125] offset:50688
	s_waitcnt vmcnt(8)
	ds_write_b128 v105, v[126:129] offset:13824
	s_waitcnt lgkmcnt(3)
	v_mfma_f32_32x32x16_bf16 v[16:31], v[114:117], v[162:165], v[16:31]
	s_waitcnt lgkmcnt(2)
	v_mfma_f32_32x32x16_bf16 v[48:63], v[114:117], v[166:169], v[48:63]
	v_mfma_f32_32x32x16_bf16 v[0:15], v[118:121], v[162:165], v[0:15]
	v_mfma_f32_32x32x16_bf16 v[32:47], v[118:121], v[166:169], v[32:47]
	s_waitcnt lgkmcnt(0)
	s_barrier
; __device__ __forceinline__ void gemm_run(int tid, f32x16 (&acc)[2][2], GRegs& g, const GOp& o, int K, unsigned char* smem) {
;     ...
;   for (int k = 0; k < nk; k++) {
;     bf16r* cur = sbuf + (k & 1) * (256 * LDK);
;     bf16r* nxt = sbuf + ((k & 1) ^ 1) * (256 * LDK);
;     const bf16r* As = cur + (wm * 64 + fr) * LDK + fh * 8;
;     const bf16r* Bs = cur + 128 * LDK + (wn * 64 + fr) * LDK + fh * 8;
;     const bool wr = (k + 1 < nk), ld = (k + 2 < nk);
;     bf16x8 fa[2][2], fb[2][2];
;     fa[0][0] = *(const bf16x8*)(As);
;     fa[0][1] = *(const bf16x8*)(As + 32 * LDK);
;     fb[0][0] = *(const bf16x8*)(Bs);
;     fb[0][1] = *(const bf16x8*)(Bs + 32 * LDK);
; #pragma unroll
;     for (int i = 0; i < 4; i++) {
;       if (wr) {
;         *(u32x4*)(nxt + (r0 + i * 32) * LDK + sg * 8) = g.a[i];
;         *(u32x4*)(nxt + 128 * LDK + (r0 + i * 32) * LDK + sg * 8) = g.b[i];
;       }
;       if (ld) {
;         g.a[i] = *(const u32x4*)(Ap + (size_t)i * 32 * o.lda + (k + 2) * 64);
;         g.b[i] = *(const u32x4*)(Bp + o.bs.o[i] + (k + 2) * 64);
;       }
;       if (i < 3) {
;         fa[(i + 1) & 1][0] = *(const bf16x8*)(As + (i + 1) * 16);
;         fa[(i + 1) & 1][1] = *(const bf16x8*)(As + 32 * LDK + (i + 1) * 16);
;         fb[(i + 1) & 1][0] = *(const bf16x8*)(Bs + (i + 1) * 16);
;         fb[(i + 1) & 1][1] = *(const bf16x8*)(Bs + 32 * LDK + (i + 1) * 16);
;       }
;       __builtin_amdgcn_sched_barrier(0);
;       __builtin_amdgcn_s_setprio(1);
;       acc[0][0] = __builtin_amdgcn_mfma_f32_32x32x16_bf16(fa[i & 1][0], fb[i & 1][0], acc[0][0], 0, 0, 0);
;       acc[0][1] = __builtin_amdgcn_mfma_f32_32x32x16_bf16(fa[i & 1][0], fb[i & 1][1], acc[0][1], 0, 0, 0);
;       acc[1][0] = __builtin_amdgcn_mfma_f32_32x32x16_bf16(fa[i & 1][1], fb[i & 1][0], acc[1][0], 0, 0, 0);
;       acc[1][1] = __builtin_amdgcn_mfma_f32_32x32x16_bf16(fa[i & 1][1], fb[i & 1][1], acc[1][1], 0, 0, 0);
;       __builtin_amdgcn_s_setprio(0);
;     }
;     __syncthreads();
	global_load_dwordx4 v[114:117], v[64:65], off offset:1152
	global_load_dwordx4 v[118:121], v[106:107], off offset:1152
	ds_read_b128 v[122:125], v104 offset:36864
	ds_read_b128 v[126:129], v104 offset:41472
	ds_read_b128 v[154:157], v101 offset:55296
	ds_read_b128 v[158:161], v101 offset:59904
	s_waitcnt vmcnt(9)
	ds_write_b128 v100, v[130:133]
	s_waitcnt vmcnt(8)
	ds_write_b128 v100, v[134:137] offset:18432
	ds_read_b128 v[130:133], v104 offset:36896
	ds_read_b128 v[134:137], v104 offset:41504
	ds_read_b128 v[162:165], v101 offset:55328
	ds_read_b128 v[166:169], v101 offset:59936
	s_waitcnt lgkmcnt(7)
	v_mfma_f32_32x32x16_bf16 v[16:31], v[122:125], v[154:157], v[16:31]
	s_waitcnt lgkmcnt(6)
	v_mfma_f32_32x32x16_bf16 v[48:63], v[122:125], v[158:161], v[48:63]
	v_mfma_f32_32x32x16_bf16 v[0:15], v[126:129], v[154:157], v[0:15]
	v_mfma_f32_32x32x16_bf16 v[32:47], v[126:129], v[158:161], v[32:47]
	global_load_dwordx4 v[122:125], v[72:73], off offset:1152
	global_load_dwordx4 v[126:129], v[76:77], off offset:1152
	s_waitcnt vmcnt(9)
	ds_write_b128 v100, v[146:149] offset:4608
	s_waitcnt vmcnt(8)
	ds_write_b128 v100, v[150:153] offset:23040
	ds_read_b128 v[146:149], v104 offset:36928
	ds_read_b128 v[150:153], v104 offset:41536
	ds_read_b128 v[154:157], v101 offset:55360
	ds_read_b128 v[158:161], v101 offset:59968
	s_waitcnt lgkmcnt(7)
	v_mfma_f32_32x32x16_bf16 v[16:31], v[130:133], v[162:165], v[16:31]
	s_waitcnt lgkmcnt(6)
	v_mfma_f32_32x32x16_bf16 v[48:63], v[130:133], v[166:169], v[48:63]
	v_mfma_f32_32x32x16_bf16 v[0:15], v[134:137], v[162:165], v[0:15]
	v_mfma_f32_32x32x16_bf16 v[32:47], v[134:137], v[166:169], v[32:47]
	global_load_dwordx4 v[130:133], v[80:81], off offset:1152
	global_load_dwordx4 v[134:137], v[84:85], off offset:1152
	s_waitcnt vmcnt(9)
	ds_write_b128 v100, v[66:69] offset:9216
	s_waitcnt vmcnt(8)
	ds_write_b128 v100, v[110:113] offset:27648
	ds_read_b128 v[66:69], v104 offset:36960
	ds_read_b128 v[110:113], v104 offset:41568
	ds_read_b128 v[162:165], v101 offset:55392
	ds_read_b128 v[166:169], v101 offset:60000
	s_waitcnt lgkmcnt(7)
	v_mfma_f32_32x32x16_bf16 v[16:31], v[146:149], v[154:157], v[16:31]
	s_waitcnt lgkmcnt(6)
	v_mfma_f32_32x32x16_bf16 v[48:63], v[146:149], v[158:161], v[48:63]
	v_mfma_f32_32x32x16_bf16 v[0:15], v[150:153], v[154:157], v[0:15]
	v_mfma_f32_32x32x16_bf16 v[32:47], v[150:153], v[158:161], v[32:47]
	global_load_dwordx4 v[146:149], v[88:89], off offset:1152
	global_load_dwordx4 v[150:153], v[92:93], off offset:1152
	s_waitcnt vmcnt(9)
	ds_write_b128 v100, v[138:141] offset:13824
	s_waitcnt vmcnt(8)
	ds_write_b128 v100, v[142:145] offset:32256
	s_waitcnt lgkmcnt(3)
	v_mfma_f32_32x32x16_bf16 v[16:31], v[66:69], v[162:165], v[16:31]
	s_waitcnt lgkmcnt(2)
	v_mfma_f32_32x32x16_bf16 v[48:63], v[66:69], v[166:169], v[48:63]
	v_mfma_f32_32x32x16_bf16 v[0:15], v[110:113], v[162:165], v[0:15]
	v_mfma_f32_32x32x16_bf16 v[32:47], v[110:113], v[166:169], v[32:47]
	s_waitcnt lgkmcnt(0)
	s_barrier
	global_load_dwordx4 v[66:69], v[64:65], off offset:1280
	global_load_dwordx4 v[110:113], v[106:107], off offset:1280
	ds_read_b128 v[138:141], v104
	ds_read_b128 v[142:145], v104 offset:4608
	ds_read_b128 v[154:157], v101 offset:18432
	ds_read_b128 v[158:161], v101 offset:23040
	s_waitcnt vmcnt(9)
	ds_write_b128 v100, v[114:117] offset:36864
	s_waitcnt vmcnt(8)
	ds_write_b128 v100, v[118:121] offset:55296
	ds_read_b128 v[114:117], v104 offset:32
	ds_read_b128 v[118:121], v104 offset:4640
	ds_read_b128 v[162:165], v101 offset:18464
	ds_read_b128 v[166:169], v101 offset:23072
	s_waitcnt lgkmcnt(7)
	v_mfma_f32_32x32x16_bf16 v[16:31], v[138:141], v[154:157], v[16:31]
	s_waitcnt lgkmcnt(6)
	v_mfma_f32_32x32x16_bf16 v[48:63], v[138:141], v[158:161], v[48:63]
	v_mfma_f32_32x32x16_bf16 v[0:15], v[142:145], v[154:157], v[0:15]
	v_mfma_f32_32x32x16_bf16 v[32:47], v[142:145], v[158:161], v[32:47]
	global_load_dwordx4 v[138:141], v[72:73], off offset:1280
	global_load_dwordx4 v[142:145], v[76:77], off offset:1280
	s_waitcnt vmcnt(9)
	ds_write_b128 v100, v[122:125] offset:41472
	s_waitcnt vmcnt(8)
	ds_write_b128 v100, v[126:129] offset:59904
	ds_read_b128 v[122:125], v104 offset:64
	ds_read_b128 v[126:129], v104 offset:4672
	ds_read_b128 v[154:157], v101 offset:18496
	ds_read_b128 v[158:161], v101 offset:23104
	s_waitcnt lgkmcnt(7)
	v_mfma_f32_32x32x16_bf16 v[16:31], v[114:117], v[162:165], v[16:31]
	s_waitcnt lgkmcnt(6)
	v_mfma_f32_32x32x16_bf16 v[48:63], v[114:117], v[166:169], v[48:63]
	v_mfma_f32_32x32x16_bf16 v[0:15], v[118:121], v[162:165], v[0:15]
	v_mfma_f32_32x32x16_bf16 v[32:47], v[118:121], v[166:169], v[32:47]
	global_load_dwordx4 v[114:117], v[80:81], off offset:1280
	global_load_dwordx4 v[118:121], v[84:85], off offset:1280
	s_waitcnt vmcnt(9)
	ds_write_b128 v100, v[130:133] offset:46080
	s_waitcnt vmcnt(8)
	ds_write_b128 v100, v[134:137] offset:64512
	ds_read_b128 v[130:133], v104 offset:96
	ds_read_b128 v[134:137], v104 offset:4704
	ds_read_b128 v[162:165], v101 offset:18528
	ds_read_b128 v[166:169], v101 offset:23136
	s_waitcnt lgkmcnt(7)
	v_mfma_f32_32x32x16_bf16 v[16:31], v[122:125], v[154:157], v[16:31]
	s_waitcnt lgkmcnt(6)
	v_mfma_f32_32x32x16_bf16 v[48:63], v[122:125], v[158:161], v[48:63]
	v_mfma_f32_32x32x16_bf16 v[0:15], v[126:129], v[154:157], v[0:15]
	v_mfma_f32_32x32x16_bf16 v[32:47], v[126:129], v[158:161], v[32:47]
	global_load_dwordx4 v[122:125], v[88:89], off offset:1280
	global_load_dwordx4 v[126:129], v[92:93], off offset:1280
	s_waitcnt vmcnt(9)
	ds_write_b128 v100, v[146:149] offset:50688
	s_waitcnt vmcnt(8)
	ds_write_b128 v105, v[150:153] offset:13824
	s_waitcnt lgkmcnt(3)
	v_mfma_f32_32x32x16_bf16 v[16:31], v[130:133], v[162:165], v[16:31]
	s_waitcnt lgkmcnt(2)
	v_mfma_f32_32x32x16_bf16 v[48:63], v[130:133], v[166:169], v[48:63]
	v_mfma_f32_32x32x16_bf16 v[0:15], v[134:137], v[162:165], v[0:15]
	v_mfma_f32_32x32x16_bf16 v[32:47], v[134:137], v[166:169], v[32:47]
	s_waitcnt lgkmcnt(0)
	s_barrier
; __device__ __forceinline__ void gemm_run(int tid, f32x16 (&acc)[2][2], GRegs& g, const GOp& o, int K, unsigned char* smem) {
;     ...
;   for (int k = 0; k < nk; k++) {
;     bf16r* cur = sbuf + (k & 1) * (256 * LDK);
;     bf16r* nxt = sbuf + ((k & 1) ^ 1) * (256 * LDK);
;     const bf16r* As = cur + (wm * 64 + fr) * LDK + fh * 8;
;     const bf16r* Bs = cur + 128 * LDK + (wn * 64 + fr) * LDK + fh * 8;
;     const bool wr = (k + 1 < nk), ld = (k + 2 < nk);
;     bf16x8 fa[2][2], fb[2][2];
;     fa[0][0] = *(const bf16x8*)(As);
;     fa[0][1] = *(const bf16x8*)(As + 32 * LDK);
;     fb[0][0] = *(const bf16x8*)(Bs);
;     fb[0][1] = *(const bf16x8*)(Bs + 32 * LDK);
; #pragma unroll
;     for (int i = 0; i < 4; i++) {
;       if (wr) {
;         *(u32x4*)(nxt + (r0 + i * 32) * LDK + sg * 8) = g.a[i];
;         *(u32x4*)(nxt + 128 * LDK + (r0 + i * 32) * LDK + sg * 8) = g.b[i];
;       }
;       if (ld) {
;         g.a[i] = *(const u32x4*)(Ap + (size_t)i * 32 * o.lda + (k + 2) * 64);
;         g.b[i] = *(const u32x4*)(Bp + o.bs.o[i] + (k + 2) * 64);
;       }
;       if (i < 3) {
;         fa[(i + 1) & 1][0] = *(const bf16x8*)(As + (i + 1) * 16);
;         fa[(i + 1) & 1][1] = *(const bf16x8*)(As + 32 * LDK + (i + 1) * 16);
;         fb[(i + 1) & 1][0] = *(const bf16x8*)(Bs + (i + 1) * 16);
;         fb[(i + 1) & 1][1] = *(const bf16x8*)(Bs + 32 * LDK + (i + 1) * 16);
;       }
;       __builtin_amdgcn_sched_barrier(0);
;       __builtin_amdgcn_s_setprio(1);
;       acc[0][0] = __builtin_amdgcn_mfma_f32_32x32x16_bf16(fa[i & 1][0], fb[i & 1][0], acc[0][0], 0, 0, 0);
;       acc[0][1] = __builtin_amdgcn_mfma_f32_32x32x16_bf16(fa[i & 1][0], fb[i & 1][1], acc[0][1], 0, 0, 0);
;       acc[1][0] = __builtin_amdgcn_mfma_f32_32x32x16_bf16(fa[i & 1][1], fb[i & 1][0], acc[1][0], 0, 0, 0);
;       acc[1][1] = __builtin_amdgcn_mfma_f32_32x32x16_bf16(fa[i & 1][1], fb[i & 1][1], acc[1][1], 0, 0, 0);
;       __builtin_amdgcn_s_setprio(0);
;     }
;     __syncthreads();
	global_load_dwordx4 v[130:133], v[64:65], off offset:1408
	global_load_dwordx4 v[134:137], v[106:107], off offset:1408
	ds_read_b128 v[146:149], v104 offset:36864
	ds_read_b128 v[150:153], v104 offset:41472
	ds_read_b128 v[154:157], v101 offset:55296
	ds_read_b128 v[158:161], v101 offset:59904
	s_waitcnt vmcnt(9)
	ds_write_b128 v100, v[66:69]
	s_waitcnt vmcnt(8)
	ds_write_b128 v100, v[110:113] offset:18432
	ds_read_b128 v[66:69], v104 offset:36896
	ds_read_b128 v[110:113], v104 offset:41504
	ds_read_b128 v[162:165], v101 offset:55328
	ds_read_b128 v[166:169], v101 offset:59936
	s_waitcnt lgkmcnt(7)
	v_mfma_f32_32x32x16_bf16 v[16:31], v[146:149], v[154:157], v[16:31]
	s_waitcnt lgkmcnt(6)
	v_mfma_f32_32x32x16_bf16 v[48:63], v[146:149], v[158:161], v[48:63]
	v_mfma_f32_32x32x16_bf16 v[0:15], v[150:153], v[154:157], v[0:15]
	v_mfma_f32_32x32x16_bf16 v[32:47], v[150:153], v[158:161], v[32:47]
	global_load_dwordx4 v[146:149], v[72:73], off offset:1408
	global_load_dwordx4 v[150:153], v[76:77], off offset:1408
	s_waitcnt vmcnt(9)
	ds_write_b128 v100, v[138:141] offset:4608
	s_waitcnt vmcnt(8)
	ds_write_b128 v100, v[142:145] offset:23040
	ds_read_b128 v[138:141], v104 offset:36928
	ds_read_b128 v[142:145], v104 offset:41536
	ds_read_b128 v[154:157], v101 offset:55360
	ds_read_b128 v[158:161], v101 offset:59968
	s_waitcnt lgkmcnt(7)
	v_mfma_f32_32x32x16_bf16 v[16:31], v[66:69], v[162:165], v[16:31]
	s_waitcnt lgkmcnt(6)
	v_mfma_f32_32x32x16_bf16 v[48:63], v[66:69], v[166:169], v[48:63]
	v_mfma_f32_32x32x16_bf16 v[0:15], v[110:113], v[162:165], v[0:15]
	v_mfma_f32_32x32x16_bf16 v[32:47], v[110:113], v[166:169], v[32:47]
	global_load_dwordx4 v[66:69], v[80:81], off offset:1408
	global_load_dwordx4 v[110:113], v[84:85], off offset:1408
	s_waitcnt vmcnt(9)
	ds_write_b128 v100, v[114:117] offset:9216
	s_waitcnt vmcnt(8)
	ds_write_b128 v100, v[118:121] offset:27648
	ds_read_b128 v[114:117], v104 offset:36960
	ds_read_b128 v[118:121], v104 offset:41568
	ds_read_b128 v[162:165], v101 offset:55392
	ds_read_b128 v[166:169], v101 offset:60000
	s_waitcnt lgkmcnt(7)
	v_mfma_f32_32x32x16_bf16 v[16:31], v[138:141], v[154:157], v[16:31]
	s_waitcnt lgkmcnt(6)
	v_mfma_f32_32x32x16_bf16 v[48:63], v[138:141], v[158:161], v[48:63]
	v_mfma_f32_32x32x16_bf16 v[0:15], v[142:145], v[154:157], v[0:15]
	v_mfma_f32_32x32x16_bf16 v[32:47], v[142:145], v[158:161], v[32:47]
	global_load_dwordx4 v[138:141], v[88:89], off offset:1408
	global_load_dwordx4 v[142:145], v[92:93], off offset:1408
	s_waitcnt vmcnt(9)
	ds_write_b128 v100, v[122:125] offset:13824
	s_waitcnt vmcnt(8)
	ds_write_b128 v100, v[126:129] offset:32256
	s_waitcnt lgkmcnt(3)
	v_mfma_f32_32x32x16_bf16 v[16:31], v[114:117], v[162:165], v[16:31]
	s_waitcnt lgkmcnt(2)
	v_mfma_f32_32x32x16_bf16 v[48:63], v[114:117], v[166:169], v[48:63]
	v_mfma_f32_32x32x16_bf16 v[0:15], v[118:121], v[162:165], v[0:15]
	v_mfma_f32_32x32x16_bf16 v[32:47], v[118:121], v[166:169], v[32:47]
	s_waitcnt lgkmcnt(0)
	s_barrier
	global_load_dwordx4 v[114:117], v[64:65], off offset:1536
	global_load_dwordx4 v[118:121], v[106:107], off offset:1536
	ds_read_b128 v[122:125], v104
	ds_read_b128 v[126:129], v104 offset:4608
	ds_read_b128 v[154:157], v101 offset:18432
	ds_read_b128 v[158:161], v101 offset:23040
	s_waitcnt vmcnt(9)
	ds_write_b128 v100, v[130:133] offset:36864
	s_waitcnt vmcnt(8)
	ds_write_b128 v100, v[134:137] offset:55296
	ds_read_b128 v[130:133], v104 offset:32
	ds_read_b128 v[134:137], v104 offset:4640
	ds_read_b128 v[162:165], v101 offset:18464
	ds_read_b128 v[166:169], v101 offset:23072
	s_waitcnt lgkmcnt(7)
	v_mfma_f32_32x32x16_bf16 v[16:31], v[122:125], v[154:157], v[16:31]
	s_waitcnt lgkmcnt(6)
	v_mfma_f32_32x32x16_bf16 v[48:63], v[122:125], v[158:161], v[48:63]
	v_mfma_f32_32x32x16_bf16 v[0:15], v[126:129], v[154:157], v[0:15]
	v_mfma_f32_32x32x16_bf16 v[32:47], v[126:129], v[158:161], v[32:47]
	global_load_dwordx4 v[122:125], v[72:73], off offset:1536
	global_load_dwordx4 v[126:129], v[76:77], off offset:1536
	s_waitcnt vmcnt(9)
	ds_write_b128 v100, v[146:149] offset:41472
	s_waitcnt vmcnt(8)
	ds_write_b128 v100, v[150:153] offset:59904
	ds_read_b128 v[146:149], v104 offset:64
	ds_read_b128 v[150:153], v104 offset:4672
	ds_read_b128 v[154:157], v101 offset:18496
	ds_read_b128 v[158:161], v101 offset:23104
	s_waitcnt lgkmcnt(7)
	v_mfma_f32_32x32x16_bf16 v[16:31], v[130:133], v[162:165], v[16:31]
	s_waitcnt lgkmcnt(6)
	v_mfma_f32_32x32x16_bf16 v[48:63], v[130:133], v[166:169], v[48:63]
	v_mfma_f32_32x32x16_bf16 v[0:15], v[134:137], v[162:165], v[0:15]
	v_mfma_f32_32x32x16_bf16 v[32:47], v[134:137], v[166:169], v[32:47]
	global_load_dwordx4 v[130:133], v[80:81], off offset:1536
	global_load_dwordx4 v[134:137], v[84:85], off offset:1536
	s_waitcnt vmcnt(9)
	ds_write_b128 v100, v[66:69] offset:46080
	s_waitcnt vmcnt(8)
	ds_write_b128 v100, v[110:113] offset:64512
	ds_read_b128 v[66:69], v104 offset:96
	ds_read_b128 v[110:113], v104 offset:4704
	ds_read_b128 v[162:165], v101 offset:18528
	ds_read_b128 v[166:169], v101 offset:23136
	s_waitcnt lgkmcnt(7)
	v_mfma_f32_32x32x16_bf16 v[16:31], v[146:149], v[154:157], v[16:31]
	s_waitcnt lgkmcnt(6)
	v_mfma_f32_32x32x16_bf16 v[48:63], v[146:149], v[158:161], v[48:63]
	v_mfma_f32_32x32x16_bf16 v[0:15], v[150:153], v[154:157], v[0:15]
	v_mfma_f32_32x32x16_bf16 v[32:47], v[150:153], v[158:161], v[32:47]
	global_load_dwordx4 v[146:149], v[88:89], off offset:1536
	global_load_dwordx4 v[150:153], v[92:93], off offset:1536
	s_waitcnt vmcnt(9)
	ds_write_b128 v100, v[138:141] offset:50688
	s_waitcnt vmcnt(8)
	ds_write_b128 v105, v[142:145] offset:13824
	s_waitcnt lgkmcnt(3)
	v_mfma_f32_32x32x16_bf16 v[16:31], v[66:69], v[162:165], v[16:31]
	s_waitcnt lgkmcnt(2)
	v_mfma_f32_32x32x16_bf16 v[48:63], v[66:69], v[166:169], v[48:63]
	v_mfma_f32_32x32x16_bf16 v[0:15], v[110:113], v[162:165], v[0:15]
	v_mfma_f32_32x32x16_bf16 v[32:47], v[110:113], v[166:169], v[32:47]
	s_waitcnt lgkmcnt(0)
	s_barrier
; __device__ __forceinline__ void gemm_run(int tid, f32x16 (&acc)[2][2], GRegs& g, const GOp& o, int K, unsigned char* smem) {
;     ...
;   for (int k = 0; k < nk; k++) {
;     bf16r* cur = sbuf + (k & 1) * (256 * LDK);
;     bf16r* nxt = sbuf + ((k & 1) ^ 1) * (256 * LDK);
;     const bf16r* As = cur + (wm * 64 + fr) * LDK + fh * 8;
;     const bf16r* Bs = cur + 128 * LDK + (wn * 64 + fr) * LDK + fh * 8;
;     const bool wr = (k + 1 < nk), ld = (k + 2 < nk);
;     bf16x8 fa[2][2], fb[2][2];
;     fa[0][0] = *(const bf16x8*)(As);
;     fa[0][1] = *(const bf16x8*)(As + 32 * LDK);
;     fb[0][0] = *(const bf16x8*)(Bs);
;     fb[0][1] = *(const bf16x8*)(Bs + 32 * LDK);
; #pragma unroll
;     for (int i = 0; i < 4; i++) {
;       if (wr) {
;         *(u32x4*)(nxt + (r0 + i * 32) * LDK + sg * 8) = g.a[i];
;         *(u32x4*)(nxt + 128 * LDK + (r0 + i * 32) * LDK + sg * 8) = g.b[i];
;       }
;       if (ld) {
;         g.a[i] = *(const u32x4*)(Ap + (size_t)i * 32 * o.lda + (k + 2) * 64);
;         g.b[i] = *(const u32x4*)(Bp + o.bs.o[i] + (k + 2) * 64);
;       }
;       if (i < 3) {
;         fa[(i + 1) & 1][0] = *(const bf16x8*)(As + (i + 1) * 16);
;         fa[(i + 1) & 1][1] = *(const bf16x8*)(As + 32 * LDK + (i + 1) * 16);
;         fb[(i + 1) & 1][0] = *(const bf16x8*)(Bs + (i + 1) * 16);
;         fb[(i + 1) & 1][1] = *(const bf16x8*)(Bs + 32 * LDK + (i + 1) * 16);
;       }
;       __builtin_amdgcn_sched_barrier(0);
;       __builtin_amdgcn_s_setprio(1);
;       acc[0][0] = __builtin_amdgcn_mfma_f32_32x32x16_bf16(fa[i & 1][0], fb[i & 1][0], acc[0][0], 0, 0, 0);
;       acc[0][1] = __builtin_amdgcn_mfma_f32_32x32x16_bf16(fa[i & 1][0], fb[i & 1][1], acc[0][1], 0, 0, 0);
;       acc[1][0] = __builtin_amdgcn_mfma_f32_32x32x16_bf16(fa[i & 1][1], fb[i & 1][0], acc[1][0], 0, 0, 0);
;       acc[1][1] = __builtin_amdgcn_mfma_f32_32x32x16_bf16(fa[i & 1][1], fb[i & 1][1], acc[1][1], 0, 0, 0);
;       __builtin_amdgcn_s_setprio(0);
;     }
;     __syncthreads();
	global_load_dwordx4 v[66:69], v[64:65], off offset:1664
	global_load_dwordx4 v[110:113], v[106:107], off offset:1664
	ds_read_b128 v[138:141], v104 offset:36864
	ds_read_b128 v[142:145], v104 offset:41472
	ds_read_b128 v[154:157], v101 offset:55296
	ds_read_b128 v[158:161], v101 offset:59904
	s_waitcnt vmcnt(9)
	ds_write_b128 v100, v[114:117]
	s_waitcnt vmcnt(8)
	ds_write_b128 v100, v[118:121] offset:18432
	ds_read_b128 v[114:117], v104 offset:36896
	ds_read_b128 v[118:121], v104 offset:41504
	ds_read_b128 v[162:165], v101 offset:55328
	ds_read_b128 v[166:169], v101 offset:59936
	s_waitcnt lgkmcnt(7)
	v_mfma_f32_32x32x16_bf16 v[16:31], v[138:141], v[154:157], v[16:31]
	s_waitcnt lgkmcnt(6)
	v_mfma_f32_32x32x16_bf16 v[48:63], v[138:141], v[158:161], v[48:63]
	v_mfma_f32_32x32x16_bf16 v[0:15], v[142:145], v[154:157], v[0:15]
	v_mfma_f32_32x32x16_bf16 v[32:47], v[142:145], v[158:161], v[32:47]
	global_load_dwordx4 v[138:141], v[72:73], off offset:1664
	global_load_dwordx4 v[142:145], v[76:77], off offset:1664
	s_waitcnt vmcnt(9)
	ds_write_b128 v100, v[122:125] offset:4608
	s_waitcnt vmcnt(8)
	ds_write_b128 v100, v[126:129] offset:23040
	ds_read_b128 v[122:125], v104 offset:36928
	ds_read_b128 v[126:129], v104 offset:41536
	ds_read_b128 v[154:157], v101 offset:55360
	ds_read_b128 v[158:161], v101 offset:59968
	s_waitcnt lgkmcnt(7)
	v_mfma_f32_32x32x16_bf16 v[16:31], v[114:117], v[162:165], v[16:31]
	s_waitcnt lgkmcnt(6)
	v_mfma_f32_32x32x16_bf16 v[48:63], v[114:117], v[166:169], v[48:63]
	v_mfma_f32_32x32x16_bf16 v[0:15], v[118:121], v[162:165], v[0:15]
	v_mfma_f32_32x32x16_bf16 v[32:47], v[118:121], v[166:169], v[32:47]
	global_load_dwordx4 v[114:117], v[80:81], off offset:1664
	global_load_dwordx4 v[118:121], v[84:85], off offset:1664
	s_waitcnt vmcnt(9)
	ds_write_b128 v100, v[130:133] offset:9216
	s_waitcnt vmcnt(8)
	ds_write_b128 v100, v[134:137] offset:27648
	ds_read_b128 v[130:133], v104 offset:36960
	ds_read_b128 v[134:137], v104 offset:41568
	ds_read_b128 v[162:165], v101 offset:55392
	ds_read_b128 v[166:169], v101 offset:60000
	s_waitcnt lgkmcnt(7)
	v_mfma_f32_32x32x16_bf16 v[16:31], v[122:125], v[154:157], v[16:31]
	s_waitcnt lgkmcnt(6)
	v_mfma_f32_32x32x16_bf16 v[48:63], v[122:125], v[158:161], v[48:63]
	v_mfma_f32_32x32x16_bf16 v[0:15], v[126:129], v[154:157], v[0:15]
	v_mfma_f32_32x32x16_bf16 v[32:47], v[126:129], v[158:161], v[32:47]
	global_load_dwordx4 v[122:125], v[88:89], off offset:1664
	global_load_dwordx4 v[126:129], v[92:93], off offset:1664
	s_waitcnt vmcnt(9)
	ds_write_b128 v100, v[146:149] offset:13824
	s_waitcnt vmcnt(8)
	ds_write_b128 v100, v[150:153] offset:32256
	s_waitcnt lgkmcnt(3)
	v_mfma_f32_32x32x16_bf16 v[16:31], v[130:133], v[162:165], v[16:31]
	s_waitcnt lgkmcnt(2)
	v_mfma_f32_32x32x16_bf16 v[48:63], v[130:133], v[166:169], v[48:63]
	v_mfma_f32_32x32x16_bf16 v[0:15], v[134:137], v[162:165], v[0:15]
	v_mfma_f32_32x32x16_bf16 v[32:47], v[134:137], v[166:169], v[32:47]
	s_waitcnt lgkmcnt(0)
	s_barrier
	global_load_dwordx4 v[130:133], v[64:65], off offset:1792
	global_load_dwordx4 v[134:137], v[106:107], off offset:1792
	ds_read_b128 v[146:149], v104
	ds_read_b128 v[150:153], v104 offset:4608
	ds_read_b128 v[154:157], v101 offset:18432
	ds_read_b128 v[158:161], v101 offset:23040
	s_waitcnt vmcnt(9)
	ds_write_b128 v100, v[66:69] offset:36864
	s_waitcnt vmcnt(8)
	ds_write_b128 v100, v[110:113] offset:55296
	ds_read_b128 v[66:69], v104 offset:32
	ds_read_b128 v[110:113], v104 offset:4640
	ds_read_b128 v[162:165], v101 offset:18464
	ds_read_b128 v[166:169], v101 offset:23072
	s_waitcnt lgkmcnt(7)
	v_mfma_f32_32x32x16_bf16 v[16:31], v[146:149], v[154:157], v[16:31]
	s_waitcnt lgkmcnt(6)
	v_mfma_f32_32x32x16_bf16 v[48:63], v[146:149], v[158:161], v[48:63]
	v_mfma_f32_32x32x16_bf16 v[0:15], v[150:153], v[154:157], v[0:15]
	v_mfma_f32_32x32x16_bf16 v[32:47], v[150:153], v[158:161], v[32:47]
	global_load_dwordx4 v[146:149], v[72:73], off offset:1792
	global_load_dwordx4 v[150:153], v[76:77], off offset:1792
	s_waitcnt vmcnt(9)
	ds_write_b128 v100, v[138:141] offset:41472
	s_waitcnt vmcnt(8)
	ds_write_b128 v100, v[142:145] offset:59904
	ds_read_b128 v[138:141], v104 offset:64
	ds_read_b128 v[142:145], v104 offset:4672
	ds_read_b128 v[154:157], v101 offset:18496
	ds_read_b128 v[158:161], v101 offset:23104
	s_waitcnt lgkmcnt(7)
	v_mfma_f32_32x32x16_bf16 v[16:31], v[66:69], v[162:165], v[16:31]
	s_waitcnt lgkmcnt(6)
	v_mfma_f32_32x32x16_bf16 v[48:63], v[66:69], v[166:169], v[48:63]
	v_mfma_f32_32x32x16_bf16 v[0:15], v[110:113], v[162:165], v[0:15]
	v_mfma_f32_32x32x16_bf16 v[32:47], v[110:113], v[166:169], v[32:47]
	global_load_dwordx4 v[110:113], v[80:81], off offset:1792
	global_load_dwordx4 v[162:165], v[84:85], off offset:1792
	s_waitcnt vmcnt(9)
	ds_write_b128 v100, v[114:117] offset:46080
	s_waitcnt vmcnt(8)
	ds_write_b128 v100, v[118:121] offset:64512
	ds_read_b128 v[66:69], v104 offset:96
	ds_read_b128 v[114:117], v104 offset:4704
	ds_read_b128 v[118:121], v101 offset:18528
	ds_read_b128 v[166:169], v101 offset:23136
	s_waitcnt lgkmcnt(7)
	v_mfma_f32_32x32x16_bf16 v[16:31], v[138:141], v[154:157], v[16:31]
	s_waitcnt lgkmcnt(6)
	v_mfma_f32_32x32x16_bf16 v[48:63], v[138:141], v[158:161], v[48:63]
	v_mfma_f32_32x32x16_bf16 v[0:15], v[142:145], v[154:157], v[0:15]
	v_mfma_f32_32x32x16_bf16 v[32:47], v[142:145], v[158:161], v[32:47]
	global_load_dwordx4 v[138:141], v[88:89], off offset:1792
	global_load_dwordx4 v[142:145], v[92:93], off offset:1792
	s_waitcnt vmcnt(9)
	ds_write_b128 v100, v[122:125] offset:50688
	s_waitcnt vmcnt(8)
	ds_write_b128 v105, v[126:129] offset:13824
	s_waitcnt lgkmcnt(3)
	v_mfma_f32_32x32x16_bf16 v[16:31], v[66:69], v[118:121], v[16:31]
	s_waitcnt lgkmcnt(2)
	v_mfma_f32_32x32x16_bf16 v[48:63], v[66:69], v[166:169], v[48:63]
	v_mfma_f32_32x32x16_bf16 v[0:15], v[114:117], v[118:121], v[0:15]
	v_mfma_f32_32x32x16_bf16 v[32:47], v[114:117], v[166:169], v[32:47]
	s_waitcnt lgkmcnt(0)
	s_barrier
; __device__ __forceinline__ void gemm_run(int tid, f32x16 (&acc)[2][2], GRegs& g, const GOp& o, int K, unsigned char* smem) {
;     ...
;   for (int k = 0; k < nk; k++) {
;     bf16r* cur = sbuf + (k & 1) * (256 * LDK);
;     bf16r* nxt = sbuf + ((k & 1) ^ 1) * (256 * LDK);
;     const bf16r* As = cur + (wm * 64 + fr) * LDK + fh * 8;
;     const bf16r* Bs = cur + 128 * LDK + (wn * 64 + fr) * LDK + fh * 8;
;     const bool wr = (k + 1 < nk), ld = (k + 2 < nk);
;     bf16x8 fa[2][2], fb[2][2];
;     fa[0][0] = *(const bf16x8*)(As);
;     fa[0][1] = *(const bf16x8*)(As + 32 * LDK);
;     fb[0][0] = *(const bf16x8*)(Bs);
;     fb[0][1] = *(const bf16x8*)(Bs + 32 * LDK);
; #pragma unroll
;     for (int i = 0; i < 4; i++) {
;       if (wr) {
;         *(u32x4*)(nxt + (r0 + i * 32) * LDK + sg * 8) = g.a[i];
;         *(u32x4*)(nxt + 128 * LDK + (r0 + i * 32) * LDK + sg * 8) = g.b[i];
;       }
;       if (ld) {
;         g.a[i] = *(const u32x4*)(Ap + (size_t)i * 32 * o.lda + (k + 2) * 64);
;         g.b[i] = *(const u32x4*)(Bp + o.bs.o[i] + (k + 2) * 64);
;       }
;       if (i < 3) {
;         fa[(i + 1) & 1][0] = *(const bf16x8*)(As + (i + 1) * 16);
;         fa[(i + 1) & 1][1] = *(const bf16x8*)(As + 32 * LDK + (i + 1) * 16);
;         fb[(i + 1) & 1][0] = *(const bf16x8*)(Bs + (i + 1) * 16);
;         fb[(i + 1) & 1][1] = *(const bf16x8*)(Bs + 32 * LDK + (i + 1) * 16);
;       }
;       __builtin_amdgcn_sched_barrier(0);
;       __builtin_amdgcn_s_setprio(1);
;       acc[0][0] = __builtin_amdgcn_mfma_f32_32x32x16_bf16(fa[i & 1][0], fb[i & 1][0], acc[0][0], 0, 0, 0);
;       acc[0][1] = __builtin_amdgcn_mfma_f32_32x32x16_bf16(fa[i & 1][0], fb[i & 1][1], acc[0][1], 0, 0, 0);
;       acc[1][0] = __builtin_amdgcn_mfma_f32_32x32x16_bf16(fa[i & 1][1], fb[i & 1][0], acc[1][0], 0, 0, 0);
;       acc[1][1] = __builtin_amdgcn_mfma_f32_32x32x16_bf16(fa[i & 1][1], fb[i & 1][1], acc[1][1], 0, 0, 0);
;       __builtin_amdgcn_s_setprio(0);
;     }
;     __syncthreads();
	global_load_dwordx4 v[64:67], v[64:65], off offset:1920
	s_nop 0
	global_load_dwordx4 v[68:71], v[106:107], off offset:1920
	ds_read_b128 v[114:117], v104 offset:36864
	ds_read_b128 v[118:121], v104 offset:41472
	ds_read_b128 v[122:125], v101 offset:55296
	ds_read_b128 v[126:129], v101 offset:59904
	s_waitcnt vmcnt(9)
	ds_write_b128 v100, v[130:133]
	s_waitcnt vmcnt(8)
	ds_write_b128 v100, v[134:137] offset:18432
	ds_read_b128 v[130:133], v104 offset:36896
	ds_read_b128 v[134:137], v104 offset:41504
	ds_read_b128 v[154:157], v101 offset:55328
	ds_read_b128 v[158:161], v101 offset:59936
	s_waitcnt lgkmcnt(7)
	v_mfma_f32_32x32x16_bf16 v[16:31], v[114:117], v[122:125], v[16:31]
	s_waitcnt lgkmcnt(6)
	v_mfma_f32_32x32x16_bf16 v[48:63], v[114:117], v[126:129], v[48:63]
	v_mfma_f32_32x32x16_bf16 v[0:15], v[118:121], v[122:125], v[0:15]
	v_mfma_f32_32x32x16_bf16 v[32:47], v[118:121], v[126:129], v[32:47]
	global_load_dwordx4 v[72:75], v[72:73], off offset:1920
	s_nop 0
	global_load_dwordx4 v[76:79], v[76:77], off offset:1920
	s_waitcnt vmcnt(9)
	ds_write_b128 v100, v[146:149] offset:4608
	s_waitcnt vmcnt(8)
	ds_write_b128 v100, v[150:153] offset:23040
	ds_read_b128 v[114:117], v104 offset:36928
	ds_read_b128 v[118:121], v104 offset:41536
	ds_read_b128 v[122:125], v101 offset:55360
	ds_read_b128 v[126:129], v101 offset:59968
	s_waitcnt lgkmcnt(7)
	v_mfma_f32_32x32x16_bf16 v[16:31], v[130:133], v[154:157], v[16:31]
	s_waitcnt lgkmcnt(6)
	v_mfma_f32_32x32x16_bf16 v[48:63], v[130:133], v[158:161], v[48:63]
	v_mfma_f32_32x32x16_bf16 v[0:15], v[134:137], v[154:157], v[0:15]
	v_mfma_f32_32x32x16_bf16 v[32:47], v[134:137], v[158:161], v[32:47]
	global_load_dwordx4 v[80:83], v[80:81], off offset:1920
	s_nop 0
	global_load_dwordx4 v[84:87], v[84:85], off offset:1920
	s_waitcnt vmcnt(9)
	ds_write_b128 v100, v[110:113] offset:9216
	s_waitcnt vmcnt(8)
	ds_write_b128 v100, v[162:165] offset:27648
	ds_read_b128 v[110:113], v104 offset:36960
	ds_read_b128 v[130:133], v104 offset:41568
	ds_read_b128 v[134:137], v101 offset:55392
	ds_read_b128 v[146:149], v101 offset:60000
	s_waitcnt lgkmcnt(7)
	v_mfma_f32_32x32x16_bf16 v[16:31], v[114:117], v[122:125], v[16:31]
	s_waitcnt lgkmcnt(6)
	v_mfma_f32_32x32x16_bf16 v[48:63], v[114:117], v[126:129], v[48:63]
	v_mfma_f32_32x32x16_bf16 v[0:15], v[118:121], v[122:125], v[0:15]
	v_mfma_f32_32x32x16_bf16 v[32:47], v[118:121], v[126:129], v[32:47]
	global_load_dwordx4 v[88:91], v[88:89], off offset:1920
	s_nop 0
	global_load_dwordx4 v[92:95], v[92:93], off offset:1920
	s_waitcnt vmcnt(9)
	ds_write_b128 v100, v[138:141] offset:13824
	s_waitcnt vmcnt(8)
	ds_write_b128 v100, v[142:145] offset:32256
	s_waitcnt lgkmcnt(3)
	v_mfma_f32_32x32x16_bf16 v[16:31], v[110:113], v[134:137], v[16:31]
	s_waitcnt lgkmcnt(2)
	v_mfma_f32_32x32x16_bf16 v[48:63], v[110:113], v[146:149], v[48:63]
	v_mfma_f32_32x32x16_bf16 v[0:15], v[130:133], v[134:137], v[0:15]
	v_mfma_f32_32x32x16_bf16 v[32:47], v[130:133], v[146:149], v[32:47]
	s_waitcnt lgkmcnt(0)
	s_barrier
; __device__ __forceinline__ void gemm_run(int tid, f32x16 (&acc)[2][2], GRegs& g, const GOp& o, int K, unsigned char* smem) {
;     ...
;   for (int k = 0; k < nk; k++) {
;     bf16r* cur = sbuf + (k & 1) * (256 * LDK);
;     bf16r* nxt = sbuf + ((k & 1) ^ 1) * (256 * LDK);
;     const bf16r* As = cur + (wm * 64 + fr) * LDK + fh * 8;
;     const bf16r* Bs = cur + 128 * LDK + (wn * 64 + fr) * LDK + fh * 8;
;     const bool wr = (k + 1 < nk), ld = (k + 2 < nk);
;     bf16x8 fa[2][2], fb[2][2];
;     fa[0][0] = *(const bf16x8*)(As);
;     fa[0][1] = *(const bf16x8*)(As + 32 * LDK);
;     fb[0][0] = *(const bf16x8*)(Bs);
;     fb[0][1] = *(const bf16x8*)(Bs + 32 * LDK);
; #pragma unroll
;     for (int i = 0; i < 4; i++) {
;       if (wr) {
;         *(u32x4*)(nxt + (r0 + i * 32) * LDK + sg * 8) = g.a[i];
;         *(u32x4*)(nxt + 128 * LDK + (r0 + i * 32) * LDK + sg * 8) = g.b[i];
;       }
;       if (ld) {
;         g.a[i] = *(const u32x4*)(Ap + (size_t)i * 32 * o.lda + (k + 2) * 64);
;         g.b[i] = *(const u32x4*)(Bp + o.bs.o[i] + (k + 2) * 64);
;       }
;       if (i < 3) {
;         fa[(i + 1) & 1][0] = *(const bf16x8*)(As + (i + 1) * 16);
;         fa[(i + 1) & 1][1] = *(const bf16x8*)(As + 32 * LDK + (i + 1) * 16);
;         fb[(i + 1) & 1][0] = *(const bf16x8*)(Bs + (i + 1) * 16);
;         fb[(i + 1) & 1][1] = *(const bf16x8*)(Bs + 32 * LDK + (i + 1) * 16);
;       }
;       __builtin_amdgcn_sched_barrier(0);
;       __builtin_amdgcn_s_setprio(1);
;       acc[0][0] = __builtin_amdgcn_mfma_f32_32x32x16_bf16(fa[i & 1][0], fb[i & 1][0], acc[0][0], 0, 0, 0);
;       acc[0][1] = __builtin_amdgcn_mfma_f32_32x32x16_bf16(fa[i & 1][0], fb[i & 1][1], acc[0][1], 0, 0, 0);
;       acc[1][0] = __builtin_amdgcn_mfma_f32_32x32x16_bf16(fa[i & 1][1], fb[i & 1][0], acc[1][0], 0, 0, 0);
;       acc[1][1] = __builtin_amdgcn_mfma_f32_32x32x16_bf16(fa[i & 1][1], fb[i & 1][1], acc[1][1], 0, 0, 0);
;       __builtin_amdgcn_s_setprio(0);
;     }
;     __syncthreads();
;   }
; __device__ __forceinline__ bool tile_map(int it, int nn, int& mt, int& nt) {
;   const int xcd = blockIdx.x & 7, li = blockIdx.x >> 3, nb = gridDim.x >> 3;
;   int q = it * nb + li;
;   const int per = 16 * nn;
;   if (q < per) {
;     int sub = q / (8 * nn), r = q - sub * (8 * nn);
;     nt = r >> 3;
;     mt = xcd * 16 + sub * 8 + (r & 7);
;     return true;
;   }
;   q -= per;
;   int n = q * 8 + xcd;
	ds_read_b128 v[110:113], v104
	ds_read_b128 v[114:117], v104 offset:4608
	ds_read_b128 v[118:121], v101 offset:18432
	ds_read_b128 v[122:125], v101 offset:23040
	s_waitcnt vmcnt(7)
	ds_write_b128 v100, v[64:67] offset:36864
	s_waitcnt vmcnt(6)
	ds_write_b128 v100, v[68:71] offset:55296
	ds_read_b128 v[126:129], v104 offset:32
	ds_read_b128 v[130:133], v104 offset:4640
	ds_read_b128 v[134:137], v101 offset:18464
	ds_read_b128 v[138:141], v101 offset:23072
	s_waitcnt lgkmcnt(7)
	v_mfma_f32_32x32x16_bf16 v[16:31], v[110:113], v[118:121], v[16:31]
	s_waitcnt lgkmcnt(6)
	v_mfma_f32_32x32x16_bf16 v[48:63], v[110:113], v[122:125], v[48:63]
	v_mfma_f32_32x32x16_bf16 v[0:15], v[114:117], v[118:121], v[0:15]
	v_mfma_f32_32x32x16_bf16 v[32:47], v[114:117], v[122:125], v[32:47]
	s_waitcnt vmcnt(5)
	ds_write_b128 v100, v[72:75] offset:41472
	s_waitcnt vmcnt(4)
	ds_write_b128 v100, v[76:79] offset:59904
	ds_read_b128 v[110:113], v104 offset:64
	ds_read_b128 v[114:117], v104 offset:4672
	ds_read_b128 v[118:121], v101 offset:18496
	ds_read_b128 v[122:125], v101 offset:23104
	s_waitcnt lgkmcnt(7)
	v_mfma_f32_32x32x16_bf16 v[16:31], v[126:129], v[134:137], v[16:31]
	s_waitcnt lgkmcnt(6)
	v_mfma_f32_32x32x16_bf16 v[48:63], v[126:129], v[138:141], v[48:63]
	v_mfma_f32_32x32x16_bf16 v[0:15], v[130:133], v[134:137], v[0:15]
	v_mfma_f32_32x32x16_bf16 v[32:47], v[130:133], v[138:141], v[32:47]
	s_waitcnt vmcnt(3)
	ds_write_b128 v100, v[80:83] offset:46080
	s_waitcnt vmcnt(2)
	ds_write_b128 v100, v[84:87] offset:64512
	ds_read_b128 v[126:129], v104 offset:96
	ds_read_b128 v[130:133], v104 offset:4704
	ds_read_b128 v[134:137], v101 offset:18528
	ds_read_b128 v[138:141], v101 offset:23136
	s_waitcnt lgkmcnt(7)
	v_mfma_f32_32x32x16_bf16 v[16:31], v[110:113], v[118:121], v[16:31]
	s_waitcnt lgkmcnt(6)
	v_mfma_f32_32x32x16_bf16 v[48:63], v[110:113], v[122:125], v[48:63]
	v_mfma_f32_32x32x16_bf16 v[0:15], v[114:117], v[118:121], v[0:15]
	v_mfma_f32_32x32x16_bf16 v[32:47], v[114:117], v[122:125], v[32:47]
	s_waitcnt vmcnt(1)
	ds_write_b128 v100, v[88:91] offset:50688
	s_waitcnt vmcnt(0)
	ds_write_b128 v105, v[92:95] offset:13824
	s_waitcnt lgkmcnt(3)
	v_mfma_f32_32x32x16_bf16 v[16:31], v[126:129], v[134:137], v[16:31]
	s_waitcnt lgkmcnt(2)
	v_mfma_f32_32x32x16_bf16 v[48:63], v[126:129], v[138:141], v[48:63]
	v_mfma_f32_32x32x16_bf16 v[0:15], v[130:133], v[134:137], v[0:15]
	v_mfma_f32_32x32x16_bf16 v[32:47], v[130:133], v[138:141], v[32:47]
	s_waitcnt lgkmcnt(0)
	s_barrier
	ds_read_b128 v[110:113], v104 offset:36864
	ds_read_b128 v[114:117], v104 offset:36896
	ds_read_b128 v[118:121], v104 offset:41472
	ds_read_b128 v[122:125], v104 offset:41504
	ds_read_b128 v[126:129], v101 offset:55296
	ds_read_b128 v[130:133], v101 offset:55328
	ds_read_b128 v[134:137], v101 offset:59904
	ds_read_b128 v[138:141], v101 offset:59936
	s_waitcnt lgkmcnt(3)
	v_mfma_f32_32x32x16_bf16 v[16:31], v[110:113], v[126:129], v[16:31]
	s_waitcnt lgkmcnt(1)
	v_mfma_f32_32x32x16_bf16 v[48:63], v[110:113], v[134:137], v[48:63]
	v_mfma_f32_32x32x16_bf16 v[0:15], v[118:121], v[126:129], v[0:15]
	v_mfma_f32_32x32x16_bf16 v[32:47], v[118:121], v[134:137], v[32:47]
	ds_read_b128 v[110:113], v104 offset:36928
	ds_read_b128 v[118:121], v104 offset:41536
	ds_read_b128 v[126:129], v101 offset:55360
	ds_read_b128 v[134:137], v101 offset:59968
	v_mfma_f32_32x32x16_bf16 v[16:31], v[114:117], v[130:133], v[16:31]
	s_waitcnt lgkmcnt(4)
	v_mfma_f32_32x32x16_bf16 v[48:63], v[114:117], v[138:141], v[48:63]
	v_mfma_f32_32x32x16_bf16 v[0:15], v[122:125], v[130:133], v[0:15]
	v_mfma_f32_32x32x16_bf16 v[32:47], v[122:125], v[138:141], v[32:47]
	ds_read_b128 v[114:117], v104 offset:36960
	ds_read_b128 v[122:125], v104 offset:41568
	ds_read_b128 v[130:133], v101 offset:55392
	ds_read_b128 v[138:141], v101 offset:60000
	s_waitcnt lgkmcnt(5)
	v_mfma_f32_32x32x16_bf16 v[16:31], v[110:113], v[126:129], v[16:31]
	s_waitcnt lgkmcnt(4)
	v_mfma_f32_32x32x16_bf16 v[48:63], v[110:113], v[134:137], v[48:63]
	v_mfma_f32_32x32x16_bf16 v[0:15], v[118:121], v[126:129], v[0:15]
	v_mfma_f32_32x32x16_bf16 v[32:47], v[118:121], v[134:137], v[32:47]
	s_waitcnt lgkmcnt(1)
	v_mfma_f32_32x32x16_bf16 v[16:31], v[114:117], v[130:133], v[16:31]
	s_waitcnt lgkmcnt(0)
	v_mfma_f32_32x32x16_bf16 v[48:63], v[114:117], v[138:141], v[48:63]
	v_mfma_f32_32x32x16_bf16 v[0:15], v[122:125], v[130:133], v[0:15]
	v_mfma_f32_32x32x16_bf16 v[32:47], v[122:125], v[138:141], v[32:47]
	s_cmpk_gt_u32 s86, 0x17f
	s_mov_b64 s[4:5], -1
	s_barrier
	s_cbranch_scc0 .LBB0_150
	s_mov_b64 s[4:5], 0
	s_cmp_gt_i32 s2, 23
	s_mov_b64 s[0:1], 0
	s_cbranch_scc1 .LBB0_150
	s_movk_i32 s88, 0x80
	s_mov_b64 s[0:1], -1
	s_mov_b32 s82, s2

; __device__ __forceinline__ void gemm_run(int tid, f32x16 (&acc)[2][2], GRegs& g, const GOp& o, int K, unsigned char* smem) {
;     ...
;   for (int i = 0; i < 4; i++) {
;     *(u32x4*)(sbuf + (r0 + i * 32) * LDK + sg * 8) = g.a[i];
;     *(u32x4*)(sbuf + 128 * LDK + (r0 + i * 32) * LDK + sg * 8) = g.b[i];
;   }
;   if (nk > 1) {
; #pragma unroll
;     for (int i = 0; i < 4; i++) {
;       g.a[i] = *(const u32x4*)(Ap + (size_t)i * 32 * o.lda + 64);
;       g.b[i] = *(const u32x4*)(Bp + o.bs.o[i] + 64);
;     }
;   }
;   __syncthreads();
;   const int lane = tid & 63, fr = lane & 31, fh = lane >> 5;
;   for (int k = 0; k < nk; k++) {
;     bf16r* cur = sbuf + (k & 1) * (256 * LDK);
;     bf16r* nxt = sbuf + ((k & 1) ^ 1) * (256 * LDK);
;     const bf16r* As = cur + (wm * 64 + fr) * LDK + fh * 8;
;     const bf16r* Bs = cur + 128 * LDK + (wn * 64 + fr) * LDK + fh * 8;
;     const bool wr = (k + 1 < nk), ld = (k + 2 < nk);
;     bf16x8 fa[2][2], fb[2][2];
;     fa[0][0] = *(const bf16x8*)(As);
;     fa[0][1] = *(const bf16x8*)(As + 32 * LDK);
;     fb[0][0] = *(const bf16x8*)(Bs);
;     fb[0][1] = *(const bf16x8*)(Bs + 32 * LDK);
; #pragma unroll
;     for (int i = 0; i < 4; i++) {
;       if (wr) {
;         *(u32x4*)(nxt + (r0 + i * 32) * LDK + sg * 8) = g.a[i];
;         *(u32x4*)(nxt + 128 * LDK + (r0 + i * 32) * LDK + sg * 8) = g.b[i];
;       }
;       if (ld) {
;         g.a[i] = *(const u32x4*)(Ap + (size_t)i * 32 * o.lda + (k + 2) * 64);
;         g.b[i] = *(const u32x4*)(Bp + o.bs.o[i] + (k + 2) * 64);
;       }
;       if (i < 3) {
;         fa[(i + 1) & 1][0] = *(const bf16x8*)(As + (i + 1) * 16);
;         fa[(i + 1) & 1][1] = *(const bf16x8*)(As + 32 * LDK + (i + 1) * 16);
;         fb[(i + 1) & 1][0] = *(const bf16x8*)(Bs + (i + 1) * 16);
;         fb[(i + 1) & 1][1] = *(const bf16x8*)(Bs + 32 * LDK + (i + 1) * 16);
;       }
;       __builtin_amdgcn_sched_barrier(0);
;       __builtin_amdgcn_s_setprio(1);
;       acc[0][0] = __builtin_amdgcn_mfma_f32_32x32x16_bf16(fa[i & 1][0], fb[i & 1][0], acc[0][0], 0, 0, 0);
;       acc[0][1] = __builtin_amdgcn_mfma_f32_32x32x16_bf16(fa[i & 1][0], fb[i & 1][1], acc[0][1], 0, 0, 0);
;       acc[1][0] = __builtin_amdgcn_mfma_f32_32x32x16_bf16(fa[i & 1][1], fb[i & 1][0], acc[1][0], 0, 0, 0);
;       acc[1][1] = __builtin_amdgcn_mfma_f32_32x32x16_bf16(fa[i & 1][1], fb[i & 1][1], acc[1][1], 0, 0, 0);
.LBB0_466:
	s_ashr_i32 s7, s6, 31
	s_lshl_b64 s[4:5], s[6:7], 18
	s_ashr_i32 s9, s8, 31
	s_waitcnt vmcnt(7)
	ds_write_b128 v100, v[64:67]
	s_waitcnt vmcnt(6)
	ds_write_b128 v100, v[68:71] offset:18432
	s_waitcnt vmcnt(5)
	ds_write_b128 v100, v[72:75] offset:4608
	s_waitcnt vmcnt(4)
	ds_write_b128 v100, v[76:79] offset:23040
	s_waitcnt vmcnt(3)
	ds_write_b128 v100, v[80:83] offset:9216
	s_waitcnt vmcnt(2)
	ds_write_b128 v100, v[84:87] offset:27648
	s_waitcnt vmcnt(1)
	ds_write_b128 v100, v[88:91] offset:13824
	s_waitcnt vmcnt(0)
	ds_write_b128 v100, v[92:95] offset:32256
	v_lshl_add_u64 v[64:65], v[102:103], 0, s[4:5]
	s_lshl_b64 s[10:11], s[8:9], 18
	v_add_co_u32_e32 v72, vcc, s2, v64
	v_lshl_add_u64 v[106:107], v[98:99], 0, s[10:11]
	s_nop 0
	v_addc_co_u32_e32 v73, vcc, 0, v65, vcc
	v_add_co_u32_e32 v76, vcc, s2, v106
	global_load_dwordx4 v[0:3], v[64:65], off offset:128
	global_load_dwordx4 v[4:7], v[106:107], off offset:128
	v_addc_co_u32_e32 v77, vcc, 0, v107, vcc
	v_add_co_u32_e32 v80, vcc, s94, v64
	global_load_dwordx4 v[66:69], v[72:73], off offset:128
	global_load_dwordx4 v[110:113], v[76:77], off offset:128
	v_addc_co_u32_e32 v81, vcc, 0, v65, vcc
	v_add_co_u32_e32 v84, vcc, s94, v106
	s_nop 1
	v_addc_co_u32_e32 v85, vcc, 0, v107, vcc
	v_add_co_u32_e32 v88, vcc, s95, v64
	global_load_dwordx4 v[114:117], v[80:81], off offset:128
	global_load_dwordx4 v[118:121], v[84:85], off offset:128
	v_addc_co_u32_e32 v89, vcc, 0, v65, vcc
	v_add_co_u32_e32 v92, vcc, s95, v106
	s_nop 1
	v_addc_co_u32_e32 v93, vcc, 0, v107, vcc
	global_load_dwordx4 v[122:125], v[88:89], off offset:128
	global_load_dwordx4 v[126:129], v[92:93], off offset:128
	s_waitcnt lgkmcnt(0)
	s_barrier
	global_load_dwordx4 v[130:133], v[64:65], off offset:256
	global_load_dwordx4 v[134:137], v[106:107], off offset:256
	ds_read_b128 v[8:11], v104
	ds_read_b128 v[32:35], v104 offset:4608
	ds_read_b128 v[12:15], v101 offset:18432
	ds_read_b128 v[36:39], v101 offset:23040
	s_waitcnt vmcnt(9)
	ds_write_b128 v100, v[0:3] offset:36864
	s_waitcnt vmcnt(8)
	ds_write_b128 v100, v[4:7] offset:55296
	ds_read_b128 v[138:141], v104 offset:32
	ds_read_b128 v[142:145], v104 offset:4640
	ds_read_b128 v[146:149], v101 offset:18464
	ds_read_b128 v[150:153], v101 offset:23072
	s_waitcnt lgkmcnt(7)
	v_mfma_f32_32x32x16_bf16 v[16:31], v[8:11], v[12:15], 0
	s_waitcnt lgkmcnt(6)
	v_mfma_f32_32x32x16_bf16 v[48:63], v[8:11], v[36:39], 0
	v_mfma_f32_32x32x16_bf16 v[0:15], v[32:35], v[12:15], 0
	v_mfma_f32_32x32x16_bf16 v[32:47], v[32:35], v[36:39], 0
	global_load_dwordx4 v[154:157], v[72:73], off offset:256
	global_load_dwordx4 v[158:161], v[76:77], off offset:256
	s_waitcnt vmcnt(9)
	ds_write_b128 v100, v[66:69] offset:41472
	s_waitcnt vmcnt(8)
	ds_write_b128 v100, v[110:113] offset:59904
	ds_read_b128 v[66:69], v104 offset:64
	ds_read_b128 v[110:113], v104 offset:4672
	ds_read_b128 v[162:165], v101 offset:18496
	ds_read_b128 v[166:169], v101 offset:23104
	s_waitcnt lgkmcnt(7)
	v_mfma_f32_32x32x16_bf16 v[16:31], v[138:141], v[146:149], v[16:31]
	s_waitcnt lgkmcnt(6)
	v_mfma_f32_32x32x16_bf16 v[48:63], v[138:141], v[150:153], v[48:63]
	v_mfma_f32_32x32x16_bf16 v[0:15], v[142:145], v[146:149], v[0:15]
	v_mfma_f32_32x32x16_bf16 v[32:47], v[142:145], v[150:153], v[32:47]
	global_load_dwordx4 v[138:141], v[80:81], off offset:256
	global_load_dwordx4 v[142:145], v[84:85], off offset:256
	s_waitcnt vmcnt(9)
	ds_write_b128 v100, v[114:117] offset:46080
	s_waitcnt vmcnt(8)
	ds_write_b128 v100, v[118:121] offset:64512
	ds_read_b128 v[114:117], v104 offset:96
	ds_read_b128 v[118:121], v104 offset:4704
	ds_read_b128 v[146:149], v101 offset:18528
	ds_read_b128 v[150:153], v101 offset:23136
	s_waitcnt lgkmcnt(7)
	v_mfma_f32_32x32x16_bf16 v[16:31], v[66:69], v[162:165], v[16:31]
	s_waitcnt lgkmcnt(6)
	v_mfma_f32_32x32x16_bf16 v[48:63], v[66:69], v[166:169], v[48:63]
	v_mfma_f32_32x32x16_bf16 v[0:15], v[110:113], v[162:165], v[0:15]
	v_mfma_f32_32x32x16_bf16 v[32:47], v[110:113], v[166:169], v[32:47]
	global_load_dwordx4 v[66:69], v[88:89], off offset:256
	global_load_dwordx4 v[110:113], v[92:93], off offset:256
	s_waitcnt vmcnt(9)
	ds_write_b128 v100, v[122:125] offset:50688
	s_waitcnt vmcnt(8)
	ds_write_b128 v105, v[126:129] offset:13824
	s_waitcnt lgkmcnt(3)
	v_mfma_f32_32x32x16_bf16 v[16:31], v[114:117], v[146:149], v[16:31]
	s_waitcnt lgkmcnt(2)
	v_mfma_f32_32x32x16_bf16 v[48:63], v[114:117], v[150:153], v[48:63]
	v_mfma_f32_32x32x16_bf16 v[0:15], v[118:121], v[146:149], v[0:15]
	v_mfma_f32_32x32x16_bf16 v[32:47], v[118:121], v[150:153], v[32:47]
	s_waitcnt lgkmcnt(0)
	s_barrier
; __device__ __forceinline__ void gemm_run(int tid, f32x16 (&acc)[2][2], GRegs& g, const GOp& o, int K, unsigned char* smem) {
;     ...
;   for (int k = 0; k < nk; k++) {
;     bf16r* cur = sbuf + (k & 1) * (256 * LDK);
;     bf16r* nxt = sbuf + ((k & 1) ^ 1) * (256 * LDK);
;     const bf16r* As = cur + (wm * 64 + fr) * LDK + fh * 8;
;     const bf16r* Bs = cur + 128 * LDK + (wn * 64 + fr) * LDK + fh * 8;
;     const bool wr = (k + 1 < nk), ld = (k + 2 < nk);
;     bf16x8 fa[2][2], fb[2][2];
;     fa[0][0] = *(const bf16x8*)(As);
;     fa[0][1] = *(const bf16x8*)(As + 32 * LDK);
;     fb[0][0] = *(const bf16x8*)(Bs);
;     fb[0][1] = *(const bf16x8*)(Bs + 32 * LDK);
; #pragma unroll
;     for (int i = 0; i < 4; i++) {
;       if (wr) {
;         *(u32x4*)(nxt + (r0 + i * 32) * LDK + sg * 8) = g.a[i];
;         *(u32x4*)(nxt + 128 * LDK + (r0 + i * 32) * LDK + sg * 8) = g.b[i];
;       }
;       if (ld) {
;         g.a[i] = *(const u32x4*)(Ap + (size_t)i * 32 * o.lda + (k + 2) * 64);
;         g.b[i] = *(const u32x4*)(Bp + o.bs.o[i] + (k + 2) * 64);
;       }
;       if (i < 3) {
;         fa[(i + 1) & 1][0] = *(const bf16x8*)(As + (i + 1) * 16);
;         fa[(i + 1) & 1][1] = *(const bf16x8*)(As + 32 * LDK + (i + 1) * 16);
;         fb[(i + 1) & 1][0] = *(const bf16x8*)(Bs + (i + 1) * 16);
;         fb[(i + 1) & 1][1] = *(const bf16x8*)(Bs + 32 * LDK + (i + 1) * 16);
;       }
;       __builtin_amdgcn_sched_barrier(0);
;       __builtin_amdgcn_s_setprio(1);
;       acc[0][0] = __builtin_amdgcn_mfma_f32_32x32x16_bf16(fa[i & 1][0], fb[i & 1][0], acc[0][0], 0, 0, 0);
;       acc[0][1] = __builtin_amdgcn_mfma_f32_32x32x16_bf16(fa[i & 1][0], fb[i & 1][1], acc[0][1], 0, 0, 0);
;       acc[1][0] = __builtin_amdgcn_mfma_f32_32x32x16_bf16(fa[i & 1][1], fb[i & 1][0], acc[1][0], 0, 0, 0);
;       acc[1][1] = __builtin_amdgcn_mfma_f32_32x32x16_bf16(fa[i & 1][1], fb[i & 1][1], acc[1][1], 0, 0, 0);
;       __builtin_amdgcn_s_setprio(0);
;     }
	global_load_dwordx4 v[114:117], v[64:65], off offset:384
	global_load_dwordx4 v[118:121], v[106:107], off offset:384
	ds_read_b128 v[122:125], v104 offset:36864
	ds_read_b128 v[126:129], v104 offset:41472
	ds_read_b128 v[146:149], v101 offset:55296
	ds_read_b128 v[150:153], v101 offset:59904
	s_waitcnt vmcnt(9)
	ds_write_b128 v100, v[130:133]
	s_waitcnt vmcnt(8)
	ds_write_b128 v100, v[134:137] offset:18432
	ds_read_b128 v[130:133], v104 offset:36896
	ds_read_b128 v[134:137], v104 offset:41504
	ds_read_b128 v[162:165], v101 offset:55328
	ds_read_b128 v[166:169], v101 offset:59936
	s_waitcnt lgkmcnt(7)
	v_mfma_f32_32x32x16_bf16 v[16:31], v[122:125], v[146:149], v[16:31]
	s_waitcnt lgkmcnt(6)
	v_mfma_f32_32x32x16_bf16 v[48:63], v[122:125], v[150:153], v[48:63]
	v_mfma_f32_32x32x16_bf16 v[0:15], v[126:129], v[146:149], v[0:15]
	v_mfma_f32_32x32x16_bf16 v[32:47], v[126:129], v[150:153], v[32:47]
	global_load_dwordx4 v[122:125], v[72:73], off offset:384
	global_load_dwordx4 v[126:129], v[76:77], off offset:384
	s_waitcnt vmcnt(9)
	ds_write_b128 v100, v[154:157] offset:4608
	s_waitcnt vmcnt(8)
	ds_write_b128 v100, v[158:161] offset:23040
	ds_read_b128 v[146:149], v104 offset:36928
	ds_read_b128 v[150:153], v104 offset:41536
	ds_read_b128 v[154:157], v101 offset:55360
	ds_read_b128 v[158:161], v101 offset:59968
	s_waitcnt lgkmcnt(7)
	v_mfma_f32_32x32x16_bf16 v[16:31], v[130:133], v[162:165], v[16:31]
	s_waitcnt lgkmcnt(6)
	v_mfma_f32_32x32x16_bf16 v[48:63], v[130:133], v[166:169], v[48:63]
	v_mfma_f32_32x32x16_bf16 v[0:15], v[134:137], v[162:165], v[0:15]
	v_mfma_f32_32x32x16_bf16 v[32:47], v[134:137], v[166:169], v[32:47]
	global_load_dwordx4 v[130:133], v[80:81], off offset:384
	global_load_dwordx4 v[134:137], v[84:85], off offset:384
	s_waitcnt vmcnt(9)
	ds_write_b128 v100, v[138:141] offset:9216
	s_waitcnt vmcnt(8)
	ds_write_b128 v100, v[142:145] offset:27648
	ds_read_b128 v[138:141], v104 offset:36960
	ds_read_b128 v[142:145], v104 offset:41568
	ds_read_b128 v[162:165], v101 offset:55392
	ds_read_b128 v[166:169], v101 offset:60000
	s_waitcnt lgkmcnt(7)
	v_mfma_f32_32x32x16_bf16 v[16:31], v[146:149], v[154:157], v[16:31]
	s_waitcnt lgkmcnt(6)
	v_mfma_f32_32x32x16_bf16 v[48:63], v[146:149], v[158:161], v[48:63]
	v_mfma_f32_32x32x16_bf16 v[0:15], v[150:153], v[154:157], v[0:15]
	v_mfma_f32_32x32x16_bf16 v[32:47], v[150:153], v[158:161], v[32:47]
	global_load_dwordx4 v[146:149], v[88:89], off offset:384
	global_load_dwordx4 v[150:153], v[92:93], off offset:384
	s_waitcnt vmcnt(9)
	ds_write_b128 v100, v[66:69] offset:13824
	s_waitcnt vmcnt(8)
	ds_write_b128 v100, v[110:113] offset:32256
	s_waitcnt lgkmcnt(3)
	v_mfma_f32_32x32x16_bf16 v[16:31], v[138:141], v[162:165], v[16:31]
	s_waitcnt lgkmcnt(2)
	v_mfma_f32_32x32x16_bf16 v[48:63], v[138:141], v[166:169], v[48:63]
	v_mfma_f32_32x32x16_bf16 v[0:15], v[142:145], v[162:165], v[0:15]
	v_mfma_f32_32x32x16_bf16 v[32:47], v[142:145], v[166:169], v[32:47]
	s_waitcnt lgkmcnt(0)
	s_barrier
	global_load_dwordx4 v[66:69], v[64:65], off offset:512
	global_load_dwordx4 v[110:113], v[106:107], off offset:512
	ds_read_b128 v[138:141], v104
	ds_read_b128 v[142:145], v104 offset:4608
	ds_read_b128 v[154:157], v101 offset:18432
	ds_read_b128 v[158:161], v101 offset:23040
	s_waitcnt vmcnt(9)
	ds_write_b128 v100, v[114:117] offset:36864
	s_waitcnt vmcnt(8)
	ds_write_b128 v100, v[118:121] offset:55296
	ds_read_b128 v[114:117], v104 offset:32
	ds_read_b128 v[118:121], v104 offset:4640
	ds_read_b128 v[162:165], v101 offset:18464
	ds_read_b128 v[166:169], v101 offset:23072
	s_waitcnt lgkmcnt(7)
	v_mfma_f32_32x32x16_bf16 v[16:31], v[138:141], v[154:157], v[16:31]
	s_waitcnt lgkmcnt(6)
	v_mfma_f32_32x32x16_bf16 v[48:63], v[138:141], v[158:161], v[48:63]
	v_mfma_f32_32x32x16_bf16 v[0:15], v[142:145], v[154:157], v[0:15]
	v_mfma_f32_32x32x16_bf16 v[32:47], v[142:145], v[158:161], v[32:47]
	global_load_dwordx4 v[138:141], v[72:73], off offset:512
	global_load_dwordx4 v[142:145], v[76:77], off offset:512
	s_waitcnt vmcnt(9)
	ds_write_b128 v100, v[122:125] offset:41472
	s_waitcnt vmcnt(8)
	ds_write_b128 v100, v[126:129] offset:59904
	ds_read_b128 v[122:125], v104 offset:64
	ds_read_b128 v[126:129], v104 offset:4672
	ds_read_b128 v[154:157], v101 offset:18496
	ds_read_b128 v[158:161], v101 offset:23104
	s_waitcnt lgkmcnt(7)
	v_mfma_f32_32x32x16_bf16 v[16:31], v[114:117], v[162:165], v[16:31]
	s_waitcnt lgkmcnt(6)
	v_mfma_f32_32x32x16_bf16 v[48:63], v[114:117], v[166:169], v[48:63]
	v_mfma_f32_32x32x16_bf16 v[0:15], v[118:121], v[162:165], v[0:15]
	v_mfma_f32_32x32x16_bf16 v[32:47], v[118:121], v[166:169], v[32:47]
	global_load_dwordx4 v[114:117], v[80:81], off offset:512
	global_load_dwordx4 v[118:121], v[84:85], off offset:512
	s_waitcnt vmcnt(9)
	ds_write_b128 v100, v[130:133] offset:46080
	s_waitcnt vmcnt(8)
	ds_write_b128 v100, v[134:137] offset:64512
	ds_read_b128 v[130:133], v104 offset:96
	ds_read_b128 v[134:137], v104 offset:4704
	ds_read_b128 v[162:165], v101 offset:18528
	ds_read_b128 v[166:169], v101 offset:23136
	s_waitcnt lgkmcnt(7)
	v_mfma_f32_32x32x16_bf16 v[16:31], v[122:125], v[154:157], v[16:31]
	s_waitcnt lgkmcnt(6)
	v_mfma_f32_32x32x16_bf16 v[48:63], v[122:125], v[158:161], v[48:63]
	v_mfma_f32_32x32x16_bf16 v[0:15], v[126:129], v[154:157], v[0:15]
	v_mfma_f32_32x32x16_bf16 v[32:47], v[126:129], v[158:161], v[32:47]
	global_load_dwordx4 v[122:125], v[88:89], off offset:512
	global_load_dwordx4 v[126:129], v[92:93], off offset:512
	s_waitcnt vmcnt(9)
	ds_write_b128 v100, v[146:149] offset:50688
	s_waitcnt vmcnt(8)
	ds_write_b128 v105, v[150:153] offset:13824
	s_waitcnt lgkmcnt(3)
	v_mfma_f32_32x32x16_bf16 v[16:31], v[130:133], v[162:165], v[16:31]
	s_waitcnt lgkmcnt(2)
	v_mfma_f32_32x32x16_bf16 v[48:63], v[130:133], v[166:169], v[48:63]
	v_mfma_f32_32x32x16_bf16 v[0:15], v[134:137], v[162:165], v[0:15]
	v_mfma_f32_32x32x16_bf16 v[32:47], v[134:137], v[166:169], v[32:47]
	s_waitcnt lgkmcnt(0)
	s_barrier
; __device__ __forceinline__ void gemm_run(int tid, f32x16 (&acc)[2][2], GRegs& g, const GOp& o, int K, unsigned char* smem) {
;     ...
;   for (int k = 0; k < nk; k++) {
;     bf16r* cur = sbuf + (k & 1) * (256 * LDK);
;     bf16r* nxt = sbuf + ((k & 1) ^ 1) * (256 * LDK);
;     const bf16r* As = cur + (wm * 64 + fr) * LDK + fh * 8;
;     const bf16r* Bs = cur + 128 * LDK + (wn * 64 + fr) * LDK + fh * 8;
;     const bool wr = (k + 1 < nk), ld = (k + 2 < nk);
;     bf16x8 fa[2][2], fb[2][2];
;     fa[0][0] = *(const bf16x8*)(As);
;     fa[0][1] = *(const bf16x8*)(As + 32 * LDK);
;     fb[0][0] = *(const bf16x8*)(Bs);
;     fb[0][1] = *(const bf16x8*)(Bs + 32 * LDK);
; #pragma unroll
;     for (int i = 0; i < 4; i++) {
;       if (wr) {
;         *(u32x4*)(nxt + (r0 + i * 32) * LDK + sg * 8) = g.a[i];
;         *(u32x4*)(nxt + 128 * LDK + (r0 + i * 32) * LDK + sg * 8) = g.b[i];
;       }
;       if (ld) {
;         g.a[i] = *(const u32x4*)(Ap + (size_t)i * 32 * o.lda + (k + 2) * 64);
;         g.b[i] = *(const u32x4*)(Bp + o.bs.o[i] + (k + 2) * 64);
;       }
;       if (i < 3) {
;         fa[(i + 1) & 1][0] = *(const bf16x8*)(As + (i + 1) * 16);
;         fa[(i + 1) & 1][1] = *(const bf16x8*)(As + 32 * LDK + (i + 1) * 16);
;         fb[(i + 1) & 1][0] = *(const bf16x8*)(Bs + (i + 1) * 16);
;         fb[(i + 1) & 1][1] = *(const bf16x8*)(Bs + 32 * LDK + (i + 1) * 16);
;       }
;       __builtin_amdgcn_sched_barrier(0);
;       __builtin_amdgcn_s_setprio(1);
;       acc[0][0] = __builtin_amdgcn_mfma_f32_32x32x16_bf16(fa[i & 1][0], fb[i & 1][0], acc[0][0], 0, 0, 0);
;       acc[0][1] = __builtin_amdgcn_mfma_f32_32x32x16_bf16(fa[i & 1][0], fb[i & 1][1], acc[0][1], 0, 0, 0);
;       acc[1][0] = __builtin_amdgcn_mfma_f32_32x32x16_bf16(fa[i & 1][1], fb[i & 1][0], acc[1][0], 0, 0, 0);
;       acc[1][1] = __builtin_amdgcn_mfma_f32_32x32x16_bf16(fa[i & 1][1], fb[i & 1][1], acc[1][1], 0, 0, 0);
;       __builtin_amdgcn_s_setprio(0);
;     }
	global_load_dwordx4 v[130:133], v[64:65], off offset:640
	global_load_dwordx4 v[134:137], v[106:107], off offset:640
	ds_read_b128 v[146:149], v104 offset:36864
	ds_read_b128 v[150:153], v104 offset:41472
	ds_read_b128 v[154:157], v101 offset:55296
	ds_read_b128 v[158:161], v101 offset:59904
	s_waitcnt vmcnt(9)
	ds_write_b128 v100, v[66:69]
	s_waitcnt vmcnt(8)
	ds_write_b128 v100, v[110:113] offset:18432
	ds_read_b128 v[66:69], v104 offset:36896
	ds_read_b128 v[110:113], v104 offset:41504
	ds_read_b128 v[162:165], v101 offset:55328
	ds_read_b128 v[166:169], v101 offset:59936
	s_waitcnt lgkmcnt(7)
	v_mfma_f32_32x32x16_bf16 v[16:31], v[146:149], v[154:157], v[16:31]
	s_waitcnt lgkmcnt(6)
	v_mfma_f32_32x32x16_bf16 v[48:63], v[146:149], v[158:161], v[48:63]
	v_mfma_f32_32x32x16_bf16 v[0:15], v[150:153], v[154:157], v[0:15]
	v_mfma_f32_32x32x16_bf16 v[32:47], v[150:153], v[158:161], v[32:47]
	global_load_dwordx4 v[146:149], v[72:73], off offset:640
	global_load_dwordx4 v[150:153], v[76:77], off offset:640
	s_waitcnt vmcnt(9)
	ds_write_b128 v100, v[138:141] offset:4608
	s_waitcnt vmcnt(8)
	ds_write_b128 v100, v[142:145] offset:23040
	ds_read_b128 v[138:141], v104 offset:36928
	ds_read_b128 v[142:145], v104 offset:41536
	ds_read_b128 v[154:157], v101 offset:55360
	ds_read_b128 v[158:161], v101 offset:59968
	s_waitcnt lgkmcnt(7)
	v_mfma_f32_32x32x16_bf16 v[16:31], v[66:69], v[162:165], v[16:31]
	s_waitcnt lgkmcnt(6)
	v_mfma_f32_32x32x16_bf16 v[48:63], v[66:69], v[166:169], v[48:63]
	v_mfma_f32_32x32x16_bf16 v[0:15], v[110:113], v[162:165], v[0:15]
	v_mfma_f32_32x32x16_bf16 v[32:47], v[110:113], v[166:169], v[32:47]
	global_load_dwordx4 v[66:69], v[80:81], off offset:640
	global_load_dwordx4 v[110:113], v[84:85], off offset:640
	s_waitcnt vmcnt(9)
	ds_write_b128 v100, v[114:117] offset:9216
	s_waitcnt vmcnt(8)
	ds_write_b128 v100, v[118:121] offset:27648
	ds_read_b128 v[114:117], v104 offset:36960
	ds_read_b128 v[118:121], v104 offset:41568
	ds_read_b128 v[162:165], v101 offset:55392
	ds_read_b128 v[166:169], v101 offset:60000
	s_waitcnt lgkmcnt(7)
	v_mfma_f32_32x32x16_bf16 v[16:31], v[138:141], v[154:157], v[16:31]
	s_waitcnt lgkmcnt(6)
	v_mfma_f32_32x32x16_bf16 v[48:63], v[138:141], v[158:161], v[48:63]
	v_mfma_f32_32x32x16_bf16 v[0:15], v[142:145], v[154:157], v[0:15]
	v_mfma_f32_32x32x16_bf16 v[32:47], v[142:145], v[158:161], v[32:47]
	global_load_dwordx4 v[138:141], v[88:89], off offset:640
	global_load_dwordx4 v[142:145], v[92:93], off offset:640
	s_waitcnt vmcnt(9)
	ds_write_b128 v100, v[122:125] offset:13824
	s_waitcnt vmcnt(8)
	ds_write_b128 v100, v[126:129] offset:32256
	s_waitcnt lgkmcnt(3)
	v_mfma_f32_32x32x16_bf16 v[16:31], v[114:117], v[162:165], v[16:31]
	s_waitcnt lgkmcnt(2)
	v_mfma_f32_32x32x16_bf16 v[48:63], v[114:117], v[166:169], v[48:63]
	v_mfma_f32_32x32x16_bf16 v[0:15], v[118:121], v[162:165], v[0:15]
	v_mfma_f32_32x32x16_bf16 v[32:47], v[118:121], v[166:169], v[32:47]
	s_waitcnt lgkmcnt(0)
	s_barrier
	global_load_dwordx4 v[114:117], v[64:65], off offset:768
	global_load_dwordx4 v[118:121], v[106:107], off offset:768
	ds_read_b128 v[122:125], v104
	ds_read_b128 v[126:129], v104 offset:4608
	ds_read_b128 v[154:157], v101 offset:18432
	ds_read_b128 v[158:161], v101 offset:23040
	s_waitcnt vmcnt(9)
	ds_write_b128 v100, v[130:133] offset:36864
	s_waitcnt vmcnt(8)
	ds_write_b128 v100, v[134:137] offset:55296
	ds_read_b128 v[130:133], v104 offset:32
	ds_read_b128 v[134:137], v104 offset:4640
	ds_read_b128 v[162:165], v101 offset:18464
	ds_read_b128 v[166:169], v101 offset:23072
	s_waitcnt lgkmcnt(7)
	v_mfma_f32_32x32x16_bf16 v[16:31], v[122:125], v[154:157], v[16:31]
	s_waitcnt lgkmcnt(6)
	v_mfma_f32_32x32x16_bf16 v[48:63], v[122:125], v[158:161], v[48:63]
	v_mfma_f32_32x32x16_bf16 v[0:15], v[126:129], v[154:157], v[0:15]
	v_mfma_f32_32x32x16_bf16 v[32:47], v[126:129], v[158:161], v[32:47]
	global_load_dwordx4 v[122:125], v[72:73], off offset:768
	global_load_dwordx4 v[126:129], v[76:77], off offset:768
	s_waitcnt vmcnt(9)
	ds_write_b128 v100, v[146:149] offset:41472
	s_waitcnt vmcnt(8)
	ds_write_b128 v100, v[150:153] offset:59904
	ds_read_b128 v[146:149], v104 offset:64
	ds_read_b128 v[150:153], v104 offset:4672
	ds_read_b128 v[154:157], v101 offset:18496
	ds_read_b128 v[158:161], v101 offset:23104
	s_waitcnt lgkmcnt(7)
	v_mfma_f32_32x32x16_bf16 v[16:31], v[130:133], v[162:165], v[16:31]
	s_waitcnt lgkmcnt(6)
	v_mfma_f32_32x32x16_bf16 v[48:63], v[130:133], v[166:169], v[48:63]
	v_mfma_f32_32x32x16_bf16 v[0:15], v[134:137], v[162:165], v[0:15]
	v_mfma_f32_32x32x16_bf16 v[32:47], v[134:137], v[166:169], v[32:47]
	global_load_dwordx4 v[130:133], v[80:81], off offset:768
	global_load_dwordx4 v[134:137], v[84:85], off offset:768
	s_waitcnt vmcnt(9)
	ds_write_b128 v100, v[66:69] offset:46080
	s_waitcnt vmcnt(8)
	ds_write_b128 v100, v[110:113] offset:64512
	ds_read_b128 v[66:69], v104 offset:96
	ds_read_b128 v[110:113], v104 offset:4704
	ds_read_b128 v[162:165], v101 offset:18528
	ds_read_b128 v[166:169], v101 offset:23136
	s_waitcnt lgkmcnt(7)
	v_mfma_f32_32x32x16_bf16 v[16:31], v[146:149], v[154:157], v[16:31]
	s_waitcnt lgkmcnt(6)
	v_mfma_f32_32x32x16_bf16 v[48:63], v[146:149], v[158:161], v[48:63]
	v_mfma_f32_32x32x16_bf16 v[0:15], v[150:153], v[154:157], v[0:15]
	v_mfma_f32_32x32x16_bf16 v[32:47], v[150:153], v[158:161], v[32:47]
	global_load_dwordx4 v[146:149], v[88:89], off offset:768
	global_load_dwordx4 v[150:153], v[92:93], off offset:768
	s_waitcnt vmcnt(9)
	ds_write_b128 v100, v[138:141] offset:50688
	s_waitcnt vmcnt(8)
	ds_write_b128 v105, v[142:145] offset:13824
	s_waitcnt lgkmcnt(3)
	v_mfma_f32_32x32x16_bf16 v[16:31], v[66:69], v[162:165], v[16:31]
	s_waitcnt lgkmcnt(2)
	v_mfma_f32_32x32x16_bf16 v[48:63], v[66:69], v[166:169], v[48:63]
	v_mfma_f32_32x32x16_bf16 v[0:15], v[110:113], v[162:165], v[0:15]
	v_mfma_f32_32x32x16_bf16 v[32:47], v[110:113], v[166:169], v[32:47]
	s_waitcnt lgkmcnt(0)
	s_barrier
; __device__ __forceinline__ void gemm_run(int tid, f32x16 (&acc)[2][2], GRegs& g, const GOp& o, int K, unsigned char* smem) {
;     ...
;   for (int k = 0; k < nk; k++) {
;     bf16r* cur = sbuf + (k & 1) * (256 * LDK);
;     bf16r* nxt = sbuf + ((k & 1) ^ 1) * (256 * LDK);
;     const bf16r* As = cur + (wm * 64 + fr) * LDK + fh * 8;
;     const bf16r* Bs = cur + 128 * LDK + (wn * 64 + fr) * LDK + fh * 8;
;     const bool wr = (k + 1 < nk), ld = (k + 2 < nk);
;     bf16x8 fa[2][2], fb[2][2];
;     fa[0][0] = *(const bf16x8*)(As);
;     fa[0][1] = *(const bf16x8*)(As + 32 * LDK);
;     fb[0][0] = *(const bf16x8*)(Bs);
;     fb[0][1] = *(const bf16x8*)(Bs + 32 * LDK);
; #pragma unroll
;     for (int i = 0; i < 4; i++) {
;       if (wr) {
;         *(u32x4*)(nxt + (r0 + i * 32) * LDK + sg * 8) = g.a[i];
;         *(u32x4*)(nxt + 128 * LDK + (r0 + i * 32) * LDK + sg * 8) = g.b[i];
;       }
;       if (ld) {
;         g.a[i] = *(const u32x4*)(Ap + (size_t)i * 32 * o.lda + (k + 2) * 64);
;         g.b[i] = *(const u32x4*)(Bp + o.bs.o[i] + (k + 2) * 64);
;       }
;       if (i < 3) {
;         fa[(i + 1) & 1][0] = *(const bf16x8*)(As + (i + 1) * 16);
;         fa[(i + 1) & 1][1] = *(const bf16x8*)(As + 32 * LDK + (i + 1) * 16);
;         fb[(i + 1) & 1][0] = *(const bf16x8*)(Bs + (i + 1) * 16);
;         fb[(i + 1) & 1][1] = *(const bf16x8*)(Bs + 32 * LDK + (i + 1) * 16);
;       }
;       __builtin_amdgcn_sched_barrier(0);
;       __builtin_amdgcn_s_setprio(1);
;       acc[0][0] = __builtin_amdgcn_mfma_f32_32x32x16_bf16(fa[i & 1][0], fb[i & 1][0], acc[0][0], 0, 0, 0);
;       acc[0][1] = __builtin_amdgcn_mfma_f32_32x32x16_bf16(fa[i & 1][0], fb[i & 1][1], acc[0][1], 0, 0, 0);
;       acc[1][0] = __builtin_amdgcn_mfma_f32_32x32x16_bf16(fa[i & 1][1], fb[i & 1][0], acc[1][0], 0, 0, 0);
;       acc[1][1] = __builtin_amdgcn_mfma_f32_32x32x16_bf16(fa[i & 1][1], fb[i & 1][1], acc[1][1], 0, 0, 0);
;       __builtin_amdgcn_s_setprio(0);
;     }
	global_load_dwordx4 v[66:69], v[64:65], off offset:896
	global_load_dwordx4 v[110:113], v[106:107], off offset:896
	ds_read_b128 v[138:141], v104 offset:36864
	ds_read_b128 v[142:145], v104 offset:41472
	ds_read_b128 v[154:157], v101 offset:55296
	ds_read_b128 v[158:161], v101 offset:59904
	s_waitcnt vmcnt(9)
	ds_write_b128 v100, v[114:117]
	s_waitcnt vmcnt(8)
	ds_write_b128 v100, v[118:121] offset:18432
	ds_read_b128 v[114:117], v104 offset:36896
	ds_read_b128 v[118:121], v104 offset:41504
	ds_read_b128 v[162:165], v101 offset:55328
	ds_read_b128 v[166:169], v101 offset:59936
	s_waitcnt lgkmcnt(7)
	v_mfma_f32_32x32x16_bf16 v[16:31], v[138:141], v[154:157], v[16:31]
	s_waitcnt lgkmcnt(6)
	v_mfma_f32_32x32x16_bf16 v[48:63], v[138:141], v[158:161], v[48:63]
	v_mfma_f32_32x32x16_bf16 v[0:15], v[142:145], v[154:157], v[0:15]
	v_mfma_f32_32x32x16_bf16 v[32:47], v[142:145], v[158:161], v[32:47]
	global_load_dwordx4 v[138:141], v[72:73], off offset:896
	global_load_dwordx4 v[142:145], v[76:77], off offset:896
	s_waitcnt vmcnt(9)
	ds_write_b128 v100, v[122:125] offset:4608
	s_waitcnt vmcnt(8)
	ds_write_b128 v100, v[126:129] offset:23040
	ds_read_b128 v[122:125], v104 offset:36928
	ds_read_b128 v[126:129], v104 offset:41536
	ds_read_b128 v[154:157], v101 offset:55360
	ds_read_b128 v[158:161], v101 offset:59968
	s_waitcnt lgkmcnt(7)
	v_mfma_f32_32x32x16_bf16 v[16:31], v[114:117], v[162:165], v[16:31]
	s_waitcnt lgkmcnt(6)
	v_mfma_f32_32x32x16_bf16 v[48:63], v[114:117], v[166:169], v[48:63]
	v_mfma_f32_32x32x16_bf16 v[0:15], v[118:121], v[162:165], v[0:15]
	v_mfma_f32_32x32x16_bf16 v[32:47], v[118:121], v[166:169], v[32:47]
	global_load_dwordx4 v[114:117], v[80:81], off offset:896
	global_load_dwordx4 v[118:121], v[84:85], off offset:896
	s_waitcnt vmcnt(9)
	ds_write_b128 v100, v[130:133] offset:9216
	s_waitcnt vmcnt(8)
	ds_write_b128 v100, v[134:137] offset:27648
	ds_read_b128 v[130:133], v104 offset:36960
	ds_read_b128 v[134:137], v104 offset:41568
	ds_read_b128 v[162:165], v101 offset:55392
	ds_read_b128 v[166:169], v101 offset:60000
	s_waitcnt lgkmcnt(7)
	v_mfma_f32_32x32x16_bf16 v[16:31], v[122:125], v[154:157], v[16:31]
	s_waitcnt lgkmcnt(6)
	v_mfma_f32_32x32x16_bf16 v[48:63], v[122:125], v[158:161], v[48:63]
	v_mfma_f32_32x32x16_bf16 v[0:15], v[126:129], v[154:157], v[0:15]
	v_mfma_f32_32x32x16_bf16 v[32:47], v[126:129], v[158:161], v[32:47]
	global_load_dwordx4 v[122:125], v[88:89], off offset:896
	global_load_dwordx4 v[126:129], v[92:93], off offset:896
	s_waitcnt vmcnt(9)
	ds_write_b128 v100, v[146:149] offset:13824
	s_waitcnt vmcnt(8)
	ds_write_b128 v100, v[150:153] offset:32256
	s_waitcnt lgkmcnt(3)
	v_mfma_f32_32x32x16_bf16 v[16:31], v[130:133], v[162:165], v[16:31]
	s_waitcnt lgkmcnt(2)
	v_mfma_f32_32x32x16_bf16 v[48:63], v[130:133], v[166:169], v[48:63]
	v_mfma_f32_32x32x16_bf16 v[0:15], v[134:137], v[162:165], v[0:15]
	v_mfma_f32_32x32x16_bf16 v[32:47], v[134:137], v[166:169], v[32:47]
	s_waitcnt lgkmcnt(0)
	s_barrier
	global_load_dwordx4 v[130:133], v[64:65], off offset:1024
	global_load_dwordx4 v[134:137], v[106:107], off offset:1024
	ds_read_b128 v[146:149], v104
	ds_read_b128 v[150:153], v104 offset:4608
	ds_read_b128 v[154:157], v101 offset:18432
	ds_read_b128 v[158:161], v101 offset:23040
	s_waitcnt vmcnt(9)
	ds_write_b128 v100, v[66:69] offset:36864
	s_waitcnt vmcnt(8)
	ds_write_b128 v100, v[110:113] offset:55296
	ds_read_b128 v[66:69], v104 offset:32
	ds_read_b128 v[110:113], v104 offset:4640
	ds_read_b128 v[162:165], v101 offset:18464
	ds_read_b128 v[166:169], v101 offset:23072
	s_waitcnt lgkmcnt(7)
	v_mfma_f32_32x32x16_bf16 v[16:31], v[146:149], v[154:157], v[16:31]
	s_waitcnt lgkmcnt(6)
	v_mfma_f32_32x32x16_bf16 v[48:63], v[146:149], v[158:161], v[48:63]
	v_mfma_f32_32x32x16_bf16 v[0:15], v[150:153], v[154:157], v[0:15]
	v_mfma_f32_32x32x16_bf16 v[32:47], v[150:153], v[158:161], v[32:47]
	global_load_dwordx4 v[146:149], v[72:73], off offset:1024
	global_load_dwordx4 v[150:153], v[76:77], off offset:1024
	s_waitcnt vmcnt(9)
	ds_write_b128 v100, v[138:141] offset:41472
	s_waitcnt vmcnt(8)
	ds_write_b128 v100, v[142:145] offset:59904
	ds_read_b128 v[138:141], v104 offset:64
	ds_read_b128 v[142:145], v104 offset:4672
	ds_read_b128 v[154:157], v101 offset:18496
	ds_read_b128 v[158:161], v101 offset:23104
	s_waitcnt lgkmcnt(7)
	v_mfma_f32_32x32x16_bf16 v[16:31], v[66:69], v[162:165], v[16:31]
	s_waitcnt lgkmcnt(6)
	v_mfma_f32_32x32x16_bf16 v[48:63], v[66:69], v[166:169], v[48:63]
	v_mfma_f32_32x32x16_bf16 v[0:15], v[110:113], v[162:165], v[0:15]
	v_mfma_f32_32x32x16_bf16 v[32:47], v[110:113], v[166:169], v[32:47]
	global_load_dwordx4 v[66:69], v[80:81], off offset:1024
	global_load_dwordx4 v[110:113], v[84:85], off offset:1024
	s_waitcnt vmcnt(9)
	ds_write_b128 v100, v[114:117] offset:46080
	s_waitcnt vmcnt(8)
	ds_write_b128 v100, v[118:121] offset:64512
	ds_read_b128 v[114:117], v104 offset:96
	ds_read_b128 v[118:121], v104 offset:4704
	ds_read_b128 v[162:165], v101 offset:18528
	ds_read_b128 v[166:169], v101 offset:23136
	s_waitcnt lgkmcnt(7)
	v_mfma_f32_32x32x16_bf16 v[16:31], v[138:141], v[154:157], v[16:31]
	s_waitcnt lgkmcnt(6)
	v_mfma_f32_32x32x16_bf16 v[48:63], v[138:141], v[158:161], v[48:63]
	v_mfma_f32_32x32x16_bf16 v[0:15], v[142:145], v[154:157], v[0:15]
	v_mfma_f32_32x32x16_bf16 v[32:47], v[142:145], v[158:161], v[32:47]
	global_load_dwordx4 v[138:141], v[88:89], off offset:1024
	global_load_dwordx4 v[142:145], v[92:93], off offset:1024
	s_waitcnt vmcnt(9)
	ds_write_b128 v100, v[122:125] offset:50688
	s_waitcnt vmcnt(8)
	ds_write_b128 v105, v[126:129] offset:13824
	s_waitcnt lgkmcnt(3)
	v_mfma_f32_32x32x16_bf16 v[16:31], v[114:117], v[162:165], v[16:31]
	s_waitcnt lgkmcnt(2)
	v_mfma_f32_32x32x16_bf16 v[48:63], v[114:117], v[166:169], v[48:63]
	v_mfma_f32_32x32x16_bf16 v[0:15], v[118:121], v[162:165], v[0:15]
	v_mfma_f32_32x32x16_bf16 v[32:47], v[118:121], v[166:169], v[32:47]
	s_waitcnt lgkmcnt(0)
	s_barrier
; __device__ __forceinline__ void gemm_run(int tid, f32x16 (&acc)[2][2], GRegs& g, const GOp& o, int K, unsigned char* smem) {
;     ...
;   for (int k = 0; k < nk; k++) {
;     bf16r* cur = sbuf + (k & 1) * (256 * LDK);
;     bf16r* nxt = sbuf + ((k & 1) ^ 1) * (256 * LDK);
;     const bf16r* As = cur + (wm * 64 + fr) * LDK + fh * 8;
;     const bf16r* Bs = cur + 128 * LDK + (wn * 64 + fr) * LDK + fh * 8;
;     const bool wr = (k + 1 < nk), ld = (k + 2 < nk);
;     bf16x8 fa[2][2], fb[2][2];
;     fa[0][0] = *(const bf16x8*)(As);
;     fa[0][1] = *(const bf16x8*)(As + 32 * LDK);
;     fb[0][0] = *(const bf16x8*)(Bs);
;     fb[0][1] = *(const bf16x8*)(Bs + 32 * LDK);
; #pragma unroll
;     for (int i = 0; i < 4; i++) {
;       if (wr) {
;         *(u32x4*)(nxt + (r0 + i * 32) * LDK + sg * 8) = g.a[i];
;         *(u32x4*)(nxt + 128 * LDK + (r0 + i * 32) * LDK + sg * 8) = g.b[i];
;       }
;       if (ld) {
;         g.a[i] = *(const u32x4*)(Ap + (size_t)i * 32 * o.lda + (k + 2) * 64);
;         g.b[i] = *(const u32x4*)(Bp + o.bs.o[i] + (k + 2) * 64);
;       }
;       if (i < 3) {
;         fa[(i + 1) & 1][0] = *(const bf16x8*)(As + (i + 1) * 16);
;         fa[(i + 1) & 1][1] = *(const bf16x8*)(As + 32 * LDK + (i + 1) * 16);
;         fb[(i + 1) & 1][0] = *(const bf16x8*)(Bs + (i + 1) * 16);
;         fb[(i + 1) & 1][1] = *(const bf16x8*)(Bs + 32 * LDK + (i + 1) * 16);
;       }
;       __builtin_amdgcn_sched_barrier(0);
;       __builtin_amdgcn_s_setprio(1);
;       acc[0][0] = __builtin_amdgcn_mfma_f32_32x32x16_bf16(fa[i & 1][0], fb[i & 1][0], acc[0][0], 0, 0, 0);
;       acc[0][1] = __builtin_amdgcn_mfma_f32_32x32x16_bf16(fa[i & 1][0], fb[i & 1][1], acc[0][1], 0, 0, 0);
;       acc[1][0] = __builtin_amdgcn_mfma_f32_32x32x16_bf16(fa[i & 1][1], fb[i & 1][0], acc[1][0], 0, 0, 0);
;       acc[1][1] = __builtin_amdgcn_mfma_f32_32x32x16_bf16(fa[i & 1][1], fb[i & 1][1], acc[1][1], 0, 0, 0);
;       __builtin_amdgcn_s_setprio(0);
;     }
	global_load_dwordx4 v[114:117], v[64:65], off offset:1152
	global_load_dwordx4 v[118:121], v[106:107], off offset:1152
	ds_read_b128 v[122:125], v104 offset:36864
	ds_read_b128 v[126:129], v104 offset:41472
	ds_read_b128 v[154:157], v101 offset:55296
	ds_read_b128 v[158:161], v101 offset:59904
	s_waitcnt vmcnt(9)
	ds_write_b128 v100, v[130:133]
	s_waitcnt vmcnt(8)
	ds_write_b128 v100, v[134:137] offset:18432
	ds_read_b128 v[130:133], v104 offset:36896
	ds_read_b128 v[134:137], v104 offset:41504
	ds_read_b128 v[162:165], v101 offset:55328
	ds_read_b128 v[166:169], v101 offset:59936
	s_waitcnt lgkmcnt(7)
	v_mfma_f32_32x32x16_bf16 v[16:31], v[122:125], v[154:157], v[16:31]
	s_waitcnt lgkmcnt(6)
	v_mfma_f32_32x32x16_bf16 v[48:63], v[122:125], v[158:161], v[48:63]
	v_mfma_f32_32x32x16_bf16 v[0:15], v[126:129], v[154:157], v[0:15]
	v_mfma_f32_32x32x16_bf16 v[32:47], v[126:129], v[158:161], v[32:47]
	global_load_dwordx4 v[122:125], v[72:73], off offset:1152
	global_load_dwordx4 v[126:129], v[76:77], off offset:1152
	s_waitcnt vmcnt(9)
	ds_write_b128 v100, v[146:149] offset:4608
	s_waitcnt vmcnt(8)
	ds_write_b128 v100, v[150:153] offset:23040
	ds_read_b128 v[146:149], v104 offset:36928
	ds_read_b128 v[150:153], v104 offset:41536
	ds_read_b128 v[154:157], v101 offset:55360
	ds_read_b128 v[158:161], v101 offset:59968
	s_waitcnt lgkmcnt(7)
	v_mfma_f32_32x32x16_bf16 v[16:31], v[130:133], v[162:165], v[16:31]
	s_waitcnt lgkmcnt(6)
	v_mfma_f32_32x32x16_bf16 v[48:63], v[130:133], v[166:169], v[48:63]
	v_mfma_f32_32x32x16_bf16 v[0:15], v[134:137], v[162:165], v[0:15]
	v_mfma_f32_32x32x16_bf16 v[32:47], v[134:137], v[166:169], v[32:47]
	global_load_dwordx4 v[130:133], v[80:81], off offset:1152
	global_load_dwordx4 v[134:137], v[84:85], off offset:1152
	s_waitcnt vmcnt(9)
	ds_write_b128 v100, v[66:69] offset:9216
	s_waitcnt vmcnt(8)
	ds_write_b128 v100, v[110:113] offset:27648
	ds_read_b128 v[66:69], v104 offset:36960
	ds_read_b128 v[110:113], v104 offset:41568
	ds_read_b128 v[162:165], v101 offset:55392
	ds_read_b128 v[166:169], v101 offset:60000
	s_waitcnt lgkmcnt(7)
	v_mfma_f32_32x32x16_bf16 v[16:31], v[146:149], v[154:157], v[16:31]
	s_waitcnt lgkmcnt(6)
	v_mfma_f32_32x32x16_bf16 v[48:63], v[146:149], v[158:161], v[48:63]
	v_mfma_f32_32x32x16_bf16 v[0:15], v[150:153], v[154:157], v[0:15]
	v_mfma_f32_32x32x16_bf16 v[32:47], v[150:153], v[158:161], v[32:47]
	global_load_dwordx4 v[146:149], v[88:89], off offset:1152
	global_load_dwordx4 v[150:153], v[92:93], off offset:1152
	s_waitcnt vmcnt(9)
	ds_write_b128 v100, v[138:141] offset:13824
	s_waitcnt vmcnt(8)
	ds_write_b128 v100, v[142:145] offset:32256
	s_waitcnt lgkmcnt(3)
	v_mfma_f32_32x32x16_bf16 v[16:31], v[66:69], v[162:165], v[16:31]
	s_waitcnt lgkmcnt(2)
	v_mfma_f32_32x32x16_bf16 v[48:63], v[66:69], v[166:169], v[48:63]
	v_mfma_f32_32x32x16_bf16 v[0:15], v[110:113], v[162:165], v[0:15]
	v_mfma_f32_32x32x16_bf16 v[32:47], v[110:113], v[166:169], v[32:47]
	s_waitcnt lgkmcnt(0)
	s_barrier
	global_load_dwordx4 v[66:69], v[64:65], off offset:1280
	global_load_dwordx4 v[110:113], v[106:107], off offset:1280
	ds_read_b128 v[138:141], v104
	ds_read_b128 v[142:145], v104 offset:4608
	ds_read_b128 v[154:157], v101 offset:18432
	ds_read_b128 v[158:161], v101 offset:23040
	s_waitcnt vmcnt(9)
	ds_write_b128 v100, v[114:117] offset:36864
	s_waitcnt vmcnt(8)
	ds_write_b128 v100, v[118:121] offset:55296
	ds_read_b128 v[114:117], v104 offset:32
	ds_read_b128 v[118:121], v104 offset:4640
	ds_read_b128 v[162:165], v101 offset:18464
	ds_read_b128 v[166:169], v101 offset:23072
	s_waitcnt lgkmcnt(7)
	v_mfma_f32_32x32x16_bf16 v[16:31], v[138:141], v[154:157], v[16:31]
	s_waitcnt lgkmcnt(6)
	v_mfma_f32_32x32x16_bf16 v[48:63], v[138:141], v[158:161], v[48:63]
	v_mfma_f32_32x32x16_bf16 v[0:15], v[142:145], v[154:157], v[0:15]
	v_mfma_f32_32x32x16_bf16 v[32:47], v[142:145], v[158:161], v[32:47]
	global_load_dwordx4 v[138:141], v[72:73], off offset:1280
	global_load_dwordx4 v[142:145], v[76:77], off offset:1280
	s_waitcnt vmcnt(9)
	ds_write_b128 v100, v[122:125] offset:41472
	s_waitcnt vmcnt(8)
	ds_write_b128 v100, v[126:129] offset:59904
	ds_read_b128 v[122:125], v104 offset:64
	ds_read_b128 v[126:129], v104 offset:4672
	ds_read_b128 v[154:157], v101 offset:18496
	ds_read_b128 v[158:161], v101 offset:23104
	s_waitcnt lgkmcnt(7)
	v_mfma_f32_32x32x16_bf16 v[16:31], v[114:117], v[162:165], v[16:31]
	s_waitcnt lgkmcnt(6)
	v_mfma_f32_32x32x16_bf16 v[48:63], v[114:117], v[166:169], v[48:63]
	v_mfma_f32_32x32x16_bf16 v[0:15], v[118:121], v[162:165], v[0:15]
	v_mfma_f32_32x32x16_bf16 v[32:47], v[118:121], v[166:169], v[32:47]
	global_load_dwordx4 v[114:117], v[80:81], off offset:1280
	global_load_dwordx4 v[118:121], v[84:85], off offset:1280
	s_waitcnt vmcnt(9)
	ds_write_b128 v100, v[130:133] offset:46080
	s_waitcnt vmcnt(8)
	ds_write_b128 v100, v[134:137] offset:64512
	ds_read_b128 v[130:133], v104 offset:96
	ds_read_b128 v[134:137], v104 offset:4704
	ds_read_b128 v[162:165], v101 offset:18528
	ds_read_b128 v[166:169], v101 offset:23136
	s_waitcnt lgkmcnt(7)
	v_mfma_f32_32x32x16_bf16 v[16:31], v[122:125], v[154:157], v[16:31]
	s_waitcnt lgkmcnt(6)
	v_mfma_f32_32x32x16_bf16 v[48:63], v[122:125], v[158:161], v[48:63]
	v_mfma_f32_32x32x16_bf16 v[0:15], v[126:129], v[154:157], v[0:15]
	v_mfma_f32_32x32x16_bf16 v[32:47], v[126:129], v[158:161], v[32:47]
	global_load_dwordx4 v[122:125], v[88:89], off offset:1280
	global_load_dwordx4 v[126:129], v[92:93], off offset:1280
	s_waitcnt vmcnt(9)
	ds_write_b128 v100, v[146:149] offset:50688
	s_waitcnt vmcnt(8)
	ds_write_b128 v105, v[150:153] offset:13824
	s_waitcnt lgkmcnt(3)
	v_mfma_f32_32x32x16_bf16 v[16:31], v[130:133], v[162:165], v[16:31]
	s_waitcnt lgkmcnt(2)
	v_mfma_f32_32x32x16_bf16 v[48:63], v[130:133], v[166:169], v[48:63]
	v_mfma_f32_32x32x16_bf16 v[0:15], v[134:137], v[162:165], v[0:15]
	v_mfma_f32_32x32x16_bf16 v[32:47], v[134:137], v[166:169], v[32:47]
	s_waitcnt lgkmcnt(0)
	s_barrier
; __device__ __forceinline__ void gemm_run(int tid, f32x16 (&acc)[2][2], GRegs& g, const GOp& o, int K, unsigned char* smem) {
;     ...
;   for (int k = 0; k < nk; k++) {
;     bf16r* cur = sbuf + (k & 1) * (256 * LDK);
;     bf16r* nxt = sbuf + ((k & 1) ^ 1) * (256 * LDK);
;     const bf16r* As = cur + (wm * 64 + fr) * LDK + fh * 8;
;     const bf16r* Bs = cur + 128 * LDK + (wn * 64 + fr) * LDK + fh * 8;
;     const bool wr = (k + 1 < nk), ld = (k + 2 < nk);
;     bf16x8 fa[2][2], fb[2][2];
;     fa[0][0] = *(const bf16x8*)(As);
;     fa[0][1] = *(const bf16x8*)(As + 32 * LDK);
;     fb[0][0] = *(const bf16x8*)(Bs);
;     fb[0][1] = *(const bf16x8*)(Bs + 32 * LDK);
; #pragma unroll
;     for (int i = 0; i < 4; i++) {
;       if (wr) {
;         *(u32x4*)(nxt + (r0 + i * 32) * LDK + sg * 8) = g.a[i];
;         *(u32x4*)(nxt + 128 * LDK + (r0 + i * 32) * LDK + sg * 8) = g.b[i];
;       }
;       if (ld) {
;         g.a[i] = *(const u32x4*)(Ap + (size_t)i * 32 * o.lda + (k + 2) * 64);
;         g.b[i] = *(const u32x4*)(Bp + o.bs.o[i] + (k + 2) * 64);
;       }
;       if (i < 3) {
;         fa[(i + 1) & 1][0] = *(const bf16x8*)(As + (i + 1) * 16);
;         fa[(i + 1) & 1][1] = *(const bf16x8*)(As + 32 * LDK + (i + 1) * 16);
;         fb[(i + 1) & 1][0] = *(const bf16x8*)(Bs + (i + 1) * 16);
;         fb[(i + 1) & 1][1] = *(const bf16x8*)(Bs + 32 * LDK + (i + 1) * 16);
;       }
;       __builtin_amdgcn_sched_barrier(0);
;       __builtin_amdgcn_s_setprio(1);
;       acc[0][0] = __builtin_amdgcn_mfma_f32_32x32x16_bf16(fa[i & 1][0], fb[i & 1][0], acc[0][0], 0, 0, 0);
;       acc[0][1] = __builtin_amdgcn_mfma_f32_32x32x16_bf16(fa[i & 1][0], fb[i & 1][1], acc[0][1], 0, 0, 0);
;       acc[1][0] = __builtin_amdgcn_mfma_f32_32x32x16_bf16(fa[i & 1][1], fb[i & 1][0], acc[1][0], 0, 0, 0);
;       acc[1][1] = __builtin_amdgcn_mfma_f32_32x32x16_bf16(fa[i & 1][1], fb[i & 1][1], acc[1][1], 0, 0, 0);
;       __builtin_amdgcn_s_setprio(0);
;     }
	global_load_dwordx4 v[130:133], v[64:65], off offset:1408
	global_load_dwordx4 v[134:137], v[106:107], off offset:1408
	ds_read_b128 v[146:149], v104 offset:36864
	ds_read_b128 v[150:153], v104 offset:41472
	ds_read_b128 v[154:157], v101 offset:55296
	ds_read_b128 v[158:161], v101 offset:59904
	s_waitcnt vmcnt(9)
	ds_write_b128 v100, v[66:69]
	s_waitcnt vmcnt(8)
	ds_write_b128 v100, v[110:113] offset:18432
	ds_read_b128 v[66:69], v104 offset:36896
	ds_read_b128 v[110:113], v104 offset:41504
	ds_read_b128 v[162:165], v101 offset:55328
	ds_read_b128 v[166:169], v101 offset:59936
	s_waitcnt lgkmcnt(7)
	v_mfma_f32_32x32x16_bf16 v[16:31], v[146:149], v[154:157], v[16:31]
	s_waitcnt lgkmcnt(6)
	v_mfma_f32_32x32x16_bf16 v[48:63], v[146:149], v[158:161], v[48:63]
	v_mfma_f32_32x32x16_bf16 v[0:15], v[150:153], v[154:157], v[0:15]
	v_mfma_f32_32x32x16_bf16 v[32:47], v[150:153], v[158:161], v[32:47]
	global_load_dwordx4 v[146:149], v[72:73], off offset:1408
	global_load_dwordx4 v[150:153], v[76:77], off offset:1408
	s_waitcnt vmcnt(9)
	ds_write_b128 v100, v[138:141] offset:4608
	s_waitcnt vmcnt(8)
	ds_write_b128 v100, v[142:145] offset:23040
	ds_read_b128 v[138:141], v104 offset:36928
	ds_read_b128 v[142:145], v104 offset:41536
	ds_read_b128 v[154:157], v101 offset:55360
	ds_read_b128 v[158:161], v101 offset:59968
	s_waitcnt lgkmcnt(7)
	v_mfma_f32_32x32x16_bf16 v[16:31], v[66:69], v[162:165], v[16:31]
	s_waitcnt lgkmcnt(6)
	v_mfma_f32_32x32x16_bf16 v[48:63], v[66:69], v[166:169], v[48:63]
	v_mfma_f32_32x32x16_bf16 v[0:15], v[110:113], v[162:165], v[0:15]
	v_mfma_f32_32x32x16_bf16 v[32:47], v[110:113], v[166:169], v[32:47]
	global_load_dwordx4 v[66:69], v[80:81], off offset:1408
	global_load_dwordx4 v[110:113], v[84:85], off offset:1408
	s_waitcnt vmcnt(9)
	ds_write_b128 v100, v[114:117] offset:9216
	s_waitcnt vmcnt(8)
	ds_write_b128 v100, v[118:121] offset:27648
	ds_read_b128 v[114:117], v104 offset:36960
	ds_read_b128 v[118:121], v104 offset:41568
	ds_read_b128 v[162:165], v101 offset:55392
	ds_read_b128 v[166:169], v101 offset:60000
	s_waitcnt lgkmcnt(7)
	v_mfma_f32_32x32x16_bf16 v[16:31], v[138:141], v[154:157], v[16:31]
	s_waitcnt lgkmcnt(6)
	v_mfma_f32_32x32x16_bf16 v[48:63], v[138:141], v[158:161], v[48:63]
	v_mfma_f32_32x32x16_bf16 v[0:15], v[142:145], v[154:157], v[0:15]
	v_mfma_f32_32x32x16_bf16 v[32:47], v[142:145], v[158:161], v[32:47]
	global_load_dwordx4 v[138:141], v[88:89], off offset:1408
	global_load_dwordx4 v[142:145], v[92:93], off offset:1408
	s_waitcnt vmcnt(9)
	ds_write_b128 v100, v[122:125] offset:13824
	s_waitcnt vmcnt(8)
	ds_write_b128 v100, v[126:129] offset:32256
	s_waitcnt lgkmcnt(3)
	v_mfma_f32_32x32x16_bf16 v[16:31], v[114:117], v[162:165], v[16:31]
	s_waitcnt lgkmcnt(2)
	v_mfma_f32_32x32x16_bf16 v[48:63], v[114:117], v[166:169], v[48:63]
	v_mfma_f32_32x32x16_bf16 v[0:15], v[118:121], v[162:165], v[0:15]
	v_mfma_f32_32x32x16_bf16 v[32:47], v[118:121], v[166:169], v[32:47]
	s_waitcnt lgkmcnt(0)
	s_barrier
	global_load_dwordx4 v[114:117], v[64:65], off offset:1536
	global_load_dwordx4 v[118:121], v[106:107], off offset:1536
	ds_read_b128 v[122:125], v104
	ds_read_b128 v[126:129], v104 offset:4608
	ds_read_b128 v[154:157], v101 offset:18432
	ds_read_b128 v[158:161], v101 offset:23040
	s_waitcnt vmcnt(9)
	ds_write_b128 v100, v[130:133] offset:36864
	s_waitcnt vmcnt(8)
	ds_write_b128 v100, v[134:137] offset:55296
	ds_read_b128 v[130:133], v104 offset:32
	ds_read_b128 v[134:137], v104 offset:4640
	ds_read_b128 v[162:165], v101 offset:18464
	ds_read_b128 v[166:169], v101 offset:23072
	s_waitcnt lgkmcnt(7)
	v_mfma_f32_32x32x16_bf16 v[16:31], v[122:125], v[154:157], v[16:31]
	s_waitcnt lgkmcnt(6)
	v_mfma_f32_32x32x16_bf16 v[48:63], v[122:125], v[158:161], v[48:63]
	v_mfma_f32_32x32x16_bf16 v[0:15], v[126:129], v[154:157], v[0:15]
	v_mfma_f32_32x32x16_bf16 v[32:47], v[126:129], v[158:161], v[32:47]
	global_load_dwordx4 v[122:125], v[72:73], off offset:1536
	global_load_dwordx4 v[126:129], v[76:77], off offset:1536
	s_waitcnt vmcnt(9)
	ds_write_b128 v100, v[146:149] offset:41472
	s_waitcnt vmcnt(8)
	ds_write_b128 v100, v[150:153] offset:59904
	ds_read_b128 v[146:149], v104 offset:64
	ds_read_b128 v[150:153], v104 offset:4672
	ds_read_b128 v[154:157], v101 offset:18496
	ds_read_b128 v[158:161], v101 offset:23104
	s_waitcnt lgkmcnt(7)
	v_mfma_f32_32x32x16_bf16 v[16:31], v[130:133], v[162:165], v[16:31]
	s_waitcnt lgkmcnt(6)
	v_mfma_f32_32x32x16_bf16 v[48:63], v[130:133], v[166:169], v[48:63]
	v_mfma_f32_32x32x16_bf16 v[0:15], v[134:137], v[162:165], v[0:15]
	v_mfma_f32_32x32x16_bf16 v[32:47], v[134:137], v[166:169], v[32:47]
	global_load_dwordx4 v[130:133], v[80:81], off offset:1536
	global_load_dwordx4 v[134:137], v[84:85], off offset:1536
	s_waitcnt vmcnt(9)
	ds_write_b128 v100, v[66:69] offset:46080
	s_waitcnt vmcnt(8)
	ds_write_b128 v100, v[110:113] offset:64512
	ds_read_b128 v[66:69], v104 offset:96
	ds_read_b128 v[110:113], v104 offset:4704
	ds_read_b128 v[162:165], v101 offset:18528
	ds_read_b128 v[166:169], v101 offset:23136
	s_waitcnt lgkmcnt(7)
	v_mfma_f32_32x32x16_bf16 v[16:31], v[146:149], v[154:157], v[16:31]
	s_waitcnt lgkmcnt(6)
	v_mfma_f32_32x32x16_bf16 v[48:63], v[146:149], v[158:161], v[48:63]
	v_mfma_f32_32x32x16_bf16 v[0:15], v[150:153], v[154:157], v[0:15]
	v_mfma_f32_32x32x16_bf16 v[32:47], v[150:153], v[158:161], v[32:47]
	global_load_dwordx4 v[146:149], v[88:89], off offset:1536
	global_load_dwordx4 v[150:153], v[92:93], off offset:1536
	s_waitcnt vmcnt(9)
	ds_write_b128 v100, v[138:141] offset:50688
	s_waitcnt vmcnt(8)
	ds_write_b128 v105, v[142:145] offset:13824
	s_waitcnt lgkmcnt(3)
	v_mfma_f32_32x32x16_bf16 v[16:31], v[66:69], v[162:165], v[16:31]
	s_waitcnt lgkmcnt(2)
	v_mfma_f32_32x32x16_bf16 v[48:63], v[66:69], v[166:169], v[48:63]
	v_mfma_f32_32x32x16_bf16 v[0:15], v[110:113], v[162:165], v[0:15]
	v_mfma_f32_32x32x16_bf16 v[32:47], v[110:113], v[166:169], v[32:47]
	s_waitcnt lgkmcnt(0)
	s_barrier
; __device__ __forceinline__ void gemm_run(int tid, f32x16 (&acc)[2][2], GRegs& g, const GOp& o, int K, unsigned char* smem) {
;     ...
;   for (int k = 0; k < nk; k++) {
;     bf16r* cur = sbuf + (k & 1) * (256 * LDK);
;     bf16r* nxt = sbuf + ((k & 1) ^ 1) * (256 * LDK);
;     const bf16r* As = cur + (wm * 64 + fr) * LDK + fh * 8;
;     const bf16r* Bs = cur + 128 * LDK + (wn * 64 + fr) * LDK + fh * 8;
;     const bool wr = (k + 1 < nk), ld = (k + 2 < nk);
;     bf16x8 fa[2][2], fb[2][2];
;     fa[0][0] = *(const bf16x8*)(As);
;     fa[0][1] = *(const bf16x8*)(As + 32 * LDK);
;     fb[0][0] = *(const bf16x8*)(Bs);
;     fb[0][1] = *(const bf16x8*)(Bs + 32 * LDK);
; #pragma unroll
;     for (int i = 0; i < 4; i++) {
;       if (wr) {
;         *(u32x4*)(nxt + (r0 + i * 32) * LDK + sg * 8) = g.a[i];
;         *(u32x4*)(nxt + 128 * LDK + (r0 + i * 32) * LDK + sg * 8) = g.b[i];
;       }
;       if (ld) {
;         g.a[i] = *(const u32x4*)(Ap + (size_t)i * 32 * o.lda + (k + 2) * 64);
;         g.b[i] = *(const u32x4*)(Bp + o.bs.o[i] + (k + 2) * 64);
;       }
;       if (i < 3) {
;         fa[(i + 1) & 1][0] = *(const bf16x8*)(As + (i + 1) * 16);
;         fa[(i + 1) & 1][1] = *(const bf16x8*)(As + 32 * LDK + (i + 1) * 16);
;         fb[(i + 1) & 1][0] = *(const bf16x8*)(Bs + (i + 1) * 16);
;         fb[(i + 1) & 1][1] = *(const bf16x8*)(Bs + 32 * LDK + (i + 1) * 16);
;       }
;       __builtin_amdgcn_sched_barrier(0);
;       __builtin_amdgcn_s_setprio(1);
;       acc[0][0] = __builtin_amdgcn_mfma_f32_32x32x16_bf16(fa[i & 1][0], fb[i & 1][0], acc[0][0], 0, 0, 0);
;       acc[0][1] = __builtin_amdgcn_mfma_f32_32x32x16_bf16(fa[i & 1][0], fb[i & 1][1], acc[0][1], 0, 0, 0);
;       acc[1][0] = __builtin_amdgcn_mfma_f32_32x32x16_bf16(fa[i & 1][1], fb[i & 1][0], acc[1][0], 0, 0, 0);
;       acc[1][1] = __builtin_amdgcn_mfma_f32_32x32x16_bf16(fa[i & 1][1], fb[i & 1][1], acc[1][1], 0, 0, 0);
;       __builtin_amdgcn_s_setprio(0);
;     }
	global_load_dwordx4 v[66:69], v[64:65], off offset:1664
	global_load_dwordx4 v[110:113], v[106:107], off offset:1664
	ds_read_b128 v[138:141], v104 offset:36864
	ds_read_b128 v[142:145], v104 offset:41472
	ds_read_b128 v[154:157], v101 offset:55296
	ds_read_b128 v[158:161], v101 offset:59904
	s_waitcnt vmcnt(9)
	ds_write_b128 v100, v[114:117]
	s_waitcnt vmcnt(8)
	ds_write_b128 v100, v[118:121] offset:18432
	ds_read_b128 v[114:117], v104 offset:36896
	ds_read_b128 v[118:121], v104 offset:41504
	ds_read_b128 v[162:165], v101 offset:55328
	ds_read_b128 v[166:169], v101 offset:59936
	s_waitcnt lgkmcnt(7)
	v_mfma_f32_32x32x16_bf16 v[16:31], v[138:141], v[154:157], v[16:31]
	s_waitcnt lgkmcnt(6)
	v_mfma_f32_32x32x16_bf16 v[48:63], v[138:141], v[158:161], v[48:63]
	v_mfma_f32_32x32x16_bf16 v[0:15], v[142:145], v[154:157], v[0:15]
	v_mfma_f32_32x32x16_bf16 v[32:47], v[142:145], v[158:161], v[32:47]
	global_load_dwordx4 v[138:141], v[72:73], off offset:1664
	global_load_dwordx4 v[142:145], v[76:77], off offset:1664
	s_waitcnt vmcnt(9)
	ds_write_b128 v100, v[122:125] offset:4608
	s_waitcnt vmcnt(8)
	ds_write_b128 v100, v[126:129] offset:23040
	ds_read_b128 v[122:125], v104 offset:36928
	ds_read_b128 v[126:129], v104 offset:41536
	ds_read_b128 v[154:157], v101 offset:55360
	ds_read_b128 v[158:161], v101 offset:59968
	s_waitcnt lgkmcnt(7)
	v_mfma_f32_32x32x16_bf16 v[16:31], v[114:117], v[162:165], v[16:31]
	s_waitcnt lgkmcnt(6)
	v_mfma_f32_32x32x16_bf16 v[48:63], v[114:117], v[166:169], v[48:63]
	v_mfma_f32_32x32x16_bf16 v[0:15], v[118:121], v[162:165], v[0:15]
	v_mfma_f32_32x32x16_bf16 v[32:47], v[118:121], v[166:169], v[32:47]
	global_load_dwordx4 v[114:117], v[80:81], off offset:1664
	global_load_dwordx4 v[118:121], v[84:85], off offset:1664
	s_waitcnt vmcnt(9)
	ds_write_b128 v100, v[130:133] offset:9216
	s_waitcnt vmcnt(8)
	ds_write_b128 v100, v[134:137] offset:27648
	ds_read_b128 v[130:133], v104 offset:36960
	ds_read_b128 v[134:137], v104 offset:41568
	ds_read_b128 v[162:165], v101 offset:55392
	ds_read_b128 v[166:169], v101 offset:60000
	s_waitcnt lgkmcnt(7)
	v_mfma_f32_32x32x16_bf16 v[16:31], v[122:125], v[154:157], v[16:31]
	s_waitcnt lgkmcnt(6)
	v_mfma_f32_32x32x16_bf16 v[48:63], v[122:125], v[158:161], v[48:63]
	v_mfma_f32_32x32x16_bf16 v[0:15], v[126:129], v[154:157], v[0:15]
	v_mfma_f32_32x32x16_bf16 v[32:47], v[126:129], v[158:161], v[32:47]
	global_load_dwordx4 v[122:125], v[88:89], off offset:1664
	global_load_dwordx4 v[126:129], v[92:93], off offset:1664
	s_waitcnt vmcnt(9)
	ds_write_b128 v100, v[146:149] offset:13824
	s_waitcnt vmcnt(8)
	ds_write_b128 v100, v[150:153] offset:32256
	s_waitcnt lgkmcnt(3)
	v_mfma_f32_32x32x16_bf16 v[16:31], v[130:133], v[162:165], v[16:31]
	s_waitcnt lgkmcnt(2)
	v_mfma_f32_32x32x16_bf16 v[48:63], v[130:133], v[166:169], v[48:63]
	v_mfma_f32_32x32x16_bf16 v[0:15], v[134:137], v[162:165], v[0:15]
	v_mfma_f32_32x32x16_bf16 v[32:47], v[134:137], v[166:169], v[32:47]
	s_waitcnt lgkmcnt(0)
	s_barrier
	global_load_dwordx4 v[130:133], v[64:65], off offset:1792
	global_load_dwordx4 v[134:137], v[106:107], off offset:1792
	ds_read_b128 v[146:149], v104
	ds_read_b128 v[150:153], v104 offset:4608
	ds_read_b128 v[154:157], v101 offset:18432
	ds_read_b128 v[158:161], v101 offset:23040
	s_waitcnt vmcnt(9)
	ds_write_b128 v100, v[66:69] offset:36864
	s_waitcnt vmcnt(8)
	ds_write_b128 v100, v[110:113] offset:55296
	ds_read_b128 v[66:69], v104 offset:32
	ds_read_b128 v[110:113], v104 offset:4640
	ds_read_b128 v[162:165], v101 offset:18464
	ds_read_b128 v[166:169], v101 offset:23072
	s_waitcnt lgkmcnt(7)
	v_mfma_f32_32x32x16_bf16 v[16:31], v[146:149], v[154:157], v[16:31]
	s_waitcnt lgkmcnt(6)
	v_mfma_f32_32x32x16_bf16 v[48:63], v[146:149], v[158:161], v[48:63]
	v_mfma_f32_32x32x16_bf16 v[0:15], v[150:153], v[154:157], v[0:15]
	v_mfma_f32_32x32x16_bf16 v[32:47], v[150:153], v[158:161], v[32:47]
	global_load_dwordx4 v[146:149], v[72:73], off offset:1792
	global_load_dwordx4 v[150:153], v[76:77], off offset:1792
	s_waitcnt vmcnt(9)
	ds_write_b128 v100, v[138:141] offset:41472
	s_waitcnt vmcnt(8)
	ds_write_b128 v100, v[142:145] offset:59904
	ds_read_b128 v[138:141], v104 offset:64
	ds_read_b128 v[142:145], v104 offset:4672
	ds_read_b128 v[154:157], v101 offset:18496
	ds_read_b128 v[158:161], v101 offset:23104
	s_waitcnt lgkmcnt(7)
	v_mfma_f32_32x32x16_bf16 v[16:31], v[66:69], v[162:165], v[16:31]
	s_waitcnt lgkmcnt(6)
	v_mfma_f32_32x32x16_bf16 v[48:63], v[66:69], v[166:169], v[48:63]
	v_mfma_f32_32x32x16_bf16 v[0:15], v[110:113], v[162:165], v[0:15]
	v_mfma_f32_32x32x16_bf16 v[32:47], v[110:113], v[166:169], v[32:47]
	global_load_dwordx4 v[110:113], v[80:81], off offset:1792
	global_load_dwordx4 v[162:165], v[84:85], off offset:1792
	s_waitcnt vmcnt(9)
	ds_write_b128 v100, v[114:117] offset:46080
	s_waitcnt vmcnt(8)
	ds_write_b128 v100, v[118:121] offset:64512
	ds_read_b128 v[66:69], v104 offset:96
	ds_read_b128 v[114:117], v104 offset:4704
	ds_read_b128 v[118:121], v101 offset:18528
	ds_read_b128 v[166:169], v101 offset:23136
	s_waitcnt lgkmcnt(7)
	v_mfma_f32_32x32x16_bf16 v[16:31], v[138:141], v[154:157], v[16:31]
	s_waitcnt lgkmcnt(6)
	v_mfma_f32_32x32x16_bf16 v[48:63], v[138:141], v[158:161], v[48:63]
	v_mfma_f32_32x32x16_bf16 v[0:15], v[142:145], v[154:157], v[0:15]
	v_mfma_f32_32x32x16_bf16 v[32:47], v[142:145], v[158:161], v[32:47]
	global_load_dwordx4 v[138:141], v[88:89], off offset:1792
	global_load_dwordx4 v[142:145], v[92:93], off offset:1792
	s_waitcnt vmcnt(9)
	ds_write_b128 v100, v[122:125] offset:50688
	s_waitcnt vmcnt(8)
	ds_write_b128 v105, v[126:129] offset:13824
	s_waitcnt lgkmcnt(3)
	v_mfma_f32_32x32x16_bf16 v[16:31], v[66:69], v[118:121], v[16:31]
	s_waitcnt lgkmcnt(2)
	v_mfma_f32_32x32x16_bf16 v[48:63], v[66:69], v[166:169], v[48:63]
	v_mfma_f32_32x32x16_bf16 v[0:15], v[114:117], v[118:121], v[0:15]
	v_mfma_f32_32x32x16_bf16 v[32:47], v[114:117], v[166:169], v[32:47]
	s_waitcnt lgkmcnt(0)
	s_barrier
; __device__ __forceinline__ void gemm_run(int tid, f32x16 (&acc)[2][2], GRegs& g, const GOp& o, int K, unsigned char* smem) {
;     ...
;   for (int k = 0; k < nk; k++) {
;     bf16r* cur = sbuf + (k & 1) * (256 * LDK);
;     bf16r* nxt = sbuf + ((k & 1) ^ 1) * (256 * LDK);
;     const bf16r* As = cur + (wm * 64 + fr) * LDK + fh * 8;
;     const bf16r* Bs = cur + 128 * LDK + (wn * 64 + fr) * LDK + fh * 8;
;     const bool wr = (k + 1 < nk), ld = (k + 2 < nk);
;     bf16x8 fa[2][2], fb[2][2];
;     fa[0][0] = *(const bf16x8*)(As);
;     fa[0][1] = *(const bf16x8*)(As + 32 * LDK);
;     fb[0][0] = *(const bf16x8*)(Bs);
;     fb[0][1] = *(const bf16x8*)(Bs + 32 * LDK);
; #pragma unroll
;     for (int i = 0; i < 4; i++) {
;       if (wr) {
;         *(u32x4*)(nxt + (r0 + i * 32) * LDK + sg * 8) = g.a[i];
;         *(u32x4*)(nxt + 128 * LDK + (r0 + i * 32) * LDK + sg * 8) = g.b[i];
;       }
;       if (ld) {
;         g.a[i] = *(const u32x4*)(Ap + (size_t)i * 32 * o.lda + (k + 2) * 64);
;         g.b[i] = *(const u32x4*)(Bp + o.bs.o[i] + (k + 2) * 64);
;       }
;       if (i < 3) {
;         fa[(i + 1) & 1][0] = *(const bf16x8*)(As + (i + 1) * 16);
;         fa[(i + 1) & 1][1] = *(const bf16x8*)(As + 32 * LDK + (i + 1) * 16);
;         fb[(i + 1) & 1][0] = *(const bf16x8*)(Bs + (i + 1) * 16);
;         fb[(i + 1) & 1][1] = *(const bf16x8*)(Bs + 32 * LDK + (i + 1) * 16);
;       }
;       __builtin_amdgcn_sched_barrier(0);
;       __builtin_amdgcn_s_setprio(1);
;       acc[0][0] = __builtin_amdgcn_mfma_f32_32x32x16_bf16(fa[i & 1][0], fb[i & 1][0], acc[0][0], 0, 0, 0);
;       acc[0][1] = __builtin_amdgcn_mfma_f32_32x32x16_bf16(fa[i & 1][0], fb[i & 1][1], acc[0][1], 0, 0, 0);
;       acc[1][0] = __builtin_amdgcn_mfma_f32_32x32x16_bf16(fa[i & 1][1], fb[i & 1][0], acc[1][0], 0, 0, 0);
;       acc[1][1] = __builtin_amdgcn_mfma_f32_32x32x16_bf16(fa[i & 1][1], fb[i & 1][1], acc[1][1], 0, 0, 0);
;       __builtin_amdgcn_s_setprio(0);
;     }
	global_load_dwordx4 v[64:67], v[64:65], off offset:1920
	s_nop 0
	global_load_dwordx4 v[68:71], v[106:107], off offset:1920
	ds_read_b128 v[114:117], v104 offset:36864
	ds_read_b128 v[118:121], v104 offset:41472
	ds_read_b128 v[122:125], v101 offset:55296
	ds_read_b128 v[126:129], v101 offset:59904
	s_waitcnt vmcnt(9)
	ds_write_b128 v100, v[130:133]
	s_waitcnt vmcnt(8)
	ds_write_b128 v100, v[134:137] offset:18432
	ds_read_b128 v[130:133], v104 offset:36896
	ds_read_b128 v[134:137], v104 offset:41504
	ds_read_b128 v[154:157], v101 offset:55328
	ds_read_b128 v[158:161], v101 offset:59936
	s_waitcnt lgkmcnt(7)
	v_mfma_f32_32x32x16_bf16 v[16:31], v[114:117], v[122:125], v[16:31]
	s_waitcnt lgkmcnt(6)
	v_mfma_f32_32x32x16_bf16 v[48:63], v[114:117], v[126:129], v[48:63]
	v_mfma_f32_32x32x16_bf16 v[0:15], v[118:121], v[122:125], v[0:15]
	v_mfma_f32_32x32x16_bf16 v[32:47], v[118:121], v[126:129], v[32:47]
	global_load_dwordx4 v[72:75], v[72:73], off offset:1920
	s_nop 0
	global_load_dwordx4 v[76:79], v[76:77], off offset:1920
	s_waitcnt vmcnt(9)
	ds_write_b128 v100, v[146:149] offset:4608
	s_waitcnt vmcnt(8)
	ds_write_b128 v100, v[150:153] offset:23040
	ds_read_b128 v[114:117], v104 offset:36928
	ds_read_b128 v[118:121], v104 offset:41536
	ds_read_b128 v[122:125], v101 offset:55360
	ds_read_b128 v[126:129], v101 offset:59968
	s_waitcnt lgkmcnt(7)
	v_mfma_f32_32x32x16_bf16 v[16:31], v[130:133], v[154:157], v[16:31]
	s_waitcnt lgkmcnt(6)
	v_mfma_f32_32x32x16_bf16 v[48:63], v[130:133], v[158:161], v[48:63]
	v_mfma_f32_32x32x16_bf16 v[0:15], v[134:137], v[154:157], v[0:15]
	v_mfma_f32_32x32x16_bf16 v[32:47], v[134:137], v[158:161], v[32:47]
	global_load_dwordx4 v[80:83], v[80:81], off offset:1920
	s_nop 0
	global_load_dwordx4 v[84:87], v[84:85], off offset:1920
	s_waitcnt vmcnt(9)
	ds_write_b128 v100, v[110:113] offset:9216
	s_waitcnt vmcnt(8)
	ds_write_b128 v100, v[162:165] offset:27648
	ds_read_b128 v[110:113], v104 offset:36960
	ds_read_b128 v[130:133], v104 offset:41568
	ds_read_b128 v[134:137], v101 offset:55392
	ds_read_b128 v[146:149], v101 offset:60000
	s_waitcnt lgkmcnt(7)
	v_mfma_f32_32x32x16_bf16 v[16:31], v[114:117], v[122:125], v[16:31]
	s_waitcnt lgkmcnt(6)
	v_mfma_f32_32x32x16_bf16 v[48:63], v[114:117], v[126:129], v[48:63]
	v_mfma_f32_32x32x16_bf16 v[0:15], v[118:121], v[122:125], v[0:15]
	v_mfma_f32_32x32x16_bf16 v[32:47], v[118:121], v[126:129], v[32:47]
	global_load_dwordx4 v[88:91], v[88:89], off offset:1920
	s_nop 0
	global_load_dwordx4 v[92:95], v[92:93], off offset:1920
	s_waitcnt vmcnt(9)
	ds_write_b128 v100, v[138:141] offset:13824
	s_waitcnt vmcnt(8)
	ds_write_b128 v100, v[142:145] offset:32256
	s_waitcnt lgkmcnt(3)
	v_mfma_f32_32x32x16_bf16 v[16:31], v[110:113], v[134:137], v[16:31]
	s_waitcnt lgkmcnt(2)
	v_mfma_f32_32x32x16_bf16 v[48:63], v[110:113], v[146:149], v[48:63]
	v_mfma_f32_32x32x16_bf16 v[0:15], v[130:133], v[134:137], v[0:15]
	v_mfma_f32_32x32x16_bf16 v[32:47], v[130:133], v[146:149], v[32:47]
	s_waitcnt lgkmcnt(0)
	s_barrier
; __device__ __forceinline__ void gemm_run(int tid, f32x16 (&acc)[2][2], GRegs& g, const GOp& o, int K, unsigned char* smem) {
;     ...
;   for (int k = 0; k < nk; k++) {
;     bf16r* cur = sbuf + (k & 1) * (256 * LDK);
;     bf16r* nxt = sbuf + ((k & 1) ^ 1) * (256 * LDK);
;     const bf16r* As = cur + (wm * 64 + fr) * LDK + fh * 8;
;     const bf16r* Bs = cur + 128 * LDK + (wn * 64 + fr) * LDK + fh * 8;
;     const bool wr = (k + 1 < nk), ld = (k + 2 < nk);
;     bf16x8 fa[2][2], fb[2][2];
;     fa[0][0] = *(const bf16x8*)(As);
;     fa[0][1] = *(const bf16x8*)(As + 32 * LDK);
;     fb[0][0] = *(const bf16x8*)(Bs);
;     fb[0][1] = *(const bf16x8*)(Bs + 32 * LDK);
; #pragma unroll
;     for (int i = 0; i < 4; i++) {
;       if (wr) {
;         *(u32x4*)(nxt + (r0 + i * 32) * LDK + sg * 8) = g.a[i];
;         *(u32x4*)(nxt + 128 * LDK + (r0 + i * 32) * LDK + sg * 8) = g.b[i];
;       }
;       if (ld) {
;         g.a[i] = *(const u32x4*)(Ap + (size_t)i * 32 * o.lda + (k + 2) * 64);
;         g.b[i] = *(const u32x4*)(Bp + o.bs.o[i] + (k + 2) * 64);
;       }
;       if (i < 3) {
;         fa[(i + 1) & 1][0] = *(const bf16x8*)(As + (i + 1) * 16);
;         fa[(i + 1) & 1][1] = *(const bf16x8*)(As + 32 * LDK + (i + 1) * 16);
;         fb[(i + 1) & 1][0] = *(const bf16x8*)(Bs + (i + 1) * 16);
;         fb[(i + 1) & 1][1] = *(const bf16x8*)(Bs + 32 * LDK + (i + 1) * 16);
;       }
;       __builtin_amdgcn_sched_barrier(0);
;       __builtin_amdgcn_s_setprio(1);
;       acc[0][0] = __builtin_amdgcn_mfma_f32_32x32x16_bf16(fa[i & 1][0], fb[i & 1][0], acc[0][0], 0, 0, 0);
;       acc[0][1] = __builtin_amdgcn_mfma_f32_32x32x16_bf16(fa[i & 1][0], fb[i & 1][1], acc[0][1], 0, 0, 0);
;       acc[1][0] = __builtin_amdgcn_mfma_f32_32x32x16_bf16(fa[i & 1][1], fb[i & 1][0], acc[1][0], 0, 0, 0);
;       acc[1][1] = __builtin_amdgcn_mfma_f32_32x32x16_bf16(fa[i & 1][1], fb[i & 1][1], acc[1][1], 0, 0, 0);
;       __builtin_amdgcn_s_setprio(0);
;     }
;     __syncthreads();
;   }
; __device__ __forceinline__ bool tile_map(int it, int nn, int& mt, int& nt) {
;   const int xcd = blockIdx.x & 7, li = blockIdx.x >> 3, nb = gridDim.x >> 3;
;   int q = it * nb + li;
;   const int per = 16 * nn;
;   if (q < per) {
;     int sub = q / (8 * nn), r = q - sub * (8 * nn);
;     nt = r >> 3;
;     mt = xcd * 16 + sub * 8 + (r & 7);
;     return true;
;   }
;   q -= per;
;   int n = q * 8 + xcd;
	ds_read_b128 v[110:113], v104
	ds_read_b128 v[114:117], v104 offset:4608
	ds_read_b128 v[118:121], v101 offset:18432
	ds_read_b128 v[122:125], v101 offset:23040
	s_waitcnt vmcnt(7)
	ds_write_b128 v100, v[64:67] offset:36864
	s_waitcnt vmcnt(6)
	ds_write_b128 v100, v[68:71] offset:55296
	ds_read_b128 v[126:129], v104 offset:32
	ds_read_b128 v[130:133], v104 offset:4640
	ds_read_b128 v[134:137], v101 offset:18464
	ds_read_b128 v[138:141], v101 offset:23072
	s_waitcnt lgkmcnt(7)
	v_mfma_f32_32x32x16_bf16 v[16:31], v[110:113], v[118:121], v[16:31]
	s_waitcnt lgkmcnt(6)
	v_mfma_f32_32x32x16_bf16 v[48:63], v[110:113], v[122:125], v[48:63]
	v_mfma_f32_32x32x16_bf16 v[0:15], v[114:117], v[118:121], v[0:15]
	v_mfma_f32_32x32x16_bf16 v[32:47], v[114:117], v[122:125], v[32:47]
	s_waitcnt vmcnt(5)
	ds_write_b128 v100, v[72:75] offset:41472
	s_waitcnt vmcnt(4)
	ds_write_b128 v100, v[76:79] offset:59904
	ds_read_b128 v[110:113], v104 offset:64
	ds_read_b128 v[114:117], v104 offset:4672
	ds_read_b128 v[118:121], v101 offset:18496
	ds_read_b128 v[122:125], v101 offset:23104
	s_waitcnt lgkmcnt(7)
	v_mfma_f32_32x32x16_bf16 v[16:31], v[126:129], v[134:137], v[16:31]
	s_waitcnt lgkmcnt(6)
	v_mfma_f32_32x32x16_bf16 v[48:63], v[126:129], v[138:141], v[48:63]
	v_mfma_f32_32x32x16_bf16 v[0:15], v[130:133], v[134:137], v[0:15]
	v_mfma_f32_32x32x16_bf16 v[32:47], v[130:133], v[138:141], v[32:47]
	s_waitcnt vmcnt(3)
	ds_write_b128 v100, v[80:83] offset:46080
	s_waitcnt vmcnt(2)
	ds_write_b128 v100, v[84:87] offset:64512
	ds_read_b128 v[126:129], v104 offset:96
	ds_read_b128 v[130:133], v104 offset:4704
	ds_read_b128 v[134:137], v101 offset:18528
	ds_read_b128 v[138:141], v101 offset:23136
	s_waitcnt lgkmcnt(7)
	v_mfma_f32_32x32x16_bf16 v[16:31], v[110:113], v[118:121], v[16:31]
	s_waitcnt lgkmcnt(6)
	v_mfma_f32_32x32x16_bf16 v[48:63], v[110:113], v[122:125], v[48:63]
	v_mfma_f32_32x32x16_bf16 v[0:15], v[114:117], v[118:121], v[0:15]
	v_mfma_f32_32x32x16_bf16 v[32:47], v[114:117], v[122:125], v[32:47]
	s_waitcnt vmcnt(1)
	ds_write_b128 v100, v[88:91] offset:50688
	s_waitcnt vmcnt(0)
	ds_write_b128 v105, v[92:95] offset:13824
	s_waitcnt lgkmcnt(3)
	v_mfma_f32_32x32x16_bf16 v[16:31], v[126:129], v[134:137], v[16:31]
	s_waitcnt lgkmcnt(2)
	v_mfma_f32_32x32x16_bf16 v[48:63], v[126:129], v[138:141], v[48:63]
	v_mfma_f32_32x32x16_bf16 v[0:15], v[130:133], v[134:137], v[0:15]
	v_mfma_f32_32x32x16_bf16 v[32:47], v[130:133], v[138:141], v[32:47]
	s_waitcnt lgkmcnt(0)
	s_barrier
	ds_read_b128 v[110:113], v104 offset:36864
	ds_read_b128 v[114:117], v104 offset:36896
	ds_read_b128 v[118:121], v104 offset:41472
	ds_read_b128 v[122:125], v104 offset:41504
	ds_read_b128 v[126:129], v101 offset:55296
	ds_read_b128 v[130:133], v101 offset:55328
	ds_read_b128 v[134:137], v101 offset:59904
	ds_read_b128 v[138:141], v101 offset:59936
	s_waitcnt lgkmcnt(3)
	v_mfma_f32_32x32x16_bf16 v[16:31], v[110:113], v[126:129], v[16:31]
	s_waitcnt lgkmcnt(1)
	v_mfma_f32_32x32x16_bf16 v[48:63], v[110:113], v[134:137], v[48:63]
	v_mfma_f32_32x32x16_bf16 v[0:15], v[118:121], v[126:129], v[0:15]
	v_mfma_f32_32x32x16_bf16 v[32:47], v[118:121], v[134:137], v[32:47]
	ds_read_b128 v[110:113], v104 offset:36928
	ds_read_b128 v[118:121], v104 offset:41536
	ds_read_b128 v[126:129], v101 offset:55360
	ds_read_b128 v[134:137], v101 offset:59968
	v_mfma_f32_32x32x16_bf16 v[16:31], v[114:117], v[130:133], v[16:31]
	s_waitcnt lgkmcnt(4)
	v_mfma_f32_32x32x16_bf16 v[48:63], v[114:117], v[138:141], v[48:63]
	v_mfma_f32_32x32x16_bf16 v[0:15], v[122:125], v[130:133], v[0:15]
	v_mfma_f32_32x32x16_bf16 v[32:47], v[122:125], v[138:141], v[32:47]
	ds_read_b128 v[114:117], v104 offset:36960
	ds_read_b128 v[122:125], v104 offset:41568
	ds_read_b128 v[130:133], v101 offset:55392
	ds_read_b128 v[138:141], v101 offset:60000
	s_waitcnt lgkmcnt(5)
	v_mfma_f32_32x32x16_bf16 v[16:31], v[110:113], v[126:129], v[16:31]
	s_waitcnt lgkmcnt(4)
	v_mfma_f32_32x32x16_bf16 v[48:63], v[110:113], v[134:137], v[48:63]
	v_mfma_f32_32x32x16_bf16 v[0:15], v[118:121], v[126:129], v[0:15]
	v_mfma_f32_32x32x16_bf16 v[32:47], v[118:121], v[134:137], v[32:47]
	s_waitcnt lgkmcnt(1)
	v_mfma_f32_32x32x16_bf16 v[16:31], v[114:117], v[130:133], v[16:31]
	s_waitcnt lgkmcnt(0)
	v_mfma_f32_32x32x16_bf16 v[48:63], v[114:117], v[138:141], v[48:63]
	v_mfma_f32_32x32x16_bf16 v[0:15], v[122:125], v[130:133], v[0:15]
	v_mfma_f32_32x32x16_bf16 v[32:47], v[122:125], v[138:141], v[32:47]
	s_cmpk_gt_u32 s86, 0x18f
	s_mov_b64 s[10:11], -1
	s_barrier
	s_cbranch_scc0 .LBB0_469
	s_mov_b64 s[10:11], 0
	s_cmp_gt_i32 s87, 24
	s_mov_b64 s[4:5], 0
	s_cbranch_scc1 .LBB0_469
	s_movk_i32 s0, 0x80
	s_mov_b64 s[4:5], -1
	s_mov_b32 s83, s87

; __device__ __forceinline__ void gemm_run(int tid, f32x16 (&acc)[2][2], GRegs& g, const GOp& o, int K, unsigned char* smem) {
;     ...
;   for (int i = 0; i < 4; i++) {
;     *(u32x4*)(sbuf + (r0 + i * 32) * LDK + sg * 8) = g.a[i];
;     *(u32x4*)(sbuf + 128 * LDK + (r0 + i * 32) * LDK + sg * 8) = g.b[i];
;   }
;   if (nk > 1) {
; #pragma unroll
;     for (int i = 0; i < 4; i++) {
;       g.a[i] = *(const u32x4*)(Ap + (size_t)i * 32 * o.lda + 64);
;       g.b[i] = *(const u32x4*)(Bp + o.bs.o[i] + 64);
;     }
;   }
;   __syncthreads();
;   const int lane = tid & 63, fr = lane & 31, fh = lane >> 5;
;   for (int k = 0; k < nk; k++) {
;     bf16r* cur = sbuf + (k & 1) * (256 * LDK);
;     bf16r* nxt = sbuf + ((k & 1) ^ 1) * (256 * LDK);
;     const bf16r* As = cur + (wm * 64 + fr) * LDK + fh * 8;
;     const bf16r* Bs = cur + 128 * LDK + (wn * 64 + fr) * LDK + fh * 8;
;     const bool wr = (k + 1 < nk), ld = (k + 2 < nk);
;     bf16x8 fa[2][2], fb[2][2];
;     fa[0][0] = *(const bf16x8*)(As);
;     fa[0][1] = *(const bf16x8*)(As + 32 * LDK);
;     fb[0][0] = *(const bf16x8*)(Bs);
;     fb[0][1] = *(const bf16x8*)(Bs + 32 * LDK);
; #pragma unroll
;     for (int i = 0; i < 4; i++) {
;       if (wr) {
;         *(u32x4*)(nxt + (r0 + i * 32) * LDK + sg * 8) = g.a[i];
;         *(u32x4*)(nxt + 128 * LDK + (r0 + i * 32) * LDK + sg * 8) = g.b[i];
;       }
;       if (ld) {
;         g.a[i] = *(const u32x4*)(Ap + (size_t)i * 32 * o.lda + (k + 2) * 64);
;         g.b[i] = *(const u32x4*)(Bp + o.bs.o[i] + (k + 2) * 64);
;       }
;       if (i < 3) {
;         fa[(i + 1) & 1][0] = *(const bf16x8*)(As + (i + 1) * 16);
;         fa[(i + 1) & 1][1] = *(const bf16x8*)(As + 32 * LDK + (i + 1) * 16);
;         fb[(i + 1) & 1][0] = *(const bf16x8*)(Bs + (i + 1) * 16);
;         fb[(i + 1) & 1][1] = *(const bf16x8*)(Bs + 32 * LDK + (i + 1) * 16);
;       }
;       __builtin_amdgcn_sched_barrier(0);
;       __builtin_amdgcn_s_setprio(1);
;       acc[0][0] = __builtin_amdgcn_mfma_f32_32x32x16_bf16(fa[i & 1][0], fb[i & 1][0], acc[0][0], 0, 0, 0);
;       acc[0][1] = __builtin_amdgcn_mfma_f32_32x32x16_bf16(fa[i & 1][0], fb[i & 1][1], acc[0][1], 0, 0, 0);
;       acc[1][0] = __builtin_amdgcn_mfma_f32_32x32x16_bf16(fa[i & 1][1], fb[i & 1][0], acc[1][0], 0, 0, 0);
;       acc[1][1] = __builtin_amdgcn_mfma_f32_32x32x16_bf16(fa[i & 1][1], fb[i & 1][1], acc[1][1], 0, 0, 0);
.LBB0_800:
	s_ashr_i32 s7, s6, 31
	s_lshl_b64 s[0:1], s[6:7], 18
	s_ashr_i32 s9, s8, 31
	s_waitcnt vmcnt(7)
	ds_write_b128 v100, v[64:67]
	s_waitcnt vmcnt(6)
	ds_write_b128 v100, v[68:71] offset:18432
	s_waitcnt vmcnt(5)
	ds_write_b128 v100, v[72:75] offset:4608
	s_waitcnt vmcnt(4)
	ds_write_b128 v100, v[76:79] offset:23040
	s_waitcnt vmcnt(3)
	ds_write_b128 v100, v[80:83] offset:9216
	s_waitcnt vmcnt(2)
	ds_write_b128 v100, v[84:87] offset:27648
	s_waitcnt vmcnt(1)
	ds_write_b128 v100, v[88:91] offset:13824
	s_waitcnt vmcnt(0)
	ds_write_b128 v100, v[92:95] offset:32256
	v_lshl_add_u64 v[64:65], v[102:103], 0, s[0:1]
	s_lshl_b64 s[4:5], s[8:9], 18
	v_add_co_u32_e32 v72, vcc, s84, v64
	v_lshl_add_u64 v[106:107], v[98:99], 0, s[4:5]
	s_nop 0
	v_addc_co_u32_e32 v73, vcc, 0, v65, vcc
	v_add_co_u32_e32 v76, vcc, s84, v106
	global_load_dwordx4 v[0:3], v[64:65], off offset:128
	global_load_dwordx4 v[4:7], v[106:107], off offset:128
	v_addc_co_u32_e32 v77, vcc, 0, v107, vcc
	v_add_co_u32_e32 v80, vcc, s85, v64
	global_load_dwordx4 v[66:69], v[72:73], off offset:128
	global_load_dwordx4 v[110:113], v[76:77], off offset:128
	v_addc_co_u32_e32 v81, vcc, 0, v65, vcc
	v_add_co_u32_e32 v84, vcc, s85, v106
	s_nop 1
	v_addc_co_u32_e32 v85, vcc, 0, v107, vcc
	v_add_co_u32_e32 v88, vcc, s76, v64
	global_load_dwordx4 v[114:117], v[80:81], off offset:128
	global_load_dwordx4 v[118:121], v[84:85], off offset:128
	v_addc_co_u32_e32 v89, vcc, 0, v65, vcc
	v_add_co_u32_e32 v92, vcc, s76, v106
	s_nop 1
	v_addc_co_u32_e32 v93, vcc, 0, v107, vcc
	global_load_dwordx4 v[122:125], v[88:89], off offset:128
	global_load_dwordx4 v[126:129], v[92:93], off offset:128
	s_waitcnt lgkmcnt(0)
	s_barrier
	global_load_dwordx4 v[130:133], v[64:65], off offset:256
	global_load_dwordx4 v[134:137], v[106:107], off offset:256
	ds_read_b128 v[8:11], v104
	ds_read_b128 v[32:35], v104 offset:4608
	ds_read_b128 v[12:15], v101 offset:18432
	ds_read_b128 v[36:39], v101 offset:23040
	s_waitcnt vmcnt(9)
	ds_write_b128 v100, v[0:3] offset:36864
	s_waitcnt vmcnt(8)
	ds_write_b128 v100, v[4:7] offset:55296
	ds_read_b128 v[138:141], v104 offset:32
	ds_read_b128 v[142:145], v104 offset:4640
	ds_read_b128 v[146:149], v101 offset:18464
	ds_read_b128 v[150:153], v101 offset:23072
	s_waitcnt lgkmcnt(7)
	v_mfma_f32_32x32x16_bf16 v[16:31], v[8:11], v[12:15], 0
	s_waitcnt lgkmcnt(6)
	v_mfma_f32_32x32x16_bf16 v[48:63], v[8:11], v[36:39], 0
	v_mfma_f32_32x32x16_bf16 v[0:15], v[32:35], v[12:15], 0
	v_mfma_f32_32x32x16_bf16 v[32:47], v[32:35], v[36:39], 0
	global_load_dwordx4 v[154:157], v[72:73], off offset:256
	global_load_dwordx4 v[158:161], v[76:77], off offset:256
	s_waitcnt vmcnt(9)
	ds_write_b128 v100, v[66:69] offset:41472
	s_waitcnt vmcnt(8)
	ds_write_b128 v100, v[110:113] offset:59904
	ds_read_b128 v[66:69], v104 offset:64
	ds_read_b128 v[110:113], v104 offset:4672
	ds_read_b128 v[162:165], v101 offset:18496
	ds_read_b128 v[166:169], v101 offset:23104
	s_waitcnt lgkmcnt(7)
	v_mfma_f32_32x32x16_bf16 v[16:31], v[138:141], v[146:149], v[16:31]
	s_waitcnt lgkmcnt(6)
	v_mfma_f32_32x32x16_bf16 v[48:63], v[138:141], v[150:153], v[48:63]
	v_mfma_f32_32x32x16_bf16 v[0:15], v[142:145], v[146:149], v[0:15]
	v_mfma_f32_32x32x16_bf16 v[32:47], v[142:145], v[150:153], v[32:47]
	global_load_dwordx4 v[138:141], v[80:81], off offset:256
	global_load_dwordx4 v[142:145], v[84:85], off offset:256
	s_waitcnt vmcnt(9)
	ds_write_b128 v100, v[114:117] offset:46080
	s_waitcnt vmcnt(8)
	ds_write_b128 v100, v[118:121] offset:64512
	ds_read_b128 v[114:117], v104 offset:96
	ds_read_b128 v[118:121], v104 offset:4704
	ds_read_b128 v[146:149], v101 offset:18528
	ds_read_b128 v[150:153], v101 offset:23136
	s_waitcnt lgkmcnt(7)
	v_mfma_f32_32x32x16_bf16 v[16:31], v[66:69], v[162:165], v[16:31]
	s_waitcnt lgkmcnt(6)
	v_mfma_f32_32x32x16_bf16 v[48:63], v[66:69], v[166:169], v[48:63]
	v_mfma_f32_32x32x16_bf16 v[0:15], v[110:113], v[162:165], v[0:15]
	v_mfma_f32_32x32x16_bf16 v[32:47], v[110:113], v[166:169], v[32:47]
	global_load_dwordx4 v[66:69], v[88:89], off offset:256
	global_load_dwordx4 v[110:113], v[92:93], off offset:256
	s_waitcnt vmcnt(9)
	ds_write_b128 v100, v[122:125] offset:50688
	s_waitcnt vmcnt(8)
	ds_write_b128 v105, v[126:129] offset:13824
	s_waitcnt lgkmcnt(3)
	v_mfma_f32_32x32x16_bf16 v[16:31], v[114:117], v[146:149], v[16:31]
	s_waitcnt lgkmcnt(2)
	v_mfma_f32_32x32x16_bf16 v[48:63], v[114:117], v[150:153], v[48:63]
	v_mfma_f32_32x32x16_bf16 v[0:15], v[118:121], v[146:149], v[0:15]
	v_mfma_f32_32x32x16_bf16 v[32:47], v[118:121], v[150:153], v[32:47]
	s_waitcnt lgkmcnt(0)
	s_barrier
; __device__ __forceinline__ void gemm_run(int tid, f32x16 (&acc)[2][2], GRegs& g, const GOp& o, int K, unsigned char* smem) {
;     ...
;   for (int k = 0; k < nk; k++) {
;     bf16r* cur = sbuf + (k & 1) * (256 * LDK);
;     bf16r* nxt = sbuf + ((k & 1) ^ 1) * (256 * LDK);
;     const bf16r* As = cur + (wm * 64 + fr) * LDK + fh * 8;
;     const bf16r* Bs = cur + 128 * LDK + (wn * 64 + fr) * LDK + fh * 8;
;     const bool wr = (k + 1 < nk), ld = (k + 2 < nk);
;     bf16x8 fa[2][2], fb[2][2];
;     fa[0][0] = *(const bf16x8*)(As);
;     fa[0][1] = *(const bf16x8*)(As + 32 * LDK);
;     fb[0][0] = *(const bf16x8*)(Bs);
;     fb[0][1] = *(const bf16x8*)(Bs + 32 * LDK);
; #pragma unroll
;     for (int i = 0; i < 4; i++) {
;       if (wr) {
;         *(u32x4*)(nxt + (r0 + i * 32) * LDK + sg * 8) = g.a[i];
;         *(u32x4*)(nxt + 128 * LDK + (r0 + i * 32) * LDK + sg * 8) = g.b[i];
;       }
;       if (ld) {
;         g.a[i] = *(const u32x4*)(Ap + (size_t)i * 32 * o.lda + (k + 2) * 64);
;         g.b[i] = *(const u32x4*)(Bp + o.bs.o[i] + (k + 2) * 64);
;       }
;       if (i < 3) {
;         fa[(i + 1) & 1][0] = *(const bf16x8*)(As + (i + 1) * 16);
;         fa[(i + 1) & 1][1] = *(const bf16x8*)(As + 32 * LDK + (i + 1) * 16);
;         fb[(i + 1) & 1][0] = *(const bf16x8*)(Bs + (i + 1) * 16);
;         fb[(i + 1) & 1][1] = *(const bf16x8*)(Bs + 32 * LDK + (i + 1) * 16);
;       }
;       __builtin_amdgcn_sched_barrier(0);
;       __builtin_amdgcn_s_setprio(1);
;       acc[0][0] = __builtin_amdgcn_mfma_f32_32x32x16_bf16(fa[i & 1][0], fb[i & 1][0], acc[0][0], 0, 0, 0);
;       acc[0][1] = __builtin_amdgcn_mfma_f32_32x32x16_bf16(fa[i & 1][0], fb[i & 1][1], acc[0][1], 0, 0, 0);
;       acc[1][0] = __builtin_amdgcn_mfma_f32_32x32x16_bf16(fa[i & 1][1], fb[i & 1][0], acc[1][0], 0, 0, 0);
;       acc[1][1] = __builtin_amdgcn_mfma_f32_32x32x16_bf16(fa[i & 1][1], fb[i & 1][1], acc[1][1], 0, 0, 0);
;       __builtin_amdgcn_s_setprio(0);
;     }
	global_load_dwordx4 v[114:117], v[64:65], off offset:384
	global_load_dwordx4 v[118:121], v[106:107], off offset:384
	ds_read_b128 v[122:125], v104 offset:36864
	ds_read_b128 v[126:129], v104 offset:41472
	ds_read_b128 v[146:149], v101 offset:55296
	ds_read_b128 v[150:153], v101 offset:59904
	s_waitcnt vmcnt(9)
	ds_write_b128 v100, v[130:133]
	s_waitcnt vmcnt(8)
	ds_write_b128 v100, v[134:137] offset:18432
	ds_read_b128 v[130:133], v104 offset:36896
	ds_read_b128 v[134:137], v104 offset:41504
	ds_read_b128 v[162:165], v101 offset:55328
	ds_read_b128 v[166:169], v101 offset:59936
	s_waitcnt lgkmcnt(7)
	v_mfma_f32_32x32x16_bf16 v[16:31], v[122:125], v[146:149], v[16:31]
	s_waitcnt lgkmcnt(6)
	v_mfma_f32_32x32x16_bf16 v[48:63], v[122:125], v[150:153], v[48:63]
	v_mfma_f32_32x32x16_bf16 v[0:15], v[126:129], v[146:149], v[0:15]
	v_mfma_f32_32x32x16_bf16 v[32:47], v[126:129], v[150:153], v[32:47]
	global_load_dwordx4 v[122:125], v[72:73], off offset:384
	global_load_dwordx4 v[126:129], v[76:77], off offset:384
	s_waitcnt vmcnt(9)
	ds_write_b128 v100, v[154:157] offset:4608
	s_waitcnt vmcnt(8)
	ds_write_b128 v100, v[158:161] offset:23040
	ds_read_b128 v[146:149], v104 offset:36928
	ds_read_b128 v[150:153], v104 offset:41536
	ds_read_b128 v[154:157], v101 offset:55360
	ds_read_b128 v[158:161], v101 offset:59968
	s_waitcnt lgkmcnt(7)
	v_mfma_f32_32x32x16_bf16 v[16:31], v[130:133], v[162:165], v[16:31]
	s_waitcnt lgkmcnt(6)
	v_mfma_f32_32x32x16_bf16 v[48:63], v[130:133], v[166:169], v[48:63]
	v_mfma_f32_32x32x16_bf16 v[0:15], v[134:137], v[162:165], v[0:15]
	v_mfma_f32_32x32x16_bf16 v[32:47], v[134:137], v[166:169], v[32:47]
	global_load_dwordx4 v[130:133], v[80:81], off offset:384
	global_load_dwordx4 v[134:137], v[84:85], off offset:384
	s_waitcnt vmcnt(9)
	ds_write_b128 v100, v[138:141] offset:9216
	s_waitcnt vmcnt(8)
	ds_write_b128 v100, v[142:145] offset:27648
	ds_read_b128 v[138:141], v104 offset:36960
	ds_read_b128 v[142:145], v104 offset:41568
	ds_read_b128 v[162:165], v101 offset:55392
	ds_read_b128 v[166:169], v101 offset:60000
	s_waitcnt lgkmcnt(7)
	v_mfma_f32_32x32x16_bf16 v[16:31], v[146:149], v[154:157], v[16:31]
	s_waitcnt lgkmcnt(6)
	v_mfma_f32_32x32x16_bf16 v[48:63], v[146:149], v[158:161], v[48:63]
	v_mfma_f32_32x32x16_bf16 v[0:15], v[150:153], v[154:157], v[0:15]
	v_mfma_f32_32x32x16_bf16 v[32:47], v[150:153], v[158:161], v[32:47]
	global_load_dwordx4 v[146:149], v[88:89], off offset:384
	global_load_dwordx4 v[150:153], v[92:93], off offset:384
	s_waitcnt vmcnt(9)
	ds_write_b128 v100, v[66:69] offset:13824
	s_waitcnt vmcnt(8)
	ds_write_b128 v100, v[110:113] offset:32256
	s_waitcnt lgkmcnt(3)
	v_mfma_f32_32x32x16_bf16 v[16:31], v[138:141], v[162:165], v[16:31]
	s_waitcnt lgkmcnt(2)
	v_mfma_f32_32x32x16_bf16 v[48:63], v[138:141], v[166:169], v[48:63]
	v_mfma_f32_32x32x16_bf16 v[0:15], v[142:145], v[162:165], v[0:15]
	v_mfma_f32_32x32x16_bf16 v[32:47], v[142:145], v[166:169], v[32:47]
	s_waitcnt lgkmcnt(0)
	s_barrier
	global_load_dwordx4 v[66:69], v[64:65], off offset:512
	global_load_dwordx4 v[110:113], v[106:107], off offset:512
	ds_read_b128 v[138:141], v104
	ds_read_b128 v[142:145], v104 offset:4608
	ds_read_b128 v[154:157], v101 offset:18432
	ds_read_b128 v[158:161], v101 offset:23040
	s_waitcnt vmcnt(9)
	ds_write_b128 v100, v[114:117] offset:36864
	s_waitcnt vmcnt(8)
	ds_write_b128 v100, v[118:121] offset:55296
	ds_read_b128 v[114:117], v104 offset:32
	ds_read_b128 v[118:121], v104 offset:4640
	ds_read_b128 v[162:165], v101 offset:18464
	ds_read_b128 v[166:169], v101 offset:23072
	s_waitcnt lgkmcnt(7)
	v_mfma_f32_32x32x16_bf16 v[16:31], v[138:141], v[154:157], v[16:31]
	s_waitcnt lgkmcnt(6)
	v_mfma_f32_32x32x16_bf16 v[48:63], v[138:141], v[158:161], v[48:63]
	v_mfma_f32_32x32x16_bf16 v[0:15], v[142:145], v[154:157], v[0:15]
	v_mfma_f32_32x32x16_bf16 v[32:47], v[142:145], v[158:161], v[32:47]
	global_load_dwordx4 v[138:141], v[72:73], off offset:512
	global_load_dwordx4 v[142:145], v[76:77], off offset:512
	s_waitcnt vmcnt(9)
	ds_write_b128 v100, v[122:125] offset:41472
	s_waitcnt vmcnt(8)
	ds_write_b128 v100, v[126:129] offset:59904
	ds_read_b128 v[122:125], v104 offset:64
	ds_read_b128 v[126:129], v104 offset:4672
	ds_read_b128 v[154:157], v101 offset:18496
	ds_read_b128 v[158:161], v101 offset:23104
	s_waitcnt lgkmcnt(7)
	v_mfma_f32_32x32x16_bf16 v[16:31], v[114:117], v[162:165], v[16:31]
	s_waitcnt lgkmcnt(6)
	v_mfma_f32_32x32x16_bf16 v[48:63], v[114:117], v[166:169], v[48:63]
	v_mfma_f32_32x32x16_bf16 v[0:15], v[118:121], v[162:165], v[0:15]
	v_mfma_f32_32x32x16_bf16 v[32:47], v[118:121], v[166:169], v[32:47]
	global_load_dwordx4 v[114:117], v[80:81], off offset:512
	global_load_dwordx4 v[118:121], v[84:85], off offset:512
	s_waitcnt vmcnt(9)
	ds_write_b128 v100, v[130:133] offset:46080
	s_waitcnt vmcnt(8)
	ds_write_b128 v100, v[134:137] offset:64512
	ds_read_b128 v[130:133], v104 offset:96
	ds_read_b128 v[134:137], v104 offset:4704
	ds_read_b128 v[162:165], v101 offset:18528
	ds_read_b128 v[166:169], v101 offset:23136
	s_waitcnt lgkmcnt(7)
	v_mfma_f32_32x32x16_bf16 v[16:31], v[122:125], v[154:157], v[16:31]
	s_waitcnt lgkmcnt(6)
	v_mfma_f32_32x32x16_bf16 v[48:63], v[122:125], v[158:161], v[48:63]
	v_mfma_f32_32x32x16_bf16 v[0:15], v[126:129], v[154:157], v[0:15]
	v_mfma_f32_32x32x16_bf16 v[32:47], v[126:129], v[158:161], v[32:47]
	global_load_dwordx4 v[122:125], v[88:89], off offset:512
	global_load_dwordx4 v[126:129], v[92:93], off offset:512
	s_waitcnt vmcnt(9)
	ds_write_b128 v100, v[146:149] offset:50688
	s_waitcnt vmcnt(8)
	ds_write_b128 v105, v[150:153] offset:13824
	s_waitcnt lgkmcnt(3)
	v_mfma_f32_32x32x16_bf16 v[16:31], v[130:133], v[162:165], v[16:31]
	s_waitcnt lgkmcnt(2)
	v_mfma_f32_32x32x16_bf16 v[48:63], v[130:133], v[166:169], v[48:63]
	v_mfma_f32_32x32x16_bf16 v[0:15], v[134:137], v[162:165], v[0:15]
	v_mfma_f32_32x32x16_bf16 v[32:47], v[134:137], v[166:169], v[32:47]
	s_waitcnt lgkmcnt(0)
	s_barrier
; __device__ __forceinline__ void gemm_run(int tid, f32x16 (&acc)[2][2], GRegs& g, const GOp& o, int K, unsigned char* smem) {
;     ...
;   for (int k = 0; k < nk; k++) {
;     bf16r* cur = sbuf + (k & 1) * (256 * LDK);
;     bf16r* nxt = sbuf + ((k & 1) ^ 1) * (256 * LDK);
;     const bf16r* As = cur + (wm * 64 + fr) * LDK + fh * 8;
;     const bf16r* Bs = cur + 128 * LDK + (wn * 64 + fr) * LDK + fh * 8;
;     const bool wr = (k + 1 < nk), ld = (k + 2 < nk);
;     bf16x8 fa[2][2], fb[2][2];
;     fa[0][0] = *(const bf16x8*)(As);
;     fa[0][1] = *(const bf16x8*)(As + 32 * LDK);
;     fb[0][0] = *(const bf16x8*)(Bs);
;     fb[0][1] = *(const bf16x8*)(Bs + 32 * LDK);
; #pragma unroll
;     for (int i = 0; i < 4; i++) {
;       if (wr) {
;         *(u32x4*)(nxt + (r0 + i * 32) * LDK + sg * 8) = g.a[i];
;         *(u32x4*)(nxt + 128 * LDK + (r0 + i * 32) * LDK + sg * 8) = g.b[i];
;       }
;       if (ld) {
;         g.a[i] = *(const u32x4*)(Ap + (size_t)i * 32 * o.lda + (k + 2) * 64);
;         g.b[i] = *(const u32x4*)(Bp + o.bs.o[i] + (k + 2) * 64);
;       }
;       if (i < 3) {
;         fa[(i + 1) & 1][0] = *(const bf16x8*)(As + (i + 1) * 16);
;         fa[(i + 1) & 1][1] = *(const bf16x8*)(As + 32 * LDK + (i + 1) * 16);
;         fb[(i + 1) & 1][0] = *(const bf16x8*)(Bs + (i + 1) * 16);
;         fb[(i + 1) & 1][1] = *(const bf16x8*)(Bs + 32 * LDK + (i + 1) * 16);
;       }
;       __builtin_amdgcn_sched_barrier(0);
;       __builtin_amdgcn_s_setprio(1);
;       acc[0][0] = __builtin_amdgcn_mfma_f32_32x32x16_bf16(fa[i & 1][0], fb[i & 1][0], acc[0][0], 0, 0, 0);
;       acc[0][1] = __builtin_amdgcn_mfma_f32_32x32x16_bf16(fa[i & 1][0], fb[i & 1][1], acc[0][1], 0, 0, 0);
;       acc[1][0] = __builtin_amdgcn_mfma_f32_32x32x16_bf16(fa[i & 1][1], fb[i & 1][0], acc[1][0], 0, 0, 0);
;       acc[1][1] = __builtin_amdgcn_mfma_f32_32x32x16_bf16(fa[i & 1][1], fb[i & 1][1], acc[1][1], 0, 0, 0);
;       __builtin_amdgcn_s_setprio(0);
;     }
	global_load_dwordx4 v[130:133], v[64:65], off offset:640
	global_load_dwordx4 v[134:137], v[106:107], off offset:640
	ds_read_b128 v[146:149], v104 offset:36864
	ds_read_b128 v[150:153], v104 offset:41472
	ds_read_b128 v[154:157], v101 offset:55296
	ds_read_b128 v[158:161], v101 offset:59904
	s_waitcnt vmcnt(9)
	ds_write_b128 v100, v[66:69]
	s_waitcnt vmcnt(8)
	ds_write_b128 v100, v[110:113] offset:18432
	ds_read_b128 v[66:69], v104 offset:36896
	ds_read_b128 v[110:113], v104 offset:41504
	ds_read_b128 v[162:165], v101 offset:55328
	ds_read_b128 v[166:169], v101 offset:59936
	s_waitcnt lgkmcnt(7)
	v_mfma_f32_32x32x16_bf16 v[16:31], v[146:149], v[154:157], v[16:31]
	s_waitcnt lgkmcnt(6)
	v_mfma_f32_32x32x16_bf16 v[48:63], v[146:149], v[158:161], v[48:63]
	v_mfma_f32_32x32x16_bf16 v[0:15], v[150:153], v[154:157], v[0:15]
	v_mfma_f32_32x32x16_bf16 v[32:47], v[150:153], v[158:161], v[32:47]
	global_load_dwordx4 v[146:149], v[72:73], off offset:640
	global_load_dwordx4 v[150:153], v[76:77], off offset:640
	s_waitcnt vmcnt(9)
	ds_write_b128 v100, v[138:141] offset:4608
	s_waitcnt vmcnt(8)
	ds_write_b128 v100, v[142:145] offset:23040
	ds_read_b128 v[138:141], v104 offset:36928
	ds_read_b128 v[142:145], v104 offset:41536
	ds_read_b128 v[154:157], v101 offset:55360
	ds_read_b128 v[158:161], v101 offset:59968
	s_waitcnt lgkmcnt(7)
	v_mfma_f32_32x32x16_bf16 v[16:31], v[66:69], v[162:165], v[16:31]
	s_waitcnt lgkmcnt(6)
	v_mfma_f32_32x32x16_bf16 v[48:63], v[66:69], v[166:169], v[48:63]
	v_mfma_f32_32x32x16_bf16 v[0:15], v[110:113], v[162:165], v[0:15]
	v_mfma_f32_32x32x16_bf16 v[32:47], v[110:113], v[166:169], v[32:47]
	global_load_dwordx4 v[66:69], v[80:81], off offset:640
	global_load_dwordx4 v[110:113], v[84:85], off offset:640
	s_waitcnt vmcnt(9)
	ds_write_b128 v100, v[114:117] offset:9216
	s_waitcnt vmcnt(8)
	ds_write_b128 v100, v[118:121] offset:27648
	ds_read_b128 v[114:117], v104 offset:36960
	ds_read_b128 v[118:121], v104 offset:41568
	ds_read_b128 v[162:165], v101 offset:55392
	ds_read_b128 v[166:169], v101 offset:60000
	s_waitcnt lgkmcnt(7)
	v_mfma_f32_32x32x16_bf16 v[16:31], v[138:141], v[154:157], v[16:31]
	s_waitcnt lgkmcnt(6)
	v_mfma_f32_32x32x16_bf16 v[48:63], v[138:141], v[158:161], v[48:63]
	v_mfma_f32_32x32x16_bf16 v[0:15], v[142:145], v[154:157], v[0:15]
	v_mfma_f32_32x32x16_bf16 v[32:47], v[142:145], v[158:161], v[32:47]
	global_load_dwordx4 v[138:141], v[88:89], off offset:640
	global_load_dwordx4 v[142:145], v[92:93], off offset:640
	s_waitcnt vmcnt(9)
	ds_write_b128 v100, v[122:125] offset:13824
	s_waitcnt vmcnt(8)
	ds_write_b128 v100, v[126:129] offset:32256
	s_waitcnt lgkmcnt(3)
	v_mfma_f32_32x32x16_bf16 v[16:31], v[114:117], v[162:165], v[16:31]
	s_waitcnt lgkmcnt(2)
	v_mfma_f32_32x32x16_bf16 v[48:63], v[114:117], v[166:169], v[48:63]
	v_mfma_f32_32x32x16_bf16 v[0:15], v[118:121], v[162:165], v[0:15]
	v_mfma_f32_32x32x16_bf16 v[32:47], v[118:121], v[166:169], v[32:47]
	s_waitcnt lgkmcnt(0)
	s_barrier
	global_load_dwordx4 v[114:117], v[64:65], off offset:768
	global_load_dwordx4 v[118:121], v[106:107], off offset:768
	ds_read_b128 v[122:125], v104
	ds_read_b128 v[126:129], v104 offset:4608
	ds_read_b128 v[154:157], v101 offset:18432
	ds_read_b128 v[158:161], v101 offset:23040
	s_waitcnt vmcnt(9)
	ds_write_b128 v100, v[130:133] offset:36864
	s_waitcnt vmcnt(8)
	ds_write_b128 v100, v[134:137] offset:55296
	ds_read_b128 v[130:133], v104 offset:32
	ds_read_b128 v[134:137], v104 offset:4640
	ds_read_b128 v[162:165], v101 offset:18464
	ds_read_b128 v[166:169], v101 offset:23072
	s_waitcnt lgkmcnt(7)
	v_mfma_f32_32x32x16_bf16 v[16:31], v[122:125], v[154:157], v[16:31]
	s_waitcnt lgkmcnt(6)
	v_mfma_f32_32x32x16_bf16 v[48:63], v[122:125], v[158:161], v[48:63]
	v_mfma_f32_32x32x16_bf16 v[0:15], v[126:129], v[154:157], v[0:15]
	v_mfma_f32_32x32x16_bf16 v[32:47], v[126:129], v[158:161], v[32:47]
	global_load_dwordx4 v[122:125], v[72:73], off offset:768
	global_load_dwordx4 v[126:129], v[76:77], off offset:768
	s_waitcnt vmcnt(9)
	ds_write_b128 v100, v[146:149] offset:41472
	s_waitcnt vmcnt(8)
	ds_write_b128 v100, v[150:153] offset:59904
	ds_read_b128 v[146:149], v104 offset:64
	ds_read_b128 v[150:153], v104 offset:4672
	ds_read_b128 v[154:157], v101 offset:18496
	ds_read_b128 v[158:161], v101 offset:23104
	s_waitcnt lgkmcnt(7)
	v_mfma_f32_32x32x16_bf16 v[16:31], v[130:133], v[162:165], v[16:31]
	s_waitcnt lgkmcnt(6)
	v_mfma_f32_32x32x16_bf16 v[48:63], v[130:133], v[166:169], v[48:63]
	v_mfma_f32_32x32x16_bf16 v[0:15], v[134:137], v[162:165], v[0:15]
	v_mfma_f32_32x32x16_bf16 v[32:47], v[134:137], v[166:169], v[32:47]
	global_load_dwordx4 v[130:133], v[80:81], off offset:768
	global_load_dwordx4 v[134:137], v[84:85], off offset:768
	s_waitcnt vmcnt(9)
	ds_write_b128 v100, v[66:69] offset:46080
	s_waitcnt vmcnt(8)
	ds_write_b128 v100, v[110:113] offset:64512
	ds_read_b128 v[66:69], v104 offset:96
	ds_read_b128 v[110:113], v104 offset:4704
	ds_read_b128 v[162:165], v101 offset:18528
	ds_read_b128 v[166:169], v101 offset:23136
	s_waitcnt lgkmcnt(7)
	v_mfma_f32_32x32x16_bf16 v[16:31], v[146:149], v[154:157], v[16:31]
	s_waitcnt lgkmcnt(6)
	v_mfma_f32_32x32x16_bf16 v[48:63], v[146:149], v[158:161], v[48:63]
	v_mfma_f32_32x32x16_bf16 v[0:15], v[150:153], v[154:157], v[0:15]
	v_mfma_f32_32x32x16_bf16 v[32:47], v[150:153], v[158:161], v[32:47]
	global_load_dwordx4 v[146:149], v[88:89], off offset:768
	global_load_dwordx4 v[150:153], v[92:93], off offset:768
	s_waitcnt vmcnt(9)
	ds_write_b128 v100, v[138:141] offset:50688
	s_waitcnt vmcnt(8)
	ds_write_b128 v105, v[142:145] offset:13824
	s_waitcnt lgkmcnt(3)
	v_mfma_f32_32x32x16_bf16 v[16:31], v[66:69], v[162:165], v[16:31]
	s_waitcnt lgkmcnt(2)
	v_mfma_f32_32x32x16_bf16 v[48:63], v[66:69], v[166:169], v[48:63]
	v_mfma_f32_32x32x16_bf16 v[0:15], v[110:113], v[162:165], v[0:15]
	v_mfma_f32_32x32x16_bf16 v[32:47], v[110:113], v[166:169], v[32:47]
	s_waitcnt lgkmcnt(0)
	s_barrier
; __device__ __forceinline__ void gemm_run(int tid, f32x16 (&acc)[2][2], GRegs& g, const GOp& o, int K, unsigned char* smem) {
;     ...
;   for (int k = 0; k < nk; k++) {
;     bf16r* cur = sbuf + (k & 1) * (256 * LDK);
;     bf16r* nxt = sbuf + ((k & 1) ^ 1) * (256 * LDK);
;     const bf16r* As = cur + (wm * 64 + fr) * LDK + fh * 8;
;     const bf16r* Bs = cur + 128 * LDK + (wn * 64 + fr) * LDK + fh * 8;
;     const bool wr = (k + 1 < nk), ld = (k + 2 < nk);
;     bf16x8 fa[2][2], fb[2][2];
;     fa[0][0] = *(const bf16x8*)(As);
;     fa[0][1] = *(const bf16x8*)(As + 32 * LDK);
;     fb[0][0] = *(const bf16x8*)(Bs);
;     fb[0][1] = *(const bf16x8*)(Bs + 32 * LDK);
; #pragma unroll
;     for (int i = 0; i < 4; i++) {
;       if (wr) {
;         *(u32x4*)(nxt + (r0 + i * 32) * LDK + sg * 8) = g.a[i];
;         *(u32x4*)(nxt + 128 * LDK + (r0 + i * 32) * LDK + sg * 8) = g.b[i];
;       }
;       if (ld) {
;         g.a[i] = *(const u32x4*)(Ap + (size_t)i * 32 * o.lda + (k + 2) * 64);
;         g.b[i] = *(const u32x4*)(Bp + o.bs.o[i] + (k + 2) * 64);
;       }
;       if (i < 3) {
;         fa[(i + 1) & 1][0] = *(const bf16x8*)(As + (i + 1) * 16);
;         fa[(i + 1) & 1][1] = *(const bf16x8*)(As + 32 * LDK + (i + 1) * 16);
;         fb[(i + 1) & 1][0] = *(const bf16x8*)(Bs + (i + 1) * 16);
;         fb[(i + 1) & 1][1] = *(const bf16x8*)(Bs + 32 * LDK + (i + 1) * 16);
;       }
;       __builtin_amdgcn_sched_barrier(0);
;       __builtin_amdgcn_s_setprio(1);
;       acc[0][0] = __builtin_amdgcn_mfma_f32_32x32x16_bf16(fa[i & 1][0], fb[i & 1][0], acc[0][0], 0, 0, 0);
;       acc[0][1] = __builtin_amdgcn_mfma_f32_32x32x16_bf16(fa[i & 1][0], fb[i & 1][1], acc[0][1], 0, 0, 0);
;       acc[1][0] = __builtin_amdgcn_mfma_f32_32x32x16_bf16(fa[i & 1][1], fb[i & 1][0], acc[1][0], 0, 0, 0);
;       acc[1][1] = __builtin_amdgcn_mfma_f32_32x32x16_bf16(fa[i & 1][1], fb[i & 1][1], acc[1][1], 0, 0, 0);
;       __builtin_amdgcn_s_setprio(0);
;     }
	global_load_dwordx4 v[66:69], v[64:65], off offset:896
	global_load_dwordx4 v[110:113], v[106:107], off offset:896
	ds_read_b128 v[138:141], v104 offset:36864
	ds_read_b128 v[142:145], v104 offset:41472
	ds_read_b128 v[154:157], v101 offset:55296
	ds_read_b128 v[158:161], v101 offset:59904
	s_waitcnt vmcnt(9)
	ds_write_b128 v100, v[114:117]
	s_waitcnt vmcnt(8)
	ds_write_b128 v100, v[118:121] offset:18432
	ds_read_b128 v[114:117], v104 offset:36896
	ds_read_b128 v[118:121], v104 offset:41504
	ds_read_b128 v[162:165], v101 offset:55328
	ds_read_b128 v[166:169], v101 offset:59936
	s_waitcnt lgkmcnt(7)
	v_mfma_f32_32x32x16_bf16 v[16:31], v[138:141], v[154:157], v[16:31]
	s_waitcnt lgkmcnt(6)
	v_mfma_f32_32x32x16_bf16 v[48:63], v[138:141], v[158:161], v[48:63]
	v_mfma_f32_32x32x16_bf16 v[0:15], v[142:145], v[154:157], v[0:15]
	v_mfma_f32_32x32x16_bf16 v[32:47], v[142:145], v[158:161], v[32:47]
	global_load_dwordx4 v[138:141], v[72:73], off offset:896
	global_load_dwordx4 v[142:145], v[76:77], off offset:896
	s_waitcnt vmcnt(9)
	ds_write_b128 v100, v[122:125] offset:4608
	s_waitcnt vmcnt(8)
	ds_write_b128 v100, v[126:129] offset:23040
	ds_read_b128 v[122:125], v104 offset:36928
	ds_read_b128 v[126:129], v104 offset:41536
	ds_read_b128 v[154:157], v101 offset:55360
	ds_read_b128 v[158:161], v101 offset:59968
	s_waitcnt lgkmcnt(7)
	v_mfma_f32_32x32x16_bf16 v[16:31], v[114:117], v[162:165], v[16:31]
	s_waitcnt lgkmcnt(6)
	v_mfma_f32_32x32x16_bf16 v[48:63], v[114:117], v[166:169], v[48:63]
	v_mfma_f32_32x32x16_bf16 v[0:15], v[118:121], v[162:165], v[0:15]
	v_mfma_f32_32x32x16_bf16 v[32:47], v[118:121], v[166:169], v[32:47]
	global_load_dwordx4 v[114:117], v[80:81], off offset:896
	global_load_dwordx4 v[118:121], v[84:85], off offset:896
	s_waitcnt vmcnt(9)
	ds_write_b128 v100, v[130:133] offset:9216
	s_waitcnt vmcnt(8)
	ds_write_b128 v100, v[134:137] offset:27648
	ds_read_b128 v[130:133], v104 offset:36960
	ds_read_b128 v[134:137], v104 offset:41568
	ds_read_b128 v[162:165], v101 offset:55392
	ds_read_b128 v[166:169], v101 offset:60000
	s_waitcnt lgkmcnt(7)
	v_mfma_f32_32x32x16_bf16 v[16:31], v[122:125], v[154:157], v[16:31]
	s_waitcnt lgkmcnt(6)
	v_mfma_f32_32x32x16_bf16 v[48:63], v[122:125], v[158:161], v[48:63]
	v_mfma_f32_32x32x16_bf16 v[0:15], v[126:129], v[154:157], v[0:15]
	v_mfma_f32_32x32x16_bf16 v[32:47], v[126:129], v[158:161], v[32:47]
	global_load_dwordx4 v[122:125], v[88:89], off offset:896
	global_load_dwordx4 v[126:129], v[92:93], off offset:896
	s_waitcnt vmcnt(9)
	ds_write_b128 v100, v[146:149] offset:13824
	s_waitcnt vmcnt(8)
	ds_write_b128 v100, v[150:153] offset:32256
	s_waitcnt lgkmcnt(3)
	v_mfma_f32_32x32x16_bf16 v[16:31], v[130:133], v[162:165], v[16:31]
	s_waitcnt lgkmcnt(2)
	v_mfma_f32_32x32x16_bf16 v[48:63], v[130:133], v[166:169], v[48:63]
	v_mfma_f32_32x32x16_bf16 v[0:15], v[134:137], v[162:165], v[0:15]
	v_mfma_f32_32x32x16_bf16 v[32:47], v[134:137], v[166:169], v[32:47]
	s_waitcnt lgkmcnt(0)
	s_barrier
	global_load_dwordx4 v[130:133], v[64:65], off offset:1024
	global_load_dwordx4 v[134:137], v[106:107], off offset:1024
	ds_read_b128 v[146:149], v104
	ds_read_b128 v[150:153], v104 offset:4608
	ds_read_b128 v[154:157], v101 offset:18432
	ds_read_b128 v[158:161], v101 offset:23040
	s_waitcnt vmcnt(9)
	ds_write_b128 v100, v[66:69] offset:36864
	s_waitcnt vmcnt(8)
	ds_write_b128 v100, v[110:113] offset:55296
	ds_read_b128 v[66:69], v104 offset:32
	ds_read_b128 v[110:113], v104 offset:4640
	ds_read_b128 v[162:165], v101 offset:18464
	ds_read_b128 v[166:169], v101 offset:23072
	s_waitcnt lgkmcnt(7)
	v_mfma_f32_32x32x16_bf16 v[16:31], v[146:149], v[154:157], v[16:31]
	s_waitcnt lgkmcnt(6)
	v_mfma_f32_32x32x16_bf16 v[48:63], v[146:149], v[158:161], v[48:63]
	v_mfma_f32_32x32x16_bf16 v[0:15], v[150:153], v[154:157], v[0:15]
	v_mfma_f32_32x32x16_bf16 v[32:47], v[150:153], v[158:161], v[32:47]
	global_load_dwordx4 v[146:149], v[72:73], off offset:1024
	global_load_dwordx4 v[150:153], v[76:77], off offset:1024
	s_waitcnt vmcnt(9)
	ds_write_b128 v100, v[138:141] offset:41472
	s_waitcnt vmcnt(8)
	ds_write_b128 v100, v[142:145] offset:59904
	ds_read_b128 v[138:141], v104 offset:64
	ds_read_b128 v[142:145], v104 offset:4672
	ds_read_b128 v[154:157], v101 offset:18496
	ds_read_b128 v[158:161], v101 offset:23104
	s_waitcnt lgkmcnt(7)
	v_mfma_f32_32x32x16_bf16 v[16:31], v[66:69], v[162:165], v[16:31]
	s_waitcnt lgkmcnt(6)
	v_mfma_f32_32x32x16_bf16 v[48:63], v[66:69], v[166:169], v[48:63]
	v_mfma_f32_32x32x16_bf16 v[0:15], v[110:113], v[162:165], v[0:15]
	v_mfma_f32_32x32x16_bf16 v[32:47], v[110:113], v[166:169], v[32:47]
	global_load_dwordx4 v[66:69], v[80:81], off offset:1024
	global_load_dwordx4 v[110:113], v[84:85], off offset:1024
	s_waitcnt vmcnt(9)
	ds_write_b128 v100, v[114:117] offset:46080
	s_waitcnt vmcnt(8)
	ds_write_b128 v100, v[118:121] offset:64512
	ds_read_b128 v[114:117], v104 offset:96
	ds_read_b128 v[118:121], v104 offset:4704
	ds_read_b128 v[162:165], v101 offset:18528
	ds_read_b128 v[166:169], v101 offset:23136
	s_waitcnt lgkmcnt(7)
	v_mfma_f32_32x32x16_bf16 v[16:31], v[138:141], v[154:157], v[16:31]
	s_waitcnt lgkmcnt(6)
	v_mfma_f32_32x32x16_bf16 v[48:63], v[138:141], v[158:161], v[48:63]
	v_mfma_f32_32x32x16_bf16 v[0:15], v[142:145], v[154:157], v[0:15]
	v_mfma_f32_32x32x16_bf16 v[32:47], v[142:145], v[158:161], v[32:47]
	global_load_dwordx4 v[138:141], v[88:89], off offset:1024
	global_load_dwordx4 v[142:145], v[92:93], off offset:1024
	s_waitcnt vmcnt(9)
	ds_write_b128 v100, v[122:125] offset:50688
	s_waitcnt vmcnt(8)
	ds_write_b128 v105, v[126:129] offset:13824
	s_waitcnt lgkmcnt(3)
	v_mfma_f32_32x32x16_bf16 v[16:31], v[114:117], v[162:165], v[16:31]
	s_waitcnt lgkmcnt(2)
	v_mfma_f32_32x32x16_bf16 v[48:63], v[114:117], v[166:169], v[48:63]
	v_mfma_f32_32x32x16_bf16 v[0:15], v[118:121], v[162:165], v[0:15]
	v_mfma_f32_32x32x16_bf16 v[32:47], v[118:121], v[166:169], v[32:47]
	s_waitcnt lgkmcnt(0)
	s_barrier
; __device__ __forceinline__ void gemm_run(int tid, f32x16 (&acc)[2][2], GRegs& g, const GOp& o, int K, unsigned char* smem) {
;     ...
;   for (int k = 0; k < nk; k++) {
;     bf16r* cur = sbuf + (k & 1) * (256 * LDK);
;     bf16r* nxt = sbuf + ((k & 1) ^ 1) * (256 * LDK);
;     const bf16r* As = cur + (wm * 64 + fr) * LDK + fh * 8;
;     const bf16r* Bs = cur + 128 * LDK + (wn * 64 + fr) * LDK + fh * 8;
;     const bool wr = (k + 1 < nk), ld = (k + 2 < nk);
;     bf16x8 fa[2][2], fb[2][2];
;     fa[0][0] = *(const bf16x8*)(As);
;     fa[0][1] = *(const bf16x8*)(As + 32 * LDK);
;     fb[0][0] = *(const bf16x8*)(Bs);
;     fb[0][1] = *(const bf16x8*)(Bs + 32 * LDK);
; #pragma unroll
;     for (int i = 0; i < 4; i++) {
;       if (wr) {
;         *(u32x4*)(nxt + (r0 + i * 32) * LDK + sg * 8) = g.a[i];
;         *(u32x4*)(nxt + 128 * LDK + (r0 + i * 32) * LDK + sg * 8) = g.b[i];
;       }
;       if (ld) {
;         g.a[i] = *(const u32x4*)(Ap + (size_t)i * 32 * o.lda + (k + 2) * 64);
;         g.b[i] = *(const u32x4*)(Bp + o.bs.o[i] + (k + 2) * 64);
;       }
;       if (i < 3) {
;         fa[(i + 1) & 1][0] = *(const bf16x8*)(As + (i + 1) * 16);
;         fa[(i + 1) & 1][1] = *(const bf16x8*)(As + 32 * LDK + (i + 1) * 16);
;         fb[(i + 1) & 1][0] = *(const bf16x8*)(Bs + (i + 1) * 16);
;         fb[(i + 1) & 1][1] = *(const bf16x8*)(Bs + 32 * LDK + (i + 1) * 16);
;       }
;       __builtin_amdgcn_sched_barrier(0);
;       __builtin_amdgcn_s_setprio(1);
;       acc[0][0] = __builtin_amdgcn_mfma_f32_32x32x16_bf16(fa[i & 1][0], fb[i & 1][0], acc[0][0], 0, 0, 0);
;       acc[0][1] = __builtin_amdgcn_mfma_f32_32x32x16_bf16(fa[i & 1][0], fb[i & 1][1], acc[0][1], 0, 0, 0);
;       acc[1][0] = __builtin_amdgcn_mfma_f32_32x32x16_bf16(fa[i & 1][1], fb[i & 1][0], acc[1][0], 0, 0, 0);
;       acc[1][1] = __builtin_amdgcn_mfma_f32_32x32x16_bf16(fa[i & 1][1], fb[i & 1][1], acc[1][1], 0, 0, 0);
;       __builtin_amdgcn_s_setprio(0);
;     }
	global_load_dwordx4 v[114:117], v[64:65], off offset:1152
	global_load_dwordx4 v[118:121], v[106:107], off offset:1152
	ds_read_b128 v[122:125], v104 offset:36864
	ds_read_b128 v[126:129], v104 offset:41472
	ds_read_b128 v[154:157], v101 offset:55296
	ds_read_b128 v[158:161], v101 offset:59904
	s_waitcnt vmcnt(9)
	ds_write_b128 v100, v[130:133]
	s_waitcnt vmcnt(8)
	ds_write_b128 v100, v[134:137] offset:18432
	ds_read_b128 v[130:133], v104 offset:36896
	ds_read_b128 v[134:137], v104 offset:41504
	ds_read_b128 v[162:165], v101 offset:55328
	ds_read_b128 v[166:169], v101 offset:59936
	s_waitcnt lgkmcnt(7)
	v_mfma_f32_32x32x16_bf16 v[16:31], v[122:125], v[154:157], v[16:31]
	s_waitcnt lgkmcnt(6)
	v_mfma_f32_32x32x16_bf16 v[48:63], v[122:125], v[158:161], v[48:63]
	v_mfma_f32_32x32x16_bf16 v[0:15], v[126:129], v[154:157], v[0:15]
	v_mfma_f32_32x32x16_bf16 v[32:47], v[126:129], v[158:161], v[32:47]
	global_load_dwordx4 v[122:125], v[72:73], off offset:1152
	global_load_dwordx4 v[126:129], v[76:77], off offset:1152
	s_waitcnt vmcnt(9)
	ds_write_b128 v100, v[146:149] offset:4608
	s_waitcnt vmcnt(8)
	ds_write_b128 v100, v[150:153] offset:23040
	ds_read_b128 v[146:149], v104 offset:36928
	ds_read_b128 v[150:153], v104 offset:41536
	ds_read_b128 v[154:157], v101 offset:55360
	ds_read_b128 v[158:161], v101 offset:59968
	s_waitcnt lgkmcnt(7)
	v_mfma_f32_32x32x16_bf16 v[16:31], v[130:133], v[162:165], v[16:31]
	s_waitcnt lgkmcnt(6)
	v_mfma_f32_32x32x16_bf16 v[48:63], v[130:133], v[166:169], v[48:63]
	v_mfma_f32_32x32x16_bf16 v[0:15], v[134:137], v[162:165], v[0:15]
	v_mfma_f32_32x32x16_bf16 v[32:47], v[134:137], v[166:169], v[32:47]
	global_load_dwordx4 v[130:133], v[80:81], off offset:1152
	global_load_dwordx4 v[134:137], v[84:85], off offset:1152
	s_waitcnt vmcnt(9)
	ds_write_b128 v100, v[66:69] offset:9216
	s_waitcnt vmcnt(8)
	ds_write_b128 v100, v[110:113] offset:27648
	ds_read_b128 v[66:69], v104 offset:36960
	ds_read_b128 v[110:113], v104 offset:41568
	ds_read_b128 v[162:165], v101 offset:55392
	ds_read_b128 v[166:169], v101 offset:60000
	s_waitcnt lgkmcnt(7)
	v_mfma_f32_32x32x16_bf16 v[16:31], v[146:149], v[154:157], v[16:31]
	s_waitcnt lgkmcnt(6)
	v_mfma_f32_32x32x16_bf16 v[48:63], v[146:149], v[158:161], v[48:63]
	v_mfma_f32_32x32x16_bf16 v[0:15], v[150:153], v[154:157], v[0:15]
	v_mfma_f32_32x32x16_bf16 v[32:47], v[150:153], v[158:161], v[32:47]
	global_load_dwordx4 v[146:149], v[88:89], off offset:1152
	global_load_dwordx4 v[150:153], v[92:93], off offset:1152
	s_waitcnt vmcnt(9)
	ds_write_b128 v100, v[138:141] offset:13824
	s_waitcnt vmcnt(8)
	ds_write_b128 v100, v[142:145] offset:32256
	s_waitcnt lgkmcnt(3)
	v_mfma_f32_32x32x16_bf16 v[16:31], v[66:69], v[162:165], v[16:31]
	s_waitcnt lgkmcnt(2)
	v_mfma_f32_32x32x16_bf16 v[48:63], v[66:69], v[166:169], v[48:63]
	v_mfma_f32_32x32x16_bf16 v[0:15], v[110:113], v[162:165], v[0:15]
	v_mfma_f32_32x32x16_bf16 v[32:47], v[110:113], v[166:169], v[32:47]
	s_waitcnt lgkmcnt(0)
	s_barrier
	global_load_dwordx4 v[66:69], v[64:65], off offset:1280
	global_load_dwordx4 v[110:113], v[106:107], off offset:1280
	ds_read_b128 v[138:141], v104
	ds_read_b128 v[142:145], v104 offset:4608
	ds_read_b128 v[154:157], v101 offset:18432
	ds_read_b128 v[158:161], v101 offset:23040
	s_waitcnt vmcnt(9)
	ds_write_b128 v100, v[114:117] offset:36864
	s_waitcnt vmcnt(8)
	ds_write_b128 v100, v[118:121] offset:55296
	ds_read_b128 v[114:117], v104 offset:32
	ds_read_b128 v[118:121], v104 offset:4640
	ds_read_b128 v[162:165], v101 offset:18464
	ds_read_b128 v[166:169], v101 offset:23072
	s_waitcnt lgkmcnt(7)
	v_mfma_f32_32x32x16_bf16 v[16:31], v[138:141], v[154:157], v[16:31]
	s_waitcnt lgkmcnt(6)
	v_mfma_f32_32x32x16_bf16 v[48:63], v[138:141], v[158:161], v[48:63]
	v_mfma_f32_32x32x16_bf16 v[0:15], v[142:145], v[154:157], v[0:15]
	v_mfma_f32_32x32x16_bf16 v[32:47], v[142:145], v[158:161], v[32:47]
	global_load_dwordx4 v[138:141], v[72:73], off offset:1280
	global_load_dwordx4 v[142:145], v[76:77], off offset:1280
	s_waitcnt vmcnt(9)
	ds_write_b128 v100, v[122:125] offset:41472
	s_waitcnt vmcnt(8)
	ds_write_b128 v100, v[126:129] offset:59904
	ds_read_b128 v[122:125], v104 offset:64
	ds_read_b128 v[126:129], v104 offset:4672
	ds_read_b128 v[154:157], v101 offset:18496
	ds_read_b128 v[158:161], v101 offset:23104
	s_waitcnt lgkmcnt(7)
	v_mfma_f32_32x32x16_bf16 v[16:31], v[114:117], v[162:165], v[16:31]
	s_waitcnt lgkmcnt(6)
	v_mfma_f32_32x32x16_bf16 v[48:63], v[114:117], v[166:169], v[48:63]
	v_mfma_f32_32x32x16_bf16 v[0:15], v[118:121], v[162:165], v[0:15]
	v_mfma_f32_32x32x16_bf16 v[32:47], v[118:121], v[166:169], v[32:47]
	global_load_dwordx4 v[114:117], v[80:81], off offset:1280
	global_load_dwordx4 v[118:121], v[84:85], off offset:1280
	s_waitcnt vmcnt(9)
	ds_write_b128 v100, v[130:133] offset:46080
	s_waitcnt vmcnt(8)
	ds_write_b128 v100, v[134:137] offset:64512
	ds_read_b128 v[130:133], v104 offset:96
	ds_read_b128 v[134:137], v104 offset:4704
	ds_read_b128 v[162:165], v101 offset:18528
	ds_read_b128 v[166:169], v101 offset:23136
	s_waitcnt lgkmcnt(7)
	v_mfma_f32_32x32x16_bf16 v[16:31], v[122:125], v[154:157], v[16:31]
	s_waitcnt lgkmcnt(6)
	v_mfma_f32_32x32x16_bf16 v[48:63], v[122:125], v[158:161], v[48:63]
	v_mfma_f32_32x32x16_bf16 v[0:15], v[126:129], v[154:157], v[0:15]
	v_mfma_f32_32x32x16_bf16 v[32:47], v[126:129], v[158:161], v[32:47]
	global_load_dwordx4 v[122:125], v[88:89], off offset:1280
	global_load_dwordx4 v[126:129], v[92:93], off offset:1280
	s_waitcnt vmcnt(9)
	ds_write_b128 v100, v[146:149] offset:50688
	s_waitcnt vmcnt(8)
	ds_write_b128 v105, v[150:153] offset:13824
	s_waitcnt lgkmcnt(3)
	v_mfma_f32_32x32x16_bf16 v[16:31], v[130:133], v[162:165], v[16:31]
	s_waitcnt lgkmcnt(2)
	v_mfma_f32_32x32x16_bf16 v[48:63], v[130:133], v[166:169], v[48:63]
	v_mfma_f32_32x32x16_bf16 v[0:15], v[134:137], v[162:165], v[0:15]
	v_mfma_f32_32x32x16_bf16 v[32:47], v[134:137], v[166:169], v[32:47]
	s_waitcnt lgkmcnt(0)
	s_barrier
; __device__ __forceinline__ void gemm_run(int tid, f32x16 (&acc)[2][2], GRegs& g, const GOp& o, int K, unsigned char* smem) {
;     ...
;   for (int k = 0; k < nk; k++) {
;     bf16r* cur = sbuf + (k & 1) * (256 * LDK);
;     bf16r* nxt = sbuf + ((k & 1) ^ 1) * (256 * LDK);
;     const bf16r* As = cur + (wm * 64 + fr) * LDK + fh * 8;
;     const bf16r* Bs = cur + 128 * LDK + (wn * 64 + fr) * LDK + fh * 8;
;     const bool wr = (k + 1 < nk), ld = (k + 2 < nk);
;     bf16x8 fa[2][2], fb[2][2];
;     fa[0][0] = *(const bf16x8*)(As);
;     fa[0][1] = *(const bf16x8*)(As + 32 * LDK);
;     fb[0][0] = *(const bf16x8*)(Bs);
;     fb[0][1] = *(const bf16x8*)(Bs + 32 * LDK);
; #pragma unroll
;     for (int i = 0; i < 4; i++) {
;       if (wr) {
;         *(u32x4*)(nxt + (r0 + i * 32) * LDK + sg * 8) = g.a[i];
;         *(u32x4*)(nxt + 128 * LDK + (r0 + i * 32) * LDK + sg * 8) = g.b[i];
;       }
;       if (ld) {
;         g.a[i] = *(const u32x4*)(Ap + (size_t)i * 32 * o.lda + (k + 2) * 64);
;         g.b[i] = *(const u32x4*)(Bp + o.bs.o[i] + (k + 2) * 64);
;       }
;       if (i < 3) {
;         fa[(i + 1) & 1][0] = *(const bf16x8*)(As + (i + 1) * 16);
;         fa[(i + 1) & 1][1] = *(const bf16x8*)(As + 32 * LDK + (i + 1) * 16);
;         fb[(i + 1) & 1][0] = *(const bf16x8*)(Bs + (i + 1) * 16);
;         fb[(i + 1) & 1][1] = *(const bf16x8*)(Bs + 32 * LDK + (i + 1) * 16);
;       }
;       __builtin_amdgcn_sched_barrier(0);
;       __builtin_amdgcn_s_setprio(1);
;       acc[0][0] = __builtin_amdgcn_mfma_f32_32x32x16_bf16(fa[i & 1][0], fb[i & 1][0], acc[0][0], 0, 0, 0);
;       acc[0][1] = __builtin_amdgcn_mfma_f32_32x32x16_bf16(fa[i & 1][0], fb[i & 1][1], acc[0][1], 0, 0, 0);
;       acc[1][0] = __builtin_amdgcn_mfma_f32_32x32x16_bf16(fa[i & 1][1], fb[i & 1][0], acc[1][0], 0, 0, 0);
;       acc[1][1] = __builtin_amdgcn_mfma_f32_32x32x16_bf16(fa[i & 1][1], fb[i & 1][1], acc[1][1], 0, 0, 0);
;       __builtin_amdgcn_s_setprio(0);
;     }
	global_load_dwordx4 v[130:133], v[64:65], off offset:1408
	global_load_dwordx4 v[134:137], v[106:107], off offset:1408
	ds_read_b128 v[146:149], v104 offset:36864
	ds_read_b128 v[150:153], v104 offset:41472
	ds_read_b128 v[154:157], v101 offset:55296
	ds_read_b128 v[158:161], v101 offset:59904
	s_waitcnt vmcnt(9)
	ds_write_b128 v100, v[66:69]
	s_waitcnt vmcnt(8)
	ds_write_b128 v100, v[110:113] offset:18432
	ds_read_b128 v[66:69], v104 offset:36896
	ds_read_b128 v[110:113], v104 offset:41504
	ds_read_b128 v[162:165], v101 offset:55328
	ds_read_b128 v[166:169], v101 offset:59936
	s_waitcnt lgkmcnt(7)
	v_mfma_f32_32x32x16_bf16 v[16:31], v[146:149], v[154:157], v[16:31]
	s_waitcnt lgkmcnt(6)
	v_mfma_f32_32x32x16_bf16 v[48:63], v[146:149], v[158:161], v[48:63]
	v_mfma_f32_32x32x16_bf16 v[0:15], v[150:153], v[154:157], v[0:15]
	v_mfma_f32_32x32x16_bf16 v[32:47], v[150:153], v[158:161], v[32:47]
	global_load_dwordx4 v[146:149], v[72:73], off offset:1408
	global_load_dwordx4 v[150:153], v[76:77], off offset:1408
	s_waitcnt vmcnt(9)
	ds_write_b128 v100, v[138:141] offset:4608
	s_waitcnt vmcnt(8)
	ds_write_b128 v100, v[142:145] offset:23040
	ds_read_b128 v[138:141], v104 offset:36928
	ds_read_b128 v[142:145], v104 offset:41536
	ds_read_b128 v[154:157], v101 offset:55360
	ds_read_b128 v[158:161], v101 offset:59968
	s_waitcnt lgkmcnt(7)
	v_mfma_f32_32x32x16_bf16 v[16:31], v[66:69], v[162:165], v[16:31]
	s_waitcnt lgkmcnt(6)
	v_mfma_f32_32x32x16_bf16 v[48:63], v[66:69], v[166:169], v[48:63]
	v_mfma_f32_32x32x16_bf16 v[0:15], v[110:113], v[162:165], v[0:15]
	v_mfma_f32_32x32x16_bf16 v[32:47], v[110:113], v[166:169], v[32:47]
	global_load_dwordx4 v[66:69], v[80:81], off offset:1408
	global_load_dwordx4 v[110:113], v[84:85], off offset:1408
	s_waitcnt vmcnt(9)
	ds_write_b128 v100, v[114:117] offset:9216
	s_waitcnt vmcnt(8)
	ds_write_b128 v100, v[118:121] offset:27648
	ds_read_b128 v[114:117], v104 offset:36960
	ds_read_b128 v[118:121], v104 offset:41568
	ds_read_b128 v[162:165], v101 offset:55392
	ds_read_b128 v[166:169], v101 offset:60000
	s_waitcnt lgkmcnt(7)
	v_mfma_f32_32x32x16_bf16 v[16:31], v[138:141], v[154:157], v[16:31]
	s_waitcnt lgkmcnt(6)
	v_mfma_f32_32x32x16_bf16 v[48:63], v[138:141], v[158:161], v[48:63]
	v_mfma_f32_32x32x16_bf16 v[0:15], v[142:145], v[154:157], v[0:15]
	v_mfma_f32_32x32x16_bf16 v[32:47], v[142:145], v[158:161], v[32:47]
	global_load_dwordx4 v[138:141], v[88:89], off offset:1408
	global_load_dwordx4 v[142:145], v[92:93], off offset:1408
	s_waitcnt vmcnt(9)
	ds_write_b128 v100, v[122:125] offset:13824
	s_waitcnt vmcnt(8)
	ds_write_b128 v100, v[126:129] offset:32256
	s_waitcnt lgkmcnt(3)
	v_mfma_f32_32x32x16_bf16 v[16:31], v[114:117], v[162:165], v[16:31]
	s_waitcnt lgkmcnt(2)
	v_mfma_f32_32x32x16_bf16 v[48:63], v[114:117], v[166:169], v[48:63]
	v_mfma_f32_32x32x16_bf16 v[0:15], v[118:121], v[162:165], v[0:15]
	v_mfma_f32_32x32x16_bf16 v[32:47], v[118:121], v[166:169], v[32:47]
	s_waitcnt lgkmcnt(0)
	s_barrier
	global_load_dwordx4 v[114:117], v[64:65], off offset:1536
	global_load_dwordx4 v[118:121], v[106:107], off offset:1536
	ds_read_b128 v[122:125], v104
	ds_read_b128 v[126:129], v104 offset:4608
	ds_read_b128 v[154:157], v101 offset:18432
	ds_read_b128 v[158:161], v101 offset:23040
	s_waitcnt vmcnt(9)
	ds_write_b128 v100, v[130:133] offset:36864
	s_waitcnt vmcnt(8)
	ds_write_b128 v100, v[134:137] offset:55296
	ds_read_b128 v[130:133], v104 offset:32
	ds_read_b128 v[134:137], v104 offset:4640
	ds_read_b128 v[162:165], v101 offset:18464
	ds_read_b128 v[166:169], v101 offset:23072
	s_waitcnt lgkmcnt(7)
	v_mfma_f32_32x32x16_bf16 v[16:31], v[122:125], v[154:157], v[16:31]
	s_waitcnt lgkmcnt(6)
	v_mfma_f32_32x32x16_bf16 v[48:63], v[122:125], v[158:161], v[48:63]
	v_mfma_f32_32x32x16_bf16 v[0:15], v[126:129], v[154:157], v[0:15]
	v_mfma_f32_32x32x16_bf16 v[32:47], v[126:129], v[158:161], v[32:47]
	global_load_dwordx4 v[122:125], v[72:73], off offset:1536
	global_load_dwordx4 v[126:129], v[76:77], off offset:1536
	s_waitcnt vmcnt(9)
	ds_write_b128 v100, v[146:149] offset:41472
	s_waitcnt vmcnt(8)
	ds_write_b128 v100, v[150:153] offset:59904
	ds_read_b128 v[146:149], v104 offset:64
	ds_read_b128 v[150:153], v104 offset:4672
	ds_read_b128 v[154:157], v101 offset:18496
	ds_read_b128 v[158:161], v101 offset:23104
	s_waitcnt lgkmcnt(7)
	v_mfma_f32_32x32x16_bf16 v[16:31], v[130:133], v[162:165], v[16:31]
	s_waitcnt lgkmcnt(6)
	v_mfma_f32_32x32x16_bf16 v[48:63], v[130:133], v[166:169], v[48:63]
	v_mfma_f32_32x32x16_bf16 v[0:15], v[134:137], v[162:165], v[0:15]
	v_mfma_f32_32x32x16_bf16 v[32:47], v[134:137], v[166:169], v[32:47]
	global_load_dwordx4 v[130:133], v[80:81], off offset:1536
	global_load_dwordx4 v[134:137], v[84:85], off offset:1536
	s_waitcnt vmcnt(9)
	ds_write_b128 v100, v[66:69] offset:46080
	s_waitcnt vmcnt(8)
	ds_write_b128 v100, v[110:113] offset:64512
	ds_read_b128 v[66:69], v104 offset:96
	ds_read_b128 v[110:113], v104 offset:4704
	ds_read_b128 v[162:165], v101 offset:18528
	ds_read_b128 v[166:169], v101 offset:23136
	s_waitcnt lgkmcnt(7)
	v_mfma_f32_32x32x16_bf16 v[16:31], v[146:149], v[154:157], v[16:31]
	s_waitcnt lgkmcnt(6)
	v_mfma_f32_32x32x16_bf16 v[48:63], v[146:149], v[158:161], v[48:63]
	v_mfma_f32_32x32x16_bf16 v[0:15], v[150:153], v[154:157], v[0:15]
	v_mfma_f32_32x32x16_bf16 v[32:47], v[150:153], v[158:161], v[32:47]
	global_load_dwordx4 v[146:149], v[88:89], off offset:1536
	global_load_dwordx4 v[150:153], v[92:93], off offset:1536
	s_waitcnt vmcnt(9)
	ds_write_b128 v100, v[138:141] offset:50688
	s_waitcnt vmcnt(8)
	ds_write_b128 v105, v[142:145] offset:13824
	s_waitcnt lgkmcnt(3)
	v_mfma_f32_32x32x16_bf16 v[16:31], v[66:69], v[162:165], v[16:31]
	s_waitcnt lgkmcnt(2)
	v_mfma_f32_32x32x16_bf16 v[48:63], v[66:69], v[166:169], v[48:63]
	v_mfma_f32_32x32x16_bf16 v[0:15], v[110:113], v[162:165], v[0:15]
	v_mfma_f32_32x32x16_bf16 v[32:47], v[110:113], v[166:169], v[32:47]
	s_waitcnt lgkmcnt(0)
	s_barrier
; __device__ __forceinline__ void gemm_run(int tid, f32x16 (&acc)[2][2], GRegs& g, const GOp& o, int K, unsigned char* smem) {
;     ...
;   for (int k = 0; k < nk; k++) {
;     bf16r* cur = sbuf + (k & 1) * (256 * LDK);
;     bf16r* nxt = sbuf + ((k & 1) ^ 1) * (256 * LDK);
;     const bf16r* As = cur + (wm * 64 + fr) * LDK + fh * 8;
;     const bf16r* Bs = cur + 128 * LDK + (wn * 64 + fr) * LDK + fh * 8;
;     const bool wr = (k + 1 < nk), ld = (k + 2 < nk);
;     bf16x8 fa[2][2], fb[2][2];
;     fa[0][0] = *(const bf16x8*)(As);
;     fa[0][1] = *(const bf16x8*)(As + 32 * LDK);
;     fb[0][0] = *(const bf16x8*)(Bs);
;     fb[0][1] = *(const bf16x8*)(Bs + 32 * LDK);
; #pragma unroll
;     for (int i = 0; i < 4; i++) {
;       if (wr) {
;         *(u32x4*)(nxt + (r0 + i * 32) * LDK + sg * 8) = g.a[i];
;         *(u32x4*)(nxt + 128 * LDK + (r0 + i * 32) * LDK + sg * 8) = g.b[i];
;       }
;       if (ld) {
;         g.a[i] = *(const u32x4*)(Ap + (size_t)i * 32 * o.lda + (k + 2) * 64);
;         g.b[i] = *(const u32x4*)(Bp + o.bs.o[i] + (k + 2) * 64);
;       }
;       if (i < 3) {
;         fa[(i + 1) & 1][0] = *(const bf16x8*)(As + (i + 1) * 16);
;         fa[(i + 1) & 1][1] = *(const bf16x8*)(As + 32 * LDK + (i + 1) * 16);
;         fb[(i + 1) & 1][0] = *(const bf16x8*)(Bs + (i + 1) * 16);
;         fb[(i + 1) & 1][1] = *(const bf16x8*)(Bs + 32 * LDK + (i + 1) * 16);
;       }
;       __builtin_amdgcn_sched_barrier(0);
;       __builtin_amdgcn_s_setprio(1);
;       acc[0][0] = __builtin_amdgcn_mfma_f32_32x32x16_bf16(fa[i & 1][0], fb[i & 1][0], acc[0][0], 0, 0, 0);
;       acc[0][1] = __builtin_amdgcn_mfma_f32_32x32x16_bf16(fa[i & 1][0], fb[i & 1][1], acc[0][1], 0, 0, 0);
;       acc[1][0] = __builtin_amdgcn_mfma_f32_32x32x16_bf16(fa[i & 1][1], fb[i & 1][0], acc[1][0], 0, 0, 0);
;       acc[1][1] = __builtin_amdgcn_mfma_f32_32x32x16_bf16(fa[i & 1][1], fb[i & 1][1], acc[1][1], 0, 0, 0);
;       __builtin_amdgcn_s_setprio(0);
;     }
	global_load_dwordx4 v[66:69], v[64:65], off offset:1664
	global_load_dwordx4 v[110:113], v[106:107], off offset:1664
	ds_read_b128 v[138:141], v104 offset:36864
	ds_read_b128 v[142:145], v104 offset:41472
	ds_read_b128 v[154:157], v101 offset:55296
	ds_read_b128 v[158:161], v101 offset:59904
	s_waitcnt vmcnt(9)
	ds_write_b128 v100, v[114:117]
	s_waitcnt vmcnt(8)
	ds_write_b128 v100, v[118:121] offset:18432
	ds_read_b128 v[114:117], v104 offset:36896
	ds_read_b128 v[118:121], v104 offset:41504
	ds_read_b128 v[162:165], v101 offset:55328
	ds_read_b128 v[166:169], v101 offset:59936
	s_waitcnt lgkmcnt(7)
	v_mfma_f32_32x32x16_bf16 v[16:31], v[138:141], v[154:157], v[16:31]
	s_waitcnt lgkmcnt(6)
	v_mfma_f32_32x32x16_bf16 v[48:63], v[138:141], v[158:161], v[48:63]
	v_mfma_f32_32x32x16_bf16 v[0:15], v[142:145], v[154:157], v[0:15]
	v_mfma_f32_32x32x16_bf16 v[32:47], v[142:145], v[158:161], v[32:47]
	global_load_dwordx4 v[138:141], v[72:73], off offset:1664
	global_load_dwordx4 v[142:145], v[76:77], off offset:1664
	s_waitcnt vmcnt(9)
	ds_write_b128 v100, v[122:125] offset:4608
	s_waitcnt vmcnt(8)
	ds_write_b128 v100, v[126:129] offset:23040
	ds_read_b128 v[122:125], v104 offset:36928
	ds_read_b128 v[126:129], v104 offset:41536
	ds_read_b128 v[154:157], v101 offset:55360
	ds_read_b128 v[158:161], v101 offset:59968
	s_waitcnt lgkmcnt(7)
	v_mfma_f32_32x32x16_bf16 v[16:31], v[114:117], v[162:165], v[16:31]
	s_waitcnt lgkmcnt(6)
	v_mfma_f32_32x32x16_bf16 v[48:63], v[114:117], v[166:169], v[48:63]
	v_mfma_f32_32x32x16_bf16 v[0:15], v[118:121], v[162:165], v[0:15]
	v_mfma_f32_32x32x16_bf16 v[32:47], v[118:121], v[166:169], v[32:47]
	global_load_dwordx4 v[114:117], v[80:81], off offset:1664
	global_load_dwordx4 v[118:121], v[84:85], off offset:1664
	s_waitcnt vmcnt(9)
	ds_write_b128 v100, v[130:133] offset:9216
	s_waitcnt vmcnt(8)
	ds_write_b128 v100, v[134:137] offset:27648
	ds_read_b128 v[130:133], v104 offset:36960
	ds_read_b128 v[134:137], v104 offset:41568
	ds_read_b128 v[162:165], v101 offset:55392
	ds_read_b128 v[166:169], v101 offset:60000
	s_waitcnt lgkmcnt(7)
	v_mfma_f32_32x32x16_bf16 v[16:31], v[122:125], v[154:157], v[16:31]
	s_waitcnt lgkmcnt(6)
	v_mfma_f32_32x32x16_bf16 v[48:63], v[122:125], v[158:161], v[48:63]
	v_mfma_f32_32x32x16_bf16 v[0:15], v[126:129], v[154:157], v[0:15]
	v_mfma_f32_32x32x16_bf16 v[32:47], v[126:129], v[158:161], v[32:47]
	global_load_dwordx4 v[122:125], v[88:89], off offset:1664
	global_load_dwordx4 v[126:129], v[92:93], off offset:1664
	s_waitcnt vmcnt(9)
	ds_write_b128 v100, v[146:149] offset:13824
	s_waitcnt vmcnt(8)
	ds_write_b128 v100, v[150:153] offset:32256
	s_waitcnt lgkmcnt(3)
	v_mfma_f32_32x32x16_bf16 v[16:31], v[130:133], v[162:165], v[16:31]
	s_waitcnt lgkmcnt(2)
	v_mfma_f32_32x32x16_bf16 v[48:63], v[130:133], v[166:169], v[48:63]
	v_mfma_f32_32x32x16_bf16 v[0:15], v[134:137], v[162:165], v[0:15]
	v_mfma_f32_32x32x16_bf16 v[32:47], v[134:137], v[166:169], v[32:47]
	s_waitcnt lgkmcnt(0)
	s_barrier
	global_load_dwordx4 v[130:133], v[64:65], off offset:1792
	global_load_dwordx4 v[134:137], v[106:107], off offset:1792
	ds_read_b128 v[146:149], v104
	ds_read_b128 v[150:153], v104 offset:4608
	ds_read_b128 v[154:157], v101 offset:18432
	ds_read_b128 v[158:161], v101 offset:23040
	s_waitcnt vmcnt(9)
	ds_write_b128 v100, v[66:69] offset:36864
	s_waitcnt vmcnt(8)
	ds_write_b128 v100, v[110:113] offset:55296
	ds_read_b128 v[66:69], v104 offset:32
	ds_read_b128 v[110:113], v104 offset:4640
	ds_read_b128 v[162:165], v101 offset:18464
	ds_read_b128 v[166:169], v101 offset:23072
	s_waitcnt lgkmcnt(7)
	v_mfma_f32_32x32x16_bf16 v[16:31], v[146:149], v[154:157], v[16:31]
	s_waitcnt lgkmcnt(6)
	v_mfma_f32_32x32x16_bf16 v[48:63], v[146:149], v[158:161], v[48:63]
	v_mfma_f32_32x32x16_bf16 v[0:15], v[150:153], v[154:157], v[0:15]
	v_mfma_f32_32x32x16_bf16 v[32:47], v[150:153], v[158:161], v[32:47]
	global_load_dwordx4 v[146:149], v[72:73], off offset:1792
	global_load_dwordx4 v[150:153], v[76:77], off offset:1792
	s_waitcnt vmcnt(9)
	ds_write_b128 v100, v[138:141] offset:41472
	s_waitcnt vmcnt(8)
	ds_write_b128 v100, v[142:145] offset:59904
	ds_read_b128 v[138:141], v104 offset:64
	ds_read_b128 v[142:145], v104 offset:4672
	ds_read_b128 v[154:157], v101 offset:18496
	ds_read_b128 v[158:161], v101 offset:23104
	s_waitcnt lgkmcnt(7)
	v_mfma_f32_32x32x16_bf16 v[16:31], v[66:69], v[162:165], v[16:31]
	s_waitcnt lgkmcnt(6)
	v_mfma_f32_32x32x16_bf16 v[48:63], v[66:69], v[166:169], v[48:63]
	v_mfma_f32_32x32x16_bf16 v[0:15], v[110:113], v[162:165], v[0:15]
	v_mfma_f32_32x32x16_bf16 v[32:47], v[110:113], v[166:169], v[32:47]
	global_load_dwordx4 v[110:113], v[80:81], off offset:1792
	global_load_dwordx4 v[162:165], v[84:85], off offset:1792
	s_waitcnt vmcnt(9)
	ds_write_b128 v100, v[114:117] offset:46080
	s_waitcnt vmcnt(8)
	ds_write_b128 v100, v[118:121] offset:64512
	ds_read_b128 v[66:69], v104 offset:96
	ds_read_b128 v[114:117], v104 offset:4704
	ds_read_b128 v[118:121], v101 offset:18528
	ds_read_b128 v[166:169], v101 offset:23136
	s_waitcnt lgkmcnt(7)
	v_mfma_f32_32x32x16_bf16 v[16:31], v[138:141], v[154:157], v[16:31]
	s_waitcnt lgkmcnt(6)
	v_mfma_f32_32x32x16_bf16 v[48:63], v[138:141], v[158:161], v[48:63]
	v_mfma_f32_32x32x16_bf16 v[0:15], v[142:145], v[154:157], v[0:15]
	v_mfma_f32_32x32x16_bf16 v[32:47], v[142:145], v[158:161], v[32:47]
	global_load_dwordx4 v[138:141], v[88:89], off offset:1792
	global_load_dwordx4 v[142:145], v[92:93], off offset:1792
	s_waitcnt vmcnt(9)
	ds_write_b128 v100, v[122:125] offset:50688
	s_waitcnt vmcnt(8)
	ds_write_b128 v105, v[126:129] offset:13824
	s_waitcnt lgkmcnt(3)
	v_mfma_f32_32x32x16_bf16 v[16:31], v[66:69], v[118:121], v[16:31]
	s_waitcnt lgkmcnt(2)
	v_mfma_f32_32x32x16_bf16 v[48:63], v[66:69], v[166:169], v[48:63]
	v_mfma_f32_32x32x16_bf16 v[0:15], v[114:117], v[118:121], v[0:15]
	v_mfma_f32_32x32x16_bf16 v[32:47], v[114:117], v[166:169], v[32:47]
	s_waitcnt lgkmcnt(0)
	s_barrier
; __device__ __forceinline__ void gemm_run(int tid, f32x16 (&acc)[2][2], GRegs& g, const GOp& o, int K, unsigned char* smem) {
;     ...
;   for (int k = 0; k < nk; k++) {
;     bf16r* cur = sbuf + (k & 1) * (256 * LDK);
;     bf16r* nxt = sbuf + ((k & 1) ^ 1) * (256 * LDK);
;     const bf16r* As = cur + (wm * 64 + fr) * LDK + fh * 8;
;     const bf16r* Bs = cur + 128 * LDK + (wn * 64 + fr) * LDK + fh * 8;
;     const bool wr = (k + 1 < nk), ld = (k + 2 < nk);
;     bf16x8 fa[2][2], fb[2][2];
;     fa[0][0] = *(const bf16x8*)(As);
;     fa[0][1] = *(const bf16x8*)(As + 32 * LDK);
;     fb[0][0] = *(const bf16x8*)(Bs);
;     fb[0][1] = *(const bf16x8*)(Bs + 32 * LDK);
; #pragma unroll
;     for (int i = 0; i < 4; i++) {
;       if (wr) {
;         *(u32x4*)(nxt + (r0 + i * 32) * LDK + sg * 8) = g.a[i];
;         *(u32x4*)(nxt + 128 * LDK + (r0 + i * 32) * LDK + sg * 8) = g.b[i];
;       }
;       if (ld) {
;         g.a[i] = *(const u32x4*)(Ap + (size_t)i * 32 * o.lda + (k + 2) * 64);
;         g.b[i] = *(const u32x4*)(Bp + o.bs.o[i] + (k + 2) * 64);
;       }
;       if (i < 3) {
;         fa[(i + 1) & 1][0] = *(const bf16x8*)(As + (i + 1) * 16);
;         fa[(i + 1) & 1][1] = *(const bf16x8*)(As + 32 * LDK + (i + 1) * 16);
;         fb[(i + 1) & 1][0] = *(const bf16x8*)(Bs + (i + 1) * 16);
;         fb[(i + 1) & 1][1] = *(const bf16x8*)(Bs + 32 * LDK + (i + 1) * 16);
;       }
;       __builtin_amdgcn_sched_barrier(0);
;       __builtin_amdgcn_s_setprio(1);
;       acc[0][0] = __builtin_amdgcn_mfma_f32_32x32x16_bf16(fa[i & 1][0], fb[i & 1][0], acc[0][0], 0, 0, 0);
;       acc[0][1] = __builtin_amdgcn_mfma_f32_32x32x16_bf16(fa[i & 1][0], fb[i & 1][1], acc[0][1], 0, 0, 0);
;       acc[1][0] = __builtin_amdgcn_mfma_f32_32x32x16_bf16(fa[i & 1][1], fb[i & 1][0], acc[1][0], 0, 0, 0);
;       acc[1][1] = __builtin_amdgcn_mfma_f32_32x32x16_bf16(fa[i & 1][1], fb[i & 1][1], acc[1][1], 0, 0, 0);
;       __builtin_amdgcn_s_setprio(0);
;     }
	global_load_dwordx4 v[64:67], v[64:65], off offset:1920
	s_nop 0
	global_load_dwordx4 v[68:71], v[106:107], off offset:1920
	ds_read_b128 v[114:117], v104 offset:36864
	ds_read_b128 v[118:121], v104 offset:41472
	ds_read_b128 v[122:125], v101 offset:55296
	ds_read_b128 v[126:129], v101 offset:59904
	s_waitcnt vmcnt(9)
	ds_write_b128 v100, v[130:133]
	s_waitcnt vmcnt(8)
	ds_write_b128 v100, v[134:137] offset:18432
	ds_read_b128 v[130:133], v104 offset:36896
	ds_read_b128 v[134:137], v104 offset:41504
	ds_read_b128 v[154:157], v101 offset:55328
	ds_read_b128 v[158:161], v101 offset:59936
	s_waitcnt lgkmcnt(7)
	v_mfma_f32_32x32x16_bf16 v[16:31], v[114:117], v[122:125], v[16:31]
	s_waitcnt lgkmcnt(6)
	v_mfma_f32_32x32x16_bf16 v[48:63], v[114:117], v[126:129], v[48:63]
	v_mfma_f32_32x32x16_bf16 v[0:15], v[118:121], v[122:125], v[0:15]
	v_mfma_f32_32x32x16_bf16 v[32:47], v[118:121], v[126:129], v[32:47]
	global_load_dwordx4 v[72:75], v[72:73], off offset:1920
	s_nop 0
	global_load_dwordx4 v[76:79], v[76:77], off offset:1920
	s_waitcnt vmcnt(9)
	ds_write_b128 v100, v[146:149] offset:4608
	s_waitcnt vmcnt(8)
	ds_write_b128 v100, v[150:153] offset:23040
	ds_read_b128 v[114:117], v104 offset:36928
	ds_read_b128 v[118:121], v104 offset:41536
	ds_read_b128 v[122:125], v101 offset:55360
	ds_read_b128 v[126:129], v101 offset:59968
	s_waitcnt lgkmcnt(7)
	v_mfma_f32_32x32x16_bf16 v[16:31], v[130:133], v[154:157], v[16:31]
	s_waitcnt lgkmcnt(6)
	v_mfma_f32_32x32x16_bf16 v[48:63], v[130:133], v[158:161], v[48:63]
	v_mfma_f32_32x32x16_bf16 v[0:15], v[134:137], v[154:157], v[0:15]
	v_mfma_f32_32x32x16_bf16 v[32:47], v[134:137], v[158:161], v[32:47]
	global_load_dwordx4 v[80:83], v[80:81], off offset:1920
	s_nop 0
	global_load_dwordx4 v[84:87], v[84:85], off offset:1920
	s_waitcnt vmcnt(9)
	ds_write_b128 v100, v[110:113] offset:9216
	s_waitcnt vmcnt(8)
	ds_write_b128 v100, v[162:165] offset:27648
	ds_read_b128 v[110:113], v104 offset:36960
	ds_read_b128 v[130:133], v104 offset:41568
	ds_read_b128 v[134:137], v101 offset:55392
	ds_read_b128 v[146:149], v101 offset:60000
	s_waitcnt lgkmcnt(7)
	v_mfma_f32_32x32x16_bf16 v[16:31], v[114:117], v[122:125], v[16:31]
	s_waitcnt lgkmcnt(6)
	v_mfma_f32_32x32x16_bf16 v[48:63], v[114:117], v[126:129], v[48:63]
	v_mfma_f32_32x32x16_bf16 v[0:15], v[118:121], v[122:125], v[0:15]
	v_mfma_f32_32x32x16_bf16 v[32:47], v[118:121], v[126:129], v[32:47]
	global_load_dwordx4 v[88:91], v[88:89], off offset:1920
	s_nop 0
	global_load_dwordx4 v[92:95], v[92:93], off offset:1920
	s_waitcnt vmcnt(9)
	ds_write_b128 v100, v[138:141] offset:13824
	s_waitcnt vmcnt(8)
	ds_write_b128 v100, v[142:145] offset:32256
	s_waitcnt lgkmcnt(3)
	v_mfma_f32_32x32x16_bf16 v[16:31], v[110:113], v[134:137], v[16:31]
	s_waitcnt lgkmcnt(2)
	v_mfma_f32_32x32x16_bf16 v[48:63], v[110:113], v[146:149], v[48:63]
	v_mfma_f32_32x32x16_bf16 v[0:15], v[130:133], v[134:137], v[0:15]
	v_mfma_f32_32x32x16_bf16 v[32:47], v[130:133], v[146:149], v[32:47]
	s_waitcnt lgkmcnt(0)
	s_barrier
; __device__ __forceinline__ void gemm_run(int tid, f32x16 (&acc)[2][2], GRegs& g, const GOp& o, int K, unsigned char* smem) {
;     ...
;   for (int k = 0; k < nk; k++) {
;     bf16r* cur = sbuf + (k & 1) * (256 * LDK);
;     bf16r* nxt = sbuf + ((k & 1) ^ 1) * (256 * LDK);
;     const bf16r* As = cur + (wm * 64 + fr) * LDK + fh * 8;
;     const bf16r* Bs = cur + 128 * LDK + (wn * 64 + fr) * LDK + fh * 8;
;     const bool wr = (k + 1 < nk), ld = (k + 2 < nk);
;     bf16x8 fa[2][2], fb[2][2];
;     fa[0][0] = *(const bf16x8*)(As);
;     fa[0][1] = *(const bf16x8*)(As + 32 * LDK);
;     fb[0][0] = *(const bf16x8*)(Bs);
;     fb[0][1] = *(const bf16x8*)(Bs + 32 * LDK);
; #pragma unroll
;     for (int i = 0; i < 4; i++) {
;       if (wr) {
;         *(u32x4*)(nxt + (r0 + i * 32) * LDK + sg * 8) = g.a[i];
;         *(u32x4*)(nxt + 128 * LDK + (r0 + i * 32) * LDK + sg * 8) = g.b[i];
;       }
;       if (ld) {
;         g.a[i] = *(const u32x4*)(Ap + (size_t)i * 32 * o.lda + (k + 2) * 64);
;         g.b[i] = *(const u32x4*)(Bp + o.bs.o[i] + (k + 2) * 64);
;       }
;       if (i < 3) {
;         fa[(i + 1) & 1][0] = *(const bf16x8*)(As + (i + 1) * 16);
;         fa[(i + 1) & 1][1] = *(const bf16x8*)(As + 32 * LDK + (i + 1) * 16);
;         fb[(i + 1) & 1][0] = *(const bf16x8*)(Bs + (i + 1) * 16);
;         fb[(i + 1) & 1][1] = *(const bf16x8*)(Bs + 32 * LDK + (i + 1) * 16);
;       }
;       __builtin_amdgcn_sched_barrier(0);
;       __builtin_amdgcn_s_setprio(1);
;       acc[0][0] = __builtin_amdgcn_mfma_f32_32x32x16_bf16(fa[i & 1][0], fb[i & 1][0], acc[0][0], 0, 0, 0);
;       acc[0][1] = __builtin_amdgcn_mfma_f32_32x32x16_bf16(fa[i & 1][0], fb[i & 1][1], acc[0][1], 0, 0, 0);
;       acc[1][0] = __builtin_amdgcn_mfma_f32_32x32x16_bf16(fa[i & 1][1], fb[i & 1][0], acc[1][0], 0, 0, 0);
;       acc[1][1] = __builtin_amdgcn_mfma_f32_32x32x16_bf16(fa[i & 1][1], fb[i & 1][1], acc[1][1], 0, 0, 0);
;       __builtin_amdgcn_s_setprio(0);
;     }
;     __syncthreads();
;   }
; __device__ __forceinline__ bool tile_map(int it, int nn, int& mt, int& nt) {
;   const int xcd = blockIdx.x & 7, li = blockIdx.x >> 3, nb = gridDim.x >> 3;
;   int q = it * nb + li;
;   const int per = 16 * nn;
;   if (q < per) {
;     int sub = q / (8 * nn), r = q - sub * (8 * nn);
;     nt = r >> 3;
;     mt = xcd * 16 + sub * 8 + (r & 7);
;     return true;
;   }
;   q -= per;
;   int n = q * 8 + xcd;
	ds_read_b128 v[110:113], v104
	ds_read_b128 v[114:117], v104 offset:4608
	ds_read_b128 v[118:121], v101 offset:18432
	ds_read_b128 v[122:125], v101 offset:23040
	s_waitcnt vmcnt(7)
	ds_write_b128 v100, v[64:67] offset:36864
	s_waitcnt vmcnt(6)
	ds_write_b128 v100, v[68:71] offset:55296
	ds_read_b128 v[126:129], v104 offset:32
	ds_read_b128 v[130:133], v104 offset:4640
	ds_read_b128 v[134:137], v101 offset:18464
	ds_read_b128 v[138:141], v101 offset:23072
	s_waitcnt lgkmcnt(7)
	v_mfma_f32_32x32x16_bf16 v[16:31], v[110:113], v[118:121], v[16:31]
	s_waitcnt lgkmcnt(6)
	v_mfma_f32_32x32x16_bf16 v[48:63], v[110:113], v[122:125], v[48:63]
	v_mfma_f32_32x32x16_bf16 v[0:15], v[114:117], v[118:121], v[0:15]
	v_mfma_f32_32x32x16_bf16 v[32:47], v[114:117], v[122:125], v[32:47]
	s_waitcnt vmcnt(5)
	ds_write_b128 v100, v[72:75] offset:41472
	s_waitcnt vmcnt(4)
	ds_write_b128 v100, v[76:79] offset:59904
	ds_read_b128 v[110:113], v104 offset:64
	ds_read_b128 v[114:117], v104 offset:4672
	ds_read_b128 v[118:121], v101 offset:18496
	ds_read_b128 v[122:125], v101 offset:23104
	s_waitcnt lgkmcnt(7)
	v_mfma_f32_32x32x16_bf16 v[16:31], v[126:129], v[134:137], v[16:31]
	s_waitcnt lgkmcnt(6)
	v_mfma_f32_32x32x16_bf16 v[48:63], v[126:129], v[138:141], v[48:63]
	v_mfma_f32_32x32x16_bf16 v[0:15], v[130:133], v[134:137], v[0:15]
	v_mfma_f32_32x32x16_bf16 v[32:47], v[130:133], v[138:141], v[32:47]
	s_waitcnt vmcnt(3)
	ds_write_b128 v100, v[80:83] offset:46080
	s_waitcnt vmcnt(2)
	ds_write_b128 v100, v[84:87] offset:64512
	ds_read_b128 v[126:129], v104 offset:96
	ds_read_b128 v[130:133], v104 offset:4704
	ds_read_b128 v[134:137], v101 offset:18528
	ds_read_b128 v[138:141], v101 offset:23136
	s_waitcnt lgkmcnt(7)
	v_mfma_f32_32x32x16_bf16 v[16:31], v[110:113], v[118:121], v[16:31]
	s_waitcnt lgkmcnt(6)
	v_mfma_f32_32x32x16_bf16 v[48:63], v[110:113], v[122:125], v[48:63]
	v_mfma_f32_32x32x16_bf16 v[0:15], v[114:117], v[118:121], v[0:15]
	v_mfma_f32_32x32x16_bf16 v[32:47], v[114:117], v[122:125], v[32:47]
	s_waitcnt vmcnt(1)
	ds_write_b128 v100, v[88:91] offset:50688
	s_waitcnt vmcnt(0)
	ds_write_b128 v105, v[92:95] offset:13824
	s_waitcnt lgkmcnt(3)
	v_mfma_f32_32x32x16_bf16 v[16:31], v[126:129], v[134:137], v[16:31]
	s_waitcnt lgkmcnt(2)
	v_mfma_f32_32x32x16_bf16 v[48:63], v[126:129], v[138:141], v[48:63]
	v_mfma_f32_32x32x16_bf16 v[0:15], v[130:133], v[134:137], v[0:15]
	v_mfma_f32_32x32x16_bf16 v[32:47], v[130:133], v[138:141], v[32:47]
	s_waitcnt lgkmcnt(0)
	s_barrier
	ds_read_b128 v[110:113], v104 offset:36864
	ds_read_b128 v[114:117], v104 offset:36896
	ds_read_b128 v[118:121], v104 offset:41472
	ds_read_b128 v[122:125], v104 offset:41504
	ds_read_b128 v[126:129], v101 offset:55296
	ds_read_b128 v[130:133], v101 offset:55328
	ds_read_b128 v[134:137], v101 offset:59904
	ds_read_b128 v[138:141], v101 offset:59936
	s_waitcnt lgkmcnt(3)
	v_mfma_f32_32x32x16_bf16 v[16:31], v[110:113], v[126:129], v[16:31]
	s_waitcnt lgkmcnt(1)
	v_mfma_f32_32x32x16_bf16 v[48:63], v[110:113], v[134:137], v[48:63]
	v_mfma_f32_32x32x16_bf16 v[0:15], v[118:121], v[126:129], v[0:15]
	v_mfma_f32_32x32x16_bf16 v[32:47], v[118:121], v[134:137], v[32:47]
	ds_read_b128 v[110:113], v104 offset:36928
	ds_read_b128 v[118:121], v104 offset:41536
	ds_read_b128 v[126:129], v101 offset:55360
	ds_read_b128 v[134:137], v101 offset:59968
	v_mfma_f32_32x32x16_bf16 v[16:31], v[114:117], v[130:133], v[16:31]
	s_waitcnt lgkmcnt(4)
	v_mfma_f32_32x32x16_bf16 v[48:63], v[114:117], v[138:141], v[48:63]
	v_mfma_f32_32x32x16_bf16 v[0:15], v[122:125], v[130:133], v[0:15]
	v_mfma_f32_32x32x16_bf16 v[32:47], v[122:125], v[138:141], v[32:47]
	ds_read_b128 v[114:117], v104 offset:36960
	ds_read_b128 v[122:125], v104 offset:41568
	ds_read_b128 v[130:133], v101 offset:55392
	ds_read_b128 v[138:141], v101 offset:60000
	s_waitcnt lgkmcnt(5)
	v_mfma_f32_32x32x16_bf16 v[16:31], v[110:113], v[126:129], v[16:31]
	s_waitcnt lgkmcnt(4)
	v_mfma_f32_32x32x16_bf16 v[48:63], v[110:113], v[134:137], v[48:63]
	v_mfma_f32_32x32x16_bf16 v[0:15], v[118:121], v[126:129], v[0:15]
	v_mfma_f32_32x32x16_bf16 v[32:47], v[118:121], v[134:137], v[32:47]
	s_waitcnt lgkmcnt(1)
	v_mfma_f32_32x32x16_bf16 v[16:31], v[114:117], v[130:133], v[16:31]
	s_waitcnt lgkmcnt(0)
	v_mfma_f32_32x32x16_bf16 v[48:63], v[114:117], v[138:141], v[48:63]
	v_mfma_f32_32x32x16_bf16 v[0:15], v[122:125], v[130:133], v[0:15]
	v_mfma_f32_32x32x16_bf16 v[32:47], v[122:125], v[138:141], v[32:47]
	s_cmpk_gt_u32 s2, 0x1ff
	s_mov_b64 s[4:5], -1
	s_barrier
	s_cbranch_scc0 .LBB0_803
	s_mov_b64 s[4:5], 0
	s_cmp_gt_i32 s42, 31
	s_mov_b64 s[0:1], 0
	s_cbranch_scc1 .LBB0_803
	s_movk_i32 s62, 0x80
	s_mov_b64 s[0:1], -1
	s_mov_b32 s33, s42

; __device__ __forceinline__ void gemm_run(int tid, f32x16 (&acc)[2][2], GRegs& g, const GOp& o, int K, unsigned char* smem) {
;     ...
;   for (int i = 0; i < 4; i++) {
;     *(u32x4*)(sbuf + (r0 + i * 32) * LDK + sg * 8) = g.a[i];
;     *(u32x4*)(sbuf + 128 * LDK + (r0 + i * 32) * LDK + sg * 8) = g.b[i];
;   }
;   if (nk > 1) {
; #pragma unroll
;     for (int i = 0; i < 4; i++) {
;       g.a[i] = *(const u32x4*)(Ap + (size_t)i * 32 * o.lda + 64);
;       g.b[i] = *(const u32x4*)(Bp + o.bs.o[i] + 64);
;     }
;   }
;   __syncthreads();
;   const int lane = tid & 63, fr = lane & 31, fh = lane >> 5;
;   for (int k = 0; k < nk; k++) {
;     bf16r* cur = sbuf + (k & 1) * (256 * LDK);
;     bf16r* nxt = sbuf + ((k & 1) ^ 1) * (256 * LDK);
;     const bf16r* As = cur + (wm * 64 + fr) * LDK + fh * 8;
;     const bf16r* Bs = cur + 128 * LDK + (wn * 64 + fr) * LDK + fh * 8;
;     const bool wr = (k + 1 < nk), ld = (k + 2 < nk);
;     bf16x8 fa[2][2], fb[2][2];
;     fa[0][0] = *(const bf16x8*)(As);
;     fa[0][1] = *(const bf16x8*)(As + 32 * LDK);
;     fb[0][0] = *(const bf16x8*)(Bs);
;     fb[0][1] = *(const bf16x8*)(Bs + 32 * LDK);
; #pragma unroll
;     for (int i = 0; i < 4; i++) {
;       if (wr) {
;         *(u32x4*)(nxt + (r0 + i * 32) * LDK + sg * 8) = g.a[i];
;         *(u32x4*)(nxt + 128 * LDK + (r0 + i * 32) * LDK + sg * 8) = g.b[i];
;       }
;       if (ld) {
;         g.a[i] = *(const u32x4*)(Ap + (size_t)i * 32 * o.lda + (k + 2) * 64);
;         g.b[i] = *(const u32x4*)(Bp + o.bs.o[i] + (k + 2) * 64);
;       }
;       if (i < 3) {
;         fa[(i + 1) & 1][0] = *(const bf16x8*)(As + (i + 1) * 16);
;         fa[(i + 1) & 1][1] = *(const bf16x8*)(As + 32 * LDK + (i + 1) * 16);
;         fb[(i + 1) & 1][0] = *(const bf16x8*)(Bs + (i + 1) * 16);
;         fb[(i + 1) & 1][1] = *(const bf16x8*)(Bs + 32 * LDK + (i + 1) * 16);
;       }
;       __builtin_amdgcn_sched_barrier(0);
;       __builtin_amdgcn_s_setprio(1);
;       acc[0][0] = __builtin_amdgcn_mfma_f32_32x32x16_bf16(fa[i & 1][0], fb[i & 1][0], acc[0][0], 0, 0, 0);
;       acc[0][1] = __builtin_amdgcn_mfma_f32_32x32x16_bf16(fa[i & 1][0], fb[i & 1][1], acc[0][1], 0, 0, 0);
;       acc[1][0] = __builtin_amdgcn_mfma_f32_32x32x16_bf16(fa[i & 1][1], fb[i & 1][0], acc[1][0], 0, 0, 0);
;       acc[1][1] = __builtin_amdgcn_mfma_f32_32x32x16_bf16(fa[i & 1][1], fb[i & 1][1], acc[1][1], 0, 0, 0);
.LBB0_1584:
	s_ashr_i32 s7, s6, 31
	s_lshl_b64 s[0:1], s[6:7], 18
	s_ashr_i32 s9, s8, 31
	s_waitcnt vmcnt(7)
	ds_write_b128 v100, v[64:67]
	s_waitcnt vmcnt(6)
	ds_write_b128 v100, v[68:71] offset:18432
	s_waitcnt vmcnt(5)
	ds_write_b128 v100, v[72:75] offset:4608
	s_waitcnt vmcnt(4)
	ds_write_b128 v100, v[76:79] offset:23040
	s_waitcnt vmcnt(3)
	ds_write_b128 v100, v[80:83] offset:9216
	s_waitcnt vmcnt(2)
	ds_write_b128 v100, v[84:87] offset:27648
	s_waitcnt vmcnt(1)
	ds_write_b128 v100, v[88:91] offset:13824
	s_waitcnt vmcnt(0)
	ds_write_b128 v100, v[92:95] offset:32256
	v_lshl_add_u64 v[64:65], v[102:103], 0, s[0:1]
	s_lshl_b64 s[4:5], s[8:9], 18
	v_add_co_u32_e32 v72, vcc, s2, v64
	v_lshl_add_u64 v[106:107], v[98:99], 0, s[4:5]
	s_nop 0
	v_addc_co_u32_e32 v73, vcc, 0, v65, vcc
	v_add_co_u32_e32 v76, vcc, s2, v106
	global_load_dwordx4 v[0:3], v[64:65], off offset:128
	global_load_dwordx4 v[4:7], v[106:107], off offset:128
	v_addc_co_u32_e32 v77, vcc, 0, v107, vcc
	v_add_co_u32_e32 v80, vcc, s3, v64
	global_load_dwordx4 v[66:69], v[72:73], off offset:128
	global_load_dwordx4 v[110:113], v[76:77], off offset:128
	v_addc_co_u32_e32 v81, vcc, 0, v65, vcc
	v_add_co_u32_e32 v84, vcc, s3, v106
	s_nop 1
	v_addc_co_u32_e32 v85, vcc, 0, v107, vcc
	v_add_co_u32_e32 v88, vcc, s86, v64
	global_load_dwordx4 v[114:117], v[80:81], off offset:128
	global_load_dwordx4 v[118:121], v[84:85], off offset:128
	v_addc_co_u32_e32 v89, vcc, 0, v65, vcc
	v_add_co_u32_e32 v92, vcc, s86, v106
	s_nop 1
	v_addc_co_u32_e32 v93, vcc, 0, v107, vcc
	global_load_dwordx4 v[122:125], v[88:89], off offset:128
	global_load_dwordx4 v[126:129], v[92:93], off offset:128
	s_waitcnt lgkmcnt(0)
	s_barrier
	global_load_dwordx4 v[130:133], v[64:65], off offset:256
	global_load_dwordx4 v[134:137], v[106:107], off offset:256
	ds_read_b128 v[8:11], v104
	ds_read_b128 v[32:35], v104 offset:4608
	ds_read_b128 v[12:15], v101 offset:18432
	ds_read_b128 v[36:39], v101 offset:23040
	s_waitcnt vmcnt(9)
	ds_write_b128 v100, v[0:3] offset:36864
	s_waitcnt vmcnt(8)
	ds_write_b128 v100, v[4:7] offset:55296
	ds_read_b128 v[138:141], v104 offset:32
	ds_read_b128 v[142:145], v104 offset:4640
	ds_read_b128 v[146:149], v101 offset:18464
	ds_read_b128 v[150:153], v101 offset:23072
	s_waitcnt lgkmcnt(7)
	v_mfma_f32_32x32x16_bf16 v[16:31], v[8:11], v[12:15], 0
	s_waitcnt lgkmcnt(6)
	v_mfma_f32_32x32x16_bf16 v[48:63], v[8:11], v[36:39], 0
	v_mfma_f32_32x32x16_bf16 v[0:15], v[32:35], v[12:15], 0
	v_mfma_f32_32x32x16_bf16 v[32:47], v[32:35], v[36:39], 0
	global_load_dwordx4 v[154:157], v[72:73], off offset:256
	global_load_dwordx4 v[158:161], v[76:77], off offset:256
	s_waitcnt vmcnt(9)
	ds_write_b128 v100, v[66:69] offset:41472
	s_waitcnt vmcnt(8)
	ds_write_b128 v100, v[110:113] offset:59904
	ds_read_b128 v[66:69], v104 offset:64
	ds_read_b128 v[110:113], v104 offset:4672
	ds_read_b128 v[162:165], v101 offset:18496
	ds_read_b128 v[166:169], v101 offset:23104
	s_waitcnt lgkmcnt(7)
	v_mfma_f32_32x32x16_bf16 v[16:31], v[138:141], v[146:149], v[16:31]
	s_waitcnt lgkmcnt(6)
	v_mfma_f32_32x32x16_bf16 v[48:63], v[138:141], v[150:153], v[48:63]
	v_mfma_f32_32x32x16_bf16 v[0:15], v[142:145], v[146:149], v[0:15]
	v_mfma_f32_32x32x16_bf16 v[32:47], v[142:145], v[150:153], v[32:47]
	global_load_dwordx4 v[138:141], v[80:81], off offset:256
	global_load_dwordx4 v[142:145], v[84:85], off offset:256
	s_waitcnt vmcnt(9)
	ds_write_b128 v100, v[114:117] offset:46080
	s_waitcnt vmcnt(8)
	ds_write_b128 v100, v[118:121] offset:64512
	ds_read_b128 v[114:117], v104 offset:96
	ds_read_b128 v[118:121], v104 offset:4704
	ds_read_b128 v[146:149], v101 offset:18528
	ds_read_b128 v[150:153], v101 offset:23136
	s_waitcnt lgkmcnt(7)
	v_mfma_f32_32x32x16_bf16 v[16:31], v[66:69], v[162:165], v[16:31]
	s_waitcnt lgkmcnt(6)
	v_mfma_f32_32x32x16_bf16 v[48:63], v[66:69], v[166:169], v[48:63]
	v_mfma_f32_32x32x16_bf16 v[0:15], v[110:113], v[162:165], v[0:15]
	v_mfma_f32_32x32x16_bf16 v[32:47], v[110:113], v[166:169], v[32:47]
	global_load_dwordx4 v[66:69], v[88:89], off offset:256
	global_load_dwordx4 v[110:113], v[92:93], off offset:256
	s_waitcnt vmcnt(9)
	ds_write_b128 v100, v[122:125] offset:50688
	s_waitcnt vmcnt(8)
	ds_write_b128 v105, v[126:129] offset:13824
	s_waitcnt lgkmcnt(3)
	v_mfma_f32_32x32x16_bf16 v[16:31], v[114:117], v[146:149], v[16:31]
	s_waitcnt lgkmcnt(2)
	v_mfma_f32_32x32x16_bf16 v[48:63], v[114:117], v[150:153], v[48:63]
	v_mfma_f32_32x32x16_bf16 v[0:15], v[118:121], v[146:149], v[0:15]
	v_mfma_f32_32x32x16_bf16 v[32:47], v[118:121], v[150:153], v[32:47]
	s_waitcnt lgkmcnt(0)
	s_barrier
; __device__ __forceinline__ void gemm_run(int tid, f32x16 (&acc)[2][2], GRegs& g, const GOp& o, int K, unsigned char* smem) {
;     ...
;   for (int k = 0; k < nk; k++) {
;     bf16r* cur = sbuf + (k & 1) * (256 * LDK);
;     bf16r* nxt = sbuf + ((k & 1) ^ 1) * (256 * LDK);
;     const bf16r* As = cur + (wm * 64 + fr) * LDK + fh * 8;
;     const bf16r* Bs = cur + 128 * LDK + (wn * 64 + fr) * LDK + fh * 8;
;     const bool wr = (k + 1 < nk), ld = (k + 2 < nk);
;     bf16x8 fa[2][2], fb[2][2];
;     fa[0][0] = *(const bf16x8*)(As);
;     fa[0][1] = *(const bf16x8*)(As + 32 * LDK);
;     fb[0][0] = *(const bf16x8*)(Bs);
;     fb[0][1] = *(const bf16x8*)(Bs + 32 * LDK);
; #pragma unroll
;     for (int i = 0; i < 4; i++) {
;       if (wr) {
;         *(u32x4*)(nxt + (r0 + i * 32) * LDK + sg * 8) = g.a[i];
;         *(u32x4*)(nxt + 128 * LDK + (r0 + i * 32) * LDK + sg * 8) = g.b[i];
;       }
;       if (ld) {
;         g.a[i] = *(const u32x4*)(Ap + (size_t)i * 32 * o.lda + (k + 2) * 64);
;         g.b[i] = *(const u32x4*)(Bp + o.bs.o[i] + (k + 2) * 64);
;       }
;       if (i < 3) {
;         fa[(i + 1) & 1][0] = *(const bf16x8*)(As + (i + 1) * 16);
;         fa[(i + 1) & 1][1] = *(const bf16x8*)(As + 32 * LDK + (i + 1) * 16);
;         fb[(i + 1) & 1][0] = *(const bf16x8*)(Bs + (i + 1) * 16);
;         fb[(i + 1) & 1][1] = *(const bf16x8*)(Bs + 32 * LDK + (i + 1) * 16);
;       }
;       __builtin_amdgcn_sched_barrier(0);
;       __builtin_amdgcn_s_setprio(1);
;       acc[0][0] = __builtin_amdgcn_mfma_f32_32x32x16_bf16(fa[i & 1][0], fb[i & 1][0], acc[0][0], 0, 0, 0);
;       acc[0][1] = __builtin_amdgcn_mfma_f32_32x32x16_bf16(fa[i & 1][0], fb[i & 1][1], acc[0][1], 0, 0, 0);
;       acc[1][0] = __builtin_amdgcn_mfma_f32_32x32x16_bf16(fa[i & 1][1], fb[i & 1][0], acc[1][0], 0, 0, 0);
;       acc[1][1] = __builtin_amdgcn_mfma_f32_32x32x16_bf16(fa[i & 1][1], fb[i & 1][1], acc[1][1], 0, 0, 0);
;       __builtin_amdgcn_s_setprio(0);
;     }
	global_load_dwordx4 v[114:117], v[64:65], off offset:384
	global_load_dwordx4 v[118:121], v[106:107], off offset:384
	ds_read_b128 v[122:125], v104 offset:36864
	ds_read_b128 v[126:129], v104 offset:41472
	ds_read_b128 v[146:149], v101 offset:55296
	ds_read_b128 v[150:153], v101 offset:59904
	s_waitcnt vmcnt(9)
	ds_write_b128 v100, v[130:133]
	s_waitcnt vmcnt(8)
	ds_write_b128 v100, v[134:137] offset:18432
	ds_read_b128 v[130:133], v104 offset:36896
	ds_read_b128 v[134:137], v104 offset:41504
	ds_read_b128 v[162:165], v101 offset:55328
	ds_read_b128 v[166:169], v101 offset:59936
	s_waitcnt lgkmcnt(7)
	v_mfma_f32_32x32x16_bf16 v[16:31], v[122:125], v[146:149], v[16:31]
	s_waitcnt lgkmcnt(6)
	v_mfma_f32_32x32x16_bf16 v[48:63], v[122:125], v[150:153], v[48:63]
	v_mfma_f32_32x32x16_bf16 v[0:15], v[126:129], v[146:149], v[0:15]
	v_mfma_f32_32x32x16_bf16 v[32:47], v[126:129], v[150:153], v[32:47]
	global_load_dwordx4 v[122:125], v[72:73], off offset:384
	global_load_dwordx4 v[126:129], v[76:77], off offset:384
	s_waitcnt vmcnt(9)
	ds_write_b128 v100, v[154:157] offset:4608
	s_waitcnt vmcnt(8)
	ds_write_b128 v100, v[158:161] offset:23040
	ds_read_b128 v[146:149], v104 offset:36928
	ds_read_b128 v[150:153], v104 offset:41536
	ds_read_b128 v[154:157], v101 offset:55360
	ds_read_b128 v[158:161], v101 offset:59968
	s_waitcnt lgkmcnt(7)
	v_mfma_f32_32x32x16_bf16 v[16:31], v[130:133], v[162:165], v[16:31]
	s_waitcnt lgkmcnt(6)
	v_mfma_f32_32x32x16_bf16 v[48:63], v[130:133], v[166:169], v[48:63]
	v_mfma_f32_32x32x16_bf16 v[0:15], v[134:137], v[162:165], v[0:15]
	v_mfma_f32_32x32x16_bf16 v[32:47], v[134:137], v[166:169], v[32:47]
	global_load_dwordx4 v[130:133], v[80:81], off offset:384
	global_load_dwordx4 v[134:137], v[84:85], off offset:384
	s_waitcnt vmcnt(9)
	ds_write_b128 v100, v[138:141] offset:9216
	s_waitcnt vmcnt(8)
	ds_write_b128 v100, v[142:145] offset:27648
	ds_read_b128 v[138:141], v104 offset:36960
	ds_read_b128 v[142:145], v104 offset:41568
	ds_read_b128 v[162:165], v101 offset:55392
	ds_read_b128 v[166:169], v101 offset:60000
	s_waitcnt lgkmcnt(7)
	v_mfma_f32_32x32x16_bf16 v[16:31], v[146:149], v[154:157], v[16:31]
	s_waitcnt lgkmcnt(6)
	v_mfma_f32_32x32x16_bf16 v[48:63], v[146:149], v[158:161], v[48:63]
	v_mfma_f32_32x32x16_bf16 v[0:15], v[150:153], v[154:157], v[0:15]
	v_mfma_f32_32x32x16_bf16 v[32:47], v[150:153], v[158:161], v[32:47]
	global_load_dwordx4 v[146:149], v[88:89], off offset:384
	global_load_dwordx4 v[150:153], v[92:93], off offset:384
	s_waitcnt vmcnt(9)
	ds_write_b128 v100, v[66:69] offset:13824
	s_waitcnt vmcnt(8)
	ds_write_b128 v100, v[110:113] offset:32256
	s_waitcnt lgkmcnt(3)
	v_mfma_f32_32x32x16_bf16 v[16:31], v[138:141], v[162:165], v[16:31]
	s_waitcnt lgkmcnt(2)
	v_mfma_f32_32x32x16_bf16 v[48:63], v[138:141], v[166:169], v[48:63]
	v_mfma_f32_32x32x16_bf16 v[0:15], v[142:145], v[162:165], v[0:15]
	v_mfma_f32_32x32x16_bf16 v[32:47], v[142:145], v[166:169], v[32:47]
	s_waitcnt lgkmcnt(0)
	s_barrier
	global_load_dwordx4 v[66:69], v[64:65], off offset:512
	global_load_dwordx4 v[110:113], v[106:107], off offset:512
	ds_read_b128 v[138:141], v104
	ds_read_b128 v[142:145], v104 offset:4608
	ds_read_b128 v[154:157], v101 offset:18432
	ds_read_b128 v[158:161], v101 offset:23040
	s_waitcnt vmcnt(9)
	ds_write_b128 v100, v[114:117] offset:36864
	s_waitcnt vmcnt(8)
	ds_write_b128 v100, v[118:121] offset:55296
	ds_read_b128 v[114:117], v104 offset:32
	ds_read_b128 v[118:121], v104 offset:4640
	ds_read_b128 v[162:165], v101 offset:18464
	ds_read_b128 v[166:169], v101 offset:23072
	s_waitcnt lgkmcnt(7)
	v_mfma_f32_32x32x16_bf16 v[16:31], v[138:141], v[154:157], v[16:31]
	s_waitcnt lgkmcnt(6)
	v_mfma_f32_32x32x16_bf16 v[48:63], v[138:141], v[158:161], v[48:63]
	v_mfma_f32_32x32x16_bf16 v[0:15], v[142:145], v[154:157], v[0:15]
	v_mfma_f32_32x32x16_bf16 v[32:47], v[142:145], v[158:161], v[32:47]
	global_load_dwordx4 v[138:141], v[72:73], off offset:512
	global_load_dwordx4 v[142:145], v[76:77], off offset:512
	s_waitcnt vmcnt(9)
	ds_write_b128 v100, v[122:125] offset:41472
	s_waitcnt vmcnt(8)
	ds_write_b128 v100, v[126:129] offset:59904
	ds_read_b128 v[122:125], v104 offset:64
	ds_read_b128 v[126:129], v104 offset:4672
	ds_read_b128 v[154:157], v101 offset:18496
	ds_read_b128 v[158:161], v101 offset:23104
	s_waitcnt lgkmcnt(7)
	v_mfma_f32_32x32x16_bf16 v[16:31], v[114:117], v[162:165], v[16:31]
	s_waitcnt lgkmcnt(6)
	v_mfma_f32_32x32x16_bf16 v[48:63], v[114:117], v[166:169], v[48:63]
	v_mfma_f32_32x32x16_bf16 v[0:15], v[118:121], v[162:165], v[0:15]
	v_mfma_f32_32x32x16_bf16 v[32:47], v[118:121], v[166:169], v[32:47]
	global_load_dwordx4 v[114:117], v[80:81], off offset:512
	global_load_dwordx4 v[118:121], v[84:85], off offset:512
	s_waitcnt vmcnt(9)
	ds_write_b128 v100, v[130:133] offset:46080
	s_waitcnt vmcnt(8)
	ds_write_b128 v100, v[134:137] offset:64512
	ds_read_b128 v[130:133], v104 offset:96
	ds_read_b128 v[134:137], v104 offset:4704
	ds_read_b128 v[162:165], v101 offset:18528
	ds_read_b128 v[166:169], v101 offset:23136
	s_waitcnt lgkmcnt(7)
	v_mfma_f32_32x32x16_bf16 v[16:31], v[122:125], v[154:157], v[16:31]
	s_waitcnt lgkmcnt(6)
	v_mfma_f32_32x32x16_bf16 v[48:63], v[122:125], v[158:161], v[48:63]
	v_mfma_f32_32x32x16_bf16 v[0:15], v[126:129], v[154:157], v[0:15]
	v_mfma_f32_32x32x16_bf16 v[32:47], v[126:129], v[158:161], v[32:47]
	global_load_dwordx4 v[122:125], v[88:89], off offset:512
	global_load_dwordx4 v[126:129], v[92:93], off offset:512
	s_waitcnt vmcnt(9)
	ds_write_b128 v100, v[146:149] offset:50688
	s_waitcnt vmcnt(8)
	ds_write_b128 v105, v[150:153] offset:13824
	s_waitcnt lgkmcnt(3)
	v_mfma_f32_32x32x16_bf16 v[16:31], v[130:133], v[162:165], v[16:31]
	s_waitcnt lgkmcnt(2)
	v_mfma_f32_32x32x16_bf16 v[48:63], v[130:133], v[166:169], v[48:63]
	v_mfma_f32_32x32x16_bf16 v[0:15], v[134:137], v[162:165], v[0:15]
	v_mfma_f32_32x32x16_bf16 v[32:47], v[134:137], v[166:169], v[32:47]
	s_waitcnt lgkmcnt(0)
	s_barrier
; __device__ __forceinline__ void gemm_run(int tid, f32x16 (&acc)[2][2], GRegs& g, const GOp& o, int K, unsigned char* smem) {
;     ...
;   for (int k = 0; k < nk; k++) {
;     bf16r* cur = sbuf + (k & 1) * (256 * LDK);
;     bf16r* nxt = sbuf + ((k & 1) ^ 1) * (256 * LDK);
;     const bf16r* As = cur + (wm * 64 + fr) * LDK + fh * 8;
;     const bf16r* Bs = cur + 128 * LDK + (wn * 64 + fr) * LDK + fh * 8;
;     const bool wr = (k + 1 < nk), ld = (k + 2 < nk);
;     bf16x8 fa[2][2], fb[2][2];
;     fa[0][0] = *(const bf16x8*)(As);
;     fa[0][1] = *(const bf16x8*)(As + 32 * LDK);
;     fb[0][0] = *(const bf16x8*)(Bs);
;     fb[0][1] = *(const bf16x8*)(Bs + 32 * LDK);
; #pragma unroll
;     for (int i = 0; i < 4; i++) {
;       if (wr) {
;         *(u32x4*)(nxt + (r0 + i * 32) * LDK + sg * 8) = g.a[i];
;         *(u32x4*)(nxt + 128 * LDK + (r0 + i * 32) * LDK + sg * 8) = g.b[i];
;       }
;       if (ld) {
;         g.a[i] = *(const u32x4*)(Ap + (size_t)i * 32 * o.lda + (k + 2) * 64);
;         g.b[i] = *(const u32x4*)(Bp + o.bs.o[i] + (k + 2) * 64);
;       }
;       if (i < 3) {
;         fa[(i + 1) & 1][0] = *(const bf16x8*)(As + (i + 1) * 16);
;         fa[(i + 1) & 1][1] = *(const bf16x8*)(As + 32 * LDK + (i + 1) * 16);
;         fb[(i + 1) & 1][0] = *(const bf16x8*)(Bs + (i + 1) * 16);
;         fb[(i + 1) & 1][1] = *(const bf16x8*)(Bs + 32 * LDK + (i + 1) * 16);
;       }
;       __builtin_amdgcn_sched_barrier(0);
;       __builtin_amdgcn_s_setprio(1);
;       acc[0][0] = __builtin_amdgcn_mfma_f32_32x32x16_bf16(fa[i & 1][0], fb[i & 1][0], acc[0][0], 0, 0, 0);
;       acc[0][1] = __builtin_amdgcn_mfma_f32_32x32x16_bf16(fa[i & 1][0], fb[i & 1][1], acc[0][1], 0, 0, 0);
;       acc[1][0] = __builtin_amdgcn_mfma_f32_32x32x16_bf16(fa[i & 1][1], fb[i & 1][0], acc[1][0], 0, 0, 0);
;       acc[1][1] = __builtin_amdgcn_mfma_f32_32x32x16_bf16(fa[i & 1][1], fb[i & 1][1], acc[1][1], 0, 0, 0);
;       __builtin_amdgcn_s_setprio(0);
;     }
	global_load_dwordx4 v[130:133], v[64:65], off offset:640
	global_load_dwordx4 v[134:137], v[106:107], off offset:640
	ds_read_b128 v[146:149], v104 offset:36864
	ds_read_b128 v[150:153], v104 offset:41472
	ds_read_b128 v[154:157], v101 offset:55296
	ds_read_b128 v[158:161], v101 offset:59904
	s_waitcnt vmcnt(9)
	ds_write_b128 v100, v[66:69]
	s_waitcnt vmcnt(8)
	ds_write_b128 v100, v[110:113] offset:18432
	ds_read_b128 v[66:69], v104 offset:36896
	ds_read_b128 v[110:113], v104 offset:41504
	ds_read_b128 v[162:165], v101 offset:55328
	ds_read_b128 v[166:169], v101 offset:59936
	s_waitcnt lgkmcnt(7)
	v_mfma_f32_32x32x16_bf16 v[16:31], v[146:149], v[154:157], v[16:31]
	s_waitcnt lgkmcnt(6)
	v_mfma_f32_32x32x16_bf16 v[48:63], v[146:149], v[158:161], v[48:63]
	v_mfma_f32_32x32x16_bf16 v[0:15], v[150:153], v[154:157], v[0:15]
	v_mfma_f32_32x32x16_bf16 v[32:47], v[150:153], v[158:161], v[32:47]
	global_load_dwordx4 v[146:149], v[72:73], off offset:640
	global_load_dwordx4 v[150:153], v[76:77], off offset:640
	s_waitcnt vmcnt(9)
	ds_write_b128 v100, v[138:141] offset:4608
	s_waitcnt vmcnt(8)
	ds_write_b128 v100, v[142:145] offset:23040
	ds_read_b128 v[138:141], v104 offset:36928
	ds_read_b128 v[142:145], v104 offset:41536
	ds_read_b128 v[154:157], v101 offset:55360
	ds_read_b128 v[158:161], v101 offset:59968
	s_waitcnt lgkmcnt(7)
	v_mfma_f32_32x32x16_bf16 v[16:31], v[66:69], v[162:165], v[16:31]
	s_waitcnt lgkmcnt(6)
	v_mfma_f32_32x32x16_bf16 v[48:63], v[66:69], v[166:169], v[48:63]
	v_mfma_f32_32x32x16_bf16 v[0:15], v[110:113], v[162:165], v[0:15]
	v_mfma_f32_32x32x16_bf16 v[32:47], v[110:113], v[166:169], v[32:47]
	global_load_dwordx4 v[66:69], v[80:81], off offset:640
	global_load_dwordx4 v[110:113], v[84:85], off offset:640
	s_waitcnt vmcnt(9)
	ds_write_b128 v100, v[114:117] offset:9216
	s_waitcnt vmcnt(8)
	ds_write_b128 v100, v[118:121] offset:27648
	ds_read_b128 v[114:117], v104 offset:36960
	ds_read_b128 v[118:121], v104 offset:41568
	ds_read_b128 v[162:165], v101 offset:55392
	ds_read_b128 v[166:169], v101 offset:60000
	s_waitcnt lgkmcnt(7)
	v_mfma_f32_32x32x16_bf16 v[16:31], v[138:141], v[154:157], v[16:31]
	s_waitcnt lgkmcnt(6)
	v_mfma_f32_32x32x16_bf16 v[48:63], v[138:141], v[158:161], v[48:63]
	v_mfma_f32_32x32x16_bf16 v[0:15], v[142:145], v[154:157], v[0:15]
	v_mfma_f32_32x32x16_bf16 v[32:47], v[142:145], v[158:161], v[32:47]
	global_load_dwordx4 v[138:141], v[88:89], off offset:640
	global_load_dwordx4 v[142:145], v[92:93], off offset:640
	s_waitcnt vmcnt(9)
	ds_write_b128 v100, v[122:125] offset:13824
	s_waitcnt vmcnt(8)
	ds_write_b128 v100, v[126:129] offset:32256
	s_waitcnt lgkmcnt(3)
	v_mfma_f32_32x32x16_bf16 v[16:31], v[114:117], v[162:165], v[16:31]
	s_waitcnt lgkmcnt(2)
	v_mfma_f32_32x32x16_bf16 v[48:63], v[114:117], v[166:169], v[48:63]
	v_mfma_f32_32x32x16_bf16 v[0:15], v[118:121], v[162:165], v[0:15]
	v_mfma_f32_32x32x16_bf16 v[32:47], v[118:121], v[166:169], v[32:47]
	s_waitcnt lgkmcnt(0)
	s_barrier
	global_load_dwordx4 v[114:117], v[64:65], off offset:768
	global_load_dwordx4 v[118:121], v[106:107], off offset:768
	ds_read_b128 v[122:125], v104
	ds_read_b128 v[126:129], v104 offset:4608
	ds_read_b128 v[154:157], v101 offset:18432
	ds_read_b128 v[158:161], v101 offset:23040
	s_waitcnt vmcnt(9)
	ds_write_b128 v100, v[130:133] offset:36864
	s_waitcnt vmcnt(8)
	ds_write_b128 v100, v[134:137] offset:55296
	ds_read_b128 v[130:133], v104 offset:32
	ds_read_b128 v[134:137], v104 offset:4640
	ds_read_b128 v[162:165], v101 offset:18464
	ds_read_b128 v[166:169], v101 offset:23072
	s_waitcnt lgkmcnt(7)
	v_mfma_f32_32x32x16_bf16 v[16:31], v[122:125], v[154:157], v[16:31]
	s_waitcnt lgkmcnt(6)
	v_mfma_f32_32x32x16_bf16 v[48:63], v[122:125], v[158:161], v[48:63]
	v_mfma_f32_32x32x16_bf16 v[0:15], v[126:129], v[154:157], v[0:15]
	v_mfma_f32_32x32x16_bf16 v[32:47], v[126:129], v[158:161], v[32:47]
	global_load_dwordx4 v[122:125], v[72:73], off offset:768
	global_load_dwordx4 v[126:129], v[76:77], off offset:768
	s_waitcnt vmcnt(9)
	ds_write_b128 v100, v[146:149] offset:41472
	s_waitcnt vmcnt(8)
	ds_write_b128 v100, v[150:153] offset:59904
	ds_read_b128 v[146:149], v104 offset:64
	ds_read_b128 v[150:153], v104 offset:4672
	ds_read_b128 v[154:157], v101 offset:18496
	ds_read_b128 v[158:161], v101 offset:23104
	s_waitcnt lgkmcnt(7)
	v_mfma_f32_32x32x16_bf16 v[16:31], v[130:133], v[162:165], v[16:31]
	s_waitcnt lgkmcnt(6)
	v_mfma_f32_32x32x16_bf16 v[48:63], v[130:133], v[166:169], v[48:63]
	v_mfma_f32_32x32x16_bf16 v[0:15], v[134:137], v[162:165], v[0:15]
	v_mfma_f32_32x32x16_bf16 v[32:47], v[134:137], v[166:169], v[32:47]
	global_load_dwordx4 v[130:133], v[80:81], off offset:768
	global_load_dwordx4 v[134:137], v[84:85], off offset:768
	s_waitcnt vmcnt(9)
	ds_write_b128 v100, v[66:69] offset:46080
	s_waitcnt vmcnt(8)
	ds_write_b128 v100, v[110:113] offset:64512
	ds_read_b128 v[66:69], v104 offset:96
	ds_read_b128 v[110:113], v104 offset:4704
	ds_read_b128 v[162:165], v101 offset:18528
	ds_read_b128 v[166:169], v101 offset:23136
	s_waitcnt lgkmcnt(7)
	v_mfma_f32_32x32x16_bf16 v[16:31], v[146:149], v[154:157], v[16:31]
	s_waitcnt lgkmcnt(6)
	v_mfma_f32_32x32x16_bf16 v[48:63], v[146:149], v[158:161], v[48:63]
	v_mfma_f32_32x32x16_bf16 v[0:15], v[150:153], v[154:157], v[0:15]
	v_mfma_f32_32x32x16_bf16 v[32:47], v[150:153], v[158:161], v[32:47]
	global_load_dwordx4 v[146:149], v[88:89], off offset:768
	global_load_dwordx4 v[150:153], v[92:93], off offset:768
	s_waitcnt vmcnt(9)
	ds_write_b128 v100, v[138:141] offset:50688
	s_waitcnt vmcnt(8)
	ds_write_b128 v105, v[142:145] offset:13824
	s_waitcnt lgkmcnt(3)
	v_mfma_f32_32x32x16_bf16 v[16:31], v[66:69], v[162:165], v[16:31]
	s_waitcnt lgkmcnt(2)
	v_mfma_f32_32x32x16_bf16 v[48:63], v[66:69], v[166:169], v[48:63]
	v_mfma_f32_32x32x16_bf16 v[0:15], v[110:113], v[162:165], v[0:15]
	v_mfma_f32_32x32x16_bf16 v[32:47], v[110:113], v[166:169], v[32:47]
	s_waitcnt lgkmcnt(0)
	s_barrier
; __device__ __forceinline__ void gemm_run(int tid, f32x16 (&acc)[2][2], GRegs& g, const GOp& o, int K, unsigned char* smem) {
;     ...
;   for (int k = 0; k < nk; k++) {
;     bf16r* cur = sbuf + (k & 1) * (256 * LDK);
;     bf16r* nxt = sbuf + ((k & 1) ^ 1) * (256 * LDK);
;     const bf16r* As = cur + (wm * 64 + fr) * LDK + fh * 8;
;     const bf16r* Bs = cur + 128 * LDK + (wn * 64 + fr) * LDK + fh * 8;
;     const bool wr = (k + 1 < nk), ld = (k + 2 < nk);
;     bf16x8 fa[2][2], fb[2][2];
;     fa[0][0] = *(const bf16x8*)(As);
;     fa[0][1] = *(const bf16x8*)(As + 32 * LDK);
;     fb[0][0] = *(const bf16x8*)(Bs);
;     fb[0][1] = *(const bf16x8*)(Bs + 32 * LDK);
; #pragma unroll
;     for (int i = 0; i < 4; i++) {
;       if (wr) {
;         *(u32x4*)(nxt + (r0 + i * 32) * LDK + sg * 8) = g.a[i];
;         *(u32x4*)(nxt + 128 * LDK + (r0 + i * 32) * LDK + sg * 8) = g.b[i];
;       }
;       if (ld) {
;         g.a[i] = *(const u32x4*)(Ap + (size_t)i * 32 * o.lda + (k + 2) * 64);
;         g.b[i] = *(const u32x4*)(Bp + o.bs.o[i] + (k + 2) * 64);
;       }
;       if (i < 3) {
;         fa[(i + 1) & 1][0] = *(const bf16x8*)(As + (i + 1) * 16);
;         fa[(i + 1) & 1][1] = *(const bf16x8*)(As + 32 * LDK + (i + 1) * 16);
;         fb[(i + 1) & 1][0] = *(const bf16x8*)(Bs + (i + 1) * 16);
;         fb[(i + 1) & 1][1] = *(const bf16x8*)(Bs + 32 * LDK + (i + 1) * 16);
;       }
;       __builtin_amdgcn_sched_barrier(0);
;       __builtin_amdgcn_s_setprio(1);
;       acc[0][0] = __builtin_amdgcn_mfma_f32_32x32x16_bf16(fa[i & 1][0], fb[i & 1][0], acc[0][0], 0, 0, 0);
;       acc[0][1] = __builtin_amdgcn_mfma_f32_32x32x16_bf16(fa[i & 1][0], fb[i & 1][1], acc[0][1], 0, 0, 0);
;       acc[1][0] = __builtin_amdgcn_mfma_f32_32x32x16_bf16(fa[i & 1][1], fb[i & 1][0], acc[1][0], 0, 0, 0);
;       acc[1][1] = __builtin_amdgcn_mfma_f32_32x32x16_bf16(fa[i & 1][1], fb[i & 1][1], acc[1][1], 0, 0, 0);
;       __builtin_amdgcn_s_setprio(0);
;     }
	global_load_dwordx4 v[66:69], v[64:65], off offset:896
	global_load_dwordx4 v[110:113], v[106:107], off offset:896
	ds_read_b128 v[138:141], v104 offset:36864
	ds_read_b128 v[142:145], v104 offset:41472
	ds_read_b128 v[154:157], v101 offset:55296
	ds_read_b128 v[158:161], v101 offset:59904
	s_waitcnt vmcnt(9)
	ds_write_b128 v100, v[114:117]
	s_waitcnt vmcnt(8)
	ds_write_b128 v100, v[118:121] offset:18432
	ds_read_b128 v[114:117], v104 offset:36896
	ds_read_b128 v[118:121], v104 offset:41504
	ds_read_b128 v[162:165], v101 offset:55328
	ds_read_b128 v[166:169], v101 offset:59936
	s_waitcnt lgkmcnt(7)
	v_mfma_f32_32x32x16_bf16 v[16:31], v[138:141], v[154:157], v[16:31]
	s_waitcnt lgkmcnt(6)
	v_mfma_f32_32x32x16_bf16 v[48:63], v[138:141], v[158:161], v[48:63]
	v_mfma_f32_32x32x16_bf16 v[0:15], v[142:145], v[154:157], v[0:15]
	v_mfma_f32_32x32x16_bf16 v[32:47], v[142:145], v[158:161], v[32:47]
	global_load_dwordx4 v[138:141], v[72:73], off offset:896
	global_load_dwordx4 v[142:145], v[76:77], off offset:896
	s_waitcnt vmcnt(9)
	ds_write_b128 v100, v[122:125] offset:4608
	s_waitcnt vmcnt(8)
	ds_write_b128 v100, v[126:129] offset:23040
	ds_read_b128 v[122:125], v104 offset:36928
	ds_read_b128 v[126:129], v104 offset:41536
	ds_read_b128 v[154:157], v101 offset:55360
	ds_read_b128 v[158:161], v101 offset:59968
	s_waitcnt lgkmcnt(7)
	v_mfma_f32_32x32x16_bf16 v[16:31], v[114:117], v[162:165], v[16:31]
	s_waitcnt lgkmcnt(6)
	v_mfma_f32_32x32x16_bf16 v[48:63], v[114:117], v[166:169], v[48:63]
	v_mfma_f32_32x32x16_bf16 v[0:15], v[118:121], v[162:165], v[0:15]
	v_mfma_f32_32x32x16_bf16 v[32:47], v[118:121], v[166:169], v[32:47]
	global_load_dwordx4 v[114:117], v[80:81], off offset:896
	global_load_dwordx4 v[118:121], v[84:85], off offset:896
	s_waitcnt vmcnt(9)
	ds_write_b128 v100, v[130:133] offset:9216
	s_waitcnt vmcnt(8)
	ds_write_b128 v100, v[134:137] offset:27648
	ds_read_b128 v[130:133], v104 offset:36960
	ds_read_b128 v[134:137], v104 offset:41568
	ds_read_b128 v[162:165], v101 offset:55392
	ds_read_b128 v[166:169], v101 offset:60000
	s_waitcnt lgkmcnt(7)
	v_mfma_f32_32x32x16_bf16 v[16:31], v[122:125], v[154:157], v[16:31]
	s_waitcnt lgkmcnt(6)
	v_mfma_f32_32x32x16_bf16 v[48:63], v[122:125], v[158:161], v[48:63]
	v_mfma_f32_32x32x16_bf16 v[0:15], v[126:129], v[154:157], v[0:15]
	v_mfma_f32_32x32x16_bf16 v[32:47], v[126:129], v[158:161], v[32:47]
	global_load_dwordx4 v[122:125], v[88:89], off offset:896
	global_load_dwordx4 v[126:129], v[92:93], off offset:896
	s_waitcnt vmcnt(9)
	ds_write_b128 v100, v[146:149] offset:13824
	s_waitcnt vmcnt(8)
	ds_write_b128 v100, v[150:153] offset:32256
	s_waitcnt lgkmcnt(3)
	v_mfma_f32_32x32x16_bf16 v[16:31], v[130:133], v[162:165], v[16:31]
	s_waitcnt lgkmcnt(2)
	v_mfma_f32_32x32x16_bf16 v[48:63], v[130:133], v[166:169], v[48:63]
	v_mfma_f32_32x32x16_bf16 v[0:15], v[134:137], v[162:165], v[0:15]
	v_mfma_f32_32x32x16_bf16 v[32:47], v[134:137], v[166:169], v[32:47]
	s_waitcnt lgkmcnt(0)
	s_barrier
	global_load_dwordx4 v[130:133], v[64:65], off offset:1024
	global_load_dwordx4 v[134:137], v[106:107], off offset:1024
	ds_read_b128 v[146:149], v104
	ds_read_b128 v[150:153], v104 offset:4608
	ds_read_b128 v[154:157], v101 offset:18432
	ds_read_b128 v[158:161], v101 offset:23040
	s_waitcnt vmcnt(9)
	ds_write_b128 v100, v[66:69] offset:36864
	s_waitcnt vmcnt(8)
	ds_write_b128 v100, v[110:113] offset:55296
	ds_read_b128 v[66:69], v104 offset:32
	ds_read_b128 v[110:113], v104 offset:4640
	ds_read_b128 v[162:165], v101 offset:18464
	ds_read_b128 v[166:169], v101 offset:23072
	s_waitcnt lgkmcnt(7)
	v_mfma_f32_32x32x16_bf16 v[16:31], v[146:149], v[154:157], v[16:31]
	s_waitcnt lgkmcnt(6)
	v_mfma_f32_32x32x16_bf16 v[48:63], v[146:149], v[158:161], v[48:63]
	v_mfma_f32_32x32x16_bf16 v[0:15], v[150:153], v[154:157], v[0:15]
	v_mfma_f32_32x32x16_bf16 v[32:47], v[150:153], v[158:161], v[32:47]
	global_load_dwordx4 v[146:149], v[72:73], off offset:1024
	global_load_dwordx4 v[150:153], v[76:77], off offset:1024
	s_waitcnt vmcnt(9)
	ds_write_b128 v100, v[138:141] offset:41472
	s_waitcnt vmcnt(8)
	ds_write_b128 v100, v[142:145] offset:59904
	ds_read_b128 v[138:141], v104 offset:64
	ds_read_b128 v[142:145], v104 offset:4672
	ds_read_b128 v[154:157], v101 offset:18496
	ds_read_b128 v[158:161], v101 offset:23104
	s_waitcnt lgkmcnt(7)
	v_mfma_f32_32x32x16_bf16 v[16:31], v[66:69], v[162:165], v[16:31]
	s_waitcnt lgkmcnt(6)
	v_mfma_f32_32x32x16_bf16 v[48:63], v[66:69], v[166:169], v[48:63]
	v_mfma_f32_32x32x16_bf16 v[0:15], v[110:113], v[162:165], v[0:15]
	v_mfma_f32_32x32x16_bf16 v[32:47], v[110:113], v[166:169], v[32:47]
	global_load_dwordx4 v[66:69], v[80:81], off offset:1024
	global_load_dwordx4 v[110:113], v[84:85], off offset:1024
	s_waitcnt vmcnt(9)
	ds_write_b128 v100, v[114:117] offset:46080
	s_waitcnt vmcnt(8)
	ds_write_b128 v100, v[118:121] offset:64512
	ds_read_b128 v[114:117], v104 offset:96
	ds_read_b128 v[118:121], v104 offset:4704
	ds_read_b128 v[162:165], v101 offset:18528
	ds_read_b128 v[166:169], v101 offset:23136
	s_waitcnt lgkmcnt(7)
	v_mfma_f32_32x32x16_bf16 v[16:31], v[138:141], v[154:157], v[16:31]
	s_waitcnt lgkmcnt(6)
	v_mfma_f32_32x32x16_bf16 v[48:63], v[138:141], v[158:161], v[48:63]
	v_mfma_f32_32x32x16_bf16 v[0:15], v[142:145], v[154:157], v[0:15]
	v_mfma_f32_32x32x16_bf16 v[32:47], v[142:145], v[158:161], v[32:47]
	global_load_dwordx4 v[138:141], v[88:89], off offset:1024
	global_load_dwordx4 v[142:145], v[92:93], off offset:1024
	s_waitcnt vmcnt(9)
	ds_write_b128 v100, v[122:125] offset:50688
	s_waitcnt vmcnt(8)
	ds_write_b128 v105, v[126:129] offset:13824
	s_waitcnt lgkmcnt(3)
	v_mfma_f32_32x32x16_bf16 v[16:31], v[114:117], v[162:165], v[16:31]
	s_waitcnt lgkmcnt(2)
	v_mfma_f32_32x32x16_bf16 v[48:63], v[114:117], v[166:169], v[48:63]
	v_mfma_f32_32x32x16_bf16 v[0:15], v[118:121], v[162:165], v[0:15]
	v_mfma_f32_32x32x16_bf16 v[32:47], v[118:121], v[166:169], v[32:47]
	s_waitcnt lgkmcnt(0)
	s_barrier
; __device__ __forceinline__ void gemm_run(int tid, f32x16 (&acc)[2][2], GRegs& g, const GOp& o, int K, unsigned char* smem) {
;     ...
;     bf16r* cur = sbuf + (k & 1) * (256 * LDK);
;     bf16r* nxt = sbuf + ((k & 1) ^ 1) * (256 * LDK);
;     const bf16r* As = cur + (wm * 64 + fr) * LDK + fh * 8;
;     const bf16r* Bs = cur + 128 * LDK + (wn * 64 + fr) * LDK + fh * 8;
;     const bool wr = (k + 1 < nk), ld = (k + 2 < nk);
;     bf16x8 fa[2][2], fb[2][2];
;     fa[0][0] = *(const bf16x8*)(As);
;     fa[0][1] = *(const bf16x8*)(As + 32 * LDK);
;     fb[0][0] = *(const bf16x8*)(Bs);
;     fb[0][1] = *(const bf16x8*)(Bs + 32 * LDK);
; #pragma unroll
;     for (int i = 0; i < 4; i++) {
;       if (wr) {
;         *(u32x4*)(nxt + (r0 + i * 32) * LDK + sg * 8) = g.a[i];
;         *(u32x4*)(nxt + 128 * LDK + (r0 + i * 32) * LDK + sg * 8) = g.b[i];
;       }
;       if (ld) {
;         g.a[i] = *(const u32x4*)(Ap + (size_t)i * 32 * o.lda + (k + 2) * 64);
;         g.b[i] = *(const u32x4*)(Bp + o.bs.o[i] + (k + 2) * 64);
;       }
;       if (i < 3) {
;         fa[(i + 1) & 1][0] = *(const bf16x8*)(As + (i + 1) * 16);
;         fa[(i + 1) & 1][1] = *(const bf16x8*)(As + 32 * LDK + (i + 1) * 16);
;         fb[(i + 1) & 1][0] = *(const bf16x8*)(Bs + (i + 1) * 16);
;         fb[(i + 1) & 1][1] = *(const bf16x8*)(Bs + 32 * LDK + (i + 1) * 16);
;       }
;       __builtin_amdgcn_sched_barrier(0);
;       __builtin_amdgcn_s_setprio(1);
;       acc[0][0] = __builtin_amdgcn_mfma_f32_32x32x16_bf16(fa[i & 1][0], fb[i & 1][0], acc[0][0], 0, 0, 0);
;       acc[0][1] = __builtin_amdgcn_mfma_f32_32x32x16_bf16(fa[i & 1][0], fb[i & 1][1], acc[0][1], 0, 0, 0);
;       acc[1][0] = __builtin_amdgcn_mfma_f32_32x32x16_bf16(fa[i & 1][1], fb[i & 1][0], acc[1][0], 0, 0, 0);
;       acc[1][1] = __builtin_amdgcn_mfma_f32_32x32x16_bf16(fa[i & 1][1], fb[i & 1][1], acc[1][1], 0, 0, 0);
;       __builtin_amdgcn_s_setprio(0);
;     }
;     __syncthreads();
	global_load_dwordx4 v[114:117], v[64:65], off offset:1152
	global_load_dwordx4 v[118:121], v[106:107], off offset:1152
	ds_read_b128 v[122:125], v104 offset:36864
	ds_read_b128 v[126:129], v104 offset:41472
	ds_read_b128 v[154:157], v101 offset:55296
	ds_read_b128 v[158:161], v101 offset:59904
	s_waitcnt vmcnt(9)
	ds_write_b128 v100, v[130:133]
	s_waitcnt vmcnt(8)
	ds_write_b128 v100, v[134:137] offset:18432
	ds_read_b128 v[130:133], v104 offset:36896
	ds_read_b128 v[134:137], v104 offset:41504
	ds_read_b128 v[162:165], v101 offset:55328
	ds_read_b128 v[166:169], v101 offset:59936
	s_waitcnt lgkmcnt(7)
	v_mfma_f32_32x32x16_bf16 v[16:31], v[122:125], v[154:157], v[16:31]
	s_waitcnt lgkmcnt(6)
	v_mfma_f32_32x32x16_bf16 v[48:63], v[122:125], v[158:161], v[48:63]
	v_mfma_f32_32x32x16_bf16 v[0:15], v[126:129], v[154:157], v[0:15]
	v_mfma_f32_32x32x16_bf16 v[32:47], v[126:129], v[158:161], v[32:47]
	global_load_dwordx4 v[122:125], v[72:73], off offset:1152
	global_load_dwordx4 v[126:129], v[76:77], off offset:1152
	s_waitcnt vmcnt(9)
	ds_write_b128 v100, v[146:149] offset:4608
	s_waitcnt vmcnt(8)
	ds_write_b128 v100, v[150:153] offset:23040
	ds_read_b128 v[146:149], v104 offset:36928
	ds_read_b128 v[150:153], v104 offset:41536
	ds_read_b128 v[154:157], v101 offset:55360
	ds_read_b128 v[158:161], v101 offset:59968
	s_waitcnt lgkmcnt(7)
	v_mfma_f32_32x32x16_bf16 v[16:31], v[130:133], v[162:165], v[16:31]
	s_waitcnt lgkmcnt(6)
	v_mfma_f32_32x32x16_bf16 v[48:63], v[130:133], v[166:169], v[48:63]
	v_mfma_f32_32x32x16_bf16 v[0:15], v[134:137], v[162:165], v[0:15]
	v_mfma_f32_32x32x16_bf16 v[32:47], v[134:137], v[166:169], v[32:47]
	global_load_dwordx4 v[130:133], v[80:81], off offset:1152
	global_load_dwordx4 v[134:137], v[84:85], off offset:1152
	s_waitcnt vmcnt(9)
	ds_write_b128 v100, v[66:69] offset:9216
	s_waitcnt vmcnt(8)
	ds_write_b128 v100, v[110:113] offset:27648
	ds_read_b128 v[66:69], v104 offset:36960
	ds_read_b128 v[110:113], v104 offset:41568
	ds_read_b128 v[162:165], v101 offset:55392
	ds_read_b128 v[166:169], v101 offset:60000
	s_waitcnt lgkmcnt(7)
	v_mfma_f32_32x32x16_bf16 v[16:31], v[146:149], v[154:157], v[16:31]
	s_waitcnt lgkmcnt(6)
	v_mfma_f32_32x32x16_bf16 v[48:63], v[146:149], v[158:161], v[48:63]
	v_mfma_f32_32x32x16_bf16 v[0:15], v[150:153], v[154:157], v[0:15]
	v_mfma_f32_32x32x16_bf16 v[32:47], v[150:153], v[158:161], v[32:47]
	global_load_dwordx4 v[146:149], v[88:89], off offset:1152
	global_load_dwordx4 v[150:153], v[92:93], off offset:1152
	s_waitcnt vmcnt(9)
	ds_write_b128 v100, v[138:141] offset:13824
	s_waitcnt vmcnt(8)
	ds_write_b128 v100, v[142:145] offset:32256
	s_waitcnt lgkmcnt(3)
	v_mfma_f32_32x32x16_bf16 v[16:31], v[66:69], v[162:165], v[16:31]
	s_waitcnt lgkmcnt(2)
	v_mfma_f32_32x32x16_bf16 v[48:63], v[66:69], v[166:169], v[48:63]
	v_mfma_f32_32x32x16_bf16 v[0:15], v[110:113], v[162:165], v[0:15]
	v_mfma_f32_32x32x16_bf16 v[32:47], v[110:113], v[166:169], v[32:47]
	s_waitcnt lgkmcnt(0)
	s_barrier
	global_load_dwordx4 v[66:69], v[64:65], off offset:1280
	global_load_dwordx4 v[110:113], v[106:107], off offset:1280
	ds_read_b128 v[138:141], v104
	ds_read_b128 v[142:145], v104 offset:4608
	ds_read_b128 v[154:157], v101 offset:18432
	ds_read_b128 v[158:161], v101 offset:23040
	s_waitcnt vmcnt(9)
	ds_write_b128 v100, v[114:117] offset:36864
	s_waitcnt vmcnt(8)
	ds_write_b128 v100, v[118:121] offset:55296
	ds_read_b128 v[114:117], v104 offset:32
	ds_read_b128 v[118:121], v104 offset:4640
	ds_read_b128 v[162:165], v101 offset:18464
	ds_read_b128 v[166:169], v101 offset:23072
	s_waitcnt lgkmcnt(7)
	v_mfma_f32_32x32x16_bf16 v[16:31], v[138:141], v[154:157], v[16:31]
	s_waitcnt lgkmcnt(6)
	v_mfma_f32_32x32x16_bf16 v[48:63], v[138:141], v[158:161], v[48:63]
	v_mfma_f32_32x32x16_bf16 v[0:15], v[142:145], v[154:157], v[0:15]
	v_mfma_f32_32x32x16_bf16 v[32:47], v[142:145], v[158:161], v[32:47]
	global_load_dwordx4 v[138:141], v[72:73], off offset:1280
	global_load_dwordx4 v[142:145], v[76:77], off offset:1280
	s_waitcnt vmcnt(9)
	ds_write_b128 v100, v[122:125] offset:41472
	s_waitcnt vmcnt(8)
	ds_write_b128 v100, v[126:129] offset:59904
	ds_read_b128 v[122:125], v104 offset:64
	ds_read_b128 v[126:129], v104 offset:4672
	ds_read_b128 v[154:157], v101 offset:18496
	ds_read_b128 v[158:161], v101 offset:23104
	s_waitcnt lgkmcnt(7)
	v_mfma_f32_32x32x16_bf16 v[16:31], v[114:117], v[162:165], v[16:31]
	s_waitcnt lgkmcnt(6)
	v_mfma_f32_32x32x16_bf16 v[48:63], v[114:117], v[166:169], v[48:63]
	v_mfma_f32_32x32x16_bf16 v[0:15], v[118:121], v[162:165], v[0:15]
	v_mfma_f32_32x32x16_bf16 v[32:47], v[118:121], v[166:169], v[32:47]
	global_load_dwordx4 v[114:117], v[80:81], off offset:1280
	global_load_dwordx4 v[118:121], v[84:85], off offset:1280
	s_waitcnt vmcnt(9)
	ds_write_b128 v100, v[130:133] offset:46080
	s_waitcnt vmcnt(8)
	ds_write_b128 v100, v[134:137] offset:64512
	ds_read_b128 v[130:133], v104 offset:96
	ds_read_b128 v[134:137], v104 offset:4704
	ds_read_b128 v[162:165], v101 offset:18528
	ds_read_b128 v[166:169], v101 offset:23136
	s_waitcnt lgkmcnt(7)
	v_mfma_f32_32x32x16_bf16 v[16:31], v[122:125], v[154:157], v[16:31]
	s_waitcnt lgkmcnt(6)
	v_mfma_f32_32x32x16_bf16 v[48:63], v[122:125], v[158:161], v[48:63]
	v_mfma_f32_32x32x16_bf16 v[0:15], v[126:129], v[154:157], v[0:15]
	v_mfma_f32_32x32x16_bf16 v[32:47], v[126:129], v[158:161], v[32:47]
	global_load_dwordx4 v[122:125], v[88:89], off offset:1280
	global_load_dwordx4 v[126:129], v[92:93], off offset:1280
	s_waitcnt vmcnt(9)
	ds_write_b128 v100, v[146:149] offset:50688
	s_waitcnt vmcnt(8)
	ds_write_b128 v105, v[150:153] offset:13824
	s_waitcnt lgkmcnt(3)
	v_mfma_f32_32x32x16_bf16 v[16:31], v[130:133], v[162:165], v[16:31]
	s_waitcnt lgkmcnt(2)
	v_mfma_f32_32x32x16_bf16 v[48:63], v[130:133], v[166:169], v[48:63]
	v_mfma_f32_32x32x16_bf16 v[0:15], v[134:137], v[162:165], v[0:15]
	v_mfma_f32_32x32x16_bf16 v[32:47], v[134:137], v[166:169], v[32:47]
	s_waitcnt lgkmcnt(0)
	s_barrier
; __device__ __forceinline__ void gemm_run(int tid, f32x16 (&acc)[2][2], GRegs& g, const GOp& o, int K, unsigned char* smem) {
;     ...
;     bf16r* cur = sbuf + (k & 1) * (256 * LDK);
;     bf16r* nxt = sbuf + ((k & 1) ^ 1) * (256 * LDK);
;     const bf16r* As = cur + (wm * 64 + fr) * LDK + fh * 8;
;     const bf16r* Bs = cur + 128 * LDK + (wn * 64 + fr) * LDK + fh * 8;
;     const bool wr = (k + 1 < nk), ld = (k + 2 < nk);
;     bf16x8 fa[2][2], fb[2][2];
;     fa[0][0] = *(const bf16x8*)(As);
;     fa[0][1] = *(const bf16x8*)(As + 32 * LDK);
;     fb[0][0] = *(const bf16x8*)(Bs);
;     fb[0][1] = *(const bf16x8*)(Bs + 32 * LDK);
; #pragma unroll
;     for (int i = 0; i < 4; i++) {
;       if (wr) {
;         *(u32x4*)(nxt + (r0 + i * 32) * LDK + sg * 8) = g.a[i];
;         *(u32x4*)(nxt + 128 * LDK + (r0 + i * 32) * LDK + sg * 8) = g.b[i];
;       }
;       if (ld) {
;         g.a[i] = *(const u32x4*)(Ap + (size_t)i * 32 * o.lda + (k + 2) * 64);
;         g.b[i] = *(const u32x4*)(Bp + o.bs.o[i] + (k + 2) * 64);
;       }
;       if (i < 3) {
;         fa[(i + 1) & 1][0] = *(const bf16x8*)(As + (i + 1) * 16);
;         fa[(i + 1) & 1][1] = *(const bf16x8*)(As + 32 * LDK + (i + 1) * 16);
;         fb[(i + 1) & 1][0] = *(const bf16x8*)(Bs + (i + 1) * 16);
;         fb[(i + 1) & 1][1] = *(const bf16x8*)(Bs + 32 * LDK + (i + 1) * 16);
;       }
;       __builtin_amdgcn_sched_barrier(0);
;       __builtin_amdgcn_s_setprio(1);
;       acc[0][0] = __builtin_amdgcn_mfma_f32_32x32x16_bf16(fa[i & 1][0], fb[i & 1][0], acc[0][0], 0, 0, 0);
;       acc[0][1] = __builtin_amdgcn_mfma_f32_32x32x16_bf16(fa[i & 1][0], fb[i & 1][1], acc[0][1], 0, 0, 0);
;       acc[1][0] = __builtin_amdgcn_mfma_f32_32x32x16_bf16(fa[i & 1][1], fb[i & 1][0], acc[1][0], 0, 0, 0);
;       acc[1][1] = __builtin_amdgcn_mfma_f32_32x32x16_bf16(fa[i & 1][1], fb[i & 1][1], acc[1][1], 0, 0, 0);
;       __builtin_amdgcn_s_setprio(0);
;     }
;     __syncthreads();
	global_load_dwordx4 v[130:133], v[64:65], off offset:1408
	global_load_dwordx4 v[134:137], v[106:107], off offset:1408
	ds_read_b128 v[146:149], v104 offset:36864
	ds_read_b128 v[150:153], v104 offset:41472
	ds_read_b128 v[154:157], v101 offset:55296
	ds_read_b128 v[158:161], v101 offset:59904
	s_waitcnt vmcnt(9)
	ds_write_b128 v100, v[66:69]
	s_waitcnt vmcnt(8)
	ds_write_b128 v100, v[110:113] offset:18432
	ds_read_b128 v[66:69], v104 offset:36896
	ds_read_b128 v[110:113], v104 offset:41504
	ds_read_b128 v[162:165], v101 offset:55328
	ds_read_b128 v[166:169], v101 offset:59936
	s_waitcnt lgkmcnt(7)
	v_mfma_f32_32x32x16_bf16 v[16:31], v[146:149], v[154:157], v[16:31]
	s_waitcnt lgkmcnt(6)
	v_mfma_f32_32x32x16_bf16 v[48:63], v[146:149], v[158:161], v[48:63]
	v_mfma_f32_32x32x16_bf16 v[0:15], v[150:153], v[154:157], v[0:15]
	v_mfma_f32_32x32x16_bf16 v[32:47], v[150:153], v[158:161], v[32:47]
	global_load_dwordx4 v[146:149], v[72:73], off offset:1408
	global_load_dwordx4 v[150:153], v[76:77], off offset:1408
	s_waitcnt vmcnt(9)
	ds_write_b128 v100, v[138:141] offset:4608
	s_waitcnt vmcnt(8)
	ds_write_b128 v100, v[142:145] offset:23040
	ds_read_b128 v[138:141], v104 offset:36928
	ds_read_b128 v[142:145], v104 offset:41536
	ds_read_b128 v[154:157], v101 offset:55360
	ds_read_b128 v[158:161], v101 offset:59968
	s_waitcnt lgkmcnt(7)
	v_mfma_f32_32x32x16_bf16 v[16:31], v[66:69], v[162:165], v[16:31]
	s_waitcnt lgkmcnt(6)
	v_mfma_f32_32x32x16_bf16 v[48:63], v[66:69], v[166:169], v[48:63]
	v_mfma_f32_32x32x16_bf16 v[0:15], v[110:113], v[162:165], v[0:15]
	v_mfma_f32_32x32x16_bf16 v[32:47], v[110:113], v[166:169], v[32:47]
	global_load_dwordx4 v[66:69], v[80:81], off offset:1408
	global_load_dwordx4 v[110:113], v[84:85], off offset:1408
	s_waitcnt vmcnt(9)
	ds_write_b128 v100, v[114:117] offset:9216
	s_waitcnt vmcnt(8)
	ds_write_b128 v100, v[118:121] offset:27648
	ds_read_b128 v[114:117], v104 offset:36960
	ds_read_b128 v[118:121], v104 offset:41568
	ds_read_b128 v[162:165], v101 offset:55392
	ds_read_b128 v[166:169], v101 offset:60000
	s_waitcnt lgkmcnt(7)
	v_mfma_f32_32x32x16_bf16 v[16:31], v[138:141], v[154:157], v[16:31]
	s_waitcnt lgkmcnt(6)
	v_mfma_f32_32x32x16_bf16 v[48:63], v[138:141], v[158:161], v[48:63]
	v_mfma_f32_32x32x16_bf16 v[0:15], v[142:145], v[154:157], v[0:15]
	v_mfma_f32_32x32x16_bf16 v[32:47], v[142:145], v[158:161], v[32:47]
	global_load_dwordx4 v[138:141], v[88:89], off offset:1408
	global_load_dwordx4 v[142:145], v[92:93], off offset:1408
	s_waitcnt vmcnt(9)
	ds_write_b128 v100, v[122:125] offset:13824
	s_waitcnt vmcnt(8)
	ds_write_b128 v100, v[126:129] offset:32256
	s_waitcnt lgkmcnt(3)
	v_mfma_f32_32x32x16_bf16 v[16:31], v[114:117], v[162:165], v[16:31]
	s_waitcnt lgkmcnt(2)
	v_mfma_f32_32x32x16_bf16 v[48:63], v[114:117], v[166:169], v[48:63]
	v_mfma_f32_32x32x16_bf16 v[0:15], v[118:121], v[162:165], v[0:15]
	v_mfma_f32_32x32x16_bf16 v[32:47], v[118:121], v[166:169], v[32:47]
	s_waitcnt lgkmcnt(0)
	s_barrier
	global_load_dwordx4 v[114:117], v[64:65], off offset:1536
	global_load_dwordx4 v[118:121], v[106:107], off offset:1536
	ds_read_b128 v[122:125], v104
	ds_read_b128 v[126:129], v104 offset:4608
	ds_read_b128 v[154:157], v101 offset:18432
	ds_read_b128 v[158:161], v101 offset:23040
	s_waitcnt vmcnt(9)
	ds_write_b128 v100, v[130:133] offset:36864
	s_waitcnt vmcnt(8)
	ds_write_b128 v100, v[134:137] offset:55296
	ds_read_b128 v[130:133], v104 offset:32
	ds_read_b128 v[134:137], v104 offset:4640
	ds_read_b128 v[162:165], v101 offset:18464
	ds_read_b128 v[166:169], v101 offset:23072
	s_waitcnt lgkmcnt(7)
	v_mfma_f32_32x32x16_bf16 v[16:31], v[122:125], v[154:157], v[16:31]
	s_waitcnt lgkmcnt(6)
	v_mfma_f32_32x32x16_bf16 v[48:63], v[122:125], v[158:161], v[48:63]
	v_mfma_f32_32x32x16_bf16 v[0:15], v[126:129], v[154:157], v[0:15]
	v_mfma_f32_32x32x16_bf16 v[32:47], v[126:129], v[158:161], v[32:47]
	global_load_dwordx4 v[122:125], v[72:73], off offset:1536
	global_load_dwordx4 v[126:129], v[76:77], off offset:1536
	s_waitcnt vmcnt(9)
	ds_write_b128 v100, v[146:149] offset:41472
	s_waitcnt vmcnt(8)
	ds_write_b128 v100, v[150:153] offset:59904
	ds_read_b128 v[146:149], v104 offset:64
	ds_read_b128 v[150:153], v104 offset:4672
	ds_read_b128 v[154:157], v101 offset:18496
	ds_read_b128 v[158:161], v101 offset:23104
	s_waitcnt lgkmcnt(7)
	v_mfma_f32_32x32x16_bf16 v[16:31], v[130:133], v[162:165], v[16:31]
	s_waitcnt lgkmcnt(6)
	v_mfma_f32_32x32x16_bf16 v[48:63], v[130:133], v[166:169], v[48:63]
	v_mfma_f32_32x32x16_bf16 v[0:15], v[134:137], v[162:165], v[0:15]
	v_mfma_f32_32x32x16_bf16 v[32:47], v[134:137], v[166:169], v[32:47]
	global_load_dwordx4 v[130:133], v[80:81], off offset:1536
	global_load_dwordx4 v[134:137], v[84:85], off offset:1536
	s_waitcnt vmcnt(9)
	ds_write_b128 v100, v[66:69] offset:46080
	s_waitcnt vmcnt(8)
	ds_write_b128 v100, v[110:113] offset:64512
	ds_read_b128 v[66:69], v104 offset:96
	ds_read_b128 v[110:113], v104 offset:4704
	ds_read_b128 v[162:165], v101 offset:18528
	ds_read_b128 v[166:169], v101 offset:23136
	s_waitcnt lgkmcnt(7)
	v_mfma_f32_32x32x16_bf16 v[16:31], v[146:149], v[154:157], v[16:31]
	s_waitcnt lgkmcnt(6)
	v_mfma_f32_32x32x16_bf16 v[48:63], v[146:149], v[158:161], v[48:63]
	v_mfma_f32_32x32x16_bf16 v[0:15], v[150:153], v[154:157], v[0:15]
	v_mfma_f32_32x32x16_bf16 v[32:47], v[150:153], v[158:161], v[32:47]
	global_load_dwordx4 v[146:149], v[88:89], off offset:1536
	global_load_dwordx4 v[150:153], v[92:93], off offset:1536
	s_waitcnt vmcnt(9)
	ds_write_b128 v100, v[138:141] offset:50688
	s_waitcnt vmcnt(8)
	ds_write_b128 v105, v[142:145] offset:13824
	s_waitcnt lgkmcnt(3)
	v_mfma_f32_32x32x16_bf16 v[16:31], v[66:69], v[162:165], v[16:31]
	s_waitcnt lgkmcnt(2)
	v_mfma_f32_32x32x16_bf16 v[48:63], v[66:69], v[166:169], v[48:63]
	v_mfma_f32_32x32x16_bf16 v[0:15], v[110:113], v[162:165], v[0:15]
	v_mfma_f32_32x32x16_bf16 v[32:47], v[110:113], v[166:169], v[32:47]
	s_waitcnt lgkmcnt(0)
	s_barrier
; __device__ __forceinline__ void gemm_run(int tid, f32x16 (&acc)[2][2], GRegs& g, const GOp& o, int K, unsigned char* smem) {
;     ...
;     bf16r* cur = sbuf + (k & 1) * (256 * LDK);
;     bf16r* nxt = sbuf + ((k & 1) ^ 1) * (256 * LDK);
;     const bf16r* As = cur + (wm * 64 + fr) * LDK + fh * 8;
;     const bf16r* Bs = cur + 128 * LDK + (wn * 64 + fr) * LDK + fh * 8;
;     const bool wr = (k + 1 < nk), ld = (k + 2 < nk);
;     bf16x8 fa[2][2], fb[2][2];
;     fa[0][0] = *(const bf16x8*)(As);
;     fa[0][1] = *(const bf16x8*)(As + 32 * LDK);
;     fb[0][0] = *(const bf16x8*)(Bs);
;     fb[0][1] = *(const bf16x8*)(Bs + 32 * LDK);
; #pragma unroll
;     for (int i = 0; i < 4; i++) {
;       if (wr) {
;         *(u32x4*)(nxt + (r0 + i * 32) * LDK + sg * 8) = g.a[i];
;         *(u32x4*)(nxt + 128 * LDK + (r0 + i * 32) * LDK + sg * 8) = g.b[i];
;       }
;       if (ld) {
;         g.a[i] = *(const u32x4*)(Ap + (size_t)i * 32 * o.lda + (k + 2) * 64);
;         g.b[i] = *(const u32x4*)(Bp + o.bs.o[i] + (k + 2) * 64);
;       }
;       if (i < 3) {
;         fa[(i + 1) & 1][0] = *(const bf16x8*)(As + (i + 1) * 16);
;         fa[(i + 1) & 1][1] = *(const bf16x8*)(As + 32 * LDK + (i + 1) * 16);
;         fb[(i + 1) & 1][0] = *(const bf16x8*)(Bs + (i + 1) * 16);
;         fb[(i + 1) & 1][1] = *(const bf16x8*)(Bs + 32 * LDK + (i + 1) * 16);
;       }
;       __builtin_amdgcn_sched_barrier(0);
;       __builtin_amdgcn_s_setprio(1);
;       acc[0][0] = __builtin_amdgcn_mfma_f32_32x32x16_bf16(fa[i & 1][0], fb[i & 1][0], acc[0][0], 0, 0, 0);
;       acc[0][1] = __builtin_amdgcn_mfma_f32_32x32x16_bf16(fa[i & 1][0], fb[i & 1][1], acc[0][1], 0, 0, 0);
;       acc[1][0] = __builtin_amdgcn_mfma_f32_32x32x16_bf16(fa[i & 1][1], fb[i & 1][0], acc[1][0], 0, 0, 0);
;       acc[1][1] = __builtin_amdgcn_mfma_f32_32x32x16_bf16(fa[i & 1][1], fb[i & 1][1], acc[1][1], 0, 0, 0);
;       __builtin_amdgcn_s_setprio(0);
;     }
;     __syncthreads();
	global_load_dwordx4 v[66:69], v[64:65], off offset:1664
	global_load_dwordx4 v[110:113], v[106:107], off offset:1664
	ds_read_b128 v[138:141], v104 offset:36864
	ds_read_b128 v[142:145], v104 offset:41472
	ds_read_b128 v[154:157], v101 offset:55296
	ds_read_b128 v[158:161], v101 offset:59904
	s_waitcnt vmcnt(9)
	ds_write_b128 v100, v[114:117]
	s_waitcnt vmcnt(8)
	ds_write_b128 v100, v[118:121] offset:18432
	ds_read_b128 v[114:117], v104 offset:36896
	ds_read_b128 v[118:121], v104 offset:41504
	ds_read_b128 v[162:165], v101 offset:55328
	ds_read_b128 v[166:169], v101 offset:59936
	s_waitcnt lgkmcnt(7)
	v_mfma_f32_32x32x16_bf16 v[16:31], v[138:141], v[154:157], v[16:31]
	s_waitcnt lgkmcnt(6)
	v_mfma_f32_32x32x16_bf16 v[48:63], v[138:141], v[158:161], v[48:63]
	v_mfma_f32_32x32x16_bf16 v[0:15], v[142:145], v[154:157], v[0:15]
	v_mfma_f32_32x32x16_bf16 v[32:47], v[142:145], v[158:161], v[32:47]
	global_load_dwordx4 v[138:141], v[72:73], off offset:1664
	global_load_dwordx4 v[142:145], v[76:77], off offset:1664
	s_waitcnt vmcnt(9)
	ds_write_b128 v100, v[122:125] offset:4608
	s_waitcnt vmcnt(8)
	ds_write_b128 v100, v[126:129] offset:23040
	ds_read_b128 v[122:125], v104 offset:36928
	ds_read_b128 v[126:129], v104 offset:41536
	ds_read_b128 v[154:157], v101 offset:55360
	ds_read_b128 v[158:161], v101 offset:59968
	s_waitcnt lgkmcnt(7)
	v_mfma_f32_32x32x16_bf16 v[16:31], v[114:117], v[162:165], v[16:31]
	s_waitcnt lgkmcnt(6)
	v_mfma_f32_32x32x16_bf16 v[48:63], v[114:117], v[166:169], v[48:63]
	v_mfma_f32_32x32x16_bf16 v[0:15], v[118:121], v[162:165], v[0:15]
	v_mfma_f32_32x32x16_bf16 v[32:47], v[118:121], v[166:169], v[32:47]
	global_load_dwordx4 v[114:117], v[80:81], off offset:1664
	global_load_dwordx4 v[118:121], v[84:85], off offset:1664
	s_waitcnt vmcnt(9)
	ds_write_b128 v100, v[130:133] offset:9216
	s_waitcnt vmcnt(8)
	ds_write_b128 v100, v[134:137] offset:27648
	ds_read_b128 v[130:133], v104 offset:36960
	ds_read_b128 v[134:137], v104 offset:41568
	ds_read_b128 v[162:165], v101 offset:55392
	ds_read_b128 v[166:169], v101 offset:60000
	s_waitcnt lgkmcnt(7)
	v_mfma_f32_32x32x16_bf16 v[16:31], v[122:125], v[154:157], v[16:31]
	s_waitcnt lgkmcnt(6)
	v_mfma_f32_32x32x16_bf16 v[48:63], v[122:125], v[158:161], v[48:63]
	v_mfma_f32_32x32x16_bf16 v[0:15], v[126:129], v[154:157], v[0:15]
	v_mfma_f32_32x32x16_bf16 v[32:47], v[126:129], v[158:161], v[32:47]
	global_load_dwordx4 v[122:125], v[88:89], off offset:1664
	global_load_dwordx4 v[126:129], v[92:93], off offset:1664
	s_waitcnt vmcnt(9)
	ds_write_b128 v100, v[146:149] offset:13824
	s_waitcnt vmcnt(8)
	ds_write_b128 v100, v[150:153] offset:32256
	s_waitcnt lgkmcnt(3)
	v_mfma_f32_32x32x16_bf16 v[16:31], v[130:133], v[162:165], v[16:31]
	s_waitcnt lgkmcnt(2)
	v_mfma_f32_32x32x16_bf16 v[48:63], v[130:133], v[166:169], v[48:63]
	v_mfma_f32_32x32x16_bf16 v[0:15], v[134:137], v[162:165], v[0:15]
	v_mfma_f32_32x32x16_bf16 v[32:47], v[134:137], v[166:169], v[32:47]
	s_waitcnt lgkmcnt(0)
	s_barrier
	global_load_dwordx4 v[130:133], v[64:65], off offset:1792
	global_load_dwordx4 v[134:137], v[106:107], off offset:1792
	ds_read_b128 v[146:149], v104
	ds_read_b128 v[150:153], v104 offset:4608
	ds_read_b128 v[154:157], v101 offset:18432
	ds_read_b128 v[158:161], v101 offset:23040
	s_waitcnt vmcnt(9)
	ds_write_b128 v100, v[66:69] offset:36864
	s_waitcnt vmcnt(8)
	ds_write_b128 v100, v[110:113] offset:55296
	ds_read_b128 v[66:69], v104 offset:32
	ds_read_b128 v[110:113], v104 offset:4640
	ds_read_b128 v[162:165], v101 offset:18464
	ds_read_b128 v[166:169], v101 offset:23072
	s_waitcnt lgkmcnt(7)
	v_mfma_f32_32x32x16_bf16 v[16:31], v[146:149], v[154:157], v[16:31]
	s_waitcnt lgkmcnt(6)
	v_mfma_f32_32x32x16_bf16 v[48:63], v[146:149], v[158:161], v[48:63]
	v_mfma_f32_32x32x16_bf16 v[0:15], v[150:153], v[154:157], v[0:15]
	v_mfma_f32_32x32x16_bf16 v[32:47], v[150:153], v[158:161], v[32:47]
	global_load_dwordx4 v[146:149], v[72:73], off offset:1792
	global_load_dwordx4 v[150:153], v[76:77], off offset:1792
	s_waitcnt vmcnt(9)
	ds_write_b128 v100, v[138:141] offset:41472
	s_waitcnt vmcnt(8)
	ds_write_b128 v100, v[142:145] offset:59904
	ds_read_b128 v[138:141], v104 offset:64
	ds_read_b128 v[142:145], v104 offset:4672
	ds_read_b128 v[154:157], v101 offset:18496
	ds_read_b128 v[158:161], v101 offset:23104
	s_waitcnt lgkmcnt(7)
	v_mfma_f32_32x32x16_bf16 v[16:31], v[66:69], v[162:165], v[16:31]
	s_waitcnt lgkmcnt(6)
	v_mfma_f32_32x32x16_bf16 v[48:63], v[66:69], v[166:169], v[48:63]
	v_mfma_f32_32x32x16_bf16 v[0:15], v[110:113], v[162:165], v[0:15]
	v_mfma_f32_32x32x16_bf16 v[32:47], v[110:113], v[166:169], v[32:47]
	global_load_dwordx4 v[110:113], v[80:81], off offset:1792
	global_load_dwordx4 v[162:165], v[84:85], off offset:1792
	s_waitcnt vmcnt(9)
	ds_write_b128 v100, v[114:117] offset:46080
	s_waitcnt vmcnt(8)
	ds_write_b128 v100, v[118:121] offset:64512
	ds_read_b128 v[66:69], v104 offset:96
	ds_read_b128 v[114:117], v104 offset:4704
	ds_read_b128 v[118:121], v101 offset:18528
	ds_read_b128 v[166:169], v101 offset:23136
	s_waitcnt lgkmcnt(7)
	v_mfma_f32_32x32x16_bf16 v[16:31], v[138:141], v[154:157], v[16:31]
	s_waitcnt lgkmcnt(6)
	v_mfma_f32_32x32x16_bf16 v[48:63], v[138:141], v[158:161], v[48:63]
	v_mfma_f32_32x32x16_bf16 v[0:15], v[142:145], v[154:157], v[0:15]
	v_mfma_f32_32x32x16_bf16 v[32:47], v[142:145], v[158:161], v[32:47]
	global_load_dwordx4 v[138:141], v[88:89], off offset:1792
	global_load_dwordx4 v[142:145], v[92:93], off offset:1792
	s_waitcnt vmcnt(9)
	ds_write_b128 v100, v[122:125] offset:50688
	s_waitcnt vmcnt(8)
	ds_write_b128 v105, v[126:129] offset:13824
	s_waitcnt lgkmcnt(3)
	v_mfma_f32_32x32x16_bf16 v[16:31], v[66:69], v[118:121], v[16:31]
	s_waitcnt lgkmcnt(2)
	v_mfma_f32_32x32x16_bf16 v[48:63], v[66:69], v[166:169], v[48:63]
	v_mfma_f32_32x32x16_bf16 v[0:15], v[114:117], v[118:121], v[0:15]
	v_mfma_f32_32x32x16_bf16 v[32:47], v[114:117], v[166:169], v[32:47]
	s_waitcnt lgkmcnt(0)
	s_barrier
; __device__ __forceinline__ void gemm_run(int tid, f32x16 (&acc)[2][2], GRegs& g, const GOp& o, int K, unsigned char* smem) {
;     ...
;     bf16r* cur = sbuf + (k & 1) * (256 * LDK);
;     bf16r* nxt = sbuf + ((k & 1) ^ 1) * (256 * LDK);
;     const bf16r* As = cur + (wm * 64 + fr) * LDK + fh * 8;
;     const bf16r* Bs = cur + 128 * LDK + (wn * 64 + fr) * LDK + fh * 8;
;     const bool wr = (k + 1 < nk), ld = (k + 2 < nk);
;     bf16x8 fa[2][2], fb[2][2];
;     fa[0][0] = *(const bf16x8*)(As);
;     fa[0][1] = *(const bf16x8*)(As + 32 * LDK);
;     fb[0][0] = *(const bf16x8*)(Bs);
;     fb[0][1] = *(const bf16x8*)(Bs + 32 * LDK);
; #pragma unroll
;     for (int i = 0; i < 4; i++) {
;       if (wr) {
;         *(u32x4*)(nxt + (r0 + i * 32) * LDK + sg * 8) = g.a[i];
;         *(u32x4*)(nxt + 128 * LDK + (r0 + i * 32) * LDK + sg * 8) = g.b[i];
;       }
;       if (ld) {
;         g.a[i] = *(const u32x4*)(Ap + (size_t)i * 32 * o.lda + (k + 2) * 64);
;         g.b[i] = *(const u32x4*)(Bp + o.bs.o[i] + (k + 2) * 64);
;       }
;       if (i < 3) {
;         fa[(i + 1) & 1][0] = *(const bf16x8*)(As + (i + 1) * 16);
;         fa[(i + 1) & 1][1] = *(const bf16x8*)(As + 32 * LDK + (i + 1) * 16);
;         fb[(i + 1) & 1][0] = *(const bf16x8*)(Bs + (i + 1) * 16);
;         fb[(i + 1) & 1][1] = *(const bf16x8*)(Bs + 32 * LDK + (i + 1) * 16);
;       }
;       __builtin_amdgcn_sched_barrier(0);
;       __builtin_amdgcn_s_setprio(1);
;       acc[0][0] = __builtin_amdgcn_mfma_f32_32x32x16_bf16(fa[i & 1][0], fb[i & 1][0], acc[0][0], 0, 0, 0);
;       acc[0][1] = __builtin_amdgcn_mfma_f32_32x32x16_bf16(fa[i & 1][0], fb[i & 1][1], acc[0][1], 0, 0, 0);
;       acc[1][0] = __builtin_amdgcn_mfma_f32_32x32x16_bf16(fa[i & 1][1], fb[i & 1][0], acc[1][0], 0, 0, 0);
;       acc[1][1] = __builtin_amdgcn_mfma_f32_32x32x16_bf16(fa[i & 1][1], fb[i & 1][1], acc[1][1], 0, 0, 0);
;       __builtin_amdgcn_s_setprio(0);
;     }
;     __syncthreads();
	global_load_dwordx4 v[64:67], v[64:65], off offset:1920
	s_nop 0
	global_load_dwordx4 v[68:71], v[106:107], off offset:1920
	ds_read_b128 v[114:117], v104 offset:36864
	ds_read_b128 v[118:121], v104 offset:41472
	ds_read_b128 v[122:125], v101 offset:55296
	ds_read_b128 v[126:129], v101 offset:59904
	s_waitcnt vmcnt(9)
	ds_write_b128 v100, v[130:133]
	s_waitcnt vmcnt(8)
	ds_write_b128 v100, v[134:137] offset:18432
	ds_read_b128 v[130:133], v104 offset:36896
	ds_read_b128 v[134:137], v104 offset:41504
	ds_read_b128 v[154:157], v101 offset:55328
	ds_read_b128 v[158:161], v101 offset:59936
	s_waitcnt lgkmcnt(7)
	v_mfma_f32_32x32x16_bf16 v[16:31], v[114:117], v[122:125], v[16:31]
	s_waitcnt lgkmcnt(6)
	v_mfma_f32_32x32x16_bf16 v[48:63], v[114:117], v[126:129], v[48:63]
	v_mfma_f32_32x32x16_bf16 v[0:15], v[118:121], v[122:125], v[0:15]
	v_mfma_f32_32x32x16_bf16 v[32:47], v[118:121], v[126:129], v[32:47]
	global_load_dwordx4 v[72:75], v[72:73], off offset:1920
	s_nop 0
	global_load_dwordx4 v[76:79], v[76:77], off offset:1920
	s_waitcnt vmcnt(9)
	ds_write_b128 v100, v[146:149] offset:4608
	s_waitcnt vmcnt(8)
	ds_write_b128 v100, v[150:153] offset:23040
	ds_read_b128 v[114:117], v104 offset:36928
	ds_read_b128 v[118:121], v104 offset:41536
	ds_read_b128 v[122:125], v101 offset:55360
	ds_read_b128 v[126:129], v101 offset:59968
	s_waitcnt lgkmcnt(7)
	v_mfma_f32_32x32x16_bf16 v[16:31], v[130:133], v[154:157], v[16:31]
	s_waitcnt lgkmcnt(6)
	v_mfma_f32_32x32x16_bf16 v[48:63], v[130:133], v[158:161], v[48:63]
	v_mfma_f32_32x32x16_bf16 v[0:15], v[134:137], v[154:157], v[0:15]
	v_mfma_f32_32x32x16_bf16 v[32:47], v[134:137], v[158:161], v[32:47]
	global_load_dwordx4 v[80:83], v[80:81], off offset:1920
	s_nop 0
	global_load_dwordx4 v[84:87], v[84:85], off offset:1920
	s_waitcnt vmcnt(9)
	ds_write_b128 v100, v[110:113] offset:9216
	s_waitcnt vmcnt(8)
	ds_write_b128 v100, v[162:165] offset:27648
	ds_read_b128 v[110:113], v104 offset:36960
	ds_read_b128 v[130:133], v104 offset:41568
	ds_read_b128 v[134:137], v101 offset:55392
	ds_read_b128 v[146:149], v101 offset:60000
	s_waitcnt lgkmcnt(7)
	v_mfma_f32_32x32x16_bf16 v[16:31], v[114:117], v[122:125], v[16:31]
	s_waitcnt lgkmcnt(6)
	v_mfma_f32_32x32x16_bf16 v[48:63], v[114:117], v[126:129], v[48:63]
	v_mfma_f32_32x32x16_bf16 v[0:15], v[118:121], v[122:125], v[0:15]
	v_mfma_f32_32x32x16_bf16 v[32:47], v[118:121], v[126:129], v[32:47]
	global_load_dwordx4 v[88:91], v[88:89], off offset:1920
	s_nop 0
	global_load_dwordx4 v[92:95], v[92:93], off offset:1920
	s_waitcnt vmcnt(9)
	ds_write_b128 v100, v[138:141] offset:13824
	s_waitcnt vmcnt(8)
	ds_write_b128 v100, v[142:145] offset:32256
	s_waitcnt lgkmcnt(3)
	v_mfma_f32_32x32x16_bf16 v[16:31], v[110:113], v[134:137], v[16:31]
	s_waitcnt lgkmcnt(2)
	v_mfma_f32_32x32x16_bf16 v[48:63], v[110:113], v[146:149], v[48:63]
	v_mfma_f32_32x32x16_bf16 v[0:15], v[130:133], v[134:137], v[0:15]
	v_mfma_f32_32x32x16_bf16 v[32:47], v[130:133], v[146:149], v[32:47]
	s_waitcnt lgkmcnt(0)
	s_barrier
; __device__ __forceinline__ void gemm_run(int tid, f32x16 (&acc)[2][2], GRegs& g, const GOp& o, int K, unsigned char* smem) {
;     ...
;   for (int k = 0; k < nk; k++) {
;     bf16r* cur = sbuf + (k & 1) * (256 * LDK);
;     bf16r* nxt = sbuf + ((k & 1) ^ 1) * (256 * LDK);
;     const bf16r* As = cur + (wm * 64 + fr) * LDK + fh * 8;
;     const bf16r* Bs = cur + 128 * LDK + (wn * 64 + fr) * LDK + fh * 8;
;     const bool wr = (k + 1 < nk), ld = (k + 2 < nk);
;     bf16x8 fa[2][2], fb[2][2];
;     fa[0][0] = *(const bf16x8*)(As);
;     fa[0][1] = *(const bf16x8*)(As + 32 * LDK);
;     fb[0][0] = *(const bf16x8*)(Bs);
;     fb[0][1] = *(const bf16x8*)(Bs + 32 * LDK);
; #pragma unroll
;     for (int i = 0; i < 4; i++) {
;       if (wr) {
;         *(u32x4*)(nxt + (r0 + i * 32) * LDK + sg * 8) = g.a[i];
;         *(u32x4*)(nxt + 128 * LDK + (r0 + i * 32) * LDK + sg * 8) = g.b[i];
;       }
;       if (ld) {
;         g.a[i] = *(const u32x4*)(Ap + (size_t)i * 32 * o.lda + (k + 2) * 64);
;         g.b[i] = *(const u32x4*)(Bp + o.bs.o[i] + (k + 2) * 64);
;       }
;       if (i < 3) {
;         fa[(i + 1) & 1][0] = *(const bf16x8*)(As + (i + 1) * 16);
;         fa[(i + 1) & 1][1] = *(const bf16x8*)(As + 32 * LDK + (i + 1) * 16);
;         fb[(i + 1) & 1][0] = *(const bf16x8*)(Bs + (i + 1) * 16);
;         fb[(i + 1) & 1][1] = *(const bf16x8*)(Bs + 32 * LDK + (i + 1) * 16);
;       }
;       __builtin_amdgcn_sched_barrier(0);
;       __builtin_amdgcn_s_setprio(1);
;       acc[0][0] = __builtin_amdgcn_mfma_f32_32x32x16_bf16(fa[i & 1][0], fb[i & 1][0], acc[0][0], 0, 0, 0);
;       acc[0][1] = __builtin_amdgcn_mfma_f32_32x32x16_bf16(fa[i & 1][0], fb[i & 1][1], acc[0][1], 0, 0, 0);
;       acc[1][0] = __builtin_amdgcn_mfma_f32_32x32x16_bf16(fa[i & 1][1], fb[i & 1][0], acc[1][0], 0, 0, 0);
;       acc[1][1] = __builtin_amdgcn_mfma_f32_32x32x16_bf16(fa[i & 1][1], fb[i & 1][1], acc[1][1], 0, 0, 0);
;       __builtin_amdgcn_s_setprio(0);
;     }
;     __syncthreads();
;   }
; __device__ __forceinline__ bool tile_map(int it, int nn, int& mt, int& nt) {
;   const int xcd = blockIdx.x & 7, li = blockIdx.x >> 3, nb = gridDim.x >> 3;
;   int q = it * nb + li;
;   const int per = 16 * nn;
;   if (q < per) {
;     int sub = q / (8 * nn), r = q - sub * (8 * nn);
;     nt = r >> 3;
;     mt = xcd * 16 + sub * 8 + (r & 7);
;     return true;
;   }
;   q -= per;
;   int n = q * 8 + xcd;
	ds_read_b128 v[110:113], v104
	ds_read_b128 v[114:117], v104 offset:4608
	ds_read_b128 v[118:121], v101 offset:18432
	ds_read_b128 v[122:125], v101 offset:23040
	s_waitcnt vmcnt(7)
	ds_write_b128 v100, v[64:67] offset:36864
	s_waitcnt vmcnt(6)
	ds_write_b128 v100, v[68:71] offset:55296
	ds_read_b128 v[126:129], v104 offset:32
	ds_read_b128 v[130:133], v104 offset:4640
	ds_read_b128 v[134:137], v101 offset:18464
	ds_read_b128 v[138:141], v101 offset:23072
	s_waitcnt lgkmcnt(7)
	v_mfma_f32_32x32x16_bf16 v[16:31], v[110:113], v[118:121], v[16:31]
	s_waitcnt lgkmcnt(6)
	v_mfma_f32_32x32x16_bf16 v[48:63], v[110:113], v[122:125], v[48:63]
	v_mfma_f32_32x32x16_bf16 v[0:15], v[114:117], v[118:121], v[0:15]
	v_mfma_f32_32x32x16_bf16 v[32:47], v[114:117], v[122:125], v[32:47]
	s_waitcnt vmcnt(5)
	ds_write_b128 v100, v[72:75] offset:41472
	s_waitcnt vmcnt(4)
	ds_write_b128 v100, v[76:79] offset:59904
	ds_read_b128 v[110:113], v104 offset:64
	ds_read_b128 v[114:117], v104 offset:4672
	ds_read_b128 v[118:121], v101 offset:18496
	ds_read_b128 v[122:125], v101 offset:23104
	s_waitcnt lgkmcnt(7)
	v_mfma_f32_32x32x16_bf16 v[16:31], v[126:129], v[134:137], v[16:31]
	s_waitcnt lgkmcnt(6)
	v_mfma_f32_32x32x16_bf16 v[48:63], v[126:129], v[138:141], v[48:63]
	v_mfma_f32_32x32x16_bf16 v[0:15], v[130:133], v[134:137], v[0:15]
	v_mfma_f32_32x32x16_bf16 v[32:47], v[130:133], v[138:141], v[32:47]
	s_waitcnt vmcnt(3)
	ds_write_b128 v100, v[80:83] offset:46080
	s_waitcnt vmcnt(2)
	ds_write_b128 v100, v[84:87] offset:64512
	ds_read_b128 v[126:129], v104 offset:96
	ds_read_b128 v[130:133], v104 offset:4704
	ds_read_b128 v[134:137], v101 offset:18528
	ds_read_b128 v[138:141], v101 offset:23136
	s_waitcnt lgkmcnt(7)
	v_mfma_f32_32x32x16_bf16 v[16:31], v[110:113], v[118:121], v[16:31]
	s_waitcnt lgkmcnt(6)
	v_mfma_f32_32x32x16_bf16 v[48:63], v[110:113], v[122:125], v[48:63]
	v_mfma_f32_32x32x16_bf16 v[0:15], v[114:117], v[118:121], v[0:15]
	v_mfma_f32_32x32x16_bf16 v[32:47], v[114:117], v[122:125], v[32:47]
	s_waitcnt vmcnt(1)
	ds_write_b128 v100, v[88:91] offset:50688
	s_waitcnt vmcnt(0)
	ds_write_b128 v105, v[92:95] offset:13824
	s_waitcnt lgkmcnt(3)
	v_mfma_f32_32x32x16_bf16 v[16:31], v[126:129], v[134:137], v[16:31]
	s_waitcnt lgkmcnt(2)
	v_mfma_f32_32x32x16_bf16 v[48:63], v[126:129], v[138:141], v[48:63]
	v_mfma_f32_32x32x16_bf16 v[0:15], v[130:133], v[134:137], v[0:15]
	v_mfma_f32_32x32x16_bf16 v[32:47], v[130:133], v[138:141], v[32:47]
	s_waitcnt lgkmcnt(0)
	s_barrier
	ds_read_b128 v[110:113], v104 offset:36864
	ds_read_b128 v[114:117], v104 offset:36896
	ds_read_b128 v[118:121], v104 offset:41472
	ds_read_b128 v[122:125], v104 offset:41504
	ds_read_b128 v[126:129], v101 offset:55296
	ds_read_b128 v[130:133], v101 offset:55328
	ds_read_b128 v[134:137], v101 offset:59904
	ds_read_b128 v[138:141], v101 offset:59936
	s_waitcnt lgkmcnt(3)
	v_mfma_f32_32x32x16_bf16 v[16:31], v[110:113], v[126:129], v[16:31]
	s_waitcnt lgkmcnt(1)
	v_mfma_f32_32x32x16_bf16 v[48:63], v[110:113], v[134:137], v[48:63]
	v_mfma_f32_32x32x16_bf16 v[0:15], v[118:121], v[126:129], v[0:15]
	v_mfma_f32_32x32x16_bf16 v[32:47], v[118:121], v[134:137], v[32:47]
	ds_read_b128 v[110:113], v104 offset:36928
	ds_read_b128 v[118:121], v104 offset:41536
	ds_read_b128 v[126:129], v101 offset:55360
	ds_read_b128 v[134:137], v101 offset:59968
	v_mfma_f32_32x32x16_bf16 v[16:31], v[114:117], v[130:133], v[16:31]
	s_waitcnt lgkmcnt(4)
	v_mfma_f32_32x32x16_bf16 v[48:63], v[114:117], v[138:141], v[48:63]
	v_mfma_f32_32x32x16_bf16 v[0:15], v[122:125], v[130:133], v[0:15]
	v_mfma_f32_32x32x16_bf16 v[32:47], v[122:125], v[138:141], v[32:47]
	ds_read_b128 v[114:117], v104 offset:36960
	ds_read_b128 v[122:125], v104 offset:41568
	ds_read_b128 v[130:133], v101 offset:55392
	ds_read_b128 v[138:141], v101 offset:60000
	s_waitcnt lgkmcnt(5)
	v_mfma_f32_32x32x16_bf16 v[16:31], v[110:113], v[126:129], v[16:31]
	s_waitcnt lgkmcnt(4)
	v_mfma_f32_32x32x16_bf16 v[48:63], v[110:113], v[134:137], v[48:63]
	v_mfma_f32_32x32x16_bf16 v[0:15], v[118:121], v[126:129], v[0:15]
	v_mfma_f32_32x32x16_bf16 v[32:47], v[118:121], v[134:137], v[32:47]
	s_waitcnt lgkmcnt(1)
	v_mfma_f32_32x32x16_bf16 v[16:31], v[114:117], v[130:133], v[16:31]
	s_waitcnt lgkmcnt(0)
	v_mfma_f32_32x32x16_bf16 v[48:63], v[114:117], v[138:141], v[48:63]
	v_mfma_f32_32x32x16_bf16 v[0:15], v[122:125], v[130:133], v[0:15]
	v_mfma_f32_32x32x16_bf16 v[32:47], v[122:125], v[138:141], v[32:47]
	s_cmpk_gt_u32 s87, 0x17f
	s_mov_b64 s[4:5], -1
	s_barrier
	s_cbranch_scc0 .LBB0_1587
	s_mov_b64 s[4:5], 0
	s_cmp_gt_i32 s42, 23
	s_mov_b64 s[0:1], 0
	s_cbranch_scc1 .LBB0_1587
	s_movk_i32 s90, 0x80
	s_mov_b64 s[0:1], -1
	s_mov_b32 s83, s42

; __device__ __forceinline__ void gemm_run(int tid, f32x16 (&acc)[2][2], GRegs& g, const GOp& o, int K, unsigned char* smem) {
;     ...
;   for (int i = 0; i < 4; i++) {
;     *(u32x4*)(sbuf + (r0 + i * 32) * LDK + sg * 8) = g.a[i];
;     *(u32x4*)(sbuf + 128 * LDK + (r0 + i * 32) * LDK + sg * 8) = g.b[i];
;   }
;   if (nk > 1) {
; #pragma unroll
;     for (int i = 0; i < 4; i++) {
;       g.a[i] = *(const u32x4*)(Ap + (size_t)i * 32 * o.lda + 64);
;       g.b[i] = *(const u32x4*)(Bp + o.bs.o[i] + 64);
;     }
;   }
;   __syncthreads();
;   const int lane = tid & 63, fr = lane & 31, fh = lane >> 5;
;   for (int k = 0; k < nk; k++) {
;     bf16r* cur = sbuf + (k & 1) * (256 * LDK);
;     bf16r* nxt = sbuf + ((k & 1) ^ 1) * (256 * LDK);
;     const bf16r* As = cur + (wm * 64 + fr) * LDK + fh * 8;
;     const bf16r* Bs = cur + 128 * LDK + (wn * 64 + fr) * LDK + fh * 8;
;     const bool wr = (k + 1 < nk), ld = (k + 2 < nk);
;     bf16x8 fa[2][2], fb[2][2];
;     fa[0][0] = *(const bf16x8*)(As);
;     fa[0][1] = *(const bf16x8*)(As + 32 * LDK);
;     fb[0][0] = *(const bf16x8*)(Bs);
;     fb[0][1] = *(const bf16x8*)(Bs + 32 * LDK);
; #pragma unroll
;     for (int i = 0; i < 4; i++) {
;       if (wr) {
;         *(u32x4*)(nxt + (r0 + i * 32) * LDK + sg * 8) = g.a[i];
;         *(u32x4*)(nxt + 128 * LDK + (r0 + i * 32) * LDK + sg * 8) = g.b[i];
;       }
;       if (ld) {
;         g.a[i] = *(const u32x4*)(Ap + (size_t)i * 32 * o.lda + (k + 2) * 64);
;         g.b[i] = *(const u32x4*)(Bp + o.bs.o[i] + (k + 2) * 64);
;       }
;       if (i < 3) {
;         fa[(i + 1) & 1][0] = *(const bf16x8*)(As + (i + 1) * 16);
;         fa[(i + 1) & 1][1] = *(const bf16x8*)(As + 32 * LDK + (i + 1) * 16);
;         fb[(i + 1) & 1][0] = *(const bf16x8*)(Bs + (i + 1) * 16);
;         fb[(i + 1) & 1][1] = *(const bf16x8*)(Bs + 32 * LDK + (i + 1) * 16);
;       }
;       __builtin_amdgcn_sched_barrier(0);
;       __builtin_amdgcn_s_setprio(1);
;       acc[0][0] = __builtin_amdgcn_mfma_f32_32x32x16_bf16(fa[i & 1][0], fb[i & 1][0], acc[0][0], 0, 0, 0);
;       acc[0][1] = __builtin_amdgcn_mfma_f32_32x32x16_bf16(fa[i & 1][0], fb[i & 1][1], acc[0][1], 0, 0, 0);
;       acc[1][0] = __builtin_amdgcn_mfma_f32_32x32x16_bf16(fa[i & 1][1], fb[i & 1][0], acc[1][0], 0, 0, 0);
;       acc[1][1] = __builtin_amdgcn_mfma_f32_32x32x16_bf16(fa[i & 1][1], fb[i & 1][1], acc[1][1], 0, 0, 0);
.LBB0_1975:
	s_ashr_i32 s7, s6, 31
	s_lshl_b64 s[0:1], s[6:7], 18
	s_ashr_i32 s9, s8, 31
	s_waitcnt vmcnt(7)
	ds_write_b128 v100, v[64:67]
	s_waitcnt vmcnt(6)
	ds_write_b128 v100, v[68:71] offset:18432
	s_waitcnt vmcnt(5)
	ds_write_b128 v100, v[72:75] offset:4608
	s_waitcnt vmcnt(4)
	ds_write_b128 v100, v[76:79] offset:23040
	s_waitcnt vmcnt(3)
	ds_write_b128 v100, v[80:83] offset:9216
	s_waitcnt vmcnt(2)
	ds_write_b128 v100, v[84:87] offset:27648
	s_waitcnt vmcnt(1)
	ds_write_b128 v100, v[88:91] offset:13824
	s_waitcnt vmcnt(0)
	ds_write_b128 v100, v[92:95] offset:32256
	v_lshl_add_u64 v[64:65], v[102:103], 0, s[0:1]
	s_lshl_b64 s[4:5], s[8:9], 18
	v_add_co_u32_e32 v72, vcc, s42, v64
	v_lshl_add_u64 v[106:107], v[98:99], 0, s[4:5]
	s_nop 0
	v_addc_co_u32_e32 v73, vcc, 0, v65, vcc
	v_add_co_u32_e32 v76, vcc, s42, v106
	global_load_dwordx4 v[0:3], v[64:65], off offset:128
	global_load_dwordx4 v[4:7], v[106:107], off offset:128
	v_addc_co_u32_e32 v77, vcc, 0, v107, vcc
	v_add_co_u32_e32 v80, vcc, s43, v64
	global_load_dwordx4 v[66:69], v[72:73], off offset:128
	global_load_dwordx4 v[110:113], v[76:77], off offset:128
	v_addc_co_u32_e32 v81, vcc, 0, v65, vcc
	v_add_co_u32_e32 v84, vcc, s43, v106
	s_nop 1
	v_addc_co_u32_e32 v85, vcc, 0, v107, vcc
	v_add_co_u32_e32 v88, vcc, s33, v64
	global_load_dwordx4 v[114:117], v[80:81], off offset:128
	global_load_dwordx4 v[118:121], v[84:85], off offset:128
	v_addc_co_u32_e32 v89, vcc, 0, v65, vcc
	v_add_co_u32_e32 v92, vcc, s33, v106
	s_nop 1
	v_addc_co_u32_e32 v93, vcc, 0, v107, vcc
	global_load_dwordx4 v[122:125], v[88:89], off offset:128
	global_load_dwordx4 v[126:129], v[92:93], off offset:128
	s_waitcnt lgkmcnt(0)
	s_barrier
	global_load_dwordx4 v[130:133], v[64:65], off offset:256
	global_load_dwordx4 v[134:137], v[106:107], off offset:256
	ds_read_b128 v[8:11], v104
	ds_read_b128 v[32:35], v104 offset:4608
	ds_read_b128 v[12:15], v101 offset:18432
	ds_read_b128 v[36:39], v101 offset:23040
	s_waitcnt vmcnt(9)
	ds_write_b128 v100, v[0:3] offset:36864
	s_waitcnt vmcnt(8)
	ds_write_b128 v100, v[4:7] offset:55296
	ds_read_b128 v[138:141], v104 offset:32
	ds_read_b128 v[142:145], v104 offset:4640
	ds_read_b128 v[146:149], v101 offset:18464
	ds_read_b128 v[150:153], v101 offset:23072
	s_waitcnt lgkmcnt(7)
	v_mfma_f32_32x32x16_bf16 v[16:31], v[8:11], v[12:15], 0
	s_waitcnt lgkmcnt(6)
	v_mfma_f32_32x32x16_bf16 v[48:63], v[8:11], v[36:39], 0
	v_mfma_f32_32x32x16_bf16 v[0:15], v[32:35], v[12:15], 0
	v_mfma_f32_32x32x16_bf16 v[32:47], v[32:35], v[36:39], 0
	global_load_dwordx4 v[154:157], v[72:73], off offset:256
	global_load_dwordx4 v[158:161], v[76:77], off offset:256
	s_waitcnt vmcnt(9)
	ds_write_b128 v100, v[66:69] offset:41472
	s_waitcnt vmcnt(8)
	ds_write_b128 v100, v[110:113] offset:59904
	ds_read_b128 v[66:69], v104 offset:64
	ds_read_b128 v[110:113], v104 offset:4672
	ds_read_b128 v[162:165], v101 offset:18496
	ds_read_b128 v[166:169], v101 offset:23104
	s_waitcnt lgkmcnt(7)
	v_mfma_f32_32x32x16_bf16 v[16:31], v[138:141], v[146:149], v[16:31]
	s_waitcnt lgkmcnt(6)
	v_mfma_f32_32x32x16_bf16 v[48:63], v[138:141], v[150:153], v[48:63]
	v_mfma_f32_32x32x16_bf16 v[0:15], v[142:145], v[146:149], v[0:15]
	v_mfma_f32_32x32x16_bf16 v[32:47], v[142:145], v[150:153], v[32:47]
	global_load_dwordx4 v[138:141], v[80:81], off offset:256
	global_load_dwordx4 v[142:145], v[84:85], off offset:256
	s_waitcnt vmcnt(9)
	ds_write_b128 v100, v[114:117] offset:46080
	s_waitcnt vmcnt(8)
	ds_write_b128 v100, v[118:121] offset:64512
	ds_read_b128 v[114:117], v104 offset:96
	ds_read_b128 v[118:121], v104 offset:4704
	ds_read_b128 v[146:149], v101 offset:18528
	ds_read_b128 v[150:153], v101 offset:23136
	s_waitcnt lgkmcnt(7)
	v_mfma_f32_32x32x16_bf16 v[16:31], v[66:69], v[162:165], v[16:31]
	s_waitcnt lgkmcnt(6)
	v_mfma_f32_32x32x16_bf16 v[48:63], v[66:69], v[166:169], v[48:63]
	v_mfma_f32_32x32x16_bf16 v[0:15], v[110:113], v[162:165], v[0:15]
	v_mfma_f32_32x32x16_bf16 v[32:47], v[110:113], v[166:169], v[32:47]
	global_load_dwordx4 v[66:69], v[88:89], off offset:256
	global_load_dwordx4 v[110:113], v[92:93], off offset:256
	s_waitcnt vmcnt(9)
	ds_write_b128 v100, v[122:125] offset:50688
	s_waitcnt vmcnt(8)
	ds_write_b128 v105, v[126:129] offset:13824
	s_waitcnt lgkmcnt(3)
	v_mfma_f32_32x32x16_bf16 v[16:31], v[114:117], v[146:149], v[16:31]
	s_waitcnt lgkmcnt(2)
	v_mfma_f32_32x32x16_bf16 v[48:63], v[114:117], v[150:153], v[48:63]
	v_mfma_f32_32x32x16_bf16 v[0:15], v[118:121], v[146:149], v[0:15]
	v_mfma_f32_32x32x16_bf16 v[32:47], v[118:121], v[150:153], v[32:47]
	s_waitcnt lgkmcnt(0)
	s_barrier
; __device__ __forceinline__ void gemm_run(int tid, f32x16 (&acc)[2][2], GRegs& g, const GOp& o, int K, unsigned char* smem) {
;     ...
;     bf16r* cur = sbuf + (k & 1) * (256 * LDK);
;     bf16r* nxt = sbuf + ((k & 1) ^ 1) * (256 * LDK);
;     const bf16r* As = cur + (wm * 64 + fr) * LDK + fh * 8;
;     const bf16r* Bs = cur + 128 * LDK + (wn * 64 + fr) * LDK + fh * 8;
;     const bool wr = (k + 1 < nk), ld = (k + 2 < nk);
;     bf16x8 fa[2][2], fb[2][2];
;     fa[0][0] = *(const bf16x8*)(As);
;     fa[0][1] = *(const bf16x8*)(As + 32 * LDK);
;     fb[0][0] = *(const bf16x8*)(Bs);
;     fb[0][1] = *(const bf16x8*)(Bs + 32 * LDK);
; #pragma unroll
;     for (int i = 0; i < 4; i++) {
;       if (wr) {
;         *(u32x4*)(nxt + (r0 + i * 32) * LDK + sg * 8) = g.a[i];
;         *(u32x4*)(nxt + 128 * LDK + (r0 + i * 32) * LDK + sg * 8) = g.b[i];
;       }
;       if (ld) {
;         g.a[i] = *(const u32x4*)(Ap + (size_t)i * 32 * o.lda + (k + 2) * 64);
;         g.b[i] = *(const u32x4*)(Bp + o.bs.o[i] + (k + 2) * 64);
;       }
;       if (i < 3) {
;         fa[(i + 1) & 1][0] = *(const bf16x8*)(As + (i + 1) * 16);
;         fa[(i + 1) & 1][1] = *(const bf16x8*)(As + 32 * LDK + (i + 1) * 16);
;         fb[(i + 1) & 1][0] = *(const bf16x8*)(Bs + (i + 1) * 16);
;         fb[(i + 1) & 1][1] = *(const bf16x8*)(Bs + 32 * LDK + (i + 1) * 16);
;       }
;       __builtin_amdgcn_sched_barrier(0);
;       __builtin_amdgcn_s_setprio(1);
;       acc[0][0] = __builtin_amdgcn_mfma_f32_32x32x16_bf16(fa[i & 1][0], fb[i & 1][0], acc[0][0], 0, 0, 0);
;       acc[0][1] = __builtin_amdgcn_mfma_f32_32x32x16_bf16(fa[i & 1][0], fb[i & 1][1], acc[0][1], 0, 0, 0);
;       acc[1][0] = __builtin_amdgcn_mfma_f32_32x32x16_bf16(fa[i & 1][1], fb[i & 1][0], acc[1][0], 0, 0, 0);
;       acc[1][1] = __builtin_amdgcn_mfma_f32_32x32x16_bf16(fa[i & 1][1], fb[i & 1][1], acc[1][1], 0, 0, 0);
;       __builtin_amdgcn_s_setprio(0);
;     }
;     __syncthreads();
	global_load_dwordx4 v[114:117], v[64:65], off offset:384
	global_load_dwordx4 v[118:121], v[106:107], off offset:384
	ds_read_b128 v[122:125], v104 offset:36864
	ds_read_b128 v[126:129], v104 offset:41472
	ds_read_b128 v[146:149], v101 offset:55296
	ds_read_b128 v[150:153], v101 offset:59904
	s_waitcnt vmcnt(9)
	ds_write_b128 v100, v[130:133]
	s_waitcnt vmcnt(8)
	ds_write_b128 v100, v[134:137] offset:18432
	ds_read_b128 v[130:133], v104 offset:36896
	ds_read_b128 v[134:137], v104 offset:41504
	ds_read_b128 v[162:165], v101 offset:55328
	ds_read_b128 v[166:169], v101 offset:59936
	s_waitcnt lgkmcnt(7)
	v_mfma_f32_32x32x16_bf16 v[16:31], v[122:125], v[146:149], v[16:31]
	s_waitcnt lgkmcnt(6)
	v_mfma_f32_32x32x16_bf16 v[48:63], v[122:125], v[150:153], v[48:63]
	v_mfma_f32_32x32x16_bf16 v[0:15], v[126:129], v[146:149], v[0:15]
	v_mfma_f32_32x32x16_bf16 v[32:47], v[126:129], v[150:153], v[32:47]
	global_load_dwordx4 v[122:125], v[72:73], off offset:384
	global_load_dwordx4 v[126:129], v[76:77], off offset:384
	s_waitcnt vmcnt(9)
	ds_write_b128 v100, v[154:157] offset:4608
	s_waitcnt vmcnt(8)
	ds_write_b128 v100, v[158:161] offset:23040
	ds_read_b128 v[146:149], v104 offset:36928
	ds_read_b128 v[150:153], v104 offset:41536
	ds_read_b128 v[154:157], v101 offset:55360
	ds_read_b128 v[158:161], v101 offset:59968
	s_waitcnt lgkmcnt(7)
	v_mfma_f32_32x32x16_bf16 v[16:31], v[130:133], v[162:165], v[16:31]
	s_waitcnt lgkmcnt(6)
	v_mfma_f32_32x32x16_bf16 v[48:63], v[130:133], v[166:169], v[48:63]
	v_mfma_f32_32x32x16_bf16 v[0:15], v[134:137], v[162:165], v[0:15]
	v_mfma_f32_32x32x16_bf16 v[32:47], v[134:137], v[166:169], v[32:47]
	global_load_dwordx4 v[130:133], v[80:81], off offset:384
	global_load_dwordx4 v[134:137], v[84:85], off offset:384
	s_waitcnt vmcnt(9)
	ds_write_b128 v100, v[138:141] offset:9216
	s_waitcnt vmcnt(8)
	ds_write_b128 v100, v[142:145] offset:27648
	ds_read_b128 v[138:141], v104 offset:36960
	ds_read_b128 v[142:145], v104 offset:41568
	ds_read_b128 v[162:165], v101 offset:55392
	ds_read_b128 v[166:169], v101 offset:60000
	s_waitcnt lgkmcnt(7)
	v_mfma_f32_32x32x16_bf16 v[16:31], v[146:149], v[154:157], v[16:31]
	s_waitcnt lgkmcnt(6)
	v_mfma_f32_32x32x16_bf16 v[48:63], v[146:149], v[158:161], v[48:63]
	v_mfma_f32_32x32x16_bf16 v[0:15], v[150:153], v[154:157], v[0:15]
	v_mfma_f32_32x32x16_bf16 v[32:47], v[150:153], v[158:161], v[32:47]
	global_load_dwordx4 v[146:149], v[88:89], off offset:384
	global_load_dwordx4 v[150:153], v[92:93], off offset:384
	s_waitcnt vmcnt(9)
	ds_write_b128 v100, v[66:69] offset:13824
	s_waitcnt vmcnt(8)
	ds_write_b128 v100, v[110:113] offset:32256
	s_waitcnt lgkmcnt(3)
	v_mfma_f32_32x32x16_bf16 v[16:31], v[138:141], v[162:165], v[16:31]
	s_waitcnt lgkmcnt(2)
	v_mfma_f32_32x32x16_bf16 v[48:63], v[138:141], v[166:169], v[48:63]
	v_mfma_f32_32x32x16_bf16 v[0:15], v[142:145], v[162:165], v[0:15]
	v_mfma_f32_32x32x16_bf16 v[32:47], v[142:145], v[166:169], v[32:47]
	s_waitcnt lgkmcnt(0)
	s_barrier
	global_load_dwordx4 v[66:69], v[64:65], off offset:512
	global_load_dwordx4 v[110:113], v[106:107], off offset:512
	ds_read_b128 v[138:141], v104
	ds_read_b128 v[142:145], v104 offset:4608
	ds_read_b128 v[154:157], v101 offset:18432
	ds_read_b128 v[158:161], v101 offset:23040
	s_waitcnt vmcnt(9)
	ds_write_b128 v100, v[114:117] offset:36864
	s_waitcnt vmcnt(8)
	ds_write_b128 v100, v[118:121] offset:55296
	ds_read_b128 v[114:117], v104 offset:32
	ds_read_b128 v[118:121], v104 offset:4640
	ds_read_b128 v[162:165], v101 offset:18464
	ds_read_b128 v[166:169], v101 offset:23072
	s_waitcnt lgkmcnt(7)
	v_mfma_f32_32x32x16_bf16 v[16:31], v[138:141], v[154:157], v[16:31]
	s_waitcnt lgkmcnt(6)
	v_mfma_f32_32x32x16_bf16 v[48:63], v[138:141], v[158:161], v[48:63]
	v_mfma_f32_32x32x16_bf16 v[0:15], v[142:145], v[154:157], v[0:15]
	v_mfma_f32_32x32x16_bf16 v[32:47], v[142:145], v[158:161], v[32:47]
	global_load_dwordx4 v[138:141], v[72:73], off offset:512
	global_load_dwordx4 v[142:145], v[76:77], off offset:512
	s_waitcnt vmcnt(9)
	ds_write_b128 v100, v[122:125] offset:41472
	s_waitcnt vmcnt(8)
	ds_write_b128 v100, v[126:129] offset:59904
	ds_read_b128 v[122:125], v104 offset:64
	ds_read_b128 v[126:129], v104 offset:4672
	ds_read_b128 v[154:157], v101 offset:18496
	ds_read_b128 v[158:161], v101 offset:23104
	s_waitcnt lgkmcnt(7)
	v_mfma_f32_32x32x16_bf16 v[16:31], v[114:117], v[162:165], v[16:31]
	s_waitcnt lgkmcnt(6)
	v_mfma_f32_32x32x16_bf16 v[48:63], v[114:117], v[166:169], v[48:63]
	v_mfma_f32_32x32x16_bf16 v[0:15], v[118:121], v[162:165], v[0:15]
	v_mfma_f32_32x32x16_bf16 v[32:47], v[118:121], v[166:169], v[32:47]
	global_load_dwordx4 v[114:117], v[80:81], off offset:512
	global_load_dwordx4 v[118:121], v[84:85], off offset:512
	s_waitcnt vmcnt(9)
	ds_write_b128 v100, v[130:133] offset:46080
	s_waitcnt vmcnt(8)
	ds_write_b128 v100, v[134:137] offset:64512
	ds_read_b128 v[130:133], v104 offset:96
	ds_read_b128 v[134:137], v104 offset:4704
	ds_read_b128 v[162:165], v101 offset:18528
	ds_read_b128 v[166:169], v101 offset:23136
	s_waitcnt lgkmcnt(7)
	v_mfma_f32_32x32x16_bf16 v[16:31], v[122:125], v[154:157], v[16:31]
	s_waitcnt lgkmcnt(6)
	v_mfma_f32_32x32x16_bf16 v[48:63], v[122:125], v[158:161], v[48:63]
	v_mfma_f32_32x32x16_bf16 v[0:15], v[126:129], v[154:157], v[0:15]
	v_mfma_f32_32x32x16_bf16 v[32:47], v[126:129], v[158:161], v[32:47]
	global_load_dwordx4 v[122:125], v[88:89], off offset:512
	global_load_dwordx4 v[126:129], v[92:93], off offset:512
	s_waitcnt vmcnt(9)
	ds_write_b128 v100, v[146:149] offset:50688
	s_waitcnt vmcnt(8)
	ds_write_b128 v105, v[150:153] offset:13824
	s_waitcnt lgkmcnt(3)
	v_mfma_f32_32x32x16_bf16 v[16:31], v[130:133], v[162:165], v[16:31]
	s_waitcnt lgkmcnt(2)
	v_mfma_f32_32x32x16_bf16 v[48:63], v[130:133], v[166:169], v[48:63]
	v_mfma_f32_32x32x16_bf16 v[0:15], v[134:137], v[162:165], v[0:15]
	v_mfma_f32_32x32x16_bf16 v[32:47], v[134:137], v[166:169], v[32:47]
	s_waitcnt lgkmcnt(0)
	s_barrier
; __device__ __forceinline__ void gemm_run(int tid, f32x16 (&acc)[2][2], GRegs& g, const GOp& o, int K, unsigned char* smem) {
;     ...
;     bf16r* cur = sbuf + (k & 1) * (256 * LDK);
;     bf16r* nxt = sbuf + ((k & 1) ^ 1) * (256 * LDK);
;     const bf16r* As = cur + (wm * 64 + fr) * LDK + fh * 8;
;     const bf16r* Bs = cur + 128 * LDK + (wn * 64 + fr) * LDK + fh * 8;
;     const bool wr = (k + 1 < nk), ld = (k + 2 < nk);
;     bf16x8 fa[2][2], fb[2][2];
;     fa[0][0] = *(const bf16x8*)(As);
;     fa[0][1] = *(const bf16x8*)(As + 32 * LDK);
;     fb[0][0] = *(const bf16x8*)(Bs);
;     fb[0][1] = *(const bf16x8*)(Bs + 32 * LDK);
; #pragma unroll
;     for (int i = 0; i < 4; i++) {
;       if (wr) {
;         *(u32x4*)(nxt + (r0 + i * 32) * LDK + sg * 8) = g.a[i];
;         *(u32x4*)(nxt + 128 * LDK + (r0 + i * 32) * LDK + sg * 8) = g.b[i];
;       }
;       if (ld) {
;         g.a[i] = *(const u32x4*)(Ap + (size_t)i * 32 * o.lda + (k + 2) * 64);
;         g.b[i] = *(const u32x4*)(Bp + o.bs.o[i] + (k + 2) * 64);
;       }
;       if (i < 3) {
;         fa[(i + 1) & 1][0] = *(const bf16x8*)(As + (i + 1) * 16);
;         fa[(i + 1) & 1][1] = *(const bf16x8*)(As + 32 * LDK + (i + 1) * 16);
;         fb[(i + 1) & 1][0] = *(const bf16x8*)(Bs + (i + 1) * 16);
;         fb[(i + 1) & 1][1] = *(const bf16x8*)(Bs + 32 * LDK + (i + 1) * 16);
;       }
;       __builtin_amdgcn_sched_barrier(0);
;       __builtin_amdgcn_s_setprio(1);
;       acc[0][0] = __builtin_amdgcn_mfma_f32_32x32x16_bf16(fa[i & 1][0], fb[i & 1][0], acc[0][0], 0, 0, 0);
;       acc[0][1] = __builtin_amdgcn_mfma_f32_32x32x16_bf16(fa[i & 1][0], fb[i & 1][1], acc[0][1], 0, 0, 0);
;       acc[1][0] = __builtin_amdgcn_mfma_f32_32x32x16_bf16(fa[i & 1][1], fb[i & 1][0], acc[1][0], 0, 0, 0);
;       acc[1][1] = __builtin_amdgcn_mfma_f32_32x32x16_bf16(fa[i & 1][1], fb[i & 1][1], acc[1][1], 0, 0, 0);
;       __builtin_amdgcn_s_setprio(0);
;     }
;     __syncthreads();
	global_load_dwordx4 v[130:133], v[64:65], off offset:640
	global_load_dwordx4 v[134:137], v[106:107], off offset:640
	ds_read_b128 v[146:149], v104 offset:36864
	ds_read_b128 v[150:153], v104 offset:41472
	ds_read_b128 v[154:157], v101 offset:55296
	ds_read_b128 v[158:161], v101 offset:59904
	s_waitcnt vmcnt(9)
	ds_write_b128 v100, v[66:69]
	s_waitcnt vmcnt(8)
	ds_write_b128 v100, v[110:113] offset:18432
	ds_read_b128 v[66:69], v104 offset:36896
	ds_read_b128 v[110:113], v104 offset:41504
	ds_read_b128 v[162:165], v101 offset:55328
	ds_read_b128 v[166:169], v101 offset:59936
	s_waitcnt lgkmcnt(7)
	v_mfma_f32_32x32x16_bf16 v[16:31], v[146:149], v[154:157], v[16:31]
	s_waitcnt lgkmcnt(6)
	v_mfma_f32_32x32x16_bf16 v[48:63], v[146:149], v[158:161], v[48:63]
	v_mfma_f32_32x32x16_bf16 v[0:15], v[150:153], v[154:157], v[0:15]
	v_mfma_f32_32x32x16_bf16 v[32:47], v[150:153], v[158:161], v[32:47]
	global_load_dwordx4 v[146:149], v[72:73], off offset:640
	global_load_dwordx4 v[150:153], v[76:77], off offset:640
	s_waitcnt vmcnt(9)
	ds_write_b128 v100, v[138:141] offset:4608
	s_waitcnt vmcnt(8)
	ds_write_b128 v100, v[142:145] offset:23040
	ds_read_b128 v[138:141], v104 offset:36928
	ds_read_b128 v[142:145], v104 offset:41536
	ds_read_b128 v[154:157], v101 offset:55360
	ds_read_b128 v[158:161], v101 offset:59968
	s_waitcnt lgkmcnt(7)
	v_mfma_f32_32x32x16_bf16 v[16:31], v[66:69], v[162:165], v[16:31]
	s_waitcnt lgkmcnt(6)
	v_mfma_f32_32x32x16_bf16 v[48:63], v[66:69], v[166:169], v[48:63]
	v_mfma_f32_32x32x16_bf16 v[0:15], v[110:113], v[162:165], v[0:15]
	v_mfma_f32_32x32x16_bf16 v[32:47], v[110:113], v[166:169], v[32:47]
	global_load_dwordx4 v[66:69], v[80:81], off offset:640
	global_load_dwordx4 v[110:113], v[84:85], off offset:640
	s_waitcnt vmcnt(9)
	ds_write_b128 v100, v[114:117] offset:9216
	s_waitcnt vmcnt(8)
	ds_write_b128 v100, v[118:121] offset:27648
	ds_read_b128 v[114:117], v104 offset:36960
	ds_read_b128 v[118:121], v104 offset:41568
	ds_read_b128 v[162:165], v101 offset:55392
	ds_read_b128 v[166:169], v101 offset:60000
	s_waitcnt lgkmcnt(7)
	v_mfma_f32_32x32x16_bf16 v[16:31], v[138:141], v[154:157], v[16:31]
	s_waitcnt lgkmcnt(6)
	v_mfma_f32_32x32x16_bf16 v[48:63], v[138:141], v[158:161], v[48:63]
	v_mfma_f32_32x32x16_bf16 v[0:15], v[142:145], v[154:157], v[0:15]
	v_mfma_f32_32x32x16_bf16 v[32:47], v[142:145], v[158:161], v[32:47]
	global_load_dwordx4 v[138:141], v[88:89], off offset:640
	global_load_dwordx4 v[142:145], v[92:93], off offset:640
	s_waitcnt vmcnt(9)
	ds_write_b128 v100, v[122:125] offset:13824
	s_waitcnt vmcnt(8)
	ds_write_b128 v100, v[126:129] offset:32256
	s_waitcnt lgkmcnt(3)
	v_mfma_f32_32x32x16_bf16 v[16:31], v[114:117], v[162:165], v[16:31]
	s_waitcnt lgkmcnt(2)
	v_mfma_f32_32x32x16_bf16 v[48:63], v[114:117], v[166:169], v[48:63]
	v_mfma_f32_32x32x16_bf16 v[0:15], v[118:121], v[162:165], v[0:15]
	v_mfma_f32_32x32x16_bf16 v[32:47], v[118:121], v[166:169], v[32:47]
	s_waitcnt lgkmcnt(0)
	s_barrier
	global_load_dwordx4 v[114:117], v[64:65], off offset:768
	global_load_dwordx4 v[118:121], v[106:107], off offset:768
	ds_read_b128 v[122:125], v104
	ds_read_b128 v[126:129], v104 offset:4608
	ds_read_b128 v[154:157], v101 offset:18432
	ds_read_b128 v[158:161], v101 offset:23040
	s_waitcnt vmcnt(9)
	ds_write_b128 v100, v[130:133] offset:36864
	s_waitcnt vmcnt(8)
	ds_write_b128 v100, v[134:137] offset:55296
	ds_read_b128 v[130:133], v104 offset:32
	ds_read_b128 v[134:137], v104 offset:4640
	ds_read_b128 v[162:165], v101 offset:18464
	ds_read_b128 v[166:169], v101 offset:23072
	s_waitcnt lgkmcnt(7)
	v_mfma_f32_32x32x16_bf16 v[16:31], v[122:125], v[154:157], v[16:31]
	s_waitcnt lgkmcnt(6)
	v_mfma_f32_32x32x16_bf16 v[48:63], v[122:125], v[158:161], v[48:63]
	v_mfma_f32_32x32x16_bf16 v[0:15], v[126:129], v[154:157], v[0:15]
	v_mfma_f32_32x32x16_bf16 v[32:47], v[126:129], v[158:161], v[32:47]
	global_load_dwordx4 v[122:125], v[72:73], off offset:768
	global_load_dwordx4 v[126:129], v[76:77], off offset:768
	s_waitcnt vmcnt(9)
	ds_write_b128 v100, v[146:149] offset:41472
	s_waitcnt vmcnt(8)
	ds_write_b128 v100, v[150:153] offset:59904
	ds_read_b128 v[146:149], v104 offset:64
	ds_read_b128 v[150:153], v104 offset:4672
	ds_read_b128 v[154:157], v101 offset:18496
	ds_read_b128 v[158:161], v101 offset:23104
	s_waitcnt lgkmcnt(7)
	v_mfma_f32_32x32x16_bf16 v[16:31], v[130:133], v[162:165], v[16:31]
	s_waitcnt lgkmcnt(6)
	v_mfma_f32_32x32x16_bf16 v[48:63], v[130:133], v[166:169], v[48:63]
	v_mfma_f32_32x32x16_bf16 v[0:15], v[134:137], v[162:165], v[0:15]
	v_mfma_f32_32x32x16_bf16 v[32:47], v[134:137], v[166:169], v[32:47]
	global_load_dwordx4 v[130:133], v[80:81], off offset:768
	global_load_dwordx4 v[134:137], v[84:85], off offset:768
	s_waitcnt vmcnt(9)
	ds_write_b128 v100, v[66:69] offset:46080
	s_waitcnt vmcnt(8)
	ds_write_b128 v100, v[110:113] offset:64512
	ds_read_b128 v[66:69], v104 offset:96
	ds_read_b128 v[110:113], v104 offset:4704
	ds_read_b128 v[162:165], v101 offset:18528
	ds_read_b128 v[166:169], v101 offset:23136
	s_waitcnt lgkmcnt(7)
	v_mfma_f32_32x32x16_bf16 v[16:31], v[146:149], v[154:157], v[16:31]
	s_waitcnt lgkmcnt(6)
	v_mfma_f32_32x32x16_bf16 v[48:63], v[146:149], v[158:161], v[48:63]
	v_mfma_f32_32x32x16_bf16 v[0:15], v[150:153], v[154:157], v[0:15]
	v_mfma_f32_32x32x16_bf16 v[32:47], v[150:153], v[158:161], v[32:47]
	global_load_dwordx4 v[146:149], v[88:89], off offset:768
	global_load_dwordx4 v[150:153], v[92:93], off offset:768
	s_waitcnt vmcnt(9)
	ds_write_b128 v100, v[138:141] offset:50688
	s_waitcnt vmcnt(8)
	ds_write_b128 v105, v[142:145] offset:13824
	s_waitcnt lgkmcnt(3)
	v_mfma_f32_32x32x16_bf16 v[16:31], v[66:69], v[162:165], v[16:31]
	s_waitcnt lgkmcnt(2)
	v_mfma_f32_32x32x16_bf16 v[48:63], v[66:69], v[166:169], v[48:63]
	v_mfma_f32_32x32x16_bf16 v[0:15], v[110:113], v[162:165], v[0:15]
	v_mfma_f32_32x32x16_bf16 v[32:47], v[110:113], v[166:169], v[32:47]
	s_waitcnt lgkmcnt(0)
	s_barrier
; __device__ __forceinline__ void gemm_run(int tid, f32x16 (&acc)[2][2], GRegs& g, const GOp& o, int K, unsigned char* smem) {
;     ...
;     bf16r* cur = sbuf + (k & 1) * (256 * LDK);
;     bf16r* nxt = sbuf + ((k & 1) ^ 1) * (256 * LDK);
;     const bf16r* As = cur + (wm * 64 + fr) * LDK + fh * 8;
;     const bf16r* Bs = cur + 128 * LDK + (wn * 64 + fr) * LDK + fh * 8;
;     const bool wr = (k + 1 < nk), ld = (k + 2 < nk);
;     bf16x8 fa[2][2], fb[2][2];
;     fa[0][0] = *(const bf16x8*)(As);
;     fa[0][1] = *(const bf16x8*)(As + 32 * LDK);
;     fb[0][0] = *(const bf16x8*)(Bs);
;     fb[0][1] = *(const bf16x8*)(Bs + 32 * LDK);
; #pragma unroll
;     for (int i = 0; i < 4; i++) {
;       if (wr) {
;         *(u32x4*)(nxt + (r0 + i * 32) * LDK + sg * 8) = g.a[i];
;         *(u32x4*)(nxt + 128 * LDK + (r0 + i * 32) * LDK + sg * 8) = g.b[i];
;       }
;       if (ld) {
;         g.a[i] = *(const u32x4*)(Ap + (size_t)i * 32 * o.lda + (k + 2) * 64);
;         g.b[i] = *(const u32x4*)(Bp + o.bs.o[i] + (k + 2) * 64);
;       }
;       if (i < 3) {
;         fa[(i + 1) & 1][0] = *(const bf16x8*)(As + (i + 1) * 16);
;         fa[(i + 1) & 1][1] = *(const bf16x8*)(As + 32 * LDK + (i + 1) * 16);
;         fb[(i + 1) & 1][0] = *(const bf16x8*)(Bs + (i + 1) * 16);
;         fb[(i + 1) & 1][1] = *(const bf16x8*)(Bs + 32 * LDK + (i + 1) * 16);
;       }
;       __builtin_amdgcn_sched_barrier(0);
;       __builtin_amdgcn_s_setprio(1);
;       acc[0][0] = __builtin_amdgcn_mfma_f32_32x32x16_bf16(fa[i & 1][0], fb[i & 1][0], acc[0][0], 0, 0, 0);
;       acc[0][1] = __builtin_amdgcn_mfma_f32_32x32x16_bf16(fa[i & 1][0], fb[i & 1][1], acc[0][1], 0, 0, 0);
;       acc[1][0] = __builtin_amdgcn_mfma_f32_32x32x16_bf16(fa[i & 1][1], fb[i & 1][0], acc[1][0], 0, 0, 0);
;       acc[1][1] = __builtin_amdgcn_mfma_f32_32x32x16_bf16(fa[i & 1][1], fb[i & 1][1], acc[1][1], 0, 0, 0);
;       __builtin_amdgcn_s_setprio(0);
;     }
;     __syncthreads();
	global_load_dwordx4 v[66:69], v[64:65], off offset:896
	global_load_dwordx4 v[110:113], v[106:107], off offset:896
	ds_read_b128 v[138:141], v104 offset:36864
	ds_read_b128 v[142:145], v104 offset:41472
	ds_read_b128 v[154:157], v101 offset:55296
	ds_read_b128 v[158:161], v101 offset:59904
	s_waitcnt vmcnt(9)
	ds_write_b128 v100, v[114:117]
	s_waitcnt vmcnt(8)
	ds_write_b128 v100, v[118:121] offset:18432
	ds_read_b128 v[114:117], v104 offset:36896
	ds_read_b128 v[118:121], v104 offset:41504
	ds_read_b128 v[162:165], v101 offset:55328
	ds_read_b128 v[166:169], v101 offset:59936
	s_waitcnt lgkmcnt(7)
	v_mfma_f32_32x32x16_bf16 v[16:31], v[138:141], v[154:157], v[16:31]
	s_waitcnt lgkmcnt(6)
	v_mfma_f32_32x32x16_bf16 v[48:63], v[138:141], v[158:161], v[48:63]
	v_mfma_f32_32x32x16_bf16 v[0:15], v[142:145], v[154:157], v[0:15]
	v_mfma_f32_32x32x16_bf16 v[32:47], v[142:145], v[158:161], v[32:47]
	global_load_dwordx4 v[138:141], v[72:73], off offset:896
	global_load_dwordx4 v[142:145], v[76:77], off offset:896
	s_waitcnt vmcnt(9)
	ds_write_b128 v100, v[122:125] offset:4608
	s_waitcnt vmcnt(8)
	ds_write_b128 v100, v[126:129] offset:23040
	ds_read_b128 v[122:125], v104 offset:36928
	ds_read_b128 v[126:129], v104 offset:41536
	ds_read_b128 v[154:157], v101 offset:55360
	ds_read_b128 v[158:161], v101 offset:59968
	s_waitcnt lgkmcnt(7)
	v_mfma_f32_32x32x16_bf16 v[16:31], v[114:117], v[162:165], v[16:31]
	s_waitcnt lgkmcnt(6)
	v_mfma_f32_32x32x16_bf16 v[48:63], v[114:117], v[166:169], v[48:63]
	v_mfma_f32_32x32x16_bf16 v[0:15], v[118:121], v[162:165], v[0:15]
	v_mfma_f32_32x32x16_bf16 v[32:47], v[118:121], v[166:169], v[32:47]
	global_load_dwordx4 v[114:117], v[80:81], off offset:896
	global_load_dwordx4 v[118:121], v[84:85], off offset:896
	s_waitcnt vmcnt(9)
	ds_write_b128 v100, v[130:133] offset:9216
	s_waitcnt vmcnt(8)
	ds_write_b128 v100, v[134:137] offset:27648
	ds_read_b128 v[130:133], v104 offset:36960
	ds_read_b128 v[134:137], v104 offset:41568
	ds_read_b128 v[162:165], v101 offset:55392
	ds_read_b128 v[166:169], v101 offset:60000
	s_waitcnt lgkmcnt(7)
	v_mfma_f32_32x32x16_bf16 v[16:31], v[122:125], v[154:157], v[16:31]
	s_waitcnt lgkmcnt(6)
	v_mfma_f32_32x32x16_bf16 v[48:63], v[122:125], v[158:161], v[48:63]
	v_mfma_f32_32x32x16_bf16 v[0:15], v[126:129], v[154:157], v[0:15]
	v_mfma_f32_32x32x16_bf16 v[32:47], v[126:129], v[158:161], v[32:47]
	global_load_dwordx4 v[122:125], v[88:89], off offset:896
	global_load_dwordx4 v[126:129], v[92:93], off offset:896
	s_waitcnt vmcnt(9)
	ds_write_b128 v100, v[146:149] offset:13824
	s_waitcnt vmcnt(8)
	ds_write_b128 v100, v[150:153] offset:32256
	s_waitcnt lgkmcnt(3)
	v_mfma_f32_32x32x16_bf16 v[16:31], v[130:133], v[162:165], v[16:31]
	s_waitcnt lgkmcnt(2)
	v_mfma_f32_32x32x16_bf16 v[48:63], v[130:133], v[166:169], v[48:63]
	v_mfma_f32_32x32x16_bf16 v[0:15], v[134:137], v[162:165], v[0:15]
	v_mfma_f32_32x32x16_bf16 v[32:47], v[134:137], v[166:169], v[32:47]
	s_waitcnt lgkmcnt(0)
	s_barrier
	global_load_dwordx4 v[130:133], v[64:65], off offset:1024
	global_load_dwordx4 v[134:137], v[106:107], off offset:1024
	ds_read_b128 v[146:149], v104
	ds_read_b128 v[150:153], v104 offset:4608
	ds_read_b128 v[154:157], v101 offset:18432
	ds_read_b128 v[158:161], v101 offset:23040
	s_waitcnt vmcnt(9)
	ds_write_b128 v100, v[66:69] offset:36864
	s_waitcnt vmcnt(8)
	ds_write_b128 v100, v[110:113] offset:55296
	ds_read_b128 v[66:69], v104 offset:32
	ds_read_b128 v[110:113], v104 offset:4640
	ds_read_b128 v[162:165], v101 offset:18464
	ds_read_b128 v[166:169], v101 offset:23072
	s_waitcnt lgkmcnt(7)
	v_mfma_f32_32x32x16_bf16 v[16:31], v[146:149], v[154:157], v[16:31]
	s_waitcnt lgkmcnt(6)
	v_mfma_f32_32x32x16_bf16 v[48:63], v[146:149], v[158:161], v[48:63]
	v_mfma_f32_32x32x16_bf16 v[0:15], v[150:153], v[154:157], v[0:15]
	v_mfma_f32_32x32x16_bf16 v[32:47], v[150:153], v[158:161], v[32:47]
	global_load_dwordx4 v[146:149], v[72:73], off offset:1024
	global_load_dwordx4 v[150:153], v[76:77], off offset:1024
	s_waitcnt vmcnt(9)
	ds_write_b128 v100, v[138:141] offset:41472
	s_waitcnt vmcnt(8)
	ds_write_b128 v100, v[142:145] offset:59904
	ds_read_b128 v[138:141], v104 offset:64
	ds_read_b128 v[142:145], v104 offset:4672
	ds_read_b128 v[154:157], v101 offset:18496
	ds_read_b128 v[158:161], v101 offset:23104
	s_waitcnt lgkmcnt(7)
	v_mfma_f32_32x32x16_bf16 v[16:31], v[66:69], v[162:165], v[16:31]
	s_waitcnt lgkmcnt(6)
	v_mfma_f32_32x32x16_bf16 v[48:63], v[66:69], v[166:169], v[48:63]
	v_mfma_f32_32x32x16_bf16 v[0:15], v[110:113], v[162:165], v[0:15]
	v_mfma_f32_32x32x16_bf16 v[32:47], v[110:113], v[166:169], v[32:47]
	global_load_dwordx4 v[66:69], v[80:81], off offset:1024
	global_load_dwordx4 v[110:113], v[84:85], off offset:1024
	s_waitcnt vmcnt(9)
	ds_write_b128 v100, v[114:117] offset:46080
	s_waitcnt vmcnt(8)
	ds_write_b128 v100, v[118:121] offset:64512
	ds_read_b128 v[114:117], v104 offset:96
	ds_read_b128 v[118:121], v104 offset:4704
	ds_read_b128 v[162:165], v101 offset:18528
	ds_read_b128 v[166:169], v101 offset:23136
	s_waitcnt lgkmcnt(7)
	v_mfma_f32_32x32x16_bf16 v[16:31], v[138:141], v[154:157], v[16:31]
	s_waitcnt lgkmcnt(6)
	v_mfma_f32_32x32x16_bf16 v[48:63], v[138:141], v[158:161], v[48:63]
	v_mfma_f32_32x32x16_bf16 v[0:15], v[142:145], v[154:157], v[0:15]
	v_mfma_f32_32x32x16_bf16 v[32:47], v[142:145], v[158:161], v[32:47]
	global_load_dwordx4 v[138:141], v[88:89], off offset:1024
	global_load_dwordx4 v[142:145], v[92:93], off offset:1024
	s_waitcnt vmcnt(9)
	ds_write_b128 v100, v[122:125] offset:50688
	s_waitcnt vmcnt(8)
	ds_write_b128 v105, v[126:129] offset:13824
	s_waitcnt lgkmcnt(3)
	v_mfma_f32_32x32x16_bf16 v[16:31], v[114:117], v[162:165], v[16:31]
	s_waitcnt lgkmcnt(2)
	v_mfma_f32_32x32x16_bf16 v[48:63], v[114:117], v[166:169], v[48:63]
	v_mfma_f32_32x32x16_bf16 v[0:15], v[118:121], v[162:165], v[0:15]
	v_mfma_f32_32x32x16_bf16 v[32:47], v[118:121], v[166:169], v[32:47]
	s_waitcnt lgkmcnt(0)
	s_barrier
; __device__ __forceinline__ void gemm_run(int tid, f32x16 (&acc)[2][2], GRegs& g, const GOp& o, int K, unsigned char* smem) {
;     ...
;     bf16r* cur = sbuf + (k & 1) * (256 * LDK);
;     bf16r* nxt = sbuf + ((k & 1) ^ 1) * (256 * LDK);
;     const bf16r* As = cur + (wm * 64 + fr) * LDK + fh * 8;
;     const bf16r* Bs = cur + 128 * LDK + (wn * 64 + fr) * LDK + fh * 8;
;     const bool wr = (k + 1 < nk), ld = (k + 2 < nk);
;     bf16x8 fa[2][2], fb[2][2];
;     fa[0][0] = *(const bf16x8*)(As);
;     fa[0][1] = *(const bf16x8*)(As + 32 * LDK);
;     fb[0][0] = *(const bf16x8*)(Bs);
;     fb[0][1] = *(const bf16x8*)(Bs + 32 * LDK);
; #pragma unroll
;     for (int i = 0; i < 4; i++) {
;       if (wr) {
;         *(u32x4*)(nxt + (r0 + i * 32) * LDK + sg * 8) = g.a[i];
;         *(u32x4*)(nxt + 128 * LDK + (r0 + i * 32) * LDK + sg * 8) = g.b[i];
;       }
;       if (ld) {
;         g.a[i] = *(const u32x4*)(Ap + (size_t)i * 32 * o.lda + (k + 2) * 64);
;         g.b[i] = *(const u32x4*)(Bp + o.bs.o[i] + (k + 2) * 64);
;       }
;       if (i < 3) {
;         fa[(i + 1) & 1][0] = *(const bf16x8*)(As + (i + 1) * 16);
;         fa[(i + 1) & 1][1] = *(const bf16x8*)(As + 32 * LDK + (i + 1) * 16);
;         fb[(i + 1) & 1][0] = *(const bf16x8*)(Bs + (i + 1) * 16);
;         fb[(i + 1) & 1][1] = *(const bf16x8*)(Bs + 32 * LDK + (i + 1) * 16);
;       }
;       __builtin_amdgcn_sched_barrier(0);
;       __builtin_amdgcn_s_setprio(1);
;       acc[0][0] = __builtin_amdgcn_mfma_f32_32x32x16_bf16(fa[i & 1][0], fb[i & 1][0], acc[0][0], 0, 0, 0);
;       acc[0][1] = __builtin_amdgcn_mfma_f32_32x32x16_bf16(fa[i & 1][0], fb[i & 1][1], acc[0][1], 0, 0, 0);
;       acc[1][0] = __builtin_amdgcn_mfma_f32_32x32x16_bf16(fa[i & 1][1], fb[i & 1][0], acc[1][0], 0, 0, 0);
;       acc[1][1] = __builtin_amdgcn_mfma_f32_32x32x16_bf16(fa[i & 1][1], fb[i & 1][1], acc[1][1], 0, 0, 0);
;       __builtin_amdgcn_s_setprio(0);
;     }
;     __syncthreads();
	global_load_dwordx4 v[114:117], v[64:65], off offset:1152
	global_load_dwordx4 v[118:121], v[106:107], off offset:1152
	ds_read_b128 v[122:125], v104 offset:36864
	ds_read_b128 v[126:129], v104 offset:41472
	ds_read_b128 v[154:157], v101 offset:55296
	ds_read_b128 v[158:161], v101 offset:59904
	s_waitcnt vmcnt(9)
	ds_write_b128 v100, v[130:133]
	s_waitcnt vmcnt(8)
	ds_write_b128 v100, v[134:137] offset:18432
	ds_read_b128 v[130:133], v104 offset:36896
	ds_read_b128 v[134:137], v104 offset:41504
	ds_read_b128 v[162:165], v101 offset:55328
	ds_read_b128 v[166:169], v101 offset:59936
	s_waitcnt lgkmcnt(7)
	v_mfma_f32_32x32x16_bf16 v[16:31], v[122:125], v[154:157], v[16:31]
	s_waitcnt lgkmcnt(6)
	v_mfma_f32_32x32x16_bf16 v[48:63], v[122:125], v[158:161], v[48:63]
	v_mfma_f32_32x32x16_bf16 v[0:15], v[126:129], v[154:157], v[0:15]
	v_mfma_f32_32x32x16_bf16 v[32:47], v[126:129], v[158:161], v[32:47]
	global_load_dwordx4 v[122:125], v[72:73], off offset:1152
	global_load_dwordx4 v[126:129], v[76:77], off offset:1152
	s_waitcnt vmcnt(9)
	ds_write_b128 v100, v[146:149] offset:4608
	s_waitcnt vmcnt(8)
	ds_write_b128 v100, v[150:153] offset:23040
	ds_read_b128 v[146:149], v104 offset:36928
	ds_read_b128 v[150:153], v104 offset:41536
	ds_read_b128 v[154:157], v101 offset:55360
	ds_read_b128 v[158:161], v101 offset:59968
	s_waitcnt lgkmcnt(7)
	v_mfma_f32_32x32x16_bf16 v[16:31], v[130:133], v[162:165], v[16:31]
	s_waitcnt lgkmcnt(6)
	v_mfma_f32_32x32x16_bf16 v[48:63], v[130:133], v[166:169], v[48:63]
	v_mfma_f32_32x32x16_bf16 v[0:15], v[134:137], v[162:165], v[0:15]
	v_mfma_f32_32x32x16_bf16 v[32:47], v[134:137], v[166:169], v[32:47]
	global_load_dwordx4 v[130:133], v[80:81], off offset:1152
	global_load_dwordx4 v[134:137], v[84:85], off offset:1152
	s_waitcnt vmcnt(9)
	ds_write_b128 v100, v[66:69] offset:9216
	s_waitcnt vmcnt(8)
	ds_write_b128 v100, v[110:113] offset:27648
	ds_read_b128 v[66:69], v104 offset:36960
	ds_read_b128 v[110:113], v104 offset:41568
	ds_read_b128 v[162:165], v101 offset:55392
	ds_read_b128 v[166:169], v101 offset:60000
	s_waitcnt lgkmcnt(7)
	v_mfma_f32_32x32x16_bf16 v[16:31], v[146:149], v[154:157], v[16:31]
	s_waitcnt lgkmcnt(6)
	v_mfma_f32_32x32x16_bf16 v[48:63], v[146:149], v[158:161], v[48:63]
	v_mfma_f32_32x32x16_bf16 v[0:15], v[150:153], v[154:157], v[0:15]
	v_mfma_f32_32x32x16_bf16 v[32:47], v[150:153], v[158:161], v[32:47]
	global_load_dwordx4 v[146:149], v[88:89], off offset:1152
	global_load_dwordx4 v[150:153], v[92:93], off offset:1152
	s_waitcnt vmcnt(9)
	ds_write_b128 v100, v[138:141] offset:13824
	s_waitcnt vmcnt(8)
	ds_write_b128 v100, v[142:145] offset:32256
	s_waitcnt lgkmcnt(3)
	v_mfma_f32_32x32x16_bf16 v[16:31], v[66:69], v[162:165], v[16:31]
	s_waitcnt lgkmcnt(2)
	v_mfma_f32_32x32x16_bf16 v[48:63], v[66:69], v[166:169], v[48:63]
	v_mfma_f32_32x32x16_bf16 v[0:15], v[110:113], v[162:165], v[0:15]
	v_mfma_f32_32x32x16_bf16 v[32:47], v[110:113], v[166:169], v[32:47]
	s_waitcnt lgkmcnt(0)
	s_barrier
	global_load_dwordx4 v[66:69], v[64:65], off offset:1280
	global_load_dwordx4 v[110:113], v[106:107], off offset:1280
	ds_read_b128 v[138:141], v104
	ds_read_b128 v[142:145], v104 offset:4608
	ds_read_b128 v[154:157], v101 offset:18432
	ds_read_b128 v[158:161], v101 offset:23040
	s_waitcnt vmcnt(9)
	ds_write_b128 v100, v[114:117] offset:36864
	s_waitcnt vmcnt(8)
	ds_write_b128 v100, v[118:121] offset:55296
	ds_read_b128 v[114:117], v104 offset:32
	ds_read_b128 v[118:121], v104 offset:4640
	ds_read_b128 v[162:165], v101 offset:18464
	ds_read_b128 v[166:169], v101 offset:23072
	s_waitcnt lgkmcnt(7)
	v_mfma_f32_32x32x16_bf16 v[16:31], v[138:141], v[154:157], v[16:31]
	s_waitcnt lgkmcnt(6)
	v_mfma_f32_32x32x16_bf16 v[48:63], v[138:141], v[158:161], v[48:63]
	v_mfma_f32_32x32x16_bf16 v[0:15], v[142:145], v[154:157], v[0:15]
	v_mfma_f32_32x32x16_bf16 v[32:47], v[142:145], v[158:161], v[32:47]
	global_load_dwordx4 v[138:141], v[72:73], off offset:1280
	global_load_dwordx4 v[142:145], v[76:77], off offset:1280
	s_waitcnt vmcnt(9)
	ds_write_b128 v100, v[122:125] offset:41472
	s_waitcnt vmcnt(8)
	ds_write_b128 v100, v[126:129] offset:59904
	ds_read_b128 v[122:125], v104 offset:64
	ds_read_b128 v[126:129], v104 offset:4672
	ds_read_b128 v[154:157], v101 offset:18496
	ds_read_b128 v[158:161], v101 offset:23104
	s_waitcnt lgkmcnt(7)
	v_mfma_f32_32x32x16_bf16 v[16:31], v[114:117], v[162:165], v[16:31]
	s_waitcnt lgkmcnt(6)
	v_mfma_f32_32x32x16_bf16 v[48:63], v[114:117], v[166:169], v[48:63]
	v_mfma_f32_32x32x16_bf16 v[0:15], v[118:121], v[162:165], v[0:15]
	v_mfma_f32_32x32x16_bf16 v[32:47], v[118:121], v[166:169], v[32:47]
	global_load_dwordx4 v[114:117], v[80:81], off offset:1280
	global_load_dwordx4 v[118:121], v[84:85], off offset:1280
	s_waitcnt vmcnt(9)
	ds_write_b128 v100, v[130:133] offset:46080
	s_waitcnt vmcnt(8)
	ds_write_b128 v100, v[134:137] offset:64512
	ds_read_b128 v[130:133], v104 offset:96
	ds_read_b128 v[134:137], v104 offset:4704
	ds_read_b128 v[162:165], v101 offset:18528
	ds_read_b128 v[166:169], v101 offset:23136
	s_waitcnt lgkmcnt(7)
	v_mfma_f32_32x32x16_bf16 v[16:31], v[122:125], v[154:157], v[16:31]
	s_waitcnt lgkmcnt(6)
	v_mfma_f32_32x32x16_bf16 v[48:63], v[122:125], v[158:161], v[48:63]
	v_mfma_f32_32x32x16_bf16 v[0:15], v[126:129], v[154:157], v[0:15]
	v_mfma_f32_32x32x16_bf16 v[32:47], v[126:129], v[158:161], v[32:47]
	global_load_dwordx4 v[122:125], v[88:89], off offset:1280
	global_load_dwordx4 v[126:129], v[92:93], off offset:1280
	s_waitcnt vmcnt(9)
	ds_write_b128 v100, v[146:149] offset:50688
	s_waitcnt vmcnt(8)
	ds_write_b128 v105, v[150:153] offset:13824
	s_waitcnt lgkmcnt(3)
	v_mfma_f32_32x32x16_bf16 v[16:31], v[130:133], v[162:165], v[16:31]
	s_waitcnt lgkmcnt(2)
	v_mfma_f32_32x32x16_bf16 v[48:63], v[130:133], v[166:169], v[48:63]
	v_mfma_f32_32x32x16_bf16 v[0:15], v[134:137], v[162:165], v[0:15]
	v_mfma_f32_32x32x16_bf16 v[32:47], v[134:137], v[166:169], v[32:47]
	s_waitcnt lgkmcnt(0)
	s_barrier
; __device__ __forceinline__ void gemm_run(int tid, f32x16 (&acc)[2][2], GRegs& g, const GOp& o, int K, unsigned char* smem) {
;     ...
;     bf16r* cur = sbuf + (k & 1) * (256 * LDK);
;     bf16r* nxt = sbuf + ((k & 1) ^ 1) * (256 * LDK);
;     const bf16r* As = cur + (wm * 64 + fr) * LDK + fh * 8;
;     const bf16r* Bs = cur + 128 * LDK + (wn * 64 + fr) * LDK + fh * 8;
;     const bool wr = (k + 1 < nk), ld = (k + 2 < nk);
;     bf16x8 fa[2][2], fb[2][2];
;     fa[0][0] = *(const bf16x8*)(As);
;     fa[0][1] = *(const bf16x8*)(As + 32 * LDK);
;     fb[0][0] = *(const bf16x8*)(Bs);
;     fb[0][1] = *(const bf16x8*)(Bs + 32 * LDK);
; #pragma unroll
;     for (int i = 0; i < 4; i++) {
;       if (wr) {
;         *(u32x4*)(nxt + (r0 + i * 32) * LDK + sg * 8) = g.a[i];
;         *(u32x4*)(nxt + 128 * LDK + (r0 + i * 32) * LDK + sg * 8) = g.b[i];
;       }
;       if (ld) {
;         g.a[i] = *(const u32x4*)(Ap + (size_t)i * 32 * o.lda + (k + 2) * 64);
;         g.b[i] = *(const u32x4*)(Bp + o.bs.o[i] + (k + 2) * 64);
;       }
;       if (i < 3) {
;         fa[(i + 1) & 1][0] = *(const bf16x8*)(As + (i + 1) * 16);
;         fa[(i + 1) & 1][1] = *(const bf16x8*)(As + 32 * LDK + (i + 1) * 16);
;         fb[(i + 1) & 1][0] = *(const bf16x8*)(Bs + (i + 1) * 16);
;         fb[(i + 1) & 1][1] = *(const bf16x8*)(Bs + 32 * LDK + (i + 1) * 16);
;       }
;       __builtin_amdgcn_sched_barrier(0);
;       __builtin_amdgcn_s_setprio(1);
;       acc[0][0] = __builtin_amdgcn_mfma_f32_32x32x16_bf16(fa[i & 1][0], fb[i & 1][0], acc[0][0], 0, 0, 0);
;       acc[0][1] = __builtin_amdgcn_mfma_f32_32x32x16_bf16(fa[i & 1][0], fb[i & 1][1], acc[0][1], 0, 0, 0);
;       acc[1][0] = __builtin_amdgcn_mfma_f32_32x32x16_bf16(fa[i & 1][1], fb[i & 1][0], acc[1][0], 0, 0, 0);
;       acc[1][1] = __builtin_amdgcn_mfma_f32_32x32x16_bf16(fa[i & 1][1], fb[i & 1][1], acc[1][1], 0, 0, 0);
;       __builtin_amdgcn_s_setprio(0);
;     }
;     __syncthreads();
	global_load_dwordx4 v[130:133], v[64:65], off offset:1408
	global_load_dwordx4 v[134:137], v[106:107], off offset:1408
	ds_read_b128 v[146:149], v104 offset:36864
	ds_read_b128 v[150:153], v104 offset:41472
	ds_read_b128 v[154:157], v101 offset:55296
	ds_read_b128 v[158:161], v101 offset:59904
	s_waitcnt vmcnt(9)
	ds_write_b128 v100, v[66:69]
	s_waitcnt vmcnt(8)
	ds_write_b128 v100, v[110:113] offset:18432
	ds_read_b128 v[66:69], v104 offset:36896
	ds_read_b128 v[110:113], v104 offset:41504
	ds_read_b128 v[162:165], v101 offset:55328
	ds_read_b128 v[166:169], v101 offset:59936
	s_waitcnt lgkmcnt(7)
	v_mfma_f32_32x32x16_bf16 v[16:31], v[146:149], v[154:157], v[16:31]
	s_waitcnt lgkmcnt(6)
	v_mfma_f32_32x32x16_bf16 v[48:63], v[146:149], v[158:161], v[48:63]
	v_mfma_f32_32x32x16_bf16 v[0:15], v[150:153], v[154:157], v[0:15]
	v_mfma_f32_32x32x16_bf16 v[32:47], v[150:153], v[158:161], v[32:47]
	global_load_dwordx4 v[146:149], v[72:73], off offset:1408
	global_load_dwordx4 v[150:153], v[76:77], off offset:1408
	s_waitcnt vmcnt(9)
	ds_write_b128 v100, v[138:141] offset:4608
	s_waitcnt vmcnt(8)
	ds_write_b128 v100, v[142:145] offset:23040
	ds_read_b128 v[138:141], v104 offset:36928
	ds_read_b128 v[142:145], v104 offset:41536
	ds_read_b128 v[154:157], v101 offset:55360
	ds_read_b128 v[158:161], v101 offset:59968
	s_waitcnt lgkmcnt(7)
	v_mfma_f32_32x32x16_bf16 v[16:31], v[66:69], v[162:165], v[16:31]
	s_waitcnt lgkmcnt(6)
	v_mfma_f32_32x32x16_bf16 v[48:63], v[66:69], v[166:169], v[48:63]
	v_mfma_f32_32x32x16_bf16 v[0:15], v[110:113], v[162:165], v[0:15]
	v_mfma_f32_32x32x16_bf16 v[32:47], v[110:113], v[166:169], v[32:47]
	global_load_dwordx4 v[66:69], v[80:81], off offset:1408
	global_load_dwordx4 v[110:113], v[84:85], off offset:1408
	s_waitcnt vmcnt(9)
	ds_write_b128 v100, v[114:117] offset:9216
	s_waitcnt vmcnt(8)
	ds_write_b128 v100, v[118:121] offset:27648
	ds_read_b128 v[114:117], v104 offset:36960
	ds_read_b128 v[118:121], v104 offset:41568
	ds_read_b128 v[162:165], v101 offset:55392
	ds_read_b128 v[166:169], v101 offset:60000
	s_waitcnt lgkmcnt(7)
	v_mfma_f32_32x32x16_bf16 v[16:31], v[138:141], v[154:157], v[16:31]
	s_waitcnt lgkmcnt(6)
	v_mfma_f32_32x32x16_bf16 v[48:63], v[138:141], v[158:161], v[48:63]
	v_mfma_f32_32x32x16_bf16 v[0:15], v[142:145], v[154:157], v[0:15]
	v_mfma_f32_32x32x16_bf16 v[32:47], v[142:145], v[158:161], v[32:47]
	global_load_dwordx4 v[138:141], v[88:89], off offset:1408
	global_load_dwordx4 v[142:145], v[92:93], off offset:1408
	s_waitcnt vmcnt(9)
	ds_write_b128 v100, v[122:125] offset:13824
	s_waitcnt vmcnt(8)
	ds_write_b128 v100, v[126:129] offset:32256
	s_waitcnt lgkmcnt(3)
	v_mfma_f32_32x32x16_bf16 v[16:31], v[114:117], v[162:165], v[16:31]
	s_waitcnt lgkmcnt(2)
	v_mfma_f32_32x32x16_bf16 v[48:63], v[114:117], v[166:169], v[48:63]
	v_mfma_f32_32x32x16_bf16 v[0:15], v[118:121], v[162:165], v[0:15]
	v_mfma_f32_32x32x16_bf16 v[32:47], v[118:121], v[166:169], v[32:47]
	s_waitcnt lgkmcnt(0)
	s_barrier
	global_load_dwordx4 v[114:117], v[64:65], off offset:1536
	global_load_dwordx4 v[118:121], v[106:107], off offset:1536
	ds_read_b128 v[122:125], v104
	ds_read_b128 v[126:129], v104 offset:4608
	ds_read_b128 v[154:157], v101 offset:18432
	ds_read_b128 v[158:161], v101 offset:23040
	s_waitcnt vmcnt(9)
	ds_write_b128 v100, v[130:133] offset:36864
	s_waitcnt vmcnt(8)
	ds_write_b128 v100, v[134:137] offset:55296
	ds_read_b128 v[130:133], v104 offset:32
	ds_read_b128 v[134:137], v104 offset:4640
	ds_read_b128 v[162:165], v101 offset:18464
	ds_read_b128 v[166:169], v101 offset:23072
	s_waitcnt lgkmcnt(7)
	v_mfma_f32_32x32x16_bf16 v[16:31], v[122:125], v[154:157], v[16:31]
	s_waitcnt lgkmcnt(6)
	v_mfma_f32_32x32x16_bf16 v[48:63], v[122:125], v[158:161], v[48:63]
	v_mfma_f32_32x32x16_bf16 v[0:15], v[126:129], v[154:157], v[0:15]
	v_mfma_f32_32x32x16_bf16 v[32:47], v[126:129], v[158:161], v[32:47]
	global_load_dwordx4 v[122:125], v[72:73], off offset:1536
	global_load_dwordx4 v[126:129], v[76:77], off offset:1536
	s_waitcnt vmcnt(9)
	ds_write_b128 v100, v[146:149] offset:41472
	s_waitcnt vmcnt(8)
	ds_write_b128 v100, v[150:153] offset:59904
	ds_read_b128 v[146:149], v104 offset:64
	ds_read_b128 v[150:153], v104 offset:4672
	ds_read_b128 v[154:157], v101 offset:18496
	ds_read_b128 v[158:161], v101 offset:23104
	s_waitcnt lgkmcnt(7)
	v_mfma_f32_32x32x16_bf16 v[16:31], v[130:133], v[162:165], v[16:31]
	s_waitcnt lgkmcnt(6)
	v_mfma_f32_32x32x16_bf16 v[48:63], v[130:133], v[166:169], v[48:63]
	v_mfma_f32_32x32x16_bf16 v[0:15], v[134:137], v[162:165], v[0:15]
	v_mfma_f32_32x32x16_bf16 v[32:47], v[134:137], v[166:169], v[32:47]
	global_load_dwordx4 v[130:133], v[80:81], off offset:1536
	global_load_dwordx4 v[134:137], v[84:85], off offset:1536
	s_waitcnt vmcnt(9)
	ds_write_b128 v100, v[66:69] offset:46080
	s_waitcnt vmcnt(8)
	ds_write_b128 v100, v[110:113] offset:64512
	ds_read_b128 v[66:69], v104 offset:96
	ds_read_b128 v[110:113], v104 offset:4704
	ds_read_b128 v[162:165], v101 offset:18528
	ds_read_b128 v[166:169], v101 offset:23136
	s_waitcnt lgkmcnt(7)
	v_mfma_f32_32x32x16_bf16 v[16:31], v[146:149], v[154:157], v[16:31]
	s_waitcnt lgkmcnt(6)
	v_mfma_f32_32x32x16_bf16 v[48:63], v[146:149], v[158:161], v[48:63]
	v_mfma_f32_32x32x16_bf16 v[0:15], v[150:153], v[154:157], v[0:15]
	v_mfma_f32_32x32x16_bf16 v[32:47], v[150:153], v[158:161], v[32:47]
	global_load_dwordx4 v[146:149], v[88:89], off offset:1536
	global_load_dwordx4 v[150:153], v[92:93], off offset:1536
	s_waitcnt vmcnt(9)
	ds_write_b128 v100, v[138:141] offset:50688
	s_waitcnt vmcnt(8)
	ds_write_b128 v105, v[142:145] offset:13824
	s_waitcnt lgkmcnt(3)
	v_mfma_f32_32x32x16_bf16 v[16:31], v[66:69], v[162:165], v[16:31]
	s_waitcnt lgkmcnt(2)
	v_mfma_f32_32x32x16_bf16 v[48:63], v[66:69], v[166:169], v[48:63]
	v_mfma_f32_32x32x16_bf16 v[0:15], v[110:113], v[162:165], v[0:15]
	v_mfma_f32_32x32x16_bf16 v[32:47], v[110:113], v[166:169], v[32:47]
	s_waitcnt lgkmcnt(0)
	s_barrier
; __device__ __forceinline__ void gemm_run(int tid, f32x16 (&acc)[2][2], GRegs& g, const GOp& o, int K, unsigned char* smem) {
;     ...
;     bf16r* cur = sbuf + (k & 1) * (256 * LDK);
;     bf16r* nxt = sbuf + ((k & 1) ^ 1) * (256 * LDK);
;     const bf16r* As = cur + (wm * 64 + fr) * LDK + fh * 8;
;     const bf16r* Bs = cur + 128 * LDK + (wn * 64 + fr) * LDK + fh * 8;
;     const bool wr = (k + 1 < nk), ld = (k + 2 < nk);
;     bf16x8 fa[2][2], fb[2][2];
;     fa[0][0] = *(const bf16x8*)(As);
;     fa[0][1] = *(const bf16x8*)(As + 32 * LDK);
;     fb[0][0] = *(const bf16x8*)(Bs);
;     fb[0][1] = *(const bf16x8*)(Bs + 32 * LDK);
; #pragma unroll
;     for (int i = 0; i < 4; i++) {
;       if (wr) {
;         *(u32x4*)(nxt + (r0 + i * 32) * LDK + sg * 8) = g.a[i];
;         *(u32x4*)(nxt + 128 * LDK + (r0 + i * 32) * LDK + sg * 8) = g.b[i];
;       }
;       if (ld) {
;         g.a[i] = *(const u32x4*)(Ap + (size_t)i * 32 * o.lda + (k + 2) * 64);
;         g.b[i] = *(const u32x4*)(Bp + o.bs.o[i] + (k + 2) * 64);
;       }
;       if (i < 3) {
;         fa[(i + 1) & 1][0] = *(const bf16x8*)(As + (i + 1) * 16);
;         fa[(i + 1) & 1][1] = *(const bf16x8*)(As + 32 * LDK + (i + 1) * 16);
;         fb[(i + 1) & 1][0] = *(const bf16x8*)(Bs + (i + 1) * 16);
;         fb[(i + 1) & 1][1] = *(const bf16x8*)(Bs + 32 * LDK + (i + 1) * 16);
;       }
;       __builtin_amdgcn_sched_barrier(0);
;       __builtin_amdgcn_s_setprio(1);
;       acc[0][0] = __builtin_amdgcn_mfma_f32_32x32x16_bf16(fa[i & 1][0], fb[i & 1][0], acc[0][0], 0, 0, 0);
;       acc[0][1] = __builtin_amdgcn_mfma_f32_32x32x16_bf16(fa[i & 1][0], fb[i & 1][1], acc[0][1], 0, 0, 0);
;       acc[1][0] = __builtin_amdgcn_mfma_f32_32x32x16_bf16(fa[i & 1][1], fb[i & 1][0], acc[1][0], 0, 0, 0);
;       acc[1][1] = __builtin_amdgcn_mfma_f32_32x32x16_bf16(fa[i & 1][1], fb[i & 1][1], acc[1][1], 0, 0, 0);
;       __builtin_amdgcn_s_setprio(0);
;     }
;     __syncthreads();
	global_load_dwordx4 v[66:69], v[64:65], off offset:1664
	global_load_dwordx4 v[110:113], v[106:107], off offset:1664
	ds_read_b128 v[138:141], v104 offset:36864
	ds_read_b128 v[142:145], v104 offset:41472
	ds_read_b128 v[154:157], v101 offset:55296
	ds_read_b128 v[158:161], v101 offset:59904
	s_waitcnt vmcnt(9)
	ds_write_b128 v100, v[114:117]
	s_waitcnt vmcnt(8)
	ds_write_b128 v100, v[118:121] offset:18432
	ds_read_b128 v[114:117], v104 offset:36896
	ds_read_b128 v[118:121], v104 offset:41504
	ds_read_b128 v[162:165], v101 offset:55328
	ds_read_b128 v[166:169], v101 offset:59936
	s_waitcnt lgkmcnt(7)
	v_mfma_f32_32x32x16_bf16 v[16:31], v[138:141], v[154:157], v[16:31]
	s_waitcnt lgkmcnt(6)
	v_mfma_f32_32x32x16_bf16 v[48:63], v[138:141], v[158:161], v[48:63]
	v_mfma_f32_32x32x16_bf16 v[0:15], v[142:145], v[154:157], v[0:15]
	v_mfma_f32_32x32x16_bf16 v[32:47], v[142:145], v[158:161], v[32:47]
	global_load_dwordx4 v[138:141], v[72:73], off offset:1664
	global_load_dwordx4 v[142:145], v[76:77], off offset:1664
	s_waitcnt vmcnt(9)
	ds_write_b128 v100, v[122:125] offset:4608
	s_waitcnt vmcnt(8)
	ds_write_b128 v100, v[126:129] offset:23040
	ds_read_b128 v[122:125], v104 offset:36928
	ds_read_b128 v[126:129], v104 offset:41536
	ds_read_b128 v[154:157], v101 offset:55360
	ds_read_b128 v[158:161], v101 offset:59968
	s_waitcnt lgkmcnt(7)
	v_mfma_f32_32x32x16_bf16 v[16:31], v[114:117], v[162:165], v[16:31]
	s_waitcnt lgkmcnt(6)
	v_mfma_f32_32x32x16_bf16 v[48:63], v[114:117], v[166:169], v[48:63]
	v_mfma_f32_32x32x16_bf16 v[0:15], v[118:121], v[162:165], v[0:15]
	v_mfma_f32_32x32x16_bf16 v[32:47], v[118:121], v[166:169], v[32:47]
	global_load_dwordx4 v[114:117], v[80:81], off offset:1664
	global_load_dwordx4 v[118:121], v[84:85], off offset:1664
	s_waitcnt vmcnt(9)
	ds_write_b128 v100, v[130:133] offset:9216
	s_waitcnt vmcnt(8)
	ds_write_b128 v100, v[134:137] offset:27648
	ds_read_b128 v[130:133], v104 offset:36960
	ds_read_b128 v[134:137], v104 offset:41568
	ds_read_b128 v[162:165], v101 offset:55392
	ds_read_b128 v[166:169], v101 offset:60000
	s_waitcnt lgkmcnt(7)
	v_mfma_f32_32x32x16_bf16 v[16:31], v[122:125], v[154:157], v[16:31]
	s_waitcnt lgkmcnt(6)
	v_mfma_f32_32x32x16_bf16 v[48:63], v[122:125], v[158:161], v[48:63]
	v_mfma_f32_32x32x16_bf16 v[0:15], v[126:129], v[154:157], v[0:15]
	v_mfma_f32_32x32x16_bf16 v[32:47], v[126:129], v[158:161], v[32:47]
	global_load_dwordx4 v[122:125], v[88:89], off offset:1664
	global_load_dwordx4 v[126:129], v[92:93], off offset:1664
	s_waitcnt vmcnt(9)
	ds_write_b128 v100, v[146:149] offset:13824
	s_waitcnt vmcnt(8)
	ds_write_b128 v100, v[150:153] offset:32256
	s_waitcnt lgkmcnt(3)
	v_mfma_f32_32x32x16_bf16 v[16:31], v[130:133], v[162:165], v[16:31]
	s_waitcnt lgkmcnt(2)
	v_mfma_f32_32x32x16_bf16 v[48:63], v[130:133], v[166:169], v[48:63]
	v_mfma_f32_32x32x16_bf16 v[0:15], v[134:137], v[162:165], v[0:15]
	v_mfma_f32_32x32x16_bf16 v[32:47], v[134:137], v[166:169], v[32:47]
	s_waitcnt lgkmcnt(0)
	s_barrier
	global_load_dwordx4 v[130:133], v[64:65], off offset:1792
	global_load_dwordx4 v[134:137], v[106:107], off offset:1792
	ds_read_b128 v[146:149], v104
	ds_read_b128 v[150:153], v104 offset:4608
	ds_read_b128 v[154:157], v101 offset:18432
	ds_read_b128 v[158:161], v101 offset:23040
	s_waitcnt vmcnt(9)
	ds_write_b128 v100, v[66:69] offset:36864
	s_waitcnt vmcnt(8)
	ds_write_b128 v100, v[110:113] offset:55296
	ds_read_b128 v[66:69], v104 offset:32
	ds_read_b128 v[110:113], v104 offset:4640
	ds_read_b128 v[162:165], v101 offset:18464
	ds_read_b128 v[166:169], v101 offset:23072
	s_waitcnt lgkmcnt(7)
	v_mfma_f32_32x32x16_bf16 v[16:31], v[146:149], v[154:157], v[16:31]
	s_waitcnt lgkmcnt(6)
	v_mfma_f32_32x32x16_bf16 v[48:63], v[146:149], v[158:161], v[48:63]
	v_mfma_f32_32x32x16_bf16 v[0:15], v[150:153], v[154:157], v[0:15]
	v_mfma_f32_32x32x16_bf16 v[32:47], v[150:153], v[158:161], v[32:47]
	global_load_dwordx4 v[146:149], v[72:73], off offset:1792
	global_load_dwordx4 v[150:153], v[76:77], off offset:1792
	s_waitcnt vmcnt(9)
	ds_write_b128 v100, v[138:141] offset:41472
	s_waitcnt vmcnt(8)
	ds_write_b128 v100, v[142:145] offset:59904
	ds_read_b128 v[138:141], v104 offset:64
	ds_read_b128 v[142:145], v104 offset:4672
	ds_read_b128 v[154:157], v101 offset:18496
	ds_read_b128 v[158:161], v101 offset:23104
	s_waitcnt lgkmcnt(7)
	v_mfma_f32_32x32x16_bf16 v[16:31], v[66:69], v[162:165], v[16:31]
	s_waitcnt lgkmcnt(6)
	v_mfma_f32_32x32x16_bf16 v[48:63], v[66:69], v[166:169], v[48:63]
	v_mfma_f32_32x32x16_bf16 v[0:15], v[110:113], v[162:165], v[0:15]
	v_mfma_f32_32x32x16_bf16 v[32:47], v[110:113], v[166:169], v[32:47]
	global_load_dwordx4 v[110:113], v[80:81], off offset:1792
	global_load_dwordx4 v[162:165], v[84:85], off offset:1792
	s_waitcnt vmcnt(9)
	ds_write_b128 v100, v[114:117] offset:46080
	s_waitcnt vmcnt(8)
	ds_write_b128 v100, v[118:121] offset:64512
	ds_read_b128 v[66:69], v104 offset:96
	ds_read_b128 v[114:117], v104 offset:4704
	ds_read_b128 v[118:121], v101 offset:18528
	ds_read_b128 v[166:169], v101 offset:23136
	s_waitcnt lgkmcnt(7)
	v_mfma_f32_32x32x16_bf16 v[16:31], v[138:141], v[154:157], v[16:31]
	s_waitcnt lgkmcnt(6)
	v_mfma_f32_32x32x16_bf16 v[48:63], v[138:141], v[158:161], v[48:63]
	v_mfma_f32_32x32x16_bf16 v[0:15], v[142:145], v[154:157], v[0:15]
	v_mfma_f32_32x32x16_bf16 v[32:47], v[142:145], v[158:161], v[32:47]
	global_load_dwordx4 v[138:141], v[88:89], off offset:1792
	global_load_dwordx4 v[142:145], v[92:93], off offset:1792
	s_waitcnt vmcnt(9)
	ds_write_b128 v100, v[122:125] offset:50688
	s_waitcnt vmcnt(8)
	ds_write_b128 v105, v[126:129] offset:13824
	s_waitcnt lgkmcnt(3)
	v_mfma_f32_32x32x16_bf16 v[16:31], v[66:69], v[118:121], v[16:31]
	s_waitcnt lgkmcnt(2)
	v_mfma_f32_32x32x16_bf16 v[48:63], v[66:69], v[166:169], v[48:63]
	v_mfma_f32_32x32x16_bf16 v[0:15], v[114:117], v[118:121], v[0:15]
	v_mfma_f32_32x32x16_bf16 v[32:47], v[114:117], v[166:169], v[32:47]
	s_waitcnt lgkmcnt(0)
	s_barrier
; __device__ __forceinline__ void gemm_run(int tid, f32x16 (&acc)[2][2], GRegs& g, const GOp& o, int K, unsigned char* smem) {
;     ...
;     bf16r* cur = sbuf + (k & 1) * (256 * LDK);
;     bf16r* nxt = sbuf + ((k & 1) ^ 1) * (256 * LDK);
;     const bf16r* As = cur + (wm * 64 + fr) * LDK + fh * 8;
;     const bf16r* Bs = cur + 128 * LDK + (wn * 64 + fr) * LDK + fh * 8;
;     const bool wr = (k + 1 < nk), ld = (k + 2 < nk);
;     bf16x8 fa[2][2], fb[2][2];
;     fa[0][0] = *(const bf16x8*)(As);
;     fa[0][1] = *(const bf16x8*)(As + 32 * LDK);
;     fb[0][0] = *(const bf16x8*)(Bs);
;     fb[0][1] = *(const bf16x8*)(Bs + 32 * LDK);
; #pragma unroll
;     for (int i = 0; i < 4; i++) {
;       if (wr) {
;         *(u32x4*)(nxt + (r0 + i * 32) * LDK + sg * 8) = g.a[i];
;         *(u32x4*)(nxt + 128 * LDK + (r0 + i * 32) * LDK + sg * 8) = g.b[i];
;       }
;       if (ld) {
;         g.a[i] = *(const u32x4*)(Ap + (size_t)i * 32 * o.lda + (k + 2) * 64);
;         g.b[i] = *(const u32x4*)(Bp + o.bs.o[i] + (k + 2) * 64);
;       }
;       if (i < 3) {
;         fa[(i + 1) & 1][0] = *(const bf16x8*)(As + (i + 1) * 16);
;         fa[(i + 1) & 1][1] = *(const bf16x8*)(As + 32 * LDK + (i + 1) * 16);
;         fb[(i + 1) & 1][0] = *(const bf16x8*)(Bs + (i + 1) * 16);
;         fb[(i + 1) & 1][1] = *(const bf16x8*)(Bs + 32 * LDK + (i + 1) * 16);
;       }
;       __builtin_amdgcn_sched_barrier(0);
;       __builtin_amdgcn_s_setprio(1);
;       acc[0][0] = __builtin_amdgcn_mfma_f32_32x32x16_bf16(fa[i & 1][0], fb[i & 1][0], acc[0][0], 0, 0, 0);
;       acc[0][1] = __builtin_amdgcn_mfma_f32_32x32x16_bf16(fa[i & 1][0], fb[i & 1][1], acc[0][1], 0, 0, 0);
;       acc[1][0] = __builtin_amdgcn_mfma_f32_32x32x16_bf16(fa[i & 1][1], fb[i & 1][0], acc[1][0], 0, 0, 0);
;       acc[1][1] = __builtin_amdgcn_mfma_f32_32x32x16_bf16(fa[i & 1][1], fb[i & 1][1], acc[1][1], 0, 0, 0);
;       __builtin_amdgcn_s_setprio(0);
;     }
;     __syncthreads();
	global_load_dwordx4 v[64:67], v[64:65], off offset:1920
	s_nop 0
	global_load_dwordx4 v[68:71], v[106:107], off offset:1920
	ds_read_b128 v[114:117], v104 offset:36864
	ds_read_b128 v[118:121], v104 offset:41472
	ds_read_b128 v[122:125], v101 offset:55296
	ds_read_b128 v[126:129], v101 offset:59904
	s_waitcnt vmcnt(9)
	ds_write_b128 v100, v[130:133]
	s_waitcnt vmcnt(8)
	ds_write_b128 v100, v[134:137] offset:18432
	ds_read_b128 v[130:133], v104 offset:36896
	ds_read_b128 v[134:137], v104 offset:41504
	ds_read_b128 v[154:157], v101 offset:55328
	ds_read_b128 v[158:161], v101 offset:59936
	s_waitcnt lgkmcnt(7)
	v_mfma_f32_32x32x16_bf16 v[16:31], v[114:117], v[122:125], v[16:31]
	s_waitcnt lgkmcnt(6)
	v_mfma_f32_32x32x16_bf16 v[48:63], v[114:117], v[126:129], v[48:63]
	v_mfma_f32_32x32x16_bf16 v[0:15], v[118:121], v[122:125], v[0:15]
	v_mfma_f32_32x32x16_bf16 v[32:47], v[118:121], v[126:129], v[32:47]
	global_load_dwordx4 v[72:75], v[72:73], off offset:1920
	s_nop 0
	global_load_dwordx4 v[76:79], v[76:77], off offset:1920
	s_waitcnt vmcnt(9)
	ds_write_b128 v100, v[146:149] offset:4608
	s_waitcnt vmcnt(8)
	ds_write_b128 v100, v[150:153] offset:23040
	ds_read_b128 v[114:117], v104 offset:36928
	ds_read_b128 v[118:121], v104 offset:41536
	ds_read_b128 v[122:125], v101 offset:55360
	ds_read_b128 v[126:129], v101 offset:59968
	s_waitcnt lgkmcnt(7)
	v_mfma_f32_32x32x16_bf16 v[16:31], v[130:133], v[154:157], v[16:31]
	s_waitcnt lgkmcnt(6)
	v_mfma_f32_32x32x16_bf16 v[48:63], v[130:133], v[158:161], v[48:63]
	v_mfma_f32_32x32x16_bf16 v[0:15], v[134:137], v[154:157], v[0:15]
	v_mfma_f32_32x32x16_bf16 v[32:47], v[134:137], v[158:161], v[32:47]
	global_load_dwordx4 v[80:83], v[80:81], off offset:1920
	s_nop 0
	global_load_dwordx4 v[84:87], v[84:85], off offset:1920
	s_waitcnt vmcnt(9)
	ds_write_b128 v100, v[110:113] offset:9216
	s_waitcnt vmcnt(8)
	ds_write_b128 v100, v[162:165] offset:27648
	ds_read_b128 v[110:113], v104 offset:36960
	ds_read_b128 v[130:133], v104 offset:41568
	ds_read_b128 v[134:137], v101 offset:55392
	ds_read_b128 v[146:149], v101 offset:60000
	s_waitcnt lgkmcnt(7)
	v_mfma_f32_32x32x16_bf16 v[16:31], v[114:117], v[122:125], v[16:31]
	s_waitcnt lgkmcnt(6)
	v_mfma_f32_32x32x16_bf16 v[48:63], v[114:117], v[126:129], v[48:63]
	v_mfma_f32_32x32x16_bf16 v[0:15], v[118:121], v[122:125], v[0:15]
	v_mfma_f32_32x32x16_bf16 v[32:47], v[118:121], v[126:129], v[32:47]
	global_load_dwordx4 v[88:91], v[88:89], off offset:1920
	s_nop 0
	global_load_dwordx4 v[92:95], v[92:93], off offset:1920
	s_waitcnt vmcnt(9)
	ds_write_b128 v100, v[138:141] offset:13824
	s_waitcnt vmcnt(8)
	ds_write_b128 v100, v[142:145] offset:32256
	s_waitcnt lgkmcnt(3)
	v_mfma_f32_32x32x16_bf16 v[16:31], v[110:113], v[134:137], v[16:31]
	s_waitcnt lgkmcnt(2)
	v_mfma_f32_32x32x16_bf16 v[48:63], v[110:113], v[146:149], v[48:63]
	v_mfma_f32_32x32x16_bf16 v[0:15], v[130:133], v[134:137], v[0:15]
	v_mfma_f32_32x32x16_bf16 v[32:47], v[130:133], v[146:149], v[32:47]
	s_waitcnt lgkmcnt(0)
	s_barrier
; __device__ __forceinline__ void gemm_run(int tid, f32x16 (&acc)[2][2], GRegs& g, const GOp& o, int K, unsigned char* smem) {
;     ...
;   for (int k = 0; k < nk; k++) {
;     bf16r* cur = sbuf + (k & 1) * (256 * LDK);
;     bf16r* nxt = sbuf + ((k & 1) ^ 1) * (256 * LDK);
;     const bf16r* As = cur + (wm * 64 + fr) * LDK + fh * 8;
;     const bf16r* Bs = cur + 128 * LDK + (wn * 64 + fr) * LDK + fh * 8;
;     const bool wr = (k + 1 < nk), ld = (k + 2 < nk);
;     bf16x8 fa[2][2], fb[2][2];
;     fa[0][0] = *(const bf16x8*)(As);
;     fa[0][1] = *(const bf16x8*)(As + 32 * LDK);
;     fb[0][0] = *(const bf16x8*)(Bs);
;     fb[0][1] = *(const bf16x8*)(Bs + 32 * LDK);
; #pragma unroll
;     for (int i = 0; i < 4; i++) {
;       if (wr) {
;         *(u32x4*)(nxt + (r0 + i * 32) * LDK + sg * 8) = g.a[i];
;         *(u32x4*)(nxt + 128 * LDK + (r0 + i * 32) * LDK + sg * 8) = g.b[i];
;       }
;       if (ld) {
;         g.a[i] = *(const u32x4*)(Ap + (size_t)i * 32 * o.lda + (k + 2) * 64);
;         g.b[i] = *(const u32x4*)(Bp + o.bs.o[i] + (k + 2) * 64);
;       }
;       if (i < 3) {
;         fa[(i + 1) & 1][0] = *(const bf16x8*)(As + (i + 1) * 16);
;         fa[(i + 1) & 1][1] = *(const bf16x8*)(As + 32 * LDK + (i + 1) * 16);
;         fb[(i + 1) & 1][0] = *(const bf16x8*)(Bs + (i + 1) * 16);
;         fb[(i + 1) & 1][1] = *(const bf16x8*)(Bs + 32 * LDK + (i + 1) * 16);
;       }
;       __builtin_amdgcn_sched_barrier(0);
;       __builtin_amdgcn_s_setprio(1);
;       acc[0][0] = __builtin_amdgcn_mfma_f32_32x32x16_bf16(fa[i & 1][0], fb[i & 1][0], acc[0][0], 0, 0, 0);
;       acc[0][1] = __builtin_amdgcn_mfma_f32_32x32x16_bf16(fa[i & 1][0], fb[i & 1][1], acc[0][1], 0, 0, 0);
;       acc[1][0] = __builtin_amdgcn_mfma_f32_32x32x16_bf16(fa[i & 1][1], fb[i & 1][0], acc[1][0], 0, 0, 0);
;       acc[1][1] = __builtin_amdgcn_mfma_f32_32x32x16_bf16(fa[i & 1][1], fb[i & 1][1], acc[1][1], 0, 0, 0);
;       __builtin_amdgcn_s_setprio(0);
;     }
;     __syncthreads();
;   }
; __device__ __forceinline__ bool tile_map(int it, int nn, int& mt, int& nt) {
;   const int xcd = blockIdx.x & 7, li = blockIdx.x >> 3, nb = gridDim.x >> 3;
;   int q = it * nb + li;
;   const int per = 16 * nn;
;   if (q < per) {
;     int sub = q / (8 * nn), r = q - sub * (8 * nn);
;     nt = r >> 3;
;     mt = xcd * 16 + sub * 8 + (r & 7);
;     return true;
;   }
;   q -= per;
;   int n = q * 8 + xcd;
	ds_read_b128 v[110:113], v104
	ds_read_b128 v[114:117], v104 offset:4608
	ds_read_b128 v[118:121], v101 offset:18432
	ds_read_b128 v[122:125], v101 offset:23040
	s_waitcnt vmcnt(7)
	ds_write_b128 v100, v[64:67] offset:36864
	s_waitcnt vmcnt(6)
	ds_write_b128 v100, v[68:71] offset:55296
	ds_read_b128 v[126:129], v104 offset:32
	ds_read_b128 v[130:133], v104 offset:4640
	ds_read_b128 v[134:137], v101 offset:18464
	ds_read_b128 v[138:141], v101 offset:23072
	s_waitcnt lgkmcnt(7)
	v_mfma_f32_32x32x16_bf16 v[16:31], v[110:113], v[118:121], v[16:31]
	s_waitcnt lgkmcnt(6)
	v_mfma_f32_32x32x16_bf16 v[48:63], v[110:113], v[122:125], v[48:63]
	v_mfma_f32_32x32x16_bf16 v[0:15], v[114:117], v[118:121], v[0:15]
	v_mfma_f32_32x32x16_bf16 v[32:47], v[114:117], v[122:125], v[32:47]
	s_waitcnt vmcnt(5)
	ds_write_b128 v100, v[72:75] offset:41472
	s_waitcnt vmcnt(4)
	ds_write_b128 v100, v[76:79] offset:59904
	ds_read_b128 v[110:113], v104 offset:64
	ds_read_b128 v[114:117], v104 offset:4672
	ds_read_b128 v[118:121], v101 offset:18496
	ds_read_b128 v[122:125], v101 offset:23104
	s_waitcnt lgkmcnt(7)
	v_mfma_f32_32x32x16_bf16 v[16:31], v[126:129], v[134:137], v[16:31]
	s_waitcnt lgkmcnt(6)
	v_mfma_f32_32x32x16_bf16 v[48:63], v[126:129], v[138:141], v[48:63]
	v_mfma_f32_32x32x16_bf16 v[0:15], v[130:133], v[134:137], v[0:15]
	v_mfma_f32_32x32x16_bf16 v[32:47], v[130:133], v[138:141], v[32:47]
	s_waitcnt vmcnt(3)
	ds_write_b128 v100, v[80:83] offset:46080
	s_waitcnt vmcnt(2)
	ds_write_b128 v100, v[84:87] offset:64512
	ds_read_b128 v[126:129], v104 offset:96
	ds_read_b128 v[130:133], v104 offset:4704
	ds_read_b128 v[134:137], v101 offset:18528
	ds_read_b128 v[138:141], v101 offset:23136
	s_waitcnt lgkmcnt(7)
	v_mfma_f32_32x32x16_bf16 v[16:31], v[110:113], v[118:121], v[16:31]
	s_waitcnt lgkmcnt(6)
	v_mfma_f32_32x32x16_bf16 v[48:63], v[110:113], v[122:125], v[48:63]
	v_mfma_f32_32x32x16_bf16 v[0:15], v[114:117], v[118:121], v[0:15]
	v_mfma_f32_32x32x16_bf16 v[32:47], v[114:117], v[122:125], v[32:47]
	s_waitcnt vmcnt(1)
	ds_write_b128 v100, v[88:91] offset:50688
	s_waitcnt vmcnt(0)
	ds_write_b128 v105, v[92:95] offset:13824
	s_waitcnt lgkmcnt(3)
	v_mfma_f32_32x32x16_bf16 v[16:31], v[126:129], v[134:137], v[16:31]
	s_waitcnt lgkmcnt(2)
	v_mfma_f32_32x32x16_bf16 v[48:63], v[126:129], v[138:141], v[48:63]
	v_mfma_f32_32x32x16_bf16 v[0:15], v[130:133], v[134:137], v[0:15]
	v_mfma_f32_32x32x16_bf16 v[32:47], v[130:133], v[138:141], v[32:47]
	s_waitcnt lgkmcnt(0)
	s_barrier
	ds_read_b128 v[110:113], v104 offset:36864
	ds_read_b128 v[114:117], v104 offset:36896
	ds_read_b128 v[118:121], v104 offset:41472
	ds_read_b128 v[122:125], v104 offset:41504
	ds_read_b128 v[126:129], v101 offset:55296
	ds_read_b128 v[130:133], v101 offset:55328
	ds_read_b128 v[134:137], v101 offset:59904
	ds_read_b128 v[138:141], v101 offset:59936
	s_waitcnt lgkmcnt(3)
	v_mfma_f32_32x32x16_bf16 v[16:31], v[110:113], v[126:129], v[16:31]
	s_waitcnt lgkmcnt(1)
	v_mfma_f32_32x32x16_bf16 v[48:63], v[110:113], v[134:137], v[48:63]
	v_mfma_f32_32x32x16_bf16 v[0:15], v[118:121], v[126:129], v[0:15]
	v_mfma_f32_32x32x16_bf16 v[32:47], v[118:121], v[134:137], v[32:47]
	ds_read_b128 v[110:113], v104 offset:36928
	ds_read_b128 v[118:121], v104 offset:41536
	ds_read_b128 v[126:129], v101 offset:55360
	ds_read_b128 v[134:137], v101 offset:59968
	v_mfma_f32_32x32x16_bf16 v[16:31], v[114:117], v[130:133], v[16:31]
	s_waitcnt lgkmcnt(4)
	v_mfma_f32_32x32x16_bf16 v[48:63], v[114:117], v[138:141], v[48:63]
	v_mfma_f32_32x32x16_bf16 v[0:15], v[122:125], v[130:133], v[0:15]
	v_mfma_f32_32x32x16_bf16 v[32:47], v[122:125], v[138:141], v[32:47]
	ds_read_b128 v[114:117], v104 offset:36960
	ds_read_b128 v[122:125], v104 offset:41568
	ds_read_b128 v[130:133], v101 offset:55392
	ds_read_b128 v[138:141], v101 offset:60000
	s_waitcnt lgkmcnt(5)
	v_mfma_f32_32x32x16_bf16 v[16:31], v[110:113], v[126:129], v[16:31]
	s_waitcnt lgkmcnt(4)
	v_mfma_f32_32x32x16_bf16 v[48:63], v[110:113], v[134:137], v[48:63]
	v_mfma_f32_32x32x16_bf16 v[0:15], v[118:121], v[126:129], v[0:15]
	v_mfma_f32_32x32x16_bf16 v[32:47], v[118:121], v[134:137], v[32:47]
	s_waitcnt lgkmcnt(1)
	v_mfma_f32_32x32x16_bf16 v[16:31], v[114:117], v[130:133], v[16:31]
	s_waitcnt lgkmcnt(0)
	v_mfma_f32_32x32x16_bf16 v[48:63], v[114:117], v[138:141], v[48:63]
	v_mfma_f32_32x32x16_bf16 v[0:15], v[122:125], v[130:133], v[0:15]
	v_mfma_f32_32x32x16_bf16 v[32:47], v[122:125], v[138:141], v[32:47]
	s_cmpk_gt_u32 s96, 0x1ff
	s_mov_b64 s[4:5], -1
	s_barrier
	s_cbranch_scc0 .LBB0_1978
	s_mov_b64 s[4:5], 0
	s_cmp_gt_i32 s2, 31
	s_mov_b64 s[0:1], 0
	s_cbranch_scc1 .LBB0_1978
	s_movk_i32 s92, 0x80
	s_mov_b64 s[0:1], -1
	s_mov_b32 s83, s2

; __device__ __forceinline__ void gemm_run(int tid, f32x16 (&acc)[2][2], GRegs& g, const GOp& o, int K, unsigned char* smem) {
;     ...
;   for (int i = 0; i < 4; i++) {
;     *(u32x4*)(sbuf + (r0 + i * 32) * LDK + sg * 8) = g.a[i];
;     *(u32x4*)(sbuf + 128 * LDK + (r0 + i * 32) * LDK + sg * 8) = g.b[i];
;   }
;   if (nk > 1) {
; #pragma unroll
;     for (int i = 0; i < 4; i++) {
;       g.a[i] = *(const u32x4*)(Ap + (size_t)i * 32 * o.lda + 64);
;       g.b[i] = *(const u32x4*)(Bp + o.bs.o[i] + 64);
;     }
;   }
;   __syncthreads();
;   const int lane = tid & 63, fr = lane & 31, fh = lane >> 5;
;   for (int k = 0; k < nk; k++) {
;     bf16r* cur = sbuf + (k & 1) * (256 * LDK);
;     bf16r* nxt = sbuf + ((k & 1) ^ 1) * (256 * LDK);
;     const bf16r* As = cur + (wm * 64 + fr) * LDK + fh * 8;
;     const bf16r* Bs = cur + 128 * LDK + (wn * 64 + fr) * LDK + fh * 8;
;     const bool wr = (k + 1 < nk), ld = (k + 2 < nk);
;     bf16x8 fa[2][2], fb[2][2];
;     fa[0][0] = *(const bf16x8*)(As);
;     fa[0][1] = *(const bf16x8*)(As + 32 * LDK);
;     fb[0][0] = *(const bf16x8*)(Bs);
;     fb[0][1] = *(const bf16x8*)(Bs + 32 * LDK);
; #pragma unroll
;     for (int i = 0; i < 4; i++) {
;       if (wr) {
;         *(u32x4*)(nxt + (r0 + i * 32) * LDK + sg * 8) = g.a[i];
;         *(u32x4*)(nxt + 128 * LDK + (r0 + i * 32) * LDK + sg * 8) = g.b[i];
;       }
;       if (ld) {
;         g.a[i] = *(const u32x4*)(Ap + (size_t)i * 32 * o.lda + (k + 2) * 64);
;         g.b[i] = *(const u32x4*)(Bp + o.bs.o[i] + (k + 2) * 64);
;       }
;       if (i < 3) {
;         fa[(i + 1) & 1][0] = *(const bf16x8*)(As + (i + 1) * 16);
;         fa[(i + 1) & 1][1] = *(const bf16x8*)(As + 32 * LDK + (i + 1) * 16);
;         fb[(i + 1) & 1][0] = *(const bf16x8*)(Bs + (i + 1) * 16);
;         fb[(i + 1) & 1][1] = *(const bf16x8*)(Bs + 32 * LDK + (i + 1) * 16);
;       }
;       __builtin_amdgcn_sched_barrier(0);
;       __builtin_amdgcn_s_setprio(1);
;       acc[0][0] = __builtin_amdgcn_mfma_f32_32x32x16_bf16(fa[i & 1][0], fb[i & 1][0], acc[0][0], 0, 0, 0);
;       acc[0][1] = __builtin_amdgcn_mfma_f32_32x32x16_bf16(fa[i & 1][0], fb[i & 1][1], acc[0][1], 0, 0, 0);
;       acc[1][0] = __builtin_amdgcn_mfma_f32_32x32x16_bf16(fa[i & 1][1], fb[i & 1][0], acc[1][0], 0, 0, 0);
;       acc[1][1] = __builtin_amdgcn_mfma_f32_32x32x16_bf16(fa[i & 1][1], fb[i & 1][1], acc[1][1], 0, 0, 0);
.LBB0_2289:
	v_lshl_add_u64 v[228:229], v[208:209], 0, v[138:139]
	s_waitcnt vmcnt(7)
	ds_write_b128 v132, v[64:67]
	s_waitcnt vmcnt(6)
	ds_write_b128 v132, v[68:71] offset:18432
	s_waitcnt vmcnt(5)
	ds_write_b128 v132, v[72:75] offset:4608
	s_waitcnt vmcnt(4)
	ds_write_b128 v132, v[76:79] offset:23040
	s_waitcnt vmcnt(3)
	ds_write_b128 v132, v[80:83] offset:9216
	s_waitcnt vmcnt(2)
	ds_write_b128 v132, v[84:87] offset:27648
	s_waitcnt vmcnt(1)
	ds_write_b128 v132, v[88:91] offset:13824
	s_waitcnt vmcnt(0)
	ds_write_b128 v132, v[92:95] offset:32256
	v_add_co_u32_e32 v76, vcc, s35, v228
	v_lshl_add_u64 v[226:227], v[206:207], 0, v[138:139]
	s_nop 0
	v_addc_co_u32_e32 v77, vcc, 0, v229, vcc
	v_add_co_u32_e32 v78, vcc, s36, v226
	global_load_dwordx4 v[0:3], v[76:77], off offset:128
	s_nop 0
	v_addc_co_u32_e32 v79, vcc, 0, v227, vcc
	v_add_co_u32_e32 v72, vcc, s37, v228
	global_load_dwordx4 v[4:7], v[78:79], off offset:128
	s_nop 0
	v_addc_co_u32_e32 v73, vcc, 0, v229, vcc
	v_add_co_u32_e32 v74, vcc, s38, v226
	global_load_dwordx4 v[80:83], v[72:73], off offset:128
	s_nop 0
	v_addc_co_u32_e32 v75, vcc, 0, v227, vcc
	v_add_co_u32_e32 v68, vcc, s39, v228
	global_load_dwordx4 v[84:87], v[74:75], off offset:128
	s_nop 0
	v_addc_co_u32_e32 v69, vcc, 0, v229, vcc
	v_add_co_u32_e32 v70, vcc, s40, v226
	global_load_dwordx4 v[88:91], v[68:69], off offset:128
	s_nop 0
	v_addc_co_u32_e32 v71, vcc, 0, v227, vcc
	v_add_co_u32_e32 v64, vcc, s41, v228
	global_load_dwordx4 v[92:95], v[70:71], off offset:128
	s_nop 0
	v_addc_co_u32_e32 v65, vcc, 0, v229, vcc
	v_add_co_u32_e32 v66, vcc, s42, v226
	global_load_dwordx4 v[96:99], v[64:65], off offset:128
	s_nop 0
	v_addc_co_u32_e32 v67, vcc, 0, v227, vcc
	global_load_dwordx4 v[100:103], v[66:67], off offset:128
	s_waitcnt lgkmcnt(0)
	s_barrier
	global_load_dwordx4 v[104:107], v[76:77], off offset:256
	global_load_dwordx4 v[108:111], v[78:79], off offset:256
	ds_read_b128 v[8:11], v136
	ds_read_b128 v[12:15], v136 offset:4608
	ds_read_b128 v[16:19], v133 offset:18432
	ds_read_b128 v[112:115], v133 offset:23040
	s_waitcnt vmcnt(9)
	ds_write_b128 v132, v[0:3] offset:36864
	s_waitcnt vmcnt(8)
	ds_write_b128 v132, v[4:7] offset:55296
	ds_read_b128 v[116:119], v136 offset:32
	ds_read_b128 v[120:123], v136 offset:4640
	ds_read_b128 v[124:127], v133 offset:18464
	ds_read_b128 v[232:235], v133 offset:23072
	s_waitcnt lgkmcnt(7)
	v_mfma_f32_32x32x16_bf16 v[48:63], v[8:11], v[16:19], 0
	s_waitcnt lgkmcnt(6)
	v_mfma_f32_32x32x16_bf16 v[32:47], v[8:11], v[112:115], 0
	v_mfma_f32_32x32x16_bf16 v[16:31], v[12:15], v[16:19], 0
	v_mfma_f32_32x32x16_bf16 v[0:15], v[12:15], v[112:115], 0
	global_load_dwordx4 v[112:115], v[72:73], off offset:256
	global_load_dwordx4 v[236:239], v[74:75], off offset:256
	s_waitcnt vmcnt(9)
	ds_write_b128 v132, v[80:83] offset:41472
	s_waitcnt vmcnt(8)
	ds_write_b128 v132, v[84:87] offset:59904
	ds_read_b128 v[80:83], v136 offset:64
	ds_read_b128 v[84:87], v136 offset:4672
	ds_read_b128 v[240:243], v133 offset:18496
	ds_read_b128 v[244:247], v133 offset:23104
	s_waitcnt lgkmcnt(7)
	v_mfma_f32_32x32x16_bf16 v[48:63], v[116:119], v[124:127], v[48:63]
	s_waitcnt lgkmcnt(6)
	v_mfma_f32_32x32x16_bf16 v[32:47], v[116:119], v[232:235], v[32:47]
	v_mfma_f32_32x32x16_bf16 v[16:31], v[120:123], v[124:127], v[16:31]
	v_mfma_f32_32x32x16_bf16 v[0:15], v[120:123], v[232:235], v[0:15]
	global_load_dwordx4 v[116:119], v[68:69], off offset:256
	global_load_dwordx4 v[120:123], v[70:71], off offset:256
	s_waitcnt vmcnt(9)
	ds_write_b128 v132, v[88:91] offset:46080
	s_waitcnt vmcnt(8)
	ds_write_b128 v132, v[92:95] offset:64512
	ds_read_b128 v[88:91], v136 offset:96
	ds_read_b128 v[92:95], v136 offset:4704
	ds_read_b128 v[124:127], v133 offset:18528
	ds_read_b128 v[232:235], v133 offset:23136
	s_waitcnt lgkmcnt(7)
	v_mfma_f32_32x32x16_bf16 v[48:63], v[80:83], v[240:243], v[48:63]
	s_waitcnt lgkmcnt(6)
	v_mfma_f32_32x32x16_bf16 v[32:47], v[80:83], v[244:247], v[32:47]
	v_mfma_f32_32x32x16_bf16 v[16:31], v[84:87], v[240:243], v[16:31]
	v_mfma_f32_32x32x16_bf16 v[0:15], v[84:87], v[244:247], v[0:15]
	global_load_dwordx4 v[80:83], v[64:65], off offset:256
	global_load_dwordx4 v[84:87], v[66:67], off offset:256
	s_waitcnt vmcnt(9)
	ds_write_b128 v132, v[96:99] offset:50688
	s_waitcnt vmcnt(8)
	ds_write_b128 v137, v[100:103] offset:13824
	s_waitcnt lgkmcnt(3)
	v_mfma_f32_32x32x16_bf16 v[48:63], v[88:91], v[124:127], v[48:63]
	s_waitcnt lgkmcnt(2)
	v_mfma_f32_32x32x16_bf16 v[32:47], v[88:91], v[232:235], v[32:47]
	v_mfma_f32_32x32x16_bf16 v[16:31], v[92:95], v[124:127], v[16:31]
	v_mfma_f32_32x32x16_bf16 v[0:15], v[92:95], v[232:235], v[0:15]
	s_waitcnt lgkmcnt(0)
	s_barrier
; __device__ __forceinline__ void gemm_run(int tid, f32x16 (&acc)[2][2], GRegs& g, const GOp& o, int K, unsigned char* smem) {
;     ...
;     bf16r* cur = sbuf + (k & 1) * (256 * LDK);
;     bf16r* nxt = sbuf + ((k & 1) ^ 1) * (256 * LDK);
;     const bf16r* As = cur + (wm * 64 + fr) * LDK + fh * 8;
;     const bf16r* Bs = cur + 128 * LDK + (wn * 64 + fr) * LDK + fh * 8;
;     const bool wr = (k + 1 < nk), ld = (k + 2 < nk);
;     bf16x8 fa[2][2], fb[2][2];
;     fa[0][0] = *(const bf16x8*)(As);
;     fa[0][1] = *(const bf16x8*)(As + 32 * LDK);
;     fb[0][0] = *(const bf16x8*)(Bs);
;     fb[0][1] = *(const bf16x8*)(Bs + 32 * LDK);
; #pragma unroll
;     for (int i = 0; i < 4; i++) {
;       if (wr) {
;         *(u32x4*)(nxt + (r0 + i * 32) * LDK + sg * 8) = g.a[i];
;         *(u32x4*)(nxt + 128 * LDK + (r0 + i * 32) * LDK + sg * 8) = g.b[i];
;       }
;       if (ld) {
;         g.a[i] = *(const u32x4*)(Ap + (size_t)i * 32 * o.lda + (k + 2) * 64);
;         g.b[i] = *(const u32x4*)(Bp + o.bs.o[i] + (k + 2) * 64);
;       }
;       if (i < 3) {
;         fa[(i + 1) & 1][0] = *(const bf16x8*)(As + (i + 1) * 16);
;         fa[(i + 1) & 1][1] = *(const bf16x8*)(As + 32 * LDK + (i + 1) * 16);
;         fb[(i + 1) & 1][0] = *(const bf16x8*)(Bs + (i + 1) * 16);
;         fb[(i + 1) & 1][1] = *(const bf16x8*)(Bs + 32 * LDK + (i + 1) * 16);
;       }
;       __builtin_amdgcn_sched_barrier(0);
;       __builtin_amdgcn_s_setprio(1);
;       acc[0][0] = __builtin_amdgcn_mfma_f32_32x32x16_bf16(fa[i & 1][0], fb[i & 1][0], acc[0][0], 0, 0, 0);
;       acc[0][1] = __builtin_amdgcn_mfma_f32_32x32x16_bf16(fa[i & 1][0], fb[i & 1][1], acc[0][1], 0, 0, 0);
;       acc[1][0] = __builtin_amdgcn_mfma_f32_32x32x16_bf16(fa[i & 1][1], fb[i & 1][0], acc[1][0], 0, 0, 0);
;       acc[1][1] = __builtin_amdgcn_mfma_f32_32x32x16_bf16(fa[i & 1][1], fb[i & 1][1], acc[1][1], 0, 0, 0);
;       __builtin_amdgcn_s_setprio(0);
;     }
;     __syncthreads();
	global_load_dwordx4 v[88:91], v[76:77], off offset:384
	global_load_dwordx4 v[92:95], v[78:79], off offset:384
	ds_read_b128 v[96:99], v136 offset:36864
	ds_read_b128 v[100:103], v136 offset:41472
	ds_read_b128 v[124:127], v133 offset:55296
	ds_read_b128 v[232:235], v133 offset:59904
	s_waitcnt vmcnt(9)
	ds_write_b128 v132, v[104:107]
	s_waitcnt vmcnt(8)
	ds_write_b128 v132, v[108:111] offset:18432
	ds_read_b128 v[104:107], v136 offset:36896
	ds_read_b128 v[108:111], v136 offset:41504
	ds_read_b128 v[240:243], v133 offset:55328
	ds_read_b128 v[244:247], v133 offset:59936
	s_waitcnt lgkmcnt(7)
	v_mfma_f32_32x32x16_bf16 v[48:63], v[96:99], v[124:127], v[48:63]
	s_waitcnt lgkmcnt(6)
	v_mfma_f32_32x32x16_bf16 v[32:47], v[96:99], v[232:235], v[32:47]
	v_mfma_f32_32x32x16_bf16 v[16:31], v[100:103], v[124:127], v[16:31]
	v_mfma_f32_32x32x16_bf16 v[0:15], v[100:103], v[232:235], v[0:15]
	global_load_dwordx4 v[96:99], v[72:73], off offset:384
	global_load_dwordx4 v[100:103], v[74:75], off offset:384
	s_waitcnt vmcnt(9)
	ds_write_b128 v132, v[112:115] offset:4608
	s_waitcnt vmcnt(8)
	ds_write_b128 v132, v[236:239] offset:23040
	ds_read_b128 v[112:115], v136 offset:36928
	ds_read_b128 v[124:127], v136 offset:41536
	ds_read_b128 v[232:235], v133 offset:55360
	ds_read_b128 v[236:239], v133 offset:59968
	s_waitcnt lgkmcnt(7)
	v_mfma_f32_32x32x16_bf16 v[48:63], v[104:107], v[240:243], v[48:63]
	s_waitcnt lgkmcnt(6)
	v_mfma_f32_32x32x16_bf16 v[32:47], v[104:107], v[244:247], v[32:47]
	v_mfma_f32_32x32x16_bf16 v[16:31], v[108:111], v[240:243], v[16:31]
	v_mfma_f32_32x32x16_bf16 v[0:15], v[108:111], v[244:247], v[0:15]
	global_load_dwordx4 v[104:107], v[68:69], off offset:384
	global_load_dwordx4 v[108:111], v[70:71], off offset:384
	s_waitcnt vmcnt(9)
	ds_write_b128 v132, v[116:119] offset:9216
	s_waitcnt vmcnt(8)
	ds_write_b128 v132, v[120:123] offset:27648
	ds_read_b128 v[116:119], v136 offset:36960
	ds_read_b128 v[120:123], v136 offset:41568
	ds_read_b128 v[240:243], v133 offset:55392
	ds_read_b128 v[244:247], v133 offset:60000
	s_waitcnt lgkmcnt(7)
	v_mfma_f32_32x32x16_bf16 v[48:63], v[112:115], v[232:235], v[48:63]
	s_waitcnt lgkmcnt(6)
	v_mfma_f32_32x32x16_bf16 v[32:47], v[112:115], v[236:239], v[32:47]
	v_mfma_f32_32x32x16_bf16 v[16:31], v[124:127], v[232:235], v[16:31]
	v_mfma_f32_32x32x16_bf16 v[0:15], v[124:127], v[236:239], v[0:15]
	global_load_dwordx4 v[112:115], v[64:65], off offset:384
	global_load_dwordx4 v[124:127], v[66:67], off offset:384
	s_waitcnt vmcnt(9)
	ds_write_b128 v132, v[80:83] offset:13824
	s_waitcnt vmcnt(8)
	ds_write_b128 v132, v[84:87] offset:32256
	s_waitcnt lgkmcnt(3)
	v_mfma_f32_32x32x16_bf16 v[48:63], v[116:119], v[240:243], v[48:63]
	s_waitcnt lgkmcnt(2)
	v_mfma_f32_32x32x16_bf16 v[32:47], v[116:119], v[244:247], v[32:47]
	v_mfma_f32_32x32x16_bf16 v[16:31], v[120:123], v[240:243], v[16:31]
	v_mfma_f32_32x32x16_bf16 v[0:15], v[120:123], v[244:247], v[0:15]
	s_waitcnt lgkmcnt(0)
	s_barrier
	global_load_dwordx4 v[80:83], v[76:77], off offset:512
	global_load_dwordx4 v[84:87], v[78:79], off offset:512
	ds_read_b128 v[116:119], v136
	ds_read_b128 v[120:123], v136 offset:4608
	ds_read_b128 v[232:235], v133 offset:18432
	ds_read_b128 v[236:239], v133 offset:23040
	s_waitcnt vmcnt(9)
	ds_write_b128 v132, v[88:91] offset:36864
	s_waitcnt vmcnt(8)
	ds_write_b128 v132, v[92:95] offset:55296
	ds_read_b128 v[88:91], v136 offset:32
	ds_read_b128 v[92:95], v136 offset:4640
	ds_read_b128 v[240:243], v133 offset:18464
	ds_read_b128 v[244:247], v133 offset:23072
	s_waitcnt lgkmcnt(7)
	v_mfma_f32_32x32x16_bf16 v[48:63], v[116:119], v[232:235], v[48:63]
	s_waitcnt lgkmcnt(6)
	v_mfma_f32_32x32x16_bf16 v[32:47], v[116:119], v[236:239], v[32:47]
	v_mfma_f32_32x32x16_bf16 v[16:31], v[120:123], v[232:235], v[16:31]
	v_mfma_f32_32x32x16_bf16 v[0:15], v[120:123], v[236:239], v[0:15]
	global_load_dwordx4 v[116:119], v[72:73], off offset:512
	global_load_dwordx4 v[120:123], v[74:75], off offset:512
	s_waitcnt vmcnt(9)
	ds_write_b128 v132, v[96:99] offset:41472
	s_waitcnt vmcnt(8)
	ds_write_b128 v132, v[100:103] offset:59904
	ds_read_b128 v[96:99], v136 offset:64
	ds_read_b128 v[100:103], v136 offset:4672
	ds_read_b128 v[232:235], v133 offset:18496
	ds_read_b128 v[236:239], v133 offset:23104
	s_waitcnt lgkmcnt(7)
	v_mfma_f32_32x32x16_bf16 v[48:63], v[88:91], v[240:243], v[48:63]
	s_waitcnt lgkmcnt(6)
	v_mfma_f32_32x32x16_bf16 v[32:47], v[88:91], v[244:247], v[32:47]
	v_mfma_f32_32x32x16_bf16 v[16:31], v[92:95], v[240:243], v[16:31]
	v_mfma_f32_32x32x16_bf16 v[0:15], v[92:95], v[244:247], v[0:15]
	global_load_dwordx4 v[88:91], v[68:69], off offset:512
	global_load_dwordx4 v[92:95], v[70:71], off offset:512
	s_waitcnt vmcnt(9)
	ds_write_b128 v132, v[104:107] offset:46080
	s_waitcnt vmcnt(8)
	ds_write_b128 v132, v[108:111] offset:64512
	ds_read_b128 v[104:107], v136 offset:96
	ds_read_b128 v[108:111], v136 offset:4704
	ds_read_b128 v[240:243], v133 offset:18528
	ds_read_b128 v[244:247], v133 offset:23136
	s_waitcnt lgkmcnt(7)
	v_mfma_f32_32x32x16_bf16 v[48:63], v[96:99], v[232:235], v[48:63]
	s_waitcnt lgkmcnt(6)
	v_mfma_f32_32x32x16_bf16 v[32:47], v[96:99], v[236:239], v[32:47]
	v_mfma_f32_32x32x16_bf16 v[16:31], v[100:103], v[232:235], v[16:31]
	v_mfma_f32_32x32x16_bf16 v[0:15], v[100:103], v[236:239], v[0:15]
	global_load_dwordx4 v[96:99], v[64:65], off offset:512
	global_load_dwordx4 v[100:103], v[66:67], off offset:512
	s_waitcnt vmcnt(9)
	ds_write_b128 v132, v[112:115] offset:50688
	s_waitcnt vmcnt(8)
	ds_write_b128 v137, v[124:127] offset:13824
	s_waitcnt lgkmcnt(3)
	v_mfma_f32_32x32x16_bf16 v[48:63], v[104:107], v[240:243], v[48:63]
	s_waitcnt lgkmcnt(2)
	v_mfma_f32_32x32x16_bf16 v[32:47], v[104:107], v[244:247], v[32:47]
	v_mfma_f32_32x32x16_bf16 v[16:31], v[108:111], v[240:243], v[16:31]
	v_mfma_f32_32x32x16_bf16 v[0:15], v[108:111], v[244:247], v[0:15]
	s_waitcnt lgkmcnt(0)
	s_barrier
; __device__ __forceinline__ void gemm_run(int tid, f32x16 (&acc)[2][2], GRegs& g, const GOp& o, int K, unsigned char* smem) {
;     ...
;     bf16r* cur = sbuf + (k & 1) * (256 * LDK);
;     bf16r* nxt = sbuf + ((k & 1) ^ 1) * (256 * LDK);
;     const bf16r* As = cur + (wm * 64 + fr) * LDK + fh * 8;
;     const bf16r* Bs = cur + 128 * LDK + (wn * 64 + fr) * LDK + fh * 8;
;     const bool wr = (k + 1 < nk), ld = (k + 2 < nk);
;     bf16x8 fa[2][2], fb[2][2];
;     fa[0][0] = *(const bf16x8*)(As);
;     fa[0][1] = *(const bf16x8*)(As + 32 * LDK);
;     fb[0][0] = *(const bf16x8*)(Bs);
;     fb[0][1] = *(const bf16x8*)(Bs + 32 * LDK);
; #pragma unroll
;     for (int i = 0; i < 4; i++) {
;       if (wr) {
;         *(u32x4*)(nxt + (r0 + i * 32) * LDK + sg * 8) = g.a[i];
;         *(u32x4*)(nxt + 128 * LDK + (r0 + i * 32) * LDK + sg * 8) = g.b[i];
;       }
;       if (ld) {
;         g.a[i] = *(const u32x4*)(Ap + (size_t)i * 32 * o.lda + (k + 2) * 64);
;         g.b[i] = *(const u32x4*)(Bp + o.bs.o[i] + (k + 2) * 64);
;       }
;       if (i < 3) {
;         fa[(i + 1) & 1][0] = *(const bf16x8*)(As + (i + 1) * 16);
;         fa[(i + 1) & 1][1] = *(const bf16x8*)(As + 32 * LDK + (i + 1) * 16);
;         fb[(i + 1) & 1][0] = *(const bf16x8*)(Bs + (i + 1) * 16);
;         fb[(i + 1) & 1][1] = *(const bf16x8*)(Bs + 32 * LDK + (i + 1) * 16);
;       }
;       __builtin_amdgcn_sched_barrier(0);
;       __builtin_amdgcn_s_setprio(1);
;       acc[0][0] = __builtin_amdgcn_mfma_f32_32x32x16_bf16(fa[i & 1][0], fb[i & 1][0], acc[0][0], 0, 0, 0);
;       acc[0][1] = __builtin_amdgcn_mfma_f32_32x32x16_bf16(fa[i & 1][0], fb[i & 1][1], acc[0][1], 0, 0, 0);
;       acc[1][0] = __builtin_amdgcn_mfma_f32_32x32x16_bf16(fa[i & 1][1], fb[i & 1][0], acc[1][0], 0, 0, 0);
;       acc[1][1] = __builtin_amdgcn_mfma_f32_32x32x16_bf16(fa[i & 1][1], fb[i & 1][1], acc[1][1], 0, 0, 0);
;       __builtin_amdgcn_s_setprio(0);
;     }
;     __syncthreads();
	global_load_dwordx4 v[104:107], v[76:77], off offset:640
	global_load_dwordx4 v[108:111], v[78:79], off offset:640
	ds_read_b128 v[112:115], v136 offset:36864
	ds_read_b128 v[124:127], v136 offset:41472
	ds_read_b128 v[232:235], v133 offset:55296
	ds_read_b128 v[236:239], v133 offset:59904
	s_waitcnt vmcnt(9)
	ds_write_b128 v132, v[80:83]
	s_waitcnt vmcnt(8)
	ds_write_b128 v132, v[84:87] offset:18432
	ds_read_b128 v[80:83], v136 offset:36896
	ds_read_b128 v[84:87], v136 offset:41504
	ds_read_b128 v[240:243], v133 offset:55328
	ds_read_b128 v[244:247], v133 offset:59936
	s_waitcnt lgkmcnt(7)
	v_mfma_f32_32x32x16_bf16 v[48:63], v[112:115], v[232:235], v[48:63]
	s_waitcnt lgkmcnt(6)
	v_mfma_f32_32x32x16_bf16 v[32:47], v[112:115], v[236:239], v[32:47]
	v_mfma_f32_32x32x16_bf16 v[16:31], v[124:127], v[232:235], v[16:31]
	v_mfma_f32_32x32x16_bf16 v[0:15], v[124:127], v[236:239], v[0:15]
	global_load_dwordx4 v[112:115], v[72:73], off offset:640
	global_load_dwordx4 v[124:127], v[74:75], off offset:640
	s_waitcnt vmcnt(9)
	ds_write_b128 v132, v[116:119] offset:4608
	s_waitcnt vmcnt(8)
	ds_write_b128 v132, v[120:123] offset:23040
	ds_read_b128 v[116:119], v136 offset:36928
	ds_read_b128 v[120:123], v136 offset:41536
	ds_read_b128 v[232:235], v133 offset:55360
	ds_read_b128 v[236:239], v133 offset:59968
	s_waitcnt lgkmcnt(7)
	v_mfma_f32_32x32x16_bf16 v[48:63], v[80:83], v[240:243], v[48:63]
	s_waitcnt lgkmcnt(6)
	v_mfma_f32_32x32x16_bf16 v[32:47], v[80:83], v[244:247], v[32:47]
	v_mfma_f32_32x32x16_bf16 v[16:31], v[84:87], v[240:243], v[16:31]
	v_mfma_f32_32x32x16_bf16 v[0:15], v[84:87], v[244:247], v[0:15]
	global_load_dwordx4 v[80:83], v[68:69], off offset:640
	global_load_dwordx4 v[84:87], v[70:71], off offset:640
	s_waitcnt vmcnt(9)
	ds_write_b128 v132, v[88:91] offset:9216
	s_waitcnt vmcnt(8)
	ds_write_b128 v132, v[92:95] offset:27648
	ds_read_b128 v[88:91], v136 offset:36960
	ds_read_b128 v[92:95], v136 offset:41568
	ds_read_b128 v[240:243], v133 offset:55392
	ds_read_b128 v[244:247], v133 offset:60000
	s_waitcnt lgkmcnt(7)
	v_mfma_f32_32x32x16_bf16 v[48:63], v[116:119], v[232:235], v[48:63]
	s_waitcnt lgkmcnt(6)
	v_mfma_f32_32x32x16_bf16 v[32:47], v[116:119], v[236:239], v[32:47]
	v_mfma_f32_32x32x16_bf16 v[16:31], v[120:123], v[232:235], v[16:31]
	v_mfma_f32_32x32x16_bf16 v[0:15], v[120:123], v[236:239], v[0:15]
	global_load_dwordx4 v[116:119], v[64:65], off offset:640
	global_load_dwordx4 v[120:123], v[66:67], off offset:640
	s_waitcnt vmcnt(9)
	ds_write_b128 v132, v[96:99] offset:13824
	s_waitcnt vmcnt(8)
	ds_write_b128 v132, v[100:103] offset:32256
	s_waitcnt lgkmcnt(3)
	v_mfma_f32_32x32x16_bf16 v[48:63], v[88:91], v[240:243], v[48:63]
	s_waitcnt lgkmcnt(2)
	v_mfma_f32_32x32x16_bf16 v[32:47], v[88:91], v[244:247], v[32:47]
	v_mfma_f32_32x32x16_bf16 v[16:31], v[92:95], v[240:243], v[16:31]
	v_mfma_f32_32x32x16_bf16 v[0:15], v[92:95], v[244:247], v[0:15]
	s_waitcnt lgkmcnt(0)
	s_barrier
	global_load_dwordx4 v[88:91], v[76:77], off offset:768
	global_load_dwordx4 v[92:95], v[78:79], off offset:768
	ds_read_b128 v[96:99], v136
	ds_read_b128 v[100:103], v136 offset:4608
	ds_read_b128 v[232:235], v133 offset:18432
	ds_read_b128 v[236:239], v133 offset:23040
	s_waitcnt vmcnt(9)
	ds_write_b128 v132, v[104:107] offset:36864
	s_waitcnt vmcnt(8)
	ds_write_b128 v132, v[108:111] offset:55296
	ds_read_b128 v[104:107], v136 offset:32
	ds_read_b128 v[108:111], v136 offset:4640
	ds_read_b128 v[240:243], v133 offset:18464
	ds_read_b128 v[244:247], v133 offset:23072
	s_waitcnt lgkmcnt(7)
	v_mfma_f32_32x32x16_bf16 v[48:63], v[96:99], v[232:235], v[48:63]
	s_waitcnt lgkmcnt(6)
	v_mfma_f32_32x32x16_bf16 v[32:47], v[96:99], v[236:239], v[32:47]
	v_mfma_f32_32x32x16_bf16 v[16:31], v[100:103], v[232:235], v[16:31]
	v_mfma_f32_32x32x16_bf16 v[0:15], v[100:103], v[236:239], v[0:15]
	global_load_dwordx4 v[96:99], v[72:73], off offset:768
	global_load_dwordx4 v[100:103], v[74:75], off offset:768
	s_waitcnt vmcnt(9)
	ds_write_b128 v132, v[112:115] offset:41472
	s_waitcnt vmcnt(8)
	ds_write_b128 v132, v[124:127] offset:59904
	ds_read_b128 v[112:115], v136 offset:64
	ds_read_b128 v[124:127], v136 offset:4672
	ds_read_b128 v[232:235], v133 offset:18496
	ds_read_b128 v[236:239], v133 offset:23104
	s_waitcnt lgkmcnt(7)
	v_mfma_f32_32x32x16_bf16 v[48:63], v[104:107], v[240:243], v[48:63]
	s_waitcnt lgkmcnt(6)
	v_mfma_f32_32x32x16_bf16 v[32:47], v[104:107], v[244:247], v[32:47]
	v_mfma_f32_32x32x16_bf16 v[16:31], v[108:111], v[240:243], v[16:31]
	v_mfma_f32_32x32x16_bf16 v[0:15], v[108:111], v[244:247], v[0:15]
	global_load_dwordx4 v[104:107], v[68:69], off offset:768
	global_load_dwordx4 v[108:111], v[70:71], off offset:768
	s_waitcnt vmcnt(9)
	ds_write_b128 v132, v[80:83] offset:46080
	s_waitcnt vmcnt(8)
	ds_write_b128 v132, v[84:87] offset:64512
	ds_read_b128 v[80:83], v136 offset:96
	ds_read_b128 v[84:87], v136 offset:4704
	ds_read_b128 v[240:243], v133 offset:18528
	ds_read_b128 v[244:247], v133 offset:23136
	s_waitcnt lgkmcnt(7)
	v_mfma_f32_32x32x16_bf16 v[48:63], v[112:115], v[232:235], v[48:63]
	s_waitcnt lgkmcnt(6)
	v_mfma_f32_32x32x16_bf16 v[32:47], v[112:115], v[236:239], v[32:47]
	v_mfma_f32_32x32x16_bf16 v[16:31], v[124:127], v[232:235], v[16:31]
	v_mfma_f32_32x32x16_bf16 v[0:15], v[124:127], v[236:239], v[0:15]
	global_load_dwordx4 v[112:115], v[64:65], off offset:768
	global_load_dwordx4 v[124:127], v[66:67], off offset:768
	s_waitcnt vmcnt(9)
	ds_write_b128 v132, v[116:119] offset:50688
	s_waitcnt vmcnt(8)
	ds_write_b128 v137, v[120:123] offset:13824
	s_waitcnt lgkmcnt(3)
	v_mfma_f32_32x32x16_bf16 v[48:63], v[80:83], v[240:243], v[48:63]
	s_waitcnt lgkmcnt(2)
	v_mfma_f32_32x32x16_bf16 v[32:47], v[80:83], v[244:247], v[32:47]
	v_mfma_f32_32x32x16_bf16 v[16:31], v[84:87], v[240:243], v[16:31]
	v_mfma_f32_32x32x16_bf16 v[0:15], v[84:87], v[244:247], v[0:15]
	s_waitcnt lgkmcnt(0)
	s_barrier
; __device__ __forceinline__ void gemm_run(int tid, f32x16 (&acc)[2][2], GRegs& g, const GOp& o, int K, unsigned char* smem) {
;     ...
;     bf16r* cur = sbuf + (k & 1) * (256 * LDK);
;     bf16r* nxt = sbuf + ((k & 1) ^ 1) * (256 * LDK);
;     const bf16r* As = cur + (wm * 64 + fr) * LDK + fh * 8;
;     const bf16r* Bs = cur + 128 * LDK + (wn * 64 + fr) * LDK + fh * 8;
;     const bool wr = (k + 1 < nk), ld = (k + 2 < nk);
;     bf16x8 fa[2][2], fb[2][2];
;     fa[0][0] = *(const bf16x8*)(As);
;     fa[0][1] = *(const bf16x8*)(As + 32 * LDK);
;     fb[0][0] = *(const bf16x8*)(Bs);
;     fb[0][1] = *(const bf16x8*)(Bs + 32 * LDK);
; #pragma unroll
;     for (int i = 0; i < 4; i++) {
;       if (wr) {
;         *(u32x4*)(nxt + (r0 + i * 32) * LDK + sg * 8) = g.a[i];
;         *(u32x4*)(nxt + 128 * LDK + (r0 + i * 32) * LDK + sg * 8) = g.b[i];
;       }
;       if (ld) {
;         g.a[i] = *(const u32x4*)(Ap + (size_t)i * 32 * o.lda + (k + 2) * 64);
;         g.b[i] = *(const u32x4*)(Bp + o.bs.o[i] + (k + 2) * 64);
;       }
;       if (i < 3) {
;         fa[(i + 1) & 1][0] = *(const bf16x8*)(As + (i + 1) * 16);
;         fa[(i + 1) & 1][1] = *(const bf16x8*)(As + 32 * LDK + (i + 1) * 16);
;         fb[(i + 1) & 1][0] = *(const bf16x8*)(Bs + (i + 1) * 16);
;         fb[(i + 1) & 1][1] = *(const bf16x8*)(Bs + 32 * LDK + (i + 1) * 16);
;       }
;       __builtin_amdgcn_sched_barrier(0);
;       __builtin_amdgcn_s_setprio(1);
;       acc[0][0] = __builtin_amdgcn_mfma_f32_32x32x16_bf16(fa[i & 1][0], fb[i & 1][0], acc[0][0], 0, 0, 0);
;       acc[0][1] = __builtin_amdgcn_mfma_f32_32x32x16_bf16(fa[i & 1][0], fb[i & 1][1], acc[0][1], 0, 0, 0);
;       acc[1][0] = __builtin_amdgcn_mfma_f32_32x32x16_bf16(fa[i & 1][1], fb[i & 1][0], acc[1][0], 0, 0, 0);
;       acc[1][1] = __builtin_amdgcn_mfma_f32_32x32x16_bf16(fa[i & 1][1], fb[i & 1][1], acc[1][1], 0, 0, 0);
;       __builtin_amdgcn_s_setprio(0);
;     }
;     __syncthreads();
	global_load_dwordx4 v[80:83], v[76:77], off offset:896
	global_load_dwordx4 v[84:87], v[78:79], off offset:896
	ds_read_b128 v[116:119], v136 offset:36864
	ds_read_b128 v[120:123], v136 offset:41472
	ds_read_b128 v[232:235], v133 offset:55296
	ds_read_b128 v[236:239], v133 offset:59904
	s_waitcnt vmcnt(9)
	ds_write_b128 v132, v[88:91]
	s_waitcnt vmcnt(8)
	ds_write_b128 v132, v[92:95] offset:18432
	ds_read_b128 v[88:91], v136 offset:36896
	ds_read_b128 v[92:95], v136 offset:41504
	ds_read_b128 v[240:243], v133 offset:55328
	ds_read_b128 v[244:247], v133 offset:59936
	s_waitcnt lgkmcnt(7)
	v_mfma_f32_32x32x16_bf16 v[48:63], v[116:119], v[232:235], v[48:63]
	s_waitcnt lgkmcnt(6)
	v_mfma_f32_32x32x16_bf16 v[32:47], v[116:119], v[236:239], v[32:47]
	v_mfma_f32_32x32x16_bf16 v[16:31], v[120:123], v[232:235], v[16:31]
	v_mfma_f32_32x32x16_bf16 v[0:15], v[120:123], v[236:239], v[0:15]
	global_load_dwordx4 v[116:119], v[72:73], off offset:896
	global_load_dwordx4 v[120:123], v[74:75], off offset:896
	s_waitcnt vmcnt(9)
	ds_write_b128 v132, v[96:99] offset:4608
	s_waitcnt vmcnt(8)
	ds_write_b128 v132, v[100:103] offset:23040
	ds_read_b128 v[96:99], v136 offset:36928
	ds_read_b128 v[100:103], v136 offset:41536
	ds_read_b128 v[232:235], v133 offset:55360
	ds_read_b128 v[236:239], v133 offset:59968
	s_waitcnt lgkmcnt(7)
	v_mfma_f32_32x32x16_bf16 v[48:63], v[88:91], v[240:243], v[48:63]
	s_waitcnt lgkmcnt(6)
	v_mfma_f32_32x32x16_bf16 v[32:47], v[88:91], v[244:247], v[32:47]
	v_mfma_f32_32x32x16_bf16 v[16:31], v[92:95], v[240:243], v[16:31]
	v_mfma_f32_32x32x16_bf16 v[0:15], v[92:95], v[244:247], v[0:15]
	global_load_dwordx4 v[88:91], v[68:69], off offset:896
	global_load_dwordx4 v[92:95], v[70:71], off offset:896
	s_waitcnt vmcnt(9)
	ds_write_b128 v132, v[104:107] offset:9216
	s_waitcnt vmcnt(8)
	ds_write_b128 v132, v[108:111] offset:27648
	ds_read_b128 v[104:107], v136 offset:36960
	ds_read_b128 v[108:111], v136 offset:41568
	ds_read_b128 v[240:243], v133 offset:55392
	ds_read_b128 v[244:247], v133 offset:60000
	s_waitcnt lgkmcnt(7)
	v_mfma_f32_32x32x16_bf16 v[48:63], v[96:99], v[232:235], v[48:63]
	s_waitcnt lgkmcnt(6)
	v_mfma_f32_32x32x16_bf16 v[32:47], v[96:99], v[236:239], v[32:47]
	v_mfma_f32_32x32x16_bf16 v[16:31], v[100:103], v[232:235], v[16:31]
	v_mfma_f32_32x32x16_bf16 v[0:15], v[100:103], v[236:239], v[0:15]
	global_load_dwordx4 v[96:99], v[64:65], off offset:896
	global_load_dwordx4 v[100:103], v[66:67], off offset:896
	s_waitcnt vmcnt(9)
	ds_write_b128 v132, v[112:115] offset:13824
	s_waitcnt vmcnt(8)
	ds_write_b128 v132, v[124:127] offset:32256
	s_waitcnt lgkmcnt(3)
	v_mfma_f32_32x32x16_bf16 v[48:63], v[104:107], v[240:243], v[48:63]
	s_waitcnt lgkmcnt(2)
	v_mfma_f32_32x32x16_bf16 v[32:47], v[104:107], v[244:247], v[32:47]
	v_mfma_f32_32x32x16_bf16 v[16:31], v[108:111], v[240:243], v[16:31]
	v_mfma_f32_32x32x16_bf16 v[0:15], v[108:111], v[244:247], v[0:15]
	s_waitcnt lgkmcnt(0)
	s_barrier
	global_load_dwordx4 v[104:107], v[76:77], off offset:1024
	global_load_dwordx4 v[108:111], v[78:79], off offset:1024
	ds_read_b128 v[112:115], v136
	ds_read_b128 v[124:127], v136 offset:4608
	ds_read_b128 v[232:235], v133 offset:18432
	ds_read_b128 v[236:239], v133 offset:23040
	s_waitcnt vmcnt(9)
	ds_write_b128 v132, v[80:83] offset:36864
	s_waitcnt vmcnt(8)
	ds_write_b128 v132, v[84:87] offset:55296
	ds_read_b128 v[80:83], v136 offset:32
	ds_read_b128 v[84:87], v136 offset:4640
	ds_read_b128 v[240:243], v133 offset:18464
	ds_read_b128 v[244:247], v133 offset:23072
	s_waitcnt lgkmcnt(7)
	v_mfma_f32_32x32x16_bf16 v[48:63], v[112:115], v[232:235], v[48:63]
	s_waitcnt lgkmcnt(6)
	v_mfma_f32_32x32x16_bf16 v[32:47], v[112:115], v[236:239], v[32:47]
	v_mfma_f32_32x32x16_bf16 v[16:31], v[124:127], v[232:235], v[16:31]
	v_mfma_f32_32x32x16_bf16 v[0:15], v[124:127], v[236:239], v[0:15]
	global_load_dwordx4 v[112:115], v[72:73], off offset:1024
	global_load_dwordx4 v[124:127], v[74:75], off offset:1024
	s_waitcnt vmcnt(9)
	ds_write_b128 v132, v[116:119] offset:41472
	s_waitcnt vmcnt(8)
	ds_write_b128 v132, v[120:123] offset:59904
	ds_read_b128 v[116:119], v136 offset:64
	ds_read_b128 v[120:123], v136 offset:4672
	ds_read_b128 v[232:235], v133 offset:18496
	ds_read_b128 v[236:239], v133 offset:23104
	s_waitcnt lgkmcnt(7)
	v_mfma_f32_32x32x16_bf16 v[48:63], v[80:83], v[240:243], v[48:63]
	s_waitcnt lgkmcnt(6)
	v_mfma_f32_32x32x16_bf16 v[32:47], v[80:83], v[244:247], v[32:47]
	v_mfma_f32_32x32x16_bf16 v[16:31], v[84:87], v[240:243], v[16:31]
	v_mfma_f32_32x32x16_bf16 v[0:15], v[84:87], v[244:247], v[0:15]
	global_load_dwordx4 v[80:83], v[68:69], off offset:1024
	global_load_dwordx4 v[84:87], v[70:71], off offset:1024
	s_waitcnt vmcnt(9)
	ds_write_b128 v132, v[88:91] offset:46080
	s_waitcnt vmcnt(8)
	ds_write_b128 v132, v[92:95] offset:64512
	ds_read_b128 v[88:91], v136 offset:96
	ds_read_b128 v[92:95], v136 offset:4704
	ds_read_b128 v[240:243], v133 offset:18528
	ds_read_b128 v[244:247], v133 offset:23136
	s_waitcnt lgkmcnt(7)
	v_mfma_f32_32x32x16_bf16 v[48:63], v[116:119], v[232:235], v[48:63]
	s_waitcnt lgkmcnt(6)
	v_mfma_f32_32x32x16_bf16 v[32:47], v[116:119], v[236:239], v[32:47]
	v_mfma_f32_32x32x16_bf16 v[16:31], v[120:123], v[232:235], v[16:31]
	v_mfma_f32_32x32x16_bf16 v[0:15], v[120:123], v[236:239], v[0:15]
	global_load_dwordx4 v[116:119], v[64:65], off offset:1024
	global_load_dwordx4 v[120:123], v[66:67], off offset:1024
	s_waitcnt vmcnt(9)
	ds_write_b128 v132, v[96:99] offset:50688
	s_waitcnt vmcnt(8)
	ds_write_b128 v137, v[100:103] offset:13824
	s_waitcnt lgkmcnt(3)
	v_mfma_f32_32x32x16_bf16 v[48:63], v[88:91], v[240:243], v[48:63]
	s_waitcnt lgkmcnt(2)
	v_mfma_f32_32x32x16_bf16 v[32:47], v[88:91], v[244:247], v[32:47]
	v_mfma_f32_32x32x16_bf16 v[16:31], v[92:95], v[240:243], v[16:31]
	v_mfma_f32_32x32x16_bf16 v[0:15], v[92:95], v[244:247], v[0:15]
	s_waitcnt lgkmcnt(0)
	s_barrier
; __device__ __forceinline__ void gemm_run(int tid, f32x16 (&acc)[2][2], GRegs& g, const GOp& o, int K, unsigned char* smem) {
;     ...
;     bf16r* cur = sbuf + (k & 1) * (256 * LDK);
;     bf16r* nxt = sbuf + ((k & 1) ^ 1) * (256 * LDK);
;     const bf16r* As = cur + (wm * 64 + fr) * LDK + fh * 8;
;     const bf16r* Bs = cur + 128 * LDK + (wn * 64 + fr) * LDK + fh * 8;
;     const bool wr = (k + 1 < nk), ld = (k + 2 < nk);
;     bf16x8 fa[2][2], fb[2][2];
;     fa[0][0] = *(const bf16x8*)(As);
;     fa[0][1] = *(const bf16x8*)(As + 32 * LDK);
;     fb[0][0] = *(const bf16x8*)(Bs);
;     fb[0][1] = *(const bf16x8*)(Bs + 32 * LDK);
; #pragma unroll
;     for (int i = 0; i < 4; i++) {
;       if (wr) {
;         *(u32x4*)(nxt + (r0 + i * 32) * LDK + sg * 8) = g.a[i];
;         *(u32x4*)(nxt + 128 * LDK + (r0 + i * 32) * LDK + sg * 8) = g.b[i];
;       }
;       if (ld) {
;         g.a[i] = *(const u32x4*)(Ap + (size_t)i * 32 * o.lda + (k + 2) * 64);
;         g.b[i] = *(const u32x4*)(Bp + o.bs.o[i] + (k + 2) * 64);
;       }
;       if (i < 3) {
;         fa[(i + 1) & 1][0] = *(const bf16x8*)(As + (i + 1) * 16);
;         fa[(i + 1) & 1][1] = *(const bf16x8*)(As + 32 * LDK + (i + 1) * 16);
;         fb[(i + 1) & 1][0] = *(const bf16x8*)(Bs + (i + 1) * 16);
;         fb[(i + 1) & 1][1] = *(const bf16x8*)(Bs + 32 * LDK + (i + 1) * 16);
;       }
;       __builtin_amdgcn_sched_barrier(0);
;       __builtin_amdgcn_s_setprio(1);
;       acc[0][0] = __builtin_amdgcn_mfma_f32_32x32x16_bf16(fa[i & 1][0], fb[i & 1][0], acc[0][0], 0, 0, 0);
;       acc[0][1] = __builtin_amdgcn_mfma_f32_32x32x16_bf16(fa[i & 1][0], fb[i & 1][1], acc[0][1], 0, 0, 0);
;       acc[1][0] = __builtin_amdgcn_mfma_f32_32x32x16_bf16(fa[i & 1][1], fb[i & 1][0], acc[1][0], 0, 0, 0);
;       acc[1][1] = __builtin_amdgcn_mfma_f32_32x32x16_bf16(fa[i & 1][1], fb[i & 1][1], acc[1][1], 0, 0, 0);
;       __builtin_amdgcn_s_setprio(0);
;     }
;     __syncthreads();
	global_load_dwordx4 v[88:91], v[76:77], off offset:1152
	global_load_dwordx4 v[92:95], v[78:79], off offset:1152
	ds_read_b128 v[96:99], v136 offset:36864
	ds_read_b128 v[100:103], v136 offset:41472
	ds_read_b128 v[232:235], v133 offset:55296
	ds_read_b128 v[236:239], v133 offset:59904
	s_waitcnt vmcnt(9)
	ds_write_b128 v132, v[104:107]
	s_waitcnt vmcnt(8)
	ds_write_b128 v132, v[108:111] offset:18432
	ds_read_b128 v[104:107], v136 offset:36896
	ds_read_b128 v[108:111], v136 offset:41504
	ds_read_b128 v[240:243], v133 offset:55328
	ds_read_b128 v[244:247], v133 offset:59936
	s_waitcnt lgkmcnt(7)
	v_mfma_f32_32x32x16_bf16 v[48:63], v[96:99], v[232:235], v[48:63]
	s_waitcnt lgkmcnt(6)
	v_mfma_f32_32x32x16_bf16 v[32:47], v[96:99], v[236:239], v[32:47]
	v_mfma_f32_32x32x16_bf16 v[16:31], v[100:103], v[232:235], v[16:31]
	v_mfma_f32_32x32x16_bf16 v[0:15], v[100:103], v[236:239], v[0:15]
	global_load_dwordx4 v[96:99], v[72:73], off offset:1152
	global_load_dwordx4 v[100:103], v[74:75], off offset:1152
	s_waitcnt vmcnt(9)
	ds_write_b128 v132, v[112:115] offset:4608
	s_waitcnt vmcnt(8)
	ds_write_b128 v132, v[124:127] offset:23040
	ds_read_b128 v[112:115], v136 offset:36928
	ds_read_b128 v[124:127], v136 offset:41536
	ds_read_b128 v[232:235], v133 offset:55360
	ds_read_b128 v[236:239], v133 offset:59968
	s_waitcnt lgkmcnt(7)
	v_mfma_f32_32x32x16_bf16 v[48:63], v[104:107], v[240:243], v[48:63]
	s_waitcnt lgkmcnt(6)
	v_mfma_f32_32x32x16_bf16 v[32:47], v[104:107], v[244:247], v[32:47]
	v_mfma_f32_32x32x16_bf16 v[16:31], v[108:111], v[240:243], v[16:31]
	v_mfma_f32_32x32x16_bf16 v[0:15], v[108:111], v[244:247], v[0:15]
	global_load_dwordx4 v[104:107], v[68:69], off offset:1152
	global_load_dwordx4 v[108:111], v[70:71], off offset:1152
	s_waitcnt vmcnt(9)
	ds_write_b128 v132, v[80:83] offset:9216
	s_waitcnt vmcnt(8)
	ds_write_b128 v132, v[84:87] offset:27648
	ds_read_b128 v[80:83], v136 offset:36960
	ds_read_b128 v[84:87], v136 offset:41568
	ds_read_b128 v[240:243], v133 offset:55392
	ds_read_b128 v[244:247], v133 offset:60000
	s_waitcnt lgkmcnt(7)
	v_mfma_f32_32x32x16_bf16 v[48:63], v[112:115], v[232:235], v[48:63]
	s_waitcnt lgkmcnt(6)
	v_mfma_f32_32x32x16_bf16 v[32:47], v[112:115], v[236:239], v[32:47]
	v_mfma_f32_32x32x16_bf16 v[16:31], v[124:127], v[232:235], v[16:31]
	v_mfma_f32_32x32x16_bf16 v[0:15], v[124:127], v[236:239], v[0:15]
	global_load_dwordx4 v[112:115], v[64:65], off offset:1152
	global_load_dwordx4 v[124:127], v[66:67], off offset:1152
	s_waitcnt vmcnt(9)
	ds_write_b128 v132, v[116:119] offset:13824
	s_waitcnt vmcnt(8)
	ds_write_b128 v132, v[120:123] offset:32256
	s_waitcnt lgkmcnt(3)
	v_mfma_f32_32x32x16_bf16 v[48:63], v[80:83], v[240:243], v[48:63]
	s_waitcnt lgkmcnt(2)
	v_mfma_f32_32x32x16_bf16 v[32:47], v[80:83], v[244:247], v[32:47]
	v_mfma_f32_32x32x16_bf16 v[16:31], v[84:87], v[240:243], v[16:31]
	v_mfma_f32_32x32x16_bf16 v[0:15], v[84:87], v[244:247], v[0:15]
	s_waitcnt lgkmcnt(0)
	s_barrier
	global_load_dwordx4 v[80:83], v[76:77], off offset:1280
	global_load_dwordx4 v[84:87], v[78:79], off offset:1280
	ds_read_b128 v[116:119], v136
	ds_read_b128 v[120:123], v136 offset:4608
	ds_read_b128 v[232:235], v133 offset:18432
	ds_read_b128 v[236:239], v133 offset:23040
	s_waitcnt vmcnt(9)
	ds_write_b128 v132, v[88:91] offset:36864
	s_waitcnt vmcnt(8)
	ds_write_b128 v132, v[92:95] offset:55296
	ds_read_b128 v[88:91], v136 offset:32
	ds_read_b128 v[92:95], v136 offset:4640
	ds_read_b128 v[240:243], v133 offset:18464
	ds_read_b128 v[244:247], v133 offset:23072
	s_waitcnt lgkmcnt(7)
	v_mfma_f32_32x32x16_bf16 v[48:63], v[116:119], v[232:235], v[48:63]
	s_waitcnt lgkmcnt(6)
	v_mfma_f32_32x32x16_bf16 v[32:47], v[116:119], v[236:239], v[32:47]
	v_mfma_f32_32x32x16_bf16 v[16:31], v[120:123], v[232:235], v[16:31]
	v_mfma_f32_32x32x16_bf16 v[0:15], v[120:123], v[236:239], v[0:15]
	global_load_dwordx4 v[116:119], v[72:73], off offset:1280
	global_load_dwordx4 v[120:123], v[74:75], off offset:1280
	s_waitcnt vmcnt(9)
	ds_write_b128 v132, v[96:99] offset:41472
	s_waitcnt vmcnt(8)
	ds_write_b128 v132, v[100:103] offset:59904
	ds_read_b128 v[96:99], v136 offset:64
	ds_read_b128 v[100:103], v136 offset:4672
	ds_read_b128 v[232:235], v133 offset:18496
	ds_read_b128 v[236:239], v133 offset:23104
	s_waitcnt lgkmcnt(7)
	v_mfma_f32_32x32x16_bf16 v[48:63], v[88:91], v[240:243], v[48:63]
	s_waitcnt lgkmcnt(6)
	v_mfma_f32_32x32x16_bf16 v[32:47], v[88:91], v[244:247], v[32:47]
	v_mfma_f32_32x32x16_bf16 v[16:31], v[92:95], v[240:243], v[16:31]
	v_mfma_f32_32x32x16_bf16 v[0:15], v[92:95], v[244:247], v[0:15]
	global_load_dwordx4 v[88:91], v[68:69], off offset:1280
	global_load_dwordx4 v[92:95], v[70:71], off offset:1280
	s_waitcnt vmcnt(9)
	ds_write_b128 v132, v[104:107] offset:46080
	s_waitcnt vmcnt(8)
	ds_write_b128 v132, v[108:111] offset:64512
	ds_read_b128 v[104:107], v136 offset:96
	ds_read_b128 v[108:111], v136 offset:4704
	ds_read_b128 v[240:243], v133 offset:18528
	ds_read_b128 v[244:247], v133 offset:23136
	s_waitcnt lgkmcnt(7)
	v_mfma_f32_32x32x16_bf16 v[48:63], v[96:99], v[232:235], v[48:63]
	s_waitcnt lgkmcnt(6)
	v_mfma_f32_32x32x16_bf16 v[32:47], v[96:99], v[236:239], v[32:47]
	v_mfma_f32_32x32x16_bf16 v[16:31], v[100:103], v[232:235], v[16:31]
	v_mfma_f32_32x32x16_bf16 v[0:15], v[100:103], v[236:239], v[0:15]
	global_load_dwordx4 v[96:99], v[64:65], off offset:1280
	global_load_dwordx4 v[100:103], v[66:67], off offset:1280
	s_waitcnt vmcnt(9)
	ds_write_b128 v132, v[112:115] offset:50688
	s_waitcnt vmcnt(8)
	ds_write_b128 v137, v[124:127] offset:13824
	s_waitcnt lgkmcnt(3)
	v_mfma_f32_32x32x16_bf16 v[48:63], v[104:107], v[240:243], v[48:63]
	s_waitcnt lgkmcnt(2)
	v_mfma_f32_32x32x16_bf16 v[32:47], v[104:107], v[244:247], v[32:47]
	v_mfma_f32_32x32x16_bf16 v[16:31], v[108:111], v[240:243], v[16:31]
	v_mfma_f32_32x32x16_bf16 v[0:15], v[108:111], v[244:247], v[0:15]
	s_waitcnt lgkmcnt(0)
	s_barrier
; __device__ __forceinline__ void gemm_run(int tid, f32x16 (&acc)[2][2], GRegs& g, const GOp& o, int K, unsigned char* smem) {
;     ...
;     bf16r* cur = sbuf + (k & 1) * (256 * LDK);
;     bf16r* nxt = sbuf + ((k & 1) ^ 1) * (256 * LDK);
;     const bf16r* As = cur + (wm * 64 + fr) * LDK + fh * 8;
;     const bf16r* Bs = cur + 128 * LDK + (wn * 64 + fr) * LDK + fh * 8;
;     const bool wr = (k + 1 < nk), ld = (k + 2 < nk);
;     bf16x8 fa[2][2], fb[2][2];
;     fa[0][0] = *(const bf16x8*)(As);
;     fa[0][1] = *(const bf16x8*)(As + 32 * LDK);
;     fb[0][0] = *(const bf16x8*)(Bs);
;     fb[0][1] = *(const bf16x8*)(Bs + 32 * LDK);
; #pragma unroll
;     for (int i = 0; i < 4; i++) {
;       if (wr) {
;         *(u32x4*)(nxt + (r0 + i * 32) * LDK + sg * 8) = g.a[i];
;         *(u32x4*)(nxt + 128 * LDK + (r0 + i * 32) * LDK + sg * 8) = g.b[i];
;       }
;       if (ld) {
;         g.a[i] = *(const u32x4*)(Ap + (size_t)i * 32 * o.lda + (k + 2) * 64);
;         g.b[i] = *(const u32x4*)(Bp + o.bs.o[i] + (k + 2) * 64);
;       }
;       if (i < 3) {
;         fa[(i + 1) & 1][0] = *(const bf16x8*)(As + (i + 1) * 16);
;         fa[(i + 1) & 1][1] = *(const bf16x8*)(As + 32 * LDK + (i + 1) * 16);
;         fb[(i + 1) & 1][0] = *(const bf16x8*)(Bs + (i + 1) * 16);
;         fb[(i + 1) & 1][1] = *(const bf16x8*)(Bs + 32 * LDK + (i + 1) * 16);
;       }
;       __builtin_amdgcn_sched_barrier(0);
;       __builtin_amdgcn_s_setprio(1);
;       acc[0][0] = __builtin_amdgcn_mfma_f32_32x32x16_bf16(fa[i & 1][0], fb[i & 1][0], acc[0][0], 0, 0, 0);
;       acc[0][1] = __builtin_amdgcn_mfma_f32_32x32x16_bf16(fa[i & 1][0], fb[i & 1][1], acc[0][1], 0, 0, 0);
;       acc[1][0] = __builtin_amdgcn_mfma_f32_32x32x16_bf16(fa[i & 1][1], fb[i & 1][0], acc[1][0], 0, 0, 0);
;       acc[1][1] = __builtin_amdgcn_mfma_f32_32x32x16_bf16(fa[i & 1][1], fb[i & 1][1], acc[1][1], 0, 0, 0);
;       __builtin_amdgcn_s_setprio(0);
;     }
;     __syncthreads();
	global_load_dwordx4 v[104:107], v[76:77], off offset:1408
	global_load_dwordx4 v[108:111], v[78:79], off offset:1408
	ds_read_b128 v[112:115], v136 offset:36864
	ds_read_b128 v[124:127], v136 offset:41472
	ds_read_b128 v[232:235], v133 offset:55296
	ds_read_b128 v[236:239], v133 offset:59904
	s_waitcnt vmcnt(9)
	ds_write_b128 v132, v[80:83]
	s_waitcnt vmcnt(8)
	ds_write_b128 v132, v[84:87] offset:18432
	ds_read_b128 v[80:83], v136 offset:36896
	ds_read_b128 v[84:87], v136 offset:41504
	ds_read_b128 v[240:243], v133 offset:55328
	ds_read_b128 v[244:247], v133 offset:59936
	s_waitcnt lgkmcnt(7)
	v_mfma_f32_32x32x16_bf16 v[48:63], v[112:115], v[232:235], v[48:63]
	s_waitcnt lgkmcnt(6)
	v_mfma_f32_32x32x16_bf16 v[32:47], v[112:115], v[236:239], v[32:47]
	v_mfma_f32_32x32x16_bf16 v[16:31], v[124:127], v[232:235], v[16:31]
	v_mfma_f32_32x32x16_bf16 v[0:15], v[124:127], v[236:239], v[0:15]
	global_load_dwordx4 v[112:115], v[72:73], off offset:1408
	global_load_dwordx4 v[124:127], v[74:75], off offset:1408
	s_waitcnt vmcnt(9)
	ds_write_b128 v132, v[116:119] offset:4608
	s_waitcnt vmcnt(8)
	ds_write_b128 v132, v[120:123] offset:23040
	ds_read_b128 v[116:119], v136 offset:36928
	ds_read_b128 v[120:123], v136 offset:41536
	ds_read_b128 v[232:235], v133 offset:55360
	ds_read_b128 v[236:239], v133 offset:59968
	s_waitcnt lgkmcnt(7)
	v_mfma_f32_32x32x16_bf16 v[48:63], v[80:83], v[240:243], v[48:63]
	s_waitcnt lgkmcnt(6)
	v_mfma_f32_32x32x16_bf16 v[32:47], v[80:83], v[244:247], v[32:47]
	v_mfma_f32_32x32x16_bf16 v[16:31], v[84:87], v[240:243], v[16:31]
	v_mfma_f32_32x32x16_bf16 v[0:15], v[84:87], v[244:247], v[0:15]
	global_load_dwordx4 v[80:83], v[68:69], off offset:1408
	global_load_dwordx4 v[84:87], v[70:71], off offset:1408
	s_waitcnt vmcnt(9)
	ds_write_b128 v132, v[88:91] offset:9216
	s_waitcnt vmcnt(8)
	ds_write_b128 v132, v[92:95] offset:27648
	ds_read_b128 v[88:91], v136 offset:36960
	ds_read_b128 v[92:95], v136 offset:41568
	ds_read_b128 v[240:243], v133 offset:55392
	ds_read_b128 v[244:247], v133 offset:60000
	s_waitcnt lgkmcnt(7)
	v_mfma_f32_32x32x16_bf16 v[48:63], v[116:119], v[232:235], v[48:63]
	s_waitcnt lgkmcnt(6)
	v_mfma_f32_32x32x16_bf16 v[32:47], v[116:119], v[236:239], v[32:47]
	v_mfma_f32_32x32x16_bf16 v[16:31], v[120:123], v[232:235], v[16:31]
	v_mfma_f32_32x32x16_bf16 v[0:15], v[120:123], v[236:239], v[0:15]
	global_load_dwordx4 v[116:119], v[64:65], off offset:1408
	global_load_dwordx4 v[120:123], v[66:67], off offset:1408
	s_waitcnt vmcnt(9)
	ds_write_b128 v132, v[96:99] offset:13824
	s_waitcnt vmcnt(8)
	ds_write_b128 v132, v[100:103] offset:32256
	s_waitcnt lgkmcnt(3)
	v_mfma_f32_32x32x16_bf16 v[48:63], v[88:91], v[240:243], v[48:63]
	s_waitcnt lgkmcnt(2)
	v_mfma_f32_32x32x16_bf16 v[32:47], v[88:91], v[244:247], v[32:47]
	v_mfma_f32_32x32x16_bf16 v[16:31], v[92:95], v[240:243], v[16:31]
	v_mfma_f32_32x32x16_bf16 v[0:15], v[92:95], v[244:247], v[0:15]
	s_waitcnt lgkmcnt(0)
	s_barrier
	global_load_dwordx4 v[88:91], v[76:77], off offset:1536
	global_load_dwordx4 v[92:95], v[78:79], off offset:1536
	ds_read_b128 v[96:99], v136
	ds_read_b128 v[100:103], v136 offset:4608
	ds_read_b128 v[232:235], v133 offset:18432
	ds_read_b128 v[236:239], v133 offset:23040
	s_waitcnt vmcnt(9)
	ds_write_b128 v132, v[104:107] offset:36864
	s_waitcnt vmcnt(8)
	ds_write_b128 v132, v[108:111] offset:55296
	ds_read_b128 v[104:107], v136 offset:32
	ds_read_b128 v[108:111], v136 offset:4640
	ds_read_b128 v[240:243], v133 offset:18464
	ds_read_b128 v[244:247], v133 offset:23072
	s_waitcnt lgkmcnt(7)
	v_mfma_f32_32x32x16_bf16 v[48:63], v[96:99], v[232:235], v[48:63]
	s_waitcnt lgkmcnt(6)
	v_mfma_f32_32x32x16_bf16 v[32:47], v[96:99], v[236:239], v[32:47]
	v_mfma_f32_32x32x16_bf16 v[16:31], v[100:103], v[232:235], v[16:31]
	v_mfma_f32_32x32x16_bf16 v[0:15], v[100:103], v[236:239], v[0:15]
	global_load_dwordx4 v[96:99], v[72:73], off offset:1536
	global_load_dwordx4 v[100:103], v[74:75], off offset:1536
	s_waitcnt vmcnt(9)
	ds_write_b128 v132, v[112:115] offset:41472
	s_waitcnt vmcnt(8)
	ds_write_b128 v132, v[124:127] offset:59904
	ds_read_b128 v[112:115], v136 offset:64
	ds_read_b128 v[124:127], v136 offset:4672
	ds_read_b128 v[232:235], v133 offset:18496
	ds_read_b128 v[236:239], v133 offset:23104
	s_waitcnt lgkmcnt(7)
	v_mfma_f32_32x32x16_bf16 v[48:63], v[104:107], v[240:243], v[48:63]
	s_waitcnt lgkmcnt(6)
	v_mfma_f32_32x32x16_bf16 v[32:47], v[104:107], v[244:247], v[32:47]
	v_mfma_f32_32x32x16_bf16 v[16:31], v[108:111], v[240:243], v[16:31]
	v_mfma_f32_32x32x16_bf16 v[0:15], v[108:111], v[244:247], v[0:15]
	global_load_dwordx4 v[104:107], v[68:69], off offset:1536
	global_load_dwordx4 v[108:111], v[70:71], off offset:1536
	s_waitcnt vmcnt(9)
	ds_write_b128 v132, v[80:83] offset:46080
	s_waitcnt vmcnt(8)
	ds_write_b128 v132, v[84:87] offset:64512
	ds_read_b128 v[80:83], v136 offset:96
	ds_read_b128 v[84:87], v136 offset:4704
	ds_read_b128 v[240:243], v133 offset:18528
	ds_read_b128 v[244:247], v133 offset:23136
	s_waitcnt lgkmcnt(7)
	v_mfma_f32_32x32x16_bf16 v[48:63], v[112:115], v[232:235], v[48:63]
	s_waitcnt lgkmcnt(6)
	v_mfma_f32_32x32x16_bf16 v[32:47], v[112:115], v[236:239], v[32:47]
	v_mfma_f32_32x32x16_bf16 v[16:31], v[124:127], v[232:235], v[16:31]
	v_mfma_f32_32x32x16_bf16 v[0:15], v[124:127], v[236:239], v[0:15]
	global_load_dwordx4 v[112:115], v[64:65], off offset:1536
	global_load_dwordx4 v[124:127], v[66:67], off offset:1536
	s_waitcnt vmcnt(9)
	ds_write_b128 v132, v[116:119] offset:50688
	s_waitcnt vmcnt(8)
	ds_write_b128 v137, v[120:123] offset:13824
	s_waitcnt lgkmcnt(3)
	v_mfma_f32_32x32x16_bf16 v[48:63], v[80:83], v[240:243], v[48:63]
	s_waitcnt lgkmcnt(2)
	v_mfma_f32_32x32x16_bf16 v[32:47], v[80:83], v[244:247], v[32:47]
	v_mfma_f32_32x32x16_bf16 v[16:31], v[84:87], v[240:243], v[16:31]
	v_mfma_f32_32x32x16_bf16 v[0:15], v[84:87], v[244:247], v[0:15]
	s_waitcnt lgkmcnt(0)
	s_barrier
; __device__ __forceinline__ void gemm_run(int tid, f32x16 (&acc)[2][2], GRegs& g, const GOp& o, int K, unsigned char* smem) {
;     ...
;     bf16r* cur = sbuf + (k & 1) * (256 * LDK);
;     bf16r* nxt = sbuf + ((k & 1) ^ 1) * (256 * LDK);
;     const bf16r* As = cur + (wm * 64 + fr) * LDK + fh * 8;
;     const bf16r* Bs = cur + 128 * LDK + (wn * 64 + fr) * LDK + fh * 8;
;     const bool wr = (k + 1 < nk), ld = (k + 2 < nk);
;     bf16x8 fa[2][2], fb[2][2];
;     fa[0][0] = *(const bf16x8*)(As);
;     fa[0][1] = *(const bf16x8*)(As + 32 * LDK);
;     fb[0][0] = *(const bf16x8*)(Bs);
;     fb[0][1] = *(const bf16x8*)(Bs + 32 * LDK);
; #pragma unroll
;     for (int i = 0; i < 4; i++) {
;       if (wr) {
;         *(u32x4*)(nxt + (r0 + i * 32) * LDK + sg * 8) = g.a[i];
;         *(u32x4*)(nxt + 128 * LDK + (r0 + i * 32) * LDK + sg * 8) = g.b[i];
;       }
;       if (ld) {
;         g.a[i] = *(const u32x4*)(Ap + (size_t)i * 32 * o.lda + (k + 2) * 64);
;         g.b[i] = *(const u32x4*)(Bp + o.bs.o[i] + (k + 2) * 64);
;       }
;       if (i < 3) {
;         fa[(i + 1) & 1][0] = *(const bf16x8*)(As + (i + 1) * 16);
;         fa[(i + 1) & 1][1] = *(const bf16x8*)(As + 32 * LDK + (i + 1) * 16);
;         fb[(i + 1) & 1][0] = *(const bf16x8*)(Bs + (i + 1) * 16);
;         fb[(i + 1) & 1][1] = *(const bf16x8*)(Bs + 32 * LDK + (i + 1) * 16);
;       }
;       __builtin_amdgcn_sched_barrier(0);
;       __builtin_amdgcn_s_setprio(1);
;       acc[0][0] = __builtin_amdgcn_mfma_f32_32x32x16_bf16(fa[i & 1][0], fb[i & 1][0], acc[0][0], 0, 0, 0);
;       acc[0][1] = __builtin_amdgcn_mfma_f32_32x32x16_bf16(fa[i & 1][0], fb[i & 1][1], acc[0][1], 0, 0, 0);
;       acc[1][0] = __builtin_amdgcn_mfma_f32_32x32x16_bf16(fa[i & 1][1], fb[i & 1][0], acc[1][0], 0, 0, 0);
;       acc[1][1] = __builtin_amdgcn_mfma_f32_32x32x16_bf16(fa[i & 1][1], fb[i & 1][1], acc[1][1], 0, 0, 0);
;       __builtin_amdgcn_s_setprio(0);
;     }
;     __syncthreads();
	global_load_dwordx4 v[80:83], v[76:77], off offset:1664
	global_load_dwordx4 v[84:87], v[78:79], off offset:1664
	ds_read_b128 v[116:119], v136 offset:36864
	ds_read_b128 v[120:123], v136 offset:41472
	ds_read_b128 v[232:235], v133 offset:55296
	ds_read_b128 v[236:239], v133 offset:59904
	s_waitcnt vmcnt(9)
	ds_write_b128 v132, v[88:91]
	s_waitcnt vmcnt(8)
	ds_write_b128 v132, v[92:95] offset:18432
	ds_read_b128 v[88:91], v136 offset:36896
	ds_read_b128 v[92:95], v136 offset:41504
	ds_read_b128 v[240:243], v133 offset:55328
	ds_read_b128 v[244:247], v133 offset:59936
	s_waitcnt lgkmcnt(7)
	v_mfma_f32_32x32x16_bf16 v[48:63], v[116:119], v[232:235], v[48:63]
	s_waitcnt lgkmcnt(6)
	v_mfma_f32_32x32x16_bf16 v[32:47], v[116:119], v[236:239], v[32:47]
	v_mfma_f32_32x32x16_bf16 v[16:31], v[120:123], v[232:235], v[16:31]
	v_mfma_f32_32x32x16_bf16 v[0:15], v[120:123], v[236:239], v[0:15]
	global_load_dwordx4 v[116:119], v[72:73], off offset:1664
	global_load_dwordx4 v[120:123], v[74:75], off offset:1664
	s_waitcnt vmcnt(9)
	ds_write_b128 v132, v[96:99] offset:4608
	s_waitcnt vmcnt(8)
	ds_write_b128 v132, v[100:103] offset:23040
	ds_read_b128 v[96:99], v136 offset:36928
	ds_read_b128 v[100:103], v136 offset:41536
	ds_read_b128 v[232:235], v133 offset:55360
	ds_read_b128 v[236:239], v133 offset:59968
	s_waitcnt lgkmcnt(7)
	v_mfma_f32_32x32x16_bf16 v[48:63], v[88:91], v[240:243], v[48:63]
	s_waitcnt lgkmcnt(6)
	v_mfma_f32_32x32x16_bf16 v[32:47], v[88:91], v[244:247], v[32:47]
	v_mfma_f32_32x32x16_bf16 v[16:31], v[92:95], v[240:243], v[16:31]
	v_mfma_f32_32x32x16_bf16 v[0:15], v[92:95], v[244:247], v[0:15]
	global_load_dwordx4 v[88:91], v[68:69], off offset:1664
	global_load_dwordx4 v[92:95], v[70:71], off offset:1664
	s_waitcnt vmcnt(9)
	ds_write_b128 v132, v[104:107] offset:9216
	s_waitcnt vmcnt(8)
	ds_write_b128 v132, v[108:111] offset:27648
	ds_read_b128 v[104:107], v136 offset:36960
	ds_read_b128 v[108:111], v136 offset:41568
	ds_read_b128 v[240:243], v133 offset:55392
	ds_read_b128 v[244:247], v133 offset:60000
	s_waitcnt lgkmcnt(7)
	v_mfma_f32_32x32x16_bf16 v[48:63], v[96:99], v[232:235], v[48:63]
	s_waitcnt lgkmcnt(6)
	v_mfma_f32_32x32x16_bf16 v[32:47], v[96:99], v[236:239], v[32:47]
	v_mfma_f32_32x32x16_bf16 v[16:31], v[100:103], v[232:235], v[16:31]
	v_mfma_f32_32x32x16_bf16 v[0:15], v[100:103], v[236:239], v[0:15]
	global_load_dwordx4 v[96:99], v[64:65], off offset:1664
	global_load_dwordx4 v[100:103], v[66:67], off offset:1664
	s_waitcnt vmcnt(9)
	ds_write_b128 v132, v[112:115] offset:13824
	s_waitcnt vmcnt(8)
	ds_write_b128 v132, v[124:127] offset:32256
	s_waitcnt lgkmcnt(3)
	v_mfma_f32_32x32x16_bf16 v[48:63], v[104:107], v[240:243], v[48:63]
	s_waitcnt lgkmcnt(2)
	v_mfma_f32_32x32x16_bf16 v[32:47], v[104:107], v[244:247], v[32:47]
	v_mfma_f32_32x32x16_bf16 v[16:31], v[108:111], v[240:243], v[16:31]
	v_mfma_f32_32x32x16_bf16 v[0:15], v[108:111], v[244:247], v[0:15]
	s_waitcnt lgkmcnt(0)
	s_barrier
	global_load_dwordx4 v[104:107], v[76:77], off offset:1792
	global_load_dwordx4 v[108:111], v[78:79], off offset:1792
	ds_read_b128 v[112:115], v136
	ds_read_b128 v[124:127], v136 offset:4608
	ds_read_b128 v[232:235], v133 offset:18432
	ds_read_b128 v[236:239], v133 offset:23040
	s_waitcnt vmcnt(9)
	ds_write_b128 v132, v[80:83] offset:36864
	s_waitcnt vmcnt(8)
	ds_write_b128 v132, v[84:87] offset:55296
	ds_read_b128 v[80:83], v136 offset:32
	ds_read_b128 v[84:87], v136 offset:4640
	ds_read_b128 v[240:243], v133 offset:18464
	ds_read_b128 v[244:247], v133 offset:23072
	s_waitcnt lgkmcnt(7)
	v_mfma_f32_32x32x16_bf16 v[48:63], v[112:115], v[232:235], v[48:63]
	s_waitcnt lgkmcnt(6)
	v_mfma_f32_32x32x16_bf16 v[32:47], v[112:115], v[236:239], v[32:47]
	v_mfma_f32_32x32x16_bf16 v[16:31], v[124:127], v[232:235], v[16:31]
	v_mfma_f32_32x32x16_bf16 v[0:15], v[124:127], v[236:239], v[0:15]
	global_load_dwordx4 v[112:115], v[72:73], off offset:1792
	global_load_dwordx4 v[124:127], v[74:75], off offset:1792
	s_waitcnt vmcnt(9)
	ds_write_b128 v132, v[116:119] offset:41472
	s_waitcnt vmcnt(8)
	ds_write_b128 v132, v[120:123] offset:59904
	ds_read_b128 v[116:119], v136 offset:64
	ds_read_b128 v[120:123], v136 offset:4672
	ds_read_b128 v[232:235], v133 offset:18496
	ds_read_b128 v[236:239], v133 offset:23104
	s_waitcnt lgkmcnt(7)
	v_mfma_f32_32x32x16_bf16 v[48:63], v[80:83], v[240:243], v[48:63]
	s_waitcnt lgkmcnt(6)
	v_mfma_f32_32x32x16_bf16 v[32:47], v[80:83], v[244:247], v[32:47]
	v_mfma_f32_32x32x16_bf16 v[16:31], v[84:87], v[240:243], v[16:31]
	v_mfma_f32_32x32x16_bf16 v[0:15], v[84:87], v[244:247], v[0:15]
	global_load_dwordx4 v[80:83], v[68:69], off offset:1792
	global_load_dwordx4 v[84:87], v[70:71], off offset:1792
	s_waitcnt vmcnt(9)
	ds_write_b128 v132, v[88:91] offset:46080
	s_waitcnt vmcnt(8)
	ds_write_b128 v132, v[92:95] offset:64512
	ds_read_b128 v[88:91], v136 offset:96
	ds_read_b128 v[92:95], v136 offset:4704
	ds_read_b128 v[240:243], v133 offset:18528
	ds_read_b128 v[244:247], v133 offset:23136
	s_waitcnt lgkmcnt(7)
	v_mfma_f32_32x32x16_bf16 v[48:63], v[116:119], v[232:235], v[48:63]
	s_waitcnt lgkmcnt(6)
	v_mfma_f32_32x32x16_bf16 v[32:47], v[116:119], v[236:239], v[32:47]
	v_mfma_f32_32x32x16_bf16 v[16:31], v[120:123], v[232:235], v[16:31]
	v_mfma_f32_32x32x16_bf16 v[0:15], v[120:123], v[236:239], v[0:15]
	global_load_dwordx4 v[232:235], v[64:65], off offset:1792
	global_load_dwordx4 v[236:239], v[66:67], off offset:1792
	s_waitcnt vmcnt(9)
	ds_write_b128 v132, v[96:99] offset:50688
	s_waitcnt vmcnt(8)
	ds_write_b128 v137, v[100:103] offset:13824
	s_waitcnt lgkmcnt(3)
	v_mfma_f32_32x32x16_bf16 v[48:63], v[88:91], v[240:243], v[48:63]
	s_waitcnt lgkmcnt(2)
	v_mfma_f32_32x32x16_bf16 v[32:47], v[88:91], v[244:247], v[32:47]
	v_mfma_f32_32x32x16_bf16 v[16:31], v[92:95], v[240:243], v[16:31]
	v_mfma_f32_32x32x16_bf16 v[0:15], v[92:95], v[244:247], v[0:15]
	s_waitcnt lgkmcnt(0)
	s_barrier
; __device__ __forceinline__ void gemm_run(int tid, f32x16 (&acc)[2][2], GRegs& g, const GOp& o, int K, unsigned char* smem) {
;     ...
;     bf16r* cur = sbuf + (k & 1) * (256 * LDK);
;     bf16r* nxt = sbuf + ((k & 1) ^ 1) * (256 * LDK);
;     const bf16r* As = cur + (wm * 64 + fr) * LDK + fh * 8;
;     const bf16r* Bs = cur + 128 * LDK + (wn * 64 + fr) * LDK + fh * 8;
;     const bool wr = (k + 1 < nk), ld = (k + 2 < nk);
;     bf16x8 fa[2][2], fb[2][2];
;     fa[0][0] = *(const bf16x8*)(As);
;     fa[0][1] = *(const bf16x8*)(As + 32 * LDK);
;     fb[0][0] = *(const bf16x8*)(Bs);
;     fb[0][1] = *(const bf16x8*)(Bs + 32 * LDK);
; #pragma unroll
;     for (int i = 0; i < 4; i++) {
;       if (wr) {
;         *(u32x4*)(nxt + (r0 + i * 32) * LDK + sg * 8) = g.a[i];
;         *(u32x4*)(nxt + 128 * LDK + (r0 + i * 32) * LDK + sg * 8) = g.b[i];
;       }
;       if (ld) {
;         g.a[i] = *(const u32x4*)(Ap + (size_t)i * 32 * o.lda + (k + 2) * 64);
;         g.b[i] = *(const u32x4*)(Bp + o.bs.o[i] + (k + 2) * 64);
;       }
;       if (i < 3) {
;         fa[(i + 1) & 1][0] = *(const bf16x8*)(As + (i + 1) * 16);
;         fa[(i + 1) & 1][1] = *(const bf16x8*)(As + 32 * LDK + (i + 1) * 16);
;         fb[(i + 1) & 1][0] = *(const bf16x8*)(Bs + (i + 1) * 16);
;         fb[(i + 1) & 1][1] = *(const bf16x8*)(Bs + 32 * LDK + (i + 1) * 16);
;       }
;       __builtin_amdgcn_sched_barrier(0);
;       __builtin_amdgcn_s_setprio(1);
;       acc[0][0] = __builtin_amdgcn_mfma_f32_32x32x16_bf16(fa[i & 1][0], fb[i & 1][0], acc[0][0], 0, 0, 0);
;       acc[0][1] = __builtin_amdgcn_mfma_f32_32x32x16_bf16(fa[i & 1][0], fb[i & 1][1], acc[0][1], 0, 0, 0);
;       acc[1][0] = __builtin_amdgcn_mfma_f32_32x32x16_bf16(fa[i & 1][1], fb[i & 1][0], acc[1][0], 0, 0, 0);
;       acc[1][1] = __builtin_amdgcn_mfma_f32_32x32x16_bf16(fa[i & 1][1], fb[i & 1][1], acc[1][1], 0, 0, 0);
;       __builtin_amdgcn_s_setprio(0);
;     }
;     __syncthreads();
	global_load_dwordx4 v[100:103], v[76:77], off offset:1920
	global_load_dwordx4 v[96:99], v[78:79], off offset:1920
	ds_read_b128 v[76:79], v136 offset:36864
	ds_read_b128 v[88:91], v136 offset:41472
	ds_read_b128 v[92:95], v133 offset:55296
	ds_read_b128 v[116:119], v133 offset:59904
	s_waitcnt vmcnt(9)
	ds_write_b128 v132, v[104:107]
	s_waitcnt vmcnt(8)
	ds_write_b128 v132, v[108:111] offset:18432
	ds_read_b128 v[120:123], v136 offset:36896
	ds_read_b128 v[240:243], v136 offset:41504
	ds_read_b128 v[244:247], v133 offset:55328
	ds_read_b128 v[248:251], v133 offset:59936
	s_waitcnt lgkmcnt(7)
	v_mfma_f32_32x32x16_bf16 v[48:63], v[76:79], v[92:95], v[48:63]
	s_waitcnt lgkmcnt(6)
	v_mfma_f32_32x32x16_bf16 v[32:47], v[76:79], v[116:119], v[32:47]
	v_mfma_f32_32x32x16_bf16 v[16:31], v[88:91], v[92:95], v[16:31]
	v_mfma_f32_32x32x16_bf16 v[0:15], v[88:91], v[116:119], v[0:15]
	global_load_dwordx4 v[108:111], v[72:73], off offset:1920
	global_load_dwordx4 v[104:107], v[74:75], off offset:1920
	s_waitcnt vmcnt(9)
	ds_write_b128 v132, v[112:115] offset:4608
	s_waitcnt vmcnt(8)
	ds_write_b128 v132, v[124:127] offset:23040
	ds_read_b128 v[72:75], v136 offset:36928
	ds_read_b128 v[76:79], v136 offset:41536
	ds_read_b128 v[88:91], v133 offset:55360
	ds_read_b128 v[92:95], v133 offset:59968
	s_waitcnt lgkmcnt(7)
	v_mfma_f32_32x32x16_bf16 v[48:63], v[120:123], v[244:247], v[48:63]
	s_waitcnt lgkmcnt(6)
	v_mfma_f32_32x32x16_bf16 v[32:47], v[120:123], v[248:251], v[32:47]
	v_mfma_f32_32x32x16_bf16 v[16:31], v[240:243], v[244:247], v[16:31]
	v_mfma_f32_32x32x16_bf16 v[0:15], v[240:243], v[248:251], v[0:15]
	global_load_dwordx4 v[116:119], v[68:69], off offset:1920
	global_load_dwordx4 v[112:115], v[70:71], off offset:1920
	s_waitcnt vmcnt(9)
	ds_write_b128 v132, v[80:83] offset:9216
	s_waitcnt vmcnt(8)
	ds_write_b128 v132, v[84:87] offset:27648
	ds_read_b128 v[68:71], v136 offset:36960
	ds_read_b128 v[80:83], v136 offset:41568
	ds_read_b128 v[84:87], v133 offset:55392
	ds_read_b128 v[240:243], v133 offset:60000
	s_waitcnt lgkmcnt(7)
	v_mfma_f32_32x32x16_bf16 v[48:63], v[72:75], v[88:91], v[48:63]
	s_waitcnt lgkmcnt(6)
	v_mfma_f32_32x32x16_bf16 v[32:47], v[72:75], v[92:95], v[32:47]
	v_mfma_f32_32x32x16_bf16 v[16:31], v[76:79], v[88:91], v[16:31]
	v_mfma_f32_32x32x16_bf16 v[0:15], v[76:79], v[92:95], v[0:15]
	global_load_dwordx4 v[124:127], v[64:65], off offset:1920
	global_load_dwordx4 v[120:123], v[66:67], off offset:1920
	s_waitcnt vmcnt(9)
	ds_write_b128 v132, v[232:235] offset:13824
	s_waitcnt vmcnt(8)
	ds_write_b128 v132, v[236:239] offset:32256
	s_waitcnt lgkmcnt(3)
	v_mfma_f32_32x32x16_bf16 v[48:63], v[68:71], v[84:87], v[48:63]
	s_waitcnt lgkmcnt(2)
	v_mfma_f32_32x32x16_bf16 v[32:47], v[68:71], v[240:243], v[32:47]
	v_mfma_f32_32x32x16_bf16 v[16:31], v[80:83], v[84:87], v[16:31]
	v_mfma_f32_32x32x16_bf16 v[0:15], v[80:83], v[240:243], v[0:15]
	s_waitcnt lgkmcnt(0)
	s_barrier
	ds_read_b128 v[64:67], v136
	ds_read_b128 v[68:71], v136 offset:4608
	ds_read_b128 v[72:75], v133 offset:18432
	ds_read_b128 v[76:79], v133 offset:23040
	s_waitcnt vmcnt(7)
	ds_write_b128 v132, v[100:103] offset:36864
	s_waitcnt vmcnt(6)
	ds_write_b128 v132, v[96:99] offset:55296
	ds_read_b128 v[80:83], v136 offset:32
	ds_read_b128 v[84:87], v136 offset:4640
	ds_read_b128 v[88:91], v133 offset:18464
	ds_read_b128 v[92:95], v133 offset:23072
	s_waitcnt lgkmcnt(7)
	v_mfma_f32_32x32x16_bf16 v[48:63], v[64:67], v[72:75], v[48:63]
	s_waitcnt lgkmcnt(6)
	v_mfma_f32_32x32x16_bf16 v[32:47], v[64:67], v[76:79], v[32:47]
	v_mfma_f32_32x32x16_bf16 v[16:31], v[68:71], v[72:75], v[16:31]
	v_mfma_f32_32x32x16_bf16 v[0:15], v[68:71], v[76:79], v[0:15]
	s_waitcnt vmcnt(5)
	ds_write_b128 v132, v[108:111] offset:41472
	s_waitcnt vmcnt(4)
	ds_write_b128 v132, v[104:107] offset:59904
	ds_read_b128 v[64:67], v136 offset:64
	ds_read_b128 v[68:71], v136 offset:4672
	ds_read_b128 v[72:75], v133 offset:18496
	ds_read_b128 v[76:79], v133 offset:23104
	s_waitcnt lgkmcnt(7)
	v_mfma_f32_32x32x16_bf16 v[48:63], v[80:83], v[88:91], v[48:63]
	s_waitcnt lgkmcnt(6)
	v_mfma_f32_32x32x16_bf16 v[32:47], v[80:83], v[92:95], v[32:47]
	v_mfma_f32_32x32x16_bf16 v[16:31], v[84:87], v[88:91], v[16:31]
	v_mfma_f32_32x32x16_bf16 v[0:15], v[84:87], v[92:95], v[0:15]
	s_waitcnt vmcnt(3)
	ds_write_b128 v132, v[116:119] offset:46080
	s_waitcnt vmcnt(2)
	ds_write_b128 v132, v[112:115] offset:64512
	ds_read_b128 v[80:83], v136 offset:96
	ds_read_b128 v[84:87], v136 offset:4704
	ds_read_b128 v[88:91], v133 offset:18528
	ds_read_b128 v[92:95], v133 offset:23136
	s_waitcnt lgkmcnt(7)
	v_mfma_f32_32x32x16_bf16 v[48:63], v[64:67], v[72:75], v[48:63]
	s_waitcnt lgkmcnt(6)
	v_mfma_f32_32x32x16_bf16 v[32:47], v[64:67], v[76:79], v[32:47]
	v_mfma_f32_32x32x16_bf16 v[16:31], v[68:71], v[72:75], v[16:31]
	v_mfma_f32_32x32x16_bf16 v[0:15], v[68:71], v[76:79], v[0:15]
	s_waitcnt vmcnt(1)
	ds_write_b128 v132, v[124:127] offset:50688
	s_waitcnt vmcnt(0)
	ds_write_b128 v137, v[120:123] offset:13824
	s_waitcnt lgkmcnt(3)
	v_mfma_f32_32x32x16_bf16 v[48:63], v[80:83], v[88:91], v[48:63]
	s_waitcnt lgkmcnt(2)
	v_mfma_f32_32x32x16_bf16 v[32:47], v[80:83], v[92:95], v[32:47]
	v_mfma_f32_32x32x16_bf16 v[16:31], v[84:87], v[88:91], v[16:31]
	v_mfma_f32_32x32x16_bf16 v[0:15], v[84:87], v[92:95], v[0:15]
	s_waitcnt lgkmcnt(0)
	s_barrier
; __device__ __forceinline__ void gemm_run(int tid, f32x16 (&acc)[2][2], GRegs& g, const GOp& o, int K, unsigned char* smem) {
;     ...
;     fa[0][0] = *(const bf16x8*)(As);
;     fa[0][1] = *(const bf16x8*)(As + 32 * LDK);
;     fb[0][0] = *(const bf16x8*)(Bs);
;     fb[0][1] = *(const bf16x8*)(Bs + 32 * LDK);
; #pragma unroll
;     for (int i = 0; i < 4; i++) {
;       if (wr) {
;         *(u32x4*)(nxt + (r0 + i * 32) * LDK + sg * 8) = g.a[i];
;         *(u32x4*)(nxt + 128 * LDK + (r0 + i * 32) * LDK + sg * 8) = g.b[i];
;       }
;       if (ld) {
;         g.a[i] = *(const u32x4*)(Ap + (size_t)i * 32 * o.lda + (k + 2) * 64);
;         g.b[i] = *(const u32x4*)(Bp + o.bs.o[i] + (k + 2) * 64);
;       }
;       if (i < 3) {
;         fa[(i + 1) & 1][0] = *(const bf16x8*)(As + (i + 1) * 16);
;         fa[(i + 1) & 1][1] = *(const bf16x8*)(As + 32 * LDK + (i + 1) * 16);
;         fb[(i + 1) & 1][0] = *(const bf16x8*)(Bs + (i + 1) * 16);
;         fb[(i + 1) & 1][1] = *(const bf16x8*)(Bs + 32 * LDK + (i + 1) * 16);
;       }
;       __builtin_amdgcn_sched_barrier(0);
;       __builtin_amdgcn_s_setprio(1);
;       acc[0][0] = __builtin_amdgcn_mfma_f32_32x32x16_bf16(fa[i & 1][0], fb[i & 1][0], acc[0][0], 0, 0, 0);
;       acc[0][1] = __builtin_amdgcn_mfma_f32_32x32x16_bf16(fa[i & 1][0], fb[i & 1][1], acc[0][1], 0, 0, 0);
;       acc[1][0] = __builtin_amdgcn_mfma_f32_32x32x16_bf16(fa[i & 1][1], fb[i & 1][0], acc[1][0], 0, 0, 0);
;       acc[1][1] = __builtin_amdgcn_mfma_f32_32x32x16_bf16(fa[i & 1][1], fb[i & 1][1], acc[1][1], 0, 0, 0);
;       __builtin_amdgcn_s_setprio(0);
;     }
;     __syncthreads();
; __device__ __forceinline__ void phase_merge(const Params& p, unsigned char* smem) {
;     ...
;       gemm_run(tid, au, g, make_gop(Y + n * UE + (size_t)m0 * 1024, 1024, WbrT + ((size_t)n * 1024 + d0) * 1024, 1024), 1024, smem);
;       if (n < 3) gemm_issue0(tid, g, make_gop(Y + (n + 1) * UE + (size_t)m0 * 1024, 1024, WbrT + ((size_t)(n + 1) * 1024 + d0) * 1024, 1024));
;       else if (have2) gemm_issue0(tid, g, make_gop(Y + (size_t)mt2 * 128 * 1024, 1024, WbrT + (size_t)dtl2 * 128 * 1024, 1024));
	ds_read_b128 v[64:67], v136 offset:36864
	ds_read_b128 v[68:71], v136 offset:36896
	ds_read_b128 v[72:75], v136 offset:41472
	ds_read_b128 v[76:79], v136 offset:41504
	ds_read_b128 v[80:83], v133 offset:55296
	ds_read_b128 v[84:87], v133 offset:55328
	ds_read_b128 v[88:91], v133 offset:59904
	ds_read_b128 v[92:95], v133 offset:59936
	s_waitcnt lgkmcnt(3)
	v_mfma_f32_32x32x16_bf16 v[48:63], v[64:67], v[80:83], v[48:63]
	s_waitcnt lgkmcnt(1)
	v_mfma_f32_32x32x16_bf16 v[32:47], v[64:67], v[88:91], v[32:47]
	v_mfma_f32_32x32x16_bf16 v[16:31], v[72:75], v[80:83], v[16:31]
	v_mfma_f32_32x32x16_bf16 v[0:15], v[72:75], v[88:91], v[0:15]
	ds_read_b128 v[64:67], v136 offset:36928
	ds_read_b128 v[72:75], v136 offset:41536
	ds_read_b128 v[80:83], v133 offset:55360
	ds_read_b128 v[88:91], v133 offset:59968
	v_mfma_f32_32x32x16_bf16 v[48:63], v[68:71], v[84:87], v[48:63]
	s_waitcnt lgkmcnt(4)
	v_mfma_f32_32x32x16_bf16 v[32:47], v[68:71], v[92:95], v[32:47]
	v_mfma_f32_32x32x16_bf16 v[16:31], v[76:79], v[84:87], v[16:31]
	v_mfma_f32_32x32x16_bf16 v[0:15], v[76:79], v[92:95], v[0:15]
	ds_read_b128 v[68:71], v136 offset:36960
	ds_read_b128 v[76:79], v136 offset:41568
	ds_read_b128 v[84:87], v133 offset:55392
	ds_read_b128 v[92:95], v133 offset:60000
	s_waitcnt lgkmcnt(5)
	v_mfma_f32_32x32x16_bf16 v[48:63], v[64:67], v[80:83], v[48:63]
	s_waitcnt lgkmcnt(4)
	v_mfma_f32_32x32x16_bf16 v[32:47], v[64:67], v[88:91], v[32:47]
	v_mfma_f32_32x32x16_bf16 v[16:31], v[72:75], v[80:83], v[16:31]
	v_mfma_f32_32x32x16_bf16 v[0:15], v[72:75], v[88:91], v[0:15]
	s_waitcnt lgkmcnt(1)
	v_mfma_f32_32x32x16_bf16 v[48:63], v[68:71], v[84:87], v[48:63]
	s_waitcnt lgkmcnt(0)
	v_mfma_f32_32x32x16_bf16 v[32:47], v[68:71], v[92:95], v[32:47]
	v_mfma_f32_32x32x16_bf16 v[16:31], v[76:79], v[84:87], v[16:31]
	v_mfma_f32_32x32x16_bf16 v[0:15], v[76:79], v[92:95], v[0:15]
	s_cmp_eq_u32 s76, 3
	s_mov_b64 s[24:25], -1
	s_barrier
	s_cbranch_scc1 .LBB0_2291
	v_add_co_u32_e32 v64, vcc, 0xbdc0000, v228
	s_mov_b64 s[24:25], 0
	s_nop 0
	v_addc_co_u32_e32 v65, vcc, 0, v229, vcc
	v_add_co_u32_e32 v68, vcc, 0x8500000, v226
	global_load_dwordx4 v[64:67], v[64:65], off
	s_nop 0
	v_addc_co_u32_e32 v69, vcc, 0, v227, vcc
	v_add_co_u32_e32 v72, vcc, 0xbdd0000, v228
	global_load_dwordx4 v[68:71], v[68:69], off
	s_nop 0
	v_addc_co_u32_e32 v73, vcc, 0, v229, vcc
	v_add_co_u32_e32 v76, vcc, 0x8510000, v226
	global_load_dwordx4 v[72:75], v[72:73], off
	s_nop 0
	v_addc_co_u32_e32 v77, vcc, 0, v227, vcc
	v_add_co_u32_e32 v80, vcc, 0xbde0000, v228
	global_load_dwordx4 v[76:79], v[76:77], off
	s_nop 0
	v_addc_co_u32_e32 v81, vcc, 0, v229, vcc
	v_add_co_u32_e32 v84, vcc, 0x8520000, v226
	global_load_dwordx4 v[80:83], v[80:81], off
	s_nop 0
	v_addc_co_u32_e32 v85, vcc, 0, v227, vcc
	v_add_co_u32_e32 v88, vcc, 0xbdf0000, v228
	global_load_dwordx4 v[84:87], v[84:85], off
	s_nop 0
	v_addc_co_u32_e32 v89, vcc, 0, v229, vcc
	v_add_co_u32_e32 v92, vcc, 0x8530000, v226
	global_load_dwordx4 v[88:91], v[88:89], off
	s_nop 0
	v_addc_co_u32_e32 v93, vcc, 0, v227, vcc
	global_load_dwordx4 v[92:95], v[92:93], off

; __device__ __forceinline__ void gemm_run(int tid, f32x16 (&acc)[2][2], GRegs& g, const GOp& o, int K, unsigned char* smem) {
;     ...
;   for (int k = 0; k < nk; k++) {
;     bf16r* cur = sbuf + (k & 1) * (256 * LDK);
;     bf16r* nxt = sbuf + ((k & 1) ^ 1) * (256 * LDK);
;     const bf16r* As = cur + (wm * 64 + fr) * LDK + fh * 8;
;     const bf16r* Bs = cur + 128 * LDK + (wn * 64 + fr) * LDK + fh * 8;
;     const bool wr = (k + 1 < nk), ld = (k + 2 < nk);
;     bf16x8 fa[2][2], fb[2][2];
;     fa[0][0] = *(const bf16x8*)(As);
;     fa[0][1] = *(const bf16x8*)(As + 32 * LDK);
;     fb[0][0] = *(const bf16x8*)(Bs);
;     fb[0][1] = *(const bf16x8*)(Bs + 32 * LDK);
; #pragma unroll
;     for (int i = 0; i < 4; i++) {
;       if (wr) {
;         *(u32x4*)(nxt + (r0 + i * 32) * LDK + sg * 8) = g.a[i];
;         *(u32x4*)(nxt + 128 * LDK + (r0 + i * 32) * LDK + sg * 8) = g.b[i];
;       }
;       if (ld) {
;         g.a[i] = *(const u32x4*)(Ap + (size_t)i * 32 * o.lda + (k + 2) * 64);
;         g.b[i] = *(const u32x4*)(Bp + o.bs.o[i] + (k + 2) * 64);
;       }
;       if (i < 3) {
;         fa[(i + 1) & 1][0] = *(const bf16x8*)(As + (i + 1) * 16);
;         fa[(i + 1) & 1][1] = *(const bf16x8*)(As + 32 * LDK + (i + 1) * 16);
;         fb[(i + 1) & 1][0] = *(const bf16x8*)(Bs + (i + 1) * 16);
;         fb[(i + 1) & 1][1] = *(const bf16x8*)(Bs + 32 * LDK + (i + 1) * 16);
;       }
;       __builtin_amdgcn_sched_barrier(0);
;       __builtin_amdgcn_s_setprio(1);
;       acc[0][0] = __builtin_amdgcn_mfma_f32_32x32x16_bf16(fa[i & 1][0], fb[i & 1][0], acc[0][0], 0, 0, 0);
;       acc[0][1] = __builtin_amdgcn_mfma_f32_32x32x16_bf16(fa[i & 1][0], fb[i & 1][1], acc[0][1], 0, 0, 0);
;       acc[1][0] = __builtin_amdgcn_mfma_f32_32x32x16_bf16(fa[i & 1][1], fb[i & 1][0], acc[1][0], 0, 0, 0);
;       acc[1][1] = __builtin_amdgcn_mfma_f32_32x32x16_bf16(fa[i & 1][1], fb[i & 1][1], acc[1][1], 0, 0, 0);
;       __builtin_amdgcn_s_setprio(0);
;     }
;     __syncthreads();
;   }
.LBB0_2344:
	s_and_b32 s5, s1, 1
	v_lshl_add_u64 v[148:149], v[108:109], 0, s[10:11]
	s_mul_i32 s7, s5, 0x9000
	s_xor_b32 s5, s5, 1
	v_add_co_u32_e32 v132, vcc, s21, v148
	s_mul_i32 s5, s5, 0x9000
	v_lshl_add_u64 v[150:151], v[106:107], 0, s[10:11]
	v_addc_co_u32_e32 v133, vcc, 0, v149, vcc
	v_add3_u32 v96, s7, v101, v112
	v_add_u32_e32 v153, s5, v100
	v_add_co_u32_e32 v134, vcc, s22, v150
	v_add3_u32 v152, s7, v111, v112
	ds_read_b128 v[116:119], v96
	ds_read_b128 v[120:123], v96 offset:4608
	ds_read_b128 v[124:127], v152 offset:18432
	ds_read_b128 v[128:131], v152 offset:23040
	s_waitcnt vmcnt(7)
	ds_write_b128 v153, v[64:67]
	s_waitcnt vmcnt(6)
	ds_write_b128 v153, v[68:71] offset:18432
	v_addc_co_u32_e32 v135, vcc, 0, v151, vcc
	global_load_dwordx4 v[64:67], v[132:133], off offset:256
	global_load_dwordx4 v[68:71], v[134:135], off offset:256
	ds_read_b128 v[132:135], v96 offset:32
	ds_read_b128 v[136:139], v96 offset:4640
	ds_read_b128 v[140:143], v152 offset:18464
	ds_read_b128 v[144:147], v152 offset:23072
	s_add_i32 s1, s1, 1
	s_waitcnt lgkmcnt(7)
	v_mfma_f32_32x32x16_bf16 v[48:63], v[116:119], v[124:127], v[48:63]
	s_waitcnt lgkmcnt(6)
	v_mfma_f32_32x32x16_bf16 v[32:47], v[116:119], v[128:131], v[32:47]
	v_mfma_f32_32x32x16_bf16 v[16:31], v[120:123], v[124:127], v[16:31]
	v_mfma_f32_32x32x16_bf16 v[0:15], v[120:123], v[128:131], v[0:15]
	s_waitcnt vmcnt(7)
	ds_write_b128 v153, v[72:75] offset:4608
	s_waitcnt vmcnt(6)
	ds_write_b128 v153, v[76:79] offset:23040
	v_add_co_u32_e32 v72, vcc, s23, v148
	s_nop 1
	v_addc_co_u32_e32 v73, vcc, 0, v149, vcc
	v_add_co_u32_e32 v76, vcc, s24, v150
	s_nop 1
	v_addc_co_u32_e32 v77, vcc, 0, v151, vcc
	global_load_dwordx4 v[72:75], v[72:73], off offset:256
	s_nop 0
	global_load_dwordx4 v[76:79], v[76:77], off offset:256
	ds_read_b128 v[116:119], v96 offset:64
	ds_read_b128 v[120:123], v96 offset:4672
	ds_read_b128 v[124:127], v152 offset:18496
	ds_read_b128 v[128:131], v152 offset:23104
	s_waitcnt lgkmcnt(7)
	v_mfma_f32_32x32x16_bf16 v[48:63], v[132:135], v[140:143], v[48:63]
	s_waitcnt lgkmcnt(6)
	v_mfma_f32_32x32x16_bf16 v[32:47], v[132:135], v[144:147], v[32:47]
	v_mfma_f32_32x32x16_bf16 v[16:31], v[136:139], v[140:143], v[16:31]
	v_mfma_f32_32x32x16_bf16 v[0:15], v[136:139], v[144:147], v[0:15]
	s_waitcnt vmcnt(7)
	ds_write_b128 v153, v[80:83] offset:9216
	s_waitcnt vmcnt(6)
	ds_write_b128 v153, v[84:87] offset:27648
	v_add_co_u32_e32 v80, vcc, s25, v148
	s_nop 1
	v_addc_co_u32_e32 v81, vcc, 0, v149, vcc
	v_add_co_u32_e32 v84, vcc, s26, v150
	s_nop 1
	v_addc_co_u32_e32 v85, vcc, 0, v151, vcc
	global_load_dwordx4 v[80:83], v[80:81], off offset:256
	s_nop 0
	global_load_dwordx4 v[84:87], v[84:85], off offset:256
	ds_read_b128 v[132:135], v96 offset:96
	ds_read_b128 v[136:139], v96 offset:4704
	ds_read_b128 v[140:143], v152 offset:18528
	ds_read_b128 v[144:147], v152 offset:23136
	s_waitcnt lgkmcnt(7)
	v_mfma_f32_32x32x16_bf16 v[48:63], v[116:119], v[124:127], v[48:63]
	s_waitcnt lgkmcnt(6)
	v_mfma_f32_32x32x16_bf16 v[32:47], v[116:119], v[128:131], v[32:47]
	v_mfma_f32_32x32x16_bf16 v[16:31], v[120:123], v[124:127], v[16:31]
	v_mfma_f32_32x32x16_bf16 v[0:15], v[120:123], v[128:131], v[0:15]
	s_waitcnt vmcnt(7)
	ds_write_b128 v153, v[88:91] offset:13824
	s_waitcnt vmcnt(6)
	ds_write_b128 v153, v[92:95] offset:32256
	v_add_co_u32_e32 v88, vcc, s27, v148
	s_nop 1
	v_addc_co_u32_e32 v89, vcc, 0, v149, vcc
	v_add_co_u32_e32 v92, vcc, s28, v150
	s_nop 1
	v_addc_co_u32_e32 v93, vcc, 0, v151, vcc
	global_load_dwordx4 v[88:91], v[88:89], off offset:256
	s_nop 0
	global_load_dwordx4 v[92:95], v[92:93], off offset:256
	s_waitcnt lgkmcnt(3)
	v_mfma_f32_32x32x16_bf16 v[48:63], v[132:135], v[140:143], v[48:63]
	s_waitcnt lgkmcnt(2)
	v_mfma_f32_32x32x16_bf16 v[32:47], v[132:135], v[144:147], v[32:47]
	v_mfma_f32_32x32x16_bf16 v[16:31], v[136:139], v[140:143], v[16:31]
	v_mfma_f32_32x32x16_bf16 v[0:15], v[136:139], v[144:147], v[0:15]
	s_add_u32 s10, s10, 0x80
	s_addc_u32 s11, s11, 0
	s_cmpk_eq_i32 s10, 0x700
	s_waitcnt lgkmcnt(0)
	s_barrier
	s_cbranch_scc0 .LBB0_2344
; __device__ __forceinline__ void gemm_run(int tid, f32x16 (&acc)[2][2], GRegs& g, const GOp& o, int K, unsigned char* smem) {
;     ...
;   for (int k = 0; k < nk; k++) {
;     bf16r* cur = sbuf + (k & 1) * (256 * LDK);
;     bf16r* nxt = sbuf + ((k & 1) ^ 1) * (256 * LDK);
;     const bf16r* As = cur + (wm * 64 + fr) * LDK + fh * 8;
;     const bf16r* Bs = cur + 128 * LDK + (wn * 64 + fr) * LDK + fh * 8;
;     const bool wr = (k + 1 < nk), ld = (k + 2 < nk);
;     bf16x8 fa[2][2], fb[2][2];
;     fa[0][0] = *(const bf16x8*)(As);
;     fa[0][1] = *(const bf16x8*)(As + 32 * LDK);
;     fb[0][0] = *(const bf16x8*)(Bs);
;     fb[0][1] = *(const bf16x8*)(Bs + 32 * LDK);
; #pragma unroll
;     for (int i = 0; i < 4; i++) {
;       if (wr) {
;         *(u32x4*)(nxt + (r0 + i * 32) * LDK + sg * 8) = g.a[i];
;         *(u32x4*)(nxt + 128 * LDK + (r0 + i * 32) * LDK + sg * 8) = g.b[i];
;       }
;       if (ld) {
;         g.a[i] = *(const u32x4*)(Ap + (size_t)i * 32 * o.lda + (k + 2) * 64);
;         g.b[i] = *(const u32x4*)(Bp + o.bs.o[i] + (k + 2) * 64);
;       }
;       if (i < 3) {
;         fa[(i + 1) & 1][0] = *(const bf16x8*)(As + (i + 1) * 16);
;         fa[(i + 1) & 1][1] = *(const bf16x8*)(As + 32 * LDK + (i + 1) * 16);
;         fb[(i + 1) & 1][0] = *(const bf16x8*)(Bs + (i + 1) * 16);
;         fb[(i + 1) & 1][1] = *(const bf16x8*)(Bs + 32 * LDK + (i + 1) * 16);
;       }
;       __builtin_amdgcn_sched_barrier(0);
;       __builtin_amdgcn_s_setprio(1);
;       acc[0][0] = __builtin_amdgcn_mfma_f32_32x32x16_bf16(fa[i & 1][0], fb[i & 1][0], acc[0][0], 0, 0, 0);
;       acc[0][1] = __builtin_amdgcn_mfma_f32_32x32x16_bf16(fa[i & 1][0], fb[i & 1][1], acc[0][1], 0, 0, 0);
;       acc[1][0] = __builtin_amdgcn_mfma_f32_32x32x16_bf16(fa[i & 1][1], fb[i & 1][0], acc[1][0], 0, 0, 0);
;       acc[1][1] = __builtin_amdgcn_mfma_f32_32x32x16_bf16(fa[i & 1][1], fb[i & 1][1], acc[1][1], 0, 0, 0);
;       __builtin_amdgcn_s_setprio(0);
;     }
;     __syncthreads();
;   }
; __device__ __forceinline__ bool tile_map(int it, int nn, int& mt, int& nt) {
;   const int xcd = blockIdx.x & 7, li = blockIdx.x >> 3, nb = gridDim.x >> 3;
;   int q = it * nb + li;
;   const int per = 16 * nn;
;   if (q < per) {
;     int sub = q / (8 * nn), r = q - sub * (8 * nn);
;     nt = r >> 3;
;     mt = xcd * 16 + sub * 8 + (r & 7);
;     return true;
;   }
;   q -= per;
;   int n = q * 8 + xcd;
	ds_read_b128 v[106:109], v113
	ds_read_b128 v[116:119], v113 offset:4608
	ds_read_b128 v[120:123], v114 offset:18432
	ds_read_b128 v[124:127], v114 offset:23040
	s_waitcnt vmcnt(7)
	ds_write_b128 v100, v[64:67] offset:36864
	s_waitcnt vmcnt(6)
	ds_write_b128 v100, v[68:71] offset:55296
	ds_read_b128 v[128:131], v113 offset:32
	ds_read_b128 v[132:135], v113 offset:4640
	ds_read_b128 v[136:139], v114 offset:18464
	ds_read_b128 v[140:143], v114 offset:23072
	s_waitcnt lgkmcnt(7)
	v_mfma_f32_32x32x16_bf16 v[48:63], v[106:109], v[120:123], v[48:63]
	s_waitcnt lgkmcnt(6)
	v_mfma_f32_32x32x16_bf16 v[32:47], v[106:109], v[124:127], v[32:47]
	v_mfma_f32_32x32x16_bf16 v[16:31], v[116:119], v[120:123], v[16:31]
	v_mfma_f32_32x32x16_bf16 v[0:15], v[116:119], v[124:127], v[0:15]
	s_waitcnt vmcnt(5)
	ds_write_b128 v100, v[72:75] offset:41472
	s_waitcnt vmcnt(4)
	ds_write_b128 v100, v[76:79] offset:59904
	ds_read_b128 v[106:109], v113 offset:64
	ds_read_b128 v[116:119], v113 offset:4672
	ds_read_b128 v[120:123], v114 offset:18496
	ds_read_b128 v[124:127], v114 offset:23104
	s_waitcnt lgkmcnt(7)
	v_mfma_f32_32x32x16_bf16 v[48:63], v[128:131], v[136:139], v[48:63]
	s_waitcnt lgkmcnt(6)
	v_mfma_f32_32x32x16_bf16 v[32:47], v[128:131], v[140:143], v[32:47]
	v_mfma_f32_32x32x16_bf16 v[16:31], v[132:135], v[136:139], v[16:31]
	v_mfma_f32_32x32x16_bf16 v[0:15], v[132:135], v[140:143], v[0:15]
	s_waitcnt vmcnt(3)
	ds_write_b128 v100, v[80:83] offset:46080
	s_waitcnt vmcnt(2)
	ds_write_b128 v100, v[84:87] offset:64512
	ds_read_b128 v[128:131], v113 offset:96
	ds_read_b128 v[132:135], v113 offset:4704
	ds_read_b128 v[136:139], v114 offset:18528
	ds_read_b128 v[140:143], v114 offset:23136
	s_waitcnt lgkmcnt(7)
	v_mfma_f32_32x32x16_bf16 v[48:63], v[106:109], v[120:123], v[48:63]
	s_waitcnt lgkmcnt(6)
	v_mfma_f32_32x32x16_bf16 v[32:47], v[106:109], v[124:127], v[32:47]
	v_mfma_f32_32x32x16_bf16 v[16:31], v[116:119], v[120:123], v[16:31]
	v_mfma_f32_32x32x16_bf16 v[0:15], v[116:119], v[124:127], v[0:15]
	s_waitcnt vmcnt(1)
	ds_write_b128 v100, v[88:91] offset:50688
	s_waitcnt vmcnt(0)
	ds_write_b128 v115, v[92:95] offset:13824
	s_waitcnt lgkmcnt(3)
	v_mfma_f32_32x32x16_bf16 v[48:63], v[128:131], v[136:139], v[48:63]
	s_waitcnt lgkmcnt(2)
	v_mfma_f32_32x32x16_bf16 v[32:47], v[128:131], v[140:143], v[32:47]
	v_mfma_f32_32x32x16_bf16 v[16:31], v[132:135], v[136:139], v[16:31]
	v_mfma_f32_32x32x16_bf16 v[0:15], v[132:135], v[140:143], v[0:15]
	s_waitcnt lgkmcnt(0)
	s_barrier
	ds_read_b128 v[106:109], v113 offset:36864
	ds_read_b128 v[116:119], v113 offset:36896
	ds_read_b128 v[120:123], v113 offset:41472
	ds_read_b128 v[124:127], v113 offset:41504
	ds_read_b128 v[128:131], v114 offset:55296
	ds_read_b128 v[132:135], v114 offset:55328
	ds_read_b128 v[136:139], v114 offset:59904
	ds_read_b128 v[140:143], v114 offset:59936
	s_waitcnt lgkmcnt(3)
	v_mfma_f32_32x32x16_bf16 v[48:63], v[106:109], v[128:131], v[48:63]
	s_waitcnt lgkmcnt(1)
	v_mfma_f32_32x32x16_bf16 v[32:47], v[106:109], v[136:139], v[32:47]
	v_mfma_f32_32x32x16_bf16 v[16:31], v[120:123], v[128:131], v[16:31]
	v_mfma_f32_32x32x16_bf16 v[0:15], v[120:123], v[136:139], v[0:15]
	ds_read_b128 v[106:109], v113 offset:36928
	ds_read_b128 v[120:123], v113 offset:41536
	ds_read_b128 v[128:131], v114 offset:55360
	ds_read_b128 v[136:139], v114 offset:59968
	v_mfma_f32_32x32x16_bf16 v[48:63], v[116:119], v[132:135], v[48:63]
	s_waitcnt lgkmcnt(4)
	v_mfma_f32_32x32x16_bf16 v[32:47], v[116:119], v[140:143], v[32:47]
	v_mfma_f32_32x32x16_bf16 v[16:31], v[124:127], v[132:135], v[16:31]
	v_mfma_f32_32x32x16_bf16 v[0:15], v[124:127], v[140:143], v[0:15]
	ds_read_b128 v[116:119], v113 offset:36960
	ds_read_b128 v[124:127], v113 offset:41568
	ds_read_b128 v[132:135], v114 offset:55392
	ds_read_b128 v[140:143], v114 offset:60000
	s_waitcnt lgkmcnt(5)
	v_mfma_f32_32x32x16_bf16 v[48:63], v[106:109], v[128:131], v[48:63]
	s_waitcnt lgkmcnt(4)
	v_mfma_f32_32x32x16_bf16 v[32:47], v[106:109], v[136:139], v[32:47]
	v_mfma_f32_32x32x16_bf16 v[16:31], v[120:123], v[128:131], v[16:31]
	v_mfma_f32_32x32x16_bf16 v[0:15], v[120:123], v[136:139], v[0:15]
	s_waitcnt lgkmcnt(1)
	v_mfma_f32_32x32x16_bf16 v[48:63], v[116:119], v[132:135], v[48:63]
	s_waitcnt lgkmcnt(0)
	v_mfma_f32_32x32x16_bf16 v[32:47], v[116:119], v[140:143], v[32:47]
	v_mfma_f32_32x32x16_bf16 v[16:31], v[124:127], v[132:135], v[16:31]
	v_mfma_f32_32x32x16_bf16 v[0:15], v[124:127], v[140:143], v[0:15]
	s_add_i32 s18, s18, 1
	s_mul_i32 s1, s18, s20
	s_add_i32 s1, s1, s3
	s_cmpk_gt_u32 s1, 0x7f
	s_mov_b64 s[12:13], -1
	s_barrier
	s_cbranch_scc0 .LBB0_2348
	s_lshl_b32 s5, s1, 3
	s_add_i32 s5, s5, s19
	s_mov_b64 s[12:13], 0
	s_cmp_gt_i32 s5, 7
	s_mov_b64 s[10:11], 0
	s_cbranch_scc1 .LBB0_2348
	s_movk_i32 s4, 0x80
	s_mov_b64 s[10:11], -1
	s_mov_b32 s0, s5

; __device__ __forceinline__ void gemm_run(int tid, f32x16 (&acc)[2][2], GRegs& g, const GOp& o, int K, unsigned char* smem) {
;     ...
;   for (int i = 0; i < 4; i++) {
;     *(u32x4*)(sbuf + (r0 + i * 32) * LDK + sg * 8) = g.a[i];
;     *(u32x4*)(sbuf + 128 * LDK + (r0 + i * 32) * LDK + sg * 8) = g.b[i];
;   }
;   if (nk > 1) {
; #pragma unroll
;     for (int i = 0; i < 4; i++) {
;       g.a[i] = *(const u32x4*)(Ap + (size_t)i * 32 * o.lda + 64);
;       g.b[i] = *(const u32x4*)(Bp + o.bs.o[i] + 64);
;     }
;   }
;   __syncthreads();
;   const int lane = tid & 63, fr = lane & 31, fh = lane >> 5;
;   for (int k = 0; k < nk; k++) {
;     bf16r* cur = sbuf + (k & 1) * (256 * LDK);
;     bf16r* nxt = sbuf + ((k & 1) ^ 1) * (256 * LDK);
;     const bf16r* As = cur + (wm * 64 + fr) * LDK + fh * 8;
;     const bf16r* Bs = cur + 128 * LDK + (wn * 64 + fr) * LDK + fh * 8;
;     const bool wr = (k + 1 < nk), ld = (k + 2 < nk);
;     bf16x8 fa[2][2], fb[2][2];
;     fa[0][0] = *(const bf16x8*)(As);
;     fa[0][1] = *(const bf16x8*)(As + 32 * LDK);
;     fb[0][0] = *(const bf16x8*)(Bs);
;     fb[0][1] = *(const bf16x8*)(Bs + 32 * LDK);
; #pragma unroll
;     for (int i = 0; i < 4; i++) {
;       if (wr) {
;         *(u32x4*)(nxt + (r0 + i * 32) * LDK + sg * 8) = g.a[i];
;         *(u32x4*)(nxt + 128 * LDK + (r0 + i * 32) * LDK + sg * 8) = g.b[i];
;       }
;       if (ld) {
;         g.a[i] = *(const u32x4*)(Ap + (size_t)i * 32 * o.lda + (k + 2) * 64);
;         g.b[i] = *(const u32x4*)(Bp + o.bs.o[i] + (k + 2) * 64);
;       }
;       if (i < 3) {
;         fa[(i + 1) & 1][0] = *(const bf16x8*)(As + (i + 1) * 16);
;         fa[(i + 1) & 1][1] = *(const bf16x8*)(As + 32 * LDK + (i + 1) * 16);
;         fb[(i + 1) & 1][0] = *(const bf16x8*)(Bs + (i + 1) * 16);
;         fb[(i + 1) & 1][1] = *(const bf16x8*)(Bs + 32 * LDK + (i + 1) * 16);
;       }
;       __builtin_amdgcn_sched_barrier(0);
;       __builtin_amdgcn_s_setprio(1);
;       acc[0][0] = __builtin_amdgcn_mfma_f32_32x32x16_bf16(fa[i & 1][0], fb[i & 1][0], acc[0][0], 0, 0, 0);
;       acc[0][1] = __builtin_amdgcn_mfma_f32_32x32x16_bf16(fa[i & 1][0], fb[i & 1][1], acc[0][1], 0, 0, 0);
;       acc[1][0] = __builtin_amdgcn_mfma_f32_32x32x16_bf16(fa[i & 1][1], fb[i & 1][0], acc[1][0], 0, 0, 0);
;       acc[1][1] = __builtin_amdgcn_mfma_f32_32x32x16_bf16(fa[i & 1][1], fb[i & 1][1], acc[1][1], 0, 0, 0);
.LBB0_2446:
	s_ashr_i32 s7, s0, 31
	s_mov_b32 s6, s0
	s_lshl_b64 s[10:11], s[6:7], 18
	s_ashr_i32 s9, s8, 31
	s_waitcnt vmcnt(7)
	ds_write_b128 v100, v[64:67]
	s_waitcnt vmcnt(6)
	ds_write_b128 v100, v[68:71] offset:18432
	s_waitcnt vmcnt(5)
	ds_write_b128 v100, v[72:75] offset:4608
	s_waitcnt vmcnt(4)
	ds_write_b128 v100, v[76:79] offset:23040
	s_waitcnt vmcnt(3)
	ds_write_b128 v100, v[80:83] offset:9216
	s_waitcnt vmcnt(2)
	ds_write_b128 v100, v[84:87] offset:27648
	s_waitcnt vmcnt(1)
	ds_write_b128 v100, v[88:91] offset:13824
	s_waitcnt vmcnt(0)
	ds_write_b128 v100, v[92:95] offset:32256
	v_lshl_add_u64 v[64:65], v[102:103], 0, s[10:11]
	s_lshl_b64 s[12:13], s[8:9], 17
	v_add_co_u32_e32 v72, vcc, s15, v64
	v_lshl_add_u64 v[106:107], v[98:99], 0, s[12:13]
	s_nop 0
	v_addc_co_u32_e32 v73, vcc, 0, v65, vcc
	v_add_co_u32_e32 v76, vcc, s16, v106
	global_load_dwordx4 v[0:3], v[64:65], off offset:128
	global_load_dwordx4 v[4:7], v[106:107], off offset:128
	v_addc_co_u32_e32 v77, vcc, 0, v107, vcc
	v_add_co_u32_e32 v80, vcc, s17, v64
	global_load_dwordx4 v[66:69], v[72:73], off offset:128
	global_load_dwordx4 v[110:113], v[76:77], off offset:128
	v_addc_co_u32_e32 v81, vcc, 0, v65, vcc
	v_add_co_u32_e32 v84, vcc, s15, v106
	s_nop 1
	v_addc_co_u32_e32 v85, vcc, 0, v107, vcc
	v_add_co_u32_e32 v88, vcc, s18, v64
	global_load_dwordx4 v[114:117], v[80:81], off offset:128
	global_load_dwordx4 v[118:121], v[84:85], off offset:128
	v_addc_co_u32_e32 v89, vcc, 0, v65, vcc
	v_add_co_u32_e32 v92, vcc, s19, v106
	s_nop 1
	v_addc_co_u32_e32 v93, vcc, 0, v107, vcc
	global_load_dwordx4 v[122:125], v[88:89], off offset:128
	global_load_dwordx4 v[126:129], v[92:93], off offset:128
	s_waitcnt lgkmcnt(0)
	s_barrier
	global_load_dwordx4 v[130:133], v[64:65], off offset:256
	global_load_dwordx4 v[134:137], v[106:107], off offset:256
	ds_read_b128 v[8:11], v104
	ds_read_b128 v[16:19], v104 offset:4608
	ds_read_b128 v[12:15], v101 offset:18432
	ds_read_b128 v[20:23], v101 offset:23040
	s_waitcnt vmcnt(9)
	ds_write_b128 v100, v[0:3] offset:36864
	s_waitcnt vmcnt(8)
	ds_write_b128 v100, v[4:7] offset:55296
	ds_read_b128 v[138:141], v104 offset:32
	ds_read_b128 v[142:145], v104 offset:4640
	ds_read_b128 v[146:149], v101 offset:18464
	ds_read_b128 v[150:153], v101 offset:23072
	s_waitcnt lgkmcnt(7)
	v_mfma_f32_32x32x16_bf16 v[32:47], v[8:11], v[12:15], 0
	s_waitcnt lgkmcnt(6)
	v_mfma_f32_32x32x16_bf16 v[48:63], v[8:11], v[20:23], 0
	v_mfma_f32_32x32x16_bf16 v[0:15], v[16:19], v[12:15], 0
	v_mfma_f32_32x32x16_bf16 v[16:31], v[16:19], v[20:23], 0
	global_load_dwordx4 v[154:157], v[72:73], off offset:256
	global_load_dwordx4 v[158:161], v[76:77], off offset:256
	s_waitcnt vmcnt(9)
	ds_write_b128 v100, v[66:69] offset:41472
	s_waitcnt vmcnt(8)
	ds_write_b128 v100, v[110:113] offset:59904
	ds_read_b128 v[66:69], v104 offset:64
	ds_read_b128 v[110:113], v104 offset:4672
	ds_read_b128 v[162:165], v101 offset:18496
	ds_read_b128 v[166:169], v101 offset:23104
	s_waitcnt lgkmcnt(7)
	v_mfma_f32_32x32x16_bf16 v[32:47], v[138:141], v[146:149], v[32:47]
	s_waitcnt lgkmcnt(6)
	v_mfma_f32_32x32x16_bf16 v[48:63], v[138:141], v[150:153], v[48:63]
	v_mfma_f32_32x32x16_bf16 v[0:15], v[142:145], v[146:149], v[0:15]
	v_mfma_f32_32x32x16_bf16 v[16:31], v[142:145], v[150:153], v[16:31]
	global_load_dwordx4 v[138:141], v[80:81], off offset:256
	global_load_dwordx4 v[142:145], v[84:85], off offset:256
	s_waitcnt vmcnt(9)
	ds_write_b128 v100, v[114:117] offset:46080
	s_waitcnt vmcnt(8)
	ds_write_b128 v100, v[118:121] offset:64512
	ds_read_b128 v[114:117], v104 offset:96
	ds_read_b128 v[118:121], v104 offset:4704
	ds_read_b128 v[146:149], v101 offset:18528
	ds_read_b128 v[150:153], v101 offset:23136
	s_waitcnt lgkmcnt(7)
	v_mfma_f32_32x32x16_bf16 v[32:47], v[66:69], v[162:165], v[32:47]
	s_waitcnt lgkmcnt(6)
	v_mfma_f32_32x32x16_bf16 v[48:63], v[66:69], v[166:169], v[48:63]
	v_mfma_f32_32x32x16_bf16 v[0:15], v[110:113], v[162:165], v[0:15]
	v_mfma_f32_32x32x16_bf16 v[16:31], v[110:113], v[166:169], v[16:31]
	global_load_dwordx4 v[66:69], v[88:89], off offset:256
	global_load_dwordx4 v[110:113], v[92:93], off offset:256
	s_waitcnt vmcnt(9)
	ds_write_b128 v100, v[122:125] offset:50688
	s_waitcnt vmcnt(8)
	ds_write_b128 v105, v[126:129] offset:13824
	s_waitcnt lgkmcnt(3)
	v_mfma_f32_32x32x16_bf16 v[32:47], v[114:117], v[146:149], v[32:47]
	s_waitcnt lgkmcnt(2)
	v_mfma_f32_32x32x16_bf16 v[48:63], v[114:117], v[150:153], v[48:63]
	v_mfma_f32_32x32x16_bf16 v[0:15], v[118:121], v[146:149], v[0:15]
	v_mfma_f32_32x32x16_bf16 v[16:31], v[118:121], v[150:153], v[16:31]
	s_waitcnt lgkmcnt(0)
	s_barrier
; __device__ __forceinline__ void gemm_run(int tid, f32x16 (&acc)[2][2], GRegs& g, const GOp& o, int K, unsigned char* smem) {
;     ...
;   for (int k = 0; k < nk; k++) {
;     bf16r* cur = sbuf + (k & 1) * (256 * LDK);
;     bf16r* nxt = sbuf + ((k & 1) ^ 1) * (256 * LDK);
;     const bf16r* As = cur + (wm * 64 + fr) * LDK + fh * 8;
;     const bf16r* Bs = cur + 128 * LDK + (wn * 64 + fr) * LDK + fh * 8;
;     const bool wr = (k + 1 < nk), ld = (k + 2 < nk);
;     bf16x8 fa[2][2], fb[2][2];
;     fa[0][0] = *(const bf16x8*)(As);
;     fa[0][1] = *(const bf16x8*)(As + 32 * LDK);
;     fb[0][0] = *(const bf16x8*)(Bs);
;     fb[0][1] = *(const bf16x8*)(Bs + 32 * LDK);
; #pragma unroll
;     for (int i = 0; i < 4; i++) {
;       if (wr) {
;         *(u32x4*)(nxt + (r0 + i * 32) * LDK + sg * 8) = g.a[i];
;         *(u32x4*)(nxt + 128 * LDK + (r0 + i * 32) * LDK + sg * 8) = g.b[i];
;       }
;       if (ld) {
;         g.a[i] = *(const u32x4*)(Ap + (size_t)i * 32 * o.lda + (k + 2) * 64);
;         g.b[i] = *(const u32x4*)(Bp + o.bs.o[i] + (k + 2) * 64);
;       }
;       if (i < 3) {
;         fa[(i + 1) & 1][0] = *(const bf16x8*)(As + (i + 1) * 16);
;         fa[(i + 1) & 1][1] = *(const bf16x8*)(As + 32 * LDK + (i + 1) * 16);
;         fb[(i + 1) & 1][0] = *(const bf16x8*)(Bs + (i + 1) * 16);
;         fb[(i + 1) & 1][1] = *(const bf16x8*)(Bs + 32 * LDK + (i + 1) * 16);
;       }
;       __builtin_amdgcn_sched_barrier(0);
;       __builtin_amdgcn_s_setprio(1);
;       acc[0][0] = __builtin_amdgcn_mfma_f32_32x32x16_bf16(fa[i & 1][0], fb[i & 1][0], acc[0][0], 0, 0, 0);
;       acc[0][1] = __builtin_amdgcn_mfma_f32_32x32x16_bf16(fa[i & 1][0], fb[i & 1][1], acc[0][1], 0, 0, 0);
;       acc[1][0] = __builtin_amdgcn_mfma_f32_32x32x16_bf16(fa[i & 1][1], fb[i & 1][0], acc[1][0], 0, 0, 0);
;       acc[1][1] = __builtin_amdgcn_mfma_f32_32x32x16_bf16(fa[i & 1][1], fb[i & 1][1], acc[1][1], 0, 0, 0);
;       __builtin_amdgcn_s_setprio(0);
;     }
;     __syncthreads();
	global_load_dwordx4 v[114:117], v[64:65], off offset:384
	global_load_dwordx4 v[118:121], v[106:107], off offset:384
	ds_read_b128 v[122:125], v104 offset:36864
	ds_read_b128 v[126:129], v104 offset:41472
	ds_read_b128 v[146:149], v101 offset:55296
	ds_read_b128 v[150:153], v101 offset:59904
	s_waitcnt vmcnt(9)
	ds_write_b128 v100, v[130:133]
	s_waitcnt vmcnt(8)
	ds_write_b128 v100, v[134:137] offset:18432
	ds_read_b128 v[130:133], v104 offset:36896
	ds_read_b128 v[134:137], v104 offset:41504
	ds_read_b128 v[162:165], v101 offset:55328
	ds_read_b128 v[166:169], v101 offset:59936
	s_waitcnt lgkmcnt(7)
	v_mfma_f32_32x32x16_bf16 v[32:47], v[122:125], v[146:149], v[32:47]
	s_waitcnt lgkmcnt(6)
	v_mfma_f32_32x32x16_bf16 v[48:63], v[122:125], v[150:153], v[48:63]
	v_mfma_f32_32x32x16_bf16 v[0:15], v[126:129], v[146:149], v[0:15]
	v_mfma_f32_32x32x16_bf16 v[16:31], v[126:129], v[150:153], v[16:31]
	global_load_dwordx4 v[122:125], v[72:73], off offset:384
	global_load_dwordx4 v[126:129], v[76:77], off offset:384
	s_waitcnt vmcnt(9)
	ds_write_b128 v100, v[154:157] offset:4608
	s_waitcnt vmcnt(8)
	ds_write_b128 v100, v[158:161] offset:23040
	ds_read_b128 v[146:149], v104 offset:36928
	ds_read_b128 v[150:153], v104 offset:41536
	ds_read_b128 v[154:157], v101 offset:55360
	ds_read_b128 v[158:161], v101 offset:59968
	s_waitcnt lgkmcnt(7)
	v_mfma_f32_32x32x16_bf16 v[32:47], v[130:133], v[162:165], v[32:47]
	s_waitcnt lgkmcnt(6)
	v_mfma_f32_32x32x16_bf16 v[48:63], v[130:133], v[166:169], v[48:63]
	v_mfma_f32_32x32x16_bf16 v[0:15], v[134:137], v[162:165], v[0:15]
	v_mfma_f32_32x32x16_bf16 v[16:31], v[134:137], v[166:169], v[16:31]
	global_load_dwordx4 v[130:133], v[80:81], off offset:384
	global_load_dwordx4 v[134:137], v[84:85], off offset:384
	s_waitcnt vmcnt(9)
	ds_write_b128 v100, v[138:141] offset:9216
	s_waitcnt vmcnt(8)
	ds_write_b128 v100, v[142:145] offset:27648
	ds_read_b128 v[138:141], v104 offset:36960
	ds_read_b128 v[142:145], v104 offset:41568
	ds_read_b128 v[162:165], v101 offset:55392
	ds_read_b128 v[166:169], v101 offset:60000
	s_waitcnt lgkmcnt(7)
	v_mfma_f32_32x32x16_bf16 v[32:47], v[146:149], v[154:157], v[32:47]
	s_waitcnt lgkmcnt(6)
	v_mfma_f32_32x32x16_bf16 v[48:63], v[146:149], v[158:161], v[48:63]
	v_mfma_f32_32x32x16_bf16 v[0:15], v[150:153], v[154:157], v[0:15]
	v_mfma_f32_32x32x16_bf16 v[16:31], v[150:153], v[158:161], v[16:31]
	global_load_dwordx4 v[146:149], v[88:89], off offset:384
	global_load_dwordx4 v[150:153], v[92:93], off offset:384
	s_waitcnt vmcnt(9)
	ds_write_b128 v100, v[66:69] offset:13824
	s_waitcnt vmcnt(8)
	ds_write_b128 v100, v[110:113] offset:32256
	s_waitcnt lgkmcnt(3)
	v_mfma_f32_32x32x16_bf16 v[32:47], v[138:141], v[162:165], v[32:47]
	s_waitcnt lgkmcnt(2)
	v_mfma_f32_32x32x16_bf16 v[48:63], v[138:141], v[166:169], v[48:63]
	v_mfma_f32_32x32x16_bf16 v[0:15], v[142:145], v[162:165], v[0:15]
	v_mfma_f32_32x32x16_bf16 v[16:31], v[142:145], v[166:169], v[16:31]
	s_waitcnt lgkmcnt(0)
	s_barrier
	global_load_dwordx4 v[66:69], v[64:65], off offset:512
	global_load_dwordx4 v[110:113], v[106:107], off offset:512
	ds_read_b128 v[138:141], v104
	ds_read_b128 v[142:145], v104 offset:4608
	ds_read_b128 v[154:157], v101 offset:18432
	ds_read_b128 v[158:161], v101 offset:23040
	s_waitcnt vmcnt(9)
	ds_write_b128 v100, v[114:117] offset:36864
	s_waitcnt vmcnt(8)
	ds_write_b128 v100, v[118:121] offset:55296
	ds_read_b128 v[114:117], v104 offset:32
	ds_read_b128 v[118:121], v104 offset:4640
	ds_read_b128 v[162:165], v101 offset:18464
	ds_read_b128 v[166:169], v101 offset:23072
	s_waitcnt lgkmcnt(7)
	v_mfma_f32_32x32x16_bf16 v[32:47], v[138:141], v[154:157], v[32:47]
	s_waitcnt lgkmcnt(6)
	v_mfma_f32_32x32x16_bf16 v[48:63], v[138:141], v[158:161], v[48:63]
	v_mfma_f32_32x32x16_bf16 v[0:15], v[142:145], v[154:157], v[0:15]
	v_mfma_f32_32x32x16_bf16 v[16:31], v[142:145], v[158:161], v[16:31]
	global_load_dwordx4 v[138:141], v[72:73], off offset:512
	global_load_dwordx4 v[142:145], v[76:77], off offset:512
	s_waitcnt vmcnt(9)
	ds_write_b128 v100, v[122:125] offset:41472
	s_waitcnt vmcnt(8)
	ds_write_b128 v100, v[126:129] offset:59904
	ds_read_b128 v[122:125], v104 offset:64
	ds_read_b128 v[126:129], v104 offset:4672
	ds_read_b128 v[154:157], v101 offset:18496
	ds_read_b128 v[158:161], v101 offset:23104
	s_waitcnt lgkmcnt(7)
	v_mfma_f32_32x32x16_bf16 v[32:47], v[114:117], v[162:165], v[32:47]
	s_waitcnt lgkmcnt(6)
	v_mfma_f32_32x32x16_bf16 v[48:63], v[114:117], v[166:169], v[48:63]
	v_mfma_f32_32x32x16_bf16 v[0:15], v[118:121], v[162:165], v[0:15]
	v_mfma_f32_32x32x16_bf16 v[16:31], v[118:121], v[166:169], v[16:31]
	global_load_dwordx4 v[114:117], v[80:81], off offset:512
	global_load_dwordx4 v[118:121], v[84:85], off offset:512
	s_waitcnt vmcnt(9)
	ds_write_b128 v100, v[130:133] offset:46080
	s_waitcnt vmcnt(8)
	ds_write_b128 v100, v[134:137] offset:64512
	ds_read_b128 v[130:133], v104 offset:96
	ds_read_b128 v[134:137], v104 offset:4704
	ds_read_b128 v[162:165], v101 offset:18528
	ds_read_b128 v[166:169], v101 offset:23136
	s_waitcnt lgkmcnt(7)
	v_mfma_f32_32x32x16_bf16 v[32:47], v[122:125], v[154:157], v[32:47]
	s_waitcnt lgkmcnt(6)
	v_mfma_f32_32x32x16_bf16 v[48:63], v[122:125], v[158:161], v[48:63]
	v_mfma_f32_32x32x16_bf16 v[0:15], v[126:129], v[154:157], v[0:15]
	v_mfma_f32_32x32x16_bf16 v[16:31], v[126:129], v[158:161], v[16:31]
	global_load_dwordx4 v[122:125], v[88:89], off offset:512
	global_load_dwordx4 v[126:129], v[92:93], off offset:512
	s_waitcnt vmcnt(9)
	ds_write_b128 v100, v[146:149] offset:50688
	s_waitcnt vmcnt(8)
	ds_write_b128 v105, v[150:153] offset:13824
	s_waitcnt lgkmcnt(3)
	v_mfma_f32_32x32x16_bf16 v[32:47], v[130:133], v[162:165], v[32:47]
	s_waitcnt lgkmcnt(2)
	v_mfma_f32_32x32x16_bf16 v[48:63], v[130:133], v[166:169], v[48:63]
	v_mfma_f32_32x32x16_bf16 v[0:15], v[134:137], v[162:165], v[0:15]
	v_mfma_f32_32x32x16_bf16 v[16:31], v[134:137], v[166:169], v[16:31]
	s_waitcnt lgkmcnt(0)
	s_barrier
; __device__ __forceinline__ void gemm_run(int tid, f32x16 (&acc)[2][2], GRegs& g, const GOp& o, int K, unsigned char* smem) {
;     ...
;   for (int k = 0; k < nk; k++) {
;     bf16r* cur = sbuf + (k & 1) * (256 * LDK);
;     bf16r* nxt = sbuf + ((k & 1) ^ 1) * (256 * LDK);
;     const bf16r* As = cur + (wm * 64 + fr) * LDK + fh * 8;
;     const bf16r* Bs = cur + 128 * LDK + (wn * 64 + fr) * LDK + fh * 8;
;     const bool wr = (k + 1 < nk), ld = (k + 2 < nk);
;     bf16x8 fa[2][2], fb[2][2];
;     fa[0][0] = *(const bf16x8*)(As);
;     fa[0][1] = *(const bf16x8*)(As + 32 * LDK);
;     fb[0][0] = *(const bf16x8*)(Bs);
;     fb[0][1] = *(const bf16x8*)(Bs + 32 * LDK);
; #pragma unroll
;     for (int i = 0; i < 4; i++) {
;       if (wr) {
;         *(u32x4*)(nxt + (r0 + i * 32) * LDK + sg * 8) = g.a[i];
;         *(u32x4*)(nxt + 128 * LDK + (r0 + i * 32) * LDK + sg * 8) = g.b[i];
;       }
;       if (ld) {
;         g.a[i] = *(const u32x4*)(Ap + (size_t)i * 32 * o.lda + (k + 2) * 64);
;         g.b[i] = *(const u32x4*)(Bp + o.bs.o[i] + (k + 2) * 64);
;       }
;       if (i < 3) {
;         fa[(i + 1) & 1][0] = *(const bf16x8*)(As + (i + 1) * 16);
;         fa[(i + 1) & 1][1] = *(const bf16x8*)(As + 32 * LDK + (i + 1) * 16);
;         fb[(i + 1) & 1][0] = *(const bf16x8*)(Bs + (i + 1) * 16);
;         fb[(i + 1) & 1][1] = *(const bf16x8*)(Bs + 32 * LDK + (i + 1) * 16);
;       }
;       __builtin_amdgcn_sched_barrier(0);
;       __builtin_amdgcn_s_setprio(1);
;       acc[0][0] = __builtin_amdgcn_mfma_f32_32x32x16_bf16(fa[i & 1][0], fb[i & 1][0], acc[0][0], 0, 0, 0);
;       acc[0][1] = __builtin_amdgcn_mfma_f32_32x32x16_bf16(fa[i & 1][0], fb[i & 1][1], acc[0][1], 0, 0, 0);
;       acc[1][0] = __builtin_amdgcn_mfma_f32_32x32x16_bf16(fa[i & 1][1], fb[i & 1][0], acc[1][0], 0, 0, 0);
;       acc[1][1] = __builtin_amdgcn_mfma_f32_32x32x16_bf16(fa[i & 1][1], fb[i & 1][1], acc[1][1], 0, 0, 0);
;       __builtin_amdgcn_s_setprio(0);
;     }
;     __syncthreads();
	global_load_dwordx4 v[130:133], v[64:65], off offset:640
	global_load_dwordx4 v[134:137], v[106:107], off offset:640
	ds_read_b128 v[146:149], v104 offset:36864
	ds_read_b128 v[150:153], v104 offset:41472
	ds_read_b128 v[154:157], v101 offset:55296
	ds_read_b128 v[158:161], v101 offset:59904
	s_waitcnt vmcnt(9)
	ds_write_b128 v100, v[66:69]
	s_waitcnt vmcnt(8)
	ds_write_b128 v100, v[110:113] offset:18432
	ds_read_b128 v[66:69], v104 offset:36896
	ds_read_b128 v[110:113], v104 offset:41504
	ds_read_b128 v[162:165], v101 offset:55328
	ds_read_b128 v[166:169], v101 offset:59936
	s_waitcnt lgkmcnt(7)
	v_mfma_f32_32x32x16_bf16 v[32:47], v[146:149], v[154:157], v[32:47]
	s_waitcnt lgkmcnt(6)
	v_mfma_f32_32x32x16_bf16 v[48:63], v[146:149], v[158:161], v[48:63]
	v_mfma_f32_32x32x16_bf16 v[0:15], v[150:153], v[154:157], v[0:15]
	v_mfma_f32_32x32x16_bf16 v[16:31], v[150:153], v[158:161], v[16:31]
	global_load_dwordx4 v[146:149], v[72:73], off offset:640
	global_load_dwordx4 v[150:153], v[76:77], off offset:640
	s_waitcnt vmcnt(9)
	ds_write_b128 v100, v[138:141] offset:4608
	s_waitcnt vmcnt(8)
	ds_write_b128 v100, v[142:145] offset:23040
	ds_read_b128 v[138:141], v104 offset:36928
	ds_read_b128 v[142:145], v104 offset:41536
	ds_read_b128 v[154:157], v101 offset:55360
	ds_read_b128 v[158:161], v101 offset:59968
	s_waitcnt lgkmcnt(7)
	v_mfma_f32_32x32x16_bf16 v[32:47], v[66:69], v[162:165], v[32:47]
	s_waitcnt lgkmcnt(6)
	v_mfma_f32_32x32x16_bf16 v[48:63], v[66:69], v[166:169], v[48:63]
	v_mfma_f32_32x32x16_bf16 v[0:15], v[110:113], v[162:165], v[0:15]
	v_mfma_f32_32x32x16_bf16 v[16:31], v[110:113], v[166:169], v[16:31]
	global_load_dwordx4 v[66:69], v[80:81], off offset:640
	global_load_dwordx4 v[110:113], v[84:85], off offset:640
	s_waitcnt vmcnt(9)
	ds_write_b128 v100, v[114:117] offset:9216
	s_waitcnt vmcnt(8)
	ds_write_b128 v100, v[118:121] offset:27648
	ds_read_b128 v[114:117], v104 offset:36960
	ds_read_b128 v[118:121], v104 offset:41568
	ds_read_b128 v[162:165], v101 offset:55392
	ds_read_b128 v[166:169], v101 offset:60000
	s_waitcnt lgkmcnt(7)
	v_mfma_f32_32x32x16_bf16 v[32:47], v[138:141], v[154:157], v[32:47]
	s_waitcnt lgkmcnt(6)
	v_mfma_f32_32x32x16_bf16 v[48:63], v[138:141], v[158:161], v[48:63]
	v_mfma_f32_32x32x16_bf16 v[0:15], v[142:145], v[154:157], v[0:15]
	v_mfma_f32_32x32x16_bf16 v[16:31], v[142:145], v[158:161], v[16:31]
	global_load_dwordx4 v[138:141], v[88:89], off offset:640
	global_load_dwordx4 v[142:145], v[92:93], off offset:640
	s_waitcnt vmcnt(9)
	ds_write_b128 v100, v[122:125] offset:13824
	s_waitcnt vmcnt(8)
	ds_write_b128 v100, v[126:129] offset:32256
	s_waitcnt lgkmcnt(3)
	v_mfma_f32_32x32x16_bf16 v[32:47], v[114:117], v[162:165], v[32:47]
	s_waitcnt lgkmcnt(2)
	v_mfma_f32_32x32x16_bf16 v[48:63], v[114:117], v[166:169], v[48:63]
	v_mfma_f32_32x32x16_bf16 v[0:15], v[118:121], v[162:165], v[0:15]
	v_mfma_f32_32x32x16_bf16 v[16:31], v[118:121], v[166:169], v[16:31]
	s_waitcnt lgkmcnt(0)
	s_barrier
	global_load_dwordx4 v[114:117], v[64:65], off offset:768
	global_load_dwordx4 v[118:121], v[106:107], off offset:768
	ds_read_b128 v[122:125], v104
	ds_read_b128 v[126:129], v104 offset:4608
	ds_read_b128 v[154:157], v101 offset:18432
	ds_read_b128 v[158:161], v101 offset:23040
	s_waitcnt vmcnt(9)
	ds_write_b128 v100, v[130:133] offset:36864
	s_waitcnt vmcnt(8)
	ds_write_b128 v100, v[134:137] offset:55296
	ds_read_b128 v[130:133], v104 offset:32
	ds_read_b128 v[134:137], v104 offset:4640
	ds_read_b128 v[162:165], v101 offset:18464
	ds_read_b128 v[166:169], v101 offset:23072
	s_waitcnt lgkmcnt(7)
	v_mfma_f32_32x32x16_bf16 v[32:47], v[122:125], v[154:157], v[32:47]
	s_waitcnt lgkmcnt(6)
	v_mfma_f32_32x32x16_bf16 v[48:63], v[122:125], v[158:161], v[48:63]
	v_mfma_f32_32x32x16_bf16 v[0:15], v[126:129], v[154:157], v[0:15]
	v_mfma_f32_32x32x16_bf16 v[16:31], v[126:129], v[158:161], v[16:31]
	global_load_dwordx4 v[122:125], v[72:73], off offset:768
	global_load_dwordx4 v[126:129], v[76:77], off offset:768
	s_waitcnt vmcnt(9)
	ds_write_b128 v100, v[146:149] offset:41472
	s_waitcnt vmcnt(8)
	ds_write_b128 v100, v[150:153] offset:59904
	ds_read_b128 v[146:149], v104 offset:64
	ds_read_b128 v[150:153], v104 offset:4672
	ds_read_b128 v[154:157], v101 offset:18496
	ds_read_b128 v[158:161], v101 offset:23104
	s_waitcnt lgkmcnt(7)
	v_mfma_f32_32x32x16_bf16 v[32:47], v[130:133], v[162:165], v[32:47]
	s_waitcnt lgkmcnt(6)
	v_mfma_f32_32x32x16_bf16 v[48:63], v[130:133], v[166:169], v[48:63]
	v_mfma_f32_32x32x16_bf16 v[0:15], v[134:137], v[162:165], v[0:15]
	v_mfma_f32_32x32x16_bf16 v[16:31], v[134:137], v[166:169], v[16:31]
	global_load_dwordx4 v[130:133], v[80:81], off offset:768
	global_load_dwordx4 v[134:137], v[84:85], off offset:768
	s_waitcnt vmcnt(9)
	ds_write_b128 v100, v[66:69] offset:46080
	s_waitcnt vmcnt(8)
	ds_write_b128 v100, v[110:113] offset:64512
	ds_read_b128 v[66:69], v104 offset:96
	ds_read_b128 v[110:113], v104 offset:4704
	ds_read_b128 v[162:165], v101 offset:18528
	ds_read_b128 v[166:169], v101 offset:23136
	s_waitcnt lgkmcnt(7)
	v_mfma_f32_32x32x16_bf16 v[32:47], v[146:149], v[154:157], v[32:47]
	s_waitcnt lgkmcnt(6)
	v_mfma_f32_32x32x16_bf16 v[48:63], v[146:149], v[158:161], v[48:63]
	v_mfma_f32_32x32x16_bf16 v[0:15], v[150:153], v[154:157], v[0:15]
	v_mfma_f32_32x32x16_bf16 v[16:31], v[150:153], v[158:161], v[16:31]
	global_load_dwordx4 v[146:149], v[88:89], off offset:768
	global_load_dwordx4 v[150:153], v[92:93], off offset:768
	s_waitcnt vmcnt(9)
	ds_write_b128 v100, v[138:141] offset:50688
	s_waitcnt vmcnt(8)
	ds_write_b128 v105, v[142:145] offset:13824
	s_waitcnt lgkmcnt(3)
	v_mfma_f32_32x32x16_bf16 v[32:47], v[66:69], v[162:165], v[32:47]
	s_waitcnt lgkmcnt(2)
	v_mfma_f32_32x32x16_bf16 v[48:63], v[66:69], v[166:169], v[48:63]
	v_mfma_f32_32x32x16_bf16 v[0:15], v[110:113], v[162:165], v[0:15]
	v_mfma_f32_32x32x16_bf16 v[16:31], v[110:113], v[166:169], v[16:31]
	s_waitcnt lgkmcnt(0)
	s_barrier
; __device__ __forceinline__ void gemm_run(int tid, f32x16 (&acc)[2][2], GRegs& g, const GOp& o, int K, unsigned char* smem) {
;     ...
;   for (int k = 0; k < nk; k++) {
;     bf16r* cur = sbuf + (k & 1) * (256 * LDK);
;     bf16r* nxt = sbuf + ((k & 1) ^ 1) * (256 * LDK);
;     const bf16r* As = cur + (wm * 64 + fr) * LDK + fh * 8;
;     const bf16r* Bs = cur + 128 * LDK + (wn * 64 + fr) * LDK + fh * 8;
;     const bool wr = (k + 1 < nk), ld = (k + 2 < nk);
;     bf16x8 fa[2][2], fb[2][2];
;     fa[0][0] = *(const bf16x8*)(As);
;     fa[0][1] = *(const bf16x8*)(As + 32 * LDK);
;     fb[0][0] = *(const bf16x8*)(Bs);
;     fb[0][1] = *(const bf16x8*)(Bs + 32 * LDK);
; #pragma unroll
;     for (int i = 0; i < 4; i++) {
;       if (wr) {
;         *(u32x4*)(nxt + (r0 + i * 32) * LDK + sg * 8) = g.a[i];
;         *(u32x4*)(nxt + 128 * LDK + (r0 + i * 32) * LDK + sg * 8) = g.b[i];
;       }
;       if (ld) {
;         g.a[i] = *(const u32x4*)(Ap + (size_t)i * 32 * o.lda + (k + 2) * 64);
;         g.b[i] = *(const u32x4*)(Bp + o.bs.o[i] + (k + 2) * 64);
;       }
;       if (i < 3) {
;         fa[(i + 1) & 1][0] = *(const bf16x8*)(As + (i + 1) * 16);
;         fa[(i + 1) & 1][1] = *(const bf16x8*)(As + 32 * LDK + (i + 1) * 16);
;         fb[(i + 1) & 1][0] = *(const bf16x8*)(Bs + (i + 1) * 16);
;         fb[(i + 1) & 1][1] = *(const bf16x8*)(Bs + 32 * LDK + (i + 1) * 16);
;       }
;       __builtin_amdgcn_sched_barrier(0);
;       __builtin_amdgcn_s_setprio(1);
;       acc[0][0] = __builtin_amdgcn_mfma_f32_32x32x16_bf16(fa[i & 1][0], fb[i & 1][0], acc[0][0], 0, 0, 0);
;       acc[0][1] = __builtin_amdgcn_mfma_f32_32x32x16_bf16(fa[i & 1][0], fb[i & 1][1], acc[0][1], 0, 0, 0);
;       acc[1][0] = __builtin_amdgcn_mfma_f32_32x32x16_bf16(fa[i & 1][1], fb[i & 1][0], acc[1][0], 0, 0, 0);
;       acc[1][1] = __builtin_amdgcn_mfma_f32_32x32x16_bf16(fa[i & 1][1], fb[i & 1][1], acc[1][1], 0, 0, 0);
;       __builtin_amdgcn_s_setprio(0);
;     }
;     __syncthreads();
	global_load_dwordx4 v[66:69], v[64:65], off offset:896
	global_load_dwordx4 v[110:113], v[106:107], off offset:896
	ds_read_b128 v[138:141], v104 offset:36864
	ds_read_b128 v[142:145], v104 offset:41472
	ds_read_b128 v[154:157], v101 offset:55296
	ds_read_b128 v[158:161], v101 offset:59904
	s_waitcnt vmcnt(9)
	ds_write_b128 v100, v[114:117]
	s_waitcnt vmcnt(8)
	ds_write_b128 v100, v[118:121] offset:18432
	ds_read_b128 v[114:117], v104 offset:36896
	ds_read_b128 v[118:121], v104 offset:41504
	ds_read_b128 v[162:165], v101 offset:55328
	ds_read_b128 v[166:169], v101 offset:59936
	s_waitcnt lgkmcnt(7)
	v_mfma_f32_32x32x16_bf16 v[32:47], v[138:141], v[154:157], v[32:47]
	s_waitcnt lgkmcnt(6)
	v_mfma_f32_32x32x16_bf16 v[48:63], v[138:141], v[158:161], v[48:63]
	v_mfma_f32_32x32x16_bf16 v[0:15], v[142:145], v[154:157], v[0:15]
	v_mfma_f32_32x32x16_bf16 v[16:31], v[142:145], v[158:161], v[16:31]
	global_load_dwordx4 v[138:141], v[72:73], off offset:896
	global_load_dwordx4 v[142:145], v[76:77], off offset:896
	s_waitcnt vmcnt(9)
	ds_write_b128 v100, v[122:125] offset:4608
	s_waitcnt vmcnt(8)
	ds_write_b128 v100, v[126:129] offset:23040
	ds_read_b128 v[122:125], v104 offset:36928
	ds_read_b128 v[126:129], v104 offset:41536
	ds_read_b128 v[154:157], v101 offset:55360
	ds_read_b128 v[158:161], v101 offset:59968
	s_waitcnt lgkmcnt(7)
	v_mfma_f32_32x32x16_bf16 v[32:47], v[114:117], v[162:165], v[32:47]
	s_waitcnt lgkmcnt(6)
	v_mfma_f32_32x32x16_bf16 v[48:63], v[114:117], v[166:169], v[48:63]
	v_mfma_f32_32x32x16_bf16 v[0:15], v[118:121], v[162:165], v[0:15]
	v_mfma_f32_32x32x16_bf16 v[16:31], v[118:121], v[166:169], v[16:31]
	global_load_dwordx4 v[114:117], v[80:81], off offset:896
	global_load_dwordx4 v[118:121], v[84:85], off offset:896
	s_waitcnt vmcnt(9)
	ds_write_b128 v100, v[130:133] offset:9216
	s_waitcnt vmcnt(8)
	ds_write_b128 v100, v[134:137] offset:27648
	ds_read_b128 v[130:133], v104 offset:36960
	ds_read_b128 v[134:137], v104 offset:41568
	ds_read_b128 v[162:165], v101 offset:55392
	ds_read_b128 v[166:169], v101 offset:60000
	s_waitcnt lgkmcnt(7)
	v_mfma_f32_32x32x16_bf16 v[32:47], v[122:125], v[154:157], v[32:47]
	s_waitcnt lgkmcnt(6)
	v_mfma_f32_32x32x16_bf16 v[48:63], v[122:125], v[158:161], v[48:63]
	v_mfma_f32_32x32x16_bf16 v[0:15], v[126:129], v[154:157], v[0:15]
	v_mfma_f32_32x32x16_bf16 v[16:31], v[126:129], v[158:161], v[16:31]
	global_load_dwordx4 v[122:125], v[88:89], off offset:896
	global_load_dwordx4 v[126:129], v[92:93], off offset:896
	s_waitcnt vmcnt(9)
	ds_write_b128 v100, v[146:149] offset:13824
	s_waitcnt vmcnt(8)
	ds_write_b128 v100, v[150:153] offset:32256
	s_waitcnt lgkmcnt(3)
	v_mfma_f32_32x32x16_bf16 v[32:47], v[130:133], v[162:165], v[32:47]
	s_waitcnt lgkmcnt(2)
	v_mfma_f32_32x32x16_bf16 v[48:63], v[130:133], v[166:169], v[48:63]
	v_mfma_f32_32x32x16_bf16 v[0:15], v[134:137], v[162:165], v[0:15]
	v_mfma_f32_32x32x16_bf16 v[16:31], v[134:137], v[166:169], v[16:31]
	s_waitcnt lgkmcnt(0)
	s_barrier
	global_load_dwordx4 v[130:133], v[64:65], off offset:1024
	global_load_dwordx4 v[134:137], v[106:107], off offset:1024
	ds_read_b128 v[146:149], v104
	ds_read_b128 v[150:153], v104 offset:4608
	ds_read_b128 v[154:157], v101 offset:18432
	ds_read_b128 v[158:161], v101 offset:23040
	s_waitcnt vmcnt(9)
	ds_write_b128 v100, v[66:69] offset:36864
	s_waitcnt vmcnt(8)
	ds_write_b128 v100, v[110:113] offset:55296
	ds_read_b128 v[66:69], v104 offset:32
	ds_read_b128 v[110:113], v104 offset:4640
	ds_read_b128 v[162:165], v101 offset:18464
	ds_read_b128 v[166:169], v101 offset:23072
	s_waitcnt lgkmcnt(7)
	v_mfma_f32_32x32x16_bf16 v[32:47], v[146:149], v[154:157], v[32:47]
	s_waitcnt lgkmcnt(6)
	v_mfma_f32_32x32x16_bf16 v[48:63], v[146:149], v[158:161], v[48:63]
	v_mfma_f32_32x32x16_bf16 v[0:15], v[150:153], v[154:157], v[0:15]
	v_mfma_f32_32x32x16_bf16 v[16:31], v[150:153], v[158:161], v[16:31]
	global_load_dwordx4 v[146:149], v[72:73], off offset:1024
	global_load_dwordx4 v[150:153], v[76:77], off offset:1024
	s_waitcnt vmcnt(9)
	ds_write_b128 v100, v[138:141] offset:41472
	s_waitcnt vmcnt(8)
	ds_write_b128 v100, v[142:145] offset:59904
	ds_read_b128 v[138:141], v104 offset:64
	ds_read_b128 v[142:145], v104 offset:4672
	ds_read_b128 v[154:157], v101 offset:18496
	ds_read_b128 v[158:161], v101 offset:23104
	s_waitcnt lgkmcnt(7)
	v_mfma_f32_32x32x16_bf16 v[32:47], v[66:69], v[162:165], v[32:47]
	s_waitcnt lgkmcnt(6)
	v_mfma_f32_32x32x16_bf16 v[48:63], v[66:69], v[166:169], v[48:63]
	v_mfma_f32_32x32x16_bf16 v[0:15], v[110:113], v[162:165], v[0:15]
	v_mfma_f32_32x32x16_bf16 v[16:31], v[110:113], v[166:169], v[16:31]
	global_load_dwordx4 v[66:69], v[80:81], off offset:1024
	global_load_dwordx4 v[110:113], v[84:85], off offset:1024
	s_waitcnt vmcnt(9)
	ds_write_b128 v100, v[114:117] offset:46080
	s_waitcnt vmcnt(8)
	ds_write_b128 v100, v[118:121] offset:64512
	ds_read_b128 v[114:117], v104 offset:96
	ds_read_b128 v[118:121], v104 offset:4704
	ds_read_b128 v[162:165], v101 offset:18528
	ds_read_b128 v[166:169], v101 offset:23136
	s_waitcnt lgkmcnt(7)
	v_mfma_f32_32x32x16_bf16 v[32:47], v[138:141], v[154:157], v[32:47]
	s_waitcnt lgkmcnt(6)
	v_mfma_f32_32x32x16_bf16 v[48:63], v[138:141], v[158:161], v[48:63]
	v_mfma_f32_32x32x16_bf16 v[0:15], v[142:145], v[154:157], v[0:15]
	v_mfma_f32_32x32x16_bf16 v[16:31], v[142:145], v[158:161], v[16:31]
	global_load_dwordx4 v[138:141], v[88:89], off offset:1024
	global_load_dwordx4 v[142:145], v[92:93], off offset:1024
	s_waitcnt vmcnt(9)
	ds_write_b128 v100, v[122:125] offset:50688
	s_waitcnt vmcnt(8)
	ds_write_b128 v105, v[126:129] offset:13824
	s_waitcnt lgkmcnt(3)
	v_mfma_f32_32x32x16_bf16 v[32:47], v[114:117], v[162:165], v[32:47]
	s_waitcnt lgkmcnt(2)
	v_mfma_f32_32x32x16_bf16 v[48:63], v[114:117], v[166:169], v[48:63]
	v_mfma_f32_32x32x16_bf16 v[0:15], v[118:121], v[162:165], v[0:15]
	v_mfma_f32_32x32x16_bf16 v[16:31], v[118:121], v[166:169], v[16:31]
	s_waitcnt lgkmcnt(0)
	s_barrier
; __device__ __forceinline__ void gemm_run(int tid, f32x16 (&acc)[2][2], GRegs& g, const GOp& o, int K, unsigned char* smem) {
;     ...
;   for (int k = 0; k < nk; k++) {
;     bf16r* cur = sbuf + (k & 1) * (256 * LDK);
;     bf16r* nxt = sbuf + ((k & 1) ^ 1) * (256 * LDK);
;     const bf16r* As = cur + (wm * 64 + fr) * LDK + fh * 8;
;     const bf16r* Bs = cur + 128 * LDK + (wn * 64 + fr) * LDK + fh * 8;
;     const bool wr = (k + 1 < nk), ld = (k + 2 < nk);
;     bf16x8 fa[2][2], fb[2][2];
;     fa[0][0] = *(const bf16x8*)(As);
;     fa[0][1] = *(const bf16x8*)(As + 32 * LDK);
;     fb[0][0] = *(const bf16x8*)(Bs);
;     fb[0][1] = *(const bf16x8*)(Bs + 32 * LDK);
; #pragma unroll
;     for (int i = 0; i < 4; i++) {
;       if (wr) {
;         *(u32x4*)(nxt + (r0 + i * 32) * LDK + sg * 8) = g.a[i];
;         *(u32x4*)(nxt + 128 * LDK + (r0 + i * 32) * LDK + sg * 8) = g.b[i];
;       }
;       if (ld) {
;         g.a[i] = *(const u32x4*)(Ap + (size_t)i * 32 * o.lda + (k + 2) * 64);
;         g.b[i] = *(const u32x4*)(Bp + o.bs.o[i] + (k + 2) * 64);
;       }
;       if (i < 3) {
;         fa[(i + 1) & 1][0] = *(const bf16x8*)(As + (i + 1) * 16);
;         fa[(i + 1) & 1][1] = *(const bf16x8*)(As + 32 * LDK + (i + 1) * 16);
;         fb[(i + 1) & 1][0] = *(const bf16x8*)(Bs + (i + 1) * 16);
;         fb[(i + 1) & 1][1] = *(const bf16x8*)(Bs + 32 * LDK + (i + 1) * 16);
;       }
;       __builtin_amdgcn_sched_barrier(0);
;       __builtin_amdgcn_s_setprio(1);
;       acc[0][0] = __builtin_amdgcn_mfma_f32_32x32x16_bf16(fa[i & 1][0], fb[i & 1][0], acc[0][0], 0, 0, 0);
;       acc[0][1] = __builtin_amdgcn_mfma_f32_32x32x16_bf16(fa[i & 1][0], fb[i & 1][1], acc[0][1], 0, 0, 0);
;       acc[1][0] = __builtin_amdgcn_mfma_f32_32x32x16_bf16(fa[i & 1][1], fb[i & 1][0], acc[1][0], 0, 0, 0);
;       acc[1][1] = __builtin_amdgcn_mfma_f32_32x32x16_bf16(fa[i & 1][1], fb[i & 1][1], acc[1][1], 0, 0, 0);
;       __builtin_amdgcn_s_setprio(0);
;     }
;     __syncthreads();
	global_load_dwordx4 v[114:117], v[64:65], off offset:1152
	global_load_dwordx4 v[118:121], v[106:107], off offset:1152
	ds_read_b128 v[122:125], v104 offset:36864
	ds_read_b128 v[126:129], v104 offset:41472
	ds_read_b128 v[154:157], v101 offset:55296
	ds_read_b128 v[158:161], v101 offset:59904
	s_waitcnt vmcnt(9)
	ds_write_b128 v100, v[130:133]
	s_waitcnt vmcnt(8)
	ds_write_b128 v100, v[134:137] offset:18432
	ds_read_b128 v[130:133], v104 offset:36896
	ds_read_b128 v[134:137], v104 offset:41504
	ds_read_b128 v[162:165], v101 offset:55328
	ds_read_b128 v[166:169], v101 offset:59936
	s_waitcnt lgkmcnt(7)
	v_mfma_f32_32x32x16_bf16 v[32:47], v[122:125], v[154:157], v[32:47]
	s_waitcnt lgkmcnt(6)
	v_mfma_f32_32x32x16_bf16 v[48:63], v[122:125], v[158:161], v[48:63]
	v_mfma_f32_32x32x16_bf16 v[0:15], v[126:129], v[154:157], v[0:15]
	v_mfma_f32_32x32x16_bf16 v[16:31], v[126:129], v[158:161], v[16:31]
	global_load_dwordx4 v[122:125], v[72:73], off offset:1152
	global_load_dwordx4 v[126:129], v[76:77], off offset:1152
	s_waitcnt vmcnt(9)
	ds_write_b128 v100, v[146:149] offset:4608
	s_waitcnt vmcnt(8)
	ds_write_b128 v100, v[150:153] offset:23040
	ds_read_b128 v[146:149], v104 offset:36928
	ds_read_b128 v[150:153], v104 offset:41536
	ds_read_b128 v[154:157], v101 offset:55360
	ds_read_b128 v[158:161], v101 offset:59968
	s_waitcnt lgkmcnt(7)
	v_mfma_f32_32x32x16_bf16 v[32:47], v[130:133], v[162:165], v[32:47]
	s_waitcnt lgkmcnt(6)
	v_mfma_f32_32x32x16_bf16 v[48:63], v[130:133], v[166:169], v[48:63]
	v_mfma_f32_32x32x16_bf16 v[0:15], v[134:137], v[162:165], v[0:15]
	v_mfma_f32_32x32x16_bf16 v[16:31], v[134:137], v[166:169], v[16:31]
	global_load_dwordx4 v[130:133], v[80:81], off offset:1152
	global_load_dwordx4 v[134:137], v[84:85], off offset:1152
	s_waitcnt vmcnt(9)
	ds_write_b128 v100, v[66:69] offset:9216
	s_waitcnt vmcnt(8)
	ds_write_b128 v100, v[110:113] offset:27648
	ds_read_b128 v[66:69], v104 offset:36960
	ds_read_b128 v[110:113], v104 offset:41568
	ds_read_b128 v[162:165], v101 offset:55392
	ds_read_b128 v[166:169], v101 offset:60000
	s_waitcnt lgkmcnt(7)
	v_mfma_f32_32x32x16_bf16 v[32:47], v[146:149], v[154:157], v[32:47]
	s_waitcnt lgkmcnt(6)
	v_mfma_f32_32x32x16_bf16 v[48:63], v[146:149], v[158:161], v[48:63]
	v_mfma_f32_32x32x16_bf16 v[0:15], v[150:153], v[154:157], v[0:15]
	v_mfma_f32_32x32x16_bf16 v[16:31], v[150:153], v[158:161], v[16:31]
	global_load_dwordx4 v[146:149], v[88:89], off offset:1152
	global_load_dwordx4 v[150:153], v[92:93], off offset:1152
	s_waitcnt vmcnt(9)
	ds_write_b128 v100, v[138:141] offset:13824
	s_waitcnt vmcnt(8)
	ds_write_b128 v100, v[142:145] offset:32256
	s_waitcnt lgkmcnt(3)
	v_mfma_f32_32x32x16_bf16 v[32:47], v[66:69], v[162:165], v[32:47]
	s_waitcnt lgkmcnt(2)
	v_mfma_f32_32x32x16_bf16 v[48:63], v[66:69], v[166:169], v[48:63]
	v_mfma_f32_32x32x16_bf16 v[0:15], v[110:113], v[162:165], v[0:15]
	v_mfma_f32_32x32x16_bf16 v[16:31], v[110:113], v[166:169], v[16:31]
	s_waitcnt lgkmcnt(0)
	s_barrier
	global_load_dwordx4 v[66:69], v[64:65], off offset:1280
	global_load_dwordx4 v[110:113], v[106:107], off offset:1280
	ds_read_b128 v[138:141], v104
	ds_read_b128 v[142:145], v104 offset:4608
	ds_read_b128 v[154:157], v101 offset:18432
	ds_read_b128 v[158:161], v101 offset:23040
	s_waitcnt vmcnt(9)
	ds_write_b128 v100, v[114:117] offset:36864
	s_waitcnt vmcnt(8)
	ds_write_b128 v100, v[118:121] offset:55296
	ds_read_b128 v[114:117], v104 offset:32
	ds_read_b128 v[118:121], v104 offset:4640
	ds_read_b128 v[162:165], v101 offset:18464
	ds_read_b128 v[166:169], v101 offset:23072
	s_waitcnt lgkmcnt(7)
	v_mfma_f32_32x32x16_bf16 v[32:47], v[138:141], v[154:157], v[32:47]
	s_waitcnt lgkmcnt(6)
	v_mfma_f32_32x32x16_bf16 v[48:63], v[138:141], v[158:161], v[48:63]
	v_mfma_f32_32x32x16_bf16 v[0:15], v[142:145], v[154:157], v[0:15]
	v_mfma_f32_32x32x16_bf16 v[16:31], v[142:145], v[158:161], v[16:31]
	global_load_dwordx4 v[138:141], v[72:73], off offset:1280
	global_load_dwordx4 v[142:145], v[76:77], off offset:1280
	s_waitcnt vmcnt(9)
	ds_write_b128 v100, v[122:125] offset:41472
	s_waitcnt vmcnt(8)
	ds_write_b128 v100, v[126:129] offset:59904
	ds_read_b128 v[122:125], v104 offset:64
	ds_read_b128 v[126:129], v104 offset:4672
	ds_read_b128 v[154:157], v101 offset:18496
	ds_read_b128 v[158:161], v101 offset:23104
	s_waitcnt lgkmcnt(7)
	v_mfma_f32_32x32x16_bf16 v[32:47], v[114:117], v[162:165], v[32:47]
	s_waitcnt lgkmcnt(6)
	v_mfma_f32_32x32x16_bf16 v[48:63], v[114:117], v[166:169], v[48:63]
	v_mfma_f32_32x32x16_bf16 v[0:15], v[118:121], v[162:165], v[0:15]
	v_mfma_f32_32x32x16_bf16 v[16:31], v[118:121], v[166:169], v[16:31]
	global_load_dwordx4 v[114:117], v[80:81], off offset:1280
	global_load_dwordx4 v[118:121], v[84:85], off offset:1280
	s_waitcnt vmcnt(9)
	ds_write_b128 v100, v[130:133] offset:46080
	s_waitcnt vmcnt(8)
	ds_write_b128 v100, v[134:137] offset:64512
	ds_read_b128 v[130:133], v104 offset:96
	ds_read_b128 v[134:137], v104 offset:4704
	ds_read_b128 v[162:165], v101 offset:18528
	ds_read_b128 v[166:169], v101 offset:23136
	s_waitcnt lgkmcnt(7)
	v_mfma_f32_32x32x16_bf16 v[32:47], v[122:125], v[154:157], v[32:47]
	s_waitcnt lgkmcnt(6)
	v_mfma_f32_32x32x16_bf16 v[48:63], v[122:125], v[158:161], v[48:63]
	v_mfma_f32_32x32x16_bf16 v[0:15], v[126:129], v[154:157], v[0:15]
	v_mfma_f32_32x32x16_bf16 v[16:31], v[126:129], v[158:161], v[16:31]
	global_load_dwordx4 v[122:125], v[88:89], off offset:1280
	global_load_dwordx4 v[126:129], v[92:93], off offset:1280
	s_waitcnt vmcnt(9)
	ds_write_b128 v100, v[146:149] offset:50688
	s_waitcnt vmcnt(8)
	ds_write_b128 v105, v[150:153] offset:13824
	s_waitcnt lgkmcnt(3)
	v_mfma_f32_32x32x16_bf16 v[32:47], v[130:133], v[162:165], v[32:47]
	s_waitcnt lgkmcnt(2)
	v_mfma_f32_32x32x16_bf16 v[48:63], v[130:133], v[166:169], v[48:63]
	v_mfma_f32_32x32x16_bf16 v[0:15], v[134:137], v[162:165], v[0:15]
	v_mfma_f32_32x32x16_bf16 v[16:31], v[134:137], v[166:169], v[16:31]
	s_waitcnt lgkmcnt(0)
	s_barrier
; __device__ __forceinline__ void gemm_run(int tid, f32x16 (&acc)[2][2], GRegs& g, const GOp& o, int K, unsigned char* smem) {
;     ...
;   for (int k = 0; k < nk; k++) {
;     bf16r* cur = sbuf + (k & 1) * (256 * LDK);
;     bf16r* nxt = sbuf + ((k & 1) ^ 1) * (256 * LDK);
;     const bf16r* As = cur + (wm * 64 + fr) * LDK + fh * 8;
;     const bf16r* Bs = cur + 128 * LDK + (wn * 64 + fr) * LDK + fh * 8;
;     const bool wr = (k + 1 < nk), ld = (k + 2 < nk);
;     bf16x8 fa[2][2], fb[2][2];
;     fa[0][0] = *(const bf16x8*)(As);
;     fa[0][1] = *(const bf16x8*)(As + 32 * LDK);
;     fb[0][0] = *(const bf16x8*)(Bs);
;     fb[0][1] = *(const bf16x8*)(Bs + 32 * LDK);
; #pragma unroll
;     for (int i = 0; i < 4; i++) {
;       if (wr) {
;         *(u32x4*)(nxt + (r0 + i * 32) * LDK + sg * 8) = g.a[i];
;         *(u32x4*)(nxt + 128 * LDK + (r0 + i * 32) * LDK + sg * 8) = g.b[i];
;       }
;       if (ld) {
;         g.a[i] = *(const u32x4*)(Ap + (size_t)i * 32 * o.lda + (k + 2) * 64);
;         g.b[i] = *(const u32x4*)(Bp + o.bs.o[i] + (k + 2) * 64);
;       }
;       if (i < 3) {
;         fa[(i + 1) & 1][0] = *(const bf16x8*)(As + (i + 1) * 16);
;         fa[(i + 1) & 1][1] = *(const bf16x8*)(As + 32 * LDK + (i + 1) * 16);
;         fb[(i + 1) & 1][0] = *(const bf16x8*)(Bs + (i + 1) * 16);
;         fb[(i + 1) & 1][1] = *(const bf16x8*)(Bs + 32 * LDK + (i + 1) * 16);
;       }
;       __builtin_amdgcn_sched_barrier(0);
;       __builtin_amdgcn_s_setprio(1);
;       acc[0][0] = __builtin_amdgcn_mfma_f32_32x32x16_bf16(fa[i & 1][0], fb[i & 1][0], acc[0][0], 0, 0, 0);
;       acc[0][1] = __builtin_amdgcn_mfma_f32_32x32x16_bf16(fa[i & 1][0], fb[i & 1][1], acc[0][1], 0, 0, 0);
;       acc[1][0] = __builtin_amdgcn_mfma_f32_32x32x16_bf16(fa[i & 1][1], fb[i & 1][0], acc[1][0], 0, 0, 0);
;       acc[1][1] = __builtin_amdgcn_mfma_f32_32x32x16_bf16(fa[i & 1][1], fb[i & 1][1], acc[1][1], 0, 0, 0);
;       __builtin_amdgcn_s_setprio(0);
;     }
;     __syncthreads();
	global_load_dwordx4 v[130:133], v[64:65], off offset:1408
	global_load_dwordx4 v[134:137], v[106:107], off offset:1408
	ds_read_b128 v[146:149], v104 offset:36864
	ds_read_b128 v[150:153], v104 offset:41472
	ds_read_b128 v[154:157], v101 offset:55296
	ds_read_b128 v[158:161], v101 offset:59904
	s_waitcnt vmcnt(9)
	ds_write_b128 v100, v[66:69]
	s_waitcnt vmcnt(8)
	ds_write_b128 v100, v[110:113] offset:18432
	ds_read_b128 v[66:69], v104 offset:36896
	ds_read_b128 v[110:113], v104 offset:41504
	ds_read_b128 v[162:165], v101 offset:55328
	ds_read_b128 v[166:169], v101 offset:59936
	s_waitcnt lgkmcnt(7)
	v_mfma_f32_32x32x16_bf16 v[32:47], v[146:149], v[154:157], v[32:47]
	s_waitcnt lgkmcnt(6)
	v_mfma_f32_32x32x16_bf16 v[48:63], v[146:149], v[158:161], v[48:63]
	v_mfma_f32_32x32x16_bf16 v[0:15], v[150:153], v[154:157], v[0:15]
	v_mfma_f32_32x32x16_bf16 v[16:31], v[150:153], v[158:161], v[16:31]
	global_load_dwordx4 v[146:149], v[72:73], off offset:1408
	global_load_dwordx4 v[150:153], v[76:77], off offset:1408
	s_waitcnt vmcnt(9)
	ds_write_b128 v100, v[138:141] offset:4608
	s_waitcnt vmcnt(8)
	ds_write_b128 v100, v[142:145] offset:23040
	ds_read_b128 v[138:141], v104 offset:36928
	ds_read_b128 v[142:145], v104 offset:41536
	ds_read_b128 v[154:157], v101 offset:55360
	ds_read_b128 v[158:161], v101 offset:59968
	s_waitcnt lgkmcnt(7)
	v_mfma_f32_32x32x16_bf16 v[32:47], v[66:69], v[162:165], v[32:47]
	s_waitcnt lgkmcnt(6)
	v_mfma_f32_32x32x16_bf16 v[48:63], v[66:69], v[166:169], v[48:63]
	v_mfma_f32_32x32x16_bf16 v[0:15], v[110:113], v[162:165], v[0:15]
	v_mfma_f32_32x32x16_bf16 v[16:31], v[110:113], v[166:169], v[16:31]
	global_load_dwordx4 v[66:69], v[80:81], off offset:1408
	global_load_dwordx4 v[110:113], v[84:85], off offset:1408
	s_waitcnt vmcnt(9)
	ds_write_b128 v100, v[114:117] offset:9216
	s_waitcnt vmcnt(8)
	ds_write_b128 v100, v[118:121] offset:27648
	ds_read_b128 v[114:117], v104 offset:36960
	ds_read_b128 v[118:121], v104 offset:41568
	ds_read_b128 v[162:165], v101 offset:55392
	ds_read_b128 v[166:169], v101 offset:60000
	s_waitcnt lgkmcnt(7)
	v_mfma_f32_32x32x16_bf16 v[32:47], v[138:141], v[154:157], v[32:47]
	s_waitcnt lgkmcnt(6)
	v_mfma_f32_32x32x16_bf16 v[48:63], v[138:141], v[158:161], v[48:63]
	v_mfma_f32_32x32x16_bf16 v[0:15], v[142:145], v[154:157], v[0:15]
	v_mfma_f32_32x32x16_bf16 v[16:31], v[142:145], v[158:161], v[16:31]
	global_load_dwordx4 v[138:141], v[88:89], off offset:1408
	global_load_dwordx4 v[142:145], v[92:93], off offset:1408
	s_waitcnt vmcnt(9)
	ds_write_b128 v100, v[122:125] offset:13824
	s_waitcnt vmcnt(8)
	ds_write_b128 v100, v[126:129] offset:32256
	s_waitcnt lgkmcnt(3)
	v_mfma_f32_32x32x16_bf16 v[32:47], v[114:117], v[162:165], v[32:47]
	s_waitcnt lgkmcnt(2)
	v_mfma_f32_32x32x16_bf16 v[48:63], v[114:117], v[166:169], v[48:63]
	v_mfma_f32_32x32x16_bf16 v[0:15], v[118:121], v[162:165], v[0:15]
	v_mfma_f32_32x32x16_bf16 v[16:31], v[118:121], v[166:169], v[16:31]
	s_waitcnt lgkmcnt(0)
	s_barrier
	global_load_dwordx4 v[114:117], v[64:65], off offset:1536
	global_load_dwordx4 v[118:121], v[106:107], off offset:1536
	ds_read_b128 v[122:125], v104
	ds_read_b128 v[126:129], v104 offset:4608
	ds_read_b128 v[154:157], v101 offset:18432
	ds_read_b128 v[158:161], v101 offset:23040
	s_waitcnt vmcnt(9)
	ds_write_b128 v100, v[130:133] offset:36864
	s_waitcnt vmcnt(8)
	ds_write_b128 v100, v[134:137] offset:55296
	ds_read_b128 v[130:133], v104 offset:32
	ds_read_b128 v[134:137], v104 offset:4640
	ds_read_b128 v[162:165], v101 offset:18464
	ds_read_b128 v[166:169], v101 offset:23072
	s_waitcnt lgkmcnt(7)
	v_mfma_f32_32x32x16_bf16 v[32:47], v[122:125], v[154:157], v[32:47]
	s_waitcnt lgkmcnt(6)
	v_mfma_f32_32x32x16_bf16 v[48:63], v[122:125], v[158:161], v[48:63]
	v_mfma_f32_32x32x16_bf16 v[0:15], v[126:129], v[154:157], v[0:15]
	v_mfma_f32_32x32x16_bf16 v[16:31], v[126:129], v[158:161], v[16:31]
	global_load_dwordx4 v[122:125], v[72:73], off offset:1536
	global_load_dwordx4 v[126:129], v[76:77], off offset:1536
	s_waitcnt vmcnt(9)
	ds_write_b128 v100, v[146:149] offset:41472
	s_waitcnt vmcnt(8)
	ds_write_b128 v100, v[150:153] offset:59904
	ds_read_b128 v[146:149], v104 offset:64
	ds_read_b128 v[150:153], v104 offset:4672
	ds_read_b128 v[154:157], v101 offset:18496
	ds_read_b128 v[158:161], v101 offset:23104
	s_waitcnt lgkmcnt(7)
	v_mfma_f32_32x32x16_bf16 v[32:47], v[130:133], v[162:165], v[32:47]
	s_waitcnt lgkmcnt(6)
	v_mfma_f32_32x32x16_bf16 v[48:63], v[130:133], v[166:169], v[48:63]
	v_mfma_f32_32x32x16_bf16 v[0:15], v[134:137], v[162:165], v[0:15]
	v_mfma_f32_32x32x16_bf16 v[16:31], v[134:137], v[166:169], v[16:31]
	global_load_dwordx4 v[130:133], v[80:81], off offset:1536
	global_load_dwordx4 v[134:137], v[84:85], off offset:1536
	s_waitcnt vmcnt(9)
	ds_write_b128 v100, v[66:69] offset:46080
	s_waitcnt vmcnt(8)
	ds_write_b128 v100, v[110:113] offset:64512
	ds_read_b128 v[66:69], v104 offset:96
	ds_read_b128 v[110:113], v104 offset:4704
	ds_read_b128 v[162:165], v101 offset:18528
	ds_read_b128 v[166:169], v101 offset:23136
	s_waitcnt lgkmcnt(7)
	v_mfma_f32_32x32x16_bf16 v[32:47], v[146:149], v[154:157], v[32:47]
	s_waitcnt lgkmcnt(6)
	v_mfma_f32_32x32x16_bf16 v[48:63], v[146:149], v[158:161], v[48:63]
	v_mfma_f32_32x32x16_bf16 v[0:15], v[150:153], v[154:157], v[0:15]
	v_mfma_f32_32x32x16_bf16 v[16:31], v[150:153], v[158:161], v[16:31]
	global_load_dwordx4 v[146:149], v[88:89], off offset:1536
	global_load_dwordx4 v[150:153], v[92:93], off offset:1536
	s_waitcnt vmcnt(9)
	ds_write_b128 v100, v[138:141] offset:50688
	s_waitcnt vmcnt(8)
	ds_write_b128 v105, v[142:145] offset:13824
	s_waitcnt lgkmcnt(3)
	v_mfma_f32_32x32x16_bf16 v[32:47], v[66:69], v[162:165], v[32:47]
	s_waitcnt lgkmcnt(2)
	v_mfma_f32_32x32x16_bf16 v[48:63], v[66:69], v[166:169], v[48:63]
	v_mfma_f32_32x32x16_bf16 v[0:15], v[110:113], v[162:165], v[0:15]
	v_mfma_f32_32x32x16_bf16 v[16:31], v[110:113], v[166:169], v[16:31]
	s_waitcnt lgkmcnt(0)
	s_barrier
; __device__ __forceinline__ void gemm_run(int tid, f32x16 (&acc)[2][2], GRegs& g, const GOp& o, int K, unsigned char* smem) {
;     ...
;   for (int k = 0; k < nk; k++) {
;     bf16r* cur = sbuf + (k & 1) * (256 * LDK);
;     bf16r* nxt = sbuf + ((k & 1) ^ 1) * (256 * LDK);
;     const bf16r* As = cur + (wm * 64 + fr) * LDK + fh * 8;
;     const bf16r* Bs = cur + 128 * LDK + (wn * 64 + fr) * LDK + fh * 8;
;     const bool wr = (k + 1 < nk), ld = (k + 2 < nk);
;     bf16x8 fa[2][2], fb[2][2];
;     fa[0][0] = *(const bf16x8*)(As);
;     fa[0][1] = *(const bf16x8*)(As + 32 * LDK);
;     fb[0][0] = *(const bf16x8*)(Bs);
;     fb[0][1] = *(const bf16x8*)(Bs + 32 * LDK);
; #pragma unroll
;     for (int i = 0; i < 4; i++) {
;       if (wr) {
;         *(u32x4*)(nxt + (r0 + i * 32) * LDK + sg * 8) = g.a[i];
;         *(u32x4*)(nxt + 128 * LDK + (r0 + i * 32) * LDK + sg * 8) = g.b[i];
;       }
;       if (ld) {
;         g.a[i] = *(const u32x4*)(Ap + (size_t)i * 32 * o.lda + (k + 2) * 64);
;         g.b[i] = *(const u32x4*)(Bp + o.bs.o[i] + (k + 2) * 64);
;       }
;       if (i < 3) {
;         fa[(i + 1) & 1][0] = *(const bf16x8*)(As + (i + 1) * 16);
;         fa[(i + 1) & 1][1] = *(const bf16x8*)(As + 32 * LDK + (i + 1) * 16);
;         fb[(i + 1) & 1][0] = *(const bf16x8*)(Bs + (i + 1) * 16);
;         fb[(i + 1) & 1][1] = *(const bf16x8*)(Bs + 32 * LDK + (i + 1) * 16);
;       }
;       __builtin_amdgcn_sched_barrier(0);
;       __builtin_amdgcn_s_setprio(1);
;       acc[0][0] = __builtin_amdgcn_mfma_f32_32x32x16_bf16(fa[i & 1][0], fb[i & 1][0], acc[0][0], 0, 0, 0);
;       acc[0][1] = __builtin_amdgcn_mfma_f32_32x32x16_bf16(fa[i & 1][0], fb[i & 1][1], acc[0][1], 0, 0, 0);
;       acc[1][0] = __builtin_amdgcn_mfma_f32_32x32x16_bf16(fa[i & 1][1], fb[i & 1][0], acc[1][0], 0, 0, 0);
;       acc[1][1] = __builtin_amdgcn_mfma_f32_32x32x16_bf16(fa[i & 1][1], fb[i & 1][1], acc[1][1], 0, 0, 0);
;       __builtin_amdgcn_s_setprio(0);
;     }
;     __syncthreads();
	global_load_dwordx4 v[66:69], v[64:65], off offset:1664
	global_load_dwordx4 v[110:113], v[106:107], off offset:1664
	ds_read_b128 v[138:141], v104 offset:36864
	ds_read_b128 v[142:145], v104 offset:41472
	ds_read_b128 v[154:157], v101 offset:55296
	ds_read_b128 v[158:161], v101 offset:59904
	s_waitcnt vmcnt(9)
	ds_write_b128 v100, v[114:117]
	s_waitcnt vmcnt(8)
	ds_write_b128 v100, v[118:121] offset:18432
	ds_read_b128 v[114:117], v104 offset:36896
	ds_read_b128 v[118:121], v104 offset:41504
	ds_read_b128 v[162:165], v101 offset:55328
	ds_read_b128 v[166:169], v101 offset:59936
	s_waitcnt lgkmcnt(7)
	v_mfma_f32_32x32x16_bf16 v[32:47], v[138:141], v[154:157], v[32:47]
	s_waitcnt lgkmcnt(6)
	v_mfma_f32_32x32x16_bf16 v[48:63], v[138:141], v[158:161], v[48:63]
	v_mfma_f32_32x32x16_bf16 v[0:15], v[142:145], v[154:157], v[0:15]
	v_mfma_f32_32x32x16_bf16 v[16:31], v[142:145], v[158:161], v[16:31]
	global_load_dwordx4 v[138:141], v[72:73], off offset:1664
	global_load_dwordx4 v[142:145], v[76:77], off offset:1664
	s_waitcnt vmcnt(9)
	ds_write_b128 v100, v[122:125] offset:4608
	s_waitcnt vmcnt(8)
	ds_write_b128 v100, v[126:129] offset:23040
	ds_read_b128 v[122:125], v104 offset:36928
	ds_read_b128 v[126:129], v104 offset:41536
	ds_read_b128 v[154:157], v101 offset:55360
	ds_read_b128 v[158:161], v101 offset:59968
	s_waitcnt lgkmcnt(7)
	v_mfma_f32_32x32x16_bf16 v[32:47], v[114:117], v[162:165], v[32:47]
	s_waitcnt lgkmcnt(6)
	v_mfma_f32_32x32x16_bf16 v[48:63], v[114:117], v[166:169], v[48:63]
	v_mfma_f32_32x32x16_bf16 v[0:15], v[118:121], v[162:165], v[0:15]
	v_mfma_f32_32x32x16_bf16 v[16:31], v[118:121], v[166:169], v[16:31]
	global_load_dwordx4 v[114:117], v[80:81], off offset:1664
	global_load_dwordx4 v[118:121], v[84:85], off offset:1664
	s_waitcnt vmcnt(9)
	ds_write_b128 v100, v[130:133] offset:9216
	s_waitcnt vmcnt(8)
	ds_write_b128 v100, v[134:137] offset:27648
	ds_read_b128 v[130:133], v104 offset:36960
	ds_read_b128 v[134:137], v104 offset:41568
	ds_read_b128 v[162:165], v101 offset:55392
	ds_read_b128 v[166:169], v101 offset:60000
	s_waitcnt lgkmcnt(7)
	v_mfma_f32_32x32x16_bf16 v[32:47], v[122:125], v[154:157], v[32:47]
	s_waitcnt lgkmcnt(6)
	v_mfma_f32_32x32x16_bf16 v[48:63], v[122:125], v[158:161], v[48:63]
	v_mfma_f32_32x32x16_bf16 v[0:15], v[126:129], v[154:157], v[0:15]
	v_mfma_f32_32x32x16_bf16 v[16:31], v[126:129], v[158:161], v[16:31]
	global_load_dwordx4 v[122:125], v[88:89], off offset:1664
	global_load_dwordx4 v[126:129], v[92:93], off offset:1664
	s_waitcnt vmcnt(9)
	ds_write_b128 v100, v[146:149] offset:13824
	s_waitcnt vmcnt(8)
	ds_write_b128 v100, v[150:153] offset:32256
	s_waitcnt lgkmcnt(3)
	v_mfma_f32_32x32x16_bf16 v[32:47], v[130:133], v[162:165], v[32:47]
	s_waitcnt lgkmcnt(2)
	v_mfma_f32_32x32x16_bf16 v[48:63], v[130:133], v[166:169], v[48:63]
	v_mfma_f32_32x32x16_bf16 v[0:15], v[134:137], v[162:165], v[0:15]
	v_mfma_f32_32x32x16_bf16 v[16:31], v[134:137], v[166:169], v[16:31]
	s_waitcnt lgkmcnt(0)
	s_barrier
	global_load_dwordx4 v[130:133], v[64:65], off offset:1792
	global_load_dwordx4 v[134:137], v[106:107], off offset:1792
	ds_read_b128 v[146:149], v104
	ds_read_b128 v[150:153], v104 offset:4608
	ds_read_b128 v[154:157], v101 offset:18432
	ds_read_b128 v[158:161], v101 offset:23040
	s_waitcnt vmcnt(9)
	ds_write_b128 v100, v[66:69] offset:36864
	s_waitcnt vmcnt(8)
	ds_write_b128 v100, v[110:113] offset:55296
	ds_read_b128 v[66:69], v104 offset:32
	ds_read_b128 v[110:113], v104 offset:4640
	ds_read_b128 v[162:165], v101 offset:18464
	ds_read_b128 v[166:169], v101 offset:23072
	s_waitcnt lgkmcnt(7)
	v_mfma_f32_32x32x16_bf16 v[32:47], v[146:149], v[154:157], v[32:47]
	s_waitcnt lgkmcnt(6)
	v_mfma_f32_32x32x16_bf16 v[48:63], v[146:149], v[158:161], v[48:63]
	v_mfma_f32_32x32x16_bf16 v[0:15], v[150:153], v[154:157], v[0:15]
	v_mfma_f32_32x32x16_bf16 v[16:31], v[150:153], v[158:161], v[16:31]
	global_load_dwordx4 v[146:149], v[72:73], off offset:1792
	global_load_dwordx4 v[150:153], v[76:77], off offset:1792
	s_waitcnt vmcnt(9)
	ds_write_b128 v100, v[138:141] offset:41472
	s_waitcnt vmcnt(8)
	ds_write_b128 v100, v[142:145] offset:59904
	ds_read_b128 v[138:141], v104 offset:64
	ds_read_b128 v[142:145], v104 offset:4672
	ds_read_b128 v[154:157], v101 offset:18496
	ds_read_b128 v[158:161], v101 offset:23104
	s_waitcnt lgkmcnt(7)
	v_mfma_f32_32x32x16_bf16 v[32:47], v[66:69], v[162:165], v[32:47]
	s_waitcnt lgkmcnt(6)
	v_mfma_f32_32x32x16_bf16 v[48:63], v[66:69], v[166:169], v[48:63]
	v_mfma_f32_32x32x16_bf16 v[0:15], v[110:113], v[162:165], v[0:15]
	v_mfma_f32_32x32x16_bf16 v[16:31], v[110:113], v[166:169], v[16:31]
	global_load_dwordx4 v[110:113], v[80:81], off offset:1792
	global_load_dwordx4 v[162:165], v[84:85], off offset:1792
	s_waitcnt vmcnt(9)
	ds_write_b128 v100, v[114:117] offset:46080
	s_waitcnt vmcnt(8)
	ds_write_b128 v100, v[118:121] offset:64512
	ds_read_b128 v[66:69], v104 offset:96
	ds_read_b128 v[114:117], v104 offset:4704
	ds_read_b128 v[118:121], v101 offset:18528
	ds_read_b128 v[166:169], v101 offset:23136
	s_waitcnt lgkmcnt(7)
	v_mfma_f32_32x32x16_bf16 v[32:47], v[138:141], v[154:157], v[32:47]
	s_waitcnt lgkmcnt(6)
	v_mfma_f32_32x32x16_bf16 v[48:63], v[138:141], v[158:161], v[48:63]
	v_mfma_f32_32x32x16_bf16 v[0:15], v[142:145], v[154:157], v[0:15]
	v_mfma_f32_32x32x16_bf16 v[16:31], v[142:145], v[158:161], v[16:31]
	global_load_dwordx4 v[138:141], v[88:89], off offset:1792
	global_load_dwordx4 v[142:145], v[92:93], off offset:1792
	s_waitcnt vmcnt(9)
	ds_write_b128 v100, v[122:125] offset:50688
	s_waitcnt vmcnt(8)
	ds_write_b128 v105, v[126:129] offset:13824
	s_waitcnt lgkmcnt(3)
	v_mfma_f32_32x32x16_bf16 v[32:47], v[66:69], v[118:121], v[32:47]
	s_waitcnt lgkmcnt(2)
	v_mfma_f32_32x32x16_bf16 v[48:63], v[66:69], v[166:169], v[48:63]
	v_mfma_f32_32x32x16_bf16 v[0:15], v[114:117], v[118:121], v[0:15]
	v_mfma_f32_32x32x16_bf16 v[16:31], v[114:117], v[166:169], v[16:31]
	s_waitcnt lgkmcnt(0)
	s_barrier
; __device__ __forceinline__ void gemm_run(int tid, f32x16 (&acc)[2][2], GRegs& g, const GOp& o, int K, unsigned char* smem) {
;     ...
;   for (int k = 0; k < nk; k++) {
;     bf16r* cur = sbuf + (k & 1) * (256 * LDK);
;     bf16r* nxt = sbuf + ((k & 1) ^ 1) * (256 * LDK);
;     const bf16r* As = cur + (wm * 64 + fr) * LDK + fh * 8;
;     const bf16r* Bs = cur + 128 * LDK + (wn * 64 + fr) * LDK + fh * 8;
;     const bool wr = (k + 1 < nk), ld = (k + 2 < nk);
;     bf16x8 fa[2][2], fb[2][2];
;     fa[0][0] = *(const bf16x8*)(As);
;     fa[0][1] = *(const bf16x8*)(As + 32 * LDK);
;     fb[0][0] = *(const bf16x8*)(Bs);
;     fb[0][1] = *(const bf16x8*)(Bs + 32 * LDK);
; #pragma unroll
;     for (int i = 0; i < 4; i++) {
;       if (wr) {
;         *(u32x4*)(nxt + (r0 + i * 32) * LDK + sg * 8) = g.a[i];
;         *(u32x4*)(nxt + 128 * LDK + (r0 + i * 32) * LDK + sg * 8) = g.b[i];
;       }
;       if (ld) {
;         g.a[i] = *(const u32x4*)(Ap + (size_t)i * 32 * o.lda + (k + 2) * 64);
;         g.b[i] = *(const u32x4*)(Bp + o.bs.o[i] + (k + 2) * 64);
;       }
;       if (i < 3) {
;         fa[(i + 1) & 1][0] = *(const bf16x8*)(As + (i + 1) * 16);
;         fa[(i + 1) & 1][1] = *(const bf16x8*)(As + 32 * LDK + (i + 1) * 16);
;         fb[(i + 1) & 1][0] = *(const bf16x8*)(Bs + (i + 1) * 16);
;         fb[(i + 1) & 1][1] = *(const bf16x8*)(Bs + 32 * LDK + (i + 1) * 16);
;       }
;       __builtin_amdgcn_sched_barrier(0);
;       __builtin_amdgcn_s_setprio(1);
;       acc[0][0] = __builtin_amdgcn_mfma_f32_32x32x16_bf16(fa[i & 1][0], fb[i & 1][0], acc[0][0], 0, 0, 0);
;       acc[0][1] = __builtin_amdgcn_mfma_f32_32x32x16_bf16(fa[i & 1][0], fb[i & 1][1], acc[0][1], 0, 0, 0);
;       acc[1][0] = __builtin_amdgcn_mfma_f32_32x32x16_bf16(fa[i & 1][1], fb[i & 1][0], acc[1][0], 0, 0, 0);
;       acc[1][1] = __builtin_amdgcn_mfma_f32_32x32x16_bf16(fa[i & 1][1], fb[i & 1][1], acc[1][1], 0, 0, 0);
;       __builtin_amdgcn_s_setprio(0);
;     }
;     __syncthreads();
	global_load_dwordx4 v[64:67], v[64:65], off offset:1920
	s_nop 0
	global_load_dwordx4 v[68:71], v[106:107], off offset:1920
	ds_read_b128 v[114:117], v104 offset:36864
	ds_read_b128 v[118:121], v104 offset:41472
	ds_read_b128 v[122:125], v101 offset:55296
	ds_read_b128 v[126:129], v101 offset:59904
	s_waitcnt vmcnt(9)
	ds_write_b128 v100, v[130:133]
	s_waitcnt vmcnt(8)
	ds_write_b128 v100, v[134:137] offset:18432
	ds_read_b128 v[130:133], v104 offset:36896
	ds_read_b128 v[134:137], v104 offset:41504
	ds_read_b128 v[154:157], v101 offset:55328
	ds_read_b128 v[158:161], v101 offset:59936
	s_waitcnt lgkmcnt(7)
	v_mfma_f32_32x32x16_bf16 v[32:47], v[114:117], v[122:125], v[32:47]
	s_waitcnt lgkmcnt(6)
	v_mfma_f32_32x32x16_bf16 v[48:63], v[114:117], v[126:129], v[48:63]
	v_mfma_f32_32x32x16_bf16 v[0:15], v[118:121], v[122:125], v[0:15]
	v_mfma_f32_32x32x16_bf16 v[16:31], v[118:121], v[126:129], v[16:31]
	global_load_dwordx4 v[72:75], v[72:73], off offset:1920
	s_nop 0
	global_load_dwordx4 v[76:79], v[76:77], off offset:1920
	s_waitcnt vmcnt(9)
	ds_write_b128 v100, v[146:149] offset:4608
	s_waitcnt vmcnt(8)
	ds_write_b128 v100, v[150:153] offset:23040
	ds_read_b128 v[114:117], v104 offset:36928
	ds_read_b128 v[118:121], v104 offset:41536
	ds_read_b128 v[122:125], v101 offset:55360
	ds_read_b128 v[126:129], v101 offset:59968
	s_waitcnt lgkmcnt(7)
	v_mfma_f32_32x32x16_bf16 v[32:47], v[130:133], v[154:157], v[32:47]
	s_waitcnt lgkmcnt(6)
	v_mfma_f32_32x32x16_bf16 v[48:63], v[130:133], v[158:161], v[48:63]
	v_mfma_f32_32x32x16_bf16 v[0:15], v[134:137], v[154:157], v[0:15]
	v_mfma_f32_32x32x16_bf16 v[16:31], v[134:137], v[158:161], v[16:31]
	global_load_dwordx4 v[80:83], v[80:81], off offset:1920
	s_nop 0
	global_load_dwordx4 v[84:87], v[84:85], off offset:1920
	s_waitcnt vmcnt(9)
	ds_write_b128 v100, v[110:113] offset:9216
	s_waitcnt vmcnt(8)
	ds_write_b128 v100, v[162:165] offset:27648
	ds_read_b128 v[110:113], v104 offset:36960
	ds_read_b128 v[130:133], v104 offset:41568
	ds_read_b128 v[134:137], v101 offset:55392
	ds_read_b128 v[146:149], v101 offset:60000
	s_waitcnt lgkmcnt(7)
	v_mfma_f32_32x32x16_bf16 v[32:47], v[114:117], v[122:125], v[32:47]
	s_waitcnt lgkmcnt(6)
	v_mfma_f32_32x32x16_bf16 v[48:63], v[114:117], v[126:129], v[48:63]
	v_mfma_f32_32x32x16_bf16 v[0:15], v[118:121], v[122:125], v[0:15]
	v_mfma_f32_32x32x16_bf16 v[16:31], v[118:121], v[126:129], v[16:31]
	global_load_dwordx4 v[88:91], v[88:89], off offset:1920
	s_nop 0
	global_load_dwordx4 v[92:95], v[92:93], off offset:1920
	s_waitcnt vmcnt(9)
	ds_write_b128 v100, v[138:141] offset:13824
	s_waitcnt vmcnt(8)
	ds_write_b128 v100, v[142:145] offset:32256
	s_waitcnt lgkmcnt(3)
	v_mfma_f32_32x32x16_bf16 v[32:47], v[110:113], v[134:137], v[32:47]
	s_waitcnt lgkmcnt(2)
	v_mfma_f32_32x32x16_bf16 v[48:63], v[110:113], v[146:149], v[48:63]
	v_mfma_f32_32x32x16_bf16 v[0:15], v[130:133], v[134:137], v[0:15]
	v_mfma_f32_32x32x16_bf16 v[16:31], v[130:133], v[146:149], v[16:31]
	s_waitcnt lgkmcnt(0)
	s_barrier
; __device__ __forceinline__ void gemm_run(int tid, f32x16 (&acc)[2][2], GRegs& g, const GOp& o, int K, unsigned char* smem) {
;     ...
;   for (int k = 0; k < nk; k++) {
;     bf16r* cur = sbuf + (k & 1) * (256 * LDK);
;     bf16r* nxt = sbuf + ((k & 1) ^ 1) * (256 * LDK);
;     const bf16r* As = cur + (wm * 64 + fr) * LDK + fh * 8;
;     const bf16r* Bs = cur + 128 * LDK + (wn * 64 + fr) * LDK + fh * 8;
;     const bool wr = (k + 1 < nk), ld = (k + 2 < nk);
;     bf16x8 fa[2][2], fb[2][2];
;     fa[0][0] = *(const bf16x8*)(As);
;     fa[0][1] = *(const bf16x8*)(As + 32 * LDK);
;     fb[0][0] = *(const bf16x8*)(Bs);
;     fb[0][1] = *(const bf16x8*)(Bs + 32 * LDK);
; #pragma unroll
;     for (int i = 0; i < 4; i++) {
;       if (wr) {
;         *(u32x4*)(nxt + (r0 + i * 32) * LDK + sg * 8) = g.a[i];
;         *(u32x4*)(nxt + 128 * LDK + (r0 + i * 32) * LDK + sg * 8) = g.b[i];
;       }
;       if (ld) {
;         g.a[i] = *(const u32x4*)(Ap + (size_t)i * 32 * o.lda + (k + 2) * 64);
;         g.b[i] = *(const u32x4*)(Bp + o.bs.o[i] + (k + 2) * 64);
;       }
;       if (i < 3) {
;         fa[(i + 1) & 1][0] = *(const bf16x8*)(As + (i + 1) * 16);
;         fa[(i + 1) & 1][1] = *(const bf16x8*)(As + 32 * LDK + (i + 1) * 16);
;         fb[(i + 1) & 1][0] = *(const bf16x8*)(Bs + (i + 1) * 16);
;         fb[(i + 1) & 1][1] = *(const bf16x8*)(Bs + 32 * LDK + (i + 1) * 16);
;       }
;       __builtin_amdgcn_sched_barrier(0);
;       __builtin_amdgcn_s_setprio(1);
;       acc[0][0] = __builtin_amdgcn_mfma_f32_32x32x16_bf16(fa[i & 1][0], fb[i & 1][0], acc[0][0], 0, 0, 0);
;       acc[0][1] = __builtin_amdgcn_mfma_f32_32x32x16_bf16(fa[i & 1][0], fb[i & 1][1], acc[0][1], 0, 0, 0);
;       acc[1][0] = __builtin_amdgcn_mfma_f32_32x32x16_bf16(fa[i & 1][1], fb[i & 1][0], acc[1][0], 0, 0, 0);
;       acc[1][1] = __builtin_amdgcn_mfma_f32_32x32x16_bf16(fa[i & 1][1], fb[i & 1][1], acc[1][1], 0, 0, 0);
;       __builtin_amdgcn_s_setprio(0);
;     }
;     __syncthreads();
;   }
; __device__ __forceinline__ bool tile_map(int it, int nn, int& mt, int& nt) {
;   const int xcd = blockIdx.x & 7, li = blockIdx.x >> 3, nb = gridDim.x >> 3;
;   int q = it * nb + li;
;   const int per = 16 * nn;
;   if (q < per) {
;     int sub = q / (8 * nn), r = q - sub * (8 * nn);
;     nt = r >> 3;
;     mt = xcd * 16 + sub * 8 + (r & 7);
;     return true;
;   }
;   q -= per;
;   int n = q * 8 + xcd;
	ds_read_b128 v[110:113], v104
	ds_read_b128 v[114:117], v104 offset:4608
	ds_read_b128 v[118:121], v101 offset:18432
	ds_read_b128 v[122:125], v101 offset:23040
	s_waitcnt vmcnt(7)
	ds_write_b128 v100, v[64:67] offset:36864
	s_waitcnt vmcnt(6)
	ds_write_b128 v100, v[68:71] offset:55296
	ds_read_b128 v[126:129], v104 offset:32
	ds_read_b128 v[130:133], v104 offset:4640
	ds_read_b128 v[134:137], v101 offset:18464
	ds_read_b128 v[138:141], v101 offset:23072
	s_waitcnt lgkmcnt(7)
	v_mfma_f32_32x32x16_bf16 v[32:47], v[110:113], v[118:121], v[32:47]
	s_waitcnt lgkmcnt(6)
	v_mfma_f32_32x32x16_bf16 v[48:63], v[110:113], v[122:125], v[48:63]
	v_mfma_f32_32x32x16_bf16 v[0:15], v[114:117], v[118:121], v[0:15]
	v_mfma_f32_32x32x16_bf16 v[16:31], v[114:117], v[122:125], v[16:31]
	s_waitcnt vmcnt(5)
	ds_write_b128 v100, v[72:75] offset:41472
	s_waitcnt vmcnt(4)
	ds_write_b128 v100, v[76:79] offset:59904
	ds_read_b128 v[110:113], v104 offset:64
	ds_read_b128 v[114:117], v104 offset:4672
	ds_read_b128 v[118:121], v101 offset:18496
	ds_read_b128 v[122:125], v101 offset:23104
	s_waitcnt lgkmcnt(7)
	v_mfma_f32_32x32x16_bf16 v[32:47], v[126:129], v[134:137], v[32:47]
	s_waitcnt lgkmcnt(6)
	v_mfma_f32_32x32x16_bf16 v[48:63], v[126:129], v[138:141], v[48:63]
	v_mfma_f32_32x32x16_bf16 v[0:15], v[130:133], v[134:137], v[0:15]
	v_mfma_f32_32x32x16_bf16 v[16:31], v[130:133], v[138:141], v[16:31]
	s_waitcnt vmcnt(3)
	ds_write_b128 v100, v[80:83] offset:46080
	s_waitcnt vmcnt(2)
	ds_write_b128 v100, v[84:87] offset:64512
	ds_read_b128 v[126:129], v104 offset:96
	ds_read_b128 v[130:133], v104 offset:4704
	ds_read_b128 v[134:137], v101 offset:18528
	ds_read_b128 v[138:141], v101 offset:23136
	s_waitcnt lgkmcnt(7)
	v_mfma_f32_32x32x16_bf16 v[32:47], v[110:113], v[118:121], v[32:47]
	s_waitcnt lgkmcnt(6)
	v_mfma_f32_32x32x16_bf16 v[48:63], v[110:113], v[122:125], v[48:63]
	v_mfma_f32_32x32x16_bf16 v[0:15], v[114:117], v[118:121], v[0:15]
	v_mfma_f32_32x32x16_bf16 v[16:31], v[114:117], v[122:125], v[16:31]
	s_waitcnt vmcnt(1)
	ds_write_b128 v100, v[88:91] offset:50688
	s_waitcnt vmcnt(0)
	ds_write_b128 v105, v[92:95] offset:13824
	s_waitcnt lgkmcnt(3)
	v_mfma_f32_32x32x16_bf16 v[32:47], v[126:129], v[134:137], v[32:47]
	s_waitcnt lgkmcnt(2)
	v_mfma_f32_32x32x16_bf16 v[48:63], v[126:129], v[138:141], v[48:63]
	v_mfma_f32_32x32x16_bf16 v[0:15], v[130:133], v[134:137], v[0:15]
	v_mfma_f32_32x32x16_bf16 v[16:31], v[130:133], v[138:141], v[16:31]
	s_waitcnt lgkmcnt(0)
	s_barrier
	ds_read_b128 v[110:113], v104 offset:36864
	ds_read_b128 v[114:117], v104 offset:36896
	ds_read_b128 v[118:121], v104 offset:41472
	ds_read_b128 v[122:125], v104 offset:41504
	ds_read_b128 v[126:129], v101 offset:55296
	ds_read_b128 v[130:133], v101 offset:55328
	ds_read_b128 v[134:137], v101 offset:59904
	ds_read_b128 v[138:141], v101 offset:59936
	s_waitcnt lgkmcnt(3)
	v_mfma_f32_32x32x16_bf16 v[32:47], v[110:113], v[126:129], v[32:47]
	s_waitcnt lgkmcnt(1)
	v_mfma_f32_32x32x16_bf16 v[48:63], v[110:113], v[134:137], v[48:63]
	v_mfma_f32_32x32x16_bf16 v[0:15], v[118:121], v[126:129], v[0:15]
	v_mfma_f32_32x32x16_bf16 v[16:31], v[118:121], v[134:137], v[16:31]
	ds_read_b128 v[110:113], v104 offset:36928
	ds_read_b128 v[118:121], v104 offset:41536
	ds_read_b128 v[126:129], v101 offset:55360
	ds_read_b128 v[134:137], v101 offset:59968
	v_mfma_f32_32x32x16_bf16 v[32:47], v[114:117], v[130:133], v[32:47]
	s_waitcnt lgkmcnt(4)
	v_mfma_f32_32x32x16_bf16 v[48:63], v[114:117], v[138:141], v[48:63]
	v_mfma_f32_32x32x16_bf16 v[0:15], v[122:125], v[130:133], v[0:15]
	v_mfma_f32_32x32x16_bf16 v[16:31], v[122:125], v[138:141], v[16:31]
	ds_read_b128 v[114:117], v104 offset:36960
	ds_read_b128 v[122:125], v104 offset:41568
	ds_read_b128 v[130:133], v101 offset:55392
	ds_read_b128 v[138:141], v101 offset:60000
	s_waitcnt lgkmcnt(5)
	v_mfma_f32_32x32x16_bf16 v[32:47], v[110:113], v[126:129], v[32:47]
	s_waitcnt lgkmcnt(4)
	v_mfma_f32_32x32x16_bf16 v[48:63], v[110:113], v[134:137], v[48:63]
	v_mfma_f32_32x32x16_bf16 v[0:15], v[118:121], v[126:129], v[0:15]
	v_mfma_f32_32x32x16_bf16 v[16:31], v[118:121], v[134:137], v[16:31]
	s_waitcnt lgkmcnt(1)
	v_mfma_f32_32x32x16_bf16 v[32:47], v[114:117], v[130:133], v[32:47]
	s_waitcnt lgkmcnt(0)
	v_mfma_f32_32x32x16_bf16 v[48:63], v[114:117], v[138:141], v[48:63]
	v_mfma_f32_32x32x16_bf16 v[0:15], v[122:125], v[130:133], v[0:15]
	v_mfma_f32_32x32x16_bf16 v[16:31], v[122:125], v[138:141], v[16:31]
	s_cmpk_gt_u32 s23, 0x2bf
	s_mov_b64 s[12:13], -1
	s_barrier
	s_cbranch_scc0 .LBB0_2449
	s_mov_b64 s[12:13], 0
	s_cmp_gt_i32 s24, 43
	s_mov_b64 s[10:11], 0
	s_cbranch_scc1 .LBB0_2449
	s_movk_i32 s0, 0x80
	s_mov_b64 s[10:11], -1
	s_mov_b32 s4, s24

; __device__ __forceinline__ void gemm_run(int tid, f32x16 (&acc)[2][2], GRegs& g, const GOp& o, int K, unsigned char* smem) {
;     ...
;   for (int k = 0; k < nk; k++) {
;     bf16r* cur = sbuf + (k & 1) * (256 * LDK);
;     bf16r* nxt = sbuf + ((k & 1) ^ 1) * (256 * LDK);
;     const bf16r* As = cur + (wm * 64 + fr) * LDK + fh * 8;
;     const bf16r* Bs = cur + 128 * LDK + (wn * 64 + fr) * LDK + fh * 8;
;     const bool wr = (k + 1 < nk), ld = (k + 2 < nk);
;     bf16x8 fa[2][2], fb[2][2];
;     fa[0][0] = *(const bf16x8*)(As);
;     fa[0][1] = *(const bf16x8*)(As + 32 * LDK);
;     fb[0][0] = *(const bf16x8*)(Bs);
;     fb[0][1] = *(const bf16x8*)(Bs + 32 * LDK);
; #pragma unroll
;     for (int i = 0; i < 4; i++) {
;       if (wr) {
;         *(u32x4*)(nxt + (r0 + i * 32) * LDK + sg * 8) = g.a[i];
;         *(u32x4*)(nxt + 128 * LDK + (r0 + i * 32) * LDK + sg * 8) = g.b[i];
;       }
;       if (ld) {
;         g.a[i] = *(const u32x4*)(Ap + (size_t)i * 32 * o.lda + (k + 2) * 64);
;         g.b[i] = *(const u32x4*)(Bp + o.bs.o[i] + (k + 2) * 64);
;       }
;       if (i < 3) {
;         fa[(i + 1) & 1][0] = *(const bf16x8*)(As + (i + 1) * 16);
;         fa[(i + 1) & 1][1] = *(const bf16x8*)(As + 32 * LDK + (i + 1) * 16);
;         fb[(i + 1) & 1][0] = *(const bf16x8*)(Bs + (i + 1) * 16);
;         fb[(i + 1) & 1][1] = *(const bf16x8*)(Bs + 32 * LDK + (i + 1) * 16);
;       }
;       __builtin_amdgcn_sched_barrier(0);
;       __builtin_amdgcn_s_setprio(1);
;       acc[0][0] = __builtin_amdgcn_mfma_f32_32x32x16_bf16(fa[i & 1][0], fb[i & 1][0], acc[0][0], 0, 0, 0);
;       acc[0][1] = __builtin_amdgcn_mfma_f32_32x32x16_bf16(fa[i & 1][0], fb[i & 1][1], acc[0][1], 0, 0, 0);
;       acc[1][0] = __builtin_amdgcn_mfma_f32_32x32x16_bf16(fa[i & 1][1], fb[i & 1][0], acc[1][0], 0, 0, 0);
;       acc[1][1] = __builtin_amdgcn_mfma_f32_32x32x16_bf16(fa[i & 1][1], fb[i & 1][1], acc[1][1], 0, 0, 0);
;       __builtin_amdgcn_s_setprio(0);
;     }
;     __syncthreads();
;   }
.LBB0_2503:
	s_and_b32 s7, s6, 1
	v_lshl_add_u64 v[150:151], v[108:109], 0, s[4:5]
	s_mul_i32 s27, s7, 0x9000
	s_xor_b32 s7, s7, 1
	v_add_co_u32_e32 v134, vcc, s17, v150
	s_mul_i32 s7, s7, 0x9000
	v_lshl_add_u64 v[152:153], v[106:107], 0, s[4:5]
	v_addc_co_u32_e32 v135, vcc, 0, v151, vcc
	v_add3_u32 v96, s27, v101, v112
	v_add_u32_e32 v154, s7, v100
	v_add_co_u32_e32 v136, vcc, s18, v152
	v_add3_u32 v117, s27, v111, v112
	ds_read_b128 v[118:121], v96
	ds_read_b128 v[122:125], v96 offset:4608
	ds_read_b128 v[126:129], v117 offset:18432
	ds_read_b128 v[130:133], v117 offset:23040
	s_waitcnt vmcnt(7)
	ds_write_b128 v154, v[64:67]
	s_waitcnt vmcnt(6)
	ds_write_b128 v154, v[68:71] offset:18432
	v_addc_co_u32_e32 v137, vcc, 0, v153, vcc
	global_load_dwordx4 v[64:67], v[134:135], off offset:256
	global_load_dwordx4 v[68:71], v[136:137], off offset:256
	ds_read_b128 v[134:137], v96 offset:32
	ds_read_b128 v[138:141], v96 offset:4640
	ds_read_b128 v[142:145], v117 offset:18464
	ds_read_b128 v[146:149], v117 offset:23072
	s_add_i32 s6, s6, 1
	s_waitcnt lgkmcnt(7)
	v_mfma_f32_32x32x16_bf16 v[48:63], v[118:121], v[126:129], v[48:63]
	s_waitcnt lgkmcnt(6)
	v_mfma_f32_32x32x16_bf16 v[32:47], v[118:121], v[130:133], v[32:47]
	v_mfma_f32_32x32x16_bf16 v[16:31], v[122:125], v[126:129], v[16:31]
	v_mfma_f32_32x32x16_bf16 v[0:15], v[122:125], v[130:133], v[0:15]
	s_waitcnt vmcnt(7)
	ds_write_b128 v154, v[72:75] offset:4608
	s_waitcnt vmcnt(6)
	ds_write_b128 v154, v[76:79] offset:23040
	v_add_co_u32_e32 v72, vcc, s19, v150
	s_nop 1
	v_addc_co_u32_e32 v73, vcc, 0, v151, vcc
	v_add_co_u32_e32 v76, vcc, s20, v152
	s_nop 1
	v_addc_co_u32_e32 v77, vcc, 0, v153, vcc
	global_load_dwordx4 v[72:75], v[72:73], off offset:256
	s_nop 0
	global_load_dwordx4 v[76:79], v[76:77], off offset:256
	ds_read_b128 v[118:121], v96 offset:64
	ds_read_b128 v[122:125], v96 offset:4672
	ds_read_b128 v[126:129], v117 offset:18496
	ds_read_b128 v[130:133], v117 offset:23104
	s_waitcnt lgkmcnt(7)
	v_mfma_f32_32x32x16_bf16 v[48:63], v[134:137], v[142:145], v[48:63]
	s_waitcnt lgkmcnt(6)
	v_mfma_f32_32x32x16_bf16 v[32:47], v[134:137], v[146:149], v[32:47]
	v_mfma_f32_32x32x16_bf16 v[16:31], v[138:141], v[142:145], v[16:31]
	v_mfma_f32_32x32x16_bf16 v[0:15], v[138:141], v[146:149], v[0:15]
	s_waitcnt vmcnt(7)
	ds_write_b128 v154, v[80:83] offset:9216
	s_waitcnt vmcnt(6)
	ds_write_b128 v154, v[84:87] offset:27648
	v_add_co_u32_e32 v80, vcc, s21, v150
	s_nop 1
	v_addc_co_u32_e32 v81, vcc, 0, v151, vcc
	v_add_co_u32_e32 v84, vcc, s22, v152
	s_nop 1
	v_addc_co_u32_e32 v85, vcc, 0, v153, vcc
	global_load_dwordx4 v[80:83], v[80:81], off offset:256
	s_nop 0
	global_load_dwordx4 v[84:87], v[84:85], off offset:256
	ds_read_b128 v[134:137], v96 offset:96
	ds_read_b128 v[138:141], v96 offset:4704
	ds_read_b128 v[142:145], v117 offset:18528
	ds_read_b128 v[146:149], v117 offset:23136
	s_waitcnt lgkmcnt(7)
	v_mfma_f32_32x32x16_bf16 v[48:63], v[118:121], v[126:129], v[48:63]
	s_waitcnt lgkmcnt(6)
	v_mfma_f32_32x32x16_bf16 v[32:47], v[118:121], v[130:133], v[32:47]
	v_mfma_f32_32x32x16_bf16 v[16:31], v[122:125], v[126:129], v[16:31]
	v_mfma_f32_32x32x16_bf16 v[0:15], v[122:125], v[130:133], v[0:15]
	s_waitcnt vmcnt(7)
	ds_write_b128 v154, v[88:91] offset:13824
	s_waitcnt vmcnt(6)
	ds_write_b128 v154, v[92:95] offset:32256
	v_add_co_u32_e32 v88, vcc, s23, v150
	s_nop 1
	v_addc_co_u32_e32 v89, vcc, 0, v151, vcc
	v_add_co_u32_e32 v92, vcc, s24, v152
	s_nop 1
	v_addc_co_u32_e32 v93, vcc, 0, v153, vcc
	global_load_dwordx4 v[88:91], v[88:89], off offset:256
	s_nop 0
	global_load_dwordx4 v[92:95], v[92:93], off offset:256
	s_waitcnt lgkmcnt(3)
	v_mfma_f32_32x32x16_bf16 v[48:63], v[134:137], v[142:145], v[48:63]
	s_waitcnt lgkmcnt(2)
	v_mfma_f32_32x32x16_bf16 v[32:47], v[134:137], v[146:149], v[32:47]
	v_mfma_f32_32x32x16_bf16 v[16:31], v[138:141], v[142:145], v[16:31]
	v_mfma_f32_32x32x16_bf16 v[0:15], v[138:141], v[146:149], v[0:15]
	s_add_u32 s4, s4, 0x80
	s_addc_u32 s5, s5, 0
	s_cmpk_eq_i32 s4, 0x1500
	s_waitcnt lgkmcnt(0)
	s_barrier
	s_cbranch_scc0 .LBB0_2503
; __device__ __forceinline__ void gemm_run(int tid, f32x16 (&acc)[2][2], GRegs& g, const GOp& o, int K, unsigned char* smem) {
;     ...
;   for (int k = 0; k < nk; k++) {
;     bf16r* cur = sbuf + (k & 1) * (256 * LDK);
;     bf16r* nxt = sbuf + ((k & 1) ^ 1) * (256 * LDK);
;     const bf16r* As = cur + (wm * 64 + fr) * LDK + fh * 8;
;     const bf16r* Bs = cur + 128 * LDK + (wn * 64 + fr) * LDK + fh * 8;
;     const bool wr = (k + 1 < nk), ld = (k + 2 < nk);
;     bf16x8 fa[2][2], fb[2][2];
;     fa[0][0] = *(const bf16x8*)(As);
;     fa[0][1] = *(const bf16x8*)(As + 32 * LDK);
;     fb[0][0] = *(const bf16x8*)(Bs);
;     fb[0][1] = *(const bf16x8*)(Bs + 32 * LDK);
; #pragma unroll
;     for (int i = 0; i < 4; i++) {
;       if (wr) {
;         *(u32x4*)(nxt + (r0 + i * 32) * LDK + sg * 8) = g.a[i];
;         *(u32x4*)(nxt + 128 * LDK + (r0 + i * 32) * LDK + sg * 8) = g.b[i];
;       }
;       if (ld) {
;         g.a[i] = *(const u32x4*)(Ap + (size_t)i * 32 * o.lda + (k + 2) * 64);
;         g.b[i] = *(const u32x4*)(Bp + o.bs.o[i] + (k + 2) * 64);
;       }
;       if (i < 3) {
;         fa[(i + 1) & 1][0] = *(const bf16x8*)(As + (i + 1) * 16);
;         fa[(i + 1) & 1][1] = *(const bf16x8*)(As + 32 * LDK + (i + 1) * 16);
;         fb[(i + 1) & 1][0] = *(const bf16x8*)(Bs + (i + 1) * 16);
;         fb[(i + 1) & 1][1] = *(const bf16x8*)(Bs + 32 * LDK + (i + 1) * 16);
;       }
;       __builtin_amdgcn_sched_barrier(0);
;       __builtin_amdgcn_s_setprio(1);
;       acc[0][0] = __builtin_amdgcn_mfma_f32_32x32x16_bf16(fa[i & 1][0], fb[i & 1][0], acc[0][0], 0, 0, 0);
;       acc[0][1] = __builtin_amdgcn_mfma_f32_32x32x16_bf16(fa[i & 1][0], fb[i & 1][1], acc[0][1], 0, 0, 0);
;       acc[1][0] = __builtin_amdgcn_mfma_f32_32x32x16_bf16(fa[i & 1][1], fb[i & 1][0], acc[1][0], 0, 0, 0);
;       acc[1][1] = __builtin_amdgcn_mfma_f32_32x32x16_bf16(fa[i & 1][1], fb[i & 1][1], acc[1][1], 0, 0, 0);
;       __builtin_amdgcn_s_setprio(0);
;     }
;     __syncthreads();
;   }
; __device__ __forceinline__ bool tile_map(int it, int nn, int& mt, int& nt) {
;   const int xcd = blockIdx.x & 7, li = blockIdx.x >> 3, nb = gridDim.x >> 3;
;   int q = it * nb + li;
;   const int per = 16 * nn;
;   if (q < per) {
;     int sub = q / (8 * nn), r = q - sub * (8 * nn);
;     nt = r >> 3;
;     mt = xcd * 16 + sub * 8 + (r & 7);
;     return true;
;   }
;   q -= per;
;   int n = q * 8 + xcd;
	ds_read_b128 v[106:109], v113
	ds_read_b128 v[118:121], v113 offset:4608
	ds_read_b128 v[122:125], v114 offset:18432
	ds_read_b128 v[126:129], v114 offset:23040
	s_waitcnt vmcnt(7)
	ds_write_b128 v100, v[64:67] offset:36864
	s_waitcnt vmcnt(6)
	ds_write_b128 v100, v[68:71] offset:55296
	ds_read_b128 v[130:133], v113 offset:32
	ds_read_b128 v[134:137], v113 offset:4640
	ds_read_b128 v[138:141], v114 offset:18464
	ds_read_b128 v[142:145], v114 offset:23072
	s_waitcnt lgkmcnt(7)
	v_mfma_f32_32x32x16_bf16 v[48:63], v[106:109], v[122:125], v[48:63]
	s_waitcnt lgkmcnt(6)
	v_mfma_f32_32x32x16_bf16 v[32:47], v[106:109], v[126:129], v[32:47]
	v_mfma_f32_32x32x16_bf16 v[16:31], v[118:121], v[122:125], v[16:31]
	v_mfma_f32_32x32x16_bf16 v[0:15], v[118:121], v[126:129], v[0:15]
	s_waitcnt vmcnt(5)
	ds_write_b128 v100, v[72:75] offset:41472
	s_waitcnt vmcnt(4)
	ds_write_b128 v100, v[76:79] offset:59904
	ds_read_b128 v[106:109], v113 offset:64
	ds_read_b128 v[118:121], v113 offset:4672
	ds_read_b128 v[122:125], v114 offset:18496
	ds_read_b128 v[126:129], v114 offset:23104
	s_waitcnt lgkmcnt(7)
	v_mfma_f32_32x32x16_bf16 v[48:63], v[130:133], v[138:141], v[48:63]
	s_waitcnt lgkmcnt(6)
	v_mfma_f32_32x32x16_bf16 v[32:47], v[130:133], v[142:145], v[32:47]
	v_mfma_f32_32x32x16_bf16 v[16:31], v[134:137], v[138:141], v[16:31]
	v_mfma_f32_32x32x16_bf16 v[0:15], v[134:137], v[142:145], v[0:15]
	s_waitcnt vmcnt(3)
	ds_write_b128 v100, v[80:83] offset:46080
	s_waitcnt vmcnt(2)
	ds_write_b128 v100, v[84:87] offset:64512
	ds_read_b128 v[130:133], v113 offset:96
	ds_read_b128 v[134:137], v113 offset:4704
	ds_read_b128 v[138:141], v114 offset:18528
	ds_read_b128 v[142:145], v114 offset:23136
	s_waitcnt lgkmcnt(7)
	v_mfma_f32_32x32x16_bf16 v[48:63], v[106:109], v[122:125], v[48:63]
	s_waitcnt lgkmcnt(6)
	v_mfma_f32_32x32x16_bf16 v[32:47], v[106:109], v[126:129], v[32:47]
	v_mfma_f32_32x32x16_bf16 v[16:31], v[118:121], v[122:125], v[16:31]
	v_mfma_f32_32x32x16_bf16 v[0:15], v[118:121], v[126:129], v[0:15]
	s_waitcnt vmcnt(1)
	ds_write_b128 v100, v[88:91] offset:50688
	s_waitcnt vmcnt(0)
	ds_write_b128 v115, v[92:95] offset:13824
	s_waitcnt lgkmcnt(3)
	v_mfma_f32_32x32x16_bf16 v[48:63], v[130:133], v[138:141], v[48:63]
	s_waitcnt lgkmcnt(2)
	v_mfma_f32_32x32x16_bf16 v[32:47], v[130:133], v[142:145], v[32:47]
	v_mfma_f32_32x32x16_bf16 v[16:31], v[134:137], v[138:141], v[16:31]
	v_mfma_f32_32x32x16_bf16 v[0:15], v[134:137], v[142:145], v[0:15]
	s_waitcnt lgkmcnt(0)
	s_barrier
	ds_read_b128 v[106:109], v113 offset:36864
	ds_read_b128 v[118:121], v113 offset:36896
	ds_read_b128 v[122:125], v113 offset:41472
	ds_read_b128 v[126:129], v113 offset:41504
	ds_read_b128 v[130:133], v114 offset:55296
	ds_read_b128 v[134:137], v114 offset:55328
	ds_read_b128 v[138:141], v114 offset:59904
	ds_read_b128 v[142:145], v114 offset:59936
	s_waitcnt lgkmcnt(3)
	v_mfma_f32_32x32x16_bf16 v[48:63], v[106:109], v[130:133], v[48:63]
	s_waitcnt lgkmcnt(1)
	v_mfma_f32_32x32x16_bf16 v[32:47], v[106:109], v[138:141], v[32:47]
	v_mfma_f32_32x32x16_bf16 v[16:31], v[122:125], v[130:133], v[16:31]
	v_mfma_f32_32x32x16_bf16 v[0:15], v[122:125], v[138:141], v[0:15]
	ds_read_b128 v[106:109], v113 offset:36928
	ds_read_b128 v[122:125], v113 offset:41536
	ds_read_b128 v[130:133], v114 offset:55360
	ds_read_b128 v[138:141], v114 offset:59968
	v_mfma_f32_32x32x16_bf16 v[48:63], v[118:121], v[134:137], v[48:63]
	s_waitcnt lgkmcnt(4)
	v_mfma_f32_32x32x16_bf16 v[32:47], v[118:121], v[142:145], v[32:47]
	v_mfma_f32_32x32x16_bf16 v[16:31], v[126:129], v[134:137], v[16:31]
	v_mfma_f32_32x32x16_bf16 v[0:15], v[126:129], v[142:145], v[0:15]
	ds_read_b128 v[118:121], v113 offset:36960
	ds_read_b128 v[126:129], v113 offset:41568
	ds_read_b128 v[134:137], v114 offset:55392
	ds_read_b128 v[142:145], v114 offset:60000
	s_waitcnt lgkmcnt(5)
	v_mfma_f32_32x32x16_bf16 v[48:63], v[106:109], v[130:133], v[48:63]
	s_waitcnt lgkmcnt(4)
	v_mfma_f32_32x32x16_bf16 v[32:47], v[106:109], v[138:141], v[32:47]
	v_mfma_f32_32x32x16_bf16 v[16:31], v[122:125], v[130:133], v[16:31]
	v_mfma_f32_32x32x16_bf16 v[0:15], v[122:125], v[138:141], v[0:15]
	s_waitcnt lgkmcnt(1)
	v_mfma_f32_32x32x16_bf16 v[48:63], v[118:121], v[134:137], v[48:63]
	s_waitcnt lgkmcnt(0)
	v_mfma_f32_32x32x16_bf16 v[32:47], v[118:121], v[142:145], v[32:47]
	v_mfma_f32_32x32x16_bf16 v[16:31], v[126:129], v[134:137], v[16:31]
	v_mfma_f32_32x32x16_bf16 v[0:15], v[126:129], v[142:145], v[0:15]
	s_add_i32 s14, s14, 1
	s_mul_i32 s27, s14, s16
	s_add_i32 s27, s27, s3
	s_cmpk_gt_u32 s27, 0x7f
	s_mov_b64 s[6:7], -1
	s_barrier
	s_cbranch_scc0 .LBB0_2507
	s_lshl_b32 s28, s27, 3
	s_add_i32 s28, s28, s15
	s_mov_b64 s[6:7], 0
	s_cmp_gt_i32 s28, 7
	s_mov_b64 s[4:5], 0
	s_cbranch_scc1 .LBB0_2507
	s_movk_i32 s8, 0x80
	s_mov_b64 s[4:5], -1
	s_mov_b32 s9, s28

; __device__ __forceinline__ void gemm_run(int tid, f32x16 (&acc)[2][2], GRegs& g, const GOp& o, int K, unsigned char* smem) {
;     ...
;   for (int i = 0; i < 4; i++) {
;     *(u32x4*)(sbuf + (r0 + i * 32) * LDK + sg * 8) = g.a[i];
;     *(u32x4*)(sbuf + 128 * LDK + (r0 + i * 32) * LDK + sg * 8) = g.b[i];
;   }
;   if (nk > 1) {
; #pragma unroll
;     for (int i = 0; i < 4; i++) {
;       g.a[i] = *(const u32x4*)(Ap + (size_t)i * 32 * o.lda + 64);
;       g.b[i] = *(const u32x4*)(Bp + o.bs.o[i] + 64);
;     }
;   }
;   __syncthreads();
;   const int lane = tid & 63, fr = lane & 31, fh = lane >> 5;
;   for (int k = 0; k < nk; k++) {
;     bf16r* cur = sbuf + (k & 1) * (256 * LDK);
;     bf16r* nxt = sbuf + ((k & 1) ^ 1) * (256 * LDK);
;     const bf16r* As = cur + (wm * 64 + fr) * LDK + fh * 8;
;     const bf16r* Bs = cur + 128 * LDK + (wn * 64 + fr) * LDK + fh * 8;
;     const bool wr = (k + 1 < nk), ld = (k + 2 < nk);
;     bf16x8 fa[2][2], fb[2][2];
;     fa[0][0] = *(const bf16x8*)(As);
;     fa[0][1] = *(const bf16x8*)(As + 32 * LDK);
;     fb[0][0] = *(const bf16x8*)(Bs);
;     fb[0][1] = *(const bf16x8*)(Bs + 32 * LDK);
; #pragma unroll
;     for (int i = 0; i < 4; i++) {
;       if (wr) {
;         *(u32x4*)(nxt + (r0 + i * 32) * LDK + sg * 8) = g.a[i];
;         *(u32x4*)(nxt + 128 * LDK + (r0 + i * 32) * LDK + sg * 8) = g.b[i];
;       }
;       if (ld) {
;         g.a[i] = *(const u32x4*)(Ap + (size_t)i * 32 * o.lda + (k + 2) * 64);
;         g.b[i] = *(const u32x4*)(Bp + o.bs.o[i] + (k + 2) * 64);
;       }
;       if (i < 3) {
;         fa[(i + 1) & 1][0] = *(const bf16x8*)(As + (i + 1) * 16);
;         fa[(i + 1) & 1][1] = *(const bf16x8*)(As + 32 * LDK + (i + 1) * 16);
;         fb[(i + 1) & 1][0] = *(const bf16x8*)(Bs + (i + 1) * 16);
;         fb[(i + 1) & 1][1] = *(const bf16x8*)(Bs + 32 * LDK + (i + 1) * 16);
;       }
;       __builtin_amdgcn_sched_barrier(0);
;       __builtin_amdgcn_s_setprio(1);
;       acc[0][0] = __builtin_amdgcn_mfma_f32_32x32x16_bf16(fa[i & 1][0], fb[i & 1][0], acc[0][0], 0, 0, 0);
;       acc[0][1] = __builtin_amdgcn_mfma_f32_32x32x16_bf16(fa[i & 1][0], fb[i & 1][1], acc[0][1], 0, 0, 0);
;       acc[1][0] = __builtin_amdgcn_mfma_f32_32x32x16_bf16(fa[i & 1][1], fb[i & 1][0], acc[1][0], 0, 0, 0);
;       acc[1][1] = __builtin_amdgcn_mfma_f32_32x32x16_bf16(fa[i & 1][1], fb[i & 1][1], acc[1][1], 0, 0, 0);
.LBB0_2655:
	s_ashr_i32 s7, s6, 31
	s_lshl_b64 s[4:5], s[6:7], 18
	s_ashr_i32 s9, s8, 31
	s_waitcnt vmcnt(7)
	ds_write_b128 v100, v[64:67]
	s_waitcnt vmcnt(6)
	ds_write_b128 v100, v[68:71] offset:18432
	s_waitcnt vmcnt(5)
	ds_write_b128 v100, v[72:75] offset:4608
	s_waitcnt vmcnt(4)
	ds_write_b128 v100, v[76:79] offset:23040
	s_waitcnt vmcnt(3)
	ds_write_b128 v100, v[80:83] offset:9216
	s_waitcnt vmcnt(2)
	ds_write_b128 v100, v[84:87] offset:27648
	s_waitcnt vmcnt(1)
	ds_write_b128 v100, v[88:91] offset:13824
	s_waitcnt vmcnt(0)
	ds_write_b128 v100, v[92:95] offset:32256
	v_lshl_add_u64 v[64:65], v[102:103], 0, s[4:5]
	s_lshl_b64 s[10:11], s[8:9], 18
	v_add_co_u32_e32 v72, vcc, s76, v64
	v_lshl_add_u64 v[106:107], v[98:99], 0, s[10:11]
	s_nop 0
	v_addc_co_u32_e32 v73, vcc, 0, v65, vcc
	v_add_co_u32_e32 v76, vcc, s76, v106
	global_load_dwordx4 v[0:3], v[64:65], off offset:128
	global_load_dwordx4 v[4:7], v[106:107], off offset:128
	v_addc_co_u32_e32 v77, vcc, 0, v107, vcc
	v_add_co_u32_e32 v80, vcc, s77, v64
	global_load_dwordx4 v[66:69], v[72:73], off offset:128
	global_load_dwordx4 v[110:113], v[76:77], off offset:128
	v_addc_co_u32_e32 v81, vcc, 0, v65, vcc
	v_add_co_u32_e32 v84, vcc, s77, v106
	s_nop 1
	v_addc_co_u32_e32 v85, vcc, 0, v107, vcc
	v_add_co_u32_e32 v88, vcc, s78, v64
	global_load_dwordx4 v[114:117], v[80:81], off offset:128
	global_load_dwordx4 v[118:121], v[84:85], off offset:128
	v_addc_co_u32_e32 v89, vcc, 0, v65, vcc
	v_add_co_u32_e32 v92, vcc, s78, v106
	s_nop 1
	v_addc_co_u32_e32 v93, vcc, 0, v107, vcc
	global_load_dwordx4 v[122:125], v[88:89], off offset:128
	global_load_dwordx4 v[126:129], v[92:93], off offset:128
	s_waitcnt lgkmcnt(0)
	s_barrier
	global_load_dwordx4 v[130:133], v[64:65], off offset:256
	global_load_dwordx4 v[134:137], v[106:107], off offset:256
	ds_read_b128 v[8:11], v104
	ds_read_b128 v[32:35], v104 offset:4608
	ds_read_b128 v[12:15], v101 offset:18432
	ds_read_b128 v[36:39], v101 offset:23040
	s_waitcnt vmcnt(9)
	ds_write_b128 v100, v[0:3] offset:36864
	s_waitcnt vmcnt(8)
	ds_write_b128 v100, v[4:7] offset:55296
	ds_read_b128 v[138:141], v104 offset:32
	ds_read_b128 v[142:145], v104 offset:4640
	ds_read_b128 v[146:149], v101 offset:18464
	ds_read_b128 v[150:153], v101 offset:23072
	s_waitcnt lgkmcnt(7)
	v_mfma_f32_32x32x16_bf16 v[16:31], v[8:11], v[12:15], 0
	s_waitcnt lgkmcnt(6)
	v_mfma_f32_32x32x16_bf16 v[48:63], v[8:11], v[36:39], 0
	v_mfma_f32_32x32x16_bf16 v[0:15], v[32:35], v[12:15], 0
	v_mfma_f32_32x32x16_bf16 v[32:47], v[32:35], v[36:39], 0
	global_load_dwordx4 v[154:157], v[72:73], off offset:256
	global_load_dwordx4 v[158:161], v[76:77], off offset:256
	s_waitcnt vmcnt(9)
	ds_write_b128 v100, v[66:69] offset:41472
	s_waitcnt vmcnt(8)
	ds_write_b128 v100, v[110:113] offset:59904
	ds_read_b128 v[66:69], v104 offset:64
	ds_read_b128 v[110:113], v104 offset:4672
	ds_read_b128 v[162:165], v101 offset:18496
	ds_read_b128 v[166:169], v101 offset:23104
	s_waitcnt lgkmcnt(7)
	v_mfma_f32_32x32x16_bf16 v[16:31], v[138:141], v[146:149], v[16:31]
	s_waitcnt lgkmcnt(6)
	v_mfma_f32_32x32x16_bf16 v[48:63], v[138:141], v[150:153], v[48:63]
	v_mfma_f32_32x32x16_bf16 v[0:15], v[142:145], v[146:149], v[0:15]
	v_mfma_f32_32x32x16_bf16 v[32:47], v[142:145], v[150:153], v[32:47]
	global_load_dwordx4 v[138:141], v[80:81], off offset:256
	global_load_dwordx4 v[142:145], v[84:85], off offset:256
	s_waitcnt vmcnt(9)
	ds_write_b128 v100, v[114:117] offset:46080
	s_waitcnt vmcnt(8)
	ds_write_b128 v100, v[118:121] offset:64512
	ds_read_b128 v[114:117], v104 offset:96
	ds_read_b128 v[118:121], v104 offset:4704
	ds_read_b128 v[146:149], v101 offset:18528
	ds_read_b128 v[150:153], v101 offset:23136
	s_waitcnt lgkmcnt(7)
	v_mfma_f32_32x32x16_bf16 v[16:31], v[66:69], v[162:165], v[16:31]
	s_waitcnt lgkmcnt(6)
	v_mfma_f32_32x32x16_bf16 v[48:63], v[66:69], v[166:169], v[48:63]
	v_mfma_f32_32x32x16_bf16 v[0:15], v[110:113], v[162:165], v[0:15]
	v_mfma_f32_32x32x16_bf16 v[32:47], v[110:113], v[166:169], v[32:47]
	global_load_dwordx4 v[66:69], v[88:89], off offset:256
	global_load_dwordx4 v[110:113], v[92:93], off offset:256
	s_waitcnt vmcnt(9)
	ds_write_b128 v100, v[122:125] offset:50688
	s_waitcnt vmcnt(8)
	ds_write_b128 v105, v[126:129] offset:13824
	s_waitcnt lgkmcnt(3)
	v_mfma_f32_32x32x16_bf16 v[16:31], v[114:117], v[146:149], v[16:31]
	s_waitcnt lgkmcnt(2)
	v_mfma_f32_32x32x16_bf16 v[48:63], v[114:117], v[150:153], v[48:63]
	v_mfma_f32_32x32x16_bf16 v[0:15], v[118:121], v[146:149], v[0:15]
	v_mfma_f32_32x32x16_bf16 v[32:47], v[118:121], v[150:153], v[32:47]
	s_waitcnt lgkmcnt(0)
	s_barrier
; __device__ __forceinline__ void gemm_run(int tid, f32x16 (&acc)[2][2], GRegs& g, const GOp& o, int K, unsigned char* smem) {
;     ...
;   for (int k = 0; k < nk; k++) {
;     bf16r* cur = sbuf + (k & 1) * (256 * LDK);
;     bf16r* nxt = sbuf + ((k & 1) ^ 1) * (256 * LDK);
;     const bf16r* As = cur + (wm * 64 + fr) * LDK + fh * 8;
;     const bf16r* Bs = cur + 128 * LDK + (wn * 64 + fr) * LDK + fh * 8;
;     const bool wr = (k + 1 < nk), ld = (k + 2 < nk);
;     bf16x8 fa[2][2], fb[2][2];
;     fa[0][0] = *(const bf16x8*)(As);
;     fa[0][1] = *(const bf16x8*)(As + 32 * LDK);
;     fb[0][0] = *(const bf16x8*)(Bs);
;     fb[0][1] = *(const bf16x8*)(Bs + 32 * LDK);
; #pragma unroll
;     for (int i = 0; i < 4; i++) {
;       if (wr) {
;         *(u32x4*)(nxt + (r0 + i * 32) * LDK + sg * 8) = g.a[i];
;         *(u32x4*)(nxt + 128 * LDK + (r0 + i * 32) * LDK + sg * 8) = g.b[i];
;       }
;       if (ld) {
;         g.a[i] = *(const u32x4*)(Ap + (size_t)i * 32 * o.lda + (k + 2) * 64);
;         g.b[i] = *(const u32x4*)(Bp + o.bs.o[i] + (k + 2) * 64);
;       }
;       if (i < 3) {
;         fa[(i + 1) & 1][0] = *(const bf16x8*)(As + (i + 1) * 16);
;         fa[(i + 1) & 1][1] = *(const bf16x8*)(As + 32 * LDK + (i + 1) * 16);
;         fb[(i + 1) & 1][0] = *(const bf16x8*)(Bs + (i + 1) * 16);
;         fb[(i + 1) & 1][1] = *(const bf16x8*)(Bs + 32 * LDK + (i + 1) * 16);
;       }
;       __builtin_amdgcn_sched_barrier(0);
;       __builtin_amdgcn_s_setprio(1);
;       acc[0][0] = __builtin_amdgcn_mfma_f32_32x32x16_bf16(fa[i & 1][0], fb[i & 1][0], acc[0][0], 0, 0, 0);
;       acc[0][1] = __builtin_amdgcn_mfma_f32_32x32x16_bf16(fa[i & 1][0], fb[i & 1][1], acc[0][1], 0, 0, 0);
;       acc[1][0] = __builtin_amdgcn_mfma_f32_32x32x16_bf16(fa[i & 1][1], fb[i & 1][0], acc[1][0], 0, 0, 0);
;       acc[1][1] = __builtin_amdgcn_mfma_f32_32x32x16_bf16(fa[i & 1][1], fb[i & 1][1], acc[1][1], 0, 0, 0);
;       __builtin_amdgcn_s_setprio(0);
;     }
;     __syncthreads();
	global_load_dwordx4 v[114:117], v[64:65], off offset:384
	global_load_dwordx4 v[118:121], v[106:107], off offset:384
	ds_read_b128 v[122:125], v104 offset:36864
	ds_read_b128 v[126:129], v104 offset:41472
	ds_read_b128 v[146:149], v101 offset:55296
	ds_read_b128 v[150:153], v101 offset:59904
	s_waitcnt vmcnt(9)
	ds_write_b128 v100, v[130:133]
	s_waitcnt vmcnt(8)
	ds_write_b128 v100, v[134:137] offset:18432
	ds_read_b128 v[130:133], v104 offset:36896
	ds_read_b128 v[134:137], v104 offset:41504
	ds_read_b128 v[162:165], v101 offset:55328
	ds_read_b128 v[166:169], v101 offset:59936
	s_waitcnt lgkmcnt(7)
	v_mfma_f32_32x32x16_bf16 v[16:31], v[122:125], v[146:149], v[16:31]
	s_waitcnt lgkmcnt(6)
	v_mfma_f32_32x32x16_bf16 v[48:63], v[122:125], v[150:153], v[48:63]
	v_mfma_f32_32x32x16_bf16 v[0:15], v[126:129], v[146:149], v[0:15]
	v_mfma_f32_32x32x16_bf16 v[32:47], v[126:129], v[150:153], v[32:47]
	global_load_dwordx4 v[122:125], v[72:73], off offset:384
	global_load_dwordx4 v[126:129], v[76:77], off offset:384
	s_waitcnt vmcnt(9)
	ds_write_b128 v100, v[154:157] offset:4608
	s_waitcnt vmcnt(8)
	ds_write_b128 v100, v[158:161] offset:23040
	ds_read_b128 v[146:149], v104 offset:36928
	ds_read_b128 v[150:153], v104 offset:41536
	ds_read_b128 v[154:157], v101 offset:55360
	ds_read_b128 v[158:161], v101 offset:59968
	s_waitcnt lgkmcnt(7)
	v_mfma_f32_32x32x16_bf16 v[16:31], v[130:133], v[162:165], v[16:31]
	s_waitcnt lgkmcnt(6)
	v_mfma_f32_32x32x16_bf16 v[48:63], v[130:133], v[166:169], v[48:63]
	v_mfma_f32_32x32x16_bf16 v[0:15], v[134:137], v[162:165], v[0:15]
	v_mfma_f32_32x32x16_bf16 v[32:47], v[134:137], v[166:169], v[32:47]
	global_load_dwordx4 v[130:133], v[80:81], off offset:384
	global_load_dwordx4 v[134:137], v[84:85], off offset:384
	s_waitcnt vmcnt(9)
	ds_write_b128 v100, v[138:141] offset:9216
	s_waitcnt vmcnt(8)
	ds_write_b128 v100, v[142:145] offset:27648
	ds_read_b128 v[138:141], v104 offset:36960
	ds_read_b128 v[142:145], v104 offset:41568
	ds_read_b128 v[162:165], v101 offset:55392
	ds_read_b128 v[166:169], v101 offset:60000
	s_waitcnt lgkmcnt(7)
	v_mfma_f32_32x32x16_bf16 v[16:31], v[146:149], v[154:157], v[16:31]
	s_waitcnt lgkmcnt(6)
	v_mfma_f32_32x32x16_bf16 v[48:63], v[146:149], v[158:161], v[48:63]
	v_mfma_f32_32x32x16_bf16 v[0:15], v[150:153], v[154:157], v[0:15]
	v_mfma_f32_32x32x16_bf16 v[32:47], v[150:153], v[158:161], v[32:47]
	global_load_dwordx4 v[146:149], v[88:89], off offset:384
	global_load_dwordx4 v[150:153], v[92:93], off offset:384
	s_waitcnt vmcnt(9)
	ds_write_b128 v100, v[66:69] offset:13824
	s_waitcnt vmcnt(8)
	ds_write_b128 v100, v[110:113] offset:32256
	s_waitcnt lgkmcnt(3)
	v_mfma_f32_32x32x16_bf16 v[16:31], v[138:141], v[162:165], v[16:31]
	s_waitcnt lgkmcnt(2)
	v_mfma_f32_32x32x16_bf16 v[48:63], v[138:141], v[166:169], v[48:63]
	v_mfma_f32_32x32x16_bf16 v[0:15], v[142:145], v[162:165], v[0:15]
	v_mfma_f32_32x32x16_bf16 v[32:47], v[142:145], v[166:169], v[32:47]
	s_waitcnt lgkmcnt(0)
	s_barrier
	global_load_dwordx4 v[66:69], v[64:65], off offset:512
	global_load_dwordx4 v[110:113], v[106:107], off offset:512
	ds_read_b128 v[138:141], v104
	ds_read_b128 v[142:145], v104 offset:4608
	ds_read_b128 v[154:157], v101 offset:18432
	ds_read_b128 v[158:161], v101 offset:23040
	s_waitcnt vmcnt(9)
	ds_write_b128 v100, v[114:117] offset:36864
	s_waitcnt vmcnt(8)
	ds_write_b128 v100, v[118:121] offset:55296
	ds_read_b128 v[114:117], v104 offset:32
	ds_read_b128 v[118:121], v104 offset:4640
	ds_read_b128 v[162:165], v101 offset:18464
	ds_read_b128 v[166:169], v101 offset:23072
	s_waitcnt lgkmcnt(7)
	v_mfma_f32_32x32x16_bf16 v[16:31], v[138:141], v[154:157], v[16:31]
	s_waitcnt lgkmcnt(6)
	v_mfma_f32_32x32x16_bf16 v[48:63], v[138:141], v[158:161], v[48:63]
	v_mfma_f32_32x32x16_bf16 v[0:15], v[142:145], v[154:157], v[0:15]
	v_mfma_f32_32x32x16_bf16 v[32:47], v[142:145], v[158:161], v[32:47]
	global_load_dwordx4 v[138:141], v[72:73], off offset:512
	global_load_dwordx4 v[142:145], v[76:77], off offset:512
	s_waitcnt vmcnt(9)
	ds_write_b128 v100, v[122:125] offset:41472
	s_waitcnt vmcnt(8)
	ds_write_b128 v100, v[126:129] offset:59904
	ds_read_b128 v[122:125], v104 offset:64
	ds_read_b128 v[126:129], v104 offset:4672
	ds_read_b128 v[154:157], v101 offset:18496
	ds_read_b128 v[158:161], v101 offset:23104
	s_waitcnt lgkmcnt(7)
	v_mfma_f32_32x32x16_bf16 v[16:31], v[114:117], v[162:165], v[16:31]
	s_waitcnt lgkmcnt(6)
	v_mfma_f32_32x32x16_bf16 v[48:63], v[114:117], v[166:169], v[48:63]
	v_mfma_f32_32x32x16_bf16 v[0:15], v[118:121], v[162:165], v[0:15]
	v_mfma_f32_32x32x16_bf16 v[32:47], v[118:121], v[166:169], v[32:47]
	global_load_dwordx4 v[114:117], v[80:81], off offset:512
	global_load_dwordx4 v[118:121], v[84:85], off offset:512
	s_waitcnt vmcnt(9)
	ds_write_b128 v100, v[130:133] offset:46080
	s_waitcnt vmcnt(8)
	ds_write_b128 v100, v[134:137] offset:64512
	ds_read_b128 v[130:133], v104 offset:96
	ds_read_b128 v[134:137], v104 offset:4704
	ds_read_b128 v[162:165], v101 offset:18528
	ds_read_b128 v[166:169], v101 offset:23136
	s_waitcnt lgkmcnt(7)
	v_mfma_f32_32x32x16_bf16 v[16:31], v[122:125], v[154:157], v[16:31]
	s_waitcnt lgkmcnt(6)
	v_mfma_f32_32x32x16_bf16 v[48:63], v[122:125], v[158:161], v[48:63]
	v_mfma_f32_32x32x16_bf16 v[0:15], v[126:129], v[154:157], v[0:15]
	v_mfma_f32_32x32x16_bf16 v[32:47], v[126:129], v[158:161], v[32:47]
	global_load_dwordx4 v[122:125], v[88:89], off offset:512
	global_load_dwordx4 v[126:129], v[92:93], off offset:512
	s_waitcnt vmcnt(9)
	ds_write_b128 v100, v[146:149] offset:50688
	s_waitcnt vmcnt(8)
	ds_write_b128 v105, v[150:153] offset:13824
	s_waitcnt lgkmcnt(3)
	v_mfma_f32_32x32x16_bf16 v[16:31], v[130:133], v[162:165], v[16:31]
	s_waitcnt lgkmcnt(2)
	v_mfma_f32_32x32x16_bf16 v[48:63], v[130:133], v[166:169], v[48:63]
	v_mfma_f32_32x32x16_bf16 v[0:15], v[134:137], v[162:165], v[0:15]
	v_mfma_f32_32x32x16_bf16 v[32:47], v[134:137], v[166:169], v[32:47]
	s_waitcnt lgkmcnt(0)
	s_barrier
; __device__ __forceinline__ void gemm_run(int tid, f32x16 (&acc)[2][2], GRegs& g, const GOp& o, int K, unsigned char* smem) {
;     ...
;   for (int k = 0; k < nk; k++) {
;     bf16r* cur = sbuf + (k & 1) * (256 * LDK);
;     bf16r* nxt = sbuf + ((k & 1) ^ 1) * (256 * LDK);
;     const bf16r* As = cur + (wm * 64 + fr) * LDK + fh * 8;
;     const bf16r* Bs = cur + 128 * LDK + (wn * 64 + fr) * LDK + fh * 8;
;     const bool wr = (k + 1 < nk), ld = (k + 2 < nk);
;     bf16x8 fa[2][2], fb[2][2];
;     fa[0][0] = *(const bf16x8*)(As);
;     fa[0][1] = *(const bf16x8*)(As + 32 * LDK);
;     fb[0][0] = *(const bf16x8*)(Bs);
;     fb[0][1] = *(const bf16x8*)(Bs + 32 * LDK);
; #pragma unroll
;     for (int i = 0; i < 4; i++) {
;       if (wr) {
;         *(u32x4*)(nxt + (r0 + i * 32) * LDK + sg * 8) = g.a[i];
;         *(u32x4*)(nxt + 128 * LDK + (r0 + i * 32) * LDK + sg * 8) = g.b[i];
;       }
;       if (ld) {
;         g.a[i] = *(const u32x4*)(Ap + (size_t)i * 32 * o.lda + (k + 2) * 64);
;         g.b[i] = *(const u32x4*)(Bp + o.bs.o[i] + (k + 2) * 64);
;       }
;       if (i < 3) {
;         fa[(i + 1) & 1][0] = *(const bf16x8*)(As + (i + 1) * 16);
;         fa[(i + 1) & 1][1] = *(const bf16x8*)(As + 32 * LDK + (i + 1) * 16);
;         fb[(i + 1) & 1][0] = *(const bf16x8*)(Bs + (i + 1) * 16);
;         fb[(i + 1) & 1][1] = *(const bf16x8*)(Bs + 32 * LDK + (i + 1) * 16);
;       }
;       __builtin_amdgcn_sched_barrier(0);
;       __builtin_amdgcn_s_setprio(1);
;       acc[0][0] = __builtin_amdgcn_mfma_f32_32x32x16_bf16(fa[i & 1][0], fb[i & 1][0], acc[0][0], 0, 0, 0);
;       acc[0][1] = __builtin_amdgcn_mfma_f32_32x32x16_bf16(fa[i & 1][0], fb[i & 1][1], acc[0][1], 0, 0, 0);
;       acc[1][0] = __builtin_amdgcn_mfma_f32_32x32x16_bf16(fa[i & 1][1], fb[i & 1][0], acc[1][0], 0, 0, 0);
;       acc[1][1] = __builtin_amdgcn_mfma_f32_32x32x16_bf16(fa[i & 1][1], fb[i & 1][1], acc[1][1], 0, 0, 0);
;       __builtin_amdgcn_s_setprio(0);
;     }
;     __syncthreads();
	global_load_dwordx4 v[130:133], v[64:65], off offset:640
	global_load_dwordx4 v[134:137], v[106:107], off offset:640
	ds_read_b128 v[146:149], v104 offset:36864
	ds_read_b128 v[150:153], v104 offset:41472
	ds_read_b128 v[154:157], v101 offset:55296
	ds_read_b128 v[158:161], v101 offset:59904
	s_waitcnt vmcnt(9)
	ds_write_b128 v100, v[66:69]
	s_waitcnt vmcnt(8)
	ds_write_b128 v100, v[110:113] offset:18432
	ds_read_b128 v[66:69], v104 offset:36896
	ds_read_b128 v[110:113], v104 offset:41504
	ds_read_b128 v[162:165], v101 offset:55328
	ds_read_b128 v[166:169], v101 offset:59936
	s_waitcnt lgkmcnt(7)
	v_mfma_f32_32x32x16_bf16 v[16:31], v[146:149], v[154:157], v[16:31]
	s_waitcnt lgkmcnt(6)
	v_mfma_f32_32x32x16_bf16 v[48:63], v[146:149], v[158:161], v[48:63]
	v_mfma_f32_32x32x16_bf16 v[0:15], v[150:153], v[154:157], v[0:15]
	v_mfma_f32_32x32x16_bf16 v[32:47], v[150:153], v[158:161], v[32:47]
	global_load_dwordx4 v[146:149], v[72:73], off offset:640
	global_load_dwordx4 v[150:153], v[76:77], off offset:640
	s_waitcnt vmcnt(9)
	ds_write_b128 v100, v[138:141] offset:4608
	s_waitcnt vmcnt(8)
	ds_write_b128 v100, v[142:145] offset:23040
	ds_read_b128 v[138:141], v104 offset:36928
	ds_read_b128 v[142:145], v104 offset:41536
	ds_read_b128 v[154:157], v101 offset:55360
	ds_read_b128 v[158:161], v101 offset:59968
	s_waitcnt lgkmcnt(7)
	v_mfma_f32_32x32x16_bf16 v[16:31], v[66:69], v[162:165], v[16:31]
	s_waitcnt lgkmcnt(6)
	v_mfma_f32_32x32x16_bf16 v[48:63], v[66:69], v[166:169], v[48:63]
	v_mfma_f32_32x32x16_bf16 v[0:15], v[110:113], v[162:165], v[0:15]
	v_mfma_f32_32x32x16_bf16 v[32:47], v[110:113], v[166:169], v[32:47]
	global_load_dwordx4 v[66:69], v[80:81], off offset:640
	global_load_dwordx4 v[110:113], v[84:85], off offset:640
	s_waitcnt vmcnt(9)
	ds_write_b128 v100, v[114:117] offset:9216
	s_waitcnt vmcnt(8)
	ds_write_b128 v100, v[118:121] offset:27648
	ds_read_b128 v[114:117], v104 offset:36960
	ds_read_b128 v[118:121], v104 offset:41568
	ds_read_b128 v[162:165], v101 offset:55392
	ds_read_b128 v[166:169], v101 offset:60000
	s_waitcnt lgkmcnt(7)
	v_mfma_f32_32x32x16_bf16 v[16:31], v[138:141], v[154:157], v[16:31]
	s_waitcnt lgkmcnt(6)
	v_mfma_f32_32x32x16_bf16 v[48:63], v[138:141], v[158:161], v[48:63]
	v_mfma_f32_32x32x16_bf16 v[0:15], v[142:145], v[154:157], v[0:15]
	v_mfma_f32_32x32x16_bf16 v[32:47], v[142:145], v[158:161], v[32:47]
	global_load_dwordx4 v[138:141], v[88:89], off offset:640
	global_load_dwordx4 v[142:145], v[92:93], off offset:640
	s_waitcnt vmcnt(9)
	ds_write_b128 v100, v[122:125] offset:13824
	s_waitcnt vmcnt(8)
	ds_write_b128 v100, v[126:129] offset:32256
	s_waitcnt lgkmcnt(3)
	v_mfma_f32_32x32x16_bf16 v[16:31], v[114:117], v[162:165], v[16:31]
	s_waitcnt lgkmcnt(2)
	v_mfma_f32_32x32x16_bf16 v[48:63], v[114:117], v[166:169], v[48:63]
	v_mfma_f32_32x32x16_bf16 v[0:15], v[118:121], v[162:165], v[0:15]
	v_mfma_f32_32x32x16_bf16 v[32:47], v[118:121], v[166:169], v[32:47]
	s_waitcnt lgkmcnt(0)
	s_barrier
	global_load_dwordx4 v[114:117], v[64:65], off offset:768
	global_load_dwordx4 v[118:121], v[106:107], off offset:768
	ds_read_b128 v[122:125], v104
	ds_read_b128 v[126:129], v104 offset:4608
	ds_read_b128 v[154:157], v101 offset:18432
	ds_read_b128 v[158:161], v101 offset:23040
	s_waitcnt vmcnt(9)
	ds_write_b128 v100, v[130:133] offset:36864
	s_waitcnt vmcnt(8)
	ds_write_b128 v100, v[134:137] offset:55296
	ds_read_b128 v[130:133], v104 offset:32
	ds_read_b128 v[134:137], v104 offset:4640
	ds_read_b128 v[162:165], v101 offset:18464
	ds_read_b128 v[166:169], v101 offset:23072
	s_waitcnt lgkmcnt(7)
	v_mfma_f32_32x32x16_bf16 v[16:31], v[122:125], v[154:157], v[16:31]
	s_waitcnt lgkmcnt(6)
	v_mfma_f32_32x32x16_bf16 v[48:63], v[122:125], v[158:161], v[48:63]
	v_mfma_f32_32x32x16_bf16 v[0:15], v[126:129], v[154:157], v[0:15]
	v_mfma_f32_32x32x16_bf16 v[32:47], v[126:129], v[158:161], v[32:47]
	global_load_dwordx4 v[122:125], v[72:73], off offset:768
	global_load_dwordx4 v[126:129], v[76:77], off offset:768
	s_waitcnt vmcnt(9)
	ds_write_b128 v100, v[146:149] offset:41472
	s_waitcnt vmcnt(8)
	ds_write_b128 v100, v[150:153] offset:59904
	ds_read_b128 v[146:149], v104 offset:64
	ds_read_b128 v[150:153], v104 offset:4672
	ds_read_b128 v[154:157], v101 offset:18496
	ds_read_b128 v[158:161], v101 offset:23104
	s_waitcnt lgkmcnt(7)
	v_mfma_f32_32x32x16_bf16 v[16:31], v[130:133], v[162:165], v[16:31]
	s_waitcnt lgkmcnt(6)
	v_mfma_f32_32x32x16_bf16 v[48:63], v[130:133], v[166:169], v[48:63]
	v_mfma_f32_32x32x16_bf16 v[0:15], v[134:137], v[162:165], v[0:15]
	v_mfma_f32_32x32x16_bf16 v[32:47], v[134:137], v[166:169], v[32:47]
	global_load_dwordx4 v[130:133], v[80:81], off offset:768
	global_load_dwordx4 v[134:137], v[84:85], off offset:768
	s_waitcnt vmcnt(9)
	ds_write_b128 v100, v[66:69] offset:46080
	s_waitcnt vmcnt(8)
	ds_write_b128 v100, v[110:113] offset:64512
	ds_read_b128 v[66:69], v104 offset:96
	ds_read_b128 v[110:113], v104 offset:4704
	ds_read_b128 v[162:165], v101 offset:18528
	ds_read_b128 v[166:169], v101 offset:23136
	s_waitcnt lgkmcnt(7)
	v_mfma_f32_32x32x16_bf16 v[16:31], v[146:149], v[154:157], v[16:31]
	s_waitcnt lgkmcnt(6)
	v_mfma_f32_32x32x16_bf16 v[48:63], v[146:149], v[158:161], v[48:63]
	v_mfma_f32_32x32x16_bf16 v[0:15], v[150:153], v[154:157], v[0:15]
	v_mfma_f32_32x32x16_bf16 v[32:47], v[150:153], v[158:161], v[32:47]
	global_load_dwordx4 v[146:149], v[88:89], off offset:768
	global_load_dwordx4 v[150:153], v[92:93], off offset:768
	s_waitcnt vmcnt(9)
	ds_write_b128 v100, v[138:141] offset:50688
	s_waitcnt vmcnt(8)
	ds_write_b128 v105, v[142:145] offset:13824
	s_waitcnt lgkmcnt(3)
	v_mfma_f32_32x32x16_bf16 v[16:31], v[66:69], v[162:165], v[16:31]
	s_waitcnt lgkmcnt(2)
	v_mfma_f32_32x32x16_bf16 v[48:63], v[66:69], v[166:169], v[48:63]
	v_mfma_f32_32x32x16_bf16 v[0:15], v[110:113], v[162:165], v[0:15]
	v_mfma_f32_32x32x16_bf16 v[32:47], v[110:113], v[166:169], v[32:47]
	s_waitcnt lgkmcnt(0)
	s_barrier
; __device__ __forceinline__ void gemm_run(int tid, f32x16 (&acc)[2][2], GRegs& g, const GOp& o, int K, unsigned char* smem) {
;     ...
;   for (int k = 0; k < nk; k++) {
;     bf16r* cur = sbuf + (k & 1) * (256 * LDK);
;     bf16r* nxt = sbuf + ((k & 1) ^ 1) * (256 * LDK);
;     const bf16r* As = cur + (wm * 64 + fr) * LDK + fh * 8;
;     const bf16r* Bs = cur + 128 * LDK + (wn * 64 + fr) * LDK + fh * 8;
;     const bool wr = (k + 1 < nk), ld = (k + 2 < nk);
;     bf16x8 fa[2][2], fb[2][2];
;     fa[0][0] = *(const bf16x8*)(As);
;     fa[0][1] = *(const bf16x8*)(As + 32 * LDK);
;     fb[0][0] = *(const bf16x8*)(Bs);
;     fb[0][1] = *(const bf16x8*)(Bs + 32 * LDK);
; #pragma unroll
;     for (int i = 0; i < 4; i++) {
;       if (wr) {
;         *(u32x4*)(nxt + (r0 + i * 32) * LDK + sg * 8) = g.a[i];
;         *(u32x4*)(nxt + 128 * LDK + (r0 + i * 32) * LDK + sg * 8) = g.b[i];
;       }
;       if (ld) {
;         g.a[i] = *(const u32x4*)(Ap + (size_t)i * 32 * o.lda + (k + 2) * 64);
;         g.b[i] = *(const u32x4*)(Bp + o.bs.o[i] + (k + 2) * 64);
;       }
;       if (i < 3) {
;         fa[(i + 1) & 1][0] = *(const bf16x8*)(As + (i + 1) * 16);
;         fa[(i + 1) & 1][1] = *(const bf16x8*)(As + 32 * LDK + (i + 1) * 16);
;         fb[(i + 1) & 1][0] = *(const bf16x8*)(Bs + (i + 1) * 16);
;         fb[(i + 1) & 1][1] = *(const bf16x8*)(Bs + 32 * LDK + (i + 1) * 16);
;       }
;       __builtin_amdgcn_sched_barrier(0);
;       __builtin_amdgcn_s_setprio(1);
;       acc[0][0] = __builtin_amdgcn_mfma_f32_32x32x16_bf16(fa[i & 1][0], fb[i & 1][0], acc[0][0], 0, 0, 0);
;       acc[0][1] = __builtin_amdgcn_mfma_f32_32x32x16_bf16(fa[i & 1][0], fb[i & 1][1], acc[0][1], 0, 0, 0);
;       acc[1][0] = __builtin_amdgcn_mfma_f32_32x32x16_bf16(fa[i & 1][1], fb[i & 1][0], acc[1][0], 0, 0, 0);
;       acc[1][1] = __builtin_amdgcn_mfma_f32_32x32x16_bf16(fa[i & 1][1], fb[i & 1][1], acc[1][1], 0, 0, 0);
;       __builtin_amdgcn_s_setprio(0);
;     }
;     __syncthreads();
	global_load_dwordx4 v[66:69], v[64:65], off offset:896
	global_load_dwordx4 v[110:113], v[106:107], off offset:896
	ds_read_b128 v[138:141], v104 offset:36864
	ds_read_b128 v[142:145], v104 offset:41472
	ds_read_b128 v[154:157], v101 offset:55296
	ds_read_b128 v[158:161], v101 offset:59904
	s_waitcnt vmcnt(9)
	ds_write_b128 v100, v[114:117]
	s_waitcnt vmcnt(8)
	ds_write_b128 v100, v[118:121] offset:18432
	ds_read_b128 v[114:117], v104 offset:36896
	ds_read_b128 v[118:121], v104 offset:41504
	ds_read_b128 v[162:165], v101 offset:55328
	ds_read_b128 v[166:169], v101 offset:59936
	s_waitcnt lgkmcnt(7)
	v_mfma_f32_32x32x16_bf16 v[16:31], v[138:141], v[154:157], v[16:31]
	s_waitcnt lgkmcnt(6)
	v_mfma_f32_32x32x16_bf16 v[48:63], v[138:141], v[158:161], v[48:63]
	v_mfma_f32_32x32x16_bf16 v[0:15], v[142:145], v[154:157], v[0:15]
	v_mfma_f32_32x32x16_bf16 v[32:47], v[142:145], v[158:161], v[32:47]
	global_load_dwordx4 v[138:141], v[72:73], off offset:896
	global_load_dwordx4 v[142:145], v[76:77], off offset:896
	s_waitcnt vmcnt(9)
	ds_write_b128 v100, v[122:125] offset:4608
	s_waitcnt vmcnt(8)
	ds_write_b128 v100, v[126:129] offset:23040
	ds_read_b128 v[122:125], v104 offset:36928
	ds_read_b128 v[126:129], v104 offset:41536
	ds_read_b128 v[154:157], v101 offset:55360
	ds_read_b128 v[158:161], v101 offset:59968
	s_waitcnt lgkmcnt(7)
	v_mfma_f32_32x32x16_bf16 v[16:31], v[114:117], v[162:165], v[16:31]
	s_waitcnt lgkmcnt(6)
	v_mfma_f32_32x32x16_bf16 v[48:63], v[114:117], v[166:169], v[48:63]
	v_mfma_f32_32x32x16_bf16 v[0:15], v[118:121], v[162:165], v[0:15]
	v_mfma_f32_32x32x16_bf16 v[32:47], v[118:121], v[166:169], v[32:47]
	global_load_dwordx4 v[114:117], v[80:81], off offset:896
	global_load_dwordx4 v[118:121], v[84:85], off offset:896
	s_waitcnt vmcnt(9)
	ds_write_b128 v100, v[130:133] offset:9216
	s_waitcnt vmcnt(8)
	ds_write_b128 v100, v[134:137] offset:27648
	ds_read_b128 v[130:133], v104 offset:36960
	ds_read_b128 v[134:137], v104 offset:41568
	ds_read_b128 v[162:165], v101 offset:55392
	ds_read_b128 v[166:169], v101 offset:60000
	s_waitcnt lgkmcnt(7)
	v_mfma_f32_32x32x16_bf16 v[16:31], v[122:125], v[154:157], v[16:31]
	s_waitcnt lgkmcnt(6)
	v_mfma_f32_32x32x16_bf16 v[48:63], v[122:125], v[158:161], v[48:63]
	v_mfma_f32_32x32x16_bf16 v[0:15], v[126:129], v[154:157], v[0:15]
	v_mfma_f32_32x32x16_bf16 v[32:47], v[126:129], v[158:161], v[32:47]
	global_load_dwordx4 v[122:125], v[88:89], off offset:896
	global_load_dwordx4 v[126:129], v[92:93], off offset:896
	s_waitcnt vmcnt(9)
	ds_write_b128 v100, v[146:149] offset:13824
	s_waitcnt vmcnt(8)
	ds_write_b128 v100, v[150:153] offset:32256
	s_waitcnt lgkmcnt(3)
	v_mfma_f32_32x32x16_bf16 v[16:31], v[130:133], v[162:165], v[16:31]
	s_waitcnt lgkmcnt(2)
	v_mfma_f32_32x32x16_bf16 v[48:63], v[130:133], v[166:169], v[48:63]
	v_mfma_f32_32x32x16_bf16 v[0:15], v[134:137], v[162:165], v[0:15]
	v_mfma_f32_32x32x16_bf16 v[32:47], v[134:137], v[166:169], v[32:47]
	s_waitcnt lgkmcnt(0)
	s_barrier
	global_load_dwordx4 v[130:133], v[64:65], off offset:1024
	global_load_dwordx4 v[134:137], v[106:107], off offset:1024
	ds_read_b128 v[146:149], v104
	ds_read_b128 v[150:153], v104 offset:4608
	ds_read_b128 v[154:157], v101 offset:18432
	ds_read_b128 v[158:161], v101 offset:23040
	s_waitcnt vmcnt(9)
	ds_write_b128 v100, v[66:69] offset:36864
	s_waitcnt vmcnt(8)
	ds_write_b128 v100, v[110:113] offset:55296
	ds_read_b128 v[66:69], v104 offset:32
	ds_read_b128 v[110:113], v104 offset:4640
	ds_read_b128 v[162:165], v101 offset:18464
	ds_read_b128 v[166:169], v101 offset:23072
	s_waitcnt lgkmcnt(7)
	v_mfma_f32_32x32x16_bf16 v[16:31], v[146:149], v[154:157], v[16:31]
	s_waitcnt lgkmcnt(6)
	v_mfma_f32_32x32x16_bf16 v[48:63], v[146:149], v[158:161], v[48:63]
	v_mfma_f32_32x32x16_bf16 v[0:15], v[150:153], v[154:157], v[0:15]
	v_mfma_f32_32x32x16_bf16 v[32:47], v[150:153], v[158:161], v[32:47]
	global_load_dwordx4 v[146:149], v[72:73], off offset:1024
	global_load_dwordx4 v[150:153], v[76:77], off offset:1024
	s_waitcnt vmcnt(9)
	ds_write_b128 v100, v[138:141] offset:41472
	s_waitcnt vmcnt(8)
	ds_write_b128 v100, v[142:145] offset:59904
	ds_read_b128 v[138:141], v104 offset:64
	ds_read_b128 v[142:145], v104 offset:4672
	ds_read_b128 v[154:157], v101 offset:18496
	ds_read_b128 v[158:161], v101 offset:23104
	s_waitcnt lgkmcnt(7)
	v_mfma_f32_32x32x16_bf16 v[16:31], v[66:69], v[162:165], v[16:31]
	s_waitcnt lgkmcnt(6)
	v_mfma_f32_32x32x16_bf16 v[48:63], v[66:69], v[166:169], v[48:63]
	v_mfma_f32_32x32x16_bf16 v[0:15], v[110:113], v[162:165], v[0:15]
	v_mfma_f32_32x32x16_bf16 v[32:47], v[110:113], v[166:169], v[32:47]
	global_load_dwordx4 v[66:69], v[80:81], off offset:1024
	global_load_dwordx4 v[110:113], v[84:85], off offset:1024
	s_waitcnt vmcnt(9)
	ds_write_b128 v100, v[114:117] offset:46080
	s_waitcnt vmcnt(8)
	ds_write_b128 v100, v[118:121] offset:64512
	ds_read_b128 v[114:117], v104 offset:96
	ds_read_b128 v[118:121], v104 offset:4704
	ds_read_b128 v[162:165], v101 offset:18528
	ds_read_b128 v[166:169], v101 offset:23136
	s_waitcnt lgkmcnt(7)
	v_mfma_f32_32x32x16_bf16 v[16:31], v[138:141], v[154:157], v[16:31]
	s_waitcnt lgkmcnt(6)
	v_mfma_f32_32x32x16_bf16 v[48:63], v[138:141], v[158:161], v[48:63]
	v_mfma_f32_32x32x16_bf16 v[0:15], v[142:145], v[154:157], v[0:15]
	v_mfma_f32_32x32x16_bf16 v[32:47], v[142:145], v[158:161], v[32:47]
	global_load_dwordx4 v[138:141], v[88:89], off offset:1024
	global_load_dwordx4 v[142:145], v[92:93], off offset:1024
	s_waitcnt vmcnt(9)
	ds_write_b128 v100, v[122:125] offset:50688
	s_waitcnt vmcnt(8)
	ds_write_b128 v105, v[126:129] offset:13824
	s_waitcnt lgkmcnt(3)
	v_mfma_f32_32x32x16_bf16 v[16:31], v[114:117], v[162:165], v[16:31]
	s_waitcnt lgkmcnt(2)
	v_mfma_f32_32x32x16_bf16 v[48:63], v[114:117], v[166:169], v[48:63]
	v_mfma_f32_32x32x16_bf16 v[0:15], v[118:121], v[162:165], v[0:15]
	v_mfma_f32_32x32x16_bf16 v[32:47], v[118:121], v[166:169], v[32:47]
	s_waitcnt lgkmcnt(0)
	s_barrier
; __device__ __forceinline__ void gemm_run(int tid, f32x16 (&acc)[2][2], GRegs& g, const GOp& o, int K, unsigned char* smem) {
;     ...
;   for (int k = 0; k < nk; k++) {
;     bf16r* cur = sbuf + (k & 1) * (256 * LDK);
;     bf16r* nxt = sbuf + ((k & 1) ^ 1) * (256 * LDK);
;     const bf16r* As = cur + (wm * 64 + fr) * LDK + fh * 8;
;     const bf16r* Bs = cur + 128 * LDK + (wn * 64 + fr) * LDK + fh * 8;
;     const bool wr = (k + 1 < nk), ld = (k + 2 < nk);
;     bf16x8 fa[2][2], fb[2][2];
;     fa[0][0] = *(const bf16x8*)(As);
;     fa[0][1] = *(const bf16x8*)(As + 32 * LDK);
;     fb[0][0] = *(const bf16x8*)(Bs);
;     fb[0][1] = *(const bf16x8*)(Bs + 32 * LDK);
; #pragma unroll
;     for (int i = 0; i < 4; i++) {
;       if (wr) {
;         *(u32x4*)(nxt + (r0 + i * 32) * LDK + sg * 8) = g.a[i];
;         *(u32x4*)(nxt + 128 * LDK + (r0 + i * 32) * LDK + sg * 8) = g.b[i];
;       }
;       if (ld) {
;         g.a[i] = *(const u32x4*)(Ap + (size_t)i * 32 * o.lda + (k + 2) * 64);
;         g.b[i] = *(const u32x4*)(Bp + o.bs.o[i] + (k + 2) * 64);
;       }
;       if (i < 3) {
;         fa[(i + 1) & 1][0] = *(const bf16x8*)(As + (i + 1) * 16);
;         fa[(i + 1) & 1][1] = *(const bf16x8*)(As + 32 * LDK + (i + 1) * 16);
;         fb[(i + 1) & 1][0] = *(const bf16x8*)(Bs + (i + 1) * 16);
;         fb[(i + 1) & 1][1] = *(const bf16x8*)(Bs + 32 * LDK + (i + 1) * 16);
;       }
;       __builtin_amdgcn_sched_barrier(0);
;       __builtin_amdgcn_s_setprio(1);
;       acc[0][0] = __builtin_amdgcn_mfma_f32_32x32x16_bf16(fa[i & 1][0], fb[i & 1][0], acc[0][0], 0, 0, 0);
;       acc[0][1] = __builtin_amdgcn_mfma_f32_32x32x16_bf16(fa[i & 1][0], fb[i & 1][1], acc[0][1], 0, 0, 0);
;       acc[1][0] = __builtin_amdgcn_mfma_f32_32x32x16_bf16(fa[i & 1][1], fb[i & 1][0], acc[1][0], 0, 0, 0);
;       acc[1][1] = __builtin_amdgcn_mfma_f32_32x32x16_bf16(fa[i & 1][1], fb[i & 1][1], acc[1][1], 0, 0, 0);
;       __builtin_amdgcn_s_setprio(0);
;     }
;     __syncthreads();
	global_load_dwordx4 v[114:117], v[64:65], off offset:1152
	global_load_dwordx4 v[118:121], v[106:107], off offset:1152
	ds_read_b128 v[122:125], v104 offset:36864
	ds_read_b128 v[126:129], v104 offset:41472
	ds_read_b128 v[154:157], v101 offset:55296
	ds_read_b128 v[158:161], v101 offset:59904
	s_waitcnt vmcnt(9)
	ds_write_b128 v100, v[130:133]
	s_waitcnt vmcnt(8)
	ds_write_b128 v100, v[134:137] offset:18432
	ds_read_b128 v[130:133], v104 offset:36896
	ds_read_b128 v[134:137], v104 offset:41504
	ds_read_b128 v[162:165], v101 offset:55328
	ds_read_b128 v[166:169], v101 offset:59936
	s_waitcnt lgkmcnt(7)
	v_mfma_f32_32x32x16_bf16 v[16:31], v[122:125], v[154:157], v[16:31]
	s_waitcnt lgkmcnt(6)
	v_mfma_f32_32x32x16_bf16 v[48:63], v[122:125], v[158:161], v[48:63]
	v_mfma_f32_32x32x16_bf16 v[0:15], v[126:129], v[154:157], v[0:15]
	v_mfma_f32_32x32x16_bf16 v[32:47], v[126:129], v[158:161], v[32:47]
	global_load_dwordx4 v[122:125], v[72:73], off offset:1152
	global_load_dwordx4 v[126:129], v[76:77], off offset:1152
	s_waitcnt vmcnt(9)
	ds_write_b128 v100, v[146:149] offset:4608
	s_waitcnt vmcnt(8)
	ds_write_b128 v100, v[150:153] offset:23040
	ds_read_b128 v[146:149], v104 offset:36928
	ds_read_b128 v[150:153], v104 offset:41536
	ds_read_b128 v[154:157], v101 offset:55360
	ds_read_b128 v[158:161], v101 offset:59968
	s_waitcnt lgkmcnt(7)
	v_mfma_f32_32x32x16_bf16 v[16:31], v[130:133], v[162:165], v[16:31]
	s_waitcnt lgkmcnt(6)
	v_mfma_f32_32x32x16_bf16 v[48:63], v[130:133], v[166:169], v[48:63]
	v_mfma_f32_32x32x16_bf16 v[0:15], v[134:137], v[162:165], v[0:15]
	v_mfma_f32_32x32x16_bf16 v[32:47], v[134:137], v[166:169], v[32:47]
	global_load_dwordx4 v[130:133], v[80:81], off offset:1152
	global_load_dwordx4 v[134:137], v[84:85], off offset:1152
	s_waitcnt vmcnt(9)
	ds_write_b128 v100, v[66:69] offset:9216
	s_waitcnt vmcnt(8)
	ds_write_b128 v100, v[110:113] offset:27648
	ds_read_b128 v[66:69], v104 offset:36960
	ds_read_b128 v[110:113], v104 offset:41568
	ds_read_b128 v[162:165], v101 offset:55392
	ds_read_b128 v[166:169], v101 offset:60000
	s_waitcnt lgkmcnt(7)
	v_mfma_f32_32x32x16_bf16 v[16:31], v[146:149], v[154:157], v[16:31]
	s_waitcnt lgkmcnt(6)
	v_mfma_f32_32x32x16_bf16 v[48:63], v[146:149], v[158:161], v[48:63]
	v_mfma_f32_32x32x16_bf16 v[0:15], v[150:153], v[154:157], v[0:15]
	v_mfma_f32_32x32x16_bf16 v[32:47], v[150:153], v[158:161], v[32:47]
	global_load_dwordx4 v[146:149], v[88:89], off offset:1152
	global_load_dwordx4 v[150:153], v[92:93], off offset:1152
	s_waitcnt vmcnt(9)
	ds_write_b128 v100, v[138:141] offset:13824
	s_waitcnt vmcnt(8)
	ds_write_b128 v100, v[142:145] offset:32256
	s_waitcnt lgkmcnt(3)
	v_mfma_f32_32x32x16_bf16 v[16:31], v[66:69], v[162:165], v[16:31]
	s_waitcnt lgkmcnt(2)
	v_mfma_f32_32x32x16_bf16 v[48:63], v[66:69], v[166:169], v[48:63]
	v_mfma_f32_32x32x16_bf16 v[0:15], v[110:113], v[162:165], v[0:15]
	v_mfma_f32_32x32x16_bf16 v[32:47], v[110:113], v[166:169], v[32:47]
	s_waitcnt lgkmcnt(0)
	s_barrier
	global_load_dwordx4 v[66:69], v[64:65], off offset:1280
	global_load_dwordx4 v[110:113], v[106:107], off offset:1280
	ds_read_b128 v[138:141], v104
	ds_read_b128 v[142:145], v104 offset:4608
	ds_read_b128 v[154:157], v101 offset:18432
	ds_read_b128 v[158:161], v101 offset:23040
	s_waitcnt vmcnt(9)
	ds_write_b128 v100, v[114:117] offset:36864
	s_waitcnt vmcnt(8)
	ds_write_b128 v100, v[118:121] offset:55296
	ds_read_b128 v[114:117], v104 offset:32
	ds_read_b128 v[118:121], v104 offset:4640
	ds_read_b128 v[162:165], v101 offset:18464
	ds_read_b128 v[166:169], v101 offset:23072
	s_waitcnt lgkmcnt(7)
	v_mfma_f32_32x32x16_bf16 v[16:31], v[138:141], v[154:157], v[16:31]
	s_waitcnt lgkmcnt(6)
	v_mfma_f32_32x32x16_bf16 v[48:63], v[138:141], v[158:161], v[48:63]
	v_mfma_f32_32x32x16_bf16 v[0:15], v[142:145], v[154:157], v[0:15]
	v_mfma_f32_32x32x16_bf16 v[32:47], v[142:145], v[158:161], v[32:47]
	global_load_dwordx4 v[138:141], v[72:73], off offset:1280
	global_load_dwordx4 v[142:145], v[76:77], off offset:1280
	s_waitcnt vmcnt(9)
	ds_write_b128 v100, v[122:125] offset:41472
	s_waitcnt vmcnt(8)
	ds_write_b128 v100, v[126:129] offset:59904
	ds_read_b128 v[122:125], v104 offset:64
	ds_read_b128 v[126:129], v104 offset:4672
	ds_read_b128 v[154:157], v101 offset:18496
	ds_read_b128 v[158:161], v101 offset:23104
	s_waitcnt lgkmcnt(7)
	v_mfma_f32_32x32x16_bf16 v[16:31], v[114:117], v[162:165], v[16:31]
	s_waitcnt lgkmcnt(6)
	v_mfma_f32_32x32x16_bf16 v[48:63], v[114:117], v[166:169], v[48:63]
	v_mfma_f32_32x32x16_bf16 v[0:15], v[118:121], v[162:165], v[0:15]
	v_mfma_f32_32x32x16_bf16 v[32:47], v[118:121], v[166:169], v[32:47]
	global_load_dwordx4 v[114:117], v[80:81], off offset:1280
	global_load_dwordx4 v[118:121], v[84:85], off offset:1280
	s_waitcnt vmcnt(9)
	ds_write_b128 v100, v[130:133] offset:46080
	s_waitcnt vmcnt(8)
	ds_write_b128 v100, v[134:137] offset:64512
	ds_read_b128 v[130:133], v104 offset:96
	ds_read_b128 v[134:137], v104 offset:4704
	ds_read_b128 v[162:165], v101 offset:18528
	ds_read_b128 v[166:169], v101 offset:23136
	s_waitcnt lgkmcnt(7)
	v_mfma_f32_32x32x16_bf16 v[16:31], v[122:125], v[154:157], v[16:31]
	s_waitcnt lgkmcnt(6)
	v_mfma_f32_32x32x16_bf16 v[48:63], v[122:125], v[158:161], v[48:63]
	v_mfma_f32_32x32x16_bf16 v[0:15], v[126:129], v[154:157], v[0:15]
	v_mfma_f32_32x32x16_bf16 v[32:47], v[126:129], v[158:161], v[32:47]
	global_load_dwordx4 v[122:125], v[88:89], off offset:1280
	global_load_dwordx4 v[126:129], v[92:93], off offset:1280
	s_waitcnt vmcnt(9)
	ds_write_b128 v100, v[146:149] offset:50688
	s_waitcnt vmcnt(8)
	ds_write_b128 v105, v[150:153] offset:13824
	s_waitcnt lgkmcnt(3)
	v_mfma_f32_32x32x16_bf16 v[16:31], v[130:133], v[162:165], v[16:31]
	s_waitcnt lgkmcnt(2)
	v_mfma_f32_32x32x16_bf16 v[48:63], v[130:133], v[166:169], v[48:63]
	v_mfma_f32_32x32x16_bf16 v[0:15], v[134:137], v[162:165], v[0:15]
	v_mfma_f32_32x32x16_bf16 v[32:47], v[134:137], v[166:169], v[32:47]
	s_waitcnt lgkmcnt(0)
	s_barrier
; __device__ __forceinline__ void gemm_run(int tid, f32x16 (&acc)[2][2], GRegs& g, const GOp& o, int K, unsigned char* smem) {
;     ...
;   for (int k = 0; k < nk; k++) {
;     bf16r* cur = sbuf + (k & 1) * (256 * LDK);
;     bf16r* nxt = sbuf + ((k & 1) ^ 1) * (256 * LDK);
;     const bf16r* As = cur + (wm * 64 + fr) * LDK + fh * 8;
;     const bf16r* Bs = cur + 128 * LDK + (wn * 64 + fr) * LDK + fh * 8;
;     const bool wr = (k + 1 < nk), ld = (k + 2 < nk);
;     bf16x8 fa[2][2], fb[2][2];
;     fa[0][0] = *(const bf16x8*)(As);
;     fa[0][1] = *(const bf16x8*)(As + 32 * LDK);
;     fb[0][0] = *(const bf16x8*)(Bs);
;     fb[0][1] = *(const bf16x8*)(Bs + 32 * LDK);
; #pragma unroll
;     for (int i = 0; i < 4; i++) {
;       if (wr) {
;         *(u32x4*)(nxt + (r0 + i * 32) * LDK + sg * 8) = g.a[i];
;         *(u32x4*)(nxt + 128 * LDK + (r0 + i * 32) * LDK + sg * 8) = g.b[i];
;       }
;       if (ld) {
;         g.a[i] = *(const u32x4*)(Ap + (size_t)i * 32 * o.lda + (k + 2) * 64);
;         g.b[i] = *(const u32x4*)(Bp + o.bs.o[i] + (k + 2) * 64);
;       }
;       if (i < 3) {
;         fa[(i + 1) & 1][0] = *(const bf16x8*)(As + (i + 1) * 16);
;         fa[(i + 1) & 1][1] = *(const bf16x8*)(As + 32 * LDK + (i + 1) * 16);
;         fb[(i + 1) & 1][0] = *(const bf16x8*)(Bs + (i + 1) * 16);
;         fb[(i + 1) & 1][1] = *(const bf16x8*)(Bs + 32 * LDK + (i + 1) * 16);
;       }
;       __builtin_amdgcn_sched_barrier(0);
;       __builtin_amdgcn_s_setprio(1);
;       acc[0][0] = __builtin_amdgcn_mfma_f32_32x32x16_bf16(fa[i & 1][0], fb[i & 1][0], acc[0][0], 0, 0, 0);
;       acc[0][1] = __builtin_amdgcn_mfma_f32_32x32x16_bf16(fa[i & 1][0], fb[i & 1][1], acc[0][1], 0, 0, 0);
;       acc[1][0] = __builtin_amdgcn_mfma_f32_32x32x16_bf16(fa[i & 1][1], fb[i & 1][0], acc[1][0], 0, 0, 0);
;       acc[1][1] = __builtin_amdgcn_mfma_f32_32x32x16_bf16(fa[i & 1][1], fb[i & 1][1], acc[1][1], 0, 0, 0);
;       __builtin_amdgcn_s_setprio(0);
;     }
;     __syncthreads();
	global_load_dwordx4 v[130:133], v[64:65], off offset:1408
	global_load_dwordx4 v[134:137], v[106:107], off offset:1408
	ds_read_b128 v[146:149], v104 offset:36864
	ds_read_b128 v[150:153], v104 offset:41472
	ds_read_b128 v[154:157], v101 offset:55296
	ds_read_b128 v[158:161], v101 offset:59904
	s_waitcnt vmcnt(9)
	ds_write_b128 v100, v[66:69]
	s_waitcnt vmcnt(8)
	ds_write_b128 v100, v[110:113] offset:18432
	ds_read_b128 v[66:69], v104 offset:36896
	ds_read_b128 v[110:113], v104 offset:41504
	ds_read_b128 v[162:165], v101 offset:55328
	ds_read_b128 v[166:169], v101 offset:59936
	s_waitcnt lgkmcnt(7)
	v_mfma_f32_32x32x16_bf16 v[16:31], v[146:149], v[154:157], v[16:31]
	s_waitcnt lgkmcnt(6)
	v_mfma_f32_32x32x16_bf16 v[48:63], v[146:149], v[158:161], v[48:63]
	v_mfma_f32_32x32x16_bf16 v[0:15], v[150:153], v[154:157], v[0:15]
	v_mfma_f32_32x32x16_bf16 v[32:47], v[150:153], v[158:161], v[32:47]
	global_load_dwordx4 v[146:149], v[72:73], off offset:1408
	global_load_dwordx4 v[150:153], v[76:77], off offset:1408
	s_waitcnt vmcnt(9)
	ds_write_b128 v100, v[138:141] offset:4608
	s_waitcnt vmcnt(8)
	ds_write_b128 v100, v[142:145] offset:23040
	ds_read_b128 v[138:141], v104 offset:36928
	ds_read_b128 v[142:145], v104 offset:41536
	ds_read_b128 v[154:157], v101 offset:55360
	ds_read_b128 v[158:161], v101 offset:59968
	s_waitcnt lgkmcnt(7)
	v_mfma_f32_32x32x16_bf16 v[16:31], v[66:69], v[162:165], v[16:31]
	s_waitcnt lgkmcnt(6)
	v_mfma_f32_32x32x16_bf16 v[48:63], v[66:69], v[166:169], v[48:63]
	v_mfma_f32_32x32x16_bf16 v[0:15], v[110:113], v[162:165], v[0:15]
	v_mfma_f32_32x32x16_bf16 v[32:47], v[110:113], v[166:169], v[32:47]
	global_load_dwordx4 v[66:69], v[80:81], off offset:1408
	global_load_dwordx4 v[110:113], v[84:85], off offset:1408
	s_waitcnt vmcnt(9)
	ds_write_b128 v100, v[114:117] offset:9216
	s_waitcnt vmcnt(8)
	ds_write_b128 v100, v[118:121] offset:27648
	ds_read_b128 v[114:117], v104 offset:36960
	ds_read_b128 v[118:121], v104 offset:41568
	ds_read_b128 v[162:165], v101 offset:55392
	ds_read_b128 v[166:169], v101 offset:60000
	s_waitcnt lgkmcnt(7)
	v_mfma_f32_32x32x16_bf16 v[16:31], v[138:141], v[154:157], v[16:31]
	s_waitcnt lgkmcnt(6)
	v_mfma_f32_32x32x16_bf16 v[48:63], v[138:141], v[158:161], v[48:63]
	v_mfma_f32_32x32x16_bf16 v[0:15], v[142:145], v[154:157], v[0:15]
	v_mfma_f32_32x32x16_bf16 v[32:47], v[142:145], v[158:161], v[32:47]
	global_load_dwordx4 v[138:141], v[88:89], off offset:1408
	global_load_dwordx4 v[142:145], v[92:93], off offset:1408
	s_waitcnt vmcnt(9)
	ds_write_b128 v100, v[122:125] offset:13824
	s_waitcnt vmcnt(8)
	ds_write_b128 v100, v[126:129] offset:32256
	s_waitcnt lgkmcnt(3)
	v_mfma_f32_32x32x16_bf16 v[16:31], v[114:117], v[162:165], v[16:31]
	s_waitcnt lgkmcnt(2)
	v_mfma_f32_32x32x16_bf16 v[48:63], v[114:117], v[166:169], v[48:63]
	v_mfma_f32_32x32x16_bf16 v[0:15], v[118:121], v[162:165], v[0:15]
	v_mfma_f32_32x32x16_bf16 v[32:47], v[118:121], v[166:169], v[32:47]
	s_waitcnt lgkmcnt(0)
	s_barrier
	global_load_dwordx4 v[114:117], v[64:65], off offset:1536
	global_load_dwordx4 v[118:121], v[106:107], off offset:1536
	ds_read_b128 v[122:125], v104
	ds_read_b128 v[126:129], v104 offset:4608
	ds_read_b128 v[154:157], v101 offset:18432
	ds_read_b128 v[158:161], v101 offset:23040
	s_waitcnt vmcnt(9)
	ds_write_b128 v100, v[130:133] offset:36864
	s_waitcnt vmcnt(8)
	ds_write_b128 v100, v[134:137] offset:55296
	ds_read_b128 v[130:133], v104 offset:32
	ds_read_b128 v[134:137], v104 offset:4640
	ds_read_b128 v[162:165], v101 offset:18464
	ds_read_b128 v[166:169], v101 offset:23072
	s_waitcnt lgkmcnt(7)
	v_mfma_f32_32x32x16_bf16 v[16:31], v[122:125], v[154:157], v[16:31]
	s_waitcnt lgkmcnt(6)
	v_mfma_f32_32x32x16_bf16 v[48:63], v[122:125], v[158:161], v[48:63]
	v_mfma_f32_32x32x16_bf16 v[0:15], v[126:129], v[154:157], v[0:15]
	v_mfma_f32_32x32x16_bf16 v[32:47], v[126:129], v[158:161], v[32:47]
	global_load_dwordx4 v[122:125], v[72:73], off offset:1536
	global_load_dwordx4 v[126:129], v[76:77], off offset:1536
	s_waitcnt vmcnt(9)
	ds_write_b128 v100, v[146:149] offset:41472
	s_waitcnt vmcnt(8)
	ds_write_b128 v100, v[150:153] offset:59904
	ds_read_b128 v[146:149], v104 offset:64
	ds_read_b128 v[150:153], v104 offset:4672
	ds_read_b128 v[154:157], v101 offset:18496
	ds_read_b128 v[158:161], v101 offset:23104
	s_waitcnt lgkmcnt(7)
	v_mfma_f32_32x32x16_bf16 v[16:31], v[130:133], v[162:165], v[16:31]
	s_waitcnt lgkmcnt(6)
	v_mfma_f32_32x32x16_bf16 v[48:63], v[130:133], v[166:169], v[48:63]
	v_mfma_f32_32x32x16_bf16 v[0:15], v[134:137], v[162:165], v[0:15]
	v_mfma_f32_32x32x16_bf16 v[32:47], v[134:137], v[166:169], v[32:47]
	global_load_dwordx4 v[130:133], v[80:81], off offset:1536
	global_load_dwordx4 v[134:137], v[84:85], off offset:1536
	s_waitcnt vmcnt(9)
	ds_write_b128 v100, v[66:69] offset:46080
	s_waitcnt vmcnt(8)
	ds_write_b128 v100, v[110:113] offset:64512
	ds_read_b128 v[66:69], v104 offset:96
	ds_read_b128 v[110:113], v104 offset:4704
	ds_read_b128 v[162:165], v101 offset:18528
	ds_read_b128 v[166:169], v101 offset:23136
	s_waitcnt lgkmcnt(7)
	v_mfma_f32_32x32x16_bf16 v[16:31], v[146:149], v[154:157], v[16:31]
	s_waitcnt lgkmcnt(6)
	v_mfma_f32_32x32x16_bf16 v[48:63], v[146:149], v[158:161], v[48:63]
	v_mfma_f32_32x32x16_bf16 v[0:15], v[150:153], v[154:157], v[0:15]
	v_mfma_f32_32x32x16_bf16 v[32:47], v[150:153], v[158:161], v[32:47]
	global_load_dwordx4 v[146:149], v[88:89], off offset:1536
	global_load_dwordx4 v[150:153], v[92:93], off offset:1536
	s_waitcnt vmcnt(9)
	ds_write_b128 v100, v[138:141] offset:50688
	s_waitcnt vmcnt(8)
	ds_write_b128 v105, v[142:145] offset:13824
	s_waitcnt lgkmcnt(3)
	v_mfma_f32_32x32x16_bf16 v[16:31], v[66:69], v[162:165], v[16:31]
	s_waitcnt lgkmcnt(2)
	v_mfma_f32_32x32x16_bf16 v[48:63], v[66:69], v[166:169], v[48:63]
	v_mfma_f32_32x32x16_bf16 v[0:15], v[110:113], v[162:165], v[0:15]
	v_mfma_f32_32x32x16_bf16 v[32:47], v[110:113], v[166:169], v[32:47]
	s_waitcnt lgkmcnt(0)
	s_barrier
; __device__ __forceinline__ void gemm_run(int tid, f32x16 (&acc)[2][2], GRegs& g, const GOp& o, int K, unsigned char* smem) {
;     ...
;   for (int k = 0; k < nk; k++) {
;     bf16r* cur = sbuf + (k & 1) * (256 * LDK);
;     bf16r* nxt = sbuf + ((k & 1) ^ 1) * (256 * LDK);
;     const bf16r* As = cur + (wm * 64 + fr) * LDK + fh * 8;
;     const bf16r* Bs = cur + 128 * LDK + (wn * 64 + fr) * LDK + fh * 8;
;     const bool wr = (k + 1 < nk), ld = (k + 2 < nk);
;     bf16x8 fa[2][2], fb[2][2];
;     fa[0][0] = *(const bf16x8*)(As);
;     fa[0][1] = *(const bf16x8*)(As + 32 * LDK);
;     fb[0][0] = *(const bf16x8*)(Bs);
;     fb[0][1] = *(const bf16x8*)(Bs + 32 * LDK);
; #pragma unroll
;     for (int i = 0; i < 4; i++) {
;       if (wr) {
;         *(u32x4*)(nxt + (r0 + i * 32) * LDK + sg * 8) = g.a[i];
;         *(u32x4*)(nxt + 128 * LDK + (r0 + i * 32) * LDK + sg * 8) = g.b[i];
;       }
;       if (ld) {
;         g.a[i] = *(const u32x4*)(Ap + (size_t)i * 32 * o.lda + (k + 2) * 64);
;         g.b[i] = *(const u32x4*)(Bp + o.bs.o[i] + (k + 2) * 64);
;       }
;       if (i < 3) {
;         fa[(i + 1) & 1][0] = *(const bf16x8*)(As + (i + 1) * 16);
;         fa[(i + 1) & 1][1] = *(const bf16x8*)(As + 32 * LDK + (i + 1) * 16);
;         fb[(i + 1) & 1][0] = *(const bf16x8*)(Bs + (i + 1) * 16);
;         fb[(i + 1) & 1][1] = *(const bf16x8*)(Bs + 32 * LDK + (i + 1) * 16);
;       }
;       __builtin_amdgcn_sched_barrier(0);
;       __builtin_amdgcn_s_setprio(1);
;       acc[0][0] = __builtin_amdgcn_mfma_f32_32x32x16_bf16(fa[i & 1][0], fb[i & 1][0], acc[0][0], 0, 0, 0);
;       acc[0][1] = __builtin_amdgcn_mfma_f32_32x32x16_bf16(fa[i & 1][0], fb[i & 1][1], acc[0][1], 0, 0, 0);
;       acc[1][0] = __builtin_amdgcn_mfma_f32_32x32x16_bf16(fa[i & 1][1], fb[i & 1][0], acc[1][0], 0, 0, 0);
;       acc[1][1] = __builtin_amdgcn_mfma_f32_32x32x16_bf16(fa[i & 1][1], fb[i & 1][1], acc[1][1], 0, 0, 0);
;       __builtin_amdgcn_s_setprio(0);
;     }
;     __syncthreads();
	global_load_dwordx4 v[66:69], v[64:65], off offset:1664
	global_load_dwordx4 v[110:113], v[106:107], off offset:1664
	ds_read_b128 v[138:141], v104 offset:36864
	ds_read_b128 v[142:145], v104 offset:41472
	ds_read_b128 v[154:157], v101 offset:55296
	ds_read_b128 v[158:161], v101 offset:59904
	s_waitcnt vmcnt(9)
	ds_write_b128 v100, v[114:117]
	s_waitcnt vmcnt(8)
	ds_write_b128 v100, v[118:121] offset:18432
	ds_read_b128 v[114:117], v104 offset:36896
	ds_read_b128 v[118:121], v104 offset:41504
	ds_read_b128 v[162:165], v101 offset:55328
	ds_read_b128 v[166:169], v101 offset:59936
	s_waitcnt lgkmcnt(7)
	v_mfma_f32_32x32x16_bf16 v[16:31], v[138:141], v[154:157], v[16:31]
	s_waitcnt lgkmcnt(6)
	v_mfma_f32_32x32x16_bf16 v[48:63], v[138:141], v[158:161], v[48:63]
	v_mfma_f32_32x32x16_bf16 v[0:15], v[142:145], v[154:157], v[0:15]
	v_mfma_f32_32x32x16_bf16 v[32:47], v[142:145], v[158:161], v[32:47]
	global_load_dwordx4 v[138:141], v[72:73], off offset:1664
	global_load_dwordx4 v[142:145], v[76:77], off offset:1664
	s_waitcnt vmcnt(9)
	ds_write_b128 v100, v[122:125] offset:4608
	s_waitcnt vmcnt(8)
	ds_write_b128 v100, v[126:129] offset:23040
	ds_read_b128 v[122:125], v104 offset:36928
	ds_read_b128 v[126:129], v104 offset:41536
	ds_read_b128 v[154:157], v101 offset:55360
	ds_read_b128 v[158:161], v101 offset:59968
	s_waitcnt lgkmcnt(7)
	v_mfma_f32_32x32x16_bf16 v[16:31], v[114:117], v[162:165], v[16:31]
	s_waitcnt lgkmcnt(6)
	v_mfma_f32_32x32x16_bf16 v[48:63], v[114:117], v[166:169], v[48:63]
	v_mfma_f32_32x32x16_bf16 v[0:15], v[118:121], v[162:165], v[0:15]
	v_mfma_f32_32x32x16_bf16 v[32:47], v[118:121], v[166:169], v[32:47]
	global_load_dwordx4 v[114:117], v[80:81], off offset:1664
	global_load_dwordx4 v[118:121], v[84:85], off offset:1664
	s_waitcnt vmcnt(9)
	ds_write_b128 v100, v[130:133] offset:9216
	s_waitcnt vmcnt(8)
	ds_write_b128 v100, v[134:137] offset:27648
	ds_read_b128 v[130:133], v104 offset:36960
	ds_read_b128 v[134:137], v104 offset:41568
	ds_read_b128 v[162:165], v101 offset:55392
	ds_read_b128 v[166:169], v101 offset:60000
	s_waitcnt lgkmcnt(7)
	v_mfma_f32_32x32x16_bf16 v[16:31], v[122:125], v[154:157], v[16:31]
	s_waitcnt lgkmcnt(6)
	v_mfma_f32_32x32x16_bf16 v[48:63], v[122:125], v[158:161], v[48:63]
	v_mfma_f32_32x32x16_bf16 v[0:15], v[126:129], v[154:157], v[0:15]
	v_mfma_f32_32x32x16_bf16 v[32:47], v[126:129], v[158:161], v[32:47]
	global_load_dwordx4 v[122:125], v[88:89], off offset:1664
	global_load_dwordx4 v[126:129], v[92:93], off offset:1664
	s_waitcnt vmcnt(9)
	ds_write_b128 v100, v[146:149] offset:13824
	s_waitcnt vmcnt(8)
	ds_write_b128 v100, v[150:153] offset:32256
	s_waitcnt lgkmcnt(3)
	v_mfma_f32_32x32x16_bf16 v[16:31], v[130:133], v[162:165], v[16:31]
	s_waitcnt lgkmcnt(2)
	v_mfma_f32_32x32x16_bf16 v[48:63], v[130:133], v[166:169], v[48:63]
	v_mfma_f32_32x32x16_bf16 v[0:15], v[134:137], v[162:165], v[0:15]
	v_mfma_f32_32x32x16_bf16 v[32:47], v[134:137], v[166:169], v[32:47]
	s_waitcnt lgkmcnt(0)
	s_barrier
	global_load_dwordx4 v[130:133], v[64:65], off offset:1792
	global_load_dwordx4 v[134:137], v[106:107], off offset:1792
	ds_read_b128 v[146:149], v104
	ds_read_b128 v[150:153], v104 offset:4608
	ds_read_b128 v[154:157], v101 offset:18432
	ds_read_b128 v[158:161], v101 offset:23040
	s_waitcnt vmcnt(9)
	ds_write_b128 v100, v[66:69] offset:36864
	s_waitcnt vmcnt(8)
	ds_write_b128 v100, v[110:113] offset:55296
	ds_read_b128 v[66:69], v104 offset:32
	ds_read_b128 v[110:113], v104 offset:4640
	ds_read_b128 v[162:165], v101 offset:18464
	ds_read_b128 v[166:169], v101 offset:23072
	s_waitcnt lgkmcnt(7)
	v_mfma_f32_32x32x16_bf16 v[16:31], v[146:149], v[154:157], v[16:31]
	s_waitcnt lgkmcnt(6)
	v_mfma_f32_32x32x16_bf16 v[48:63], v[146:149], v[158:161], v[48:63]
	v_mfma_f32_32x32x16_bf16 v[0:15], v[150:153], v[154:157], v[0:15]
	v_mfma_f32_32x32x16_bf16 v[32:47], v[150:153], v[158:161], v[32:47]
	global_load_dwordx4 v[146:149], v[72:73], off offset:1792
	global_load_dwordx4 v[150:153], v[76:77], off offset:1792
	s_waitcnt vmcnt(9)
	ds_write_b128 v100, v[138:141] offset:41472
	s_waitcnt vmcnt(8)
	ds_write_b128 v100, v[142:145] offset:59904
	ds_read_b128 v[138:141], v104 offset:64
	ds_read_b128 v[142:145], v104 offset:4672
	ds_read_b128 v[154:157], v101 offset:18496
	ds_read_b128 v[158:161], v101 offset:23104
	s_waitcnt lgkmcnt(7)
	v_mfma_f32_32x32x16_bf16 v[16:31], v[66:69], v[162:165], v[16:31]
	s_waitcnt lgkmcnt(6)
	v_mfma_f32_32x32x16_bf16 v[48:63], v[66:69], v[166:169], v[48:63]
	v_mfma_f32_32x32x16_bf16 v[0:15], v[110:113], v[162:165], v[0:15]
	v_mfma_f32_32x32x16_bf16 v[32:47], v[110:113], v[166:169], v[32:47]
	global_load_dwordx4 v[110:113], v[80:81], off offset:1792
	global_load_dwordx4 v[162:165], v[84:85], off offset:1792
	s_waitcnt vmcnt(9)
	ds_write_b128 v100, v[114:117] offset:46080
	s_waitcnt vmcnt(8)
	ds_write_b128 v100, v[118:121] offset:64512
	ds_read_b128 v[66:69], v104 offset:96
	ds_read_b128 v[114:117], v104 offset:4704
	ds_read_b128 v[118:121], v101 offset:18528
	ds_read_b128 v[166:169], v101 offset:23136
	s_waitcnt lgkmcnt(7)
	v_mfma_f32_32x32x16_bf16 v[16:31], v[138:141], v[154:157], v[16:31]
	s_waitcnt lgkmcnt(6)
	v_mfma_f32_32x32x16_bf16 v[48:63], v[138:141], v[158:161], v[48:63]
	v_mfma_f32_32x32x16_bf16 v[0:15], v[142:145], v[154:157], v[0:15]
	v_mfma_f32_32x32x16_bf16 v[32:47], v[142:145], v[158:161], v[32:47]
	global_load_dwordx4 v[138:141], v[88:89], off offset:1792
	global_load_dwordx4 v[142:145], v[92:93], off offset:1792
	s_waitcnt vmcnt(9)
	ds_write_b128 v100, v[122:125] offset:50688
	s_waitcnt vmcnt(8)
	ds_write_b128 v105, v[126:129] offset:13824
	s_waitcnt lgkmcnt(3)
	v_mfma_f32_32x32x16_bf16 v[16:31], v[66:69], v[118:121], v[16:31]
	s_waitcnt lgkmcnt(2)
	v_mfma_f32_32x32x16_bf16 v[48:63], v[66:69], v[166:169], v[48:63]
	v_mfma_f32_32x32x16_bf16 v[0:15], v[114:117], v[118:121], v[0:15]
	v_mfma_f32_32x32x16_bf16 v[32:47], v[114:117], v[166:169], v[32:47]
	s_waitcnt lgkmcnt(0)
	s_barrier
; __device__ __forceinline__ void gemm_run(int tid, f32x16 (&acc)[2][2], GRegs& g, const GOp& o, int K, unsigned char* smem) {
;     ...
;   for (int k = 0; k < nk; k++) {
;     bf16r* cur = sbuf + (k & 1) * (256 * LDK);
;     bf16r* nxt = sbuf + ((k & 1) ^ 1) * (256 * LDK);
;     const bf16r* As = cur + (wm * 64 + fr) * LDK + fh * 8;
;     const bf16r* Bs = cur + 128 * LDK + (wn * 64 + fr) * LDK + fh * 8;
;     const bool wr = (k + 1 < nk), ld = (k + 2 < nk);
;     bf16x8 fa[2][2], fb[2][2];
;     fa[0][0] = *(const bf16x8*)(As);
;     fa[0][1] = *(const bf16x8*)(As + 32 * LDK);
;     fb[0][0] = *(const bf16x8*)(Bs);
;     fb[0][1] = *(const bf16x8*)(Bs + 32 * LDK);
; #pragma unroll
;     for (int i = 0; i < 4; i++) {
;       if (wr) {
;         *(u32x4*)(nxt + (r0 + i * 32) * LDK + sg * 8) = g.a[i];
;         *(u32x4*)(nxt + 128 * LDK + (r0 + i * 32) * LDK + sg * 8) = g.b[i];
;       }
;       if (ld) {
;         g.a[i] = *(const u32x4*)(Ap + (size_t)i * 32 * o.lda + (k + 2) * 64);
;         g.b[i] = *(const u32x4*)(Bp + o.bs.o[i] + (k + 2) * 64);
;       }
;       if (i < 3) {
;         fa[(i + 1) & 1][0] = *(const bf16x8*)(As + (i + 1) * 16);
;         fa[(i + 1) & 1][1] = *(const bf16x8*)(As + 32 * LDK + (i + 1) * 16);
;         fb[(i + 1) & 1][0] = *(const bf16x8*)(Bs + (i + 1) * 16);
;         fb[(i + 1) & 1][1] = *(const bf16x8*)(Bs + 32 * LDK + (i + 1) * 16);
;       }
;       __builtin_amdgcn_sched_barrier(0);
;       __builtin_amdgcn_s_setprio(1);
;       acc[0][0] = __builtin_amdgcn_mfma_f32_32x32x16_bf16(fa[i & 1][0], fb[i & 1][0], acc[0][0], 0, 0, 0);
;       acc[0][1] = __builtin_amdgcn_mfma_f32_32x32x16_bf16(fa[i & 1][0], fb[i & 1][1], acc[0][1], 0, 0, 0);
;       acc[1][0] = __builtin_amdgcn_mfma_f32_32x32x16_bf16(fa[i & 1][1], fb[i & 1][0], acc[1][0], 0, 0, 0);
;       acc[1][1] = __builtin_amdgcn_mfma_f32_32x32x16_bf16(fa[i & 1][1], fb[i & 1][1], acc[1][1], 0, 0, 0);
;       __builtin_amdgcn_s_setprio(0);
;     }
;     __syncthreads();
	global_load_dwordx4 v[64:67], v[64:65], off offset:1920
	s_nop 0
	global_load_dwordx4 v[68:71], v[106:107], off offset:1920
	ds_read_b128 v[114:117], v104 offset:36864
	ds_read_b128 v[118:121], v104 offset:41472
	ds_read_b128 v[122:125], v101 offset:55296
	ds_read_b128 v[126:129], v101 offset:59904
	s_waitcnt vmcnt(9)
	ds_write_b128 v100, v[130:133]
	s_waitcnt vmcnt(8)
	ds_write_b128 v100, v[134:137] offset:18432
	ds_read_b128 v[130:133], v104 offset:36896
	ds_read_b128 v[134:137], v104 offset:41504
	ds_read_b128 v[154:157], v101 offset:55328
	ds_read_b128 v[158:161], v101 offset:59936
	s_waitcnt lgkmcnt(7)
	v_mfma_f32_32x32x16_bf16 v[16:31], v[114:117], v[122:125], v[16:31]
	s_waitcnt lgkmcnt(6)
	v_mfma_f32_32x32x16_bf16 v[48:63], v[114:117], v[126:129], v[48:63]
	v_mfma_f32_32x32x16_bf16 v[0:15], v[118:121], v[122:125], v[0:15]
	v_mfma_f32_32x32x16_bf16 v[32:47], v[118:121], v[126:129], v[32:47]
	global_load_dwordx4 v[72:75], v[72:73], off offset:1920
	s_nop 0
	global_load_dwordx4 v[76:79], v[76:77], off offset:1920
	s_waitcnt vmcnt(9)
	ds_write_b128 v100, v[146:149] offset:4608
	s_waitcnt vmcnt(8)
	ds_write_b128 v100, v[150:153] offset:23040
	ds_read_b128 v[114:117], v104 offset:36928
	ds_read_b128 v[118:121], v104 offset:41536
	ds_read_b128 v[122:125], v101 offset:55360
	ds_read_b128 v[126:129], v101 offset:59968
	s_waitcnt lgkmcnt(7)
	v_mfma_f32_32x32x16_bf16 v[16:31], v[130:133], v[154:157], v[16:31]
	s_waitcnt lgkmcnt(6)
	v_mfma_f32_32x32x16_bf16 v[48:63], v[130:133], v[158:161], v[48:63]
	v_mfma_f32_32x32x16_bf16 v[0:15], v[134:137], v[154:157], v[0:15]
	v_mfma_f32_32x32x16_bf16 v[32:47], v[134:137], v[158:161], v[32:47]
	global_load_dwordx4 v[80:83], v[80:81], off offset:1920
	s_nop 0
	global_load_dwordx4 v[84:87], v[84:85], off offset:1920
	s_waitcnt vmcnt(9)
	ds_write_b128 v100, v[110:113] offset:9216
	s_waitcnt vmcnt(8)
	ds_write_b128 v100, v[162:165] offset:27648
	ds_read_b128 v[110:113], v104 offset:36960
	ds_read_b128 v[130:133], v104 offset:41568
	ds_read_b128 v[134:137], v101 offset:55392
	ds_read_b128 v[146:149], v101 offset:60000
	s_waitcnt lgkmcnt(7)
	v_mfma_f32_32x32x16_bf16 v[16:31], v[114:117], v[122:125], v[16:31]
	s_waitcnt lgkmcnt(6)
	v_mfma_f32_32x32x16_bf16 v[48:63], v[114:117], v[126:129], v[48:63]
	v_mfma_f32_32x32x16_bf16 v[0:15], v[118:121], v[122:125], v[0:15]
	v_mfma_f32_32x32x16_bf16 v[32:47], v[118:121], v[126:129], v[32:47]
	global_load_dwordx4 v[88:91], v[88:89], off offset:1920
	s_nop 0
	global_load_dwordx4 v[92:95], v[92:93], off offset:1920
	s_waitcnt vmcnt(9)
	ds_write_b128 v100, v[138:141] offset:13824
	s_waitcnt vmcnt(8)
	ds_write_b128 v100, v[142:145] offset:32256
	s_waitcnt lgkmcnt(3)
	v_mfma_f32_32x32x16_bf16 v[16:31], v[110:113], v[134:137], v[16:31]
	s_waitcnt lgkmcnt(2)
	v_mfma_f32_32x32x16_bf16 v[48:63], v[110:113], v[146:149], v[48:63]
	v_mfma_f32_32x32x16_bf16 v[0:15], v[130:133], v[134:137], v[0:15]
	v_mfma_f32_32x32x16_bf16 v[32:47], v[130:133], v[146:149], v[32:47]
	s_waitcnt lgkmcnt(0)
	s_barrier
; __device__ __forceinline__ void gemm_run(int tid, f32x16 (&acc)[2][2], GRegs& g, const GOp& o, int K, unsigned char* smem) {
;     ...
;   for (int k = 0; k < nk; k++) {
;     bf16r* cur = sbuf + (k & 1) * (256 * LDK);
;     bf16r* nxt = sbuf + ((k & 1) ^ 1) * (256 * LDK);
;     const bf16r* As = cur + (wm * 64 + fr) * LDK + fh * 8;
;     const bf16r* Bs = cur + 128 * LDK + (wn * 64 + fr) * LDK + fh * 8;
;     const bool wr = (k + 1 < nk), ld = (k + 2 < nk);
;     bf16x8 fa[2][2], fb[2][2];
;     fa[0][0] = *(const bf16x8*)(As);
;     fa[0][1] = *(const bf16x8*)(As + 32 * LDK);
;     fb[0][0] = *(const bf16x8*)(Bs);
;     fb[0][1] = *(const bf16x8*)(Bs + 32 * LDK);
; #pragma unroll
;     for (int i = 0; i < 4; i++) {
;       if (wr) {
;         *(u32x4*)(nxt + (r0 + i * 32) * LDK + sg * 8) = g.a[i];
;         *(u32x4*)(nxt + 128 * LDK + (r0 + i * 32) * LDK + sg * 8) = g.b[i];
;       }
;       if (ld) {
;         g.a[i] = *(const u32x4*)(Ap + (size_t)i * 32 * o.lda + (k + 2) * 64);
;         g.b[i] = *(const u32x4*)(Bp + o.bs.o[i] + (k + 2) * 64);
;       }
;       if (i < 3) {
;         fa[(i + 1) & 1][0] = *(const bf16x8*)(As + (i + 1) * 16);
;         fa[(i + 1) & 1][1] = *(const bf16x8*)(As + 32 * LDK + (i + 1) * 16);
;         fb[(i + 1) & 1][0] = *(const bf16x8*)(Bs + (i + 1) * 16);
;         fb[(i + 1) & 1][1] = *(const bf16x8*)(Bs + 32 * LDK + (i + 1) * 16);
;       }
;       __builtin_amdgcn_sched_barrier(0);
;       __builtin_amdgcn_s_setprio(1);
;       acc[0][0] = __builtin_amdgcn_mfma_f32_32x32x16_bf16(fa[i & 1][0], fb[i & 1][0], acc[0][0], 0, 0, 0);
;       acc[0][1] = __builtin_amdgcn_mfma_f32_32x32x16_bf16(fa[i & 1][0], fb[i & 1][1], acc[0][1], 0, 0, 0);
;       acc[1][0] = __builtin_amdgcn_mfma_f32_32x32x16_bf16(fa[i & 1][1], fb[i & 1][0], acc[1][0], 0, 0, 0);
;       acc[1][1] = __builtin_amdgcn_mfma_f32_32x32x16_bf16(fa[i & 1][1], fb[i & 1][1], acc[1][1], 0, 0, 0);
;       __builtin_amdgcn_s_setprio(0);
;     }
;     __syncthreads();
;   }
; __device__ __forceinline__ bool tile_map(int it, int nn, int& mt, int& nt) {
;   const int xcd = blockIdx.x & 7, li = blockIdx.x >> 3, nb = gridDim.x >> 3;
;   int q = it * nb + li;
;   const int per = 16 * nn;
;   if (q < per) {
;     int sub = q / (8 * nn), r = q - sub * (8 * nn);
;     nt = r >> 3;
;     mt = xcd * 16 + sub * 8 + (r & 7);
;     return true;
;   }
;   q -= per;
;   int n = q * 8 + xcd;
	ds_read_b128 v[110:113], v104
	ds_read_b128 v[114:117], v104 offset:4608
	ds_read_b128 v[118:121], v101 offset:18432
	ds_read_b128 v[122:125], v101 offset:23040
	s_waitcnt vmcnt(7)
	ds_write_b128 v100, v[64:67] offset:36864
	s_waitcnt vmcnt(6)
	ds_write_b128 v100, v[68:71] offset:55296
	ds_read_b128 v[126:129], v104 offset:32
	ds_read_b128 v[130:133], v104 offset:4640
	ds_read_b128 v[134:137], v101 offset:18464
	ds_read_b128 v[138:141], v101 offset:23072
	s_waitcnt lgkmcnt(7)
	v_mfma_f32_32x32x16_bf16 v[16:31], v[110:113], v[118:121], v[16:31]
	s_waitcnt lgkmcnt(6)
	v_mfma_f32_32x32x16_bf16 v[48:63], v[110:113], v[122:125], v[48:63]
	v_mfma_f32_32x32x16_bf16 v[0:15], v[114:117], v[118:121], v[0:15]
	v_mfma_f32_32x32x16_bf16 v[32:47], v[114:117], v[122:125], v[32:47]
	s_waitcnt vmcnt(5)
	ds_write_b128 v100, v[72:75] offset:41472
	s_waitcnt vmcnt(4)
	ds_write_b128 v100, v[76:79] offset:59904
	ds_read_b128 v[110:113], v104 offset:64
	ds_read_b128 v[114:117], v104 offset:4672
	ds_read_b128 v[118:121], v101 offset:18496
	ds_read_b128 v[122:125], v101 offset:23104
	s_waitcnt lgkmcnt(7)
	v_mfma_f32_32x32x16_bf16 v[16:31], v[126:129], v[134:137], v[16:31]
	s_waitcnt lgkmcnt(6)
	v_mfma_f32_32x32x16_bf16 v[48:63], v[126:129], v[138:141], v[48:63]
	v_mfma_f32_32x32x16_bf16 v[0:15], v[130:133], v[134:137], v[0:15]
	v_mfma_f32_32x32x16_bf16 v[32:47], v[130:133], v[138:141], v[32:47]
	s_waitcnt vmcnt(3)
	ds_write_b128 v100, v[80:83] offset:46080
	s_waitcnt vmcnt(2)
	ds_write_b128 v100, v[84:87] offset:64512
	ds_read_b128 v[126:129], v104 offset:96
	ds_read_b128 v[130:133], v104 offset:4704
	ds_read_b128 v[134:137], v101 offset:18528
	ds_read_b128 v[138:141], v101 offset:23136
	s_waitcnt lgkmcnt(7)
	v_mfma_f32_32x32x16_bf16 v[16:31], v[110:113], v[118:121], v[16:31]
	s_waitcnt lgkmcnt(6)
	v_mfma_f32_32x32x16_bf16 v[48:63], v[110:113], v[122:125], v[48:63]
	v_mfma_f32_32x32x16_bf16 v[0:15], v[114:117], v[118:121], v[0:15]
	v_mfma_f32_32x32x16_bf16 v[32:47], v[114:117], v[122:125], v[32:47]
	s_waitcnt vmcnt(1)
	ds_write_b128 v100, v[88:91] offset:50688
	s_waitcnt vmcnt(0)
	ds_write_b128 v105, v[92:95] offset:13824
	s_waitcnt lgkmcnt(3)
	v_mfma_f32_32x32x16_bf16 v[16:31], v[126:129], v[134:137], v[16:31]
	s_waitcnt lgkmcnt(2)
	v_mfma_f32_32x32x16_bf16 v[48:63], v[126:129], v[138:141], v[48:63]
	v_mfma_f32_32x32x16_bf16 v[0:15], v[130:133], v[134:137], v[0:15]
	v_mfma_f32_32x32x16_bf16 v[32:47], v[130:133], v[138:141], v[32:47]
	s_waitcnt lgkmcnt(0)
	s_barrier
	ds_read_b128 v[110:113], v104 offset:36864
	ds_read_b128 v[114:117], v104 offset:36896
	ds_read_b128 v[118:121], v104 offset:41472
	ds_read_b128 v[122:125], v104 offset:41504
	ds_read_b128 v[126:129], v101 offset:55296
	ds_read_b128 v[130:133], v101 offset:55328
	ds_read_b128 v[134:137], v101 offset:59904
	ds_read_b128 v[138:141], v101 offset:59936
	s_waitcnt lgkmcnt(3)
	v_mfma_f32_32x32x16_bf16 v[16:31], v[110:113], v[126:129], v[16:31]
	s_waitcnt lgkmcnt(1)
	v_mfma_f32_32x32x16_bf16 v[48:63], v[110:113], v[134:137], v[48:63]
	v_mfma_f32_32x32x16_bf16 v[0:15], v[118:121], v[126:129], v[0:15]
	v_mfma_f32_32x32x16_bf16 v[32:47], v[118:121], v[134:137], v[32:47]
	ds_read_b128 v[110:113], v104 offset:36928
	ds_read_b128 v[118:121], v104 offset:41536
	ds_read_b128 v[126:129], v101 offset:55360
	ds_read_b128 v[134:137], v101 offset:59968
	v_mfma_f32_32x32x16_bf16 v[16:31], v[114:117], v[130:133], v[16:31]
	s_waitcnt lgkmcnt(4)
	v_mfma_f32_32x32x16_bf16 v[48:63], v[114:117], v[138:141], v[48:63]
	v_mfma_f32_32x32x16_bf16 v[0:15], v[122:125], v[130:133], v[0:15]
	v_mfma_f32_32x32x16_bf16 v[32:47], v[122:125], v[138:141], v[32:47]
	ds_read_b128 v[114:117], v104 offset:36960
	ds_read_b128 v[122:125], v104 offset:41568
	ds_read_b128 v[130:133], v101 offset:55392
	ds_read_b128 v[138:141], v101 offset:60000
	s_waitcnt lgkmcnt(5)
	v_mfma_f32_32x32x16_bf16 v[16:31], v[110:113], v[126:129], v[16:31]
	s_waitcnt lgkmcnt(4)
	v_mfma_f32_32x32x16_bf16 v[48:63], v[110:113], v[134:137], v[48:63]
	v_mfma_f32_32x32x16_bf16 v[0:15], v[118:121], v[126:129], v[0:15]
	v_mfma_f32_32x32x16_bf16 v[32:47], v[118:121], v[134:137], v[32:47]
	s_waitcnt lgkmcnt(1)
	v_mfma_f32_32x32x16_bf16 v[16:31], v[114:117], v[130:133], v[16:31]
	s_waitcnt lgkmcnt(0)
	v_mfma_f32_32x32x16_bf16 v[48:63], v[114:117], v[138:141], v[48:63]
	v_mfma_f32_32x32x16_bf16 v[0:15], v[122:125], v[130:133], v[0:15]
	v_mfma_f32_32x32x16_bf16 v[32:47], v[122:125], v[138:141], v[32:47]
	s_cmpk_gt_u32 s87, 0x17f
	s_mov_b64 s[10:11], -1
	s_barrier
	s_cbranch_scc0 .LBB0_2658
	s_mov_b64 s[10:11], 0
	s_cmp_gt_i32 s52, 23
	s_mov_b64 s[4:5], 0
	s_cbranch_scc1 .LBB0_2658
	s_movk_i32 s84, 0x80
	s_mov_b64 s[4:5], -1
	s_mov_b32 s56, s52

; __device__ __forceinline__ void gemm_run(int tid, f32x16 (&acc)[2][2], GRegs& g, const GOp& o, int K, unsigned char* smem) {
;     ...
;   const int nk = K >> 6;
; #pragma unroll
;   for (int i = 0; i < 4; i++) {
;     *(u32x4*)(sbuf + (r0 + i * 32) * LDK + sg * 8) = g.a[i];
;     *(u32x4*)(sbuf + 128 * LDK + (r0 + i * 32) * LDK + sg * 8) = g.b[i];
;   }
;   if (nk > 1) {
; #pragma unroll
;     for (int i = 0; i < 4; i++) {
;       g.a[i] = *(const u32x4*)(Ap + (size_t)i * 32 * o.lda + 64);
;       g.b[i] = *(const u32x4*)(Bp + o.bs.o[i] + 64);
;     }
;   }
;   __syncthreads();
;   const int lane = tid & 63, fr = lane & 31, fh = lane >> 5;
;   for (int k = 0; k < nk; k++) {
;     bf16r* cur = sbuf + (k & 1) * (256 * LDK);
;     bf16r* nxt = sbuf + ((k & 1) ^ 1) * (256 * LDK);
;     const bf16r* As = cur + (wm * 64 + fr) * LDK + fh * 8;
;     const bf16r* Bs = cur + 128 * LDK + (wn * 64 + fr) * LDK + fh * 8;
;     const bool wr = (k + 1 < nk), ld = (k + 2 < nk);
;     bf16x8 fa[2][2], fb[2][2];
;     fa[0][0] = *(const bf16x8*)(As);
;     fa[0][1] = *(const bf16x8*)(As + 32 * LDK);
;     fb[0][0] = *(const bf16x8*)(Bs);
;     fb[0][1] = *(const bf16x8*)(Bs + 32 * LDK);
; #pragma unroll
;     for (int i = 0; i < 4; i++) {
;       if (wr) {
;         *(u32x4*)(nxt + (r0 + i * 32) * LDK + sg * 8) = g.a[i];
;         *(u32x4*)(nxt + 128 * LDK + (r0 + i * 32) * LDK + sg * 8) = g.b[i];
;       }
;       if (ld) {
;         g.a[i] = *(const u32x4*)(Ap + (size_t)i * 32 * o.lda + (k + 2) * 64);
;         g.b[i] = *(const u32x4*)(Bp + o.bs.o[i] + (k + 2) * 64);
;       }
;       if (i < 3) {
;         fa[(i + 1) & 1][0] = *(const bf16x8*)(As + (i + 1) * 16);
;         fa[(i + 1) & 1][1] = *(const bf16x8*)(As + 32 * LDK + (i + 1) * 16);
;         fb[(i + 1) & 1][0] = *(const bf16x8*)(Bs + (i + 1) * 16);
;         fb[(i + 1) & 1][1] = *(const bf16x8*)(Bs + 32 * LDK + (i + 1) * 16);
;       }
;       __builtin_amdgcn_sched_barrier(0);
;       __builtin_amdgcn_s_setprio(1);
;       acc[0][0] = __builtin_amdgcn_mfma_f32_32x32x16_bf16(fa[i & 1][0], fb[i & 1][0], acc[0][0], 0, 0, 0);
;       acc[0][1] = __builtin_amdgcn_mfma_f32_32x32x16_bf16(fa[i & 1][0], fb[i & 1][1], acc[0][1], 0, 0, 0);
;       acc[1][0] = __builtin_amdgcn_mfma_f32_32x32x16_bf16(fa[i & 1][1], fb[i & 1][0], acc[1][0], 0, 0, 0);
.LBB0_2974:
	s_ashr_i32 s7, s6, 31
	s_lshl_b64 s[4:5], s[6:7], 18
	s_ashr_i32 s9, s8, 31
	s_waitcnt vmcnt(7)
	ds_write_b128 v100, v[64:67]
	s_waitcnt vmcnt(6)
	ds_write_b128 v100, v[68:71] offset:18432
	s_waitcnt vmcnt(5)
	ds_write_b128 v100, v[72:75] offset:4608
	s_waitcnt vmcnt(4)
	ds_write_b128 v100, v[76:79] offset:23040
	s_waitcnt vmcnt(3)
	ds_write_b128 v100, v[80:83] offset:9216
	s_waitcnt vmcnt(2)
	ds_write_b128 v100, v[84:87] offset:27648
	s_waitcnt vmcnt(1)
	ds_write_b128 v100, v[88:91] offset:13824
	s_waitcnt vmcnt(0)
	ds_write_b128 v100, v[92:95] offset:32256
	v_lshl_add_u64 v[64:65], v[102:103], 0, s[4:5]
	s_lshl_b64 s[10:11], s[8:9], 18
	v_add_co_u32_e32 v72, vcc, s60, v64
	v_lshl_add_u64 v[106:107], v[98:99], 0, s[10:11]
	s_nop 0
	v_addc_co_u32_e32 v73, vcc, 0, v65, vcc
	v_add_co_u32_e32 v76, vcc, s60, v106
	global_load_dwordx4 v[0:3], v[64:65], off offset:128
	global_load_dwordx4 v[4:7], v[106:107], off offset:128
	v_addc_co_u32_e32 v77, vcc, 0, v107, vcc
	v_add_co_u32_e32 v80, vcc, s61, v64
	global_load_dwordx4 v[66:69], v[72:73], off offset:128
	global_load_dwordx4 v[110:113], v[76:77], off offset:128
	v_addc_co_u32_e32 v81, vcc, 0, v65, vcc
	v_add_co_u32_e32 v84, vcc, s61, v106
	s_nop 1
	v_addc_co_u32_e32 v85, vcc, 0, v107, vcc
	v_add_co_u32_e32 v88, vcc, s76, v64
	global_load_dwordx4 v[114:117], v[80:81], off offset:128
	global_load_dwordx4 v[118:121], v[84:85], off offset:128
	v_addc_co_u32_e32 v89, vcc, 0, v65, vcc
	v_add_co_u32_e32 v92, vcc, s76, v106
	s_nop 1
	v_addc_co_u32_e32 v93, vcc, 0, v107, vcc
	global_load_dwordx4 v[122:125], v[88:89], off offset:128
	global_load_dwordx4 v[126:129], v[92:93], off offset:128
	s_waitcnt lgkmcnt(0)
	s_barrier
	global_load_dwordx4 v[130:133], v[64:65], off offset:256
	global_load_dwordx4 v[134:137], v[106:107], off offset:256
	ds_read_b128 v[8:11], v104
	ds_read_b128 v[32:35], v104 offset:4608
	ds_read_b128 v[12:15], v101 offset:18432
	ds_read_b128 v[36:39], v101 offset:23040
	s_waitcnt vmcnt(9)
	ds_write_b128 v100, v[0:3] offset:36864
	s_waitcnt vmcnt(8)
	ds_write_b128 v100, v[4:7] offset:55296
	ds_read_b128 v[138:141], v104 offset:32
	ds_read_b128 v[142:145], v104 offset:4640
	ds_read_b128 v[146:149], v101 offset:18464
	ds_read_b128 v[150:153], v101 offset:23072
	s_waitcnt lgkmcnt(7)
	v_mfma_f32_32x32x16_bf16 v[16:31], v[8:11], v[12:15], 0
	s_waitcnt lgkmcnt(6)
	v_mfma_f32_32x32x16_bf16 v[48:63], v[8:11], v[36:39], 0
	v_mfma_f32_32x32x16_bf16 v[0:15], v[32:35], v[12:15], 0
	v_mfma_f32_32x32x16_bf16 v[32:47], v[32:35], v[36:39], 0
	global_load_dwordx4 v[154:157], v[72:73], off offset:256
	global_load_dwordx4 v[158:161], v[76:77], off offset:256
	s_waitcnt vmcnt(9)
	ds_write_b128 v100, v[66:69] offset:41472
	s_waitcnt vmcnt(8)
	ds_write_b128 v100, v[110:113] offset:59904
	ds_read_b128 v[66:69], v104 offset:64
	ds_read_b128 v[110:113], v104 offset:4672
	ds_read_b128 v[162:165], v101 offset:18496
	ds_read_b128 v[166:169], v101 offset:23104
	s_waitcnt lgkmcnt(7)
	v_mfma_f32_32x32x16_bf16 v[16:31], v[138:141], v[146:149], v[16:31]
	s_waitcnt lgkmcnt(6)
	v_mfma_f32_32x32x16_bf16 v[48:63], v[138:141], v[150:153], v[48:63]
	v_mfma_f32_32x32x16_bf16 v[0:15], v[142:145], v[146:149], v[0:15]
	v_mfma_f32_32x32x16_bf16 v[32:47], v[142:145], v[150:153], v[32:47]
	global_load_dwordx4 v[138:141], v[80:81], off offset:256
	global_load_dwordx4 v[142:145], v[84:85], off offset:256
	s_waitcnt vmcnt(9)
	ds_write_b128 v100, v[114:117] offset:46080
	s_waitcnt vmcnt(8)
	ds_write_b128 v100, v[118:121] offset:64512
	ds_read_b128 v[114:117], v104 offset:96
	ds_read_b128 v[118:121], v104 offset:4704
	ds_read_b128 v[146:149], v101 offset:18528
	ds_read_b128 v[150:153], v101 offset:23136
	s_waitcnt lgkmcnt(7)
	v_mfma_f32_32x32x16_bf16 v[16:31], v[66:69], v[162:165], v[16:31]
	s_waitcnt lgkmcnt(6)
	v_mfma_f32_32x32x16_bf16 v[48:63], v[66:69], v[166:169], v[48:63]
	v_mfma_f32_32x32x16_bf16 v[0:15], v[110:113], v[162:165], v[0:15]
	v_mfma_f32_32x32x16_bf16 v[32:47], v[110:113], v[166:169], v[32:47]
	global_load_dwordx4 v[66:69], v[88:89], off offset:256
	global_load_dwordx4 v[110:113], v[92:93], off offset:256
	s_waitcnt vmcnt(9)
	ds_write_b128 v100, v[122:125] offset:50688
	s_waitcnt vmcnt(8)
	ds_write_b128 v105, v[126:129] offset:13824
	s_waitcnt lgkmcnt(3)
	v_mfma_f32_32x32x16_bf16 v[16:31], v[114:117], v[146:149], v[16:31]
	s_waitcnt lgkmcnt(2)
	v_mfma_f32_32x32x16_bf16 v[48:63], v[114:117], v[150:153], v[48:63]
	v_mfma_f32_32x32x16_bf16 v[0:15], v[118:121], v[146:149], v[0:15]
	v_mfma_f32_32x32x16_bf16 v[32:47], v[118:121], v[150:153], v[32:47]
	s_waitcnt lgkmcnt(0)
	s_barrier
; __device__ __forceinline__ void gemm_run(int tid, f32x16 (&acc)[2][2], GRegs& g, const GOp& o, int K, unsigned char* smem) {
;     ...
;   for (int k = 0; k < nk; k++) {
;     bf16r* cur = sbuf + (k & 1) * (256 * LDK);
;     bf16r* nxt = sbuf + ((k & 1) ^ 1) * (256 * LDK);
;     const bf16r* As = cur + (wm * 64 + fr) * LDK + fh * 8;
;     const bf16r* Bs = cur + 128 * LDK + (wn * 64 + fr) * LDK + fh * 8;
;     const bool wr = (k + 1 < nk), ld = (k + 2 < nk);
;     bf16x8 fa[2][2], fb[2][2];
;     fa[0][0] = *(const bf16x8*)(As);
;     fa[0][1] = *(const bf16x8*)(As + 32 * LDK);
;     fb[0][0] = *(const bf16x8*)(Bs);
;     fb[0][1] = *(const bf16x8*)(Bs + 32 * LDK);
; #pragma unroll
;     for (int i = 0; i < 4; i++) {
;       if (wr) {
;         *(u32x4*)(nxt + (r0 + i * 32) * LDK + sg * 8) = g.a[i];
;         *(u32x4*)(nxt + 128 * LDK + (r0 + i * 32) * LDK + sg * 8) = g.b[i];
;       }
;       if (ld) {
;         g.a[i] = *(const u32x4*)(Ap + (size_t)i * 32 * o.lda + (k + 2) * 64);
;         g.b[i] = *(const u32x4*)(Bp + o.bs.o[i] + (k + 2) * 64);
;       }
;       if (i < 3) {
;         fa[(i + 1) & 1][0] = *(const bf16x8*)(As + (i + 1) * 16);
;         fa[(i + 1) & 1][1] = *(const bf16x8*)(As + 32 * LDK + (i + 1) * 16);
;         fb[(i + 1) & 1][0] = *(const bf16x8*)(Bs + (i + 1) * 16);
;         fb[(i + 1) & 1][1] = *(const bf16x8*)(Bs + 32 * LDK + (i + 1) * 16);
;       }
;       __builtin_amdgcn_sched_barrier(0);
;       __builtin_amdgcn_s_setprio(1);
;       acc[0][0] = __builtin_amdgcn_mfma_f32_32x32x16_bf16(fa[i & 1][0], fb[i & 1][0], acc[0][0], 0, 0, 0);
;       acc[0][1] = __builtin_amdgcn_mfma_f32_32x32x16_bf16(fa[i & 1][0], fb[i & 1][1], acc[0][1], 0, 0, 0);
;       acc[1][0] = __builtin_amdgcn_mfma_f32_32x32x16_bf16(fa[i & 1][1], fb[i & 1][0], acc[1][0], 0, 0, 0);
;       acc[1][1] = __builtin_amdgcn_mfma_f32_32x32x16_bf16(fa[i & 1][1], fb[i & 1][1], acc[1][1], 0, 0, 0);
;       __builtin_amdgcn_s_setprio(0);
;     }
;     __syncthreads();
	global_load_dwordx4 v[114:117], v[64:65], off offset:384
	global_load_dwordx4 v[118:121], v[106:107], off offset:384
	ds_read_b128 v[122:125], v104 offset:36864
	ds_read_b128 v[126:129], v104 offset:41472
	ds_read_b128 v[146:149], v101 offset:55296
	ds_read_b128 v[150:153], v101 offset:59904
	s_waitcnt vmcnt(9)
	ds_write_b128 v100, v[130:133]
	s_waitcnt vmcnt(8)
	ds_write_b128 v100, v[134:137] offset:18432
	ds_read_b128 v[130:133], v104 offset:36896
	ds_read_b128 v[134:137], v104 offset:41504
	ds_read_b128 v[162:165], v101 offset:55328
	ds_read_b128 v[166:169], v101 offset:59936
	s_waitcnt lgkmcnt(7)
	v_mfma_f32_32x32x16_bf16 v[16:31], v[122:125], v[146:149], v[16:31]
	s_waitcnt lgkmcnt(6)
	v_mfma_f32_32x32x16_bf16 v[48:63], v[122:125], v[150:153], v[48:63]
	v_mfma_f32_32x32x16_bf16 v[0:15], v[126:129], v[146:149], v[0:15]
	v_mfma_f32_32x32x16_bf16 v[32:47], v[126:129], v[150:153], v[32:47]
	global_load_dwordx4 v[122:125], v[72:73], off offset:384
	global_load_dwordx4 v[126:129], v[76:77], off offset:384
	s_waitcnt vmcnt(9)
	ds_write_b128 v100, v[154:157] offset:4608
	s_waitcnt vmcnt(8)
	ds_write_b128 v100, v[158:161] offset:23040
	ds_read_b128 v[146:149], v104 offset:36928
	ds_read_b128 v[150:153], v104 offset:41536
	ds_read_b128 v[154:157], v101 offset:55360
	ds_read_b128 v[158:161], v101 offset:59968
	s_waitcnt lgkmcnt(7)
	v_mfma_f32_32x32x16_bf16 v[16:31], v[130:133], v[162:165], v[16:31]
	s_waitcnt lgkmcnt(6)
	v_mfma_f32_32x32x16_bf16 v[48:63], v[130:133], v[166:169], v[48:63]
	v_mfma_f32_32x32x16_bf16 v[0:15], v[134:137], v[162:165], v[0:15]
	v_mfma_f32_32x32x16_bf16 v[32:47], v[134:137], v[166:169], v[32:47]
	global_load_dwordx4 v[130:133], v[80:81], off offset:384
	global_load_dwordx4 v[134:137], v[84:85], off offset:384
	s_waitcnt vmcnt(9)
	ds_write_b128 v100, v[138:141] offset:9216
	s_waitcnt vmcnt(8)
	ds_write_b128 v100, v[142:145] offset:27648
	ds_read_b128 v[138:141], v104 offset:36960
	ds_read_b128 v[142:145], v104 offset:41568
	ds_read_b128 v[162:165], v101 offset:55392
	ds_read_b128 v[166:169], v101 offset:60000
	s_waitcnt lgkmcnt(7)
	v_mfma_f32_32x32x16_bf16 v[16:31], v[146:149], v[154:157], v[16:31]
	s_waitcnt lgkmcnt(6)
	v_mfma_f32_32x32x16_bf16 v[48:63], v[146:149], v[158:161], v[48:63]
	v_mfma_f32_32x32x16_bf16 v[0:15], v[150:153], v[154:157], v[0:15]
	v_mfma_f32_32x32x16_bf16 v[32:47], v[150:153], v[158:161], v[32:47]
	global_load_dwordx4 v[146:149], v[88:89], off offset:384
	global_load_dwordx4 v[150:153], v[92:93], off offset:384
	s_waitcnt vmcnt(9)
	ds_write_b128 v100, v[66:69] offset:13824
	s_waitcnt vmcnt(8)
	ds_write_b128 v100, v[110:113] offset:32256
	s_waitcnt lgkmcnt(3)
	v_mfma_f32_32x32x16_bf16 v[16:31], v[138:141], v[162:165], v[16:31]
	s_waitcnt lgkmcnt(2)
	v_mfma_f32_32x32x16_bf16 v[48:63], v[138:141], v[166:169], v[48:63]
	v_mfma_f32_32x32x16_bf16 v[0:15], v[142:145], v[162:165], v[0:15]
	v_mfma_f32_32x32x16_bf16 v[32:47], v[142:145], v[166:169], v[32:47]
	s_waitcnt lgkmcnt(0)
	s_barrier
	global_load_dwordx4 v[66:69], v[64:65], off offset:512
	global_load_dwordx4 v[110:113], v[106:107], off offset:512
	ds_read_b128 v[138:141], v104
	ds_read_b128 v[142:145], v104 offset:4608
	ds_read_b128 v[154:157], v101 offset:18432
	ds_read_b128 v[158:161], v101 offset:23040
	s_waitcnt vmcnt(9)
	ds_write_b128 v100, v[114:117] offset:36864
	s_waitcnt vmcnt(8)
	ds_write_b128 v100, v[118:121] offset:55296
	ds_read_b128 v[114:117], v104 offset:32
	ds_read_b128 v[118:121], v104 offset:4640
	ds_read_b128 v[162:165], v101 offset:18464
	ds_read_b128 v[166:169], v101 offset:23072
	s_waitcnt lgkmcnt(7)
	v_mfma_f32_32x32x16_bf16 v[16:31], v[138:141], v[154:157], v[16:31]
	s_waitcnt lgkmcnt(6)
	v_mfma_f32_32x32x16_bf16 v[48:63], v[138:141], v[158:161], v[48:63]
	v_mfma_f32_32x32x16_bf16 v[0:15], v[142:145], v[154:157], v[0:15]
	v_mfma_f32_32x32x16_bf16 v[32:47], v[142:145], v[158:161], v[32:47]
	global_load_dwordx4 v[138:141], v[72:73], off offset:512
	global_load_dwordx4 v[142:145], v[76:77], off offset:512
	s_waitcnt vmcnt(9)
	ds_write_b128 v100, v[122:125] offset:41472
	s_waitcnt vmcnt(8)
	ds_write_b128 v100, v[126:129] offset:59904
	ds_read_b128 v[122:125], v104 offset:64
	ds_read_b128 v[126:129], v104 offset:4672
	ds_read_b128 v[154:157], v101 offset:18496
	ds_read_b128 v[158:161], v101 offset:23104
	s_waitcnt lgkmcnt(7)
	v_mfma_f32_32x32x16_bf16 v[16:31], v[114:117], v[162:165], v[16:31]
	s_waitcnt lgkmcnt(6)
	v_mfma_f32_32x32x16_bf16 v[48:63], v[114:117], v[166:169], v[48:63]
	v_mfma_f32_32x32x16_bf16 v[0:15], v[118:121], v[162:165], v[0:15]
	v_mfma_f32_32x32x16_bf16 v[32:47], v[118:121], v[166:169], v[32:47]
	global_load_dwordx4 v[114:117], v[80:81], off offset:512
	global_load_dwordx4 v[118:121], v[84:85], off offset:512
	s_waitcnt vmcnt(9)
	ds_write_b128 v100, v[130:133] offset:46080
	s_waitcnt vmcnt(8)
	ds_write_b128 v100, v[134:137] offset:64512
	ds_read_b128 v[130:133], v104 offset:96
	ds_read_b128 v[134:137], v104 offset:4704
	ds_read_b128 v[162:165], v101 offset:18528
	ds_read_b128 v[166:169], v101 offset:23136
	s_waitcnt lgkmcnt(7)
	v_mfma_f32_32x32x16_bf16 v[16:31], v[122:125], v[154:157], v[16:31]
	s_waitcnt lgkmcnt(6)
	v_mfma_f32_32x32x16_bf16 v[48:63], v[122:125], v[158:161], v[48:63]
	v_mfma_f32_32x32x16_bf16 v[0:15], v[126:129], v[154:157], v[0:15]
	v_mfma_f32_32x32x16_bf16 v[32:47], v[126:129], v[158:161], v[32:47]
	global_load_dwordx4 v[122:125], v[88:89], off offset:512
	global_load_dwordx4 v[126:129], v[92:93], off offset:512
	s_waitcnt vmcnt(9)
	ds_write_b128 v100, v[146:149] offset:50688
	s_waitcnt vmcnt(8)
	ds_write_b128 v105, v[150:153] offset:13824
	s_waitcnt lgkmcnt(3)
	v_mfma_f32_32x32x16_bf16 v[16:31], v[130:133], v[162:165], v[16:31]
	s_waitcnt lgkmcnt(2)
	v_mfma_f32_32x32x16_bf16 v[48:63], v[130:133], v[166:169], v[48:63]
	v_mfma_f32_32x32x16_bf16 v[0:15], v[134:137], v[162:165], v[0:15]
	v_mfma_f32_32x32x16_bf16 v[32:47], v[134:137], v[166:169], v[32:47]
	s_waitcnt lgkmcnt(0)
	s_barrier
; __device__ __forceinline__ void gemm_run(int tid, f32x16 (&acc)[2][2], GRegs& g, const GOp& o, int K, unsigned char* smem) {
;     ...
;   for (int k = 0; k < nk; k++) {
;     bf16r* cur = sbuf + (k & 1) * (256 * LDK);
;     bf16r* nxt = sbuf + ((k & 1) ^ 1) * (256 * LDK);
;     const bf16r* As = cur + (wm * 64 + fr) * LDK + fh * 8;
;     const bf16r* Bs = cur + 128 * LDK + (wn * 64 + fr) * LDK + fh * 8;
;     const bool wr = (k + 1 < nk), ld = (k + 2 < nk);
;     bf16x8 fa[2][2], fb[2][2];
;     fa[0][0] = *(const bf16x8*)(As);
;     fa[0][1] = *(const bf16x8*)(As + 32 * LDK);
;     fb[0][0] = *(const bf16x8*)(Bs);
;     fb[0][1] = *(const bf16x8*)(Bs + 32 * LDK);
; #pragma unroll
;     for (int i = 0; i < 4; i++) {
;       if (wr) {
;         *(u32x4*)(nxt + (r0 + i * 32) * LDK + sg * 8) = g.a[i];
;         *(u32x4*)(nxt + 128 * LDK + (r0 + i * 32) * LDK + sg * 8) = g.b[i];
;       }
;       if (ld) {
;         g.a[i] = *(const u32x4*)(Ap + (size_t)i * 32 * o.lda + (k + 2) * 64);
;         g.b[i] = *(const u32x4*)(Bp + o.bs.o[i] + (k + 2) * 64);
;       }
;       if (i < 3) {
;         fa[(i + 1) & 1][0] = *(const bf16x8*)(As + (i + 1) * 16);
;         fa[(i + 1) & 1][1] = *(const bf16x8*)(As + 32 * LDK + (i + 1) * 16);
;         fb[(i + 1) & 1][0] = *(const bf16x8*)(Bs + (i + 1) * 16);
;         fb[(i + 1) & 1][1] = *(const bf16x8*)(Bs + 32 * LDK + (i + 1) * 16);
;       }
;       __builtin_amdgcn_sched_barrier(0);
;       __builtin_amdgcn_s_setprio(1);
;       acc[0][0] = __builtin_amdgcn_mfma_f32_32x32x16_bf16(fa[i & 1][0], fb[i & 1][0], acc[0][0], 0, 0, 0);
;       acc[0][1] = __builtin_amdgcn_mfma_f32_32x32x16_bf16(fa[i & 1][0], fb[i & 1][1], acc[0][1], 0, 0, 0);
;       acc[1][0] = __builtin_amdgcn_mfma_f32_32x32x16_bf16(fa[i & 1][1], fb[i & 1][0], acc[1][0], 0, 0, 0);
;       acc[1][1] = __builtin_amdgcn_mfma_f32_32x32x16_bf16(fa[i & 1][1], fb[i & 1][1], acc[1][1], 0, 0, 0);
;       __builtin_amdgcn_s_setprio(0);
;     }
;     __syncthreads();
	global_load_dwordx4 v[130:133], v[64:65], off offset:640
	global_load_dwordx4 v[134:137], v[106:107], off offset:640
	ds_read_b128 v[146:149], v104 offset:36864
	ds_read_b128 v[150:153], v104 offset:41472
	ds_read_b128 v[154:157], v101 offset:55296
	ds_read_b128 v[158:161], v101 offset:59904
	s_waitcnt vmcnt(9)
	ds_write_b128 v100, v[66:69]
	s_waitcnt vmcnt(8)
	ds_write_b128 v100, v[110:113] offset:18432
	ds_read_b128 v[66:69], v104 offset:36896
	ds_read_b128 v[110:113], v104 offset:41504
	ds_read_b128 v[162:165], v101 offset:55328
	ds_read_b128 v[166:169], v101 offset:59936
	s_waitcnt lgkmcnt(7)
	v_mfma_f32_32x32x16_bf16 v[16:31], v[146:149], v[154:157], v[16:31]
	s_waitcnt lgkmcnt(6)
	v_mfma_f32_32x32x16_bf16 v[48:63], v[146:149], v[158:161], v[48:63]
	v_mfma_f32_32x32x16_bf16 v[0:15], v[150:153], v[154:157], v[0:15]
	v_mfma_f32_32x32x16_bf16 v[32:47], v[150:153], v[158:161], v[32:47]
	global_load_dwordx4 v[146:149], v[72:73], off offset:640
	global_load_dwordx4 v[150:153], v[76:77], off offset:640
	s_waitcnt vmcnt(9)
	ds_write_b128 v100, v[138:141] offset:4608
	s_waitcnt vmcnt(8)
	ds_write_b128 v100, v[142:145] offset:23040
	ds_read_b128 v[138:141], v104 offset:36928
	ds_read_b128 v[142:145], v104 offset:41536
	ds_read_b128 v[154:157], v101 offset:55360
	ds_read_b128 v[158:161], v101 offset:59968
	s_waitcnt lgkmcnt(7)
	v_mfma_f32_32x32x16_bf16 v[16:31], v[66:69], v[162:165], v[16:31]
	s_waitcnt lgkmcnt(6)
	v_mfma_f32_32x32x16_bf16 v[48:63], v[66:69], v[166:169], v[48:63]
	v_mfma_f32_32x32x16_bf16 v[0:15], v[110:113], v[162:165], v[0:15]
	v_mfma_f32_32x32x16_bf16 v[32:47], v[110:113], v[166:169], v[32:47]
	global_load_dwordx4 v[66:69], v[80:81], off offset:640
	global_load_dwordx4 v[110:113], v[84:85], off offset:640
	s_waitcnt vmcnt(9)
	ds_write_b128 v100, v[114:117] offset:9216
	s_waitcnt vmcnt(8)
	ds_write_b128 v100, v[118:121] offset:27648
	ds_read_b128 v[114:117], v104 offset:36960
	ds_read_b128 v[118:121], v104 offset:41568
	ds_read_b128 v[162:165], v101 offset:55392
	ds_read_b128 v[166:169], v101 offset:60000
	s_waitcnt lgkmcnt(7)
	v_mfma_f32_32x32x16_bf16 v[16:31], v[138:141], v[154:157], v[16:31]
	s_waitcnt lgkmcnt(6)
	v_mfma_f32_32x32x16_bf16 v[48:63], v[138:141], v[158:161], v[48:63]
	v_mfma_f32_32x32x16_bf16 v[0:15], v[142:145], v[154:157], v[0:15]
	v_mfma_f32_32x32x16_bf16 v[32:47], v[142:145], v[158:161], v[32:47]
	global_load_dwordx4 v[138:141], v[88:89], off offset:640
	global_load_dwordx4 v[142:145], v[92:93], off offset:640
	s_waitcnt vmcnt(9)
	ds_write_b128 v100, v[122:125] offset:13824
	s_waitcnt vmcnt(8)
	ds_write_b128 v100, v[126:129] offset:32256
	s_waitcnt lgkmcnt(3)
	v_mfma_f32_32x32x16_bf16 v[16:31], v[114:117], v[162:165], v[16:31]
	s_waitcnt lgkmcnt(2)
	v_mfma_f32_32x32x16_bf16 v[48:63], v[114:117], v[166:169], v[48:63]
	v_mfma_f32_32x32x16_bf16 v[0:15], v[118:121], v[162:165], v[0:15]
	v_mfma_f32_32x32x16_bf16 v[32:47], v[118:121], v[166:169], v[32:47]
	s_waitcnt lgkmcnt(0)
	s_barrier
	global_load_dwordx4 v[114:117], v[64:65], off offset:768
	global_load_dwordx4 v[118:121], v[106:107], off offset:768
	ds_read_b128 v[122:125], v104
	ds_read_b128 v[126:129], v104 offset:4608
	ds_read_b128 v[154:157], v101 offset:18432
	ds_read_b128 v[158:161], v101 offset:23040
	s_waitcnt vmcnt(9)
	ds_write_b128 v100, v[130:133] offset:36864
	s_waitcnt vmcnt(8)
	ds_write_b128 v100, v[134:137] offset:55296
	ds_read_b128 v[130:133], v104 offset:32
	ds_read_b128 v[134:137], v104 offset:4640
	ds_read_b128 v[162:165], v101 offset:18464
	ds_read_b128 v[166:169], v101 offset:23072
	s_waitcnt lgkmcnt(7)
	v_mfma_f32_32x32x16_bf16 v[16:31], v[122:125], v[154:157], v[16:31]
	s_waitcnt lgkmcnt(6)
	v_mfma_f32_32x32x16_bf16 v[48:63], v[122:125], v[158:161], v[48:63]
	v_mfma_f32_32x32x16_bf16 v[0:15], v[126:129], v[154:157], v[0:15]
	v_mfma_f32_32x32x16_bf16 v[32:47], v[126:129], v[158:161], v[32:47]
	global_load_dwordx4 v[122:125], v[72:73], off offset:768
	global_load_dwordx4 v[126:129], v[76:77], off offset:768
	s_waitcnt vmcnt(9)
	ds_write_b128 v100, v[146:149] offset:41472
	s_waitcnt vmcnt(8)
	ds_write_b128 v100, v[150:153] offset:59904
	ds_read_b128 v[146:149], v104 offset:64
	ds_read_b128 v[150:153], v104 offset:4672
	ds_read_b128 v[154:157], v101 offset:18496
	ds_read_b128 v[158:161], v101 offset:23104
	s_waitcnt lgkmcnt(7)
	v_mfma_f32_32x32x16_bf16 v[16:31], v[130:133], v[162:165], v[16:31]
	s_waitcnt lgkmcnt(6)
	v_mfma_f32_32x32x16_bf16 v[48:63], v[130:133], v[166:169], v[48:63]
	v_mfma_f32_32x32x16_bf16 v[0:15], v[134:137], v[162:165], v[0:15]
	v_mfma_f32_32x32x16_bf16 v[32:47], v[134:137], v[166:169], v[32:47]
	global_load_dwordx4 v[130:133], v[80:81], off offset:768
	global_load_dwordx4 v[134:137], v[84:85], off offset:768
	s_waitcnt vmcnt(9)
	ds_write_b128 v100, v[66:69] offset:46080
	s_waitcnt vmcnt(8)
	ds_write_b128 v100, v[110:113] offset:64512
	ds_read_b128 v[66:69], v104 offset:96
	ds_read_b128 v[110:113], v104 offset:4704
	ds_read_b128 v[162:165], v101 offset:18528
	ds_read_b128 v[166:169], v101 offset:23136
	s_waitcnt lgkmcnt(7)
	v_mfma_f32_32x32x16_bf16 v[16:31], v[146:149], v[154:157], v[16:31]
	s_waitcnt lgkmcnt(6)
	v_mfma_f32_32x32x16_bf16 v[48:63], v[146:149], v[158:161], v[48:63]
	v_mfma_f32_32x32x16_bf16 v[0:15], v[150:153], v[154:157], v[0:15]
	v_mfma_f32_32x32x16_bf16 v[32:47], v[150:153], v[158:161], v[32:47]
	global_load_dwordx4 v[146:149], v[88:89], off offset:768
	global_load_dwordx4 v[150:153], v[92:93], off offset:768
	s_waitcnt vmcnt(9)
	ds_write_b128 v100, v[138:141] offset:50688
	s_waitcnt vmcnt(8)
	ds_write_b128 v105, v[142:145] offset:13824
	s_waitcnt lgkmcnt(3)
	v_mfma_f32_32x32x16_bf16 v[16:31], v[66:69], v[162:165], v[16:31]
	s_waitcnt lgkmcnt(2)
	v_mfma_f32_32x32x16_bf16 v[48:63], v[66:69], v[166:169], v[48:63]
	v_mfma_f32_32x32x16_bf16 v[0:15], v[110:113], v[162:165], v[0:15]
	v_mfma_f32_32x32x16_bf16 v[32:47], v[110:113], v[166:169], v[32:47]
	s_waitcnt lgkmcnt(0)
	s_barrier
; __device__ __forceinline__ void gemm_run(int tid, f32x16 (&acc)[2][2], GRegs& g, const GOp& o, int K, unsigned char* smem) {
;     ...
;   for (int k = 0; k < nk; k++) {
;     bf16r* cur = sbuf + (k & 1) * (256 * LDK);
;     bf16r* nxt = sbuf + ((k & 1) ^ 1) * (256 * LDK);
;     const bf16r* As = cur + (wm * 64 + fr) * LDK + fh * 8;
;     const bf16r* Bs = cur + 128 * LDK + (wn * 64 + fr) * LDK + fh * 8;
;     const bool wr = (k + 1 < nk), ld = (k + 2 < nk);
;     bf16x8 fa[2][2], fb[2][2];
;     fa[0][0] = *(const bf16x8*)(As);
;     fa[0][1] = *(const bf16x8*)(As + 32 * LDK);
;     fb[0][0] = *(const bf16x8*)(Bs);
;     fb[0][1] = *(const bf16x8*)(Bs + 32 * LDK);
; #pragma unroll
;     for (int i = 0; i < 4; i++) {
;       if (wr) {
;         *(u32x4*)(nxt + (r0 + i * 32) * LDK + sg * 8) = g.a[i];
;         *(u32x4*)(nxt + 128 * LDK + (r0 + i * 32) * LDK + sg * 8) = g.b[i];
;       }
;       if (ld) {
;         g.a[i] = *(const u32x4*)(Ap + (size_t)i * 32 * o.lda + (k + 2) * 64);
;         g.b[i] = *(const u32x4*)(Bp + o.bs.o[i] + (k + 2) * 64);
;       }
;       if (i < 3) {
;         fa[(i + 1) & 1][0] = *(const bf16x8*)(As + (i + 1) * 16);
;         fa[(i + 1) & 1][1] = *(const bf16x8*)(As + 32 * LDK + (i + 1) * 16);
;         fb[(i + 1) & 1][0] = *(const bf16x8*)(Bs + (i + 1) * 16);
;         fb[(i + 1) & 1][1] = *(const bf16x8*)(Bs + 32 * LDK + (i + 1) * 16);
;       }
;       __builtin_amdgcn_sched_barrier(0);
;       __builtin_amdgcn_s_setprio(1);
;       acc[0][0] = __builtin_amdgcn_mfma_f32_32x32x16_bf16(fa[i & 1][0], fb[i & 1][0], acc[0][0], 0, 0, 0);
;       acc[0][1] = __builtin_amdgcn_mfma_f32_32x32x16_bf16(fa[i & 1][0], fb[i & 1][1], acc[0][1], 0, 0, 0);
;       acc[1][0] = __builtin_amdgcn_mfma_f32_32x32x16_bf16(fa[i & 1][1], fb[i & 1][0], acc[1][0], 0, 0, 0);
;       acc[1][1] = __builtin_amdgcn_mfma_f32_32x32x16_bf16(fa[i & 1][1], fb[i & 1][1], acc[1][1], 0, 0, 0);
;       __builtin_amdgcn_s_setprio(0);
;     }
;     __syncthreads();
	global_load_dwordx4 v[66:69], v[64:65], off offset:896
	global_load_dwordx4 v[110:113], v[106:107], off offset:896
	ds_read_b128 v[138:141], v104 offset:36864
	ds_read_b128 v[142:145], v104 offset:41472
	ds_read_b128 v[154:157], v101 offset:55296
	ds_read_b128 v[158:161], v101 offset:59904
	s_waitcnt vmcnt(9)
	ds_write_b128 v100, v[114:117]
	s_waitcnt vmcnt(8)
	ds_write_b128 v100, v[118:121] offset:18432
	ds_read_b128 v[114:117], v104 offset:36896
	ds_read_b128 v[118:121], v104 offset:41504
	ds_read_b128 v[162:165], v101 offset:55328
	ds_read_b128 v[166:169], v101 offset:59936
	s_waitcnt lgkmcnt(7)
	v_mfma_f32_32x32x16_bf16 v[16:31], v[138:141], v[154:157], v[16:31]
	s_waitcnt lgkmcnt(6)
	v_mfma_f32_32x32x16_bf16 v[48:63], v[138:141], v[158:161], v[48:63]
	v_mfma_f32_32x32x16_bf16 v[0:15], v[142:145], v[154:157], v[0:15]
	v_mfma_f32_32x32x16_bf16 v[32:47], v[142:145], v[158:161], v[32:47]
	global_load_dwordx4 v[138:141], v[72:73], off offset:896
	global_load_dwordx4 v[142:145], v[76:77], off offset:896
	s_waitcnt vmcnt(9)
	ds_write_b128 v100, v[122:125] offset:4608
	s_waitcnt vmcnt(8)
	ds_write_b128 v100, v[126:129] offset:23040
	ds_read_b128 v[122:125], v104 offset:36928
	ds_read_b128 v[126:129], v104 offset:41536
	ds_read_b128 v[154:157], v101 offset:55360
	ds_read_b128 v[158:161], v101 offset:59968
	s_waitcnt lgkmcnt(7)
	v_mfma_f32_32x32x16_bf16 v[16:31], v[114:117], v[162:165], v[16:31]
	s_waitcnt lgkmcnt(6)
	v_mfma_f32_32x32x16_bf16 v[48:63], v[114:117], v[166:169], v[48:63]
	v_mfma_f32_32x32x16_bf16 v[0:15], v[118:121], v[162:165], v[0:15]
	v_mfma_f32_32x32x16_bf16 v[32:47], v[118:121], v[166:169], v[32:47]
	global_load_dwordx4 v[114:117], v[80:81], off offset:896
	global_load_dwordx4 v[118:121], v[84:85], off offset:896
	s_waitcnt vmcnt(9)
	ds_write_b128 v100, v[130:133] offset:9216
	s_waitcnt vmcnt(8)
	ds_write_b128 v100, v[134:137] offset:27648
	ds_read_b128 v[130:133], v104 offset:36960
	ds_read_b128 v[134:137], v104 offset:41568
	ds_read_b128 v[162:165], v101 offset:55392
	ds_read_b128 v[166:169], v101 offset:60000
	s_waitcnt lgkmcnt(7)
	v_mfma_f32_32x32x16_bf16 v[16:31], v[122:125], v[154:157], v[16:31]
	s_waitcnt lgkmcnt(6)
	v_mfma_f32_32x32x16_bf16 v[48:63], v[122:125], v[158:161], v[48:63]
	v_mfma_f32_32x32x16_bf16 v[0:15], v[126:129], v[154:157], v[0:15]
	v_mfma_f32_32x32x16_bf16 v[32:47], v[126:129], v[158:161], v[32:47]
	global_load_dwordx4 v[122:125], v[88:89], off offset:896
	global_load_dwordx4 v[126:129], v[92:93], off offset:896
	s_waitcnt vmcnt(9)
	ds_write_b128 v100, v[146:149] offset:13824
	s_waitcnt vmcnt(8)
	ds_write_b128 v100, v[150:153] offset:32256
	s_waitcnt lgkmcnt(3)
	v_mfma_f32_32x32x16_bf16 v[16:31], v[130:133], v[162:165], v[16:31]
	s_waitcnt lgkmcnt(2)
	v_mfma_f32_32x32x16_bf16 v[48:63], v[130:133], v[166:169], v[48:63]
	v_mfma_f32_32x32x16_bf16 v[0:15], v[134:137], v[162:165], v[0:15]
	v_mfma_f32_32x32x16_bf16 v[32:47], v[134:137], v[166:169], v[32:47]
	s_waitcnt lgkmcnt(0)
	s_barrier
	global_load_dwordx4 v[130:133], v[64:65], off offset:1024
	global_load_dwordx4 v[134:137], v[106:107], off offset:1024
	ds_read_b128 v[146:149], v104
	ds_read_b128 v[150:153], v104 offset:4608
	ds_read_b128 v[154:157], v101 offset:18432
	ds_read_b128 v[158:161], v101 offset:23040
	s_waitcnt vmcnt(9)
	ds_write_b128 v100, v[66:69] offset:36864
	s_waitcnt vmcnt(8)
	ds_write_b128 v100, v[110:113] offset:55296
	ds_read_b128 v[66:69], v104 offset:32
	ds_read_b128 v[110:113], v104 offset:4640
	ds_read_b128 v[162:165], v101 offset:18464
	ds_read_b128 v[166:169], v101 offset:23072
	s_waitcnt lgkmcnt(7)
	v_mfma_f32_32x32x16_bf16 v[16:31], v[146:149], v[154:157], v[16:31]
	s_waitcnt lgkmcnt(6)
	v_mfma_f32_32x32x16_bf16 v[48:63], v[146:149], v[158:161], v[48:63]
	v_mfma_f32_32x32x16_bf16 v[0:15], v[150:153], v[154:157], v[0:15]
	v_mfma_f32_32x32x16_bf16 v[32:47], v[150:153], v[158:161], v[32:47]
	global_load_dwordx4 v[146:149], v[72:73], off offset:1024
	global_load_dwordx4 v[150:153], v[76:77], off offset:1024
	s_waitcnt vmcnt(9)
	ds_write_b128 v100, v[138:141] offset:41472
	s_waitcnt vmcnt(8)
	ds_write_b128 v100, v[142:145] offset:59904
	ds_read_b128 v[138:141], v104 offset:64
	ds_read_b128 v[142:145], v104 offset:4672
	ds_read_b128 v[154:157], v101 offset:18496
	ds_read_b128 v[158:161], v101 offset:23104
	s_waitcnt lgkmcnt(7)
	v_mfma_f32_32x32x16_bf16 v[16:31], v[66:69], v[162:165], v[16:31]
	s_waitcnt lgkmcnt(6)
	v_mfma_f32_32x32x16_bf16 v[48:63], v[66:69], v[166:169], v[48:63]
	v_mfma_f32_32x32x16_bf16 v[0:15], v[110:113], v[162:165], v[0:15]
	v_mfma_f32_32x32x16_bf16 v[32:47], v[110:113], v[166:169], v[32:47]
	global_load_dwordx4 v[66:69], v[80:81], off offset:1024
	global_load_dwordx4 v[110:113], v[84:85], off offset:1024
	s_waitcnt vmcnt(9)
	ds_write_b128 v100, v[114:117] offset:46080
	s_waitcnt vmcnt(8)
	ds_write_b128 v100, v[118:121] offset:64512
	ds_read_b128 v[114:117], v104 offset:96
	ds_read_b128 v[118:121], v104 offset:4704
	ds_read_b128 v[162:165], v101 offset:18528
	ds_read_b128 v[166:169], v101 offset:23136
	s_waitcnt lgkmcnt(7)
	v_mfma_f32_32x32x16_bf16 v[16:31], v[138:141], v[154:157], v[16:31]
	s_waitcnt lgkmcnt(6)
	v_mfma_f32_32x32x16_bf16 v[48:63], v[138:141], v[158:161], v[48:63]
	v_mfma_f32_32x32x16_bf16 v[0:15], v[142:145], v[154:157], v[0:15]
	v_mfma_f32_32x32x16_bf16 v[32:47], v[142:145], v[158:161], v[32:47]
	global_load_dwordx4 v[138:141], v[88:89], off offset:1024
	global_load_dwordx4 v[142:145], v[92:93], off offset:1024
	s_waitcnt vmcnt(9)
	ds_write_b128 v100, v[122:125] offset:50688
	s_waitcnt vmcnt(8)
	ds_write_b128 v105, v[126:129] offset:13824
	s_waitcnt lgkmcnt(3)
	v_mfma_f32_32x32x16_bf16 v[16:31], v[114:117], v[162:165], v[16:31]
	s_waitcnt lgkmcnt(2)
	v_mfma_f32_32x32x16_bf16 v[48:63], v[114:117], v[166:169], v[48:63]
	v_mfma_f32_32x32x16_bf16 v[0:15], v[118:121], v[162:165], v[0:15]
	v_mfma_f32_32x32x16_bf16 v[32:47], v[118:121], v[166:169], v[32:47]
	s_waitcnt lgkmcnt(0)
	s_barrier
; __device__ __forceinline__ void gemm_run(int tid, f32x16 (&acc)[2][2], GRegs& g, const GOp& o, int K, unsigned char* smem) {
;     ...
;   for (int k = 0; k < nk; k++) {
;     bf16r* cur = sbuf + (k & 1) * (256 * LDK);
;     bf16r* nxt = sbuf + ((k & 1) ^ 1) * (256 * LDK);
;     const bf16r* As = cur + (wm * 64 + fr) * LDK + fh * 8;
;     const bf16r* Bs = cur + 128 * LDK + (wn * 64 + fr) * LDK + fh * 8;
;     const bool wr = (k + 1 < nk), ld = (k + 2 < nk);
;     bf16x8 fa[2][2], fb[2][2];
;     fa[0][0] = *(const bf16x8*)(As);
;     fa[0][1] = *(const bf16x8*)(As + 32 * LDK);
;     fb[0][0] = *(const bf16x8*)(Bs);
;     fb[0][1] = *(const bf16x8*)(Bs + 32 * LDK);
; #pragma unroll
;     for (int i = 0; i < 4; i++) {
;       if (wr) {
;         *(u32x4*)(nxt + (r0 + i * 32) * LDK + sg * 8) = g.a[i];
;         *(u32x4*)(nxt + 128 * LDK + (r0 + i * 32) * LDK + sg * 8) = g.b[i];
;       }
;       if (ld) {
;         g.a[i] = *(const u32x4*)(Ap + (size_t)i * 32 * o.lda + (k + 2) * 64);
;         g.b[i] = *(const u32x4*)(Bp + o.bs.o[i] + (k + 2) * 64);
;       }
;       if (i < 3) {
;         fa[(i + 1) & 1][0] = *(const bf16x8*)(As + (i + 1) * 16);
;         fa[(i + 1) & 1][1] = *(const bf16x8*)(As + 32 * LDK + (i + 1) * 16);
;         fb[(i + 1) & 1][0] = *(const bf16x8*)(Bs + (i + 1) * 16);
;         fb[(i + 1) & 1][1] = *(const bf16x8*)(Bs + 32 * LDK + (i + 1) * 16);
;       }
;       __builtin_amdgcn_sched_barrier(0);
;       __builtin_amdgcn_s_setprio(1);
;       acc[0][0] = __builtin_amdgcn_mfma_f32_32x32x16_bf16(fa[i & 1][0], fb[i & 1][0], acc[0][0], 0, 0, 0);
;       acc[0][1] = __builtin_amdgcn_mfma_f32_32x32x16_bf16(fa[i & 1][0], fb[i & 1][1], acc[0][1], 0, 0, 0);
;       acc[1][0] = __builtin_amdgcn_mfma_f32_32x32x16_bf16(fa[i & 1][1], fb[i & 1][0], acc[1][0], 0, 0, 0);
;       acc[1][1] = __builtin_amdgcn_mfma_f32_32x32x16_bf16(fa[i & 1][1], fb[i & 1][1], acc[1][1], 0, 0, 0);
;       __builtin_amdgcn_s_setprio(0);
;     }
;     __syncthreads();
	global_load_dwordx4 v[114:117], v[64:65], off offset:1152
	global_load_dwordx4 v[118:121], v[106:107], off offset:1152
	ds_read_b128 v[122:125], v104 offset:36864
	ds_read_b128 v[126:129], v104 offset:41472
	ds_read_b128 v[154:157], v101 offset:55296
	ds_read_b128 v[158:161], v101 offset:59904
	s_waitcnt vmcnt(9)
	ds_write_b128 v100, v[130:133]
	s_waitcnt vmcnt(8)
	ds_write_b128 v100, v[134:137] offset:18432
	ds_read_b128 v[130:133], v104 offset:36896
	ds_read_b128 v[134:137], v104 offset:41504
	ds_read_b128 v[162:165], v101 offset:55328
	ds_read_b128 v[166:169], v101 offset:59936
	s_waitcnt lgkmcnt(7)
	v_mfma_f32_32x32x16_bf16 v[16:31], v[122:125], v[154:157], v[16:31]
	s_waitcnt lgkmcnt(6)
	v_mfma_f32_32x32x16_bf16 v[48:63], v[122:125], v[158:161], v[48:63]
	v_mfma_f32_32x32x16_bf16 v[0:15], v[126:129], v[154:157], v[0:15]
	v_mfma_f32_32x32x16_bf16 v[32:47], v[126:129], v[158:161], v[32:47]
	global_load_dwordx4 v[122:125], v[72:73], off offset:1152
	global_load_dwordx4 v[126:129], v[76:77], off offset:1152
	s_waitcnt vmcnt(9)
	ds_write_b128 v100, v[146:149] offset:4608
	s_waitcnt vmcnt(8)
	ds_write_b128 v100, v[150:153] offset:23040
	ds_read_b128 v[146:149], v104 offset:36928
	ds_read_b128 v[150:153], v104 offset:41536
	ds_read_b128 v[154:157], v101 offset:55360
	ds_read_b128 v[158:161], v101 offset:59968
	s_waitcnt lgkmcnt(7)
	v_mfma_f32_32x32x16_bf16 v[16:31], v[130:133], v[162:165], v[16:31]
	s_waitcnt lgkmcnt(6)
	v_mfma_f32_32x32x16_bf16 v[48:63], v[130:133], v[166:169], v[48:63]
	v_mfma_f32_32x32x16_bf16 v[0:15], v[134:137], v[162:165], v[0:15]
	v_mfma_f32_32x32x16_bf16 v[32:47], v[134:137], v[166:169], v[32:47]
	global_load_dwordx4 v[130:133], v[80:81], off offset:1152
	global_load_dwordx4 v[134:137], v[84:85], off offset:1152
	s_waitcnt vmcnt(9)
	ds_write_b128 v100, v[66:69] offset:9216
	s_waitcnt vmcnt(8)
	ds_write_b128 v100, v[110:113] offset:27648
	ds_read_b128 v[66:69], v104 offset:36960
	ds_read_b128 v[110:113], v104 offset:41568
	ds_read_b128 v[162:165], v101 offset:55392
	ds_read_b128 v[166:169], v101 offset:60000
	s_waitcnt lgkmcnt(7)
	v_mfma_f32_32x32x16_bf16 v[16:31], v[146:149], v[154:157], v[16:31]
	s_waitcnt lgkmcnt(6)
	v_mfma_f32_32x32x16_bf16 v[48:63], v[146:149], v[158:161], v[48:63]
	v_mfma_f32_32x32x16_bf16 v[0:15], v[150:153], v[154:157], v[0:15]
	v_mfma_f32_32x32x16_bf16 v[32:47], v[150:153], v[158:161], v[32:47]
	global_load_dwordx4 v[146:149], v[88:89], off offset:1152
	global_load_dwordx4 v[150:153], v[92:93], off offset:1152
	s_waitcnt vmcnt(9)
	ds_write_b128 v100, v[138:141] offset:13824
	s_waitcnt vmcnt(8)
	ds_write_b128 v100, v[142:145] offset:32256
	s_waitcnt lgkmcnt(3)
	v_mfma_f32_32x32x16_bf16 v[16:31], v[66:69], v[162:165], v[16:31]
	s_waitcnt lgkmcnt(2)
	v_mfma_f32_32x32x16_bf16 v[48:63], v[66:69], v[166:169], v[48:63]
	v_mfma_f32_32x32x16_bf16 v[0:15], v[110:113], v[162:165], v[0:15]
	v_mfma_f32_32x32x16_bf16 v[32:47], v[110:113], v[166:169], v[32:47]
	s_waitcnt lgkmcnt(0)
	s_barrier
	global_load_dwordx4 v[66:69], v[64:65], off offset:1280
	global_load_dwordx4 v[110:113], v[106:107], off offset:1280
	ds_read_b128 v[138:141], v104
	ds_read_b128 v[142:145], v104 offset:4608
	ds_read_b128 v[154:157], v101 offset:18432
	ds_read_b128 v[158:161], v101 offset:23040
	s_waitcnt vmcnt(9)
	ds_write_b128 v100, v[114:117] offset:36864
	s_waitcnt vmcnt(8)
	ds_write_b128 v100, v[118:121] offset:55296
	ds_read_b128 v[114:117], v104 offset:32
	ds_read_b128 v[118:121], v104 offset:4640
	ds_read_b128 v[162:165], v101 offset:18464
	ds_read_b128 v[166:169], v101 offset:23072
	s_waitcnt lgkmcnt(7)
	v_mfma_f32_32x32x16_bf16 v[16:31], v[138:141], v[154:157], v[16:31]
	s_waitcnt lgkmcnt(6)
	v_mfma_f32_32x32x16_bf16 v[48:63], v[138:141], v[158:161], v[48:63]
	v_mfma_f32_32x32x16_bf16 v[0:15], v[142:145], v[154:157], v[0:15]
	v_mfma_f32_32x32x16_bf16 v[32:47], v[142:145], v[158:161], v[32:47]
	global_load_dwordx4 v[138:141], v[72:73], off offset:1280
	global_load_dwordx4 v[142:145], v[76:77], off offset:1280
	s_waitcnt vmcnt(9)
	ds_write_b128 v100, v[122:125] offset:41472
	s_waitcnt vmcnt(8)
	ds_write_b128 v100, v[126:129] offset:59904
	ds_read_b128 v[122:125], v104 offset:64
	ds_read_b128 v[126:129], v104 offset:4672
	ds_read_b128 v[154:157], v101 offset:18496
	ds_read_b128 v[158:161], v101 offset:23104
	s_waitcnt lgkmcnt(7)
	v_mfma_f32_32x32x16_bf16 v[16:31], v[114:117], v[162:165], v[16:31]
	s_waitcnt lgkmcnt(6)
	v_mfma_f32_32x32x16_bf16 v[48:63], v[114:117], v[166:169], v[48:63]
	v_mfma_f32_32x32x16_bf16 v[0:15], v[118:121], v[162:165], v[0:15]
	v_mfma_f32_32x32x16_bf16 v[32:47], v[118:121], v[166:169], v[32:47]
	global_load_dwordx4 v[114:117], v[80:81], off offset:1280
	global_load_dwordx4 v[118:121], v[84:85], off offset:1280
	s_waitcnt vmcnt(9)
	ds_write_b128 v100, v[130:133] offset:46080
	s_waitcnt vmcnt(8)
	ds_write_b128 v100, v[134:137] offset:64512
	ds_read_b128 v[130:133], v104 offset:96
	ds_read_b128 v[134:137], v104 offset:4704
	ds_read_b128 v[162:165], v101 offset:18528
	ds_read_b128 v[166:169], v101 offset:23136
	s_waitcnt lgkmcnt(7)
	v_mfma_f32_32x32x16_bf16 v[16:31], v[122:125], v[154:157], v[16:31]
	s_waitcnt lgkmcnt(6)
	v_mfma_f32_32x32x16_bf16 v[48:63], v[122:125], v[158:161], v[48:63]
	v_mfma_f32_32x32x16_bf16 v[0:15], v[126:129], v[154:157], v[0:15]
	v_mfma_f32_32x32x16_bf16 v[32:47], v[126:129], v[158:161], v[32:47]
	global_load_dwordx4 v[122:125], v[88:89], off offset:1280
	global_load_dwordx4 v[126:129], v[92:93], off offset:1280
	s_waitcnt vmcnt(9)
	ds_write_b128 v100, v[146:149] offset:50688
	s_waitcnt vmcnt(8)
	ds_write_b128 v105, v[150:153] offset:13824
	s_waitcnt lgkmcnt(3)
	v_mfma_f32_32x32x16_bf16 v[16:31], v[130:133], v[162:165], v[16:31]
	s_waitcnt lgkmcnt(2)
	v_mfma_f32_32x32x16_bf16 v[48:63], v[130:133], v[166:169], v[48:63]
	v_mfma_f32_32x32x16_bf16 v[0:15], v[134:137], v[162:165], v[0:15]
	v_mfma_f32_32x32x16_bf16 v[32:47], v[134:137], v[166:169], v[32:47]
	s_waitcnt lgkmcnt(0)
	s_barrier
; __device__ __forceinline__ void gemm_run(int tid, f32x16 (&acc)[2][2], GRegs& g, const GOp& o, int K, unsigned char* smem) {
;     ...
;   for (int k = 0; k < nk; k++) {
;     bf16r* cur = sbuf + (k & 1) * (256 * LDK);
;     bf16r* nxt = sbuf + ((k & 1) ^ 1) * (256 * LDK);
;     const bf16r* As = cur + (wm * 64 + fr) * LDK + fh * 8;
;     const bf16r* Bs = cur + 128 * LDK + (wn * 64 + fr) * LDK + fh * 8;
;     const bool wr = (k + 1 < nk), ld = (k + 2 < nk);
;     bf16x8 fa[2][2], fb[2][2];
;     fa[0][0] = *(const bf16x8*)(As);
;     fa[0][1] = *(const bf16x8*)(As + 32 * LDK);
;     fb[0][0] = *(const bf16x8*)(Bs);
;     fb[0][1] = *(const bf16x8*)(Bs + 32 * LDK);
; #pragma unroll
;     for (int i = 0; i < 4; i++) {
;       if (wr) {
;         *(u32x4*)(nxt + (r0 + i * 32) * LDK + sg * 8) = g.a[i];
;         *(u32x4*)(nxt + 128 * LDK + (r0 + i * 32) * LDK + sg * 8) = g.b[i];
;       }
;       if (ld) {
;         g.a[i] = *(const u32x4*)(Ap + (size_t)i * 32 * o.lda + (k + 2) * 64);
;         g.b[i] = *(const u32x4*)(Bp + o.bs.o[i] + (k + 2) * 64);
;       }
;       if (i < 3) {
;         fa[(i + 1) & 1][0] = *(const bf16x8*)(As + (i + 1) * 16);
;         fa[(i + 1) & 1][1] = *(const bf16x8*)(As + 32 * LDK + (i + 1) * 16);
;         fb[(i + 1) & 1][0] = *(const bf16x8*)(Bs + (i + 1) * 16);
;         fb[(i + 1) & 1][1] = *(const bf16x8*)(Bs + 32 * LDK + (i + 1) * 16);
;       }
;       __builtin_amdgcn_sched_barrier(0);
;       __builtin_amdgcn_s_setprio(1);
;       acc[0][0] = __builtin_amdgcn_mfma_f32_32x32x16_bf16(fa[i & 1][0], fb[i & 1][0], acc[0][0], 0, 0, 0);
;       acc[0][1] = __builtin_amdgcn_mfma_f32_32x32x16_bf16(fa[i & 1][0], fb[i & 1][1], acc[0][1], 0, 0, 0);
;       acc[1][0] = __builtin_amdgcn_mfma_f32_32x32x16_bf16(fa[i & 1][1], fb[i & 1][0], acc[1][0], 0, 0, 0);
;       acc[1][1] = __builtin_amdgcn_mfma_f32_32x32x16_bf16(fa[i & 1][1], fb[i & 1][1], acc[1][1], 0, 0, 0);
;       __builtin_amdgcn_s_setprio(0);
;     }
;     __syncthreads();
	global_load_dwordx4 v[130:133], v[64:65], off offset:1408
	global_load_dwordx4 v[134:137], v[106:107], off offset:1408
	ds_read_b128 v[146:149], v104 offset:36864
	ds_read_b128 v[150:153], v104 offset:41472
	ds_read_b128 v[154:157], v101 offset:55296
	ds_read_b128 v[158:161], v101 offset:59904
	s_waitcnt vmcnt(9)
	ds_write_b128 v100, v[66:69]
	s_waitcnt vmcnt(8)
	ds_write_b128 v100, v[110:113] offset:18432
	ds_read_b128 v[66:69], v104 offset:36896
	ds_read_b128 v[110:113], v104 offset:41504
	ds_read_b128 v[162:165], v101 offset:55328
	ds_read_b128 v[166:169], v101 offset:59936
	s_waitcnt lgkmcnt(7)
	v_mfma_f32_32x32x16_bf16 v[16:31], v[146:149], v[154:157], v[16:31]
	s_waitcnt lgkmcnt(6)
	v_mfma_f32_32x32x16_bf16 v[48:63], v[146:149], v[158:161], v[48:63]
	v_mfma_f32_32x32x16_bf16 v[0:15], v[150:153], v[154:157], v[0:15]
	v_mfma_f32_32x32x16_bf16 v[32:47], v[150:153], v[158:161], v[32:47]
	global_load_dwordx4 v[146:149], v[72:73], off offset:1408
	global_load_dwordx4 v[150:153], v[76:77], off offset:1408
	s_waitcnt vmcnt(9)
	ds_write_b128 v100, v[138:141] offset:4608
	s_waitcnt vmcnt(8)
	ds_write_b128 v100, v[142:145] offset:23040
	ds_read_b128 v[138:141], v104 offset:36928
	ds_read_b128 v[142:145], v104 offset:41536
	ds_read_b128 v[154:157], v101 offset:55360
	ds_read_b128 v[158:161], v101 offset:59968
	s_waitcnt lgkmcnt(7)
	v_mfma_f32_32x32x16_bf16 v[16:31], v[66:69], v[162:165], v[16:31]
	s_waitcnt lgkmcnt(6)
	v_mfma_f32_32x32x16_bf16 v[48:63], v[66:69], v[166:169], v[48:63]
	v_mfma_f32_32x32x16_bf16 v[0:15], v[110:113], v[162:165], v[0:15]
	v_mfma_f32_32x32x16_bf16 v[32:47], v[110:113], v[166:169], v[32:47]
	global_load_dwordx4 v[66:69], v[80:81], off offset:1408
	global_load_dwordx4 v[110:113], v[84:85], off offset:1408
	s_waitcnt vmcnt(9)
	ds_write_b128 v100, v[114:117] offset:9216
	s_waitcnt vmcnt(8)
	ds_write_b128 v100, v[118:121] offset:27648
	ds_read_b128 v[114:117], v104 offset:36960
	ds_read_b128 v[118:121], v104 offset:41568
	ds_read_b128 v[162:165], v101 offset:55392
	ds_read_b128 v[166:169], v101 offset:60000
	s_waitcnt lgkmcnt(7)
	v_mfma_f32_32x32x16_bf16 v[16:31], v[138:141], v[154:157], v[16:31]
	s_waitcnt lgkmcnt(6)
	v_mfma_f32_32x32x16_bf16 v[48:63], v[138:141], v[158:161], v[48:63]
	v_mfma_f32_32x32x16_bf16 v[0:15], v[142:145], v[154:157], v[0:15]
	v_mfma_f32_32x32x16_bf16 v[32:47], v[142:145], v[158:161], v[32:47]
	global_load_dwordx4 v[138:141], v[88:89], off offset:1408
	global_load_dwordx4 v[142:145], v[92:93], off offset:1408
	s_waitcnt vmcnt(9)
	ds_write_b128 v100, v[122:125] offset:13824
	s_waitcnt vmcnt(8)
	ds_write_b128 v100, v[126:129] offset:32256
	s_waitcnt lgkmcnt(3)
	v_mfma_f32_32x32x16_bf16 v[16:31], v[114:117], v[162:165], v[16:31]
	s_waitcnt lgkmcnt(2)
	v_mfma_f32_32x32x16_bf16 v[48:63], v[114:117], v[166:169], v[48:63]
	v_mfma_f32_32x32x16_bf16 v[0:15], v[118:121], v[162:165], v[0:15]
	v_mfma_f32_32x32x16_bf16 v[32:47], v[118:121], v[166:169], v[32:47]
	s_waitcnt lgkmcnt(0)
	s_barrier
	global_load_dwordx4 v[114:117], v[64:65], off offset:1536
	global_load_dwordx4 v[118:121], v[106:107], off offset:1536
	ds_read_b128 v[122:125], v104
	ds_read_b128 v[126:129], v104 offset:4608
	ds_read_b128 v[154:157], v101 offset:18432
	ds_read_b128 v[158:161], v101 offset:23040
	s_waitcnt vmcnt(9)
	ds_write_b128 v100, v[130:133] offset:36864
	s_waitcnt vmcnt(8)
	ds_write_b128 v100, v[134:137] offset:55296
	ds_read_b128 v[130:133], v104 offset:32
	ds_read_b128 v[134:137], v104 offset:4640
	ds_read_b128 v[162:165], v101 offset:18464
	ds_read_b128 v[166:169], v101 offset:23072
	s_waitcnt lgkmcnt(7)
	v_mfma_f32_32x32x16_bf16 v[16:31], v[122:125], v[154:157], v[16:31]
	s_waitcnt lgkmcnt(6)
	v_mfma_f32_32x32x16_bf16 v[48:63], v[122:125], v[158:161], v[48:63]
	v_mfma_f32_32x32x16_bf16 v[0:15], v[126:129], v[154:157], v[0:15]
	v_mfma_f32_32x32x16_bf16 v[32:47], v[126:129], v[158:161], v[32:47]
	global_load_dwordx4 v[122:125], v[72:73], off offset:1536
	global_load_dwordx4 v[126:129], v[76:77], off offset:1536
	s_waitcnt vmcnt(9)
	ds_write_b128 v100, v[146:149] offset:41472
	s_waitcnt vmcnt(8)
	ds_write_b128 v100, v[150:153] offset:59904
	ds_read_b128 v[146:149], v104 offset:64
	ds_read_b128 v[150:153], v104 offset:4672
	ds_read_b128 v[154:157], v101 offset:18496
	ds_read_b128 v[158:161], v101 offset:23104
	s_waitcnt lgkmcnt(7)
	v_mfma_f32_32x32x16_bf16 v[16:31], v[130:133], v[162:165], v[16:31]
	s_waitcnt lgkmcnt(6)
	v_mfma_f32_32x32x16_bf16 v[48:63], v[130:133], v[166:169], v[48:63]
	v_mfma_f32_32x32x16_bf16 v[0:15], v[134:137], v[162:165], v[0:15]
	v_mfma_f32_32x32x16_bf16 v[32:47], v[134:137], v[166:169], v[32:47]
	global_load_dwordx4 v[130:133], v[80:81], off offset:1536
	global_load_dwordx4 v[134:137], v[84:85], off offset:1536
	s_waitcnt vmcnt(9)
	ds_write_b128 v100, v[66:69] offset:46080
	s_waitcnt vmcnt(8)
	ds_write_b128 v100, v[110:113] offset:64512
	ds_read_b128 v[66:69], v104 offset:96
	ds_read_b128 v[110:113], v104 offset:4704
	ds_read_b128 v[162:165], v101 offset:18528
	ds_read_b128 v[166:169], v101 offset:23136
	s_waitcnt lgkmcnt(7)
	v_mfma_f32_32x32x16_bf16 v[16:31], v[146:149], v[154:157], v[16:31]
	s_waitcnt lgkmcnt(6)
	v_mfma_f32_32x32x16_bf16 v[48:63], v[146:149], v[158:161], v[48:63]
	v_mfma_f32_32x32x16_bf16 v[0:15], v[150:153], v[154:157], v[0:15]
	v_mfma_f32_32x32x16_bf16 v[32:47], v[150:153], v[158:161], v[32:47]
	global_load_dwordx4 v[146:149], v[88:89], off offset:1536
	global_load_dwordx4 v[150:153], v[92:93], off offset:1536
	s_waitcnt vmcnt(9)
	ds_write_b128 v100, v[138:141] offset:50688
	s_waitcnt vmcnt(8)
	ds_write_b128 v105, v[142:145] offset:13824
	s_waitcnt lgkmcnt(3)
	v_mfma_f32_32x32x16_bf16 v[16:31], v[66:69], v[162:165], v[16:31]
	s_waitcnt lgkmcnt(2)
	v_mfma_f32_32x32x16_bf16 v[48:63], v[66:69], v[166:169], v[48:63]
	v_mfma_f32_32x32x16_bf16 v[0:15], v[110:113], v[162:165], v[0:15]
	v_mfma_f32_32x32x16_bf16 v[32:47], v[110:113], v[166:169], v[32:47]
	s_waitcnt lgkmcnt(0)
	s_barrier
; __device__ __forceinline__ void gemm_run(int tid, f32x16 (&acc)[2][2], GRegs& g, const GOp& o, int K, unsigned char* smem) {
;     ...
;   for (int k = 0; k < nk; k++) {
;     bf16r* cur = sbuf + (k & 1) * (256 * LDK);
;     bf16r* nxt = sbuf + ((k & 1) ^ 1) * (256 * LDK);
;     const bf16r* As = cur + (wm * 64 + fr) * LDK + fh * 8;
;     const bf16r* Bs = cur + 128 * LDK + (wn * 64 + fr) * LDK + fh * 8;
;     const bool wr = (k + 1 < nk), ld = (k + 2 < nk);
;     bf16x8 fa[2][2], fb[2][2];
;     fa[0][0] = *(const bf16x8*)(As);
;     fa[0][1] = *(const bf16x8*)(As + 32 * LDK);
;     fb[0][0] = *(const bf16x8*)(Bs);
;     fb[0][1] = *(const bf16x8*)(Bs + 32 * LDK);
; #pragma unroll
;     for (int i = 0; i < 4; i++) {
;       if (wr) {
;         *(u32x4*)(nxt + (r0 + i * 32) * LDK + sg * 8) = g.a[i];
;         *(u32x4*)(nxt + 128 * LDK + (r0 + i * 32) * LDK + sg * 8) = g.b[i];
;       }
;       if (ld) {
;         g.a[i] = *(const u32x4*)(Ap + (size_t)i * 32 * o.lda + (k + 2) * 64);
;         g.b[i] = *(const u32x4*)(Bp + o.bs.o[i] + (k + 2) * 64);
;       }
;       if (i < 3) {
;         fa[(i + 1) & 1][0] = *(const bf16x8*)(As + (i + 1) * 16);
;         fa[(i + 1) & 1][1] = *(const bf16x8*)(As + 32 * LDK + (i + 1) * 16);
;         fb[(i + 1) & 1][0] = *(const bf16x8*)(Bs + (i + 1) * 16);
;         fb[(i + 1) & 1][1] = *(const bf16x8*)(Bs + 32 * LDK + (i + 1) * 16);
;       }
;       __builtin_amdgcn_sched_barrier(0);
;       __builtin_amdgcn_s_setprio(1);
;       acc[0][0] = __builtin_amdgcn_mfma_f32_32x32x16_bf16(fa[i & 1][0], fb[i & 1][0], acc[0][0], 0, 0, 0);
;       acc[0][1] = __builtin_amdgcn_mfma_f32_32x32x16_bf16(fa[i & 1][0], fb[i & 1][1], acc[0][1], 0, 0, 0);
;       acc[1][0] = __builtin_amdgcn_mfma_f32_32x32x16_bf16(fa[i & 1][1], fb[i & 1][0], acc[1][0], 0, 0, 0);
;       acc[1][1] = __builtin_amdgcn_mfma_f32_32x32x16_bf16(fa[i & 1][1], fb[i & 1][1], acc[1][1], 0, 0, 0);
;       __builtin_amdgcn_s_setprio(0);
;     }
;     __syncthreads();
	global_load_dwordx4 v[66:69], v[64:65], off offset:1664
	global_load_dwordx4 v[110:113], v[106:107], off offset:1664
	ds_read_b128 v[138:141], v104 offset:36864
	ds_read_b128 v[142:145], v104 offset:41472
	ds_read_b128 v[154:157], v101 offset:55296
	ds_read_b128 v[158:161], v101 offset:59904
	s_waitcnt vmcnt(9)
	ds_write_b128 v100, v[114:117]
	s_waitcnt vmcnt(8)
	ds_write_b128 v100, v[118:121] offset:18432
	ds_read_b128 v[114:117], v104 offset:36896
	ds_read_b128 v[118:121], v104 offset:41504
	ds_read_b128 v[162:165], v101 offset:55328
	ds_read_b128 v[166:169], v101 offset:59936
	s_waitcnt lgkmcnt(7)
	v_mfma_f32_32x32x16_bf16 v[16:31], v[138:141], v[154:157], v[16:31]
	s_waitcnt lgkmcnt(6)
	v_mfma_f32_32x32x16_bf16 v[48:63], v[138:141], v[158:161], v[48:63]
	v_mfma_f32_32x32x16_bf16 v[0:15], v[142:145], v[154:157], v[0:15]
	v_mfma_f32_32x32x16_bf16 v[32:47], v[142:145], v[158:161], v[32:47]
	global_load_dwordx4 v[138:141], v[72:73], off offset:1664
	global_load_dwordx4 v[142:145], v[76:77], off offset:1664
	s_waitcnt vmcnt(9)
	ds_write_b128 v100, v[122:125] offset:4608
	s_waitcnt vmcnt(8)
	ds_write_b128 v100, v[126:129] offset:23040
	ds_read_b128 v[122:125], v104 offset:36928
	ds_read_b128 v[126:129], v104 offset:41536
	ds_read_b128 v[154:157], v101 offset:55360
	ds_read_b128 v[158:161], v101 offset:59968
	s_waitcnt lgkmcnt(7)
	v_mfma_f32_32x32x16_bf16 v[16:31], v[114:117], v[162:165], v[16:31]
	s_waitcnt lgkmcnt(6)
	v_mfma_f32_32x32x16_bf16 v[48:63], v[114:117], v[166:169], v[48:63]
	v_mfma_f32_32x32x16_bf16 v[0:15], v[118:121], v[162:165], v[0:15]
	v_mfma_f32_32x32x16_bf16 v[32:47], v[118:121], v[166:169], v[32:47]
	global_load_dwordx4 v[114:117], v[80:81], off offset:1664
	global_load_dwordx4 v[118:121], v[84:85], off offset:1664
	s_waitcnt vmcnt(9)
	ds_write_b128 v100, v[130:133] offset:9216
	s_waitcnt vmcnt(8)
	ds_write_b128 v100, v[134:137] offset:27648
	ds_read_b128 v[130:133], v104 offset:36960
	ds_read_b128 v[134:137], v104 offset:41568
	ds_read_b128 v[162:165], v101 offset:55392
	ds_read_b128 v[166:169], v101 offset:60000
	s_waitcnt lgkmcnt(7)
	v_mfma_f32_32x32x16_bf16 v[16:31], v[122:125], v[154:157], v[16:31]
	s_waitcnt lgkmcnt(6)
	v_mfma_f32_32x32x16_bf16 v[48:63], v[122:125], v[158:161], v[48:63]
	v_mfma_f32_32x32x16_bf16 v[0:15], v[126:129], v[154:157], v[0:15]
	v_mfma_f32_32x32x16_bf16 v[32:47], v[126:129], v[158:161], v[32:47]
	global_load_dwordx4 v[122:125], v[88:89], off offset:1664
	global_load_dwordx4 v[126:129], v[92:93], off offset:1664
	s_waitcnt vmcnt(9)
	ds_write_b128 v100, v[146:149] offset:13824
	s_waitcnt vmcnt(8)
	ds_write_b128 v100, v[150:153] offset:32256
	s_waitcnt lgkmcnt(3)
	v_mfma_f32_32x32x16_bf16 v[16:31], v[130:133], v[162:165], v[16:31]
	s_waitcnt lgkmcnt(2)
	v_mfma_f32_32x32x16_bf16 v[48:63], v[130:133], v[166:169], v[48:63]
	v_mfma_f32_32x32x16_bf16 v[0:15], v[134:137], v[162:165], v[0:15]
	v_mfma_f32_32x32x16_bf16 v[32:47], v[134:137], v[166:169], v[32:47]
	s_waitcnt lgkmcnt(0)
	s_barrier
	global_load_dwordx4 v[130:133], v[64:65], off offset:1792
	global_load_dwordx4 v[134:137], v[106:107], off offset:1792
	ds_read_b128 v[146:149], v104
	ds_read_b128 v[150:153], v104 offset:4608
	ds_read_b128 v[154:157], v101 offset:18432
	ds_read_b128 v[158:161], v101 offset:23040
	s_waitcnt vmcnt(9)
	ds_write_b128 v100, v[66:69] offset:36864
	s_waitcnt vmcnt(8)
	ds_write_b128 v100, v[110:113] offset:55296
	ds_read_b128 v[66:69], v104 offset:32
	ds_read_b128 v[110:113], v104 offset:4640
	ds_read_b128 v[162:165], v101 offset:18464
	ds_read_b128 v[166:169], v101 offset:23072
	s_waitcnt lgkmcnt(7)
	v_mfma_f32_32x32x16_bf16 v[16:31], v[146:149], v[154:157], v[16:31]
	s_waitcnt lgkmcnt(6)
	v_mfma_f32_32x32x16_bf16 v[48:63], v[146:149], v[158:161], v[48:63]
	v_mfma_f32_32x32x16_bf16 v[0:15], v[150:153], v[154:157], v[0:15]
	v_mfma_f32_32x32x16_bf16 v[32:47], v[150:153], v[158:161], v[32:47]
	global_load_dwordx4 v[146:149], v[72:73], off offset:1792
	global_load_dwordx4 v[150:153], v[76:77], off offset:1792
	s_waitcnt vmcnt(9)
	ds_write_b128 v100, v[138:141] offset:41472
	s_waitcnt vmcnt(8)
	ds_write_b128 v100, v[142:145] offset:59904
	ds_read_b128 v[138:141], v104 offset:64
	ds_read_b128 v[142:145], v104 offset:4672
	ds_read_b128 v[154:157], v101 offset:18496
	ds_read_b128 v[158:161], v101 offset:23104
	s_waitcnt lgkmcnt(7)
	v_mfma_f32_32x32x16_bf16 v[16:31], v[66:69], v[162:165], v[16:31]
	s_waitcnt lgkmcnt(6)
	v_mfma_f32_32x32x16_bf16 v[48:63], v[66:69], v[166:169], v[48:63]
	v_mfma_f32_32x32x16_bf16 v[0:15], v[110:113], v[162:165], v[0:15]
	v_mfma_f32_32x32x16_bf16 v[32:47], v[110:113], v[166:169], v[32:47]
	global_load_dwordx4 v[110:113], v[80:81], off offset:1792
	global_load_dwordx4 v[162:165], v[84:85], off offset:1792
	s_waitcnt vmcnt(9)
	ds_write_b128 v100, v[114:117] offset:46080
	s_waitcnt vmcnt(8)
	ds_write_b128 v100, v[118:121] offset:64512
	ds_read_b128 v[66:69], v104 offset:96
	ds_read_b128 v[114:117], v104 offset:4704
	ds_read_b128 v[118:121], v101 offset:18528
	ds_read_b128 v[166:169], v101 offset:23136
	s_waitcnt lgkmcnt(7)
	v_mfma_f32_32x32x16_bf16 v[16:31], v[138:141], v[154:157], v[16:31]
	s_waitcnt lgkmcnt(6)
	v_mfma_f32_32x32x16_bf16 v[48:63], v[138:141], v[158:161], v[48:63]
	v_mfma_f32_32x32x16_bf16 v[0:15], v[142:145], v[154:157], v[0:15]
	v_mfma_f32_32x32x16_bf16 v[32:47], v[142:145], v[158:161], v[32:47]
	global_load_dwordx4 v[138:141], v[88:89], off offset:1792
	global_load_dwordx4 v[142:145], v[92:93], off offset:1792
	s_waitcnt vmcnt(9)
	ds_write_b128 v100, v[122:125] offset:50688
	s_waitcnt vmcnt(8)
	ds_write_b128 v105, v[126:129] offset:13824
	s_waitcnt lgkmcnt(3)
	v_mfma_f32_32x32x16_bf16 v[16:31], v[66:69], v[118:121], v[16:31]
	s_waitcnt lgkmcnt(2)
	v_mfma_f32_32x32x16_bf16 v[48:63], v[66:69], v[166:169], v[48:63]
	v_mfma_f32_32x32x16_bf16 v[0:15], v[114:117], v[118:121], v[0:15]
	v_mfma_f32_32x32x16_bf16 v[32:47], v[114:117], v[166:169], v[32:47]
	s_waitcnt lgkmcnt(0)
	s_barrier
; __device__ __forceinline__ void gemm_run(int tid, f32x16 (&acc)[2][2], GRegs& g, const GOp& o, int K, unsigned char* smem) {
;     ...
;   for (int k = 0; k < nk; k++) {
;     bf16r* cur = sbuf + (k & 1) * (256 * LDK);
;     bf16r* nxt = sbuf + ((k & 1) ^ 1) * (256 * LDK);
;     const bf16r* As = cur + (wm * 64 + fr) * LDK + fh * 8;
;     const bf16r* Bs = cur + 128 * LDK + (wn * 64 + fr) * LDK + fh * 8;
;     const bool wr = (k + 1 < nk), ld = (k + 2 < nk);
;     bf16x8 fa[2][2], fb[2][2];
;     fa[0][0] = *(const bf16x8*)(As);
;     fa[0][1] = *(const bf16x8*)(As + 32 * LDK);
;     fb[0][0] = *(const bf16x8*)(Bs);
;     fb[0][1] = *(const bf16x8*)(Bs + 32 * LDK);
; #pragma unroll
;     for (int i = 0; i < 4; i++) {
;       if (wr) {
;         *(u32x4*)(nxt + (r0 + i * 32) * LDK + sg * 8) = g.a[i];
;         *(u32x4*)(nxt + 128 * LDK + (r0 + i * 32) * LDK + sg * 8) = g.b[i];
;       }
;       if (ld) {
;         g.a[i] = *(const u32x4*)(Ap + (size_t)i * 32 * o.lda + (k + 2) * 64);
;         g.b[i] = *(const u32x4*)(Bp + o.bs.o[i] + (k + 2) * 64);
;       }
;       if (i < 3) {
;         fa[(i + 1) & 1][0] = *(const bf16x8*)(As + (i + 1) * 16);
;         fa[(i + 1) & 1][1] = *(const bf16x8*)(As + 32 * LDK + (i + 1) * 16);
;         fb[(i + 1) & 1][0] = *(const bf16x8*)(Bs + (i + 1) * 16);
;         fb[(i + 1) & 1][1] = *(const bf16x8*)(Bs + 32 * LDK + (i + 1) * 16);
;       }
;       __builtin_amdgcn_sched_barrier(0);
;       __builtin_amdgcn_s_setprio(1);
;       acc[0][0] = __builtin_amdgcn_mfma_f32_32x32x16_bf16(fa[i & 1][0], fb[i & 1][0], acc[0][0], 0, 0, 0);
;       acc[0][1] = __builtin_amdgcn_mfma_f32_32x32x16_bf16(fa[i & 1][0], fb[i & 1][1], acc[0][1], 0, 0, 0);
;       acc[1][0] = __builtin_amdgcn_mfma_f32_32x32x16_bf16(fa[i & 1][1], fb[i & 1][0], acc[1][0], 0, 0, 0);
;       acc[1][1] = __builtin_amdgcn_mfma_f32_32x32x16_bf16(fa[i & 1][1], fb[i & 1][1], acc[1][1], 0, 0, 0);
;       __builtin_amdgcn_s_setprio(0);
;     }
;     __syncthreads();
	global_load_dwordx4 v[64:67], v[64:65], off offset:1920
	s_nop 0
	global_load_dwordx4 v[68:71], v[106:107], off offset:1920
	ds_read_b128 v[114:117], v104 offset:36864
	ds_read_b128 v[118:121], v104 offset:41472
	ds_read_b128 v[122:125], v101 offset:55296
	ds_read_b128 v[126:129], v101 offset:59904
	s_waitcnt vmcnt(9)
	ds_write_b128 v100, v[130:133]
	s_waitcnt vmcnt(8)
	ds_write_b128 v100, v[134:137] offset:18432
	ds_read_b128 v[130:133], v104 offset:36896
	ds_read_b128 v[134:137], v104 offset:41504
	ds_read_b128 v[154:157], v101 offset:55328
	ds_read_b128 v[158:161], v101 offset:59936
	s_waitcnt lgkmcnt(7)
	v_mfma_f32_32x32x16_bf16 v[16:31], v[114:117], v[122:125], v[16:31]
	s_waitcnt lgkmcnt(6)
	v_mfma_f32_32x32x16_bf16 v[48:63], v[114:117], v[126:129], v[48:63]
	v_mfma_f32_32x32x16_bf16 v[0:15], v[118:121], v[122:125], v[0:15]
	v_mfma_f32_32x32x16_bf16 v[32:47], v[118:121], v[126:129], v[32:47]
	global_load_dwordx4 v[72:75], v[72:73], off offset:1920
	s_nop 0
	global_load_dwordx4 v[76:79], v[76:77], off offset:1920
	s_waitcnt vmcnt(9)
	ds_write_b128 v100, v[146:149] offset:4608
	s_waitcnt vmcnt(8)
	ds_write_b128 v100, v[150:153] offset:23040
	ds_read_b128 v[114:117], v104 offset:36928
	ds_read_b128 v[118:121], v104 offset:41536
	ds_read_b128 v[122:125], v101 offset:55360
	ds_read_b128 v[126:129], v101 offset:59968
	s_waitcnt lgkmcnt(7)
	v_mfma_f32_32x32x16_bf16 v[16:31], v[130:133], v[154:157], v[16:31]
	s_waitcnt lgkmcnt(6)
	v_mfma_f32_32x32x16_bf16 v[48:63], v[130:133], v[158:161], v[48:63]
	v_mfma_f32_32x32x16_bf16 v[0:15], v[134:137], v[154:157], v[0:15]
	v_mfma_f32_32x32x16_bf16 v[32:47], v[134:137], v[158:161], v[32:47]
	global_load_dwordx4 v[80:83], v[80:81], off offset:1920
	s_nop 0
	global_load_dwordx4 v[84:87], v[84:85], off offset:1920
	s_waitcnt vmcnt(9)
	ds_write_b128 v100, v[110:113] offset:9216
	s_waitcnt vmcnt(8)
	ds_write_b128 v100, v[162:165] offset:27648
	ds_read_b128 v[110:113], v104 offset:36960
	ds_read_b128 v[130:133], v104 offset:41568
	ds_read_b128 v[134:137], v101 offset:55392
	ds_read_b128 v[146:149], v101 offset:60000
	s_waitcnt lgkmcnt(7)
	v_mfma_f32_32x32x16_bf16 v[16:31], v[114:117], v[122:125], v[16:31]
	s_waitcnt lgkmcnt(6)
	v_mfma_f32_32x32x16_bf16 v[48:63], v[114:117], v[126:129], v[48:63]
	v_mfma_f32_32x32x16_bf16 v[0:15], v[118:121], v[122:125], v[0:15]
	v_mfma_f32_32x32x16_bf16 v[32:47], v[118:121], v[126:129], v[32:47]
	global_load_dwordx4 v[88:91], v[88:89], off offset:1920
	s_nop 0
	global_load_dwordx4 v[92:95], v[92:93], off offset:1920
	s_waitcnt vmcnt(9)
	ds_write_b128 v100, v[138:141] offset:13824
	s_waitcnt vmcnt(8)
	ds_write_b128 v100, v[142:145] offset:32256
	s_waitcnt lgkmcnt(3)
	v_mfma_f32_32x32x16_bf16 v[16:31], v[110:113], v[134:137], v[16:31]
	s_waitcnt lgkmcnt(2)
	v_mfma_f32_32x32x16_bf16 v[48:63], v[110:113], v[146:149], v[48:63]
	v_mfma_f32_32x32x16_bf16 v[0:15], v[130:133], v[134:137], v[0:15]
	v_mfma_f32_32x32x16_bf16 v[32:47], v[130:133], v[146:149], v[32:47]
	s_waitcnt lgkmcnt(0)
	s_barrier
; __device__ __forceinline__ void gemm_run(int tid, f32x16 (&acc)[2][2], GRegs& g, const GOp& o, int K, unsigned char* smem) {
;     ...
;   for (int k = 0; k < nk; k++) {
;     bf16r* cur = sbuf + (k & 1) * (256 * LDK);
;     bf16r* nxt = sbuf + ((k & 1) ^ 1) * (256 * LDK);
;     const bf16r* As = cur + (wm * 64 + fr) * LDK + fh * 8;
;     const bf16r* Bs = cur + 128 * LDK + (wn * 64 + fr) * LDK + fh * 8;
;     const bool wr = (k + 1 < nk), ld = (k + 2 < nk);
;     bf16x8 fa[2][2], fb[2][2];
;     fa[0][0] = *(const bf16x8*)(As);
;     fa[0][1] = *(const bf16x8*)(As + 32 * LDK);
;     fb[0][0] = *(const bf16x8*)(Bs);
;     fb[0][1] = *(const bf16x8*)(Bs + 32 * LDK);
; #pragma unroll
;     for (int i = 0; i < 4; i++) {
;       if (wr) {
;         *(u32x4*)(nxt + (r0 + i * 32) * LDK + sg * 8) = g.a[i];
;         *(u32x4*)(nxt + 128 * LDK + (r0 + i * 32) * LDK + sg * 8) = g.b[i];
;       }
;       if (ld) {
;         g.a[i] = *(const u32x4*)(Ap + (size_t)i * 32 * o.lda + (k + 2) * 64);
;         g.b[i] = *(const u32x4*)(Bp + o.bs.o[i] + (k + 2) * 64);
;       }
;       if (i < 3) {
;         fa[(i + 1) & 1][0] = *(const bf16x8*)(As + (i + 1) * 16);
;         fa[(i + 1) & 1][1] = *(const bf16x8*)(As + 32 * LDK + (i + 1) * 16);
;         fb[(i + 1) & 1][0] = *(const bf16x8*)(Bs + (i + 1) * 16);
;         fb[(i + 1) & 1][1] = *(const bf16x8*)(Bs + 32 * LDK + (i + 1) * 16);
;       }
;       __builtin_amdgcn_sched_barrier(0);
;       __builtin_amdgcn_s_setprio(1);
;       acc[0][0] = __builtin_amdgcn_mfma_f32_32x32x16_bf16(fa[i & 1][0], fb[i & 1][0], acc[0][0], 0, 0, 0);
;       acc[0][1] = __builtin_amdgcn_mfma_f32_32x32x16_bf16(fa[i & 1][0], fb[i & 1][1], acc[0][1], 0, 0, 0);
;       acc[1][0] = __builtin_amdgcn_mfma_f32_32x32x16_bf16(fa[i & 1][1], fb[i & 1][0], acc[1][0], 0, 0, 0);
;       acc[1][1] = __builtin_amdgcn_mfma_f32_32x32x16_bf16(fa[i & 1][1], fb[i & 1][1], acc[1][1], 0, 0, 0);
;       __builtin_amdgcn_s_setprio(0);
;     }
;     __syncthreads();
;   }
; __device__ __forceinline__ bool tile_map(int it, int nn, int& mt, int& nt) {
;   const int xcd = blockIdx.x & 7, li = blockIdx.x >> 3, nb = gridDim.x >> 3;
;   int q = it * nb + li;
;   const int per = 16 * nn;
;   if (q < per) {
;     int sub = q / (8 * nn), r = q - sub * (8 * nn);
;     nt = r >> 3;
;     mt = xcd * 16 + sub * 8 + (r & 7);
;     return true;
	ds_read_b128 v[110:113], v104
	ds_read_b128 v[114:117], v104 offset:4608
	ds_read_b128 v[118:121], v101 offset:18432
	ds_read_b128 v[122:125], v101 offset:23040
	s_waitcnt vmcnt(7)
	ds_write_b128 v100, v[64:67] offset:36864
	s_waitcnt vmcnt(6)
	ds_write_b128 v100, v[68:71] offset:55296
	ds_read_b128 v[126:129], v104 offset:32
	ds_read_b128 v[130:133], v104 offset:4640
	ds_read_b128 v[134:137], v101 offset:18464
	ds_read_b128 v[138:141], v101 offset:23072
	s_waitcnt lgkmcnt(7)
	v_mfma_f32_32x32x16_bf16 v[16:31], v[110:113], v[118:121], v[16:31]
	s_waitcnt lgkmcnt(6)
	v_mfma_f32_32x32x16_bf16 v[48:63], v[110:113], v[122:125], v[48:63]
	v_mfma_f32_32x32x16_bf16 v[0:15], v[114:117], v[118:121], v[0:15]
	v_mfma_f32_32x32x16_bf16 v[32:47], v[114:117], v[122:125], v[32:47]
	s_waitcnt vmcnt(5)
	ds_write_b128 v100, v[72:75] offset:41472
	s_waitcnt vmcnt(4)
	ds_write_b128 v100, v[76:79] offset:59904
	ds_read_b128 v[110:113], v104 offset:64
	ds_read_b128 v[114:117], v104 offset:4672
	ds_read_b128 v[118:121], v101 offset:18496
	ds_read_b128 v[122:125], v101 offset:23104
	s_waitcnt lgkmcnt(7)
	v_mfma_f32_32x32x16_bf16 v[16:31], v[126:129], v[134:137], v[16:31]
	s_waitcnt lgkmcnt(6)
	v_mfma_f32_32x32x16_bf16 v[48:63], v[126:129], v[138:141], v[48:63]
	v_mfma_f32_32x32x16_bf16 v[0:15], v[130:133], v[134:137], v[0:15]
	v_mfma_f32_32x32x16_bf16 v[32:47], v[130:133], v[138:141], v[32:47]
	s_waitcnt vmcnt(3)
	ds_write_b128 v100, v[80:83] offset:46080
	s_waitcnt vmcnt(2)
	ds_write_b128 v100, v[84:87] offset:64512
	ds_read_b128 v[126:129], v104 offset:96
	ds_read_b128 v[130:133], v104 offset:4704
	ds_read_b128 v[134:137], v101 offset:18528
	ds_read_b128 v[138:141], v101 offset:23136
	s_waitcnt lgkmcnt(7)
	v_mfma_f32_32x32x16_bf16 v[16:31], v[110:113], v[118:121], v[16:31]
	s_waitcnt lgkmcnt(6)
	v_mfma_f32_32x32x16_bf16 v[48:63], v[110:113], v[122:125], v[48:63]
	v_mfma_f32_32x32x16_bf16 v[0:15], v[114:117], v[118:121], v[0:15]
	v_mfma_f32_32x32x16_bf16 v[32:47], v[114:117], v[122:125], v[32:47]
	s_waitcnt vmcnt(1)
	ds_write_b128 v100, v[88:91] offset:50688
	s_waitcnt vmcnt(0)
	ds_write_b128 v105, v[92:95] offset:13824
	s_waitcnt lgkmcnt(3)
	v_mfma_f32_32x32x16_bf16 v[16:31], v[126:129], v[134:137], v[16:31]
	s_waitcnt lgkmcnt(2)
	v_mfma_f32_32x32x16_bf16 v[48:63], v[126:129], v[138:141], v[48:63]
	v_mfma_f32_32x32x16_bf16 v[0:15], v[130:133], v[134:137], v[0:15]
	v_mfma_f32_32x32x16_bf16 v[32:47], v[130:133], v[138:141], v[32:47]
	s_waitcnt lgkmcnt(0)
	s_barrier
	ds_read_b128 v[110:113], v104 offset:36864
	ds_read_b128 v[114:117], v104 offset:36896
	ds_read_b128 v[118:121], v104 offset:41472
	ds_read_b128 v[122:125], v104 offset:41504
	ds_read_b128 v[126:129], v101 offset:55296
	ds_read_b128 v[130:133], v101 offset:55328
	ds_read_b128 v[134:137], v101 offset:59904
	ds_read_b128 v[138:141], v101 offset:59936
	s_waitcnt lgkmcnt(3)
	v_mfma_f32_32x32x16_bf16 v[16:31], v[110:113], v[126:129], v[16:31]
	s_waitcnt lgkmcnt(1)
	v_mfma_f32_32x32x16_bf16 v[48:63], v[110:113], v[134:137], v[48:63]
	v_mfma_f32_32x32x16_bf16 v[0:15], v[118:121], v[126:129], v[0:15]
	v_mfma_f32_32x32x16_bf16 v[32:47], v[118:121], v[134:137], v[32:47]
	ds_read_b128 v[110:113], v104 offset:36928
	ds_read_b128 v[118:121], v104 offset:41536
	ds_read_b128 v[126:129], v101 offset:55360
	ds_read_b128 v[134:137], v101 offset:59968
	v_mfma_f32_32x32x16_bf16 v[16:31], v[114:117], v[130:133], v[16:31]
	s_waitcnt lgkmcnt(4)
	v_mfma_f32_32x32x16_bf16 v[48:63], v[114:117], v[138:141], v[48:63]
	v_mfma_f32_32x32x16_bf16 v[0:15], v[122:125], v[130:133], v[0:15]
	v_mfma_f32_32x32x16_bf16 v[32:47], v[122:125], v[138:141], v[32:47]
	ds_read_b128 v[114:117], v104 offset:36960
	ds_read_b128 v[122:125], v104 offset:41568
	ds_read_b128 v[130:133], v101 offset:55392
	ds_read_b128 v[138:141], v101 offset:60000
	s_waitcnt lgkmcnt(5)
	v_mfma_f32_32x32x16_bf16 v[16:31], v[110:113], v[126:129], v[16:31]
	s_waitcnt lgkmcnt(4)
	v_mfma_f32_32x32x16_bf16 v[48:63], v[110:113], v[134:137], v[48:63]
	v_mfma_f32_32x32x16_bf16 v[0:15], v[118:121], v[126:129], v[0:15]
	v_mfma_f32_32x32x16_bf16 v[32:47], v[118:121], v[134:137], v[32:47]
	s_waitcnt lgkmcnt(1)
	v_mfma_f32_32x32x16_bf16 v[16:31], v[114:117], v[130:133], v[16:31]
	s_waitcnt lgkmcnt(0)
	v_mfma_f32_32x32x16_bf16 v[48:63], v[114:117], v[138:141], v[48:63]
	v_mfma_f32_32x32x16_bf16 v[0:15], v[122:125], v[130:133], v[0:15]
	v_mfma_f32_32x32x16_bf16 v[32:47], v[122:125], v[138:141], v[32:47]
	s_cmpk_gt_u32 s87, 0x18f
	s_mov_b64 s[10:11], -1
	s_barrier
	s_cbranch_scc0 .LBB0_2977
	s_mov_b64 s[10:11], 0
	s_cmp_gt_i32 s96, 24
	s_mov_b64 s[4:5], 0
	s_cbranch_scc1 .LBB0_2977
	s_movk_i32 s66, 0x80
	s_mov_b64 s[4:5], -1
	s_mov_b32 s42, s96

; __device__ __forceinline__ void gemm_run(int tid, f32x16 (&acc)[2][2], GRegs& g, const GOp& o, int K, unsigned char* smem) {
;     ...
;   const int nk = K >> 6;
; #pragma unroll
;   for (int i = 0; i < 4; i++) {
;     *(u32x4*)(sbuf + (r0 + i * 32) * LDK + sg * 8) = g.a[i];
;     *(u32x4*)(sbuf + 128 * LDK + (r0 + i * 32) * LDK + sg * 8) = g.b[i];
;   }
;   if (nk > 1) {
; #pragma unroll
;     for (int i = 0; i < 4; i++) {
;       g.a[i] = *(const u32x4*)(Ap + (size_t)i * 32 * o.lda + 64);
;       g.b[i] = *(const u32x4*)(Bp + o.bs.o[i] + 64);
;     }
;   }
;   __syncthreads();
;   const int lane = tid & 63, fr = lane & 31, fh = lane >> 5;
;   for (int k = 0; k < nk; k++) {
;     bf16r* cur = sbuf + (k & 1) * (256 * LDK);
;     bf16r* nxt = sbuf + ((k & 1) ^ 1) * (256 * LDK);
;     const bf16r* As = cur + (wm * 64 + fr) * LDK + fh * 8;
;     const bf16r* Bs = cur + 128 * LDK + (wn * 64 + fr) * LDK + fh * 8;
;     const bool wr = (k + 1 < nk), ld = (k + 2 < nk);
;     bf16x8 fa[2][2], fb[2][2];
;     fa[0][0] = *(const bf16x8*)(As);
;     fa[0][1] = *(const bf16x8*)(As + 32 * LDK);
;     fb[0][0] = *(const bf16x8*)(Bs);
;     fb[0][1] = *(const bf16x8*)(Bs + 32 * LDK);
; #pragma unroll
;     for (int i = 0; i < 4; i++) {
;       if (wr) {
;         *(u32x4*)(nxt + (r0 + i * 32) * LDK + sg * 8) = g.a[i];
;         *(u32x4*)(nxt + 128 * LDK + (r0 + i * 32) * LDK + sg * 8) = g.b[i];
;       }
;       if (ld) {
;         g.a[i] = *(const u32x4*)(Ap + (size_t)i * 32 * o.lda + (k + 2) * 64);
;         g.b[i] = *(const u32x4*)(Bp + o.bs.o[i] + (k + 2) * 64);
;       }
;       if (i < 3) {
;         fa[(i + 1) & 1][0] = *(const bf16x8*)(As + (i + 1) * 16);
;         fa[(i + 1) & 1][1] = *(const bf16x8*)(As + 32 * LDK + (i + 1) * 16);
;         fb[(i + 1) & 1][0] = *(const bf16x8*)(Bs + (i + 1) * 16);
;         fb[(i + 1) & 1][1] = *(const bf16x8*)(Bs + 32 * LDK + (i + 1) * 16);
;       }
;       __builtin_amdgcn_sched_barrier(0);
;       __builtin_amdgcn_s_setprio(1);
;       acc[0][0] = __builtin_amdgcn_mfma_f32_32x32x16_bf16(fa[i & 1][0], fb[i & 1][0], acc[0][0], 0, 0, 0);
;       acc[0][1] = __builtin_amdgcn_mfma_f32_32x32x16_bf16(fa[i & 1][0], fb[i & 1][1], acc[0][1], 0, 0, 0);
;       acc[1][0] = __builtin_amdgcn_mfma_f32_32x32x16_bf16(fa[i & 1][1], fb[i & 1][0], acc[1][0], 0, 0, 0);
.LBB0_3308:
	s_ashr_i32 s7, s6, 31
	s_lshl_b64 s[4:5], s[6:7], 18
	s_ashr_i32 s9, s8, 31
	s_waitcnt vmcnt(7)
	ds_write_b128 v100, v[64:67]
	s_waitcnt vmcnt(6)
	ds_write_b128 v100, v[68:71] offset:18432
	s_waitcnt vmcnt(5)
	ds_write_b128 v100, v[72:75] offset:4608
	s_waitcnt vmcnt(4)
	ds_write_b128 v100, v[76:79] offset:23040
	s_waitcnt vmcnt(3)
	ds_write_b128 v100, v[80:83] offset:9216
	s_waitcnt vmcnt(2)
	ds_write_b128 v100, v[84:87] offset:27648
	s_waitcnt vmcnt(1)
	ds_write_b128 v100, v[88:91] offset:13824
	s_waitcnt vmcnt(0)
	ds_write_b128 v100, v[92:95] offset:32256
	v_lshl_add_u64 v[64:65], v[102:103], 0, s[4:5]
	s_lshl_b64 s[10:11], s[8:9], 18
	v_add_co_u32_e32 v72, vcc, s78, v64
	v_lshl_add_u64 v[106:107], v[98:99], 0, s[10:11]
	s_nop 0
	v_addc_co_u32_e32 v73, vcc, 0, v65, vcc
	v_add_co_u32_e32 v76, vcc, s78, v106
	global_load_dwordx4 v[0:3], v[64:65], off offset:128
	global_load_dwordx4 v[4:7], v[106:107], off offset:128
	v_addc_co_u32_e32 v77, vcc, 0, v107, vcc
	v_add_co_u32_e32 v80, vcc, s79, v64
	global_load_dwordx4 v[66:69], v[72:73], off offset:128
	global_load_dwordx4 v[110:113], v[76:77], off offset:128
	v_addc_co_u32_e32 v81, vcc, 0, v65, vcc
	v_add_co_u32_e32 v84, vcc, s79, v106
	s_nop 1
	v_addc_co_u32_e32 v85, vcc, 0, v107, vcc
	v_add_co_u32_e32 v88, vcc, s80, v64
	global_load_dwordx4 v[114:117], v[80:81], off offset:128
	global_load_dwordx4 v[118:121], v[84:85], off offset:128
	v_addc_co_u32_e32 v89, vcc, 0, v65, vcc
	v_add_co_u32_e32 v92, vcc, s80, v106
	s_nop 1
	v_addc_co_u32_e32 v93, vcc, 0, v107, vcc
	global_load_dwordx4 v[122:125], v[88:89], off offset:128
	global_load_dwordx4 v[126:129], v[92:93], off offset:128
	s_waitcnt lgkmcnt(0)
	s_barrier
	global_load_dwordx4 v[130:133], v[64:65], off offset:256
	global_load_dwordx4 v[134:137], v[106:107], off offset:256
	ds_read_b128 v[8:11], v104
	ds_read_b128 v[32:35], v104 offset:4608
	ds_read_b128 v[12:15], v101 offset:18432
	ds_read_b128 v[36:39], v101 offset:23040
	s_waitcnt vmcnt(9)
	ds_write_b128 v100, v[0:3] offset:36864
	s_waitcnt vmcnt(8)
	ds_write_b128 v100, v[4:7] offset:55296
	ds_read_b128 v[138:141], v104 offset:32
	ds_read_b128 v[142:145], v104 offset:4640
	ds_read_b128 v[146:149], v101 offset:18464
	ds_read_b128 v[150:153], v101 offset:23072
	s_waitcnt lgkmcnt(7)
	v_mfma_f32_32x32x16_bf16 v[16:31], v[8:11], v[12:15], 0
	s_waitcnt lgkmcnt(6)
	v_mfma_f32_32x32x16_bf16 v[48:63], v[8:11], v[36:39], 0
	v_mfma_f32_32x32x16_bf16 v[0:15], v[32:35], v[12:15], 0
	v_mfma_f32_32x32x16_bf16 v[32:47], v[32:35], v[36:39], 0
	global_load_dwordx4 v[154:157], v[72:73], off offset:256
	global_load_dwordx4 v[158:161], v[76:77], off offset:256
	s_waitcnt vmcnt(9)
	ds_write_b128 v100, v[66:69] offset:41472
	s_waitcnt vmcnt(8)
	ds_write_b128 v100, v[110:113] offset:59904
	ds_read_b128 v[66:69], v104 offset:64
	ds_read_b128 v[110:113], v104 offset:4672
	ds_read_b128 v[162:165], v101 offset:18496
	ds_read_b128 v[166:169], v101 offset:23104
	s_waitcnt lgkmcnt(7)
	v_mfma_f32_32x32x16_bf16 v[16:31], v[138:141], v[146:149], v[16:31]
	s_waitcnt lgkmcnt(6)
	v_mfma_f32_32x32x16_bf16 v[48:63], v[138:141], v[150:153], v[48:63]
	v_mfma_f32_32x32x16_bf16 v[0:15], v[142:145], v[146:149], v[0:15]
	v_mfma_f32_32x32x16_bf16 v[32:47], v[142:145], v[150:153], v[32:47]
	global_load_dwordx4 v[138:141], v[80:81], off offset:256
	global_load_dwordx4 v[142:145], v[84:85], off offset:256
	s_waitcnt vmcnt(9)
	ds_write_b128 v100, v[114:117] offset:46080
	s_waitcnt vmcnt(8)
	ds_write_b128 v100, v[118:121] offset:64512
	ds_read_b128 v[114:117], v104 offset:96
	ds_read_b128 v[118:121], v104 offset:4704
	ds_read_b128 v[146:149], v101 offset:18528
	ds_read_b128 v[150:153], v101 offset:23136
	s_waitcnt lgkmcnt(7)
	v_mfma_f32_32x32x16_bf16 v[16:31], v[66:69], v[162:165], v[16:31]
	s_waitcnt lgkmcnt(6)
	v_mfma_f32_32x32x16_bf16 v[48:63], v[66:69], v[166:169], v[48:63]
	v_mfma_f32_32x32x16_bf16 v[0:15], v[110:113], v[162:165], v[0:15]
	v_mfma_f32_32x32x16_bf16 v[32:47], v[110:113], v[166:169], v[32:47]
	global_load_dwordx4 v[66:69], v[88:89], off offset:256
	global_load_dwordx4 v[110:113], v[92:93], off offset:256
	s_waitcnt vmcnt(9)
	ds_write_b128 v100, v[122:125] offset:50688
	s_waitcnt vmcnt(8)
	ds_write_b128 v105, v[126:129] offset:13824
	s_waitcnt lgkmcnt(3)
	v_mfma_f32_32x32x16_bf16 v[16:31], v[114:117], v[146:149], v[16:31]
	s_waitcnt lgkmcnt(2)
	v_mfma_f32_32x32x16_bf16 v[48:63], v[114:117], v[150:153], v[48:63]
	v_mfma_f32_32x32x16_bf16 v[0:15], v[118:121], v[146:149], v[0:15]
	v_mfma_f32_32x32x16_bf16 v[32:47], v[118:121], v[150:153], v[32:47]
	s_waitcnt lgkmcnt(0)
	s_barrier
; __device__ __forceinline__ void gemm_run(int tid, f32x16 (&acc)[2][2], GRegs& g, const GOp& o, int K, unsigned char* smem) {
;     ...
;   for (int k = 0; k < nk; k++) {
;     bf16r* cur = sbuf + (k & 1) * (256 * LDK);
;     bf16r* nxt = sbuf + ((k & 1) ^ 1) * (256 * LDK);
;     const bf16r* As = cur + (wm * 64 + fr) * LDK + fh * 8;
;     const bf16r* Bs = cur + 128 * LDK + (wn * 64 + fr) * LDK + fh * 8;
;     const bool wr = (k + 1 < nk), ld = (k + 2 < nk);
;     bf16x8 fa[2][2], fb[2][2];
;     fa[0][0] = *(const bf16x8*)(As);
;     fa[0][1] = *(const bf16x8*)(As + 32 * LDK);
;     fb[0][0] = *(const bf16x8*)(Bs);
;     fb[0][1] = *(const bf16x8*)(Bs + 32 * LDK);
; #pragma unroll
;     for (int i = 0; i < 4; i++) {
;       if (wr) {
;         *(u32x4*)(nxt + (r0 + i * 32) * LDK + sg * 8) = g.a[i];
;         *(u32x4*)(nxt + 128 * LDK + (r0 + i * 32) * LDK + sg * 8) = g.b[i];
;       }
;       if (ld) {
;         g.a[i] = *(const u32x4*)(Ap + (size_t)i * 32 * o.lda + (k + 2) * 64);
;         g.b[i] = *(const u32x4*)(Bp + o.bs.o[i] + (k + 2) * 64);
;       }
;       if (i < 3) {
;         fa[(i + 1) & 1][0] = *(const bf16x8*)(As + (i + 1) * 16);
;         fa[(i + 1) & 1][1] = *(const bf16x8*)(As + 32 * LDK + (i + 1) * 16);
;         fb[(i + 1) & 1][0] = *(const bf16x8*)(Bs + (i + 1) * 16);
;         fb[(i + 1) & 1][1] = *(const bf16x8*)(Bs + 32 * LDK + (i + 1) * 16);
;       }
;       __builtin_amdgcn_sched_barrier(0);
;       __builtin_amdgcn_s_setprio(1);
;       acc[0][0] = __builtin_amdgcn_mfma_f32_32x32x16_bf16(fa[i & 1][0], fb[i & 1][0], acc[0][0], 0, 0, 0);
;       acc[0][1] = __builtin_amdgcn_mfma_f32_32x32x16_bf16(fa[i & 1][0], fb[i & 1][1], acc[0][1], 0, 0, 0);
;       acc[1][0] = __builtin_amdgcn_mfma_f32_32x32x16_bf16(fa[i & 1][1], fb[i & 1][0], acc[1][0], 0, 0, 0);
;       acc[1][1] = __builtin_amdgcn_mfma_f32_32x32x16_bf16(fa[i & 1][1], fb[i & 1][1], acc[1][1], 0, 0, 0);
;       __builtin_amdgcn_s_setprio(0);
;     }
;     __syncthreads();
	global_load_dwordx4 v[114:117], v[64:65], off offset:384
	global_load_dwordx4 v[118:121], v[106:107], off offset:384
	ds_read_b128 v[122:125], v104 offset:36864
	ds_read_b128 v[126:129], v104 offset:41472
	ds_read_b128 v[146:149], v101 offset:55296
	ds_read_b128 v[150:153], v101 offset:59904
	s_waitcnt vmcnt(9)
	ds_write_b128 v100, v[130:133]
	s_waitcnt vmcnt(8)
	ds_write_b128 v100, v[134:137] offset:18432
	ds_read_b128 v[130:133], v104 offset:36896
	ds_read_b128 v[134:137], v104 offset:41504
	ds_read_b128 v[162:165], v101 offset:55328
	ds_read_b128 v[166:169], v101 offset:59936
	s_waitcnt lgkmcnt(7)
	v_mfma_f32_32x32x16_bf16 v[16:31], v[122:125], v[146:149], v[16:31]
	s_waitcnt lgkmcnt(6)
	v_mfma_f32_32x32x16_bf16 v[48:63], v[122:125], v[150:153], v[48:63]
	v_mfma_f32_32x32x16_bf16 v[0:15], v[126:129], v[146:149], v[0:15]
	v_mfma_f32_32x32x16_bf16 v[32:47], v[126:129], v[150:153], v[32:47]
	global_load_dwordx4 v[122:125], v[72:73], off offset:384
	global_load_dwordx4 v[126:129], v[76:77], off offset:384
	s_waitcnt vmcnt(9)
	ds_write_b128 v100, v[154:157] offset:4608
	s_waitcnt vmcnt(8)
	ds_write_b128 v100, v[158:161] offset:23040
	ds_read_b128 v[146:149], v104 offset:36928
	ds_read_b128 v[150:153], v104 offset:41536
	ds_read_b128 v[154:157], v101 offset:55360
	ds_read_b128 v[158:161], v101 offset:59968
	s_waitcnt lgkmcnt(7)
	v_mfma_f32_32x32x16_bf16 v[16:31], v[130:133], v[162:165], v[16:31]
	s_waitcnt lgkmcnt(6)
	v_mfma_f32_32x32x16_bf16 v[48:63], v[130:133], v[166:169], v[48:63]
	v_mfma_f32_32x32x16_bf16 v[0:15], v[134:137], v[162:165], v[0:15]
	v_mfma_f32_32x32x16_bf16 v[32:47], v[134:137], v[166:169], v[32:47]
	global_load_dwordx4 v[130:133], v[80:81], off offset:384
	global_load_dwordx4 v[134:137], v[84:85], off offset:384
	s_waitcnt vmcnt(9)
	ds_write_b128 v100, v[138:141] offset:9216
	s_waitcnt vmcnt(8)
	ds_write_b128 v100, v[142:145] offset:27648
	ds_read_b128 v[138:141], v104 offset:36960
	ds_read_b128 v[142:145], v104 offset:41568
	ds_read_b128 v[162:165], v101 offset:55392
	ds_read_b128 v[166:169], v101 offset:60000
	s_waitcnt lgkmcnt(7)
	v_mfma_f32_32x32x16_bf16 v[16:31], v[146:149], v[154:157], v[16:31]
	s_waitcnt lgkmcnt(6)
	v_mfma_f32_32x32x16_bf16 v[48:63], v[146:149], v[158:161], v[48:63]
	v_mfma_f32_32x32x16_bf16 v[0:15], v[150:153], v[154:157], v[0:15]
	v_mfma_f32_32x32x16_bf16 v[32:47], v[150:153], v[158:161], v[32:47]
	global_load_dwordx4 v[146:149], v[88:89], off offset:384
	global_load_dwordx4 v[150:153], v[92:93], off offset:384
	s_waitcnt vmcnt(9)
	ds_write_b128 v100, v[66:69] offset:13824
	s_waitcnt vmcnt(8)
	ds_write_b128 v100, v[110:113] offset:32256
	s_waitcnt lgkmcnt(3)
	v_mfma_f32_32x32x16_bf16 v[16:31], v[138:141], v[162:165], v[16:31]
	s_waitcnt lgkmcnt(2)
	v_mfma_f32_32x32x16_bf16 v[48:63], v[138:141], v[166:169], v[48:63]
	v_mfma_f32_32x32x16_bf16 v[0:15], v[142:145], v[162:165], v[0:15]
	v_mfma_f32_32x32x16_bf16 v[32:47], v[142:145], v[166:169], v[32:47]
	s_waitcnt lgkmcnt(0)
	s_barrier
	global_load_dwordx4 v[66:69], v[64:65], off offset:512
	global_load_dwordx4 v[110:113], v[106:107], off offset:512
	ds_read_b128 v[138:141], v104
	ds_read_b128 v[142:145], v104 offset:4608
	ds_read_b128 v[154:157], v101 offset:18432
	ds_read_b128 v[158:161], v101 offset:23040
	s_waitcnt vmcnt(9)
	ds_write_b128 v100, v[114:117] offset:36864
	s_waitcnt vmcnt(8)
	ds_write_b128 v100, v[118:121] offset:55296
	ds_read_b128 v[114:117], v104 offset:32
	ds_read_b128 v[118:121], v104 offset:4640
	ds_read_b128 v[162:165], v101 offset:18464
	ds_read_b128 v[166:169], v101 offset:23072
	s_waitcnt lgkmcnt(7)
	v_mfma_f32_32x32x16_bf16 v[16:31], v[138:141], v[154:157], v[16:31]
	s_waitcnt lgkmcnt(6)
	v_mfma_f32_32x32x16_bf16 v[48:63], v[138:141], v[158:161], v[48:63]
	v_mfma_f32_32x32x16_bf16 v[0:15], v[142:145], v[154:157], v[0:15]
	v_mfma_f32_32x32x16_bf16 v[32:47], v[142:145], v[158:161], v[32:47]
	global_load_dwordx4 v[138:141], v[72:73], off offset:512
	global_load_dwordx4 v[142:145], v[76:77], off offset:512
	s_waitcnt vmcnt(9)
	ds_write_b128 v100, v[122:125] offset:41472
	s_waitcnt vmcnt(8)
	ds_write_b128 v100, v[126:129] offset:59904
	ds_read_b128 v[122:125], v104 offset:64
	ds_read_b128 v[126:129], v104 offset:4672
	ds_read_b128 v[154:157], v101 offset:18496
	ds_read_b128 v[158:161], v101 offset:23104
	s_waitcnt lgkmcnt(7)
	v_mfma_f32_32x32x16_bf16 v[16:31], v[114:117], v[162:165], v[16:31]
	s_waitcnt lgkmcnt(6)
	v_mfma_f32_32x32x16_bf16 v[48:63], v[114:117], v[166:169], v[48:63]
	v_mfma_f32_32x32x16_bf16 v[0:15], v[118:121], v[162:165], v[0:15]
	v_mfma_f32_32x32x16_bf16 v[32:47], v[118:121], v[166:169], v[32:47]
	global_load_dwordx4 v[114:117], v[80:81], off offset:512
	global_load_dwordx4 v[118:121], v[84:85], off offset:512
	s_waitcnt vmcnt(9)
	ds_write_b128 v100, v[130:133] offset:46080
	s_waitcnt vmcnt(8)
	ds_write_b128 v100, v[134:137] offset:64512
	ds_read_b128 v[130:133], v104 offset:96
	ds_read_b128 v[134:137], v104 offset:4704
	ds_read_b128 v[162:165], v101 offset:18528
	ds_read_b128 v[166:169], v101 offset:23136
	s_waitcnt lgkmcnt(7)
	v_mfma_f32_32x32x16_bf16 v[16:31], v[122:125], v[154:157], v[16:31]
	s_waitcnt lgkmcnt(6)
	v_mfma_f32_32x32x16_bf16 v[48:63], v[122:125], v[158:161], v[48:63]
	v_mfma_f32_32x32x16_bf16 v[0:15], v[126:129], v[154:157], v[0:15]
	v_mfma_f32_32x32x16_bf16 v[32:47], v[126:129], v[158:161], v[32:47]
	global_load_dwordx4 v[122:125], v[88:89], off offset:512
	global_load_dwordx4 v[126:129], v[92:93], off offset:512
	s_waitcnt vmcnt(9)
	ds_write_b128 v100, v[146:149] offset:50688
	s_waitcnt vmcnt(8)
	ds_write_b128 v105, v[150:153] offset:13824
	s_waitcnt lgkmcnt(3)
	v_mfma_f32_32x32x16_bf16 v[16:31], v[130:133], v[162:165], v[16:31]
	s_waitcnt lgkmcnt(2)
	v_mfma_f32_32x32x16_bf16 v[48:63], v[130:133], v[166:169], v[48:63]
	v_mfma_f32_32x32x16_bf16 v[0:15], v[134:137], v[162:165], v[0:15]
	v_mfma_f32_32x32x16_bf16 v[32:47], v[134:137], v[166:169], v[32:47]
	s_waitcnt lgkmcnt(0)
	s_barrier
; __device__ __forceinline__ void gemm_run(int tid, f32x16 (&acc)[2][2], GRegs& g, const GOp& o, int K, unsigned char* smem) {
;     ...
;   for (int k = 0; k < nk; k++) {
;     bf16r* cur = sbuf + (k & 1) * (256 * LDK);
;     bf16r* nxt = sbuf + ((k & 1) ^ 1) * (256 * LDK);
;     const bf16r* As = cur + (wm * 64 + fr) * LDK + fh * 8;
;     const bf16r* Bs = cur + 128 * LDK + (wn * 64 + fr) * LDK + fh * 8;
;     const bool wr = (k + 1 < nk), ld = (k + 2 < nk);
;     bf16x8 fa[2][2], fb[2][2];
;     fa[0][0] = *(const bf16x8*)(As);
;     fa[0][1] = *(const bf16x8*)(As + 32 * LDK);
;     fb[0][0] = *(const bf16x8*)(Bs);
;     fb[0][1] = *(const bf16x8*)(Bs + 32 * LDK);
; #pragma unroll
;     for (int i = 0; i < 4; i++) {
;       if (wr) {
;         *(u32x4*)(nxt + (r0 + i * 32) * LDK + sg * 8) = g.a[i];
;         *(u32x4*)(nxt + 128 * LDK + (r0 + i * 32) * LDK + sg * 8) = g.b[i];
;       }
;       if (ld) {
;         g.a[i] = *(const u32x4*)(Ap + (size_t)i * 32 * o.lda + (k + 2) * 64);
;         g.b[i] = *(const u32x4*)(Bp + o.bs.o[i] + (k + 2) * 64);
;       }
;       if (i < 3) {
;         fa[(i + 1) & 1][0] = *(const bf16x8*)(As + (i + 1) * 16);
;         fa[(i + 1) & 1][1] = *(const bf16x8*)(As + 32 * LDK + (i + 1) * 16);
;         fb[(i + 1) & 1][0] = *(const bf16x8*)(Bs + (i + 1) * 16);
;         fb[(i + 1) & 1][1] = *(const bf16x8*)(Bs + 32 * LDK + (i + 1) * 16);
;       }
;       __builtin_amdgcn_sched_barrier(0);
;       __builtin_amdgcn_s_setprio(1);
;       acc[0][0] = __builtin_amdgcn_mfma_f32_32x32x16_bf16(fa[i & 1][0], fb[i & 1][0], acc[0][0], 0, 0, 0);
;       acc[0][1] = __builtin_amdgcn_mfma_f32_32x32x16_bf16(fa[i & 1][0], fb[i & 1][1], acc[0][1], 0, 0, 0);
;       acc[1][0] = __builtin_amdgcn_mfma_f32_32x32x16_bf16(fa[i & 1][1], fb[i & 1][0], acc[1][0], 0, 0, 0);
;       acc[1][1] = __builtin_amdgcn_mfma_f32_32x32x16_bf16(fa[i & 1][1], fb[i & 1][1], acc[1][1], 0, 0, 0);
;       __builtin_amdgcn_s_setprio(0);
;     }
;     __syncthreads();
	global_load_dwordx4 v[130:133], v[64:65], off offset:640
	global_load_dwordx4 v[134:137], v[106:107], off offset:640
	ds_read_b128 v[146:149], v104 offset:36864
	ds_read_b128 v[150:153], v104 offset:41472
	ds_read_b128 v[154:157], v101 offset:55296
	ds_read_b128 v[158:161], v101 offset:59904
	s_waitcnt vmcnt(9)
	ds_write_b128 v100, v[66:69]
	s_waitcnt vmcnt(8)
	ds_write_b128 v100, v[110:113] offset:18432
	ds_read_b128 v[66:69], v104 offset:36896
	ds_read_b128 v[110:113], v104 offset:41504
	ds_read_b128 v[162:165], v101 offset:55328
	ds_read_b128 v[166:169], v101 offset:59936
	s_waitcnt lgkmcnt(7)
	v_mfma_f32_32x32x16_bf16 v[16:31], v[146:149], v[154:157], v[16:31]
	s_waitcnt lgkmcnt(6)
	v_mfma_f32_32x32x16_bf16 v[48:63], v[146:149], v[158:161], v[48:63]
	v_mfma_f32_32x32x16_bf16 v[0:15], v[150:153], v[154:157], v[0:15]
	v_mfma_f32_32x32x16_bf16 v[32:47], v[150:153], v[158:161], v[32:47]
	global_load_dwordx4 v[146:149], v[72:73], off offset:640
	global_load_dwordx4 v[150:153], v[76:77], off offset:640
	s_waitcnt vmcnt(9)
	ds_write_b128 v100, v[138:141] offset:4608
	s_waitcnt vmcnt(8)
	ds_write_b128 v100, v[142:145] offset:23040
	ds_read_b128 v[138:141], v104 offset:36928
	ds_read_b128 v[142:145], v104 offset:41536
	ds_read_b128 v[154:157], v101 offset:55360
	ds_read_b128 v[158:161], v101 offset:59968
	s_waitcnt lgkmcnt(7)
	v_mfma_f32_32x32x16_bf16 v[16:31], v[66:69], v[162:165], v[16:31]
	s_waitcnt lgkmcnt(6)
	v_mfma_f32_32x32x16_bf16 v[48:63], v[66:69], v[166:169], v[48:63]
	v_mfma_f32_32x32x16_bf16 v[0:15], v[110:113], v[162:165], v[0:15]
	v_mfma_f32_32x32x16_bf16 v[32:47], v[110:113], v[166:169], v[32:47]
	global_load_dwordx4 v[66:69], v[80:81], off offset:640
	global_load_dwordx4 v[110:113], v[84:85], off offset:640
	s_waitcnt vmcnt(9)
	ds_write_b128 v100, v[114:117] offset:9216
	s_waitcnt vmcnt(8)
	ds_write_b128 v100, v[118:121] offset:27648
	ds_read_b128 v[114:117], v104 offset:36960
	ds_read_b128 v[118:121], v104 offset:41568
	ds_read_b128 v[162:165], v101 offset:55392
	ds_read_b128 v[166:169], v101 offset:60000
	s_waitcnt lgkmcnt(7)
	v_mfma_f32_32x32x16_bf16 v[16:31], v[138:141], v[154:157], v[16:31]
	s_waitcnt lgkmcnt(6)
	v_mfma_f32_32x32x16_bf16 v[48:63], v[138:141], v[158:161], v[48:63]
	v_mfma_f32_32x32x16_bf16 v[0:15], v[142:145], v[154:157], v[0:15]
	v_mfma_f32_32x32x16_bf16 v[32:47], v[142:145], v[158:161], v[32:47]
	global_load_dwordx4 v[138:141], v[88:89], off offset:640
	global_load_dwordx4 v[142:145], v[92:93], off offset:640
	s_waitcnt vmcnt(9)
	ds_write_b128 v100, v[122:125] offset:13824
	s_waitcnt vmcnt(8)
	ds_write_b128 v100, v[126:129] offset:32256
	s_waitcnt lgkmcnt(3)
	v_mfma_f32_32x32x16_bf16 v[16:31], v[114:117], v[162:165], v[16:31]
	s_waitcnt lgkmcnt(2)
	v_mfma_f32_32x32x16_bf16 v[48:63], v[114:117], v[166:169], v[48:63]
	v_mfma_f32_32x32x16_bf16 v[0:15], v[118:121], v[162:165], v[0:15]
	v_mfma_f32_32x32x16_bf16 v[32:47], v[118:121], v[166:169], v[32:47]
	s_waitcnt lgkmcnt(0)
	s_barrier
	global_load_dwordx4 v[114:117], v[64:65], off offset:768
	global_load_dwordx4 v[118:121], v[106:107], off offset:768
	ds_read_b128 v[122:125], v104
	ds_read_b128 v[126:129], v104 offset:4608
	ds_read_b128 v[154:157], v101 offset:18432
	ds_read_b128 v[158:161], v101 offset:23040
	s_waitcnt vmcnt(9)
	ds_write_b128 v100, v[130:133] offset:36864
	s_waitcnt vmcnt(8)
	ds_write_b128 v100, v[134:137] offset:55296
	ds_read_b128 v[130:133], v104 offset:32
	ds_read_b128 v[134:137], v104 offset:4640
	ds_read_b128 v[162:165], v101 offset:18464
	ds_read_b128 v[166:169], v101 offset:23072
	s_waitcnt lgkmcnt(7)
	v_mfma_f32_32x32x16_bf16 v[16:31], v[122:125], v[154:157], v[16:31]
	s_waitcnt lgkmcnt(6)
	v_mfma_f32_32x32x16_bf16 v[48:63], v[122:125], v[158:161], v[48:63]
	v_mfma_f32_32x32x16_bf16 v[0:15], v[126:129], v[154:157], v[0:15]
	v_mfma_f32_32x32x16_bf16 v[32:47], v[126:129], v[158:161], v[32:47]
	global_load_dwordx4 v[122:125], v[72:73], off offset:768
	global_load_dwordx4 v[126:129], v[76:77], off offset:768
	s_waitcnt vmcnt(9)
	ds_write_b128 v100, v[146:149] offset:41472
	s_waitcnt vmcnt(8)
	ds_write_b128 v100, v[150:153] offset:59904
	ds_read_b128 v[146:149], v104 offset:64
	ds_read_b128 v[150:153], v104 offset:4672
	ds_read_b128 v[154:157], v101 offset:18496
	ds_read_b128 v[158:161], v101 offset:23104
	s_waitcnt lgkmcnt(7)
	v_mfma_f32_32x32x16_bf16 v[16:31], v[130:133], v[162:165], v[16:31]
	s_waitcnt lgkmcnt(6)
	v_mfma_f32_32x32x16_bf16 v[48:63], v[130:133], v[166:169], v[48:63]
	v_mfma_f32_32x32x16_bf16 v[0:15], v[134:137], v[162:165], v[0:15]
	v_mfma_f32_32x32x16_bf16 v[32:47], v[134:137], v[166:169], v[32:47]
	global_load_dwordx4 v[130:133], v[80:81], off offset:768
	global_load_dwordx4 v[134:137], v[84:85], off offset:768
	s_waitcnt vmcnt(9)
	ds_write_b128 v100, v[66:69] offset:46080
	s_waitcnt vmcnt(8)
	ds_write_b128 v100, v[110:113] offset:64512
	ds_read_b128 v[66:69], v104 offset:96
	ds_read_b128 v[110:113], v104 offset:4704
	ds_read_b128 v[162:165], v101 offset:18528
	ds_read_b128 v[166:169], v101 offset:23136
	s_waitcnt lgkmcnt(7)
	v_mfma_f32_32x32x16_bf16 v[16:31], v[146:149], v[154:157], v[16:31]
	s_waitcnt lgkmcnt(6)
	v_mfma_f32_32x32x16_bf16 v[48:63], v[146:149], v[158:161], v[48:63]
	v_mfma_f32_32x32x16_bf16 v[0:15], v[150:153], v[154:157], v[0:15]
	v_mfma_f32_32x32x16_bf16 v[32:47], v[150:153], v[158:161], v[32:47]
	global_load_dwordx4 v[146:149], v[88:89], off offset:768
	global_load_dwordx4 v[150:153], v[92:93], off offset:768
	s_waitcnt vmcnt(9)
	ds_write_b128 v100, v[138:141] offset:50688
	s_waitcnt vmcnt(8)
	ds_write_b128 v105, v[142:145] offset:13824
	s_waitcnt lgkmcnt(3)
	v_mfma_f32_32x32x16_bf16 v[16:31], v[66:69], v[162:165], v[16:31]
	s_waitcnt lgkmcnt(2)
	v_mfma_f32_32x32x16_bf16 v[48:63], v[66:69], v[166:169], v[48:63]
	v_mfma_f32_32x32x16_bf16 v[0:15], v[110:113], v[162:165], v[0:15]
	v_mfma_f32_32x32x16_bf16 v[32:47], v[110:113], v[166:169], v[32:47]
	s_waitcnt lgkmcnt(0)
	s_barrier
; __device__ __forceinline__ void gemm_run(int tid, f32x16 (&acc)[2][2], GRegs& g, const GOp& o, int K, unsigned char* smem) {
;     ...
;   for (int k = 0; k < nk; k++) {
;     bf16r* cur = sbuf + (k & 1) * (256 * LDK);
;     bf16r* nxt = sbuf + ((k & 1) ^ 1) * (256 * LDK);
;     const bf16r* As = cur + (wm * 64 + fr) * LDK + fh * 8;
;     const bf16r* Bs = cur + 128 * LDK + (wn * 64 + fr) * LDK + fh * 8;
;     const bool wr = (k + 1 < nk), ld = (k + 2 < nk);
;     bf16x8 fa[2][2], fb[2][2];
;     fa[0][0] = *(const bf16x8*)(As);
;     fa[0][1] = *(const bf16x8*)(As + 32 * LDK);
;     fb[0][0] = *(const bf16x8*)(Bs);
;     fb[0][1] = *(const bf16x8*)(Bs + 32 * LDK);
; #pragma unroll
;     for (int i = 0; i < 4; i++) {
;       if (wr) {
;         *(u32x4*)(nxt + (r0 + i * 32) * LDK + sg * 8) = g.a[i];
;         *(u32x4*)(nxt + 128 * LDK + (r0 + i * 32) * LDK + sg * 8) = g.b[i];
;       }
;       if (ld) {
;         g.a[i] = *(const u32x4*)(Ap + (size_t)i * 32 * o.lda + (k + 2) * 64);
;         g.b[i] = *(const u32x4*)(Bp + o.bs.o[i] + (k + 2) * 64);
;       }
;       if (i < 3) {
;         fa[(i + 1) & 1][0] = *(const bf16x8*)(As + (i + 1) * 16);
;         fa[(i + 1) & 1][1] = *(const bf16x8*)(As + 32 * LDK + (i + 1) * 16);
;         fb[(i + 1) & 1][0] = *(const bf16x8*)(Bs + (i + 1) * 16);
;         fb[(i + 1) & 1][1] = *(const bf16x8*)(Bs + 32 * LDK + (i + 1) * 16);
;       }
;       __builtin_amdgcn_sched_barrier(0);
;       __builtin_amdgcn_s_setprio(1);
;       acc[0][0] = __builtin_amdgcn_mfma_f32_32x32x16_bf16(fa[i & 1][0], fb[i & 1][0], acc[0][0], 0, 0, 0);
;       acc[0][1] = __builtin_amdgcn_mfma_f32_32x32x16_bf16(fa[i & 1][0], fb[i & 1][1], acc[0][1], 0, 0, 0);
;       acc[1][0] = __builtin_amdgcn_mfma_f32_32x32x16_bf16(fa[i & 1][1], fb[i & 1][0], acc[1][0], 0, 0, 0);
;       acc[1][1] = __builtin_amdgcn_mfma_f32_32x32x16_bf16(fa[i & 1][1], fb[i & 1][1], acc[1][1], 0, 0, 0);
;       __builtin_amdgcn_s_setprio(0);
;     }
;     __syncthreads();
	global_load_dwordx4 v[66:69], v[64:65], off offset:896
	global_load_dwordx4 v[110:113], v[106:107], off offset:896
	ds_read_b128 v[138:141], v104 offset:36864
	ds_read_b128 v[142:145], v104 offset:41472
	ds_read_b128 v[154:157], v101 offset:55296
	ds_read_b128 v[158:161], v101 offset:59904
	s_waitcnt vmcnt(9)
	ds_write_b128 v100, v[114:117]
	s_waitcnt vmcnt(8)
	ds_write_b128 v100, v[118:121] offset:18432
	ds_read_b128 v[114:117], v104 offset:36896
	ds_read_b128 v[118:121], v104 offset:41504
	ds_read_b128 v[162:165], v101 offset:55328
	ds_read_b128 v[166:169], v101 offset:59936
	s_waitcnt lgkmcnt(7)
	v_mfma_f32_32x32x16_bf16 v[16:31], v[138:141], v[154:157], v[16:31]
	s_waitcnt lgkmcnt(6)
	v_mfma_f32_32x32x16_bf16 v[48:63], v[138:141], v[158:161], v[48:63]
	v_mfma_f32_32x32x16_bf16 v[0:15], v[142:145], v[154:157], v[0:15]
	v_mfma_f32_32x32x16_bf16 v[32:47], v[142:145], v[158:161], v[32:47]
	global_load_dwordx4 v[138:141], v[72:73], off offset:896
	global_load_dwordx4 v[142:145], v[76:77], off offset:896
	s_waitcnt vmcnt(9)
	ds_write_b128 v100, v[122:125] offset:4608
	s_waitcnt vmcnt(8)
	ds_write_b128 v100, v[126:129] offset:23040
	ds_read_b128 v[122:125], v104 offset:36928
	ds_read_b128 v[126:129], v104 offset:41536
	ds_read_b128 v[154:157], v101 offset:55360
	ds_read_b128 v[158:161], v101 offset:59968
	s_waitcnt lgkmcnt(7)
	v_mfma_f32_32x32x16_bf16 v[16:31], v[114:117], v[162:165], v[16:31]
	s_waitcnt lgkmcnt(6)
	v_mfma_f32_32x32x16_bf16 v[48:63], v[114:117], v[166:169], v[48:63]
	v_mfma_f32_32x32x16_bf16 v[0:15], v[118:121], v[162:165], v[0:15]
	v_mfma_f32_32x32x16_bf16 v[32:47], v[118:121], v[166:169], v[32:47]
	global_load_dwordx4 v[114:117], v[80:81], off offset:896
	global_load_dwordx4 v[118:121], v[84:85], off offset:896
	s_waitcnt vmcnt(9)
	ds_write_b128 v100, v[130:133] offset:9216
	s_waitcnt vmcnt(8)
	ds_write_b128 v100, v[134:137] offset:27648
	ds_read_b128 v[130:133], v104 offset:36960
	ds_read_b128 v[134:137], v104 offset:41568
	ds_read_b128 v[162:165], v101 offset:55392
	ds_read_b128 v[166:169], v101 offset:60000
	s_waitcnt lgkmcnt(7)
	v_mfma_f32_32x32x16_bf16 v[16:31], v[122:125], v[154:157], v[16:31]
	s_waitcnt lgkmcnt(6)
	v_mfma_f32_32x32x16_bf16 v[48:63], v[122:125], v[158:161], v[48:63]
	v_mfma_f32_32x32x16_bf16 v[0:15], v[126:129], v[154:157], v[0:15]
	v_mfma_f32_32x32x16_bf16 v[32:47], v[126:129], v[158:161], v[32:47]
	global_load_dwordx4 v[122:125], v[88:89], off offset:896
	global_load_dwordx4 v[126:129], v[92:93], off offset:896
	s_waitcnt vmcnt(9)
	ds_write_b128 v100, v[146:149] offset:13824
	s_waitcnt vmcnt(8)
	ds_write_b128 v100, v[150:153] offset:32256
	s_waitcnt lgkmcnt(3)
	v_mfma_f32_32x32x16_bf16 v[16:31], v[130:133], v[162:165], v[16:31]
	s_waitcnt lgkmcnt(2)
	v_mfma_f32_32x32x16_bf16 v[48:63], v[130:133], v[166:169], v[48:63]
	v_mfma_f32_32x32x16_bf16 v[0:15], v[134:137], v[162:165], v[0:15]
	v_mfma_f32_32x32x16_bf16 v[32:47], v[134:137], v[166:169], v[32:47]
	s_waitcnt lgkmcnt(0)
	s_barrier
	global_load_dwordx4 v[130:133], v[64:65], off offset:1024
	global_load_dwordx4 v[134:137], v[106:107], off offset:1024
	ds_read_b128 v[146:149], v104
	ds_read_b128 v[150:153], v104 offset:4608
	ds_read_b128 v[154:157], v101 offset:18432
	ds_read_b128 v[158:161], v101 offset:23040
	s_waitcnt vmcnt(9)
	ds_write_b128 v100, v[66:69] offset:36864
	s_waitcnt vmcnt(8)
	ds_write_b128 v100, v[110:113] offset:55296
	ds_read_b128 v[66:69], v104 offset:32
	ds_read_b128 v[110:113], v104 offset:4640
	ds_read_b128 v[162:165], v101 offset:18464
	ds_read_b128 v[166:169], v101 offset:23072
	s_waitcnt lgkmcnt(7)
	v_mfma_f32_32x32x16_bf16 v[16:31], v[146:149], v[154:157], v[16:31]
	s_waitcnt lgkmcnt(6)
	v_mfma_f32_32x32x16_bf16 v[48:63], v[146:149], v[158:161], v[48:63]
	v_mfma_f32_32x32x16_bf16 v[0:15], v[150:153], v[154:157], v[0:15]
	v_mfma_f32_32x32x16_bf16 v[32:47], v[150:153], v[158:161], v[32:47]
	global_load_dwordx4 v[146:149], v[72:73], off offset:1024
	global_load_dwordx4 v[150:153], v[76:77], off offset:1024
	s_waitcnt vmcnt(9)
	ds_write_b128 v100, v[138:141] offset:41472
	s_waitcnt vmcnt(8)
	ds_write_b128 v100, v[142:145] offset:59904
	ds_read_b128 v[138:141], v104 offset:64
	ds_read_b128 v[142:145], v104 offset:4672
	ds_read_b128 v[154:157], v101 offset:18496
	ds_read_b128 v[158:161], v101 offset:23104
	s_waitcnt lgkmcnt(7)
	v_mfma_f32_32x32x16_bf16 v[16:31], v[66:69], v[162:165], v[16:31]
	s_waitcnt lgkmcnt(6)
	v_mfma_f32_32x32x16_bf16 v[48:63], v[66:69], v[166:169], v[48:63]
	v_mfma_f32_32x32x16_bf16 v[0:15], v[110:113], v[162:165], v[0:15]
	v_mfma_f32_32x32x16_bf16 v[32:47], v[110:113], v[166:169], v[32:47]
	global_load_dwordx4 v[66:69], v[80:81], off offset:1024
	global_load_dwordx4 v[110:113], v[84:85], off offset:1024
	s_waitcnt vmcnt(9)
	ds_write_b128 v100, v[114:117] offset:46080
	s_waitcnt vmcnt(8)
	ds_write_b128 v100, v[118:121] offset:64512
	ds_read_b128 v[114:117], v104 offset:96
	ds_read_b128 v[118:121], v104 offset:4704
	ds_read_b128 v[162:165], v101 offset:18528
	ds_read_b128 v[166:169], v101 offset:23136
	s_waitcnt lgkmcnt(7)
	v_mfma_f32_32x32x16_bf16 v[16:31], v[138:141], v[154:157], v[16:31]
	s_waitcnt lgkmcnt(6)
	v_mfma_f32_32x32x16_bf16 v[48:63], v[138:141], v[158:161], v[48:63]
	v_mfma_f32_32x32x16_bf16 v[0:15], v[142:145], v[154:157], v[0:15]
	v_mfma_f32_32x32x16_bf16 v[32:47], v[142:145], v[158:161], v[32:47]
	global_load_dwordx4 v[138:141], v[88:89], off offset:1024
	global_load_dwordx4 v[142:145], v[92:93], off offset:1024
	s_waitcnt vmcnt(9)
	ds_write_b128 v100, v[122:125] offset:50688
	s_waitcnt vmcnt(8)
	ds_write_b128 v105, v[126:129] offset:13824
	s_waitcnt lgkmcnt(3)
	v_mfma_f32_32x32x16_bf16 v[16:31], v[114:117], v[162:165], v[16:31]
	s_waitcnt lgkmcnt(2)
	v_mfma_f32_32x32x16_bf16 v[48:63], v[114:117], v[166:169], v[48:63]
	v_mfma_f32_32x32x16_bf16 v[0:15], v[118:121], v[162:165], v[0:15]
	v_mfma_f32_32x32x16_bf16 v[32:47], v[118:121], v[166:169], v[32:47]
	s_waitcnt lgkmcnt(0)
	s_barrier
; __device__ __forceinline__ void gemm_run(int tid, f32x16 (&acc)[2][2], GRegs& g, const GOp& o, int K, unsigned char* smem) {
;     ...
;   for (int k = 0; k < nk; k++) {
;     bf16r* cur = sbuf + (k & 1) * (256 * LDK);
;     bf16r* nxt = sbuf + ((k & 1) ^ 1) * (256 * LDK);
;     const bf16r* As = cur + (wm * 64 + fr) * LDK + fh * 8;
;     const bf16r* Bs = cur + 128 * LDK + (wn * 64 + fr) * LDK + fh * 8;
;     const bool wr = (k + 1 < nk), ld = (k + 2 < nk);
;     bf16x8 fa[2][2], fb[2][2];
;     fa[0][0] = *(const bf16x8*)(As);
;     fa[0][1] = *(const bf16x8*)(As + 32 * LDK);
;     fb[0][0] = *(const bf16x8*)(Bs);
;     fb[0][1] = *(const bf16x8*)(Bs + 32 * LDK);
; #pragma unroll
;     for (int i = 0; i < 4; i++) {
;       if (wr) {
;         *(u32x4*)(nxt + (r0 + i * 32) * LDK + sg * 8) = g.a[i];
;         *(u32x4*)(nxt + 128 * LDK + (r0 + i * 32) * LDK + sg * 8) = g.b[i];
;       }
;       if (ld) {
;         g.a[i] = *(const u32x4*)(Ap + (size_t)i * 32 * o.lda + (k + 2) * 64);
;         g.b[i] = *(const u32x4*)(Bp + o.bs.o[i] + (k + 2) * 64);
;       }
;       if (i < 3) {
;         fa[(i + 1) & 1][0] = *(const bf16x8*)(As + (i + 1) * 16);
;         fa[(i + 1) & 1][1] = *(const bf16x8*)(As + 32 * LDK + (i + 1) * 16);
;         fb[(i + 1) & 1][0] = *(const bf16x8*)(Bs + (i + 1) * 16);
;         fb[(i + 1) & 1][1] = *(const bf16x8*)(Bs + 32 * LDK + (i + 1) * 16);
;       }
;       __builtin_amdgcn_sched_barrier(0);
;       __builtin_amdgcn_s_setprio(1);
;       acc[0][0] = __builtin_amdgcn_mfma_f32_32x32x16_bf16(fa[i & 1][0], fb[i & 1][0], acc[0][0], 0, 0, 0);
;       acc[0][1] = __builtin_amdgcn_mfma_f32_32x32x16_bf16(fa[i & 1][0], fb[i & 1][1], acc[0][1], 0, 0, 0);
;       acc[1][0] = __builtin_amdgcn_mfma_f32_32x32x16_bf16(fa[i & 1][1], fb[i & 1][0], acc[1][0], 0, 0, 0);
;       acc[1][1] = __builtin_amdgcn_mfma_f32_32x32x16_bf16(fa[i & 1][1], fb[i & 1][1], acc[1][1], 0, 0, 0);
;       __builtin_amdgcn_s_setprio(0);
;     }
;     __syncthreads();
	global_load_dwordx4 v[114:117], v[64:65], off offset:1152
	global_load_dwordx4 v[118:121], v[106:107], off offset:1152
	ds_read_b128 v[122:125], v104 offset:36864
	ds_read_b128 v[126:129], v104 offset:41472
	ds_read_b128 v[154:157], v101 offset:55296
	ds_read_b128 v[158:161], v101 offset:59904
	s_waitcnt vmcnt(9)
	ds_write_b128 v100, v[130:133]
	s_waitcnt vmcnt(8)
	ds_write_b128 v100, v[134:137] offset:18432
	ds_read_b128 v[130:133], v104 offset:36896
	ds_read_b128 v[134:137], v104 offset:41504
	ds_read_b128 v[162:165], v101 offset:55328
	ds_read_b128 v[166:169], v101 offset:59936
	s_waitcnt lgkmcnt(7)
	v_mfma_f32_32x32x16_bf16 v[16:31], v[122:125], v[154:157], v[16:31]
	s_waitcnt lgkmcnt(6)
	v_mfma_f32_32x32x16_bf16 v[48:63], v[122:125], v[158:161], v[48:63]
	v_mfma_f32_32x32x16_bf16 v[0:15], v[126:129], v[154:157], v[0:15]
	v_mfma_f32_32x32x16_bf16 v[32:47], v[126:129], v[158:161], v[32:47]
	global_load_dwordx4 v[122:125], v[72:73], off offset:1152
	global_load_dwordx4 v[126:129], v[76:77], off offset:1152
	s_waitcnt vmcnt(9)
	ds_write_b128 v100, v[146:149] offset:4608
	s_waitcnt vmcnt(8)
	ds_write_b128 v100, v[150:153] offset:23040
	ds_read_b128 v[146:149], v104 offset:36928
	ds_read_b128 v[150:153], v104 offset:41536
	ds_read_b128 v[154:157], v101 offset:55360
	ds_read_b128 v[158:161], v101 offset:59968
	s_waitcnt lgkmcnt(7)
	v_mfma_f32_32x32x16_bf16 v[16:31], v[130:133], v[162:165], v[16:31]
	s_waitcnt lgkmcnt(6)
	v_mfma_f32_32x32x16_bf16 v[48:63], v[130:133], v[166:169], v[48:63]
	v_mfma_f32_32x32x16_bf16 v[0:15], v[134:137], v[162:165], v[0:15]
	v_mfma_f32_32x32x16_bf16 v[32:47], v[134:137], v[166:169], v[32:47]
	global_load_dwordx4 v[130:133], v[80:81], off offset:1152
	global_load_dwordx4 v[134:137], v[84:85], off offset:1152
	s_waitcnt vmcnt(9)
	ds_write_b128 v100, v[66:69] offset:9216
	s_waitcnt vmcnt(8)
	ds_write_b128 v100, v[110:113] offset:27648
	ds_read_b128 v[66:69], v104 offset:36960
	ds_read_b128 v[110:113], v104 offset:41568
	ds_read_b128 v[162:165], v101 offset:55392
	ds_read_b128 v[166:169], v101 offset:60000
	s_waitcnt lgkmcnt(7)
	v_mfma_f32_32x32x16_bf16 v[16:31], v[146:149], v[154:157], v[16:31]
	s_waitcnt lgkmcnt(6)
	v_mfma_f32_32x32x16_bf16 v[48:63], v[146:149], v[158:161], v[48:63]
	v_mfma_f32_32x32x16_bf16 v[0:15], v[150:153], v[154:157], v[0:15]
	v_mfma_f32_32x32x16_bf16 v[32:47], v[150:153], v[158:161], v[32:47]
	global_load_dwordx4 v[146:149], v[88:89], off offset:1152
	global_load_dwordx4 v[150:153], v[92:93], off offset:1152
	s_waitcnt vmcnt(9)
	ds_write_b128 v100, v[138:141] offset:13824
	s_waitcnt vmcnt(8)
	ds_write_b128 v100, v[142:145] offset:32256
	s_waitcnt lgkmcnt(3)
	v_mfma_f32_32x32x16_bf16 v[16:31], v[66:69], v[162:165], v[16:31]
	s_waitcnt lgkmcnt(2)
	v_mfma_f32_32x32x16_bf16 v[48:63], v[66:69], v[166:169], v[48:63]
	v_mfma_f32_32x32x16_bf16 v[0:15], v[110:113], v[162:165], v[0:15]
	v_mfma_f32_32x32x16_bf16 v[32:47], v[110:113], v[166:169], v[32:47]
	s_waitcnt lgkmcnt(0)
	s_barrier
	global_load_dwordx4 v[66:69], v[64:65], off offset:1280
	global_load_dwordx4 v[110:113], v[106:107], off offset:1280
	ds_read_b128 v[138:141], v104
	ds_read_b128 v[142:145], v104 offset:4608
	ds_read_b128 v[154:157], v101 offset:18432
	ds_read_b128 v[158:161], v101 offset:23040
	s_waitcnt vmcnt(9)
	ds_write_b128 v100, v[114:117] offset:36864
	s_waitcnt vmcnt(8)
	ds_write_b128 v100, v[118:121] offset:55296
	ds_read_b128 v[114:117], v104 offset:32
	ds_read_b128 v[118:121], v104 offset:4640
	ds_read_b128 v[162:165], v101 offset:18464
	ds_read_b128 v[166:169], v101 offset:23072
	s_waitcnt lgkmcnt(7)
	v_mfma_f32_32x32x16_bf16 v[16:31], v[138:141], v[154:157], v[16:31]
	s_waitcnt lgkmcnt(6)
	v_mfma_f32_32x32x16_bf16 v[48:63], v[138:141], v[158:161], v[48:63]
	v_mfma_f32_32x32x16_bf16 v[0:15], v[142:145], v[154:157], v[0:15]
	v_mfma_f32_32x32x16_bf16 v[32:47], v[142:145], v[158:161], v[32:47]
	global_load_dwordx4 v[138:141], v[72:73], off offset:1280
	global_load_dwordx4 v[142:145], v[76:77], off offset:1280
	s_waitcnt vmcnt(9)
	ds_write_b128 v100, v[122:125] offset:41472
	s_waitcnt vmcnt(8)
	ds_write_b128 v100, v[126:129] offset:59904
	ds_read_b128 v[122:125], v104 offset:64
	ds_read_b128 v[126:129], v104 offset:4672
	ds_read_b128 v[154:157], v101 offset:18496
	ds_read_b128 v[158:161], v101 offset:23104
	s_waitcnt lgkmcnt(7)
	v_mfma_f32_32x32x16_bf16 v[16:31], v[114:117], v[162:165], v[16:31]
	s_waitcnt lgkmcnt(6)
	v_mfma_f32_32x32x16_bf16 v[48:63], v[114:117], v[166:169], v[48:63]
	v_mfma_f32_32x32x16_bf16 v[0:15], v[118:121], v[162:165], v[0:15]
	v_mfma_f32_32x32x16_bf16 v[32:47], v[118:121], v[166:169], v[32:47]
	global_load_dwordx4 v[114:117], v[80:81], off offset:1280
	global_load_dwordx4 v[118:121], v[84:85], off offset:1280
	s_waitcnt vmcnt(9)
	ds_write_b128 v100, v[130:133] offset:46080
	s_waitcnt vmcnt(8)
	ds_write_b128 v100, v[134:137] offset:64512
	ds_read_b128 v[130:133], v104 offset:96
	ds_read_b128 v[134:137], v104 offset:4704
	ds_read_b128 v[162:165], v101 offset:18528
	ds_read_b128 v[166:169], v101 offset:23136
	s_waitcnt lgkmcnt(7)
	v_mfma_f32_32x32x16_bf16 v[16:31], v[122:125], v[154:157], v[16:31]
	s_waitcnt lgkmcnt(6)
	v_mfma_f32_32x32x16_bf16 v[48:63], v[122:125], v[158:161], v[48:63]
	v_mfma_f32_32x32x16_bf16 v[0:15], v[126:129], v[154:157], v[0:15]
	v_mfma_f32_32x32x16_bf16 v[32:47], v[126:129], v[158:161], v[32:47]
	global_load_dwordx4 v[122:125], v[88:89], off offset:1280
	global_load_dwordx4 v[126:129], v[92:93], off offset:1280
	s_waitcnt vmcnt(9)
	ds_write_b128 v100, v[146:149] offset:50688
	s_waitcnt vmcnt(8)
	ds_write_b128 v105, v[150:153] offset:13824
	s_waitcnt lgkmcnt(3)
	v_mfma_f32_32x32x16_bf16 v[16:31], v[130:133], v[162:165], v[16:31]
	s_waitcnt lgkmcnt(2)
	v_mfma_f32_32x32x16_bf16 v[48:63], v[130:133], v[166:169], v[48:63]
	v_mfma_f32_32x32x16_bf16 v[0:15], v[134:137], v[162:165], v[0:15]
	v_mfma_f32_32x32x16_bf16 v[32:47], v[134:137], v[166:169], v[32:47]
	s_waitcnt lgkmcnt(0)
	s_barrier
; __device__ __forceinline__ void gemm_run(int tid, f32x16 (&acc)[2][2], GRegs& g, const GOp& o, int K, unsigned char* smem) {
;     ...
;   for (int k = 0; k < nk; k++) {
;     bf16r* cur = sbuf + (k & 1) * (256 * LDK);
;     bf16r* nxt = sbuf + ((k & 1) ^ 1) * (256 * LDK);
;     const bf16r* As = cur + (wm * 64 + fr) * LDK + fh * 8;
;     const bf16r* Bs = cur + 128 * LDK + (wn * 64 + fr) * LDK + fh * 8;
;     const bool wr = (k + 1 < nk), ld = (k + 2 < nk);
;     bf16x8 fa[2][2], fb[2][2];
;     fa[0][0] = *(const bf16x8*)(As);
;     fa[0][1] = *(const bf16x8*)(As + 32 * LDK);
;     fb[0][0] = *(const bf16x8*)(Bs);
;     fb[0][1] = *(const bf16x8*)(Bs + 32 * LDK);
; #pragma unroll
;     for (int i = 0; i < 4; i++) {
;       if (wr) {
;         *(u32x4*)(nxt + (r0 + i * 32) * LDK + sg * 8) = g.a[i];
;         *(u32x4*)(nxt + 128 * LDK + (r0 + i * 32) * LDK + sg * 8) = g.b[i];
;       }
;       if (ld) {
;         g.a[i] = *(const u32x4*)(Ap + (size_t)i * 32 * o.lda + (k + 2) * 64);
;         g.b[i] = *(const u32x4*)(Bp + o.bs.o[i] + (k + 2) * 64);
;       }
;       if (i < 3) {
;         fa[(i + 1) & 1][0] = *(const bf16x8*)(As + (i + 1) * 16);
;         fa[(i + 1) & 1][1] = *(const bf16x8*)(As + 32 * LDK + (i + 1) * 16);
;         fb[(i + 1) & 1][0] = *(const bf16x8*)(Bs + (i + 1) * 16);
;         fb[(i + 1) & 1][1] = *(const bf16x8*)(Bs + 32 * LDK + (i + 1) * 16);
;       }
;       __builtin_amdgcn_sched_barrier(0);
;       __builtin_amdgcn_s_setprio(1);
;       acc[0][0] = __builtin_amdgcn_mfma_f32_32x32x16_bf16(fa[i & 1][0], fb[i & 1][0], acc[0][0], 0, 0, 0);
;       acc[0][1] = __builtin_amdgcn_mfma_f32_32x32x16_bf16(fa[i & 1][0], fb[i & 1][1], acc[0][1], 0, 0, 0);
;       acc[1][0] = __builtin_amdgcn_mfma_f32_32x32x16_bf16(fa[i & 1][1], fb[i & 1][0], acc[1][0], 0, 0, 0);
;       acc[1][1] = __builtin_amdgcn_mfma_f32_32x32x16_bf16(fa[i & 1][1], fb[i & 1][1], acc[1][1], 0, 0, 0);
;       __builtin_amdgcn_s_setprio(0);
;     }
;     __syncthreads();
	global_load_dwordx4 v[130:133], v[64:65], off offset:1408
	global_load_dwordx4 v[134:137], v[106:107], off offset:1408
	ds_read_b128 v[146:149], v104 offset:36864
	ds_read_b128 v[150:153], v104 offset:41472
	ds_read_b128 v[154:157], v101 offset:55296
	ds_read_b128 v[158:161], v101 offset:59904
	s_waitcnt vmcnt(9)
	ds_write_b128 v100, v[66:69]
	s_waitcnt vmcnt(8)
	ds_write_b128 v100, v[110:113] offset:18432
	ds_read_b128 v[66:69], v104 offset:36896
	ds_read_b128 v[110:113], v104 offset:41504
	ds_read_b128 v[162:165], v101 offset:55328
	ds_read_b128 v[166:169], v101 offset:59936
	s_waitcnt lgkmcnt(7)
	v_mfma_f32_32x32x16_bf16 v[16:31], v[146:149], v[154:157], v[16:31]
	s_waitcnt lgkmcnt(6)
	v_mfma_f32_32x32x16_bf16 v[48:63], v[146:149], v[158:161], v[48:63]
	v_mfma_f32_32x32x16_bf16 v[0:15], v[150:153], v[154:157], v[0:15]
	v_mfma_f32_32x32x16_bf16 v[32:47], v[150:153], v[158:161], v[32:47]
	global_load_dwordx4 v[146:149], v[72:73], off offset:1408
	global_load_dwordx4 v[150:153], v[76:77], off offset:1408
	s_waitcnt vmcnt(9)
	ds_write_b128 v100, v[138:141] offset:4608
	s_waitcnt vmcnt(8)
	ds_write_b128 v100, v[142:145] offset:23040
	ds_read_b128 v[138:141], v104 offset:36928
	ds_read_b128 v[142:145], v104 offset:41536
	ds_read_b128 v[154:157], v101 offset:55360
	ds_read_b128 v[158:161], v101 offset:59968
	s_waitcnt lgkmcnt(7)
	v_mfma_f32_32x32x16_bf16 v[16:31], v[66:69], v[162:165], v[16:31]
	s_waitcnt lgkmcnt(6)
	v_mfma_f32_32x32x16_bf16 v[48:63], v[66:69], v[166:169], v[48:63]
	v_mfma_f32_32x32x16_bf16 v[0:15], v[110:113], v[162:165], v[0:15]
	v_mfma_f32_32x32x16_bf16 v[32:47], v[110:113], v[166:169], v[32:47]
	global_load_dwordx4 v[66:69], v[80:81], off offset:1408
	global_load_dwordx4 v[110:113], v[84:85], off offset:1408
	s_waitcnt vmcnt(9)
	ds_write_b128 v100, v[114:117] offset:9216
	s_waitcnt vmcnt(8)
	ds_write_b128 v100, v[118:121] offset:27648
	ds_read_b128 v[114:117], v104 offset:36960
	ds_read_b128 v[118:121], v104 offset:41568
	ds_read_b128 v[162:165], v101 offset:55392
	ds_read_b128 v[166:169], v101 offset:60000
	s_waitcnt lgkmcnt(7)
	v_mfma_f32_32x32x16_bf16 v[16:31], v[138:141], v[154:157], v[16:31]
	s_waitcnt lgkmcnt(6)
	v_mfma_f32_32x32x16_bf16 v[48:63], v[138:141], v[158:161], v[48:63]
	v_mfma_f32_32x32x16_bf16 v[0:15], v[142:145], v[154:157], v[0:15]
	v_mfma_f32_32x32x16_bf16 v[32:47], v[142:145], v[158:161], v[32:47]
	global_load_dwordx4 v[138:141], v[88:89], off offset:1408
	global_load_dwordx4 v[142:145], v[92:93], off offset:1408
	s_waitcnt vmcnt(9)
	ds_write_b128 v100, v[122:125] offset:13824
	s_waitcnt vmcnt(8)
	ds_write_b128 v100, v[126:129] offset:32256
	s_waitcnt lgkmcnt(3)
	v_mfma_f32_32x32x16_bf16 v[16:31], v[114:117], v[162:165], v[16:31]
	s_waitcnt lgkmcnt(2)
	v_mfma_f32_32x32x16_bf16 v[48:63], v[114:117], v[166:169], v[48:63]
	v_mfma_f32_32x32x16_bf16 v[0:15], v[118:121], v[162:165], v[0:15]
	v_mfma_f32_32x32x16_bf16 v[32:47], v[118:121], v[166:169], v[32:47]
	s_waitcnt lgkmcnt(0)
	s_barrier
	global_load_dwordx4 v[114:117], v[64:65], off offset:1536
	global_load_dwordx4 v[118:121], v[106:107], off offset:1536
	ds_read_b128 v[122:125], v104
	ds_read_b128 v[126:129], v104 offset:4608
	ds_read_b128 v[154:157], v101 offset:18432
	ds_read_b128 v[158:161], v101 offset:23040
	s_waitcnt vmcnt(9)
	ds_write_b128 v100, v[130:133] offset:36864
	s_waitcnt vmcnt(8)
	ds_write_b128 v100, v[134:137] offset:55296
	ds_read_b128 v[130:133], v104 offset:32
	ds_read_b128 v[134:137], v104 offset:4640
	ds_read_b128 v[162:165], v101 offset:18464
	ds_read_b128 v[166:169], v101 offset:23072
	s_waitcnt lgkmcnt(7)
	v_mfma_f32_32x32x16_bf16 v[16:31], v[122:125], v[154:157], v[16:31]
	s_waitcnt lgkmcnt(6)
	v_mfma_f32_32x32x16_bf16 v[48:63], v[122:125], v[158:161], v[48:63]
	v_mfma_f32_32x32x16_bf16 v[0:15], v[126:129], v[154:157], v[0:15]
	v_mfma_f32_32x32x16_bf16 v[32:47], v[126:129], v[158:161], v[32:47]
	global_load_dwordx4 v[122:125], v[72:73], off offset:1536
	global_load_dwordx4 v[126:129], v[76:77], off offset:1536
	s_waitcnt vmcnt(9)
	ds_write_b128 v100, v[146:149] offset:41472
	s_waitcnt vmcnt(8)
	ds_write_b128 v100, v[150:153] offset:59904
	ds_read_b128 v[146:149], v104 offset:64
	ds_read_b128 v[150:153], v104 offset:4672
	ds_read_b128 v[154:157], v101 offset:18496
	ds_read_b128 v[158:161], v101 offset:23104
	s_waitcnt lgkmcnt(7)
	v_mfma_f32_32x32x16_bf16 v[16:31], v[130:133], v[162:165], v[16:31]
	s_waitcnt lgkmcnt(6)
	v_mfma_f32_32x32x16_bf16 v[48:63], v[130:133], v[166:169], v[48:63]
	v_mfma_f32_32x32x16_bf16 v[0:15], v[134:137], v[162:165], v[0:15]
	v_mfma_f32_32x32x16_bf16 v[32:47], v[134:137], v[166:169], v[32:47]
	global_load_dwordx4 v[130:133], v[80:81], off offset:1536
	global_load_dwordx4 v[134:137], v[84:85], off offset:1536
	s_waitcnt vmcnt(9)
	ds_write_b128 v100, v[66:69] offset:46080
	s_waitcnt vmcnt(8)
	ds_write_b128 v100, v[110:113] offset:64512
	ds_read_b128 v[66:69], v104 offset:96
	ds_read_b128 v[110:113], v104 offset:4704
	ds_read_b128 v[162:165], v101 offset:18528
	ds_read_b128 v[166:169], v101 offset:23136
	s_waitcnt lgkmcnt(7)
	v_mfma_f32_32x32x16_bf16 v[16:31], v[146:149], v[154:157], v[16:31]
	s_waitcnt lgkmcnt(6)
	v_mfma_f32_32x32x16_bf16 v[48:63], v[146:149], v[158:161], v[48:63]
	v_mfma_f32_32x32x16_bf16 v[0:15], v[150:153], v[154:157], v[0:15]
	v_mfma_f32_32x32x16_bf16 v[32:47], v[150:153], v[158:161], v[32:47]
	global_load_dwordx4 v[146:149], v[88:89], off offset:1536
	global_load_dwordx4 v[150:153], v[92:93], off offset:1536
	s_waitcnt vmcnt(9)
	ds_write_b128 v100, v[138:141] offset:50688
	s_waitcnt vmcnt(8)
	ds_write_b128 v105, v[142:145] offset:13824
	s_waitcnt lgkmcnt(3)
	v_mfma_f32_32x32x16_bf16 v[16:31], v[66:69], v[162:165], v[16:31]
	s_waitcnt lgkmcnt(2)
	v_mfma_f32_32x32x16_bf16 v[48:63], v[66:69], v[166:169], v[48:63]
	v_mfma_f32_32x32x16_bf16 v[0:15], v[110:113], v[162:165], v[0:15]
	v_mfma_f32_32x32x16_bf16 v[32:47], v[110:113], v[166:169], v[32:47]
	s_waitcnt lgkmcnt(0)
	s_barrier
; __device__ __forceinline__ void gemm_run(int tid, f32x16 (&acc)[2][2], GRegs& g, const GOp& o, int K, unsigned char* smem) {
;     ...
;   for (int k = 0; k < nk; k++) {
;     bf16r* cur = sbuf + (k & 1) * (256 * LDK);
;     bf16r* nxt = sbuf + ((k & 1) ^ 1) * (256 * LDK);
;     const bf16r* As = cur + (wm * 64 + fr) * LDK + fh * 8;
;     const bf16r* Bs = cur + 128 * LDK + (wn * 64 + fr) * LDK + fh * 8;
;     const bool wr = (k + 1 < nk), ld = (k + 2 < nk);
;     bf16x8 fa[2][2], fb[2][2];
;     fa[0][0] = *(const bf16x8*)(As);
;     fa[0][1] = *(const bf16x8*)(As + 32 * LDK);
;     fb[0][0] = *(const bf16x8*)(Bs);
;     fb[0][1] = *(const bf16x8*)(Bs + 32 * LDK);
; #pragma unroll
;     for (int i = 0; i < 4; i++) {
;       if (wr) {
;         *(u32x4*)(nxt + (r0 + i * 32) * LDK + sg * 8) = g.a[i];
;         *(u32x4*)(nxt + 128 * LDK + (r0 + i * 32) * LDK + sg * 8) = g.b[i];
;       }
;       if (ld) {
;         g.a[i] = *(const u32x4*)(Ap + (size_t)i * 32 * o.lda + (k + 2) * 64);
;         g.b[i] = *(const u32x4*)(Bp + o.bs.o[i] + (k + 2) * 64);
;       }
;       if (i < 3) {
;         fa[(i + 1) & 1][0] = *(const bf16x8*)(As + (i + 1) * 16);
;         fa[(i + 1) & 1][1] = *(const bf16x8*)(As + 32 * LDK + (i + 1) * 16);
;         fb[(i + 1) & 1][0] = *(const bf16x8*)(Bs + (i + 1) * 16);
;         fb[(i + 1) & 1][1] = *(const bf16x8*)(Bs + 32 * LDK + (i + 1) * 16);
;       }
;       __builtin_amdgcn_sched_barrier(0);
;       __builtin_amdgcn_s_setprio(1);
;       acc[0][0] = __builtin_amdgcn_mfma_f32_32x32x16_bf16(fa[i & 1][0], fb[i & 1][0], acc[0][0], 0, 0, 0);
;       acc[0][1] = __builtin_amdgcn_mfma_f32_32x32x16_bf16(fa[i & 1][0], fb[i & 1][1], acc[0][1], 0, 0, 0);
;       acc[1][0] = __builtin_amdgcn_mfma_f32_32x32x16_bf16(fa[i & 1][1], fb[i & 1][0], acc[1][0], 0, 0, 0);
;       acc[1][1] = __builtin_amdgcn_mfma_f32_32x32x16_bf16(fa[i & 1][1], fb[i & 1][1], acc[1][1], 0, 0, 0);
;       __builtin_amdgcn_s_setprio(0);
;     }
;     __syncthreads();
	global_load_dwordx4 v[66:69], v[64:65], off offset:1664
	global_load_dwordx4 v[110:113], v[106:107], off offset:1664
	ds_read_b128 v[138:141], v104 offset:36864
	ds_read_b128 v[142:145], v104 offset:41472
	ds_read_b128 v[154:157], v101 offset:55296
	ds_read_b128 v[158:161], v101 offset:59904
	s_waitcnt vmcnt(9)
	ds_write_b128 v100, v[114:117]
	s_waitcnt vmcnt(8)
	ds_write_b128 v100, v[118:121] offset:18432
	ds_read_b128 v[114:117], v104 offset:36896
	ds_read_b128 v[118:121], v104 offset:41504
	ds_read_b128 v[162:165], v101 offset:55328
	ds_read_b128 v[166:169], v101 offset:59936
	s_waitcnt lgkmcnt(7)
	v_mfma_f32_32x32x16_bf16 v[16:31], v[138:141], v[154:157], v[16:31]
	s_waitcnt lgkmcnt(6)
	v_mfma_f32_32x32x16_bf16 v[48:63], v[138:141], v[158:161], v[48:63]
	v_mfma_f32_32x32x16_bf16 v[0:15], v[142:145], v[154:157], v[0:15]
	v_mfma_f32_32x32x16_bf16 v[32:47], v[142:145], v[158:161], v[32:47]
	global_load_dwordx4 v[138:141], v[72:73], off offset:1664
	global_load_dwordx4 v[142:145], v[76:77], off offset:1664
	s_waitcnt vmcnt(9)
	ds_write_b128 v100, v[122:125] offset:4608
	s_waitcnt vmcnt(8)
	ds_write_b128 v100, v[126:129] offset:23040
	ds_read_b128 v[122:125], v104 offset:36928
	ds_read_b128 v[126:129], v104 offset:41536
	ds_read_b128 v[154:157], v101 offset:55360
	ds_read_b128 v[158:161], v101 offset:59968
	s_waitcnt lgkmcnt(7)
	v_mfma_f32_32x32x16_bf16 v[16:31], v[114:117], v[162:165], v[16:31]
	s_waitcnt lgkmcnt(6)
	v_mfma_f32_32x32x16_bf16 v[48:63], v[114:117], v[166:169], v[48:63]
	v_mfma_f32_32x32x16_bf16 v[0:15], v[118:121], v[162:165], v[0:15]
	v_mfma_f32_32x32x16_bf16 v[32:47], v[118:121], v[166:169], v[32:47]
	global_load_dwordx4 v[114:117], v[80:81], off offset:1664
	global_load_dwordx4 v[118:121], v[84:85], off offset:1664
	s_waitcnt vmcnt(9)
	ds_write_b128 v100, v[130:133] offset:9216
	s_waitcnt vmcnt(8)
	ds_write_b128 v100, v[134:137] offset:27648
	ds_read_b128 v[130:133], v104 offset:36960
	ds_read_b128 v[134:137], v104 offset:41568
	ds_read_b128 v[162:165], v101 offset:55392
	ds_read_b128 v[166:169], v101 offset:60000
	s_waitcnt lgkmcnt(7)
	v_mfma_f32_32x32x16_bf16 v[16:31], v[122:125], v[154:157], v[16:31]
	s_waitcnt lgkmcnt(6)
	v_mfma_f32_32x32x16_bf16 v[48:63], v[122:125], v[158:161], v[48:63]
	v_mfma_f32_32x32x16_bf16 v[0:15], v[126:129], v[154:157], v[0:15]
	v_mfma_f32_32x32x16_bf16 v[32:47], v[126:129], v[158:161], v[32:47]
	global_load_dwordx4 v[122:125], v[88:89], off offset:1664
	global_load_dwordx4 v[126:129], v[92:93], off offset:1664
	s_waitcnt vmcnt(9)
	ds_write_b128 v100, v[146:149] offset:13824
	s_waitcnt vmcnt(8)
	ds_write_b128 v100, v[150:153] offset:32256
	s_waitcnt lgkmcnt(3)
	v_mfma_f32_32x32x16_bf16 v[16:31], v[130:133], v[162:165], v[16:31]
	s_waitcnt lgkmcnt(2)
	v_mfma_f32_32x32x16_bf16 v[48:63], v[130:133], v[166:169], v[48:63]
	v_mfma_f32_32x32x16_bf16 v[0:15], v[134:137], v[162:165], v[0:15]
	v_mfma_f32_32x32x16_bf16 v[32:47], v[134:137], v[166:169], v[32:47]
	s_waitcnt lgkmcnt(0)
	s_barrier
	global_load_dwordx4 v[130:133], v[64:65], off offset:1792
	global_load_dwordx4 v[134:137], v[106:107], off offset:1792
	ds_read_b128 v[146:149], v104
	ds_read_b128 v[150:153], v104 offset:4608
	ds_read_b128 v[154:157], v101 offset:18432
	ds_read_b128 v[158:161], v101 offset:23040
	s_waitcnt vmcnt(9)
	ds_write_b128 v100, v[66:69] offset:36864
	s_waitcnt vmcnt(8)
	ds_write_b128 v100, v[110:113] offset:55296
	ds_read_b128 v[66:69], v104 offset:32
	ds_read_b128 v[110:113], v104 offset:4640
	ds_read_b128 v[162:165], v101 offset:18464
	ds_read_b128 v[166:169], v101 offset:23072
	s_waitcnt lgkmcnt(7)
	v_mfma_f32_32x32x16_bf16 v[16:31], v[146:149], v[154:157], v[16:31]
	s_waitcnt lgkmcnt(6)
	v_mfma_f32_32x32x16_bf16 v[48:63], v[146:149], v[158:161], v[48:63]
	v_mfma_f32_32x32x16_bf16 v[0:15], v[150:153], v[154:157], v[0:15]
	v_mfma_f32_32x32x16_bf16 v[32:47], v[150:153], v[158:161], v[32:47]
	global_load_dwordx4 v[146:149], v[72:73], off offset:1792
	global_load_dwordx4 v[150:153], v[76:77], off offset:1792
	s_waitcnt vmcnt(9)
	ds_write_b128 v100, v[138:141] offset:41472
	s_waitcnt vmcnt(8)
	ds_write_b128 v100, v[142:145] offset:59904
	ds_read_b128 v[138:141], v104 offset:64
	ds_read_b128 v[142:145], v104 offset:4672
	ds_read_b128 v[154:157], v101 offset:18496
	ds_read_b128 v[158:161], v101 offset:23104
	s_waitcnt lgkmcnt(7)
	v_mfma_f32_32x32x16_bf16 v[16:31], v[66:69], v[162:165], v[16:31]
	s_waitcnt lgkmcnt(6)
	v_mfma_f32_32x32x16_bf16 v[48:63], v[66:69], v[166:169], v[48:63]
	v_mfma_f32_32x32x16_bf16 v[0:15], v[110:113], v[162:165], v[0:15]
	v_mfma_f32_32x32x16_bf16 v[32:47], v[110:113], v[166:169], v[32:47]
	global_load_dwordx4 v[110:113], v[80:81], off offset:1792
	global_load_dwordx4 v[162:165], v[84:85], off offset:1792
	s_waitcnt vmcnt(9)
	ds_write_b128 v100, v[114:117] offset:46080
	s_waitcnt vmcnt(8)
	ds_write_b128 v100, v[118:121] offset:64512
	ds_read_b128 v[66:69], v104 offset:96
	ds_read_b128 v[114:117], v104 offset:4704
	ds_read_b128 v[118:121], v101 offset:18528
	ds_read_b128 v[166:169], v101 offset:23136
	s_waitcnt lgkmcnt(7)
	v_mfma_f32_32x32x16_bf16 v[16:31], v[138:141], v[154:157], v[16:31]
	s_waitcnt lgkmcnt(6)
	v_mfma_f32_32x32x16_bf16 v[48:63], v[138:141], v[158:161], v[48:63]
	v_mfma_f32_32x32x16_bf16 v[0:15], v[142:145], v[154:157], v[0:15]
	v_mfma_f32_32x32x16_bf16 v[32:47], v[142:145], v[158:161], v[32:47]
	global_load_dwordx4 v[138:141], v[88:89], off offset:1792
	global_load_dwordx4 v[142:145], v[92:93], off offset:1792
	s_waitcnt vmcnt(9)
	ds_write_b128 v100, v[122:125] offset:50688
	s_waitcnt vmcnt(8)
	ds_write_b128 v105, v[126:129] offset:13824
	s_waitcnt lgkmcnt(3)
	v_mfma_f32_32x32x16_bf16 v[16:31], v[66:69], v[118:121], v[16:31]
	s_waitcnt lgkmcnt(2)
	v_mfma_f32_32x32x16_bf16 v[48:63], v[66:69], v[166:169], v[48:63]
	v_mfma_f32_32x32x16_bf16 v[0:15], v[114:117], v[118:121], v[0:15]
	v_mfma_f32_32x32x16_bf16 v[32:47], v[114:117], v[166:169], v[32:47]
	s_waitcnt lgkmcnt(0)
	s_barrier
; __device__ __forceinline__ void gemm_run(int tid, f32x16 (&acc)[2][2], GRegs& g, const GOp& o, int K, unsigned char* smem) {
;     ...
;   for (int k = 0; k < nk; k++) {
;     bf16r* cur = sbuf + (k & 1) * (256 * LDK);
;     bf16r* nxt = sbuf + ((k & 1) ^ 1) * (256 * LDK);
;     const bf16r* As = cur + (wm * 64 + fr) * LDK + fh * 8;
;     const bf16r* Bs = cur + 128 * LDK + (wn * 64 + fr) * LDK + fh * 8;
;     const bool wr = (k + 1 < nk), ld = (k + 2 < nk);
;     bf16x8 fa[2][2], fb[2][2];
;     fa[0][0] = *(const bf16x8*)(As);
;     fa[0][1] = *(const bf16x8*)(As + 32 * LDK);
;     fb[0][0] = *(const bf16x8*)(Bs);
;     fb[0][1] = *(const bf16x8*)(Bs + 32 * LDK);
; #pragma unroll
;     for (int i = 0; i < 4; i++) {
;       if (wr) {
;         *(u32x4*)(nxt + (r0 + i * 32) * LDK + sg * 8) = g.a[i];
;         *(u32x4*)(nxt + 128 * LDK + (r0 + i * 32) * LDK + sg * 8) = g.b[i];
;       }
;       if (ld) {
;         g.a[i] = *(const u32x4*)(Ap + (size_t)i * 32 * o.lda + (k + 2) * 64);
;         g.b[i] = *(const u32x4*)(Bp + o.bs.o[i] + (k + 2) * 64);
;       }
;       if (i < 3) {
;         fa[(i + 1) & 1][0] = *(const bf16x8*)(As + (i + 1) * 16);
;         fa[(i + 1) & 1][1] = *(const bf16x8*)(As + 32 * LDK + (i + 1) * 16);
;         fb[(i + 1) & 1][0] = *(const bf16x8*)(Bs + (i + 1) * 16);
;         fb[(i + 1) & 1][1] = *(const bf16x8*)(Bs + 32 * LDK + (i + 1) * 16);
;       }
;       __builtin_amdgcn_sched_barrier(0);
;       __builtin_amdgcn_s_setprio(1);
;       acc[0][0] = __builtin_amdgcn_mfma_f32_32x32x16_bf16(fa[i & 1][0], fb[i & 1][0], acc[0][0], 0, 0, 0);
;       acc[0][1] = __builtin_amdgcn_mfma_f32_32x32x16_bf16(fa[i & 1][0], fb[i & 1][1], acc[0][1], 0, 0, 0);
;       acc[1][0] = __builtin_amdgcn_mfma_f32_32x32x16_bf16(fa[i & 1][1], fb[i & 1][0], acc[1][0], 0, 0, 0);
;       acc[1][1] = __builtin_amdgcn_mfma_f32_32x32x16_bf16(fa[i & 1][1], fb[i & 1][1], acc[1][1], 0, 0, 0);
;       __builtin_amdgcn_s_setprio(0);
;     }
;     __syncthreads();
	global_load_dwordx4 v[64:67], v[64:65], off offset:1920
	s_nop 0
	global_load_dwordx4 v[68:71], v[106:107], off offset:1920
	ds_read_b128 v[114:117], v104 offset:36864
	ds_read_b128 v[118:121], v104 offset:41472
	ds_read_b128 v[122:125], v101 offset:55296
	ds_read_b128 v[126:129], v101 offset:59904
	s_waitcnt vmcnt(9)
	ds_write_b128 v100, v[130:133]
	s_waitcnt vmcnt(8)
	ds_write_b128 v100, v[134:137] offset:18432
	ds_read_b128 v[130:133], v104 offset:36896
	ds_read_b128 v[134:137], v104 offset:41504
	ds_read_b128 v[154:157], v101 offset:55328
	ds_read_b128 v[158:161], v101 offset:59936
	s_waitcnt lgkmcnt(7)
	v_mfma_f32_32x32x16_bf16 v[16:31], v[114:117], v[122:125], v[16:31]
	s_waitcnt lgkmcnt(6)
	v_mfma_f32_32x32x16_bf16 v[48:63], v[114:117], v[126:129], v[48:63]
	v_mfma_f32_32x32x16_bf16 v[0:15], v[118:121], v[122:125], v[0:15]
	v_mfma_f32_32x32x16_bf16 v[32:47], v[118:121], v[126:129], v[32:47]
	global_load_dwordx4 v[72:75], v[72:73], off offset:1920
	s_nop 0
	global_load_dwordx4 v[76:79], v[76:77], off offset:1920
	s_waitcnt vmcnt(9)
	ds_write_b128 v100, v[146:149] offset:4608
	s_waitcnt vmcnt(8)
	ds_write_b128 v100, v[150:153] offset:23040
	ds_read_b128 v[114:117], v104 offset:36928
	ds_read_b128 v[118:121], v104 offset:41536
	ds_read_b128 v[122:125], v101 offset:55360
	ds_read_b128 v[126:129], v101 offset:59968
	s_waitcnt lgkmcnt(7)
	v_mfma_f32_32x32x16_bf16 v[16:31], v[130:133], v[154:157], v[16:31]
	s_waitcnt lgkmcnt(6)
	v_mfma_f32_32x32x16_bf16 v[48:63], v[130:133], v[158:161], v[48:63]
	v_mfma_f32_32x32x16_bf16 v[0:15], v[134:137], v[154:157], v[0:15]
	v_mfma_f32_32x32x16_bf16 v[32:47], v[134:137], v[158:161], v[32:47]
	global_load_dwordx4 v[80:83], v[80:81], off offset:1920
	s_nop 0
	global_load_dwordx4 v[84:87], v[84:85], off offset:1920
	s_waitcnt vmcnt(9)
	ds_write_b128 v100, v[110:113] offset:9216
	s_waitcnt vmcnt(8)
	ds_write_b128 v100, v[162:165] offset:27648
	ds_read_b128 v[110:113], v104 offset:36960
	ds_read_b128 v[130:133], v104 offset:41568
	ds_read_b128 v[134:137], v101 offset:55392
	ds_read_b128 v[146:149], v101 offset:60000
	s_waitcnt lgkmcnt(7)
	v_mfma_f32_32x32x16_bf16 v[16:31], v[114:117], v[122:125], v[16:31]
	s_waitcnt lgkmcnt(6)
	v_mfma_f32_32x32x16_bf16 v[48:63], v[114:117], v[126:129], v[48:63]
	v_mfma_f32_32x32x16_bf16 v[0:15], v[118:121], v[122:125], v[0:15]
	v_mfma_f32_32x32x16_bf16 v[32:47], v[118:121], v[126:129], v[32:47]
	global_load_dwordx4 v[88:91], v[88:89], off offset:1920
	s_nop 0
	global_load_dwordx4 v[92:95], v[92:93], off offset:1920
	s_waitcnt vmcnt(9)
	ds_write_b128 v100, v[138:141] offset:13824
	s_waitcnt vmcnt(8)
	ds_write_b128 v100, v[142:145] offset:32256
	s_waitcnt lgkmcnt(3)
	v_mfma_f32_32x32x16_bf16 v[16:31], v[110:113], v[134:137], v[16:31]
	s_waitcnt lgkmcnt(2)
	v_mfma_f32_32x32x16_bf16 v[48:63], v[110:113], v[146:149], v[48:63]
	v_mfma_f32_32x32x16_bf16 v[0:15], v[130:133], v[134:137], v[0:15]
	v_mfma_f32_32x32x16_bf16 v[32:47], v[130:133], v[146:149], v[32:47]
	s_waitcnt lgkmcnt(0)
	s_barrier
; __device__ __forceinline__ void gemm_run(int tid, f32x16 (&acc)[2][2], GRegs& g, const GOp& o, int K, unsigned char* smem) {
;     ...
;   for (int k = 0; k < nk; k++) {
;     bf16r* cur = sbuf + (k & 1) * (256 * LDK);
;     bf16r* nxt = sbuf + ((k & 1) ^ 1) * (256 * LDK);
;     const bf16r* As = cur + (wm * 64 + fr) * LDK + fh * 8;
;     const bf16r* Bs = cur + 128 * LDK + (wn * 64 + fr) * LDK + fh * 8;
;     const bool wr = (k + 1 < nk), ld = (k + 2 < nk);
;     bf16x8 fa[2][2], fb[2][2];
;     fa[0][0] = *(const bf16x8*)(As);
;     fa[0][1] = *(const bf16x8*)(As + 32 * LDK);
;     fb[0][0] = *(const bf16x8*)(Bs);
;     fb[0][1] = *(const bf16x8*)(Bs + 32 * LDK);
; #pragma unroll
;     for (int i = 0; i < 4; i++) {
;       if (wr) {
;         *(u32x4*)(nxt + (r0 + i * 32) * LDK + sg * 8) = g.a[i];
;         *(u32x4*)(nxt + 128 * LDK + (r0 + i * 32) * LDK + sg * 8) = g.b[i];
;       }
;       if (ld) {
;         g.a[i] = *(const u32x4*)(Ap + (size_t)i * 32 * o.lda + (k + 2) * 64);
;         g.b[i] = *(const u32x4*)(Bp + o.bs.o[i] + (k + 2) * 64);
;       }
;       if (i < 3) {
;         fa[(i + 1) & 1][0] = *(const bf16x8*)(As + (i + 1) * 16);
;         fa[(i + 1) & 1][1] = *(const bf16x8*)(As + 32 * LDK + (i + 1) * 16);
;         fb[(i + 1) & 1][0] = *(const bf16x8*)(Bs + (i + 1) * 16);
;         fb[(i + 1) & 1][1] = *(const bf16x8*)(Bs + 32 * LDK + (i + 1) * 16);
;       }
;       __builtin_amdgcn_sched_barrier(0);
;       __builtin_amdgcn_s_setprio(1);
;       acc[0][0] = __builtin_amdgcn_mfma_f32_32x32x16_bf16(fa[i & 1][0], fb[i & 1][0], acc[0][0], 0, 0, 0);
;       acc[0][1] = __builtin_amdgcn_mfma_f32_32x32x16_bf16(fa[i & 1][0], fb[i & 1][1], acc[0][1], 0, 0, 0);
;       acc[1][0] = __builtin_amdgcn_mfma_f32_32x32x16_bf16(fa[i & 1][1], fb[i & 1][0], acc[1][0], 0, 0, 0);
;       acc[1][1] = __builtin_amdgcn_mfma_f32_32x32x16_bf16(fa[i & 1][1], fb[i & 1][1], acc[1][1], 0, 0, 0);
;       __builtin_amdgcn_s_setprio(0);
;     }
;     __syncthreads();
;   }
; __device__ __forceinline__ bool tile_map(int it, int nn, int& mt, int& nt) {
;   const int xcd = blockIdx.x & 7, li = blockIdx.x >> 3, nb = gridDim.x >> 3;
;   int q = it * nb + li;
;   const int per = 16 * nn;
;   if (q < per) {
;     int sub = q / (8 * nn), r = q - sub * (8 * nn);
;     nt = r >> 3;
;     mt = xcd * 16 + sub * 8 + (r & 7);
;     return true;
	ds_read_b128 v[110:113], v104
	ds_read_b128 v[114:117], v104 offset:4608
	ds_read_b128 v[118:121], v101 offset:18432
	ds_read_b128 v[122:125], v101 offset:23040
	s_waitcnt vmcnt(7)
	ds_write_b128 v100, v[64:67] offset:36864
	s_waitcnt vmcnt(6)
	ds_write_b128 v100, v[68:71] offset:55296
	ds_read_b128 v[126:129], v104 offset:32
	ds_read_b128 v[130:133], v104 offset:4640
	ds_read_b128 v[134:137], v101 offset:18464
	ds_read_b128 v[138:141], v101 offset:23072
	s_waitcnt lgkmcnt(7)
	v_mfma_f32_32x32x16_bf16 v[16:31], v[110:113], v[118:121], v[16:31]
	s_waitcnt lgkmcnt(6)
	v_mfma_f32_32x32x16_bf16 v[48:63], v[110:113], v[122:125], v[48:63]
	v_mfma_f32_32x32x16_bf16 v[0:15], v[114:117], v[118:121], v[0:15]
	v_mfma_f32_32x32x16_bf16 v[32:47], v[114:117], v[122:125], v[32:47]
	s_waitcnt vmcnt(5)
	ds_write_b128 v100, v[72:75] offset:41472
	s_waitcnt vmcnt(4)
	ds_write_b128 v100, v[76:79] offset:59904
	ds_read_b128 v[110:113], v104 offset:64
	ds_read_b128 v[114:117], v104 offset:4672
	ds_read_b128 v[118:121], v101 offset:18496
	ds_read_b128 v[122:125], v101 offset:23104
	s_waitcnt lgkmcnt(7)
	v_mfma_f32_32x32x16_bf16 v[16:31], v[126:129], v[134:137], v[16:31]
	s_waitcnt lgkmcnt(6)
	v_mfma_f32_32x32x16_bf16 v[48:63], v[126:129], v[138:141], v[48:63]
	v_mfma_f32_32x32x16_bf16 v[0:15], v[130:133], v[134:137], v[0:15]
	v_mfma_f32_32x32x16_bf16 v[32:47], v[130:133], v[138:141], v[32:47]
	s_waitcnt vmcnt(3)
	ds_write_b128 v100, v[80:83] offset:46080
	s_waitcnt vmcnt(2)
	ds_write_b128 v100, v[84:87] offset:64512
	ds_read_b128 v[126:129], v104 offset:96
	ds_read_b128 v[130:133], v104 offset:4704
	ds_read_b128 v[134:137], v101 offset:18528
	ds_read_b128 v[138:141], v101 offset:23136
	s_waitcnt lgkmcnt(7)
	v_mfma_f32_32x32x16_bf16 v[16:31], v[110:113], v[118:121], v[16:31]
	s_waitcnt lgkmcnt(6)
	v_mfma_f32_32x32x16_bf16 v[48:63], v[110:113], v[122:125], v[48:63]
	v_mfma_f32_32x32x16_bf16 v[0:15], v[114:117], v[118:121], v[0:15]
	v_mfma_f32_32x32x16_bf16 v[32:47], v[114:117], v[122:125], v[32:47]
	s_waitcnt vmcnt(1)
	ds_write_b128 v100, v[88:91] offset:50688
	s_waitcnt vmcnt(0)
	ds_write_b128 v105, v[92:95] offset:13824
	s_waitcnt lgkmcnt(3)
	v_mfma_f32_32x32x16_bf16 v[16:31], v[126:129], v[134:137], v[16:31]
	s_waitcnt lgkmcnt(2)
	v_mfma_f32_32x32x16_bf16 v[48:63], v[126:129], v[138:141], v[48:63]
	v_mfma_f32_32x32x16_bf16 v[0:15], v[130:133], v[134:137], v[0:15]
	v_mfma_f32_32x32x16_bf16 v[32:47], v[130:133], v[138:141], v[32:47]
	s_waitcnt lgkmcnt(0)
	s_barrier
	ds_read_b128 v[110:113], v104 offset:36864
	ds_read_b128 v[114:117], v104 offset:36896
	ds_read_b128 v[118:121], v104 offset:41472
	ds_read_b128 v[122:125], v104 offset:41504
	ds_read_b128 v[126:129], v101 offset:55296
	ds_read_b128 v[130:133], v101 offset:55328
	ds_read_b128 v[134:137], v101 offset:59904
	ds_read_b128 v[138:141], v101 offset:59936
	s_waitcnt lgkmcnt(3)
	v_mfma_f32_32x32x16_bf16 v[16:31], v[110:113], v[126:129], v[16:31]
	s_waitcnt lgkmcnt(1)
	v_mfma_f32_32x32x16_bf16 v[48:63], v[110:113], v[134:137], v[48:63]
	v_mfma_f32_32x32x16_bf16 v[0:15], v[118:121], v[126:129], v[0:15]
	v_mfma_f32_32x32x16_bf16 v[32:47], v[118:121], v[134:137], v[32:47]
	ds_read_b128 v[110:113], v104 offset:36928
	ds_read_b128 v[118:121], v104 offset:41536
	ds_read_b128 v[126:129], v101 offset:55360
	ds_read_b128 v[134:137], v101 offset:59968
	v_mfma_f32_32x32x16_bf16 v[16:31], v[114:117], v[130:133], v[16:31]
	s_waitcnt lgkmcnt(4)
	v_mfma_f32_32x32x16_bf16 v[48:63], v[114:117], v[138:141], v[48:63]
	v_mfma_f32_32x32x16_bf16 v[0:15], v[122:125], v[130:133], v[0:15]
	v_mfma_f32_32x32x16_bf16 v[32:47], v[122:125], v[138:141], v[32:47]
	ds_read_b128 v[114:117], v104 offset:36960
	ds_read_b128 v[122:125], v104 offset:41568
	ds_read_b128 v[130:133], v101 offset:55392
	ds_read_b128 v[138:141], v101 offset:60000
	s_waitcnt lgkmcnt(5)
	v_mfma_f32_32x32x16_bf16 v[16:31], v[110:113], v[126:129], v[16:31]
	s_waitcnt lgkmcnt(4)
	v_mfma_f32_32x32x16_bf16 v[48:63], v[110:113], v[134:137], v[48:63]
	v_mfma_f32_32x32x16_bf16 v[0:15], v[118:121], v[126:129], v[0:15]
	v_mfma_f32_32x32x16_bf16 v[32:47], v[118:121], v[134:137], v[32:47]
	s_waitcnt lgkmcnt(1)
	v_mfma_f32_32x32x16_bf16 v[16:31], v[114:117], v[130:133], v[16:31]
	s_waitcnt lgkmcnt(0)
	v_mfma_f32_32x32x16_bf16 v[48:63], v[114:117], v[138:141], v[48:63]
	v_mfma_f32_32x32x16_bf16 v[0:15], v[122:125], v[130:133], v[0:15]
	v_mfma_f32_32x32x16_bf16 v[32:47], v[122:125], v[138:141], v[32:47]
	s_cmpk_gt_u32 s87, 0x1ff
	s_mov_b64 s[10:11], -1
	s_barrier
	s_cbranch_scc0 .LBB0_3311
	s_mov_b64 s[10:11], 0
	s_cmp_gt_i32 s76, 31
	s_mov_b64 s[4:5], 0
	s_cbranch_scc1 .LBB0_3311
	s_movk_i32 s66, 0x80
	s_mov_b64 s[4:5], -1
	s_mov_b32 s94, s76

; __device__ __forceinline__ void gemm_run(int tid, f32x16 (&acc)[2][2], GRegs& g, const GOp& o, int K, unsigned char* smem) {
;     ...
;   const int nk = K >> 6;
; #pragma unroll
;   for (int i = 0; i < 4; i++) {
;     *(u32x4*)(sbuf + (r0 + i * 32) * LDK + sg * 8) = g.a[i];
;     *(u32x4*)(sbuf + 128 * LDK + (r0 + i * 32) * LDK + sg * 8) = g.b[i];
;   }
;   if (nk > 1) {
; #pragma unroll
;     for (int i = 0; i < 4; i++) {
;       g.a[i] = *(const u32x4*)(Ap + (size_t)i * 32 * o.lda + 64);
;       g.b[i] = *(const u32x4*)(Bp + o.bs.o[i] + 64);
;     }
;   }
;   __syncthreads();
;   const int lane = tid & 63, fr = lane & 31, fh = lane >> 5;
;   for (int k = 0; k < nk; k++) {
;     bf16r* cur = sbuf + (k & 1) * (256 * LDK);
;     bf16r* nxt = sbuf + ((k & 1) ^ 1) * (256 * LDK);
;     const bf16r* As = cur + (wm * 64 + fr) * LDK + fh * 8;
;     const bf16r* Bs = cur + 128 * LDK + (wn * 64 + fr) * LDK + fh * 8;
;     const bool wr = (k + 1 < nk), ld = (k + 2 < nk);
;     bf16x8 fa[2][2], fb[2][2];
;     fa[0][0] = *(const bf16x8*)(As);
;     fa[0][1] = *(const bf16x8*)(As + 32 * LDK);
;     fb[0][0] = *(const bf16x8*)(Bs);
;     fb[0][1] = *(const bf16x8*)(Bs + 32 * LDK);
; #pragma unroll
;     for (int i = 0; i < 4; i++) {
;       if (wr) {
;         *(u32x4*)(nxt + (r0 + i * 32) * LDK + sg * 8) = g.a[i];
;         *(u32x4*)(nxt + 128 * LDK + (r0 + i * 32) * LDK + sg * 8) = g.b[i];
;       }
;       if (ld) {
;         g.a[i] = *(const u32x4*)(Ap + (size_t)i * 32 * o.lda + (k + 2) * 64);
;         g.b[i] = *(const u32x4*)(Bp + o.bs.o[i] + (k + 2) * 64);
;       }
;       if (i < 3) {
;         fa[(i + 1) & 1][0] = *(const bf16x8*)(As + (i + 1) * 16);
;         fa[(i + 1) & 1][1] = *(const bf16x8*)(As + 32 * LDK + (i + 1) * 16);
;         fb[(i + 1) & 1][0] = *(const bf16x8*)(Bs + (i + 1) * 16);
;         fb[(i + 1) & 1][1] = *(const bf16x8*)(Bs + 32 * LDK + (i + 1) * 16);
;       }
;       __builtin_amdgcn_sched_barrier(0);
;       __builtin_amdgcn_s_setprio(1);
;       acc[0][0] = __builtin_amdgcn_mfma_f32_32x32x16_bf16(fa[i & 1][0], fb[i & 1][0], acc[0][0], 0, 0, 0);
;       acc[0][1] = __builtin_amdgcn_mfma_f32_32x32x16_bf16(fa[i & 1][0], fb[i & 1][1], acc[0][1], 0, 0, 0);
;       acc[1][0] = __builtin_amdgcn_mfma_f32_32x32x16_bf16(fa[i & 1][1], fb[i & 1][0], acc[1][0], 0, 0, 0);
.LBB0_4092:
	s_ashr_i32 s7, s6, 31
	s_lshl_b64 s[4:5], s[6:7], 18
	s_ashr_i32 s9, s8, 31
	s_waitcnt vmcnt(7)
	ds_write_b128 v100, v[64:67]
	s_waitcnt vmcnt(6)
	ds_write_b128 v100, v[68:71] offset:18432
	s_waitcnt vmcnt(5)
	ds_write_b128 v100, v[72:75] offset:4608
	s_waitcnt vmcnt(4)
	ds_write_b128 v100, v[76:79] offset:23040
	s_waitcnt vmcnt(3)
	ds_write_b128 v100, v[80:83] offset:9216
	s_waitcnt vmcnt(2)
	ds_write_b128 v100, v[84:87] offset:27648
	s_waitcnt vmcnt(1)
	ds_write_b128 v100, v[88:91] offset:13824
	s_waitcnt vmcnt(0)
	ds_write_b128 v100, v[92:95] offset:32256
	v_lshl_add_u64 v[64:65], v[102:103], 0, s[4:5]
	s_lshl_b64 s[10:11], s[8:9], 18
	v_add_co_u32_e32 v72, vcc, s88, v64
	v_lshl_add_u64 v[106:107], v[98:99], 0, s[10:11]
	s_nop 0
	v_addc_co_u32_e32 v73, vcc, 0, v65, vcc
	v_add_co_u32_e32 v76, vcc, s88, v106
	global_load_dwordx4 v[0:3], v[64:65], off offset:128
	global_load_dwordx4 v[4:7], v[106:107], off offset:128
	v_addc_co_u32_e32 v77, vcc, 0, v107, vcc
	v_add_co_u32_e32 v80, vcc, s76, v64
	global_load_dwordx4 v[66:69], v[72:73], off offset:128
	global_load_dwordx4 v[110:113], v[76:77], off offset:128
	v_addc_co_u32_e32 v81, vcc, 0, v65, vcc
	v_add_co_u32_e32 v84, vcc, s76, v106
	s_nop 1
	v_addc_co_u32_e32 v85, vcc, 0, v107, vcc
	v_add_co_u32_e32 v88, vcc, s77, v64
	global_load_dwordx4 v[114:117], v[80:81], off offset:128
	global_load_dwordx4 v[118:121], v[84:85], off offset:128
	v_addc_co_u32_e32 v89, vcc, 0, v65, vcc
	v_add_co_u32_e32 v92, vcc, s77, v106
	s_nop 1
	v_addc_co_u32_e32 v93, vcc, 0, v107, vcc
	global_load_dwordx4 v[122:125], v[88:89], off offset:128
	global_load_dwordx4 v[126:129], v[92:93], off offset:128
	s_waitcnt lgkmcnt(0)
	s_barrier
	global_load_dwordx4 v[130:133], v[64:65], off offset:256
	global_load_dwordx4 v[134:137], v[106:107], off offset:256
	ds_read_b128 v[8:11], v104
	ds_read_b128 v[32:35], v104 offset:4608
	ds_read_b128 v[12:15], v101 offset:18432
	ds_read_b128 v[36:39], v101 offset:23040
	s_waitcnt vmcnt(9)
	ds_write_b128 v100, v[0:3] offset:36864
	s_waitcnt vmcnt(8)
	ds_write_b128 v100, v[4:7] offset:55296
	ds_read_b128 v[138:141], v104 offset:32
	ds_read_b128 v[142:145], v104 offset:4640
	ds_read_b128 v[146:149], v101 offset:18464
	ds_read_b128 v[150:153], v101 offset:23072
	s_waitcnt lgkmcnt(7)
	v_mfma_f32_32x32x16_bf16 v[16:31], v[8:11], v[12:15], 0
	s_waitcnt lgkmcnt(6)
	v_mfma_f32_32x32x16_bf16 v[48:63], v[8:11], v[36:39], 0
	v_mfma_f32_32x32x16_bf16 v[0:15], v[32:35], v[12:15], 0
	v_mfma_f32_32x32x16_bf16 v[32:47], v[32:35], v[36:39], 0
	global_load_dwordx4 v[154:157], v[72:73], off offset:256
	global_load_dwordx4 v[158:161], v[76:77], off offset:256
	s_waitcnt vmcnt(9)
	ds_write_b128 v100, v[66:69] offset:41472
	s_waitcnt vmcnt(8)
	ds_write_b128 v100, v[110:113] offset:59904
	ds_read_b128 v[66:69], v104 offset:64
	ds_read_b128 v[110:113], v104 offset:4672
	ds_read_b128 v[162:165], v101 offset:18496
	ds_read_b128 v[166:169], v101 offset:23104
	s_waitcnt lgkmcnt(7)
	v_mfma_f32_32x32x16_bf16 v[16:31], v[138:141], v[146:149], v[16:31]
	s_waitcnt lgkmcnt(6)
	v_mfma_f32_32x32x16_bf16 v[48:63], v[138:141], v[150:153], v[48:63]
	v_mfma_f32_32x32x16_bf16 v[0:15], v[142:145], v[146:149], v[0:15]
	v_mfma_f32_32x32x16_bf16 v[32:47], v[142:145], v[150:153], v[32:47]
	global_load_dwordx4 v[138:141], v[80:81], off offset:256
	global_load_dwordx4 v[142:145], v[84:85], off offset:256
	s_waitcnt vmcnt(9)
	ds_write_b128 v100, v[114:117] offset:46080
	s_waitcnt vmcnt(8)
	ds_write_b128 v100, v[118:121] offset:64512
	ds_read_b128 v[114:117], v104 offset:96
	ds_read_b128 v[118:121], v104 offset:4704
	ds_read_b128 v[146:149], v101 offset:18528
	ds_read_b128 v[150:153], v101 offset:23136
	s_waitcnt lgkmcnt(7)
	v_mfma_f32_32x32x16_bf16 v[16:31], v[66:69], v[162:165], v[16:31]
	s_waitcnt lgkmcnt(6)
	v_mfma_f32_32x32x16_bf16 v[48:63], v[66:69], v[166:169], v[48:63]
	v_mfma_f32_32x32x16_bf16 v[0:15], v[110:113], v[162:165], v[0:15]
	v_mfma_f32_32x32x16_bf16 v[32:47], v[110:113], v[166:169], v[32:47]
	global_load_dwordx4 v[66:69], v[88:89], off offset:256
	global_load_dwordx4 v[110:113], v[92:93], off offset:256
	s_waitcnt vmcnt(9)
	ds_write_b128 v100, v[122:125] offset:50688
	s_waitcnt vmcnt(8)
	ds_write_b128 v105, v[126:129] offset:13824
	s_waitcnt lgkmcnt(3)
	v_mfma_f32_32x32x16_bf16 v[16:31], v[114:117], v[146:149], v[16:31]
	s_waitcnt lgkmcnt(2)
	v_mfma_f32_32x32x16_bf16 v[48:63], v[114:117], v[150:153], v[48:63]
	v_mfma_f32_32x32x16_bf16 v[0:15], v[118:121], v[146:149], v[0:15]
	v_mfma_f32_32x32x16_bf16 v[32:47], v[118:121], v[150:153], v[32:47]
	s_waitcnt lgkmcnt(0)
	s_barrier
; __device__ __forceinline__ void gemm_run(int tid, f32x16 (&acc)[2][2], GRegs& g, const GOp& o, int K, unsigned char* smem) {
;     ...
;   for (int k = 0; k < nk; k++) {
;     bf16r* cur = sbuf + (k & 1) * (256 * LDK);
;     bf16r* nxt = sbuf + ((k & 1) ^ 1) * (256 * LDK);
;     const bf16r* As = cur + (wm * 64 + fr) * LDK + fh * 8;
;     const bf16r* Bs = cur + 128 * LDK + (wn * 64 + fr) * LDK + fh * 8;
;     const bool wr = (k + 1 < nk), ld = (k + 2 < nk);
;     bf16x8 fa[2][2], fb[2][2];
;     fa[0][0] = *(const bf16x8*)(As);
;     fa[0][1] = *(const bf16x8*)(As + 32 * LDK);
;     fb[0][0] = *(const bf16x8*)(Bs);
;     fb[0][1] = *(const bf16x8*)(Bs + 32 * LDK);
; #pragma unroll
;     for (int i = 0; i < 4; i++) {
;       if (wr) {
;         *(u32x4*)(nxt + (r0 + i * 32) * LDK + sg * 8) = g.a[i];
;         *(u32x4*)(nxt + 128 * LDK + (r0 + i * 32) * LDK + sg * 8) = g.b[i];
;       }
;       if (ld) {
;         g.a[i] = *(const u32x4*)(Ap + (size_t)i * 32 * o.lda + (k + 2) * 64);
;         g.b[i] = *(const u32x4*)(Bp + o.bs.o[i] + (k + 2) * 64);
;       }
;       if (i < 3) {
;         fa[(i + 1) & 1][0] = *(const bf16x8*)(As + (i + 1) * 16);
;         fa[(i + 1) & 1][1] = *(const bf16x8*)(As + 32 * LDK + (i + 1) * 16);
;         fb[(i + 1) & 1][0] = *(const bf16x8*)(Bs + (i + 1) * 16);
;         fb[(i + 1) & 1][1] = *(const bf16x8*)(Bs + 32 * LDK + (i + 1) * 16);
;       }
;       __builtin_amdgcn_sched_barrier(0);
;       __builtin_amdgcn_s_setprio(1);
;       acc[0][0] = __builtin_amdgcn_mfma_f32_32x32x16_bf16(fa[i & 1][0], fb[i & 1][0], acc[0][0], 0, 0, 0);
;       acc[0][1] = __builtin_amdgcn_mfma_f32_32x32x16_bf16(fa[i & 1][0], fb[i & 1][1], acc[0][1], 0, 0, 0);
;       acc[1][0] = __builtin_amdgcn_mfma_f32_32x32x16_bf16(fa[i & 1][1], fb[i & 1][0], acc[1][0], 0, 0, 0);
;       acc[1][1] = __builtin_amdgcn_mfma_f32_32x32x16_bf16(fa[i & 1][1], fb[i & 1][1], acc[1][1], 0, 0, 0);
;       __builtin_amdgcn_s_setprio(0);
;     }
;     __syncthreads();
	global_load_dwordx4 v[114:117], v[64:65], off offset:384
	global_load_dwordx4 v[118:121], v[106:107], off offset:384
	ds_read_b128 v[122:125], v104 offset:36864
	ds_read_b128 v[126:129], v104 offset:41472
	ds_read_b128 v[146:149], v101 offset:55296
	ds_read_b128 v[150:153], v101 offset:59904
	s_waitcnt vmcnt(9)
	ds_write_b128 v100, v[130:133]
	s_waitcnt vmcnt(8)
	ds_write_b128 v100, v[134:137] offset:18432
	ds_read_b128 v[130:133], v104 offset:36896
	ds_read_b128 v[134:137], v104 offset:41504
	ds_read_b128 v[162:165], v101 offset:55328
	ds_read_b128 v[166:169], v101 offset:59936
	s_waitcnt lgkmcnt(7)
	v_mfma_f32_32x32x16_bf16 v[16:31], v[122:125], v[146:149], v[16:31]
	s_waitcnt lgkmcnt(6)
	v_mfma_f32_32x32x16_bf16 v[48:63], v[122:125], v[150:153], v[48:63]
	v_mfma_f32_32x32x16_bf16 v[0:15], v[126:129], v[146:149], v[0:15]
	v_mfma_f32_32x32x16_bf16 v[32:47], v[126:129], v[150:153], v[32:47]
	global_load_dwordx4 v[122:125], v[72:73], off offset:384
	global_load_dwordx4 v[126:129], v[76:77], off offset:384
	s_waitcnt vmcnt(9)
	ds_write_b128 v100, v[154:157] offset:4608
	s_waitcnt vmcnt(8)
	ds_write_b128 v100, v[158:161] offset:23040
	ds_read_b128 v[146:149], v104 offset:36928
	ds_read_b128 v[150:153], v104 offset:41536
	ds_read_b128 v[154:157], v101 offset:55360
	ds_read_b128 v[158:161], v101 offset:59968
	s_waitcnt lgkmcnt(7)
	v_mfma_f32_32x32x16_bf16 v[16:31], v[130:133], v[162:165], v[16:31]
	s_waitcnt lgkmcnt(6)
	v_mfma_f32_32x32x16_bf16 v[48:63], v[130:133], v[166:169], v[48:63]
	v_mfma_f32_32x32x16_bf16 v[0:15], v[134:137], v[162:165], v[0:15]
	v_mfma_f32_32x32x16_bf16 v[32:47], v[134:137], v[166:169], v[32:47]
	global_load_dwordx4 v[130:133], v[80:81], off offset:384
	global_load_dwordx4 v[134:137], v[84:85], off offset:384
	s_waitcnt vmcnt(9)
	ds_write_b128 v100, v[138:141] offset:9216
	s_waitcnt vmcnt(8)
	ds_write_b128 v100, v[142:145] offset:27648
	ds_read_b128 v[138:141], v104 offset:36960
	ds_read_b128 v[142:145], v104 offset:41568
	ds_read_b128 v[162:165], v101 offset:55392
	ds_read_b128 v[166:169], v101 offset:60000
	s_waitcnt lgkmcnt(7)
	v_mfma_f32_32x32x16_bf16 v[16:31], v[146:149], v[154:157], v[16:31]
	s_waitcnt lgkmcnt(6)
	v_mfma_f32_32x32x16_bf16 v[48:63], v[146:149], v[158:161], v[48:63]
	v_mfma_f32_32x32x16_bf16 v[0:15], v[150:153], v[154:157], v[0:15]
	v_mfma_f32_32x32x16_bf16 v[32:47], v[150:153], v[158:161], v[32:47]
	global_load_dwordx4 v[146:149], v[88:89], off offset:384
	global_load_dwordx4 v[150:153], v[92:93], off offset:384
	s_waitcnt vmcnt(9)
	ds_write_b128 v100, v[66:69] offset:13824
	s_waitcnt vmcnt(8)
	ds_write_b128 v100, v[110:113] offset:32256
	s_waitcnt lgkmcnt(3)
	v_mfma_f32_32x32x16_bf16 v[16:31], v[138:141], v[162:165], v[16:31]
	s_waitcnt lgkmcnt(2)
	v_mfma_f32_32x32x16_bf16 v[48:63], v[138:141], v[166:169], v[48:63]
	v_mfma_f32_32x32x16_bf16 v[0:15], v[142:145], v[162:165], v[0:15]
	v_mfma_f32_32x32x16_bf16 v[32:47], v[142:145], v[166:169], v[32:47]
	s_waitcnt lgkmcnt(0)
	s_barrier
	global_load_dwordx4 v[66:69], v[64:65], off offset:512
	global_load_dwordx4 v[110:113], v[106:107], off offset:512
	ds_read_b128 v[138:141], v104
	ds_read_b128 v[142:145], v104 offset:4608
	ds_read_b128 v[154:157], v101 offset:18432
	ds_read_b128 v[158:161], v101 offset:23040
	s_waitcnt vmcnt(9)
	ds_write_b128 v100, v[114:117] offset:36864
	s_waitcnt vmcnt(8)
	ds_write_b128 v100, v[118:121] offset:55296
	ds_read_b128 v[114:117], v104 offset:32
	ds_read_b128 v[118:121], v104 offset:4640
	ds_read_b128 v[162:165], v101 offset:18464
	ds_read_b128 v[166:169], v101 offset:23072
	s_waitcnt lgkmcnt(7)
	v_mfma_f32_32x32x16_bf16 v[16:31], v[138:141], v[154:157], v[16:31]
	s_waitcnt lgkmcnt(6)
	v_mfma_f32_32x32x16_bf16 v[48:63], v[138:141], v[158:161], v[48:63]
	v_mfma_f32_32x32x16_bf16 v[0:15], v[142:145], v[154:157], v[0:15]
	v_mfma_f32_32x32x16_bf16 v[32:47], v[142:145], v[158:161], v[32:47]
	global_load_dwordx4 v[138:141], v[72:73], off offset:512
	global_load_dwordx4 v[142:145], v[76:77], off offset:512
	s_waitcnt vmcnt(9)
	ds_write_b128 v100, v[122:125] offset:41472
	s_waitcnt vmcnt(8)
	ds_write_b128 v100, v[126:129] offset:59904
	ds_read_b128 v[122:125], v104 offset:64
	ds_read_b128 v[126:129], v104 offset:4672
	ds_read_b128 v[154:157], v101 offset:18496
	ds_read_b128 v[158:161], v101 offset:23104
	s_waitcnt lgkmcnt(7)
	v_mfma_f32_32x32x16_bf16 v[16:31], v[114:117], v[162:165], v[16:31]
	s_waitcnt lgkmcnt(6)
	v_mfma_f32_32x32x16_bf16 v[48:63], v[114:117], v[166:169], v[48:63]
	v_mfma_f32_32x32x16_bf16 v[0:15], v[118:121], v[162:165], v[0:15]
	v_mfma_f32_32x32x16_bf16 v[32:47], v[118:121], v[166:169], v[32:47]
	global_load_dwordx4 v[114:117], v[80:81], off offset:512
	global_load_dwordx4 v[118:121], v[84:85], off offset:512
	s_waitcnt vmcnt(9)
	ds_write_b128 v100, v[130:133] offset:46080
	s_waitcnt vmcnt(8)
	ds_write_b128 v100, v[134:137] offset:64512
	ds_read_b128 v[130:133], v104 offset:96
	ds_read_b128 v[134:137], v104 offset:4704
	ds_read_b128 v[162:165], v101 offset:18528
	ds_read_b128 v[166:169], v101 offset:23136
	s_waitcnt lgkmcnt(7)
	v_mfma_f32_32x32x16_bf16 v[16:31], v[122:125], v[154:157], v[16:31]
	s_waitcnt lgkmcnt(6)
	v_mfma_f32_32x32x16_bf16 v[48:63], v[122:125], v[158:161], v[48:63]
	v_mfma_f32_32x32x16_bf16 v[0:15], v[126:129], v[154:157], v[0:15]
	v_mfma_f32_32x32x16_bf16 v[32:47], v[126:129], v[158:161], v[32:47]
	global_load_dwordx4 v[122:125], v[88:89], off offset:512
	global_load_dwordx4 v[126:129], v[92:93], off offset:512
	s_waitcnt vmcnt(9)
	ds_write_b128 v100, v[146:149] offset:50688
	s_waitcnt vmcnt(8)
	ds_write_b128 v105, v[150:153] offset:13824
	s_waitcnt lgkmcnt(3)
	v_mfma_f32_32x32x16_bf16 v[16:31], v[130:133], v[162:165], v[16:31]
	s_waitcnt lgkmcnt(2)
	v_mfma_f32_32x32x16_bf16 v[48:63], v[130:133], v[166:169], v[48:63]
	v_mfma_f32_32x32x16_bf16 v[0:15], v[134:137], v[162:165], v[0:15]
	v_mfma_f32_32x32x16_bf16 v[32:47], v[134:137], v[166:169], v[32:47]
	s_waitcnt lgkmcnt(0)
	s_barrier
; __device__ __forceinline__ void gemm_run(int tid, f32x16 (&acc)[2][2], GRegs& g, const GOp& o, int K, unsigned char* smem) {
;     ...
;   for (int k = 0; k < nk; k++) {
;     bf16r* cur = sbuf + (k & 1) * (256 * LDK);
;     bf16r* nxt = sbuf + ((k & 1) ^ 1) * (256 * LDK);
;     const bf16r* As = cur + (wm * 64 + fr) * LDK + fh * 8;
;     const bf16r* Bs = cur + 128 * LDK + (wn * 64 + fr) * LDK + fh * 8;
;     const bool wr = (k + 1 < nk), ld = (k + 2 < nk);
;     bf16x8 fa[2][2], fb[2][2];
;     fa[0][0] = *(const bf16x8*)(As);
;     fa[0][1] = *(const bf16x8*)(As + 32 * LDK);
;     fb[0][0] = *(const bf16x8*)(Bs);
;     fb[0][1] = *(const bf16x8*)(Bs + 32 * LDK);
; #pragma unroll
;     for (int i = 0; i < 4; i++) {
;       if (wr) {
;         *(u32x4*)(nxt + (r0 + i * 32) * LDK + sg * 8) = g.a[i];
;         *(u32x4*)(nxt + 128 * LDK + (r0 + i * 32) * LDK + sg * 8) = g.b[i];
;       }
;       if (ld) {
;         g.a[i] = *(const u32x4*)(Ap + (size_t)i * 32 * o.lda + (k + 2) * 64);
;         g.b[i] = *(const u32x4*)(Bp + o.bs.o[i] + (k + 2) * 64);
;       }
;       if (i < 3) {
;         fa[(i + 1) & 1][0] = *(const bf16x8*)(As + (i + 1) * 16);
;         fa[(i + 1) & 1][1] = *(const bf16x8*)(As + 32 * LDK + (i + 1) * 16);
;         fb[(i + 1) & 1][0] = *(const bf16x8*)(Bs + (i + 1) * 16);
;         fb[(i + 1) & 1][1] = *(const bf16x8*)(Bs + 32 * LDK + (i + 1) * 16);
;       }
;       __builtin_amdgcn_sched_barrier(0);
;       __builtin_amdgcn_s_setprio(1);
;       acc[0][0] = __builtin_amdgcn_mfma_f32_32x32x16_bf16(fa[i & 1][0], fb[i & 1][0], acc[0][0], 0, 0, 0);
;       acc[0][1] = __builtin_amdgcn_mfma_f32_32x32x16_bf16(fa[i & 1][0], fb[i & 1][1], acc[0][1], 0, 0, 0);
;       acc[1][0] = __builtin_amdgcn_mfma_f32_32x32x16_bf16(fa[i & 1][1], fb[i & 1][0], acc[1][0], 0, 0, 0);
;       acc[1][1] = __builtin_amdgcn_mfma_f32_32x32x16_bf16(fa[i & 1][1], fb[i & 1][1], acc[1][1], 0, 0, 0);
;       __builtin_amdgcn_s_setprio(0);
;     }
;     __syncthreads();
	global_load_dwordx4 v[130:133], v[64:65], off offset:640
	global_load_dwordx4 v[134:137], v[106:107], off offset:640
	ds_read_b128 v[146:149], v104 offset:36864
	ds_read_b128 v[150:153], v104 offset:41472
	ds_read_b128 v[154:157], v101 offset:55296
	ds_read_b128 v[158:161], v101 offset:59904
	s_waitcnt vmcnt(9)
	ds_write_b128 v100, v[66:69]
	s_waitcnt vmcnt(8)
	ds_write_b128 v100, v[110:113] offset:18432
	ds_read_b128 v[66:69], v104 offset:36896
	ds_read_b128 v[110:113], v104 offset:41504
	ds_read_b128 v[162:165], v101 offset:55328
	ds_read_b128 v[166:169], v101 offset:59936
	s_waitcnt lgkmcnt(7)
	v_mfma_f32_32x32x16_bf16 v[16:31], v[146:149], v[154:157], v[16:31]
	s_waitcnt lgkmcnt(6)
	v_mfma_f32_32x32x16_bf16 v[48:63], v[146:149], v[158:161], v[48:63]
	v_mfma_f32_32x32x16_bf16 v[0:15], v[150:153], v[154:157], v[0:15]
	v_mfma_f32_32x32x16_bf16 v[32:47], v[150:153], v[158:161], v[32:47]
	global_load_dwordx4 v[146:149], v[72:73], off offset:640
	global_load_dwordx4 v[150:153], v[76:77], off offset:640
	s_waitcnt vmcnt(9)
	ds_write_b128 v100, v[138:141] offset:4608
	s_waitcnt vmcnt(8)
	ds_write_b128 v100, v[142:145] offset:23040
	ds_read_b128 v[138:141], v104 offset:36928
	ds_read_b128 v[142:145], v104 offset:41536
	ds_read_b128 v[154:157], v101 offset:55360
	ds_read_b128 v[158:161], v101 offset:59968
	s_waitcnt lgkmcnt(7)
	v_mfma_f32_32x32x16_bf16 v[16:31], v[66:69], v[162:165], v[16:31]
	s_waitcnt lgkmcnt(6)
	v_mfma_f32_32x32x16_bf16 v[48:63], v[66:69], v[166:169], v[48:63]
	v_mfma_f32_32x32x16_bf16 v[0:15], v[110:113], v[162:165], v[0:15]
	v_mfma_f32_32x32x16_bf16 v[32:47], v[110:113], v[166:169], v[32:47]
	global_load_dwordx4 v[66:69], v[80:81], off offset:640
	global_load_dwordx4 v[110:113], v[84:85], off offset:640
	s_waitcnt vmcnt(9)
	ds_write_b128 v100, v[114:117] offset:9216
	s_waitcnt vmcnt(8)
	ds_write_b128 v100, v[118:121] offset:27648
	ds_read_b128 v[114:117], v104 offset:36960
	ds_read_b128 v[118:121], v104 offset:41568
	ds_read_b128 v[162:165], v101 offset:55392
	ds_read_b128 v[166:169], v101 offset:60000
	s_waitcnt lgkmcnt(7)
	v_mfma_f32_32x32x16_bf16 v[16:31], v[138:141], v[154:157], v[16:31]
	s_waitcnt lgkmcnt(6)
	v_mfma_f32_32x32x16_bf16 v[48:63], v[138:141], v[158:161], v[48:63]
	v_mfma_f32_32x32x16_bf16 v[0:15], v[142:145], v[154:157], v[0:15]
	v_mfma_f32_32x32x16_bf16 v[32:47], v[142:145], v[158:161], v[32:47]
	global_load_dwordx4 v[138:141], v[88:89], off offset:640
	global_load_dwordx4 v[142:145], v[92:93], off offset:640
	s_waitcnt vmcnt(9)
	ds_write_b128 v100, v[122:125] offset:13824
	s_waitcnt vmcnt(8)
	ds_write_b128 v100, v[126:129] offset:32256
	s_waitcnt lgkmcnt(3)
	v_mfma_f32_32x32x16_bf16 v[16:31], v[114:117], v[162:165], v[16:31]
	s_waitcnt lgkmcnt(2)
	v_mfma_f32_32x32x16_bf16 v[48:63], v[114:117], v[166:169], v[48:63]
	v_mfma_f32_32x32x16_bf16 v[0:15], v[118:121], v[162:165], v[0:15]
	v_mfma_f32_32x32x16_bf16 v[32:47], v[118:121], v[166:169], v[32:47]
	s_waitcnt lgkmcnt(0)
	s_barrier
	global_load_dwordx4 v[114:117], v[64:65], off offset:768
	global_load_dwordx4 v[118:121], v[106:107], off offset:768
	ds_read_b128 v[122:125], v104
	ds_read_b128 v[126:129], v104 offset:4608
	ds_read_b128 v[154:157], v101 offset:18432
	ds_read_b128 v[158:161], v101 offset:23040
	s_waitcnt vmcnt(9)
	ds_write_b128 v100, v[130:133] offset:36864
	s_waitcnt vmcnt(8)
	ds_write_b128 v100, v[134:137] offset:55296
	ds_read_b128 v[130:133], v104 offset:32
	ds_read_b128 v[134:137], v104 offset:4640
	ds_read_b128 v[162:165], v101 offset:18464
	ds_read_b128 v[166:169], v101 offset:23072
	s_waitcnt lgkmcnt(7)
	v_mfma_f32_32x32x16_bf16 v[16:31], v[122:125], v[154:157], v[16:31]
	s_waitcnt lgkmcnt(6)
	v_mfma_f32_32x32x16_bf16 v[48:63], v[122:125], v[158:161], v[48:63]
	v_mfma_f32_32x32x16_bf16 v[0:15], v[126:129], v[154:157], v[0:15]
	v_mfma_f32_32x32x16_bf16 v[32:47], v[126:129], v[158:161], v[32:47]
	global_load_dwordx4 v[122:125], v[72:73], off offset:768
	global_load_dwordx4 v[126:129], v[76:77], off offset:768
	s_waitcnt vmcnt(9)
	ds_write_b128 v100, v[146:149] offset:41472
	s_waitcnt vmcnt(8)
	ds_write_b128 v100, v[150:153] offset:59904
	ds_read_b128 v[146:149], v104 offset:64
	ds_read_b128 v[150:153], v104 offset:4672
	ds_read_b128 v[154:157], v101 offset:18496
	ds_read_b128 v[158:161], v101 offset:23104
	s_waitcnt lgkmcnt(7)
	v_mfma_f32_32x32x16_bf16 v[16:31], v[130:133], v[162:165], v[16:31]
	s_waitcnt lgkmcnt(6)
	v_mfma_f32_32x32x16_bf16 v[48:63], v[130:133], v[166:169], v[48:63]
	v_mfma_f32_32x32x16_bf16 v[0:15], v[134:137], v[162:165], v[0:15]
	v_mfma_f32_32x32x16_bf16 v[32:47], v[134:137], v[166:169], v[32:47]
	global_load_dwordx4 v[130:133], v[80:81], off offset:768
	global_load_dwordx4 v[134:137], v[84:85], off offset:768
	s_waitcnt vmcnt(9)
	ds_write_b128 v100, v[66:69] offset:46080
	s_waitcnt vmcnt(8)
	ds_write_b128 v100, v[110:113] offset:64512
	ds_read_b128 v[66:69], v104 offset:96
	ds_read_b128 v[110:113], v104 offset:4704
	ds_read_b128 v[162:165], v101 offset:18528
	ds_read_b128 v[166:169], v101 offset:23136
	s_waitcnt lgkmcnt(7)
	v_mfma_f32_32x32x16_bf16 v[16:31], v[146:149], v[154:157], v[16:31]
	s_waitcnt lgkmcnt(6)
	v_mfma_f32_32x32x16_bf16 v[48:63], v[146:149], v[158:161], v[48:63]
	v_mfma_f32_32x32x16_bf16 v[0:15], v[150:153], v[154:157], v[0:15]
	v_mfma_f32_32x32x16_bf16 v[32:47], v[150:153], v[158:161], v[32:47]
	global_load_dwordx4 v[146:149], v[88:89], off offset:768
	global_load_dwordx4 v[150:153], v[92:93], off offset:768
	s_waitcnt vmcnt(9)
	ds_write_b128 v100, v[138:141] offset:50688
	s_waitcnt vmcnt(8)
	ds_write_b128 v105, v[142:145] offset:13824
	s_waitcnt lgkmcnt(3)
	v_mfma_f32_32x32x16_bf16 v[16:31], v[66:69], v[162:165], v[16:31]
	s_waitcnt lgkmcnt(2)
	v_mfma_f32_32x32x16_bf16 v[48:63], v[66:69], v[166:169], v[48:63]
	v_mfma_f32_32x32x16_bf16 v[0:15], v[110:113], v[162:165], v[0:15]
	v_mfma_f32_32x32x16_bf16 v[32:47], v[110:113], v[166:169], v[32:47]
	s_waitcnt lgkmcnt(0)
	s_barrier
; __device__ __forceinline__ void gemm_run(int tid, f32x16 (&acc)[2][2], GRegs& g, const GOp& o, int K, unsigned char* smem) {
;     ...
;   for (int k = 0; k < nk; k++) {
;     bf16r* cur = sbuf + (k & 1) * (256 * LDK);
;     bf16r* nxt = sbuf + ((k & 1) ^ 1) * (256 * LDK);
;     const bf16r* As = cur + (wm * 64 + fr) * LDK + fh * 8;
;     const bf16r* Bs = cur + 128 * LDK + (wn * 64 + fr) * LDK + fh * 8;
;     const bool wr = (k + 1 < nk), ld = (k + 2 < nk);
;     bf16x8 fa[2][2], fb[2][2];
;     fa[0][0] = *(const bf16x8*)(As);
;     fa[0][1] = *(const bf16x8*)(As + 32 * LDK);
;     fb[0][0] = *(const bf16x8*)(Bs);
;     fb[0][1] = *(const bf16x8*)(Bs + 32 * LDK);
; #pragma unroll
;     for (int i = 0; i < 4; i++) {
;       if (wr) {
;         *(u32x4*)(nxt + (r0 + i * 32) * LDK + sg * 8) = g.a[i];
;         *(u32x4*)(nxt + 128 * LDK + (r0 + i * 32) * LDK + sg * 8) = g.b[i];
;       }
;       if (ld) {
;         g.a[i] = *(const u32x4*)(Ap + (size_t)i * 32 * o.lda + (k + 2) * 64);
;         g.b[i] = *(const u32x4*)(Bp + o.bs.o[i] + (k + 2) * 64);
;       }
;       if (i < 3) {
;         fa[(i + 1) & 1][0] = *(const bf16x8*)(As + (i + 1) * 16);
;         fa[(i + 1) & 1][1] = *(const bf16x8*)(As + 32 * LDK + (i + 1) * 16);
;         fb[(i + 1) & 1][0] = *(const bf16x8*)(Bs + (i + 1) * 16);
;         fb[(i + 1) & 1][1] = *(const bf16x8*)(Bs + 32 * LDK + (i + 1) * 16);
;       }
;       __builtin_amdgcn_sched_barrier(0);
;       __builtin_amdgcn_s_setprio(1);
;       acc[0][0] = __builtin_amdgcn_mfma_f32_32x32x16_bf16(fa[i & 1][0], fb[i & 1][0], acc[0][0], 0, 0, 0);
;       acc[0][1] = __builtin_amdgcn_mfma_f32_32x32x16_bf16(fa[i & 1][0], fb[i & 1][1], acc[0][1], 0, 0, 0);
;       acc[1][0] = __builtin_amdgcn_mfma_f32_32x32x16_bf16(fa[i & 1][1], fb[i & 1][0], acc[1][0], 0, 0, 0);
;       acc[1][1] = __builtin_amdgcn_mfma_f32_32x32x16_bf16(fa[i & 1][1], fb[i & 1][1], acc[1][1], 0, 0, 0);
;       __builtin_amdgcn_s_setprio(0);
;     }
;     __syncthreads();
	global_load_dwordx4 v[66:69], v[64:65], off offset:896
	global_load_dwordx4 v[110:113], v[106:107], off offset:896
	ds_read_b128 v[138:141], v104 offset:36864
	ds_read_b128 v[142:145], v104 offset:41472
	ds_read_b128 v[154:157], v101 offset:55296
	ds_read_b128 v[158:161], v101 offset:59904
	s_waitcnt vmcnt(9)
	ds_write_b128 v100, v[114:117]
	s_waitcnt vmcnt(8)
	ds_write_b128 v100, v[118:121] offset:18432
	ds_read_b128 v[114:117], v104 offset:36896
	ds_read_b128 v[118:121], v104 offset:41504
	ds_read_b128 v[162:165], v101 offset:55328
	ds_read_b128 v[166:169], v101 offset:59936
	s_waitcnt lgkmcnt(7)
	v_mfma_f32_32x32x16_bf16 v[16:31], v[138:141], v[154:157], v[16:31]
	s_waitcnt lgkmcnt(6)
	v_mfma_f32_32x32x16_bf16 v[48:63], v[138:141], v[158:161], v[48:63]
	v_mfma_f32_32x32x16_bf16 v[0:15], v[142:145], v[154:157], v[0:15]
	v_mfma_f32_32x32x16_bf16 v[32:47], v[142:145], v[158:161], v[32:47]
	global_load_dwordx4 v[138:141], v[72:73], off offset:896
	global_load_dwordx4 v[142:145], v[76:77], off offset:896
	s_waitcnt vmcnt(9)
	ds_write_b128 v100, v[122:125] offset:4608
	s_waitcnt vmcnt(8)
	ds_write_b128 v100, v[126:129] offset:23040
	ds_read_b128 v[122:125], v104 offset:36928
	ds_read_b128 v[126:129], v104 offset:41536
	ds_read_b128 v[154:157], v101 offset:55360
	ds_read_b128 v[158:161], v101 offset:59968
	s_waitcnt lgkmcnt(7)
	v_mfma_f32_32x32x16_bf16 v[16:31], v[114:117], v[162:165], v[16:31]
	s_waitcnt lgkmcnt(6)
	v_mfma_f32_32x32x16_bf16 v[48:63], v[114:117], v[166:169], v[48:63]
	v_mfma_f32_32x32x16_bf16 v[0:15], v[118:121], v[162:165], v[0:15]
	v_mfma_f32_32x32x16_bf16 v[32:47], v[118:121], v[166:169], v[32:47]
	global_load_dwordx4 v[114:117], v[80:81], off offset:896
	global_load_dwordx4 v[118:121], v[84:85], off offset:896
	s_waitcnt vmcnt(9)
	ds_write_b128 v100, v[130:133] offset:9216
	s_waitcnt vmcnt(8)
	ds_write_b128 v100, v[134:137] offset:27648
	ds_read_b128 v[130:133], v104 offset:36960
	ds_read_b128 v[134:137], v104 offset:41568
	ds_read_b128 v[162:165], v101 offset:55392
	ds_read_b128 v[166:169], v101 offset:60000
	s_waitcnt lgkmcnt(7)
	v_mfma_f32_32x32x16_bf16 v[16:31], v[122:125], v[154:157], v[16:31]
	s_waitcnt lgkmcnt(6)
	v_mfma_f32_32x32x16_bf16 v[48:63], v[122:125], v[158:161], v[48:63]
	v_mfma_f32_32x32x16_bf16 v[0:15], v[126:129], v[154:157], v[0:15]
	v_mfma_f32_32x32x16_bf16 v[32:47], v[126:129], v[158:161], v[32:47]
	global_load_dwordx4 v[122:125], v[88:89], off offset:896
	global_load_dwordx4 v[126:129], v[92:93], off offset:896
	s_waitcnt vmcnt(9)
	ds_write_b128 v100, v[146:149] offset:13824
	s_waitcnt vmcnt(8)
	ds_write_b128 v100, v[150:153] offset:32256
	s_waitcnt lgkmcnt(3)
	v_mfma_f32_32x32x16_bf16 v[16:31], v[130:133], v[162:165], v[16:31]
	s_waitcnt lgkmcnt(2)
	v_mfma_f32_32x32x16_bf16 v[48:63], v[130:133], v[166:169], v[48:63]
	v_mfma_f32_32x32x16_bf16 v[0:15], v[134:137], v[162:165], v[0:15]
	v_mfma_f32_32x32x16_bf16 v[32:47], v[134:137], v[166:169], v[32:47]
	s_waitcnt lgkmcnt(0)
	s_barrier
	global_load_dwordx4 v[130:133], v[64:65], off offset:1024
	global_load_dwordx4 v[134:137], v[106:107], off offset:1024
	ds_read_b128 v[146:149], v104
	ds_read_b128 v[150:153], v104 offset:4608
	ds_read_b128 v[154:157], v101 offset:18432
	ds_read_b128 v[158:161], v101 offset:23040
	s_waitcnt vmcnt(9)
	ds_write_b128 v100, v[66:69] offset:36864
	s_waitcnt vmcnt(8)
	ds_write_b128 v100, v[110:113] offset:55296
	ds_read_b128 v[66:69], v104 offset:32
	ds_read_b128 v[110:113], v104 offset:4640
	ds_read_b128 v[162:165], v101 offset:18464
	ds_read_b128 v[166:169], v101 offset:23072
	s_waitcnt lgkmcnt(7)
	v_mfma_f32_32x32x16_bf16 v[16:31], v[146:149], v[154:157], v[16:31]
	s_waitcnt lgkmcnt(6)
	v_mfma_f32_32x32x16_bf16 v[48:63], v[146:149], v[158:161], v[48:63]
	v_mfma_f32_32x32x16_bf16 v[0:15], v[150:153], v[154:157], v[0:15]
	v_mfma_f32_32x32x16_bf16 v[32:47], v[150:153], v[158:161], v[32:47]
	global_load_dwordx4 v[146:149], v[72:73], off offset:1024
	global_load_dwordx4 v[150:153], v[76:77], off offset:1024
	s_waitcnt vmcnt(9)
	ds_write_b128 v100, v[138:141] offset:41472
	s_waitcnt vmcnt(8)
	ds_write_b128 v100, v[142:145] offset:59904
	ds_read_b128 v[138:141], v104 offset:64
	ds_read_b128 v[142:145], v104 offset:4672
	ds_read_b128 v[154:157], v101 offset:18496
	ds_read_b128 v[158:161], v101 offset:23104
	s_waitcnt lgkmcnt(7)
	v_mfma_f32_32x32x16_bf16 v[16:31], v[66:69], v[162:165], v[16:31]
	s_waitcnt lgkmcnt(6)
	v_mfma_f32_32x32x16_bf16 v[48:63], v[66:69], v[166:169], v[48:63]
	v_mfma_f32_32x32x16_bf16 v[0:15], v[110:113], v[162:165], v[0:15]
	v_mfma_f32_32x32x16_bf16 v[32:47], v[110:113], v[166:169], v[32:47]
	global_load_dwordx4 v[66:69], v[80:81], off offset:1024
	global_load_dwordx4 v[110:113], v[84:85], off offset:1024
	s_waitcnt vmcnt(9)
	ds_write_b128 v100, v[114:117] offset:46080
	s_waitcnt vmcnt(8)
	ds_write_b128 v100, v[118:121] offset:64512
	ds_read_b128 v[114:117], v104 offset:96
	ds_read_b128 v[118:121], v104 offset:4704
	ds_read_b128 v[162:165], v101 offset:18528
	ds_read_b128 v[166:169], v101 offset:23136
	s_waitcnt lgkmcnt(7)
	v_mfma_f32_32x32x16_bf16 v[16:31], v[138:141], v[154:157], v[16:31]
	s_waitcnt lgkmcnt(6)
	v_mfma_f32_32x32x16_bf16 v[48:63], v[138:141], v[158:161], v[48:63]
	v_mfma_f32_32x32x16_bf16 v[0:15], v[142:145], v[154:157], v[0:15]
	v_mfma_f32_32x32x16_bf16 v[32:47], v[142:145], v[158:161], v[32:47]
	global_load_dwordx4 v[138:141], v[88:89], off offset:1024
	global_load_dwordx4 v[142:145], v[92:93], off offset:1024
	s_waitcnt vmcnt(9)
	ds_write_b128 v100, v[122:125] offset:50688
	s_waitcnt vmcnt(8)
	ds_write_b128 v105, v[126:129] offset:13824
	s_waitcnt lgkmcnt(3)
	v_mfma_f32_32x32x16_bf16 v[16:31], v[114:117], v[162:165], v[16:31]
	s_waitcnt lgkmcnt(2)
	v_mfma_f32_32x32x16_bf16 v[48:63], v[114:117], v[166:169], v[48:63]
	v_mfma_f32_32x32x16_bf16 v[0:15], v[118:121], v[162:165], v[0:15]
	v_mfma_f32_32x32x16_bf16 v[32:47], v[118:121], v[166:169], v[32:47]
	s_waitcnt lgkmcnt(0)
	s_barrier
; __device__ __forceinline__ void gemm_run(int tid, f32x16 (&acc)[2][2], GRegs& g, const GOp& o, int K, unsigned char* smem) {
;     ...
;   for (int k = 0; k < nk; k++) {
;     bf16r* cur = sbuf + (k & 1) * (256 * LDK);
;     bf16r* nxt = sbuf + ((k & 1) ^ 1) * (256 * LDK);
;     const bf16r* As = cur + (wm * 64 + fr) * LDK + fh * 8;
;     const bf16r* Bs = cur + 128 * LDK + (wn * 64 + fr) * LDK + fh * 8;
;     const bool wr = (k + 1 < nk), ld = (k + 2 < nk);
;     bf16x8 fa[2][2], fb[2][2];
;     fa[0][0] = *(const bf16x8*)(As);
;     fa[0][1] = *(const bf16x8*)(As + 32 * LDK);
;     fb[0][0] = *(const bf16x8*)(Bs);
;     fb[0][1] = *(const bf16x8*)(Bs + 32 * LDK);
; #pragma unroll
;     for (int i = 0; i < 4; i++) {
;       if (wr) {
;         *(u32x4*)(nxt + (r0 + i * 32) * LDK + sg * 8) = g.a[i];
;         *(u32x4*)(nxt + 128 * LDK + (r0 + i * 32) * LDK + sg * 8) = g.b[i];
;       }
;       if (ld) {
;         g.a[i] = *(const u32x4*)(Ap + (size_t)i * 32 * o.lda + (k + 2) * 64);
;         g.b[i] = *(const u32x4*)(Bp + o.bs.o[i] + (k + 2) * 64);
;       }
;       if (i < 3) {
;         fa[(i + 1) & 1][0] = *(const bf16x8*)(As + (i + 1) * 16);
;         fa[(i + 1) & 1][1] = *(const bf16x8*)(As + 32 * LDK + (i + 1) * 16);
;         fb[(i + 1) & 1][0] = *(const bf16x8*)(Bs + (i + 1) * 16);
;         fb[(i + 1) & 1][1] = *(const bf16x8*)(Bs + 32 * LDK + (i + 1) * 16);
;       }
;       __builtin_amdgcn_sched_barrier(0);
;       __builtin_amdgcn_s_setprio(1);
;       acc[0][0] = __builtin_amdgcn_mfma_f32_32x32x16_bf16(fa[i & 1][0], fb[i & 1][0], acc[0][0], 0, 0, 0);
;       acc[0][1] = __builtin_amdgcn_mfma_f32_32x32x16_bf16(fa[i & 1][0], fb[i & 1][1], acc[0][1], 0, 0, 0);
;       acc[1][0] = __builtin_amdgcn_mfma_f32_32x32x16_bf16(fa[i & 1][1], fb[i & 1][0], acc[1][0], 0, 0, 0);
;       acc[1][1] = __builtin_amdgcn_mfma_f32_32x32x16_bf16(fa[i & 1][1], fb[i & 1][1], acc[1][1], 0, 0, 0);
;       __builtin_amdgcn_s_setprio(0);
;     }
;     __syncthreads();
;   }
	global_load_dwordx4 v[114:117], v[64:65], off offset:1152
	global_load_dwordx4 v[118:121], v[106:107], off offset:1152
	ds_read_b128 v[122:125], v104 offset:36864
	ds_read_b128 v[126:129], v104 offset:41472
	ds_read_b128 v[154:157], v101 offset:55296
	ds_read_b128 v[158:161], v101 offset:59904
	s_waitcnt vmcnt(9)
	ds_write_b128 v100, v[130:133]
	s_waitcnt vmcnt(8)
	ds_write_b128 v100, v[134:137] offset:18432
	ds_read_b128 v[130:133], v104 offset:36896
	ds_read_b128 v[134:137], v104 offset:41504
	ds_read_b128 v[162:165], v101 offset:55328
	ds_read_b128 v[166:169], v101 offset:59936
	s_waitcnt lgkmcnt(7)
	v_mfma_f32_32x32x16_bf16 v[16:31], v[122:125], v[154:157], v[16:31]
	s_waitcnt lgkmcnt(6)
	v_mfma_f32_32x32x16_bf16 v[48:63], v[122:125], v[158:161], v[48:63]
	v_mfma_f32_32x32x16_bf16 v[0:15], v[126:129], v[154:157], v[0:15]
	v_mfma_f32_32x32x16_bf16 v[32:47], v[126:129], v[158:161], v[32:47]
	global_load_dwordx4 v[122:125], v[72:73], off offset:1152
	global_load_dwordx4 v[126:129], v[76:77], off offset:1152
	s_waitcnt vmcnt(9)
	ds_write_b128 v100, v[146:149] offset:4608
	s_waitcnt vmcnt(8)
	ds_write_b128 v100, v[150:153] offset:23040
	ds_read_b128 v[146:149], v104 offset:36928
	ds_read_b128 v[150:153], v104 offset:41536
	ds_read_b128 v[154:157], v101 offset:55360
	ds_read_b128 v[158:161], v101 offset:59968
	s_waitcnt lgkmcnt(7)
	v_mfma_f32_32x32x16_bf16 v[16:31], v[130:133], v[162:165], v[16:31]
	s_waitcnt lgkmcnt(6)
	v_mfma_f32_32x32x16_bf16 v[48:63], v[130:133], v[166:169], v[48:63]
	v_mfma_f32_32x32x16_bf16 v[0:15], v[134:137], v[162:165], v[0:15]
	v_mfma_f32_32x32x16_bf16 v[32:47], v[134:137], v[166:169], v[32:47]
	global_load_dwordx4 v[130:133], v[80:81], off offset:1152
	global_load_dwordx4 v[134:137], v[84:85], off offset:1152
	s_waitcnt vmcnt(9)
	ds_write_b128 v100, v[66:69] offset:9216
	s_waitcnt vmcnt(8)
	ds_write_b128 v100, v[110:113] offset:27648
	ds_read_b128 v[66:69], v104 offset:36960
	ds_read_b128 v[110:113], v104 offset:41568
	ds_read_b128 v[162:165], v101 offset:55392
	ds_read_b128 v[166:169], v101 offset:60000
	s_waitcnt lgkmcnt(7)
	v_mfma_f32_32x32x16_bf16 v[16:31], v[146:149], v[154:157], v[16:31]
	s_waitcnt lgkmcnt(6)
	v_mfma_f32_32x32x16_bf16 v[48:63], v[146:149], v[158:161], v[48:63]
	v_mfma_f32_32x32x16_bf16 v[0:15], v[150:153], v[154:157], v[0:15]
	v_mfma_f32_32x32x16_bf16 v[32:47], v[150:153], v[158:161], v[32:47]
	global_load_dwordx4 v[146:149], v[88:89], off offset:1152
	global_load_dwordx4 v[150:153], v[92:93], off offset:1152
	s_waitcnt vmcnt(9)
	ds_write_b128 v100, v[138:141] offset:13824
	s_waitcnt vmcnt(8)
	ds_write_b128 v100, v[142:145] offset:32256
	s_waitcnt lgkmcnt(3)
	v_mfma_f32_32x32x16_bf16 v[16:31], v[66:69], v[162:165], v[16:31]
	s_waitcnt lgkmcnt(2)
	v_mfma_f32_32x32x16_bf16 v[48:63], v[66:69], v[166:169], v[48:63]
	v_mfma_f32_32x32x16_bf16 v[0:15], v[110:113], v[162:165], v[0:15]
	v_mfma_f32_32x32x16_bf16 v[32:47], v[110:113], v[166:169], v[32:47]
	s_waitcnt lgkmcnt(0)
	s_barrier
	global_load_dwordx4 v[66:69], v[64:65], off offset:1280
	global_load_dwordx4 v[110:113], v[106:107], off offset:1280
	ds_read_b128 v[138:141], v104
	ds_read_b128 v[142:145], v104 offset:4608
	ds_read_b128 v[154:157], v101 offset:18432
	ds_read_b128 v[158:161], v101 offset:23040
	s_waitcnt vmcnt(9)
	ds_write_b128 v100, v[114:117] offset:36864
	s_waitcnt vmcnt(8)
	ds_write_b128 v100, v[118:121] offset:55296
	ds_read_b128 v[114:117], v104 offset:32
	ds_read_b128 v[118:121], v104 offset:4640
	ds_read_b128 v[162:165], v101 offset:18464
	ds_read_b128 v[166:169], v101 offset:23072
	s_waitcnt lgkmcnt(7)
	v_mfma_f32_32x32x16_bf16 v[16:31], v[138:141], v[154:157], v[16:31]
	s_waitcnt lgkmcnt(6)
	v_mfma_f32_32x32x16_bf16 v[48:63], v[138:141], v[158:161], v[48:63]
	v_mfma_f32_32x32x16_bf16 v[0:15], v[142:145], v[154:157], v[0:15]
	v_mfma_f32_32x32x16_bf16 v[32:47], v[142:145], v[158:161], v[32:47]
	global_load_dwordx4 v[138:141], v[72:73], off offset:1280
	global_load_dwordx4 v[142:145], v[76:77], off offset:1280
	s_waitcnt vmcnt(9)
	ds_write_b128 v100, v[122:125] offset:41472
	s_waitcnt vmcnt(8)
	ds_write_b128 v100, v[126:129] offset:59904
	ds_read_b128 v[122:125], v104 offset:64
	ds_read_b128 v[126:129], v104 offset:4672
	ds_read_b128 v[154:157], v101 offset:18496
	ds_read_b128 v[158:161], v101 offset:23104
	s_waitcnt lgkmcnt(7)
	v_mfma_f32_32x32x16_bf16 v[16:31], v[114:117], v[162:165], v[16:31]
	s_waitcnt lgkmcnt(6)
	v_mfma_f32_32x32x16_bf16 v[48:63], v[114:117], v[166:169], v[48:63]
	v_mfma_f32_32x32x16_bf16 v[0:15], v[118:121], v[162:165], v[0:15]
	v_mfma_f32_32x32x16_bf16 v[32:47], v[118:121], v[166:169], v[32:47]
	global_load_dwordx4 v[114:117], v[80:81], off offset:1280
	global_load_dwordx4 v[118:121], v[84:85], off offset:1280
	s_waitcnt vmcnt(9)
	ds_write_b128 v100, v[130:133] offset:46080
	s_waitcnt vmcnt(8)
	ds_write_b128 v100, v[134:137] offset:64512
	ds_read_b128 v[130:133], v104 offset:96
	ds_read_b128 v[134:137], v104 offset:4704
	ds_read_b128 v[162:165], v101 offset:18528
	ds_read_b128 v[166:169], v101 offset:23136
	s_waitcnt lgkmcnt(7)
	v_mfma_f32_32x32x16_bf16 v[16:31], v[122:125], v[154:157], v[16:31]
	s_waitcnt lgkmcnt(6)
	v_mfma_f32_32x32x16_bf16 v[48:63], v[122:125], v[158:161], v[48:63]
	v_mfma_f32_32x32x16_bf16 v[0:15], v[126:129], v[154:157], v[0:15]
	v_mfma_f32_32x32x16_bf16 v[32:47], v[126:129], v[158:161], v[32:47]
	global_load_dwordx4 v[122:125], v[88:89], off offset:1280
	global_load_dwordx4 v[126:129], v[92:93], off offset:1280
	s_waitcnt vmcnt(9)
	ds_write_b128 v100, v[146:149] offset:50688
	s_waitcnt vmcnt(8)
	ds_write_b128 v105, v[150:153] offset:13824
	s_waitcnt lgkmcnt(3)
	v_mfma_f32_32x32x16_bf16 v[16:31], v[130:133], v[162:165], v[16:31]
	s_waitcnt lgkmcnt(2)
	v_mfma_f32_32x32x16_bf16 v[48:63], v[130:133], v[166:169], v[48:63]
	v_mfma_f32_32x32x16_bf16 v[0:15], v[134:137], v[162:165], v[0:15]
	v_mfma_f32_32x32x16_bf16 v[32:47], v[134:137], v[166:169], v[32:47]
	s_waitcnt lgkmcnt(0)
	s_barrier
; __device__ __forceinline__ void gemm_run(int tid, f32x16 (&acc)[2][2], GRegs& g, const GOp& o, int K, unsigned char* smem) {
;     ...
;   for (int k = 0; k < nk; k++) {
;     bf16r* cur = sbuf + (k & 1) * (256 * LDK);
;     bf16r* nxt = sbuf + ((k & 1) ^ 1) * (256 * LDK);
;     const bf16r* As = cur + (wm * 64 + fr) * LDK + fh * 8;
;     const bf16r* Bs = cur + 128 * LDK + (wn * 64 + fr) * LDK + fh * 8;
;     const bool wr = (k + 1 < nk), ld = (k + 2 < nk);
;     bf16x8 fa[2][2], fb[2][2];
;     fa[0][0] = *(const bf16x8*)(As);
;     fa[0][1] = *(const bf16x8*)(As + 32 * LDK);
;     fb[0][0] = *(const bf16x8*)(Bs);
;     fb[0][1] = *(const bf16x8*)(Bs + 32 * LDK);
; #pragma unroll
;     for (int i = 0; i < 4; i++) {
;       if (wr) {
;         *(u32x4*)(nxt + (r0 + i * 32) * LDK + sg * 8) = g.a[i];
;         *(u32x4*)(nxt + 128 * LDK + (r0 + i * 32) * LDK + sg * 8) = g.b[i];
;       }
;       if (ld) {
;         g.a[i] = *(const u32x4*)(Ap + (size_t)i * 32 * o.lda + (k + 2) * 64);
;         g.b[i] = *(const u32x4*)(Bp + o.bs.o[i] + (k + 2) * 64);
;       }
;       if (i < 3) {
;         fa[(i + 1) & 1][0] = *(const bf16x8*)(As + (i + 1) * 16);
;         fa[(i + 1) & 1][1] = *(const bf16x8*)(As + 32 * LDK + (i + 1) * 16);
;         fb[(i + 1) & 1][0] = *(const bf16x8*)(Bs + (i + 1) * 16);
;         fb[(i + 1) & 1][1] = *(const bf16x8*)(Bs + 32 * LDK + (i + 1) * 16);
;       }
;       __builtin_amdgcn_sched_barrier(0);
;       __builtin_amdgcn_s_setprio(1);
;       acc[0][0] = __builtin_amdgcn_mfma_f32_32x32x16_bf16(fa[i & 1][0], fb[i & 1][0], acc[0][0], 0, 0, 0);
;       acc[0][1] = __builtin_amdgcn_mfma_f32_32x32x16_bf16(fa[i & 1][0], fb[i & 1][1], acc[0][1], 0, 0, 0);
;       acc[1][0] = __builtin_amdgcn_mfma_f32_32x32x16_bf16(fa[i & 1][1], fb[i & 1][0], acc[1][0], 0, 0, 0);
;       acc[1][1] = __builtin_amdgcn_mfma_f32_32x32x16_bf16(fa[i & 1][1], fb[i & 1][1], acc[1][1], 0, 0, 0);
;       __builtin_amdgcn_s_setprio(0);
;     }
;     __syncthreads();
;   }
	global_load_dwordx4 v[130:133], v[64:65], off offset:1408
	global_load_dwordx4 v[134:137], v[106:107], off offset:1408
	ds_read_b128 v[146:149], v104 offset:36864
	ds_read_b128 v[150:153], v104 offset:41472
	ds_read_b128 v[154:157], v101 offset:55296
	ds_read_b128 v[158:161], v101 offset:59904
	s_waitcnt vmcnt(9)
	ds_write_b128 v100, v[66:69]
	s_waitcnt vmcnt(8)
	ds_write_b128 v100, v[110:113] offset:18432
	ds_read_b128 v[66:69], v104 offset:36896
	ds_read_b128 v[110:113], v104 offset:41504
	ds_read_b128 v[162:165], v101 offset:55328
	ds_read_b128 v[166:169], v101 offset:59936
	s_waitcnt lgkmcnt(7)
	v_mfma_f32_32x32x16_bf16 v[16:31], v[146:149], v[154:157], v[16:31]
	s_waitcnt lgkmcnt(6)
	v_mfma_f32_32x32x16_bf16 v[48:63], v[146:149], v[158:161], v[48:63]
	v_mfma_f32_32x32x16_bf16 v[0:15], v[150:153], v[154:157], v[0:15]
	v_mfma_f32_32x32x16_bf16 v[32:47], v[150:153], v[158:161], v[32:47]
	global_load_dwordx4 v[146:149], v[72:73], off offset:1408
	global_load_dwordx4 v[150:153], v[76:77], off offset:1408
	s_waitcnt vmcnt(9)
	ds_write_b128 v100, v[138:141] offset:4608
	s_waitcnt vmcnt(8)
	ds_write_b128 v100, v[142:145] offset:23040
	ds_read_b128 v[138:141], v104 offset:36928
	ds_read_b128 v[142:145], v104 offset:41536
	ds_read_b128 v[154:157], v101 offset:55360
	ds_read_b128 v[158:161], v101 offset:59968
	s_waitcnt lgkmcnt(7)
	v_mfma_f32_32x32x16_bf16 v[16:31], v[66:69], v[162:165], v[16:31]
	s_waitcnt lgkmcnt(6)
	v_mfma_f32_32x32x16_bf16 v[48:63], v[66:69], v[166:169], v[48:63]
	v_mfma_f32_32x32x16_bf16 v[0:15], v[110:113], v[162:165], v[0:15]
	v_mfma_f32_32x32x16_bf16 v[32:47], v[110:113], v[166:169], v[32:47]
	global_load_dwordx4 v[66:69], v[80:81], off offset:1408
	global_load_dwordx4 v[110:113], v[84:85], off offset:1408
	s_waitcnt vmcnt(9)
	ds_write_b128 v100, v[114:117] offset:9216
	s_waitcnt vmcnt(8)
	ds_write_b128 v100, v[118:121] offset:27648
	ds_read_b128 v[114:117], v104 offset:36960
	ds_read_b128 v[118:121], v104 offset:41568
	ds_read_b128 v[162:165], v101 offset:55392
	ds_read_b128 v[166:169], v101 offset:60000
	s_waitcnt lgkmcnt(7)
	v_mfma_f32_32x32x16_bf16 v[16:31], v[138:141], v[154:157], v[16:31]
	s_waitcnt lgkmcnt(6)
	v_mfma_f32_32x32x16_bf16 v[48:63], v[138:141], v[158:161], v[48:63]
	v_mfma_f32_32x32x16_bf16 v[0:15], v[142:145], v[154:157], v[0:15]
	v_mfma_f32_32x32x16_bf16 v[32:47], v[142:145], v[158:161], v[32:47]
	global_load_dwordx4 v[138:141], v[88:89], off offset:1408
	global_load_dwordx4 v[142:145], v[92:93], off offset:1408
	s_waitcnt vmcnt(9)
	ds_write_b128 v100, v[122:125] offset:13824
	s_waitcnt vmcnt(8)
	ds_write_b128 v100, v[126:129] offset:32256
	s_waitcnt lgkmcnt(3)
	v_mfma_f32_32x32x16_bf16 v[16:31], v[114:117], v[162:165], v[16:31]
	s_waitcnt lgkmcnt(2)
	v_mfma_f32_32x32x16_bf16 v[48:63], v[114:117], v[166:169], v[48:63]
	v_mfma_f32_32x32x16_bf16 v[0:15], v[118:121], v[162:165], v[0:15]
	v_mfma_f32_32x32x16_bf16 v[32:47], v[118:121], v[166:169], v[32:47]
	s_waitcnt lgkmcnt(0)
	s_barrier
	global_load_dwordx4 v[114:117], v[64:65], off offset:1536
	global_load_dwordx4 v[118:121], v[106:107], off offset:1536
	ds_read_b128 v[122:125], v104
	ds_read_b128 v[126:129], v104 offset:4608
	ds_read_b128 v[154:157], v101 offset:18432
	ds_read_b128 v[158:161], v101 offset:23040
	s_waitcnt vmcnt(9)
	ds_write_b128 v100, v[130:133] offset:36864
	s_waitcnt vmcnt(8)
	ds_write_b128 v100, v[134:137] offset:55296
	ds_read_b128 v[130:133], v104 offset:32
	ds_read_b128 v[134:137], v104 offset:4640
	ds_read_b128 v[162:165], v101 offset:18464
	ds_read_b128 v[166:169], v101 offset:23072
	s_waitcnt lgkmcnt(7)
	v_mfma_f32_32x32x16_bf16 v[16:31], v[122:125], v[154:157], v[16:31]
	s_waitcnt lgkmcnt(6)
	v_mfma_f32_32x32x16_bf16 v[48:63], v[122:125], v[158:161], v[48:63]
	v_mfma_f32_32x32x16_bf16 v[0:15], v[126:129], v[154:157], v[0:15]
	v_mfma_f32_32x32x16_bf16 v[32:47], v[126:129], v[158:161], v[32:47]
	global_load_dwordx4 v[122:125], v[72:73], off offset:1536
	global_load_dwordx4 v[126:129], v[76:77], off offset:1536
	s_waitcnt vmcnt(9)
	ds_write_b128 v100, v[146:149] offset:41472
	s_waitcnt vmcnt(8)
	ds_write_b128 v100, v[150:153] offset:59904
	ds_read_b128 v[146:149], v104 offset:64
	ds_read_b128 v[150:153], v104 offset:4672
	ds_read_b128 v[154:157], v101 offset:18496
	ds_read_b128 v[158:161], v101 offset:23104
	s_waitcnt lgkmcnt(7)
	v_mfma_f32_32x32x16_bf16 v[16:31], v[130:133], v[162:165], v[16:31]
	s_waitcnt lgkmcnt(6)
	v_mfma_f32_32x32x16_bf16 v[48:63], v[130:133], v[166:169], v[48:63]
	v_mfma_f32_32x32x16_bf16 v[0:15], v[134:137], v[162:165], v[0:15]
	v_mfma_f32_32x32x16_bf16 v[32:47], v[134:137], v[166:169], v[32:47]
	global_load_dwordx4 v[130:133], v[80:81], off offset:1536
	global_load_dwordx4 v[134:137], v[84:85], off offset:1536
	s_waitcnt vmcnt(9)
	ds_write_b128 v100, v[66:69] offset:46080
	s_waitcnt vmcnt(8)
	ds_write_b128 v100, v[110:113] offset:64512
	ds_read_b128 v[66:69], v104 offset:96
	ds_read_b128 v[110:113], v104 offset:4704
	ds_read_b128 v[162:165], v101 offset:18528
	ds_read_b128 v[166:169], v101 offset:23136
	s_waitcnt lgkmcnt(7)
	v_mfma_f32_32x32x16_bf16 v[16:31], v[146:149], v[154:157], v[16:31]
	s_waitcnt lgkmcnt(6)
	v_mfma_f32_32x32x16_bf16 v[48:63], v[146:149], v[158:161], v[48:63]
	v_mfma_f32_32x32x16_bf16 v[0:15], v[150:153], v[154:157], v[0:15]
	v_mfma_f32_32x32x16_bf16 v[32:47], v[150:153], v[158:161], v[32:47]
	global_load_dwordx4 v[146:149], v[88:89], off offset:1536
	global_load_dwordx4 v[150:153], v[92:93], off offset:1536
	s_waitcnt vmcnt(9)
	ds_write_b128 v100, v[138:141] offset:50688
	s_waitcnt vmcnt(8)
	ds_write_b128 v105, v[142:145] offset:13824
	s_waitcnt lgkmcnt(3)
	v_mfma_f32_32x32x16_bf16 v[16:31], v[66:69], v[162:165], v[16:31]
	s_waitcnt lgkmcnt(2)
	v_mfma_f32_32x32x16_bf16 v[48:63], v[66:69], v[166:169], v[48:63]
	v_mfma_f32_32x32x16_bf16 v[0:15], v[110:113], v[162:165], v[0:15]
	v_mfma_f32_32x32x16_bf16 v[32:47], v[110:113], v[166:169], v[32:47]
	s_waitcnt lgkmcnt(0)
	s_barrier
; __device__ __forceinline__ void gemm_run(int tid, f32x16 (&acc)[2][2], GRegs& g, const GOp& o, int K, unsigned char* smem) {
;     ...
;   for (int k = 0; k < nk; k++) {
;     bf16r* cur = sbuf + (k & 1) * (256 * LDK);
;     bf16r* nxt = sbuf + ((k & 1) ^ 1) * (256 * LDK);
;     const bf16r* As = cur + (wm * 64 + fr) * LDK + fh * 8;
;     const bf16r* Bs = cur + 128 * LDK + (wn * 64 + fr) * LDK + fh * 8;
;     const bool wr = (k + 1 < nk), ld = (k + 2 < nk);
;     bf16x8 fa[2][2], fb[2][2];
;     fa[0][0] = *(const bf16x8*)(As);
;     fa[0][1] = *(const bf16x8*)(As + 32 * LDK);
;     fb[0][0] = *(const bf16x8*)(Bs);
;     fb[0][1] = *(const bf16x8*)(Bs + 32 * LDK);
; #pragma unroll
;     for (int i = 0; i < 4; i++) {
;       if (wr) {
;         *(u32x4*)(nxt + (r0 + i * 32) * LDK + sg * 8) = g.a[i];
;         *(u32x4*)(nxt + 128 * LDK + (r0 + i * 32) * LDK + sg * 8) = g.b[i];
;       }
;       if (ld) {
;         g.a[i] = *(const u32x4*)(Ap + (size_t)i * 32 * o.lda + (k + 2) * 64);
;         g.b[i] = *(const u32x4*)(Bp + o.bs.o[i] + (k + 2) * 64);
;       }
;       if (i < 3) {
;         fa[(i + 1) & 1][0] = *(const bf16x8*)(As + (i + 1) * 16);
;         fa[(i + 1) & 1][1] = *(const bf16x8*)(As + 32 * LDK + (i + 1) * 16);
;         fb[(i + 1) & 1][0] = *(const bf16x8*)(Bs + (i + 1) * 16);
;         fb[(i + 1) & 1][1] = *(const bf16x8*)(Bs + 32 * LDK + (i + 1) * 16);
;       }
;       __builtin_amdgcn_sched_barrier(0);
;       __builtin_amdgcn_s_setprio(1);
;       acc[0][0] = __builtin_amdgcn_mfma_f32_32x32x16_bf16(fa[i & 1][0], fb[i & 1][0], acc[0][0], 0, 0, 0);
;       acc[0][1] = __builtin_amdgcn_mfma_f32_32x32x16_bf16(fa[i & 1][0], fb[i & 1][1], acc[0][1], 0, 0, 0);
;       acc[1][0] = __builtin_amdgcn_mfma_f32_32x32x16_bf16(fa[i & 1][1], fb[i & 1][0], acc[1][0], 0, 0, 0);
;       acc[1][1] = __builtin_amdgcn_mfma_f32_32x32x16_bf16(fa[i & 1][1], fb[i & 1][1], acc[1][1], 0, 0, 0);
;       __builtin_amdgcn_s_setprio(0);
;     }
;     __syncthreads();
;   }
	global_load_dwordx4 v[66:69], v[64:65], off offset:1664
	global_load_dwordx4 v[110:113], v[106:107], off offset:1664
	ds_read_b128 v[138:141], v104 offset:36864
	ds_read_b128 v[142:145], v104 offset:41472
	ds_read_b128 v[154:157], v101 offset:55296
	ds_read_b128 v[158:161], v101 offset:59904
	s_waitcnt vmcnt(9)
	ds_write_b128 v100, v[114:117]
	s_waitcnt vmcnt(8)
	ds_write_b128 v100, v[118:121] offset:18432
	ds_read_b128 v[114:117], v104 offset:36896
	ds_read_b128 v[118:121], v104 offset:41504
	ds_read_b128 v[162:165], v101 offset:55328
	ds_read_b128 v[166:169], v101 offset:59936
	s_waitcnt lgkmcnt(7)
	v_mfma_f32_32x32x16_bf16 v[16:31], v[138:141], v[154:157], v[16:31]
	s_waitcnt lgkmcnt(6)
	v_mfma_f32_32x32x16_bf16 v[48:63], v[138:141], v[158:161], v[48:63]
	v_mfma_f32_32x32x16_bf16 v[0:15], v[142:145], v[154:157], v[0:15]
	v_mfma_f32_32x32x16_bf16 v[32:47], v[142:145], v[158:161], v[32:47]
	global_load_dwordx4 v[138:141], v[72:73], off offset:1664
	global_load_dwordx4 v[142:145], v[76:77], off offset:1664
	s_waitcnt vmcnt(9)
	ds_write_b128 v100, v[122:125] offset:4608
	s_waitcnt vmcnt(8)
	ds_write_b128 v100, v[126:129] offset:23040
	ds_read_b128 v[122:125], v104 offset:36928
	ds_read_b128 v[126:129], v104 offset:41536
	ds_read_b128 v[154:157], v101 offset:55360
	ds_read_b128 v[158:161], v101 offset:59968
	s_waitcnt lgkmcnt(7)
	v_mfma_f32_32x32x16_bf16 v[16:31], v[114:117], v[162:165], v[16:31]
	s_waitcnt lgkmcnt(6)
	v_mfma_f32_32x32x16_bf16 v[48:63], v[114:117], v[166:169], v[48:63]
	v_mfma_f32_32x32x16_bf16 v[0:15], v[118:121], v[162:165], v[0:15]
	v_mfma_f32_32x32x16_bf16 v[32:47], v[118:121], v[166:169], v[32:47]
	global_load_dwordx4 v[114:117], v[80:81], off offset:1664
	global_load_dwordx4 v[118:121], v[84:85], off offset:1664
	s_waitcnt vmcnt(9)
	ds_write_b128 v100, v[130:133] offset:9216
	s_waitcnt vmcnt(8)
	ds_write_b128 v100, v[134:137] offset:27648
	ds_read_b128 v[130:133], v104 offset:36960
	ds_read_b128 v[134:137], v104 offset:41568
	ds_read_b128 v[162:165], v101 offset:55392
	ds_read_b128 v[166:169], v101 offset:60000
	s_waitcnt lgkmcnt(7)
	v_mfma_f32_32x32x16_bf16 v[16:31], v[122:125], v[154:157], v[16:31]
	s_waitcnt lgkmcnt(6)
	v_mfma_f32_32x32x16_bf16 v[48:63], v[122:125], v[158:161], v[48:63]
	v_mfma_f32_32x32x16_bf16 v[0:15], v[126:129], v[154:157], v[0:15]
	v_mfma_f32_32x32x16_bf16 v[32:47], v[126:129], v[158:161], v[32:47]
	global_load_dwordx4 v[122:125], v[88:89], off offset:1664
	global_load_dwordx4 v[126:129], v[92:93], off offset:1664
	s_waitcnt vmcnt(9)
	ds_write_b128 v100, v[146:149] offset:13824
	s_waitcnt vmcnt(8)
	ds_write_b128 v100, v[150:153] offset:32256
	s_waitcnt lgkmcnt(3)
	v_mfma_f32_32x32x16_bf16 v[16:31], v[130:133], v[162:165], v[16:31]
	s_waitcnt lgkmcnt(2)
	v_mfma_f32_32x32x16_bf16 v[48:63], v[130:133], v[166:169], v[48:63]
	v_mfma_f32_32x32x16_bf16 v[0:15], v[134:137], v[162:165], v[0:15]
	v_mfma_f32_32x32x16_bf16 v[32:47], v[134:137], v[166:169], v[32:47]
	s_waitcnt lgkmcnt(0)
	s_barrier
	global_load_dwordx4 v[130:133], v[64:65], off offset:1792
	global_load_dwordx4 v[134:137], v[106:107], off offset:1792
	ds_read_b128 v[146:149], v104
	ds_read_b128 v[150:153], v104 offset:4608
	ds_read_b128 v[154:157], v101 offset:18432
	ds_read_b128 v[158:161], v101 offset:23040
	s_waitcnt vmcnt(9)
	ds_write_b128 v100, v[66:69] offset:36864
	s_waitcnt vmcnt(8)
	ds_write_b128 v100, v[110:113] offset:55296
	ds_read_b128 v[66:69], v104 offset:32
	ds_read_b128 v[110:113], v104 offset:4640
	ds_read_b128 v[162:165], v101 offset:18464
	ds_read_b128 v[166:169], v101 offset:23072
	s_waitcnt lgkmcnt(7)
	v_mfma_f32_32x32x16_bf16 v[16:31], v[146:149], v[154:157], v[16:31]
	s_waitcnt lgkmcnt(6)
	v_mfma_f32_32x32x16_bf16 v[48:63], v[146:149], v[158:161], v[48:63]
	v_mfma_f32_32x32x16_bf16 v[0:15], v[150:153], v[154:157], v[0:15]
	v_mfma_f32_32x32x16_bf16 v[32:47], v[150:153], v[158:161], v[32:47]
	global_load_dwordx4 v[146:149], v[72:73], off offset:1792
	global_load_dwordx4 v[150:153], v[76:77], off offset:1792
	s_waitcnt vmcnt(9)
	ds_write_b128 v100, v[138:141] offset:41472
	s_waitcnt vmcnt(8)
	ds_write_b128 v100, v[142:145] offset:59904
	ds_read_b128 v[138:141], v104 offset:64
	ds_read_b128 v[142:145], v104 offset:4672
	ds_read_b128 v[154:157], v101 offset:18496
	ds_read_b128 v[158:161], v101 offset:23104
	s_waitcnt lgkmcnt(7)
	v_mfma_f32_32x32x16_bf16 v[16:31], v[66:69], v[162:165], v[16:31]
	s_waitcnt lgkmcnt(6)
	v_mfma_f32_32x32x16_bf16 v[48:63], v[66:69], v[166:169], v[48:63]
	v_mfma_f32_32x32x16_bf16 v[0:15], v[110:113], v[162:165], v[0:15]
	v_mfma_f32_32x32x16_bf16 v[32:47], v[110:113], v[166:169], v[32:47]
	global_load_dwordx4 v[110:113], v[80:81], off offset:1792
	global_load_dwordx4 v[162:165], v[84:85], off offset:1792
	s_waitcnt vmcnt(9)
	ds_write_b128 v100, v[114:117] offset:46080
	s_waitcnt vmcnt(8)
	ds_write_b128 v100, v[118:121] offset:64512
	ds_read_b128 v[66:69], v104 offset:96
	ds_read_b128 v[114:117], v104 offset:4704
	ds_read_b128 v[118:121], v101 offset:18528
	ds_read_b128 v[166:169], v101 offset:23136
	s_waitcnt lgkmcnt(7)
	v_mfma_f32_32x32x16_bf16 v[16:31], v[138:141], v[154:157], v[16:31]
	s_waitcnt lgkmcnt(6)
	v_mfma_f32_32x32x16_bf16 v[48:63], v[138:141], v[158:161], v[48:63]
	v_mfma_f32_32x32x16_bf16 v[0:15], v[142:145], v[154:157], v[0:15]
	v_mfma_f32_32x32x16_bf16 v[32:47], v[142:145], v[158:161], v[32:47]
	global_load_dwordx4 v[138:141], v[88:89], off offset:1792
	global_load_dwordx4 v[142:145], v[92:93], off offset:1792
	s_waitcnt vmcnt(9)
	ds_write_b128 v100, v[122:125] offset:50688
	s_waitcnt vmcnt(8)
	ds_write_b128 v105, v[126:129] offset:13824
	s_waitcnt lgkmcnt(3)
	v_mfma_f32_32x32x16_bf16 v[16:31], v[66:69], v[118:121], v[16:31]
	s_waitcnt lgkmcnt(2)
	v_mfma_f32_32x32x16_bf16 v[48:63], v[66:69], v[166:169], v[48:63]
	v_mfma_f32_32x32x16_bf16 v[0:15], v[114:117], v[118:121], v[0:15]
	v_mfma_f32_32x32x16_bf16 v[32:47], v[114:117], v[166:169], v[32:47]
	s_waitcnt lgkmcnt(0)
	s_barrier
; __device__ __forceinline__ void gemm_run(int tid, f32x16 (&acc)[2][2], GRegs& g, const GOp& o, int K, unsigned char* smem) {
;     ...
;   for (int k = 0; k < nk; k++) {
;     bf16r* cur = sbuf + (k & 1) * (256 * LDK);
;     bf16r* nxt = sbuf + ((k & 1) ^ 1) * (256 * LDK);
;     const bf16r* As = cur + (wm * 64 + fr) * LDK + fh * 8;
;     const bf16r* Bs = cur + 128 * LDK + (wn * 64 + fr) * LDK + fh * 8;
;     const bool wr = (k + 1 < nk), ld = (k + 2 < nk);
;     bf16x8 fa[2][2], fb[2][2];
;     fa[0][0] = *(const bf16x8*)(As);
;     fa[0][1] = *(const bf16x8*)(As + 32 * LDK);
;     fb[0][0] = *(const bf16x8*)(Bs);
;     fb[0][1] = *(const bf16x8*)(Bs + 32 * LDK);
; #pragma unroll
;     for (int i = 0; i < 4; i++) {
;       if (wr) {
;         *(u32x4*)(nxt + (r0 + i * 32) * LDK + sg * 8) = g.a[i];
;         *(u32x4*)(nxt + 128 * LDK + (r0 + i * 32) * LDK + sg * 8) = g.b[i];
;       }
;       if (ld) {
;         g.a[i] = *(const u32x4*)(Ap + (size_t)i * 32 * o.lda + (k + 2) * 64);
;         g.b[i] = *(const u32x4*)(Bp + o.bs.o[i] + (k + 2) * 64);
;       }
;       if (i < 3) {
;         fa[(i + 1) & 1][0] = *(const bf16x8*)(As + (i + 1) * 16);
;         fa[(i + 1) & 1][1] = *(const bf16x8*)(As + 32 * LDK + (i + 1) * 16);
;         fb[(i + 1) & 1][0] = *(const bf16x8*)(Bs + (i + 1) * 16);
;         fb[(i + 1) & 1][1] = *(const bf16x8*)(Bs + 32 * LDK + (i + 1) * 16);
;       }
;       __builtin_amdgcn_sched_barrier(0);
;       __builtin_amdgcn_s_setprio(1);
;       acc[0][0] = __builtin_amdgcn_mfma_f32_32x32x16_bf16(fa[i & 1][0], fb[i & 1][0], acc[0][0], 0, 0, 0);
;       acc[0][1] = __builtin_amdgcn_mfma_f32_32x32x16_bf16(fa[i & 1][0], fb[i & 1][1], acc[0][1], 0, 0, 0);
;       acc[1][0] = __builtin_amdgcn_mfma_f32_32x32x16_bf16(fa[i & 1][1], fb[i & 1][0], acc[1][0], 0, 0, 0);
;       acc[1][1] = __builtin_amdgcn_mfma_f32_32x32x16_bf16(fa[i & 1][1], fb[i & 1][1], acc[1][1], 0, 0, 0);
;       __builtin_amdgcn_s_setprio(0);
;     }
;     __syncthreads();
;   }
	global_load_dwordx4 v[64:67], v[64:65], off offset:1920
	s_nop 0
	global_load_dwordx4 v[68:71], v[106:107], off offset:1920
	ds_read_b128 v[114:117], v104 offset:36864
	ds_read_b128 v[118:121], v104 offset:41472
	ds_read_b128 v[122:125], v101 offset:55296
	ds_read_b128 v[126:129], v101 offset:59904
	s_waitcnt vmcnt(9)
	ds_write_b128 v100, v[130:133]
	s_waitcnt vmcnt(8)
	ds_write_b128 v100, v[134:137] offset:18432
	ds_read_b128 v[130:133], v104 offset:36896
	ds_read_b128 v[134:137], v104 offset:41504
	ds_read_b128 v[154:157], v101 offset:55328
	ds_read_b128 v[158:161], v101 offset:59936
	s_waitcnt lgkmcnt(7)
	v_mfma_f32_32x32x16_bf16 v[16:31], v[114:117], v[122:125], v[16:31]
	s_waitcnt lgkmcnt(6)
	v_mfma_f32_32x32x16_bf16 v[48:63], v[114:117], v[126:129], v[48:63]
	v_mfma_f32_32x32x16_bf16 v[0:15], v[118:121], v[122:125], v[0:15]
	v_mfma_f32_32x32x16_bf16 v[32:47], v[118:121], v[126:129], v[32:47]
	global_load_dwordx4 v[72:75], v[72:73], off offset:1920
	s_nop 0
	global_load_dwordx4 v[76:79], v[76:77], off offset:1920
	s_waitcnt vmcnt(9)
	ds_write_b128 v100, v[146:149] offset:4608
	s_waitcnt vmcnt(8)
	ds_write_b128 v100, v[150:153] offset:23040
	ds_read_b128 v[114:117], v104 offset:36928
	ds_read_b128 v[118:121], v104 offset:41536
	ds_read_b128 v[122:125], v101 offset:55360
	ds_read_b128 v[126:129], v101 offset:59968
	s_waitcnt lgkmcnt(7)
	v_mfma_f32_32x32x16_bf16 v[16:31], v[130:133], v[154:157], v[16:31]
	s_waitcnt lgkmcnt(6)
	v_mfma_f32_32x32x16_bf16 v[48:63], v[130:133], v[158:161], v[48:63]
	v_mfma_f32_32x32x16_bf16 v[0:15], v[134:137], v[154:157], v[0:15]
	v_mfma_f32_32x32x16_bf16 v[32:47], v[134:137], v[158:161], v[32:47]
	global_load_dwordx4 v[80:83], v[80:81], off offset:1920
	s_nop 0
	global_load_dwordx4 v[84:87], v[84:85], off offset:1920
	s_waitcnt vmcnt(9)
	ds_write_b128 v100, v[110:113] offset:9216
	s_waitcnt vmcnt(8)
	ds_write_b128 v100, v[162:165] offset:27648
	ds_read_b128 v[110:113], v104 offset:36960
	ds_read_b128 v[130:133], v104 offset:41568
	ds_read_b128 v[134:137], v101 offset:55392
	ds_read_b128 v[146:149], v101 offset:60000
	s_waitcnt lgkmcnt(7)
	v_mfma_f32_32x32x16_bf16 v[16:31], v[114:117], v[122:125], v[16:31]
	s_waitcnt lgkmcnt(6)
	v_mfma_f32_32x32x16_bf16 v[48:63], v[114:117], v[126:129], v[48:63]
	v_mfma_f32_32x32x16_bf16 v[0:15], v[118:121], v[122:125], v[0:15]
	v_mfma_f32_32x32x16_bf16 v[32:47], v[118:121], v[126:129], v[32:47]
	global_load_dwordx4 v[88:91], v[88:89], off offset:1920
	s_nop 0
	global_load_dwordx4 v[92:95], v[92:93], off offset:1920
	s_waitcnt vmcnt(9)
	ds_write_b128 v100, v[138:141] offset:13824
	s_waitcnt vmcnt(8)
	ds_write_b128 v100, v[142:145] offset:32256
	s_waitcnt lgkmcnt(3)
	v_mfma_f32_32x32x16_bf16 v[16:31], v[110:113], v[134:137], v[16:31]
	s_waitcnt lgkmcnt(2)
	v_mfma_f32_32x32x16_bf16 v[48:63], v[110:113], v[146:149], v[48:63]
	v_mfma_f32_32x32x16_bf16 v[0:15], v[130:133], v[134:137], v[0:15]
	v_mfma_f32_32x32x16_bf16 v[32:47], v[130:133], v[146:149], v[32:47]
	s_waitcnt lgkmcnt(0)
	s_barrier
; __device__ __forceinline__ void gemm_run(int tid, f32x16 (&acc)[2][2], GRegs& g, const GOp& o, int K, unsigned char* smem) {
;     ...
;     fa[0][0] = *(const bf16x8*)(As);
;     fa[0][1] = *(const bf16x8*)(As + 32 * LDK);
;     fb[0][0] = *(const bf16x8*)(Bs);
;     fb[0][1] = *(const bf16x8*)(Bs + 32 * LDK);
; #pragma unroll
;     for (int i = 0; i < 4; i++) {
;       if (wr) {
;         *(u32x4*)(nxt + (r0 + i * 32) * LDK + sg * 8) = g.a[i];
;         *(u32x4*)(nxt + 128 * LDK + (r0 + i * 32) * LDK + sg * 8) = g.b[i];
;       }
;       if (ld) {
;         g.a[i] = *(const u32x4*)(Ap + (size_t)i * 32 * o.lda + (k + 2) * 64);
;         g.b[i] = *(const u32x4*)(Bp + o.bs.o[i] + (k + 2) * 64);
;       }
;       if (i < 3) {
;         fa[(i + 1) & 1][0] = *(const bf16x8*)(As + (i + 1) * 16);
;         fa[(i + 1) & 1][1] = *(const bf16x8*)(As + 32 * LDK + (i + 1) * 16);
;         fb[(i + 1) & 1][0] = *(const bf16x8*)(Bs + (i + 1) * 16);
;         fb[(i + 1) & 1][1] = *(const bf16x8*)(Bs + 32 * LDK + (i + 1) * 16);
;       }
;       __builtin_amdgcn_sched_barrier(0);
;       __builtin_amdgcn_s_setprio(1);
;       acc[0][0] = __builtin_amdgcn_mfma_f32_32x32x16_bf16(fa[i & 1][0], fb[i & 1][0], acc[0][0], 0, 0, 0);
;       acc[0][1] = __builtin_amdgcn_mfma_f32_32x32x16_bf16(fa[i & 1][0], fb[i & 1][1], acc[0][1], 0, 0, 0);
;       acc[1][0] = __builtin_amdgcn_mfma_f32_32x32x16_bf16(fa[i & 1][1], fb[i & 1][0], acc[1][0], 0, 0, 0);
;       acc[1][1] = __builtin_amdgcn_mfma_f32_32x32x16_bf16(fa[i & 1][1], fb[i & 1][1], acc[1][1], 0, 0, 0);
;       __builtin_amdgcn_s_setprio(0);
;     }
;     __syncthreads();
;   }
; __device__ __forceinline__ bool tile_map(int it, int nn, int& mt, int& nt) {
;   const int xcd = blockIdx.x & 7, li = blockIdx.x >> 3, nb = gridDim.x >> 3;
;   int q = it * nb + li;
;   const int per = 16 * nn;
;   if (q < per) {
;     int sub = q / (8 * nn), r = q - sub * (8 * nn);
;     nt = r >> 3;
;     mt = xcd * 16 + sub * 8 + (r & 7);
;     return true;
;   }
;   q -= per;
;   int n = q * 8 + xcd;
;   if (n < nn) { mt = 128; nt = n; return true; }
	ds_read_b128 v[110:113], v104
	ds_read_b128 v[114:117], v104 offset:4608
	ds_read_b128 v[118:121], v101 offset:18432
	ds_read_b128 v[122:125], v101 offset:23040
	s_waitcnt vmcnt(7)
	ds_write_b128 v100, v[64:67] offset:36864
	s_waitcnt vmcnt(6)
	ds_write_b128 v100, v[68:71] offset:55296
	ds_read_b128 v[126:129], v104 offset:32
	ds_read_b128 v[130:133], v104 offset:4640
	ds_read_b128 v[134:137], v101 offset:18464
	ds_read_b128 v[138:141], v101 offset:23072
	s_waitcnt lgkmcnt(7)
	v_mfma_f32_32x32x16_bf16 v[16:31], v[110:113], v[118:121], v[16:31]
	s_waitcnt lgkmcnt(6)
	v_mfma_f32_32x32x16_bf16 v[48:63], v[110:113], v[122:125], v[48:63]
	v_mfma_f32_32x32x16_bf16 v[0:15], v[114:117], v[118:121], v[0:15]
	v_mfma_f32_32x32x16_bf16 v[32:47], v[114:117], v[122:125], v[32:47]
	s_waitcnt vmcnt(5)
	ds_write_b128 v100, v[72:75] offset:41472
	s_waitcnt vmcnt(4)
	ds_write_b128 v100, v[76:79] offset:59904
	ds_read_b128 v[110:113], v104 offset:64
	ds_read_b128 v[114:117], v104 offset:4672
	ds_read_b128 v[118:121], v101 offset:18496
	ds_read_b128 v[122:125], v101 offset:23104
	s_waitcnt lgkmcnt(7)
	v_mfma_f32_32x32x16_bf16 v[16:31], v[126:129], v[134:137], v[16:31]
	s_waitcnt lgkmcnt(6)
	v_mfma_f32_32x32x16_bf16 v[48:63], v[126:129], v[138:141], v[48:63]
	v_mfma_f32_32x32x16_bf16 v[0:15], v[130:133], v[134:137], v[0:15]
	v_mfma_f32_32x32x16_bf16 v[32:47], v[130:133], v[138:141], v[32:47]
	s_waitcnt vmcnt(3)
	ds_write_b128 v100, v[80:83] offset:46080
	s_waitcnt vmcnt(2)
	ds_write_b128 v100, v[84:87] offset:64512
	ds_read_b128 v[126:129], v104 offset:96
	ds_read_b128 v[130:133], v104 offset:4704
	ds_read_b128 v[134:137], v101 offset:18528
	ds_read_b128 v[138:141], v101 offset:23136
	s_waitcnt lgkmcnt(7)
	v_mfma_f32_32x32x16_bf16 v[16:31], v[110:113], v[118:121], v[16:31]
	s_waitcnt lgkmcnt(6)
	v_mfma_f32_32x32x16_bf16 v[48:63], v[110:113], v[122:125], v[48:63]
	v_mfma_f32_32x32x16_bf16 v[0:15], v[114:117], v[118:121], v[0:15]
	v_mfma_f32_32x32x16_bf16 v[32:47], v[114:117], v[122:125], v[32:47]
	s_waitcnt vmcnt(1)
	ds_write_b128 v100, v[88:91] offset:50688
	s_waitcnt vmcnt(0)
	ds_write_b128 v105, v[92:95] offset:13824
	s_waitcnt lgkmcnt(3)
	v_mfma_f32_32x32x16_bf16 v[16:31], v[126:129], v[134:137], v[16:31]
	s_waitcnt lgkmcnt(2)
	v_mfma_f32_32x32x16_bf16 v[48:63], v[126:129], v[138:141], v[48:63]
	v_mfma_f32_32x32x16_bf16 v[0:15], v[130:133], v[134:137], v[0:15]
	v_mfma_f32_32x32x16_bf16 v[32:47], v[130:133], v[138:141], v[32:47]
	s_waitcnt lgkmcnt(0)
	s_barrier
	ds_read_b128 v[110:113], v104 offset:36864
	ds_read_b128 v[114:117], v104 offset:36896
	ds_read_b128 v[118:121], v104 offset:41472
	ds_read_b128 v[122:125], v104 offset:41504
	ds_read_b128 v[126:129], v101 offset:55296
	ds_read_b128 v[130:133], v101 offset:55328
	ds_read_b128 v[134:137], v101 offset:59904
	ds_read_b128 v[138:141], v101 offset:59936
	s_waitcnt lgkmcnt(3)
	v_mfma_f32_32x32x16_bf16 v[16:31], v[110:113], v[126:129], v[16:31]
	s_waitcnt lgkmcnt(1)
	v_mfma_f32_32x32x16_bf16 v[48:63], v[110:113], v[134:137], v[48:63]
	v_mfma_f32_32x32x16_bf16 v[0:15], v[118:121], v[126:129], v[0:15]
	v_mfma_f32_32x32x16_bf16 v[32:47], v[118:121], v[134:137], v[32:47]
	ds_read_b128 v[110:113], v104 offset:36928
	ds_read_b128 v[118:121], v104 offset:41536
	ds_read_b128 v[126:129], v101 offset:55360
	ds_read_b128 v[134:137], v101 offset:59968
	v_mfma_f32_32x32x16_bf16 v[16:31], v[114:117], v[130:133], v[16:31]
	s_waitcnt lgkmcnt(4)
	v_mfma_f32_32x32x16_bf16 v[48:63], v[114:117], v[138:141], v[48:63]
	v_mfma_f32_32x32x16_bf16 v[0:15], v[122:125], v[130:133], v[0:15]
	v_mfma_f32_32x32x16_bf16 v[32:47], v[122:125], v[138:141], v[32:47]
	ds_read_b128 v[114:117], v104 offset:36960
	ds_read_b128 v[122:125], v104 offset:41568
	ds_read_b128 v[130:133], v101 offset:55392
	ds_read_b128 v[138:141], v101 offset:60000
	s_waitcnt lgkmcnt(5)
	v_mfma_f32_32x32x16_bf16 v[16:31], v[110:113], v[126:129], v[16:31]
	s_waitcnt lgkmcnt(4)
	v_mfma_f32_32x32x16_bf16 v[48:63], v[110:113], v[134:137], v[48:63]
	v_mfma_f32_32x32x16_bf16 v[0:15], v[118:121], v[126:129], v[0:15]
	v_mfma_f32_32x32x16_bf16 v[32:47], v[118:121], v[134:137], v[32:47]
	s_waitcnt lgkmcnt(1)
	v_mfma_f32_32x32x16_bf16 v[16:31], v[114:117], v[130:133], v[16:31]
	s_waitcnt lgkmcnt(0)
	v_mfma_f32_32x32x16_bf16 v[48:63], v[114:117], v[138:141], v[48:63]
	v_mfma_f32_32x32x16_bf16 v[0:15], v[122:125], v[130:133], v[0:15]
	v_mfma_f32_32x32x16_bf16 v[32:47], v[122:125], v[138:141], v[32:47]
	s_cmpk_gt_u32 s85, 0x17f
	s_mov_b64 s[10:11], -1
	s_barrier
	s_cbranch_scc0 .LBB0_4095
	s_mov_b64 s[10:11], 0
	s_cmp_gt_i32 s86, 23
	s_mov_b64 s[4:5], 0
	s_cbranch_scc1 .LBB0_4095
	s_movk_i32 s62, 0x80
	s_mov_b64 s[4:5], -1
	s_mov_b32 s90, s86

; __device__ __forceinline__ void gemm_run(int tid, f32x16 (&acc)[2][2], GRegs& g, const GOp& o, int K, unsigned char* smem) {
;     ...
;   const bf16r* Ap = o.A + (size_t)r0 * o.lda + sg * 8;
;   const bf16r* Bp = o.B + (size_t)r0 * o.ldb + sg * 8;
;   const int nk = K >> 6;
; #pragma unroll
;   for (int i = 0; i < 4; i++) {
;     *(u32x4*)(sbuf + (r0 + i * 32) * LDK + sg * 8) = g.a[i];
;     *(u32x4*)(sbuf + 128 * LDK + (r0 + i * 32) * LDK + sg * 8) = g.b[i];
;   }
;   if (nk > 1) {
; #pragma unroll
;     for (int i = 0; i < 4; i++) {
;       g.a[i] = *(const u32x4*)(Ap + (size_t)i * 32 * o.lda + 64);
;       g.b[i] = *(const u32x4*)(Bp + o.bs.o[i] + 64);
;     }
;   }
;   __syncthreads();
;   const int lane = tid & 63, fr = lane & 31, fh = lane >> 5;
;   for (int k = 0; k < nk; k++) {
;     bf16r* cur = sbuf + (k & 1) * (256 * LDK);
;     bf16r* nxt = sbuf + ((k & 1) ^ 1) * (256 * LDK);
;     const bf16r* As = cur + (wm * 64 + fr) * LDK + fh * 8;
;     const bf16r* Bs = cur + 128 * LDK + (wn * 64 + fr) * LDK + fh * 8;
;     const bool wr = (k + 1 < nk), ld = (k + 2 < nk);
;     bf16x8 fa[2][2], fb[2][2];
;     fa[0][0] = *(const bf16x8*)(As);
;     fa[0][1] = *(const bf16x8*)(As + 32 * LDK);
;     fb[0][0] = *(const bf16x8*)(Bs);
;     fb[0][1] = *(const bf16x8*)(Bs + 32 * LDK);
; #pragma unroll
;     for (int i = 0; i < 4; i++) {
;       if (wr) {
;         *(u32x4*)(nxt + (r0 + i * 32) * LDK + sg * 8) = g.a[i];
;         *(u32x4*)(nxt + 128 * LDK + (r0 + i * 32) * LDK + sg * 8) = g.b[i];
;       }
;       if (ld) {
;         g.a[i] = *(const u32x4*)(Ap + (size_t)i * 32 * o.lda + (k + 2) * 64);
;         g.b[i] = *(const u32x4*)(Bp + o.bs.o[i] + (k + 2) * 64);
;       }
;       if (i < 3) {
;         fa[(i + 1) & 1][0] = *(const bf16x8*)(As + (i + 1) * 16);
;         fa[(i + 1) & 1][1] = *(const bf16x8*)(As + 32 * LDK + (i + 1) * 16);
;         fb[(i + 1) & 1][0] = *(const bf16x8*)(Bs + (i + 1) * 16);
;         fb[(i + 1) & 1][1] = *(const bf16x8*)(Bs + 32 * LDK + (i + 1) * 16);
;       }
;       __builtin_amdgcn_sched_barrier(0);
;       __builtin_amdgcn_s_setprio(1);
;       acc[0][0] = __builtin_amdgcn_mfma_f32_32x32x16_bf16(fa[i & 1][0], fb[i & 1][0], acc[0][0], 0, 0, 0);
;       acc[0][1] = __builtin_amdgcn_mfma_f32_32x32x16_bf16(fa[i & 1][0], fb[i & 1][1], acc[0][1], 0, 0, 0);
.LBB0_4483:
	s_ashr_i32 s7, s6, 31
	s_lshl_b64 s[4:5], s[6:7], 18
	s_ashr_i32 s9, s8, 31
	s_waitcnt vmcnt(7)
	ds_write_b128 v100, v[64:67]
	s_waitcnt vmcnt(6)
	ds_write_b128 v100, v[68:71] offset:18432
	s_waitcnt vmcnt(5)
	ds_write_b128 v100, v[72:75] offset:4608
	s_waitcnt vmcnt(4)
	ds_write_b128 v100, v[76:79] offset:23040
	s_waitcnt vmcnt(3)
	ds_write_b128 v100, v[80:83] offset:9216
	s_waitcnt vmcnt(2)
	ds_write_b128 v100, v[84:87] offset:27648
	s_waitcnt vmcnt(1)
	ds_write_b128 v100, v[88:91] offset:13824
	s_waitcnt vmcnt(0)
	ds_write_b128 v100, v[92:95] offset:32256
	v_lshl_add_u64 v[64:65], v[102:103], 0, s[4:5]
	s_lshl_b64 s[10:11], s[8:9], 18
	v_add_co_u32_e32 v72, vcc, s78, v64
	v_lshl_add_u64 v[106:107], v[98:99], 0, s[10:11]
	s_nop 0
	v_addc_co_u32_e32 v73, vcc, 0, v65, vcc
	v_add_co_u32_e32 v76, vcc, s78, v106
	global_load_dwordx4 v[0:3], v[64:65], off offset:128
	global_load_dwordx4 v[4:7], v[106:107], off offset:128
	v_addc_co_u32_e32 v77, vcc, 0, v107, vcc
	v_add_co_u32_e32 v80, vcc, s79, v64
	global_load_dwordx4 v[66:69], v[72:73], off offset:128
	global_load_dwordx4 v[110:113], v[76:77], off offset:128
	v_addc_co_u32_e32 v81, vcc, 0, v65, vcc
	v_add_co_u32_e32 v84, vcc, s79, v106
	s_nop 1
	v_addc_co_u32_e32 v85, vcc, 0, v107, vcc
	v_add_co_u32_e32 v88, vcc, s80, v64
	global_load_dwordx4 v[114:117], v[80:81], off offset:128
	global_load_dwordx4 v[118:121], v[84:85], off offset:128
	v_addc_co_u32_e32 v89, vcc, 0, v65, vcc
	v_add_co_u32_e32 v92, vcc, s80, v106
	s_nop 1
	v_addc_co_u32_e32 v93, vcc, 0, v107, vcc
	global_load_dwordx4 v[122:125], v[88:89], off offset:128
	global_load_dwordx4 v[126:129], v[92:93], off offset:128
	s_waitcnt lgkmcnt(0)
	s_barrier
	global_load_dwordx4 v[130:133], v[64:65], off offset:256
	global_load_dwordx4 v[134:137], v[106:107], off offset:256
	ds_read_b128 v[8:11], v104
	ds_read_b128 v[32:35], v104 offset:4608
	ds_read_b128 v[12:15], v101 offset:18432
	ds_read_b128 v[36:39], v101 offset:23040
	s_waitcnt vmcnt(9)
	ds_write_b128 v100, v[0:3] offset:36864
	s_waitcnt vmcnt(8)
	ds_write_b128 v100, v[4:7] offset:55296
	ds_read_b128 v[138:141], v104 offset:32
	ds_read_b128 v[142:145], v104 offset:4640
	ds_read_b128 v[146:149], v101 offset:18464
	ds_read_b128 v[150:153], v101 offset:23072
	s_waitcnt lgkmcnt(7)
	v_mfma_f32_32x32x16_bf16 v[16:31], v[8:11], v[12:15], 0
	s_waitcnt lgkmcnt(6)
	v_mfma_f32_32x32x16_bf16 v[48:63], v[8:11], v[36:39], 0
	v_mfma_f32_32x32x16_bf16 v[0:15], v[32:35], v[12:15], 0
	v_mfma_f32_32x32x16_bf16 v[32:47], v[32:35], v[36:39], 0
	global_load_dwordx4 v[154:157], v[72:73], off offset:256
	global_load_dwordx4 v[158:161], v[76:77], off offset:256
	s_waitcnt vmcnt(9)
	ds_write_b128 v100, v[66:69] offset:41472
	s_waitcnt vmcnt(8)
	ds_write_b128 v100, v[110:113] offset:59904
	ds_read_b128 v[66:69], v104 offset:64
	ds_read_b128 v[110:113], v104 offset:4672
	ds_read_b128 v[162:165], v101 offset:18496
	ds_read_b128 v[166:169], v101 offset:23104
	s_waitcnt lgkmcnt(7)
	v_mfma_f32_32x32x16_bf16 v[16:31], v[138:141], v[146:149], v[16:31]
	s_waitcnt lgkmcnt(6)
	v_mfma_f32_32x32x16_bf16 v[48:63], v[138:141], v[150:153], v[48:63]
	v_mfma_f32_32x32x16_bf16 v[0:15], v[142:145], v[146:149], v[0:15]
	v_mfma_f32_32x32x16_bf16 v[32:47], v[142:145], v[150:153], v[32:47]
	global_load_dwordx4 v[138:141], v[80:81], off offset:256
	global_load_dwordx4 v[142:145], v[84:85], off offset:256
	s_waitcnt vmcnt(9)
	ds_write_b128 v100, v[114:117] offset:46080
	s_waitcnt vmcnt(8)
	ds_write_b128 v100, v[118:121] offset:64512
	ds_read_b128 v[114:117], v104 offset:96
	ds_read_b128 v[118:121], v104 offset:4704
	ds_read_b128 v[146:149], v101 offset:18528
	ds_read_b128 v[150:153], v101 offset:23136
	s_waitcnt lgkmcnt(7)
	v_mfma_f32_32x32x16_bf16 v[16:31], v[66:69], v[162:165], v[16:31]
	s_waitcnt lgkmcnt(6)
	v_mfma_f32_32x32x16_bf16 v[48:63], v[66:69], v[166:169], v[48:63]
	v_mfma_f32_32x32x16_bf16 v[0:15], v[110:113], v[162:165], v[0:15]
	v_mfma_f32_32x32x16_bf16 v[32:47], v[110:113], v[166:169], v[32:47]
	global_load_dwordx4 v[66:69], v[88:89], off offset:256
	global_load_dwordx4 v[110:113], v[92:93], off offset:256
	s_waitcnt vmcnt(9)
	ds_write_b128 v100, v[122:125] offset:50688
	s_waitcnt vmcnt(8)
	ds_write_b128 v105, v[126:129] offset:13824
	s_waitcnt lgkmcnt(3)
	v_mfma_f32_32x32x16_bf16 v[16:31], v[114:117], v[146:149], v[16:31]
	s_waitcnt lgkmcnt(2)
	v_mfma_f32_32x32x16_bf16 v[48:63], v[114:117], v[150:153], v[48:63]
	v_mfma_f32_32x32x16_bf16 v[0:15], v[118:121], v[146:149], v[0:15]
	v_mfma_f32_32x32x16_bf16 v[32:47], v[118:121], v[150:153], v[32:47]
	s_waitcnt lgkmcnt(0)
	s_barrier
; __device__ __forceinline__ void gemm_run(int tid, f32x16 (&acc)[2][2], GRegs& g, const GOp& o, int K, unsigned char* smem) {
;     ...
;   for (int k = 0; k < nk; k++) {
;     bf16r* cur = sbuf + (k & 1) * (256 * LDK);
;     bf16r* nxt = sbuf + ((k & 1) ^ 1) * (256 * LDK);
;     const bf16r* As = cur + (wm * 64 + fr) * LDK + fh * 8;
;     const bf16r* Bs = cur + 128 * LDK + (wn * 64 + fr) * LDK + fh * 8;
;     const bool wr = (k + 1 < nk), ld = (k + 2 < nk);
;     bf16x8 fa[2][2], fb[2][2];
;     fa[0][0] = *(const bf16x8*)(As);
;     fa[0][1] = *(const bf16x8*)(As + 32 * LDK);
;     fb[0][0] = *(const bf16x8*)(Bs);
;     fb[0][1] = *(const bf16x8*)(Bs + 32 * LDK);
; #pragma unroll
;     for (int i = 0; i < 4; i++) {
;       if (wr) {
;         *(u32x4*)(nxt + (r0 + i * 32) * LDK + sg * 8) = g.a[i];
;         *(u32x4*)(nxt + 128 * LDK + (r0 + i * 32) * LDK + sg * 8) = g.b[i];
;       }
;       if (ld) {
;         g.a[i] = *(const u32x4*)(Ap + (size_t)i * 32 * o.lda + (k + 2) * 64);
;         g.b[i] = *(const u32x4*)(Bp + o.bs.o[i] + (k + 2) * 64);
;       }
;       if (i < 3) {
;         fa[(i + 1) & 1][0] = *(const bf16x8*)(As + (i + 1) * 16);
;         fa[(i + 1) & 1][1] = *(const bf16x8*)(As + 32 * LDK + (i + 1) * 16);
;         fb[(i + 1) & 1][0] = *(const bf16x8*)(Bs + (i + 1) * 16);
;         fb[(i + 1) & 1][1] = *(const bf16x8*)(Bs + 32 * LDK + (i + 1) * 16);
;       }
;       __builtin_amdgcn_sched_barrier(0);
;       __builtin_amdgcn_s_setprio(1);
;       acc[0][0] = __builtin_amdgcn_mfma_f32_32x32x16_bf16(fa[i & 1][0], fb[i & 1][0], acc[0][0], 0, 0, 0);
;       acc[0][1] = __builtin_amdgcn_mfma_f32_32x32x16_bf16(fa[i & 1][0], fb[i & 1][1], acc[0][1], 0, 0, 0);
;       acc[1][0] = __builtin_amdgcn_mfma_f32_32x32x16_bf16(fa[i & 1][1], fb[i & 1][0], acc[1][0], 0, 0, 0);
;       acc[1][1] = __builtin_amdgcn_mfma_f32_32x32x16_bf16(fa[i & 1][1], fb[i & 1][1], acc[1][1], 0, 0, 0);
;       __builtin_amdgcn_s_setprio(0);
;     }
;     __syncthreads();
;   }
	global_load_dwordx4 v[114:117], v[64:65], off offset:384
	global_load_dwordx4 v[118:121], v[106:107], off offset:384
	ds_read_b128 v[122:125], v104 offset:36864
	ds_read_b128 v[126:129], v104 offset:41472
	ds_read_b128 v[146:149], v101 offset:55296
	ds_read_b128 v[150:153], v101 offset:59904
	s_waitcnt vmcnt(9)
	ds_write_b128 v100, v[130:133]
	s_waitcnt vmcnt(8)
	ds_write_b128 v100, v[134:137] offset:18432
	ds_read_b128 v[130:133], v104 offset:36896
	ds_read_b128 v[134:137], v104 offset:41504
	ds_read_b128 v[162:165], v101 offset:55328
	ds_read_b128 v[166:169], v101 offset:59936
	s_waitcnt lgkmcnt(7)
	v_mfma_f32_32x32x16_bf16 v[16:31], v[122:125], v[146:149], v[16:31]
	s_waitcnt lgkmcnt(6)
	v_mfma_f32_32x32x16_bf16 v[48:63], v[122:125], v[150:153], v[48:63]
	v_mfma_f32_32x32x16_bf16 v[0:15], v[126:129], v[146:149], v[0:15]
	v_mfma_f32_32x32x16_bf16 v[32:47], v[126:129], v[150:153], v[32:47]
	global_load_dwordx4 v[122:125], v[72:73], off offset:384
	global_load_dwordx4 v[126:129], v[76:77], off offset:384
	s_waitcnt vmcnt(9)
	ds_write_b128 v100, v[154:157] offset:4608
	s_waitcnt vmcnt(8)
	ds_write_b128 v100, v[158:161] offset:23040
	ds_read_b128 v[146:149], v104 offset:36928
	ds_read_b128 v[150:153], v104 offset:41536
	ds_read_b128 v[154:157], v101 offset:55360
	ds_read_b128 v[158:161], v101 offset:59968
	s_waitcnt lgkmcnt(7)
	v_mfma_f32_32x32x16_bf16 v[16:31], v[130:133], v[162:165], v[16:31]
	s_waitcnt lgkmcnt(6)
	v_mfma_f32_32x32x16_bf16 v[48:63], v[130:133], v[166:169], v[48:63]
	v_mfma_f32_32x32x16_bf16 v[0:15], v[134:137], v[162:165], v[0:15]
	v_mfma_f32_32x32x16_bf16 v[32:47], v[134:137], v[166:169], v[32:47]
	global_load_dwordx4 v[130:133], v[80:81], off offset:384
	global_load_dwordx4 v[134:137], v[84:85], off offset:384
	s_waitcnt vmcnt(9)
	ds_write_b128 v100, v[138:141] offset:9216
	s_waitcnt vmcnt(8)
	ds_write_b128 v100, v[142:145] offset:27648
	ds_read_b128 v[138:141], v104 offset:36960
	ds_read_b128 v[142:145], v104 offset:41568
	ds_read_b128 v[162:165], v101 offset:55392
	ds_read_b128 v[166:169], v101 offset:60000
	s_waitcnt lgkmcnt(7)
	v_mfma_f32_32x32x16_bf16 v[16:31], v[146:149], v[154:157], v[16:31]
	s_waitcnt lgkmcnt(6)
	v_mfma_f32_32x32x16_bf16 v[48:63], v[146:149], v[158:161], v[48:63]
	v_mfma_f32_32x32x16_bf16 v[0:15], v[150:153], v[154:157], v[0:15]
	v_mfma_f32_32x32x16_bf16 v[32:47], v[150:153], v[158:161], v[32:47]
	global_load_dwordx4 v[146:149], v[88:89], off offset:384
	global_load_dwordx4 v[150:153], v[92:93], off offset:384
	s_waitcnt vmcnt(9)
	ds_write_b128 v100, v[66:69] offset:13824
	s_waitcnt vmcnt(8)
	ds_write_b128 v100, v[110:113] offset:32256
	s_waitcnt lgkmcnt(3)
	v_mfma_f32_32x32x16_bf16 v[16:31], v[138:141], v[162:165], v[16:31]
	s_waitcnt lgkmcnt(2)
	v_mfma_f32_32x32x16_bf16 v[48:63], v[138:141], v[166:169], v[48:63]
	v_mfma_f32_32x32x16_bf16 v[0:15], v[142:145], v[162:165], v[0:15]
	v_mfma_f32_32x32x16_bf16 v[32:47], v[142:145], v[166:169], v[32:47]
	s_waitcnt lgkmcnt(0)
	s_barrier
	global_load_dwordx4 v[66:69], v[64:65], off offset:512
	global_load_dwordx4 v[110:113], v[106:107], off offset:512
	ds_read_b128 v[138:141], v104
	ds_read_b128 v[142:145], v104 offset:4608
	ds_read_b128 v[154:157], v101 offset:18432
	ds_read_b128 v[158:161], v101 offset:23040
	s_waitcnt vmcnt(9)
	ds_write_b128 v100, v[114:117] offset:36864
	s_waitcnt vmcnt(8)
	ds_write_b128 v100, v[118:121] offset:55296
	ds_read_b128 v[114:117], v104 offset:32
	ds_read_b128 v[118:121], v104 offset:4640
	ds_read_b128 v[162:165], v101 offset:18464
	ds_read_b128 v[166:169], v101 offset:23072
	s_waitcnt lgkmcnt(7)
	v_mfma_f32_32x32x16_bf16 v[16:31], v[138:141], v[154:157], v[16:31]
	s_waitcnt lgkmcnt(6)
	v_mfma_f32_32x32x16_bf16 v[48:63], v[138:141], v[158:161], v[48:63]
	v_mfma_f32_32x32x16_bf16 v[0:15], v[142:145], v[154:157], v[0:15]
	v_mfma_f32_32x32x16_bf16 v[32:47], v[142:145], v[158:161], v[32:47]
	global_load_dwordx4 v[138:141], v[72:73], off offset:512
	global_load_dwordx4 v[142:145], v[76:77], off offset:512
	s_waitcnt vmcnt(9)
	ds_write_b128 v100, v[122:125] offset:41472
	s_waitcnt vmcnt(8)
	ds_write_b128 v100, v[126:129] offset:59904
	ds_read_b128 v[122:125], v104 offset:64
	ds_read_b128 v[126:129], v104 offset:4672
	ds_read_b128 v[154:157], v101 offset:18496
	ds_read_b128 v[158:161], v101 offset:23104
	s_waitcnt lgkmcnt(7)
	v_mfma_f32_32x32x16_bf16 v[16:31], v[114:117], v[162:165], v[16:31]
	s_waitcnt lgkmcnt(6)
	v_mfma_f32_32x32x16_bf16 v[48:63], v[114:117], v[166:169], v[48:63]
	v_mfma_f32_32x32x16_bf16 v[0:15], v[118:121], v[162:165], v[0:15]
	v_mfma_f32_32x32x16_bf16 v[32:47], v[118:121], v[166:169], v[32:47]
	global_load_dwordx4 v[114:117], v[80:81], off offset:512
	global_load_dwordx4 v[118:121], v[84:85], off offset:512
	s_waitcnt vmcnt(9)
	ds_write_b128 v100, v[130:133] offset:46080
	s_waitcnt vmcnt(8)
	ds_write_b128 v100, v[134:137] offset:64512
	ds_read_b128 v[130:133], v104 offset:96
	ds_read_b128 v[134:137], v104 offset:4704
	ds_read_b128 v[162:165], v101 offset:18528
	ds_read_b128 v[166:169], v101 offset:23136
	s_waitcnt lgkmcnt(7)
	v_mfma_f32_32x32x16_bf16 v[16:31], v[122:125], v[154:157], v[16:31]
	s_waitcnt lgkmcnt(6)
	v_mfma_f32_32x32x16_bf16 v[48:63], v[122:125], v[158:161], v[48:63]
	v_mfma_f32_32x32x16_bf16 v[0:15], v[126:129], v[154:157], v[0:15]
	v_mfma_f32_32x32x16_bf16 v[32:47], v[126:129], v[158:161], v[32:47]
	global_load_dwordx4 v[122:125], v[88:89], off offset:512
	global_load_dwordx4 v[126:129], v[92:93], off offset:512
	s_waitcnt vmcnt(9)
	ds_write_b128 v100, v[146:149] offset:50688
	s_waitcnt vmcnt(8)
	ds_write_b128 v105, v[150:153] offset:13824
	s_waitcnt lgkmcnt(3)
	v_mfma_f32_32x32x16_bf16 v[16:31], v[130:133], v[162:165], v[16:31]
	s_waitcnt lgkmcnt(2)
	v_mfma_f32_32x32x16_bf16 v[48:63], v[130:133], v[166:169], v[48:63]
	v_mfma_f32_32x32x16_bf16 v[0:15], v[134:137], v[162:165], v[0:15]
	v_mfma_f32_32x32x16_bf16 v[32:47], v[134:137], v[166:169], v[32:47]
	s_waitcnt lgkmcnt(0)
	s_barrier
; __device__ __forceinline__ void gemm_run(int tid, f32x16 (&acc)[2][2], GRegs& g, const GOp& o, int K, unsigned char* smem) {
;     ...
;   for (int k = 0; k < nk; k++) {
;     bf16r* cur = sbuf + (k & 1) * (256 * LDK);
;     bf16r* nxt = sbuf + ((k & 1) ^ 1) * (256 * LDK);
;     const bf16r* As = cur + (wm * 64 + fr) * LDK + fh * 8;
;     const bf16r* Bs = cur + 128 * LDK + (wn * 64 + fr) * LDK + fh * 8;
;     const bool wr = (k + 1 < nk), ld = (k + 2 < nk);
;     bf16x8 fa[2][2], fb[2][2];
;     fa[0][0] = *(const bf16x8*)(As);
;     fa[0][1] = *(const bf16x8*)(As + 32 * LDK);
;     fb[0][0] = *(const bf16x8*)(Bs);
;     fb[0][1] = *(const bf16x8*)(Bs + 32 * LDK);
; #pragma unroll
;     for (int i = 0; i < 4; i++) {
;       if (wr) {
;         *(u32x4*)(nxt + (r0 + i * 32) * LDK + sg * 8) = g.a[i];
;         *(u32x4*)(nxt + 128 * LDK + (r0 + i * 32) * LDK + sg * 8) = g.b[i];
;       }
;       if (ld) {
;         g.a[i] = *(const u32x4*)(Ap + (size_t)i * 32 * o.lda + (k + 2) * 64);
;         g.b[i] = *(const u32x4*)(Bp + o.bs.o[i] + (k + 2) * 64);
;       }
;       if (i < 3) {
;         fa[(i + 1) & 1][0] = *(const bf16x8*)(As + (i + 1) * 16);
;         fa[(i + 1) & 1][1] = *(const bf16x8*)(As + 32 * LDK + (i + 1) * 16);
;         fb[(i + 1) & 1][0] = *(const bf16x8*)(Bs + (i + 1) * 16);
;         fb[(i + 1) & 1][1] = *(const bf16x8*)(Bs + 32 * LDK + (i + 1) * 16);
;       }
;       __builtin_amdgcn_sched_barrier(0);
;       __builtin_amdgcn_s_setprio(1);
;       acc[0][0] = __builtin_amdgcn_mfma_f32_32x32x16_bf16(fa[i & 1][0], fb[i & 1][0], acc[0][0], 0, 0, 0);
;       acc[0][1] = __builtin_amdgcn_mfma_f32_32x32x16_bf16(fa[i & 1][0], fb[i & 1][1], acc[0][1], 0, 0, 0);
;       acc[1][0] = __builtin_amdgcn_mfma_f32_32x32x16_bf16(fa[i & 1][1], fb[i & 1][0], acc[1][0], 0, 0, 0);
;       acc[1][1] = __builtin_amdgcn_mfma_f32_32x32x16_bf16(fa[i & 1][1], fb[i & 1][1], acc[1][1], 0, 0, 0);
;       __builtin_amdgcn_s_setprio(0);
;     }
;     __syncthreads();
;   }
	global_load_dwordx4 v[130:133], v[64:65], off offset:640
	global_load_dwordx4 v[134:137], v[106:107], off offset:640
	ds_read_b128 v[146:149], v104 offset:36864
	ds_read_b128 v[150:153], v104 offset:41472
	ds_read_b128 v[154:157], v101 offset:55296
	ds_read_b128 v[158:161], v101 offset:59904
	s_waitcnt vmcnt(9)
	ds_write_b128 v100, v[66:69]
	s_waitcnt vmcnt(8)
	ds_write_b128 v100, v[110:113] offset:18432
	ds_read_b128 v[66:69], v104 offset:36896
	ds_read_b128 v[110:113], v104 offset:41504
	ds_read_b128 v[162:165], v101 offset:55328
	ds_read_b128 v[166:169], v101 offset:59936
	s_waitcnt lgkmcnt(7)
	v_mfma_f32_32x32x16_bf16 v[16:31], v[146:149], v[154:157], v[16:31]
	s_waitcnt lgkmcnt(6)
	v_mfma_f32_32x32x16_bf16 v[48:63], v[146:149], v[158:161], v[48:63]
	v_mfma_f32_32x32x16_bf16 v[0:15], v[150:153], v[154:157], v[0:15]
	v_mfma_f32_32x32x16_bf16 v[32:47], v[150:153], v[158:161], v[32:47]
	global_load_dwordx4 v[146:149], v[72:73], off offset:640
	global_load_dwordx4 v[150:153], v[76:77], off offset:640
	s_waitcnt vmcnt(9)
	ds_write_b128 v100, v[138:141] offset:4608
	s_waitcnt vmcnt(8)
	ds_write_b128 v100, v[142:145] offset:23040
	ds_read_b128 v[138:141], v104 offset:36928
	ds_read_b128 v[142:145], v104 offset:41536
	ds_read_b128 v[154:157], v101 offset:55360
	ds_read_b128 v[158:161], v101 offset:59968
	s_waitcnt lgkmcnt(7)
	v_mfma_f32_32x32x16_bf16 v[16:31], v[66:69], v[162:165], v[16:31]
	s_waitcnt lgkmcnt(6)
	v_mfma_f32_32x32x16_bf16 v[48:63], v[66:69], v[166:169], v[48:63]
	v_mfma_f32_32x32x16_bf16 v[0:15], v[110:113], v[162:165], v[0:15]
	v_mfma_f32_32x32x16_bf16 v[32:47], v[110:113], v[166:169], v[32:47]
	global_load_dwordx4 v[66:69], v[80:81], off offset:640
	global_load_dwordx4 v[110:113], v[84:85], off offset:640
	s_waitcnt vmcnt(9)
	ds_write_b128 v100, v[114:117] offset:9216
	s_waitcnt vmcnt(8)
	ds_write_b128 v100, v[118:121] offset:27648
	ds_read_b128 v[114:117], v104 offset:36960
	ds_read_b128 v[118:121], v104 offset:41568
	ds_read_b128 v[162:165], v101 offset:55392
	ds_read_b128 v[166:169], v101 offset:60000
	s_waitcnt lgkmcnt(7)
	v_mfma_f32_32x32x16_bf16 v[16:31], v[138:141], v[154:157], v[16:31]
	s_waitcnt lgkmcnt(6)
	v_mfma_f32_32x32x16_bf16 v[48:63], v[138:141], v[158:161], v[48:63]
	v_mfma_f32_32x32x16_bf16 v[0:15], v[142:145], v[154:157], v[0:15]
	v_mfma_f32_32x32x16_bf16 v[32:47], v[142:145], v[158:161], v[32:47]
	global_load_dwordx4 v[138:141], v[88:89], off offset:640
	global_load_dwordx4 v[142:145], v[92:93], off offset:640
	s_waitcnt vmcnt(9)
	ds_write_b128 v100, v[122:125] offset:13824
	s_waitcnt vmcnt(8)
	ds_write_b128 v100, v[126:129] offset:32256
	s_waitcnt lgkmcnt(3)
	v_mfma_f32_32x32x16_bf16 v[16:31], v[114:117], v[162:165], v[16:31]
	s_waitcnt lgkmcnt(2)
	v_mfma_f32_32x32x16_bf16 v[48:63], v[114:117], v[166:169], v[48:63]
	v_mfma_f32_32x32x16_bf16 v[0:15], v[118:121], v[162:165], v[0:15]
	v_mfma_f32_32x32x16_bf16 v[32:47], v[118:121], v[166:169], v[32:47]
	s_waitcnt lgkmcnt(0)
	s_barrier
	global_load_dwordx4 v[114:117], v[64:65], off offset:768
	global_load_dwordx4 v[118:121], v[106:107], off offset:768
	ds_read_b128 v[122:125], v104
	ds_read_b128 v[126:129], v104 offset:4608
	ds_read_b128 v[154:157], v101 offset:18432
	ds_read_b128 v[158:161], v101 offset:23040
	s_waitcnt vmcnt(9)
	ds_write_b128 v100, v[130:133] offset:36864
	s_waitcnt vmcnt(8)
	ds_write_b128 v100, v[134:137] offset:55296
	ds_read_b128 v[130:133], v104 offset:32
	ds_read_b128 v[134:137], v104 offset:4640
	ds_read_b128 v[162:165], v101 offset:18464
	ds_read_b128 v[166:169], v101 offset:23072
	s_waitcnt lgkmcnt(7)
	v_mfma_f32_32x32x16_bf16 v[16:31], v[122:125], v[154:157], v[16:31]
	s_waitcnt lgkmcnt(6)
	v_mfma_f32_32x32x16_bf16 v[48:63], v[122:125], v[158:161], v[48:63]
	v_mfma_f32_32x32x16_bf16 v[0:15], v[126:129], v[154:157], v[0:15]
	v_mfma_f32_32x32x16_bf16 v[32:47], v[126:129], v[158:161], v[32:47]
	global_load_dwordx4 v[122:125], v[72:73], off offset:768
	global_load_dwordx4 v[126:129], v[76:77], off offset:768
	s_waitcnt vmcnt(9)
	ds_write_b128 v100, v[146:149] offset:41472
	s_waitcnt vmcnt(8)
	ds_write_b128 v100, v[150:153] offset:59904
	ds_read_b128 v[146:149], v104 offset:64
	ds_read_b128 v[150:153], v104 offset:4672
	ds_read_b128 v[154:157], v101 offset:18496
	ds_read_b128 v[158:161], v101 offset:23104
	s_waitcnt lgkmcnt(7)
	v_mfma_f32_32x32x16_bf16 v[16:31], v[130:133], v[162:165], v[16:31]
	s_waitcnt lgkmcnt(6)
	v_mfma_f32_32x32x16_bf16 v[48:63], v[130:133], v[166:169], v[48:63]
	v_mfma_f32_32x32x16_bf16 v[0:15], v[134:137], v[162:165], v[0:15]
	v_mfma_f32_32x32x16_bf16 v[32:47], v[134:137], v[166:169], v[32:47]
	global_load_dwordx4 v[130:133], v[80:81], off offset:768
	global_load_dwordx4 v[134:137], v[84:85], off offset:768
	s_waitcnt vmcnt(9)
	ds_write_b128 v100, v[66:69] offset:46080
	s_waitcnt vmcnt(8)
	ds_write_b128 v100, v[110:113] offset:64512
	ds_read_b128 v[66:69], v104 offset:96
	ds_read_b128 v[110:113], v104 offset:4704
	ds_read_b128 v[162:165], v101 offset:18528
	ds_read_b128 v[166:169], v101 offset:23136
	s_waitcnt lgkmcnt(7)
	v_mfma_f32_32x32x16_bf16 v[16:31], v[146:149], v[154:157], v[16:31]
	s_waitcnt lgkmcnt(6)
	v_mfma_f32_32x32x16_bf16 v[48:63], v[146:149], v[158:161], v[48:63]
	v_mfma_f32_32x32x16_bf16 v[0:15], v[150:153], v[154:157], v[0:15]
	v_mfma_f32_32x32x16_bf16 v[32:47], v[150:153], v[158:161], v[32:47]
	global_load_dwordx4 v[146:149], v[88:89], off offset:768
	global_load_dwordx4 v[150:153], v[92:93], off offset:768
	s_waitcnt vmcnt(9)
	ds_write_b128 v100, v[138:141] offset:50688
	s_waitcnt vmcnt(8)
	ds_write_b128 v105, v[142:145] offset:13824
	s_waitcnt lgkmcnt(3)
	v_mfma_f32_32x32x16_bf16 v[16:31], v[66:69], v[162:165], v[16:31]
	s_waitcnt lgkmcnt(2)
	v_mfma_f32_32x32x16_bf16 v[48:63], v[66:69], v[166:169], v[48:63]
	v_mfma_f32_32x32x16_bf16 v[0:15], v[110:113], v[162:165], v[0:15]
	v_mfma_f32_32x32x16_bf16 v[32:47], v[110:113], v[166:169], v[32:47]
	s_waitcnt lgkmcnt(0)
	s_barrier
; __device__ __forceinline__ void gemm_run(int tid, f32x16 (&acc)[2][2], GRegs& g, const GOp& o, int K, unsigned char* smem) {
;     ...
;   for (int k = 0; k < nk; k++) {
;     bf16r* cur = sbuf + (k & 1) * (256 * LDK);
;     bf16r* nxt = sbuf + ((k & 1) ^ 1) * (256 * LDK);
;     const bf16r* As = cur + (wm * 64 + fr) * LDK + fh * 8;
;     const bf16r* Bs = cur + 128 * LDK + (wn * 64 + fr) * LDK + fh * 8;
;     const bool wr = (k + 1 < nk), ld = (k + 2 < nk);
;     bf16x8 fa[2][2], fb[2][2];
;     fa[0][0] = *(const bf16x8*)(As);
;     fa[0][1] = *(const bf16x8*)(As + 32 * LDK);
;     fb[0][0] = *(const bf16x8*)(Bs);
;     fb[0][1] = *(const bf16x8*)(Bs + 32 * LDK);
; #pragma unroll
;     for (int i = 0; i < 4; i++) {
;       if (wr) {
;         *(u32x4*)(nxt + (r0 + i * 32) * LDK + sg * 8) = g.a[i];
;         *(u32x4*)(nxt + 128 * LDK + (r0 + i * 32) * LDK + sg * 8) = g.b[i];
;       }
;       if (ld) {
;         g.a[i] = *(const u32x4*)(Ap + (size_t)i * 32 * o.lda + (k + 2) * 64);
;         g.b[i] = *(const u32x4*)(Bp + o.bs.o[i] + (k + 2) * 64);
;       }
;       if (i < 3) {
;         fa[(i + 1) & 1][0] = *(const bf16x8*)(As + (i + 1) * 16);
;         fa[(i + 1) & 1][1] = *(const bf16x8*)(As + 32 * LDK + (i + 1) * 16);
;         fb[(i + 1) & 1][0] = *(const bf16x8*)(Bs + (i + 1) * 16);
;         fb[(i + 1) & 1][1] = *(const bf16x8*)(Bs + 32 * LDK + (i + 1) * 16);
;       }
;       __builtin_amdgcn_sched_barrier(0);
;       __builtin_amdgcn_s_setprio(1);
;       acc[0][0] = __builtin_amdgcn_mfma_f32_32x32x16_bf16(fa[i & 1][0], fb[i & 1][0], acc[0][0], 0, 0, 0);
;       acc[0][1] = __builtin_amdgcn_mfma_f32_32x32x16_bf16(fa[i & 1][0], fb[i & 1][1], acc[0][1], 0, 0, 0);
;       acc[1][0] = __builtin_amdgcn_mfma_f32_32x32x16_bf16(fa[i & 1][1], fb[i & 1][0], acc[1][0], 0, 0, 0);
;       acc[1][1] = __builtin_amdgcn_mfma_f32_32x32x16_bf16(fa[i & 1][1], fb[i & 1][1], acc[1][1], 0, 0, 0);
;       __builtin_amdgcn_s_setprio(0);
;     }
;     __syncthreads();
;   }
	global_load_dwordx4 v[66:69], v[64:65], off offset:896
	global_load_dwordx4 v[110:113], v[106:107], off offset:896
	ds_read_b128 v[138:141], v104 offset:36864
	ds_read_b128 v[142:145], v104 offset:41472
	ds_read_b128 v[154:157], v101 offset:55296
	ds_read_b128 v[158:161], v101 offset:59904
	s_waitcnt vmcnt(9)
	ds_write_b128 v100, v[114:117]
	s_waitcnt vmcnt(8)
	ds_write_b128 v100, v[118:121] offset:18432
	ds_read_b128 v[114:117], v104 offset:36896
	ds_read_b128 v[118:121], v104 offset:41504
	ds_read_b128 v[162:165], v101 offset:55328
	ds_read_b128 v[166:169], v101 offset:59936
	s_waitcnt lgkmcnt(7)
	v_mfma_f32_32x32x16_bf16 v[16:31], v[138:141], v[154:157], v[16:31]
	s_waitcnt lgkmcnt(6)
	v_mfma_f32_32x32x16_bf16 v[48:63], v[138:141], v[158:161], v[48:63]
	v_mfma_f32_32x32x16_bf16 v[0:15], v[142:145], v[154:157], v[0:15]
	v_mfma_f32_32x32x16_bf16 v[32:47], v[142:145], v[158:161], v[32:47]
	global_load_dwordx4 v[138:141], v[72:73], off offset:896
	global_load_dwordx4 v[142:145], v[76:77], off offset:896
	s_waitcnt vmcnt(9)
	ds_write_b128 v100, v[122:125] offset:4608
	s_waitcnt vmcnt(8)
	ds_write_b128 v100, v[126:129] offset:23040
	ds_read_b128 v[122:125], v104 offset:36928
	ds_read_b128 v[126:129], v104 offset:41536
	ds_read_b128 v[154:157], v101 offset:55360
	ds_read_b128 v[158:161], v101 offset:59968
	s_waitcnt lgkmcnt(7)
	v_mfma_f32_32x32x16_bf16 v[16:31], v[114:117], v[162:165], v[16:31]
	s_waitcnt lgkmcnt(6)
	v_mfma_f32_32x32x16_bf16 v[48:63], v[114:117], v[166:169], v[48:63]
	v_mfma_f32_32x32x16_bf16 v[0:15], v[118:121], v[162:165], v[0:15]
	v_mfma_f32_32x32x16_bf16 v[32:47], v[118:121], v[166:169], v[32:47]
	global_load_dwordx4 v[114:117], v[80:81], off offset:896
	global_load_dwordx4 v[118:121], v[84:85], off offset:896
	s_waitcnt vmcnt(9)
	ds_write_b128 v100, v[130:133] offset:9216
	s_waitcnt vmcnt(8)
	ds_write_b128 v100, v[134:137] offset:27648
	ds_read_b128 v[130:133], v104 offset:36960
	ds_read_b128 v[134:137], v104 offset:41568
	ds_read_b128 v[162:165], v101 offset:55392
	ds_read_b128 v[166:169], v101 offset:60000
	s_waitcnt lgkmcnt(7)
	v_mfma_f32_32x32x16_bf16 v[16:31], v[122:125], v[154:157], v[16:31]
	s_waitcnt lgkmcnt(6)
	v_mfma_f32_32x32x16_bf16 v[48:63], v[122:125], v[158:161], v[48:63]
	v_mfma_f32_32x32x16_bf16 v[0:15], v[126:129], v[154:157], v[0:15]
	v_mfma_f32_32x32x16_bf16 v[32:47], v[126:129], v[158:161], v[32:47]
	global_load_dwordx4 v[122:125], v[88:89], off offset:896
	global_load_dwordx4 v[126:129], v[92:93], off offset:896
	s_waitcnt vmcnt(9)
	ds_write_b128 v100, v[146:149] offset:13824
	s_waitcnt vmcnt(8)
	ds_write_b128 v100, v[150:153] offset:32256
	s_waitcnt lgkmcnt(3)
	v_mfma_f32_32x32x16_bf16 v[16:31], v[130:133], v[162:165], v[16:31]
	s_waitcnt lgkmcnt(2)
	v_mfma_f32_32x32x16_bf16 v[48:63], v[130:133], v[166:169], v[48:63]
	v_mfma_f32_32x32x16_bf16 v[0:15], v[134:137], v[162:165], v[0:15]
	v_mfma_f32_32x32x16_bf16 v[32:47], v[134:137], v[166:169], v[32:47]
	s_waitcnt lgkmcnt(0)
	s_barrier
	global_load_dwordx4 v[130:133], v[64:65], off offset:1024
	global_load_dwordx4 v[134:137], v[106:107], off offset:1024
	ds_read_b128 v[146:149], v104
	ds_read_b128 v[150:153], v104 offset:4608
	ds_read_b128 v[154:157], v101 offset:18432
	ds_read_b128 v[158:161], v101 offset:23040
	s_waitcnt vmcnt(9)
	ds_write_b128 v100, v[66:69] offset:36864
	s_waitcnt vmcnt(8)
	ds_write_b128 v100, v[110:113] offset:55296
	ds_read_b128 v[66:69], v104 offset:32
	ds_read_b128 v[110:113], v104 offset:4640
	ds_read_b128 v[162:165], v101 offset:18464
	ds_read_b128 v[166:169], v101 offset:23072
	s_waitcnt lgkmcnt(7)
	v_mfma_f32_32x32x16_bf16 v[16:31], v[146:149], v[154:157], v[16:31]
	s_waitcnt lgkmcnt(6)
	v_mfma_f32_32x32x16_bf16 v[48:63], v[146:149], v[158:161], v[48:63]
	v_mfma_f32_32x32x16_bf16 v[0:15], v[150:153], v[154:157], v[0:15]
	v_mfma_f32_32x32x16_bf16 v[32:47], v[150:153], v[158:161], v[32:47]
	global_load_dwordx4 v[146:149], v[72:73], off offset:1024
	global_load_dwordx4 v[150:153], v[76:77], off offset:1024
	s_waitcnt vmcnt(9)
	ds_write_b128 v100, v[138:141] offset:41472
	s_waitcnt vmcnt(8)
	ds_write_b128 v100, v[142:145] offset:59904
	ds_read_b128 v[138:141], v104 offset:64
	ds_read_b128 v[142:145], v104 offset:4672
	ds_read_b128 v[154:157], v101 offset:18496
	ds_read_b128 v[158:161], v101 offset:23104
	s_waitcnt lgkmcnt(7)
	v_mfma_f32_32x32x16_bf16 v[16:31], v[66:69], v[162:165], v[16:31]
	s_waitcnt lgkmcnt(6)
	v_mfma_f32_32x32x16_bf16 v[48:63], v[66:69], v[166:169], v[48:63]
	v_mfma_f32_32x32x16_bf16 v[0:15], v[110:113], v[162:165], v[0:15]
	v_mfma_f32_32x32x16_bf16 v[32:47], v[110:113], v[166:169], v[32:47]
	global_load_dwordx4 v[66:69], v[80:81], off offset:1024
	global_load_dwordx4 v[110:113], v[84:85], off offset:1024
	s_waitcnt vmcnt(9)
	ds_write_b128 v100, v[114:117] offset:46080
	s_waitcnt vmcnt(8)
	ds_write_b128 v100, v[118:121] offset:64512
	ds_read_b128 v[114:117], v104 offset:96
	ds_read_b128 v[118:121], v104 offset:4704
	ds_read_b128 v[162:165], v101 offset:18528
	ds_read_b128 v[166:169], v101 offset:23136
	s_waitcnt lgkmcnt(7)
	v_mfma_f32_32x32x16_bf16 v[16:31], v[138:141], v[154:157], v[16:31]
	s_waitcnt lgkmcnt(6)
	v_mfma_f32_32x32x16_bf16 v[48:63], v[138:141], v[158:161], v[48:63]
	v_mfma_f32_32x32x16_bf16 v[0:15], v[142:145], v[154:157], v[0:15]
	v_mfma_f32_32x32x16_bf16 v[32:47], v[142:145], v[158:161], v[32:47]
	global_load_dwordx4 v[138:141], v[88:89], off offset:1024
	global_load_dwordx4 v[142:145], v[92:93], off offset:1024
	s_waitcnt vmcnt(9)
	ds_write_b128 v100, v[122:125] offset:50688
	s_waitcnt vmcnt(8)
	ds_write_b128 v105, v[126:129] offset:13824
	s_waitcnt lgkmcnt(3)
	v_mfma_f32_32x32x16_bf16 v[16:31], v[114:117], v[162:165], v[16:31]
	s_waitcnt lgkmcnt(2)
	v_mfma_f32_32x32x16_bf16 v[48:63], v[114:117], v[166:169], v[48:63]
	v_mfma_f32_32x32x16_bf16 v[0:15], v[118:121], v[162:165], v[0:15]
	v_mfma_f32_32x32x16_bf16 v[32:47], v[118:121], v[166:169], v[32:47]
	s_waitcnt lgkmcnt(0)
	s_barrier
; __device__ __forceinline__ void gemm_run(int tid, f32x16 (&acc)[2][2], GRegs& g, const GOp& o, int K, unsigned char* smem) {
;     ...
;   for (int k = 0; k < nk; k++) {
;     bf16r* cur = sbuf + (k & 1) * (256 * LDK);
;     bf16r* nxt = sbuf + ((k & 1) ^ 1) * (256 * LDK);
;     const bf16r* As = cur + (wm * 64 + fr) * LDK + fh * 8;
;     const bf16r* Bs = cur + 128 * LDK + (wn * 64 + fr) * LDK + fh * 8;
;     const bool wr = (k + 1 < nk), ld = (k + 2 < nk);
;     bf16x8 fa[2][2], fb[2][2];
;     fa[0][0] = *(const bf16x8*)(As);
;     fa[0][1] = *(const bf16x8*)(As + 32 * LDK);
;     fb[0][0] = *(const bf16x8*)(Bs);
;     fb[0][1] = *(const bf16x8*)(Bs + 32 * LDK);
; #pragma unroll
;     for (int i = 0; i < 4; i++) {
;       if (wr) {
;         *(u32x4*)(nxt + (r0 + i * 32) * LDK + sg * 8) = g.a[i];
;         *(u32x4*)(nxt + 128 * LDK + (r0 + i * 32) * LDK + sg * 8) = g.b[i];
;       }
;       if (ld) {
;         g.a[i] = *(const u32x4*)(Ap + (size_t)i * 32 * o.lda + (k + 2) * 64);
;         g.b[i] = *(const u32x4*)(Bp + o.bs.o[i] + (k + 2) * 64);
;       }
;       if (i < 3) {
;         fa[(i + 1) & 1][0] = *(const bf16x8*)(As + (i + 1) * 16);
;         fa[(i + 1) & 1][1] = *(const bf16x8*)(As + 32 * LDK + (i + 1) * 16);
;         fb[(i + 1) & 1][0] = *(const bf16x8*)(Bs + (i + 1) * 16);
;         fb[(i + 1) & 1][1] = *(const bf16x8*)(Bs + 32 * LDK + (i + 1) * 16);
;       }
;       __builtin_amdgcn_sched_barrier(0);
;       __builtin_amdgcn_s_setprio(1);
;       acc[0][0] = __builtin_amdgcn_mfma_f32_32x32x16_bf16(fa[i & 1][0], fb[i & 1][0], acc[0][0], 0, 0, 0);
;       acc[0][1] = __builtin_amdgcn_mfma_f32_32x32x16_bf16(fa[i & 1][0], fb[i & 1][1], acc[0][1], 0, 0, 0);
;       acc[1][0] = __builtin_amdgcn_mfma_f32_32x32x16_bf16(fa[i & 1][1], fb[i & 1][0], acc[1][0], 0, 0, 0);
;       acc[1][1] = __builtin_amdgcn_mfma_f32_32x32x16_bf16(fa[i & 1][1], fb[i & 1][1], acc[1][1], 0, 0, 0);
;       __builtin_amdgcn_s_setprio(0);
;     }
;     __syncthreads();
;   }
	global_load_dwordx4 v[114:117], v[64:65], off offset:1152
	global_load_dwordx4 v[118:121], v[106:107], off offset:1152
	ds_read_b128 v[122:125], v104 offset:36864
	ds_read_b128 v[126:129], v104 offset:41472
	ds_read_b128 v[154:157], v101 offset:55296
	ds_read_b128 v[158:161], v101 offset:59904
	s_waitcnt vmcnt(9)
	ds_write_b128 v100, v[130:133]
	s_waitcnt vmcnt(8)
	ds_write_b128 v100, v[134:137] offset:18432
	ds_read_b128 v[130:133], v104 offset:36896
	ds_read_b128 v[134:137], v104 offset:41504
	ds_read_b128 v[162:165], v101 offset:55328
	ds_read_b128 v[166:169], v101 offset:59936
	s_waitcnt lgkmcnt(7)
	v_mfma_f32_32x32x16_bf16 v[16:31], v[122:125], v[154:157], v[16:31]
	s_waitcnt lgkmcnt(6)
	v_mfma_f32_32x32x16_bf16 v[48:63], v[122:125], v[158:161], v[48:63]
	v_mfma_f32_32x32x16_bf16 v[0:15], v[126:129], v[154:157], v[0:15]
	v_mfma_f32_32x32x16_bf16 v[32:47], v[126:129], v[158:161], v[32:47]
	global_load_dwordx4 v[122:125], v[72:73], off offset:1152
	global_load_dwordx4 v[126:129], v[76:77], off offset:1152
	s_waitcnt vmcnt(9)
	ds_write_b128 v100, v[146:149] offset:4608
	s_waitcnt vmcnt(8)
	ds_write_b128 v100, v[150:153] offset:23040
	ds_read_b128 v[146:149], v104 offset:36928
	ds_read_b128 v[150:153], v104 offset:41536
	ds_read_b128 v[154:157], v101 offset:55360
	ds_read_b128 v[158:161], v101 offset:59968
	s_waitcnt lgkmcnt(7)
	v_mfma_f32_32x32x16_bf16 v[16:31], v[130:133], v[162:165], v[16:31]
	s_waitcnt lgkmcnt(6)
	v_mfma_f32_32x32x16_bf16 v[48:63], v[130:133], v[166:169], v[48:63]
	v_mfma_f32_32x32x16_bf16 v[0:15], v[134:137], v[162:165], v[0:15]
	v_mfma_f32_32x32x16_bf16 v[32:47], v[134:137], v[166:169], v[32:47]
	global_load_dwordx4 v[130:133], v[80:81], off offset:1152
	global_load_dwordx4 v[134:137], v[84:85], off offset:1152
	s_waitcnt vmcnt(9)
	ds_write_b128 v100, v[66:69] offset:9216
	s_waitcnt vmcnt(8)
	ds_write_b128 v100, v[110:113] offset:27648
	ds_read_b128 v[66:69], v104 offset:36960
	ds_read_b128 v[110:113], v104 offset:41568
	ds_read_b128 v[162:165], v101 offset:55392
	ds_read_b128 v[166:169], v101 offset:60000
	s_waitcnt lgkmcnt(7)
	v_mfma_f32_32x32x16_bf16 v[16:31], v[146:149], v[154:157], v[16:31]
	s_waitcnt lgkmcnt(6)
	v_mfma_f32_32x32x16_bf16 v[48:63], v[146:149], v[158:161], v[48:63]
	v_mfma_f32_32x32x16_bf16 v[0:15], v[150:153], v[154:157], v[0:15]
	v_mfma_f32_32x32x16_bf16 v[32:47], v[150:153], v[158:161], v[32:47]
	global_load_dwordx4 v[146:149], v[88:89], off offset:1152
	global_load_dwordx4 v[150:153], v[92:93], off offset:1152
	s_waitcnt vmcnt(9)
	ds_write_b128 v100, v[138:141] offset:13824
	s_waitcnt vmcnt(8)
	ds_write_b128 v100, v[142:145] offset:32256
	s_waitcnt lgkmcnt(3)
	v_mfma_f32_32x32x16_bf16 v[16:31], v[66:69], v[162:165], v[16:31]
	s_waitcnt lgkmcnt(2)
	v_mfma_f32_32x32x16_bf16 v[48:63], v[66:69], v[166:169], v[48:63]
	v_mfma_f32_32x32x16_bf16 v[0:15], v[110:113], v[162:165], v[0:15]
	v_mfma_f32_32x32x16_bf16 v[32:47], v[110:113], v[166:169], v[32:47]
	s_waitcnt lgkmcnt(0)
	s_barrier
	global_load_dwordx4 v[66:69], v[64:65], off offset:1280
	global_load_dwordx4 v[110:113], v[106:107], off offset:1280
	ds_read_b128 v[138:141], v104
	ds_read_b128 v[142:145], v104 offset:4608
	ds_read_b128 v[154:157], v101 offset:18432
	ds_read_b128 v[158:161], v101 offset:23040
	s_waitcnt vmcnt(9)
	ds_write_b128 v100, v[114:117] offset:36864
	s_waitcnt vmcnt(8)
	ds_write_b128 v100, v[118:121] offset:55296
	ds_read_b128 v[114:117], v104 offset:32
	ds_read_b128 v[118:121], v104 offset:4640
	ds_read_b128 v[162:165], v101 offset:18464
	ds_read_b128 v[166:169], v101 offset:23072
	s_waitcnt lgkmcnt(7)
	v_mfma_f32_32x32x16_bf16 v[16:31], v[138:141], v[154:157], v[16:31]
	s_waitcnt lgkmcnt(6)
	v_mfma_f32_32x32x16_bf16 v[48:63], v[138:141], v[158:161], v[48:63]
	v_mfma_f32_32x32x16_bf16 v[0:15], v[142:145], v[154:157], v[0:15]
	v_mfma_f32_32x32x16_bf16 v[32:47], v[142:145], v[158:161], v[32:47]
	global_load_dwordx4 v[138:141], v[72:73], off offset:1280
	global_load_dwordx4 v[142:145], v[76:77], off offset:1280
	s_waitcnt vmcnt(9)
	ds_write_b128 v100, v[122:125] offset:41472
	s_waitcnt vmcnt(8)
	ds_write_b128 v100, v[126:129] offset:59904
	ds_read_b128 v[122:125], v104 offset:64
	ds_read_b128 v[126:129], v104 offset:4672
	ds_read_b128 v[154:157], v101 offset:18496
	ds_read_b128 v[158:161], v101 offset:23104
	s_waitcnt lgkmcnt(7)
	v_mfma_f32_32x32x16_bf16 v[16:31], v[114:117], v[162:165], v[16:31]
	s_waitcnt lgkmcnt(6)
	v_mfma_f32_32x32x16_bf16 v[48:63], v[114:117], v[166:169], v[48:63]
	v_mfma_f32_32x32x16_bf16 v[0:15], v[118:121], v[162:165], v[0:15]
	v_mfma_f32_32x32x16_bf16 v[32:47], v[118:121], v[166:169], v[32:47]
	global_load_dwordx4 v[114:117], v[80:81], off offset:1280
	global_load_dwordx4 v[118:121], v[84:85], off offset:1280
	s_waitcnt vmcnt(9)
	ds_write_b128 v100, v[130:133] offset:46080
	s_waitcnt vmcnt(8)
	ds_write_b128 v100, v[134:137] offset:64512
	ds_read_b128 v[130:133], v104 offset:96
	ds_read_b128 v[134:137], v104 offset:4704
	ds_read_b128 v[162:165], v101 offset:18528
	ds_read_b128 v[166:169], v101 offset:23136
	s_waitcnt lgkmcnt(7)
	v_mfma_f32_32x32x16_bf16 v[16:31], v[122:125], v[154:157], v[16:31]
	s_waitcnt lgkmcnt(6)
	v_mfma_f32_32x32x16_bf16 v[48:63], v[122:125], v[158:161], v[48:63]
	v_mfma_f32_32x32x16_bf16 v[0:15], v[126:129], v[154:157], v[0:15]
	v_mfma_f32_32x32x16_bf16 v[32:47], v[126:129], v[158:161], v[32:47]
	global_load_dwordx4 v[122:125], v[88:89], off offset:1280
	global_load_dwordx4 v[126:129], v[92:93], off offset:1280
	s_waitcnt vmcnt(9)
	ds_write_b128 v100, v[146:149] offset:50688
	s_waitcnt vmcnt(8)
	ds_write_b128 v105, v[150:153] offset:13824
	s_waitcnt lgkmcnt(3)
	v_mfma_f32_32x32x16_bf16 v[16:31], v[130:133], v[162:165], v[16:31]
	s_waitcnt lgkmcnt(2)
	v_mfma_f32_32x32x16_bf16 v[48:63], v[130:133], v[166:169], v[48:63]
	v_mfma_f32_32x32x16_bf16 v[0:15], v[134:137], v[162:165], v[0:15]
	v_mfma_f32_32x32x16_bf16 v[32:47], v[134:137], v[166:169], v[32:47]
	s_waitcnt lgkmcnt(0)
	s_barrier
; __device__ __forceinline__ void gemm_run(int tid, f32x16 (&acc)[2][2], GRegs& g, const GOp& o, int K, unsigned char* smem) {
;     ...
;   for (int k = 0; k < nk; k++) {
;     bf16r* cur = sbuf + (k & 1) * (256 * LDK);
;     bf16r* nxt = sbuf + ((k & 1) ^ 1) * (256 * LDK);
;     const bf16r* As = cur + (wm * 64 + fr) * LDK + fh * 8;
;     const bf16r* Bs = cur + 128 * LDK + (wn * 64 + fr) * LDK + fh * 8;
;     const bool wr = (k + 1 < nk), ld = (k + 2 < nk);
;     bf16x8 fa[2][2], fb[2][2];
;     fa[0][0] = *(const bf16x8*)(As);
;     fa[0][1] = *(const bf16x8*)(As + 32 * LDK);
;     fb[0][0] = *(const bf16x8*)(Bs);
;     fb[0][1] = *(const bf16x8*)(Bs + 32 * LDK);
; #pragma unroll
;     for (int i = 0; i < 4; i++) {
;       if (wr) {
;         *(u32x4*)(nxt + (r0 + i * 32) * LDK + sg * 8) = g.a[i];
;         *(u32x4*)(nxt + 128 * LDK + (r0 + i * 32) * LDK + sg * 8) = g.b[i];
;       }
;       if (ld) {
;         g.a[i] = *(const u32x4*)(Ap + (size_t)i * 32 * o.lda + (k + 2) * 64);
;         g.b[i] = *(const u32x4*)(Bp + o.bs.o[i] + (k + 2) * 64);
;       }
;       if (i < 3) {
;         fa[(i + 1) & 1][0] = *(const bf16x8*)(As + (i + 1) * 16);
;         fa[(i + 1) & 1][1] = *(const bf16x8*)(As + 32 * LDK + (i + 1) * 16);
;         fb[(i + 1) & 1][0] = *(const bf16x8*)(Bs + (i + 1) * 16);
;         fb[(i + 1) & 1][1] = *(const bf16x8*)(Bs + 32 * LDK + (i + 1) * 16);
;       }
;       __builtin_amdgcn_sched_barrier(0);
;       __builtin_amdgcn_s_setprio(1);
;       acc[0][0] = __builtin_amdgcn_mfma_f32_32x32x16_bf16(fa[i & 1][0], fb[i & 1][0], acc[0][0], 0, 0, 0);
;       acc[0][1] = __builtin_amdgcn_mfma_f32_32x32x16_bf16(fa[i & 1][0], fb[i & 1][1], acc[0][1], 0, 0, 0);
;       acc[1][0] = __builtin_amdgcn_mfma_f32_32x32x16_bf16(fa[i & 1][1], fb[i & 1][0], acc[1][0], 0, 0, 0);
;       acc[1][1] = __builtin_amdgcn_mfma_f32_32x32x16_bf16(fa[i & 1][1], fb[i & 1][1], acc[1][1], 0, 0, 0);
;       __builtin_amdgcn_s_setprio(0);
;     }
;     __syncthreads();
;   }
	global_load_dwordx4 v[130:133], v[64:65], off offset:1408
	global_load_dwordx4 v[134:137], v[106:107], off offset:1408
	ds_read_b128 v[146:149], v104 offset:36864
	ds_read_b128 v[150:153], v104 offset:41472
	ds_read_b128 v[154:157], v101 offset:55296
	ds_read_b128 v[158:161], v101 offset:59904
	s_waitcnt vmcnt(9)
	ds_write_b128 v100, v[66:69]
	s_waitcnt vmcnt(8)
	ds_write_b128 v100, v[110:113] offset:18432
	ds_read_b128 v[66:69], v104 offset:36896
	ds_read_b128 v[110:113], v104 offset:41504
	ds_read_b128 v[162:165], v101 offset:55328
	ds_read_b128 v[166:169], v101 offset:59936
	s_waitcnt lgkmcnt(7)
	v_mfma_f32_32x32x16_bf16 v[16:31], v[146:149], v[154:157], v[16:31]
	s_waitcnt lgkmcnt(6)
	v_mfma_f32_32x32x16_bf16 v[48:63], v[146:149], v[158:161], v[48:63]
	v_mfma_f32_32x32x16_bf16 v[0:15], v[150:153], v[154:157], v[0:15]
	v_mfma_f32_32x32x16_bf16 v[32:47], v[150:153], v[158:161], v[32:47]
	global_load_dwordx4 v[146:149], v[72:73], off offset:1408
	global_load_dwordx4 v[150:153], v[76:77], off offset:1408
	s_waitcnt vmcnt(9)
	ds_write_b128 v100, v[138:141] offset:4608
	s_waitcnt vmcnt(8)
	ds_write_b128 v100, v[142:145] offset:23040
	ds_read_b128 v[138:141], v104 offset:36928
	ds_read_b128 v[142:145], v104 offset:41536
	ds_read_b128 v[154:157], v101 offset:55360
	ds_read_b128 v[158:161], v101 offset:59968
	s_waitcnt lgkmcnt(7)
	v_mfma_f32_32x32x16_bf16 v[16:31], v[66:69], v[162:165], v[16:31]
	s_waitcnt lgkmcnt(6)
	v_mfma_f32_32x32x16_bf16 v[48:63], v[66:69], v[166:169], v[48:63]
	v_mfma_f32_32x32x16_bf16 v[0:15], v[110:113], v[162:165], v[0:15]
	v_mfma_f32_32x32x16_bf16 v[32:47], v[110:113], v[166:169], v[32:47]
	global_load_dwordx4 v[66:69], v[80:81], off offset:1408
	global_load_dwordx4 v[110:113], v[84:85], off offset:1408
	s_waitcnt vmcnt(9)
	ds_write_b128 v100, v[114:117] offset:9216
	s_waitcnt vmcnt(8)
	ds_write_b128 v100, v[118:121] offset:27648
	ds_read_b128 v[114:117], v104 offset:36960
	ds_read_b128 v[118:121], v104 offset:41568
	ds_read_b128 v[162:165], v101 offset:55392
	ds_read_b128 v[166:169], v101 offset:60000
	s_waitcnt lgkmcnt(7)
	v_mfma_f32_32x32x16_bf16 v[16:31], v[138:141], v[154:157], v[16:31]
	s_waitcnt lgkmcnt(6)
	v_mfma_f32_32x32x16_bf16 v[48:63], v[138:141], v[158:161], v[48:63]
	v_mfma_f32_32x32x16_bf16 v[0:15], v[142:145], v[154:157], v[0:15]
	v_mfma_f32_32x32x16_bf16 v[32:47], v[142:145], v[158:161], v[32:47]
	global_load_dwordx4 v[138:141], v[88:89], off offset:1408
	global_load_dwordx4 v[142:145], v[92:93], off offset:1408
	s_waitcnt vmcnt(9)
	ds_write_b128 v100, v[122:125] offset:13824
	s_waitcnt vmcnt(8)
	ds_write_b128 v100, v[126:129] offset:32256
	s_waitcnt lgkmcnt(3)
	v_mfma_f32_32x32x16_bf16 v[16:31], v[114:117], v[162:165], v[16:31]
	s_waitcnt lgkmcnt(2)
	v_mfma_f32_32x32x16_bf16 v[48:63], v[114:117], v[166:169], v[48:63]
	v_mfma_f32_32x32x16_bf16 v[0:15], v[118:121], v[162:165], v[0:15]
	v_mfma_f32_32x32x16_bf16 v[32:47], v[118:121], v[166:169], v[32:47]
	s_waitcnt lgkmcnt(0)
	s_barrier
	global_load_dwordx4 v[114:117], v[64:65], off offset:1536
	global_load_dwordx4 v[118:121], v[106:107], off offset:1536
	ds_read_b128 v[122:125], v104
	ds_read_b128 v[126:129], v104 offset:4608
	ds_read_b128 v[154:157], v101 offset:18432
	ds_read_b128 v[158:161], v101 offset:23040
	s_waitcnt vmcnt(9)
	ds_write_b128 v100, v[130:133] offset:36864
	s_waitcnt vmcnt(8)
	ds_write_b128 v100, v[134:137] offset:55296
	ds_read_b128 v[130:133], v104 offset:32
	ds_read_b128 v[134:137], v104 offset:4640
	ds_read_b128 v[162:165], v101 offset:18464
	ds_read_b128 v[166:169], v101 offset:23072
	s_waitcnt lgkmcnt(7)
	v_mfma_f32_32x32x16_bf16 v[16:31], v[122:125], v[154:157], v[16:31]
	s_waitcnt lgkmcnt(6)
	v_mfma_f32_32x32x16_bf16 v[48:63], v[122:125], v[158:161], v[48:63]
	v_mfma_f32_32x32x16_bf16 v[0:15], v[126:129], v[154:157], v[0:15]
	v_mfma_f32_32x32x16_bf16 v[32:47], v[126:129], v[158:161], v[32:47]
	global_load_dwordx4 v[122:125], v[72:73], off offset:1536
	global_load_dwordx4 v[126:129], v[76:77], off offset:1536
	s_waitcnt vmcnt(9)
	ds_write_b128 v100, v[146:149] offset:41472
	s_waitcnt vmcnt(8)
	ds_write_b128 v100, v[150:153] offset:59904
	ds_read_b128 v[146:149], v104 offset:64
	ds_read_b128 v[150:153], v104 offset:4672
	ds_read_b128 v[154:157], v101 offset:18496
	ds_read_b128 v[158:161], v101 offset:23104
	s_waitcnt lgkmcnt(7)
	v_mfma_f32_32x32x16_bf16 v[16:31], v[130:133], v[162:165], v[16:31]
	s_waitcnt lgkmcnt(6)
	v_mfma_f32_32x32x16_bf16 v[48:63], v[130:133], v[166:169], v[48:63]
	v_mfma_f32_32x32x16_bf16 v[0:15], v[134:137], v[162:165], v[0:15]
	v_mfma_f32_32x32x16_bf16 v[32:47], v[134:137], v[166:169], v[32:47]
	global_load_dwordx4 v[130:133], v[80:81], off offset:1536
	global_load_dwordx4 v[134:137], v[84:85], off offset:1536
	s_waitcnt vmcnt(9)
	ds_write_b128 v100, v[66:69] offset:46080
	s_waitcnt vmcnt(8)
	ds_write_b128 v100, v[110:113] offset:64512
	ds_read_b128 v[66:69], v104 offset:96
	ds_read_b128 v[110:113], v104 offset:4704
	ds_read_b128 v[162:165], v101 offset:18528
	ds_read_b128 v[166:169], v101 offset:23136
	s_waitcnt lgkmcnt(7)
	v_mfma_f32_32x32x16_bf16 v[16:31], v[146:149], v[154:157], v[16:31]
	s_waitcnt lgkmcnt(6)
	v_mfma_f32_32x32x16_bf16 v[48:63], v[146:149], v[158:161], v[48:63]
	v_mfma_f32_32x32x16_bf16 v[0:15], v[150:153], v[154:157], v[0:15]
	v_mfma_f32_32x32x16_bf16 v[32:47], v[150:153], v[158:161], v[32:47]
	global_load_dwordx4 v[146:149], v[88:89], off offset:1536
	global_load_dwordx4 v[150:153], v[92:93], off offset:1536
	s_waitcnt vmcnt(9)
	ds_write_b128 v100, v[138:141] offset:50688
	s_waitcnt vmcnt(8)
	ds_write_b128 v105, v[142:145] offset:13824
	s_waitcnt lgkmcnt(3)
	v_mfma_f32_32x32x16_bf16 v[16:31], v[66:69], v[162:165], v[16:31]
	s_waitcnt lgkmcnt(2)
	v_mfma_f32_32x32x16_bf16 v[48:63], v[66:69], v[166:169], v[48:63]
	v_mfma_f32_32x32x16_bf16 v[0:15], v[110:113], v[162:165], v[0:15]
	v_mfma_f32_32x32x16_bf16 v[32:47], v[110:113], v[166:169], v[32:47]
	s_waitcnt lgkmcnt(0)
	s_barrier
; __device__ __forceinline__ void gemm_run(int tid, f32x16 (&acc)[2][2], GRegs& g, const GOp& o, int K, unsigned char* smem) {
;     ...
;   for (int k = 0; k < nk; k++) {
;     bf16r* cur = sbuf + (k & 1) * (256 * LDK);
;     bf16r* nxt = sbuf + ((k & 1) ^ 1) * (256 * LDK);
;     const bf16r* As = cur + (wm * 64 + fr) * LDK + fh * 8;
;     const bf16r* Bs = cur + 128 * LDK + (wn * 64 + fr) * LDK + fh * 8;
;     const bool wr = (k + 1 < nk), ld = (k + 2 < nk);
;     bf16x8 fa[2][2], fb[2][2];
;     fa[0][0] = *(const bf16x8*)(As);
;     fa[0][1] = *(const bf16x8*)(As + 32 * LDK);
;     fb[0][0] = *(const bf16x8*)(Bs);
;     fb[0][1] = *(const bf16x8*)(Bs + 32 * LDK);
; #pragma unroll
;     for (int i = 0; i < 4; i++) {
;       if (wr) {
;         *(u32x4*)(nxt + (r0 + i * 32) * LDK + sg * 8) = g.a[i];
;         *(u32x4*)(nxt + 128 * LDK + (r0 + i * 32) * LDK + sg * 8) = g.b[i];
;       }
;       if (ld) {
;         g.a[i] = *(const u32x4*)(Ap + (size_t)i * 32 * o.lda + (k + 2) * 64);
;         g.b[i] = *(const u32x4*)(Bp + o.bs.o[i] + (k + 2) * 64);
;       }
;       if (i < 3) {
;         fa[(i + 1) & 1][0] = *(const bf16x8*)(As + (i + 1) * 16);
;         fa[(i + 1) & 1][1] = *(const bf16x8*)(As + 32 * LDK + (i + 1) * 16);
;         fb[(i + 1) & 1][0] = *(const bf16x8*)(Bs + (i + 1) * 16);
;         fb[(i + 1) & 1][1] = *(const bf16x8*)(Bs + 32 * LDK + (i + 1) * 16);
;       }
;       __builtin_amdgcn_sched_barrier(0);
;       __builtin_amdgcn_s_setprio(1);
;       acc[0][0] = __builtin_amdgcn_mfma_f32_32x32x16_bf16(fa[i & 1][0], fb[i & 1][0], acc[0][0], 0, 0, 0);
;       acc[0][1] = __builtin_amdgcn_mfma_f32_32x32x16_bf16(fa[i & 1][0], fb[i & 1][1], acc[0][1], 0, 0, 0);
;       acc[1][0] = __builtin_amdgcn_mfma_f32_32x32x16_bf16(fa[i & 1][1], fb[i & 1][0], acc[1][0], 0, 0, 0);
;       acc[1][1] = __builtin_amdgcn_mfma_f32_32x32x16_bf16(fa[i & 1][1], fb[i & 1][1], acc[1][1], 0, 0, 0);
;       __builtin_amdgcn_s_setprio(0);
;     }
;     __syncthreads();
;   }
	global_load_dwordx4 v[66:69], v[64:65], off offset:1664
	global_load_dwordx4 v[110:113], v[106:107], off offset:1664
	ds_read_b128 v[138:141], v104 offset:36864
	ds_read_b128 v[142:145], v104 offset:41472
	ds_read_b128 v[154:157], v101 offset:55296
	ds_read_b128 v[158:161], v101 offset:59904
	s_waitcnt vmcnt(9)
	ds_write_b128 v100, v[114:117]
	s_waitcnt vmcnt(8)
	ds_write_b128 v100, v[118:121] offset:18432
	ds_read_b128 v[114:117], v104 offset:36896
	ds_read_b128 v[118:121], v104 offset:41504
	ds_read_b128 v[162:165], v101 offset:55328
	ds_read_b128 v[166:169], v101 offset:59936
	s_waitcnt lgkmcnt(7)
	v_mfma_f32_32x32x16_bf16 v[16:31], v[138:141], v[154:157], v[16:31]
	s_waitcnt lgkmcnt(6)
	v_mfma_f32_32x32x16_bf16 v[48:63], v[138:141], v[158:161], v[48:63]
	v_mfma_f32_32x32x16_bf16 v[0:15], v[142:145], v[154:157], v[0:15]
	v_mfma_f32_32x32x16_bf16 v[32:47], v[142:145], v[158:161], v[32:47]
	global_load_dwordx4 v[138:141], v[72:73], off offset:1664
	global_load_dwordx4 v[142:145], v[76:77], off offset:1664
	s_waitcnt vmcnt(9)
	ds_write_b128 v100, v[122:125] offset:4608
	s_waitcnt vmcnt(8)
	ds_write_b128 v100, v[126:129] offset:23040
	ds_read_b128 v[122:125], v104 offset:36928
	ds_read_b128 v[126:129], v104 offset:41536
	ds_read_b128 v[154:157], v101 offset:55360
	ds_read_b128 v[158:161], v101 offset:59968
	s_waitcnt lgkmcnt(7)
	v_mfma_f32_32x32x16_bf16 v[16:31], v[114:117], v[162:165], v[16:31]
	s_waitcnt lgkmcnt(6)
	v_mfma_f32_32x32x16_bf16 v[48:63], v[114:117], v[166:169], v[48:63]
	v_mfma_f32_32x32x16_bf16 v[0:15], v[118:121], v[162:165], v[0:15]
	v_mfma_f32_32x32x16_bf16 v[32:47], v[118:121], v[166:169], v[32:47]
	global_load_dwordx4 v[114:117], v[80:81], off offset:1664
	global_load_dwordx4 v[118:121], v[84:85], off offset:1664
	s_waitcnt vmcnt(9)
	ds_write_b128 v100, v[130:133] offset:9216
	s_waitcnt vmcnt(8)
	ds_write_b128 v100, v[134:137] offset:27648
	ds_read_b128 v[130:133], v104 offset:36960
	ds_read_b128 v[134:137], v104 offset:41568
	ds_read_b128 v[162:165], v101 offset:55392
	ds_read_b128 v[166:169], v101 offset:60000
	s_waitcnt lgkmcnt(7)
	v_mfma_f32_32x32x16_bf16 v[16:31], v[122:125], v[154:157], v[16:31]
	s_waitcnt lgkmcnt(6)
	v_mfma_f32_32x32x16_bf16 v[48:63], v[122:125], v[158:161], v[48:63]
	v_mfma_f32_32x32x16_bf16 v[0:15], v[126:129], v[154:157], v[0:15]
	v_mfma_f32_32x32x16_bf16 v[32:47], v[126:129], v[158:161], v[32:47]
	global_load_dwordx4 v[122:125], v[88:89], off offset:1664
	global_load_dwordx4 v[126:129], v[92:93], off offset:1664
	s_waitcnt vmcnt(9)
	ds_write_b128 v100, v[146:149] offset:13824
	s_waitcnt vmcnt(8)
	ds_write_b128 v100, v[150:153] offset:32256
	s_waitcnt lgkmcnt(3)
	v_mfma_f32_32x32x16_bf16 v[16:31], v[130:133], v[162:165], v[16:31]
	s_waitcnt lgkmcnt(2)
	v_mfma_f32_32x32x16_bf16 v[48:63], v[130:133], v[166:169], v[48:63]
	v_mfma_f32_32x32x16_bf16 v[0:15], v[134:137], v[162:165], v[0:15]
	v_mfma_f32_32x32x16_bf16 v[32:47], v[134:137], v[166:169], v[32:47]
	s_waitcnt lgkmcnt(0)
	s_barrier
	global_load_dwordx4 v[130:133], v[64:65], off offset:1792
	global_load_dwordx4 v[134:137], v[106:107], off offset:1792
	ds_read_b128 v[146:149], v104
	ds_read_b128 v[150:153], v104 offset:4608
	ds_read_b128 v[154:157], v101 offset:18432
	ds_read_b128 v[158:161], v101 offset:23040
	s_waitcnt vmcnt(9)
	ds_write_b128 v100, v[66:69] offset:36864
	s_waitcnt vmcnt(8)
	ds_write_b128 v100, v[110:113] offset:55296
	ds_read_b128 v[66:69], v104 offset:32
	ds_read_b128 v[110:113], v104 offset:4640
	ds_read_b128 v[162:165], v101 offset:18464
	ds_read_b128 v[166:169], v101 offset:23072
	s_waitcnt lgkmcnt(7)
	v_mfma_f32_32x32x16_bf16 v[16:31], v[146:149], v[154:157], v[16:31]
	s_waitcnt lgkmcnt(6)
	v_mfma_f32_32x32x16_bf16 v[48:63], v[146:149], v[158:161], v[48:63]
	v_mfma_f32_32x32x16_bf16 v[0:15], v[150:153], v[154:157], v[0:15]
	v_mfma_f32_32x32x16_bf16 v[32:47], v[150:153], v[158:161], v[32:47]
	global_load_dwordx4 v[146:149], v[72:73], off offset:1792
	global_load_dwordx4 v[150:153], v[76:77], off offset:1792
	s_waitcnt vmcnt(9)
	ds_write_b128 v100, v[138:141] offset:41472
	s_waitcnt vmcnt(8)
	ds_write_b128 v100, v[142:145] offset:59904
	ds_read_b128 v[138:141], v104 offset:64
	ds_read_b128 v[142:145], v104 offset:4672
	ds_read_b128 v[154:157], v101 offset:18496
	ds_read_b128 v[158:161], v101 offset:23104
	s_waitcnt lgkmcnt(7)
	v_mfma_f32_32x32x16_bf16 v[16:31], v[66:69], v[162:165], v[16:31]
	s_waitcnt lgkmcnt(6)
	v_mfma_f32_32x32x16_bf16 v[48:63], v[66:69], v[166:169], v[48:63]
	v_mfma_f32_32x32x16_bf16 v[0:15], v[110:113], v[162:165], v[0:15]
	v_mfma_f32_32x32x16_bf16 v[32:47], v[110:113], v[166:169], v[32:47]
	global_load_dwordx4 v[110:113], v[80:81], off offset:1792
	global_load_dwordx4 v[162:165], v[84:85], off offset:1792
	s_waitcnt vmcnt(9)
	ds_write_b128 v100, v[114:117] offset:46080
	s_waitcnt vmcnt(8)
	ds_write_b128 v100, v[118:121] offset:64512
	ds_read_b128 v[66:69], v104 offset:96
	ds_read_b128 v[114:117], v104 offset:4704
	ds_read_b128 v[118:121], v101 offset:18528
	ds_read_b128 v[166:169], v101 offset:23136
	s_waitcnt lgkmcnt(7)
	v_mfma_f32_32x32x16_bf16 v[16:31], v[138:141], v[154:157], v[16:31]
	s_waitcnt lgkmcnt(6)
	v_mfma_f32_32x32x16_bf16 v[48:63], v[138:141], v[158:161], v[48:63]
	v_mfma_f32_32x32x16_bf16 v[0:15], v[142:145], v[154:157], v[0:15]
	v_mfma_f32_32x32x16_bf16 v[32:47], v[142:145], v[158:161], v[32:47]
	global_load_dwordx4 v[138:141], v[88:89], off offset:1792
	global_load_dwordx4 v[142:145], v[92:93], off offset:1792
	s_waitcnt vmcnt(9)
	ds_write_b128 v100, v[122:125] offset:50688
	s_waitcnt vmcnt(8)
	ds_write_b128 v105, v[126:129] offset:13824
	s_waitcnt lgkmcnt(3)
	v_mfma_f32_32x32x16_bf16 v[16:31], v[66:69], v[118:121], v[16:31]
	s_waitcnt lgkmcnt(2)
	v_mfma_f32_32x32x16_bf16 v[48:63], v[66:69], v[166:169], v[48:63]
	v_mfma_f32_32x32x16_bf16 v[0:15], v[114:117], v[118:121], v[0:15]
	v_mfma_f32_32x32x16_bf16 v[32:47], v[114:117], v[166:169], v[32:47]
	s_waitcnt lgkmcnt(0)
	s_barrier
; __device__ __forceinline__ void gemm_run(int tid, f32x16 (&acc)[2][2], GRegs& g, const GOp& o, int K, unsigned char* smem) {
;     ...
;   for (int k = 0; k < nk; k++) {
;     bf16r* cur = sbuf + (k & 1) * (256 * LDK);
;     bf16r* nxt = sbuf + ((k & 1) ^ 1) * (256 * LDK);
;     const bf16r* As = cur + (wm * 64 + fr) * LDK + fh * 8;
;     const bf16r* Bs = cur + 128 * LDK + (wn * 64 + fr) * LDK + fh * 8;
;     const bool wr = (k + 1 < nk), ld = (k + 2 < nk);
;     bf16x8 fa[2][2], fb[2][2];
;     fa[0][0] = *(const bf16x8*)(As);
;     fa[0][1] = *(const bf16x8*)(As + 32 * LDK);
;     fb[0][0] = *(const bf16x8*)(Bs);
;     fb[0][1] = *(const bf16x8*)(Bs + 32 * LDK);
; #pragma unroll
;     for (int i = 0; i < 4; i++) {
;       if (wr) {
;         *(u32x4*)(nxt + (r0 + i * 32) * LDK + sg * 8) = g.a[i];
;         *(u32x4*)(nxt + 128 * LDK + (r0 + i * 32) * LDK + sg * 8) = g.b[i];
;       }
;       if (ld) {
;         g.a[i] = *(const u32x4*)(Ap + (size_t)i * 32 * o.lda + (k + 2) * 64);
;         g.b[i] = *(const u32x4*)(Bp + o.bs.o[i] + (k + 2) * 64);
;       }
;       if (i < 3) {
;         fa[(i + 1) & 1][0] = *(const bf16x8*)(As + (i + 1) * 16);
;         fa[(i + 1) & 1][1] = *(const bf16x8*)(As + 32 * LDK + (i + 1) * 16);
;         fb[(i + 1) & 1][0] = *(const bf16x8*)(Bs + (i + 1) * 16);
;         fb[(i + 1) & 1][1] = *(const bf16x8*)(Bs + 32 * LDK + (i + 1) * 16);
;       }
;       __builtin_amdgcn_sched_barrier(0);
;       __builtin_amdgcn_s_setprio(1);
;       acc[0][0] = __builtin_amdgcn_mfma_f32_32x32x16_bf16(fa[i & 1][0], fb[i & 1][0], acc[0][0], 0, 0, 0);
;       acc[0][1] = __builtin_amdgcn_mfma_f32_32x32x16_bf16(fa[i & 1][0], fb[i & 1][1], acc[0][1], 0, 0, 0);
;       acc[1][0] = __builtin_amdgcn_mfma_f32_32x32x16_bf16(fa[i & 1][1], fb[i & 1][0], acc[1][0], 0, 0, 0);
;       acc[1][1] = __builtin_amdgcn_mfma_f32_32x32x16_bf16(fa[i & 1][1], fb[i & 1][1], acc[1][1], 0, 0, 0);
;       __builtin_amdgcn_s_setprio(0);
;     }
;     __syncthreads();
;   }
	global_load_dwordx4 v[64:67], v[64:65], off offset:1920
	s_nop 0
	global_load_dwordx4 v[68:71], v[106:107], off offset:1920
	ds_read_b128 v[114:117], v104 offset:36864
	ds_read_b128 v[118:121], v104 offset:41472
	ds_read_b128 v[122:125], v101 offset:55296
	ds_read_b128 v[126:129], v101 offset:59904
	s_waitcnt vmcnt(9)
	ds_write_b128 v100, v[130:133]
	s_waitcnt vmcnt(8)
	ds_write_b128 v100, v[134:137] offset:18432
	ds_read_b128 v[130:133], v104 offset:36896
	ds_read_b128 v[134:137], v104 offset:41504
	ds_read_b128 v[154:157], v101 offset:55328
	ds_read_b128 v[158:161], v101 offset:59936
	s_waitcnt lgkmcnt(7)
	v_mfma_f32_32x32x16_bf16 v[16:31], v[114:117], v[122:125], v[16:31]
	s_waitcnt lgkmcnt(6)
	v_mfma_f32_32x32x16_bf16 v[48:63], v[114:117], v[126:129], v[48:63]
	v_mfma_f32_32x32x16_bf16 v[0:15], v[118:121], v[122:125], v[0:15]
	v_mfma_f32_32x32x16_bf16 v[32:47], v[118:121], v[126:129], v[32:47]
	global_load_dwordx4 v[72:75], v[72:73], off offset:1920
	s_nop 0
	global_load_dwordx4 v[76:79], v[76:77], off offset:1920
	s_waitcnt vmcnt(9)
	ds_write_b128 v100, v[146:149] offset:4608
	s_waitcnt vmcnt(8)
	ds_write_b128 v100, v[150:153] offset:23040
	ds_read_b128 v[114:117], v104 offset:36928
	ds_read_b128 v[118:121], v104 offset:41536
	ds_read_b128 v[122:125], v101 offset:55360
	ds_read_b128 v[126:129], v101 offset:59968
	s_waitcnt lgkmcnt(7)
	v_mfma_f32_32x32x16_bf16 v[16:31], v[130:133], v[154:157], v[16:31]
	s_waitcnt lgkmcnt(6)
	v_mfma_f32_32x32x16_bf16 v[48:63], v[130:133], v[158:161], v[48:63]
	v_mfma_f32_32x32x16_bf16 v[0:15], v[134:137], v[154:157], v[0:15]
	v_mfma_f32_32x32x16_bf16 v[32:47], v[134:137], v[158:161], v[32:47]
	global_load_dwordx4 v[80:83], v[80:81], off offset:1920
	s_nop 0
	global_load_dwordx4 v[84:87], v[84:85], off offset:1920
	s_waitcnt vmcnt(9)
	ds_write_b128 v100, v[110:113] offset:9216
	s_waitcnt vmcnt(8)
	ds_write_b128 v100, v[162:165] offset:27648
	ds_read_b128 v[110:113], v104 offset:36960
	ds_read_b128 v[130:133], v104 offset:41568
	ds_read_b128 v[134:137], v101 offset:55392
	ds_read_b128 v[146:149], v101 offset:60000
	s_waitcnt lgkmcnt(7)
	v_mfma_f32_32x32x16_bf16 v[16:31], v[114:117], v[122:125], v[16:31]
	s_waitcnt lgkmcnt(6)
	v_mfma_f32_32x32x16_bf16 v[48:63], v[114:117], v[126:129], v[48:63]
	v_mfma_f32_32x32x16_bf16 v[0:15], v[118:121], v[122:125], v[0:15]
	v_mfma_f32_32x32x16_bf16 v[32:47], v[118:121], v[126:129], v[32:47]
	global_load_dwordx4 v[88:91], v[88:89], off offset:1920
	s_nop 0
	global_load_dwordx4 v[92:95], v[92:93], off offset:1920
	s_waitcnt vmcnt(9)
	ds_write_b128 v100, v[138:141] offset:13824
	s_waitcnt vmcnt(8)
	ds_write_b128 v100, v[142:145] offset:32256
	s_waitcnt lgkmcnt(3)
	v_mfma_f32_32x32x16_bf16 v[16:31], v[110:113], v[134:137], v[16:31]
	s_waitcnt lgkmcnt(2)
	v_mfma_f32_32x32x16_bf16 v[48:63], v[110:113], v[146:149], v[48:63]
	v_mfma_f32_32x32x16_bf16 v[0:15], v[130:133], v[134:137], v[0:15]
	v_mfma_f32_32x32x16_bf16 v[32:47], v[130:133], v[146:149], v[32:47]
	s_waitcnt lgkmcnt(0)
	s_barrier
; __device__ __forceinline__ void gemm_run(int tid, f32x16 (&acc)[2][2], GRegs& g, const GOp& o, int K, unsigned char* smem) {
;     ...
;     fa[0][0] = *(const bf16x8*)(As);
;     fa[0][1] = *(const bf16x8*)(As + 32 * LDK);
;     fb[0][0] = *(const bf16x8*)(Bs);
;     fb[0][1] = *(const bf16x8*)(Bs + 32 * LDK);
; #pragma unroll
;     for (int i = 0; i < 4; i++) {
;       if (wr) {
;         *(u32x4*)(nxt + (r0 + i * 32) * LDK + sg * 8) = g.a[i];
;         *(u32x4*)(nxt + 128 * LDK + (r0 + i * 32) * LDK + sg * 8) = g.b[i];
;       }
;       if (ld) {
;         g.a[i] = *(const u32x4*)(Ap + (size_t)i * 32 * o.lda + (k + 2) * 64);
;         g.b[i] = *(const u32x4*)(Bp + o.bs.o[i] + (k + 2) * 64);
;       }
;       if (i < 3) {
;         fa[(i + 1) & 1][0] = *(const bf16x8*)(As + (i + 1) * 16);
;         fa[(i + 1) & 1][1] = *(const bf16x8*)(As + 32 * LDK + (i + 1) * 16);
;         fb[(i + 1) & 1][0] = *(const bf16x8*)(Bs + (i + 1) * 16);
;         fb[(i + 1) & 1][1] = *(const bf16x8*)(Bs + 32 * LDK + (i + 1) * 16);
;       }
;       __builtin_amdgcn_sched_barrier(0);
;       __builtin_amdgcn_s_setprio(1);
;       acc[0][0] = __builtin_amdgcn_mfma_f32_32x32x16_bf16(fa[i & 1][0], fb[i & 1][0], acc[0][0], 0, 0, 0);
;       acc[0][1] = __builtin_amdgcn_mfma_f32_32x32x16_bf16(fa[i & 1][0], fb[i & 1][1], acc[0][1], 0, 0, 0);
;       acc[1][0] = __builtin_amdgcn_mfma_f32_32x32x16_bf16(fa[i & 1][1], fb[i & 1][0], acc[1][0], 0, 0, 0);
;       acc[1][1] = __builtin_amdgcn_mfma_f32_32x32x16_bf16(fa[i & 1][1], fb[i & 1][1], acc[1][1], 0, 0, 0);
;       __builtin_amdgcn_s_setprio(0);
;     }
;     __syncthreads();
;   }
; __device__ __forceinline__ bool tile_map(int it, int nn, int& mt, int& nt) {
;   const int xcd = blockIdx.x & 7, li = blockIdx.x >> 3, nb = gridDim.x >> 3;
;   int q = it * nb + li;
;   const int per = 16 * nn;
;   if (q < per) {
;     int sub = q / (8 * nn), r = q - sub * (8 * nn);
;     nt = r >> 3;
;     mt = xcd * 16 + sub * 8 + (r & 7);
;     return true;
;   }
;   q -= per;
;   int n = q * 8 + xcd;
;   if (n < nn) { mt = 128; nt = n; return true; }
	ds_read_b128 v[110:113], v104
	ds_read_b128 v[114:117], v104 offset:4608
	ds_read_b128 v[118:121], v101 offset:18432
	ds_read_b128 v[122:125], v101 offset:23040
	s_waitcnt vmcnt(7)
	ds_write_b128 v100, v[64:67] offset:36864
	s_waitcnt vmcnt(6)
	ds_write_b128 v100, v[68:71] offset:55296
	ds_read_b128 v[126:129], v104 offset:32
	ds_read_b128 v[130:133], v104 offset:4640
	ds_read_b128 v[134:137], v101 offset:18464
	ds_read_b128 v[138:141], v101 offset:23072
	s_waitcnt lgkmcnt(7)
	v_mfma_f32_32x32x16_bf16 v[16:31], v[110:113], v[118:121], v[16:31]
	s_waitcnt lgkmcnt(6)
	v_mfma_f32_32x32x16_bf16 v[48:63], v[110:113], v[122:125], v[48:63]
	v_mfma_f32_32x32x16_bf16 v[0:15], v[114:117], v[118:121], v[0:15]
	v_mfma_f32_32x32x16_bf16 v[32:47], v[114:117], v[122:125], v[32:47]
	s_waitcnt vmcnt(5)
	ds_write_b128 v100, v[72:75] offset:41472
	s_waitcnt vmcnt(4)
	ds_write_b128 v100, v[76:79] offset:59904
	ds_read_b128 v[110:113], v104 offset:64
	ds_read_b128 v[114:117], v104 offset:4672
	ds_read_b128 v[118:121], v101 offset:18496
	ds_read_b128 v[122:125], v101 offset:23104
	s_waitcnt lgkmcnt(7)
	v_mfma_f32_32x32x16_bf16 v[16:31], v[126:129], v[134:137], v[16:31]
	s_waitcnt lgkmcnt(6)
	v_mfma_f32_32x32x16_bf16 v[48:63], v[126:129], v[138:141], v[48:63]
	v_mfma_f32_32x32x16_bf16 v[0:15], v[130:133], v[134:137], v[0:15]
	v_mfma_f32_32x32x16_bf16 v[32:47], v[130:133], v[138:141], v[32:47]
	s_waitcnt vmcnt(3)
	ds_write_b128 v100, v[80:83] offset:46080
	s_waitcnt vmcnt(2)
	ds_write_b128 v100, v[84:87] offset:64512
	ds_read_b128 v[126:129], v104 offset:96
	ds_read_b128 v[130:133], v104 offset:4704
	ds_read_b128 v[134:137], v101 offset:18528
	ds_read_b128 v[138:141], v101 offset:23136
	s_waitcnt lgkmcnt(7)
	v_mfma_f32_32x32x16_bf16 v[16:31], v[110:113], v[118:121], v[16:31]
	s_waitcnt lgkmcnt(6)
	v_mfma_f32_32x32x16_bf16 v[48:63], v[110:113], v[122:125], v[48:63]
	v_mfma_f32_32x32x16_bf16 v[0:15], v[114:117], v[118:121], v[0:15]
	v_mfma_f32_32x32x16_bf16 v[32:47], v[114:117], v[122:125], v[32:47]
	s_waitcnt vmcnt(1)
	ds_write_b128 v100, v[88:91] offset:50688
	s_waitcnt vmcnt(0)
	ds_write_b128 v105, v[92:95] offset:13824
	s_waitcnt lgkmcnt(3)
	v_mfma_f32_32x32x16_bf16 v[16:31], v[126:129], v[134:137], v[16:31]
	s_waitcnt lgkmcnt(2)
	v_mfma_f32_32x32x16_bf16 v[48:63], v[126:129], v[138:141], v[48:63]
	v_mfma_f32_32x32x16_bf16 v[0:15], v[130:133], v[134:137], v[0:15]
	v_mfma_f32_32x32x16_bf16 v[32:47], v[130:133], v[138:141], v[32:47]
	s_waitcnt lgkmcnt(0)
	s_barrier
	ds_read_b128 v[110:113], v104 offset:36864
	ds_read_b128 v[114:117], v104 offset:36896
	ds_read_b128 v[118:121], v104 offset:41472
	ds_read_b128 v[122:125], v104 offset:41504
	ds_read_b128 v[126:129], v101 offset:55296
	ds_read_b128 v[130:133], v101 offset:55328
	ds_read_b128 v[134:137], v101 offset:59904
	ds_read_b128 v[138:141], v101 offset:59936
	s_waitcnt lgkmcnt(3)
	v_mfma_f32_32x32x16_bf16 v[16:31], v[110:113], v[126:129], v[16:31]
	s_waitcnt lgkmcnt(1)
	v_mfma_f32_32x32x16_bf16 v[48:63], v[110:113], v[134:137], v[48:63]
	v_mfma_f32_32x32x16_bf16 v[0:15], v[118:121], v[126:129], v[0:15]
	v_mfma_f32_32x32x16_bf16 v[32:47], v[118:121], v[134:137], v[32:47]
	ds_read_b128 v[110:113], v104 offset:36928
	ds_read_b128 v[118:121], v104 offset:41536
	ds_read_b128 v[126:129], v101 offset:55360
	ds_read_b128 v[134:137], v101 offset:59968
	v_mfma_f32_32x32x16_bf16 v[16:31], v[114:117], v[130:133], v[16:31]
	s_waitcnt lgkmcnt(4)
	v_mfma_f32_32x32x16_bf16 v[48:63], v[114:117], v[138:141], v[48:63]
	v_mfma_f32_32x32x16_bf16 v[0:15], v[122:125], v[130:133], v[0:15]
	v_mfma_f32_32x32x16_bf16 v[32:47], v[122:125], v[138:141], v[32:47]
	ds_read_b128 v[114:117], v104 offset:36960
	ds_read_b128 v[122:125], v104 offset:41568
	ds_read_b128 v[130:133], v101 offset:55392
	ds_read_b128 v[138:141], v101 offset:60000
	s_waitcnt lgkmcnt(5)
	v_mfma_f32_32x32x16_bf16 v[16:31], v[110:113], v[126:129], v[16:31]
	s_waitcnt lgkmcnt(4)
	v_mfma_f32_32x32x16_bf16 v[48:63], v[110:113], v[134:137], v[48:63]
	v_mfma_f32_32x32x16_bf16 v[0:15], v[118:121], v[126:129], v[0:15]
	v_mfma_f32_32x32x16_bf16 v[32:47], v[118:121], v[134:137], v[32:47]
	s_waitcnt lgkmcnt(1)
	v_mfma_f32_32x32x16_bf16 v[16:31], v[114:117], v[130:133], v[16:31]
	s_waitcnt lgkmcnt(0)
	v_mfma_f32_32x32x16_bf16 v[48:63], v[114:117], v[138:141], v[48:63]
	v_mfma_f32_32x32x16_bf16 v[0:15], v[122:125], v[130:133], v[0:15]
	v_mfma_f32_32x32x16_bf16 v[32:47], v[122:125], v[138:141], v[32:47]
	s_cmpk_gt_u32 s85, 0x1ff
	s_mov_b64 s[10:11], -1
	s_barrier
	s_cbranch_scc0 .LBB0_4486
	s_mov_b64 s[10:11], 0
	s_cmp_gt_i32 s76, 31
	s_mov_b64 s[4:5], 0
	s_cbranch_scc1 .LBB0_4486
	s_movk_i32 s62, 0x80
	s_mov_b64 s[4:5], -1
	s_mov_b32 s90, s76

; __device__ __forceinline__ void gemm_run(int tid, f32x16 (&acc)[2][2], GRegs& g, const GOp& o, int K, unsigned char* smem) {
;   bf16r* sbuf = (bf16r*)smem;
;   const int w = tid >> 6, wm = w >> 1, wn = w & 1;
;   const int r0 = tid >> 3, sg = tid & 7;
;   const bf16r* Ap = o.A + (size_t)r0 * o.lda + sg * 8;
;   const bf16r* Bp = o.B + (size_t)r0 * o.ldb + sg * 8;
;   const int nk = K >> 6;
; #pragma unroll
;   for (int i = 0; i < 4; i++) {
;     *(u32x4*)(sbuf + (r0 + i * 32) * LDK + sg * 8) = g.a[i];
;     *(u32x4*)(sbuf + 128 * LDK + (r0 + i * 32) * LDK + sg * 8) = g.b[i];
;   }
;   if (nk > 1) {
; #pragma unroll
;     for (int i = 0; i < 4; i++) {
;       g.a[i] = *(const u32x4*)(Ap + (size_t)i * 32 * o.lda + 64);
;       g.b[i] = *(const u32x4*)(Bp + o.bs.o[i] + 64);
;     }
;   }
;   __syncthreads();
;   const int lane = tid & 63, fr = lane & 31, fh = lane >> 5;
;   for (int k = 0; k < nk; k++) {
;     bf16r* cur = sbuf + (k & 1) * (256 * LDK);
;     bf16r* nxt = sbuf + ((k & 1) ^ 1) * (256 * LDK);
;     const bf16r* As = cur + (wm * 64 + fr) * LDK + fh * 8;
;     const bf16r* Bs = cur + 128 * LDK + (wn * 64 + fr) * LDK + fh * 8;
;     const bool wr = (k + 1 < nk), ld = (k + 2 < nk);
;     bf16x8 fa[2][2], fb[2][2];
;     fa[0][0] = *(const bf16x8*)(As);
;     fa[0][1] = *(const bf16x8*)(As + 32 * LDK);
;     fb[0][0] = *(const bf16x8*)(Bs);
;     fb[0][1] = *(const bf16x8*)(Bs + 32 * LDK);
; #pragma unroll
;     for (int i = 0; i < 4; i++) {
;       if (wr) {
;         *(u32x4*)(nxt + (r0 + i * 32) * LDK + sg * 8) = g.a[i];
;         *(u32x4*)(nxt + 128 * LDK + (r0 + i * 32) * LDK + sg * 8) = g.b[i];
;       }
;       if (ld) {
;         g.a[i] = *(const u32x4*)(Ap + (size_t)i * 32 * o.lda + (k + 2) * 64);
;         g.b[i] = *(const u32x4*)(Bp + o.bs.o[i] + (k + 2) * 64);
;       }
;       if (i < 3) {
;         fa[(i + 1) & 1][0] = *(const bf16x8*)(As + (i + 1) * 16);
;         fa[(i + 1) & 1][1] = *(const bf16x8*)(As + 32 * LDK + (i + 1) * 16);
;         fb[(i + 1) & 1][0] = *(const bf16x8*)(Bs + (i + 1) * 16);
;         fb[(i + 1) & 1][1] = *(const bf16x8*)(Bs + 32 * LDK + (i + 1) * 16);
;       }
;       __builtin_amdgcn_sched_barrier(0);
;       __builtin_amdgcn_s_setprio(1);
;       acc[0][0] = __builtin_amdgcn_mfma_f32_32x32x16_bf16(fa[i & 1][0], fb[i & 1][0], acc[0][0], 0, 0, 0);
.LBB0_4797:
	v_lshl_add_u64 v[228:229], v[208:209], 0, v[138:139]
	s_waitcnt vmcnt(7)
	ds_write_b128 v132, v[64:67]
	s_waitcnt vmcnt(6)
	ds_write_b128 v132, v[68:71] offset:18432
	s_waitcnt vmcnt(5)
	ds_write_b128 v132, v[72:75] offset:4608
	s_waitcnt vmcnt(4)
	ds_write_b128 v132, v[76:79] offset:23040
	s_waitcnt vmcnt(3)
	ds_write_b128 v132, v[80:83] offset:9216
	s_waitcnt vmcnt(2)
	ds_write_b128 v132, v[84:87] offset:27648
	s_waitcnt vmcnt(1)
	ds_write_b128 v132, v[88:91] offset:13824
	s_waitcnt vmcnt(0)
	ds_write_b128 v132, v[92:95] offset:32256
	v_add_co_u32_e32 v76, vcc, s35, v228
	v_lshl_add_u64 v[226:227], v[206:207], 0, v[138:139]
	s_nop 0
	v_addc_co_u32_e32 v77, vcc, 0, v229, vcc
	v_add_co_u32_e32 v78, vcc, s36, v226
	global_load_dwordx4 v[0:3], v[76:77], off offset:128
	s_nop 0
	v_addc_co_u32_e32 v79, vcc, 0, v227, vcc
	v_add_co_u32_e32 v72, vcc, s37, v228
	global_load_dwordx4 v[4:7], v[78:79], off offset:128
	s_nop 0
	v_addc_co_u32_e32 v73, vcc, 0, v229, vcc
	v_add_co_u32_e32 v74, vcc, s38, v226
	global_load_dwordx4 v[80:83], v[72:73], off offset:128
	s_nop 0
	v_addc_co_u32_e32 v75, vcc, 0, v227, vcc
	v_add_co_u32_e32 v68, vcc, s39, v228
	global_load_dwordx4 v[84:87], v[74:75], off offset:128
	s_nop 0
	v_addc_co_u32_e32 v69, vcc, 0, v229, vcc
	v_add_co_u32_e32 v70, vcc, s40, v226
	global_load_dwordx4 v[88:91], v[68:69], off offset:128
	s_nop 0
	v_addc_co_u32_e32 v71, vcc, 0, v227, vcc
	v_add_co_u32_e32 v64, vcc, s41, v228
	global_load_dwordx4 v[92:95], v[70:71], off offset:128
	s_nop 0
	v_addc_co_u32_e32 v65, vcc, 0, v229, vcc
	v_add_co_u32_e32 v66, vcc, s42, v226
	global_load_dwordx4 v[96:99], v[64:65], off offset:128
	s_nop 0
	v_addc_co_u32_e32 v67, vcc, 0, v227, vcc
	global_load_dwordx4 v[100:103], v[66:67], off offset:128
	s_waitcnt lgkmcnt(0)
	s_barrier
	global_load_dwordx4 v[104:107], v[76:77], off offset:256
	global_load_dwordx4 v[108:111], v[78:79], off offset:256
	ds_read_b128 v[8:11], v136
	ds_read_b128 v[12:15], v136 offset:4608
	ds_read_b128 v[16:19], v133 offset:18432
	ds_read_b128 v[112:115], v133 offset:23040
	s_waitcnt vmcnt(9)
	ds_write_b128 v132, v[0:3] offset:36864
	s_waitcnt vmcnt(8)
	ds_write_b128 v132, v[4:7] offset:55296
	ds_read_b128 v[116:119], v136 offset:32
	ds_read_b128 v[120:123], v136 offset:4640
	ds_read_b128 v[124:127], v133 offset:18464
	ds_read_b128 v[232:235], v133 offset:23072
	s_waitcnt lgkmcnt(7)
	v_mfma_f32_32x32x16_bf16 v[48:63], v[8:11], v[16:19], 0
	s_waitcnt lgkmcnt(6)
	v_mfma_f32_32x32x16_bf16 v[32:47], v[8:11], v[112:115], 0
	v_mfma_f32_32x32x16_bf16 v[16:31], v[12:15], v[16:19], 0
	v_mfma_f32_32x32x16_bf16 v[0:15], v[12:15], v[112:115], 0
	global_load_dwordx4 v[112:115], v[72:73], off offset:256
	global_load_dwordx4 v[236:239], v[74:75], off offset:256
	s_waitcnt vmcnt(9)
	ds_write_b128 v132, v[80:83] offset:41472
	s_waitcnt vmcnt(8)
	ds_write_b128 v132, v[84:87] offset:59904
	ds_read_b128 v[80:83], v136 offset:64
	ds_read_b128 v[84:87], v136 offset:4672
	ds_read_b128 v[240:243], v133 offset:18496
	ds_read_b128 v[244:247], v133 offset:23104
	s_waitcnt lgkmcnt(7)
	v_mfma_f32_32x32x16_bf16 v[48:63], v[116:119], v[124:127], v[48:63]
	s_waitcnt lgkmcnt(6)
	v_mfma_f32_32x32x16_bf16 v[32:47], v[116:119], v[232:235], v[32:47]
	v_mfma_f32_32x32x16_bf16 v[16:31], v[120:123], v[124:127], v[16:31]
	v_mfma_f32_32x32x16_bf16 v[0:15], v[120:123], v[232:235], v[0:15]
	global_load_dwordx4 v[116:119], v[68:69], off offset:256
	global_load_dwordx4 v[120:123], v[70:71], off offset:256
	s_waitcnt vmcnt(9)
	ds_write_b128 v132, v[88:91] offset:46080
	s_waitcnt vmcnt(8)
	ds_write_b128 v132, v[92:95] offset:64512
	ds_read_b128 v[88:91], v136 offset:96
	ds_read_b128 v[92:95], v136 offset:4704
	ds_read_b128 v[124:127], v133 offset:18528
	ds_read_b128 v[232:235], v133 offset:23136
	s_waitcnt lgkmcnt(7)
	v_mfma_f32_32x32x16_bf16 v[48:63], v[80:83], v[240:243], v[48:63]
	s_waitcnt lgkmcnt(6)
	v_mfma_f32_32x32x16_bf16 v[32:47], v[80:83], v[244:247], v[32:47]
	v_mfma_f32_32x32x16_bf16 v[16:31], v[84:87], v[240:243], v[16:31]
	v_mfma_f32_32x32x16_bf16 v[0:15], v[84:87], v[244:247], v[0:15]
	global_load_dwordx4 v[80:83], v[64:65], off offset:256
	global_load_dwordx4 v[84:87], v[66:67], off offset:256
	s_waitcnt vmcnt(9)
	ds_write_b128 v132, v[96:99] offset:50688
	s_waitcnt vmcnt(8)
	ds_write_b128 v137, v[100:103] offset:13824
	s_waitcnt lgkmcnt(3)
	v_mfma_f32_32x32x16_bf16 v[48:63], v[88:91], v[124:127], v[48:63]
	s_waitcnt lgkmcnt(2)
	v_mfma_f32_32x32x16_bf16 v[32:47], v[88:91], v[232:235], v[32:47]
	v_mfma_f32_32x32x16_bf16 v[16:31], v[92:95], v[124:127], v[16:31]
	v_mfma_f32_32x32x16_bf16 v[0:15], v[92:95], v[232:235], v[0:15]
	s_waitcnt lgkmcnt(0)
	s_barrier
; __device__ __forceinline__ void gemm_run(int tid, f32x16 (&acc)[2][2], GRegs& g, const GOp& o, int K, unsigned char* smem) {
;     ...
;   for (int k = 0; k < nk; k++) {
;     bf16r* cur = sbuf + (k & 1) * (256 * LDK);
;     bf16r* nxt = sbuf + ((k & 1) ^ 1) * (256 * LDK);
;     const bf16r* As = cur + (wm * 64 + fr) * LDK + fh * 8;
;     const bf16r* Bs = cur + 128 * LDK + (wn * 64 + fr) * LDK + fh * 8;
;     const bool wr = (k + 1 < nk), ld = (k + 2 < nk);
;     bf16x8 fa[2][2], fb[2][2];
;     fa[0][0] = *(const bf16x8*)(As);
;     fa[0][1] = *(const bf16x8*)(As + 32 * LDK);
;     fb[0][0] = *(const bf16x8*)(Bs);
;     fb[0][1] = *(const bf16x8*)(Bs + 32 * LDK);
; #pragma unroll
;     for (int i = 0; i < 4; i++) {
;       if (wr) {
;         *(u32x4*)(nxt + (r0 + i * 32) * LDK + sg * 8) = g.a[i];
;         *(u32x4*)(nxt + 128 * LDK + (r0 + i * 32) * LDK + sg * 8) = g.b[i];
;       }
;       if (ld) {
;         g.a[i] = *(const u32x4*)(Ap + (size_t)i * 32 * o.lda + (k + 2) * 64);
;         g.b[i] = *(const u32x4*)(Bp + o.bs.o[i] + (k + 2) * 64);
;       }
;       if (i < 3) {
;         fa[(i + 1) & 1][0] = *(const bf16x8*)(As + (i + 1) * 16);
;         fa[(i + 1) & 1][1] = *(const bf16x8*)(As + 32 * LDK + (i + 1) * 16);
;         fb[(i + 1) & 1][0] = *(const bf16x8*)(Bs + (i + 1) * 16);
;         fb[(i + 1) & 1][1] = *(const bf16x8*)(Bs + 32 * LDK + (i + 1) * 16);
;       }
;       __builtin_amdgcn_sched_barrier(0);
;       __builtin_amdgcn_s_setprio(1);
;       acc[0][0] = __builtin_amdgcn_mfma_f32_32x32x16_bf16(fa[i & 1][0], fb[i & 1][0], acc[0][0], 0, 0, 0);
;       acc[0][1] = __builtin_amdgcn_mfma_f32_32x32x16_bf16(fa[i & 1][0], fb[i & 1][1], acc[0][1], 0, 0, 0);
;       acc[1][0] = __builtin_amdgcn_mfma_f32_32x32x16_bf16(fa[i & 1][1], fb[i & 1][0], acc[1][0], 0, 0, 0);
;       acc[1][1] = __builtin_amdgcn_mfma_f32_32x32x16_bf16(fa[i & 1][1], fb[i & 1][1], acc[1][1], 0, 0, 0);
;       __builtin_amdgcn_s_setprio(0);
;     }
;     __syncthreads();
;   }
	global_load_dwordx4 v[88:91], v[76:77], off offset:384
	global_load_dwordx4 v[92:95], v[78:79], off offset:384
	ds_read_b128 v[96:99], v136 offset:36864
	ds_read_b128 v[100:103], v136 offset:41472
	ds_read_b128 v[124:127], v133 offset:55296
	ds_read_b128 v[232:235], v133 offset:59904
	s_waitcnt vmcnt(9)
	ds_write_b128 v132, v[104:107]
	s_waitcnt vmcnt(8)
	ds_write_b128 v132, v[108:111] offset:18432
	ds_read_b128 v[104:107], v136 offset:36896
	ds_read_b128 v[108:111], v136 offset:41504
	ds_read_b128 v[240:243], v133 offset:55328
	ds_read_b128 v[244:247], v133 offset:59936
	s_waitcnt lgkmcnt(7)
	v_mfma_f32_32x32x16_bf16 v[48:63], v[96:99], v[124:127], v[48:63]
	s_waitcnt lgkmcnt(6)
	v_mfma_f32_32x32x16_bf16 v[32:47], v[96:99], v[232:235], v[32:47]
	v_mfma_f32_32x32x16_bf16 v[16:31], v[100:103], v[124:127], v[16:31]
	v_mfma_f32_32x32x16_bf16 v[0:15], v[100:103], v[232:235], v[0:15]
	global_load_dwordx4 v[96:99], v[72:73], off offset:384
	global_load_dwordx4 v[100:103], v[74:75], off offset:384
	s_waitcnt vmcnt(9)
	ds_write_b128 v132, v[112:115] offset:4608
	s_waitcnt vmcnt(8)
	ds_write_b128 v132, v[236:239] offset:23040
	ds_read_b128 v[112:115], v136 offset:36928
	ds_read_b128 v[124:127], v136 offset:41536
	ds_read_b128 v[232:235], v133 offset:55360
	ds_read_b128 v[236:239], v133 offset:59968
	s_waitcnt lgkmcnt(7)
	v_mfma_f32_32x32x16_bf16 v[48:63], v[104:107], v[240:243], v[48:63]
	s_waitcnt lgkmcnt(6)
	v_mfma_f32_32x32x16_bf16 v[32:47], v[104:107], v[244:247], v[32:47]
	v_mfma_f32_32x32x16_bf16 v[16:31], v[108:111], v[240:243], v[16:31]
	v_mfma_f32_32x32x16_bf16 v[0:15], v[108:111], v[244:247], v[0:15]
	global_load_dwordx4 v[104:107], v[68:69], off offset:384
	global_load_dwordx4 v[108:111], v[70:71], off offset:384
	s_waitcnt vmcnt(9)
	ds_write_b128 v132, v[116:119] offset:9216
	s_waitcnt vmcnt(8)
	ds_write_b128 v132, v[120:123] offset:27648
	ds_read_b128 v[116:119], v136 offset:36960
	ds_read_b128 v[120:123], v136 offset:41568
	ds_read_b128 v[240:243], v133 offset:55392
	ds_read_b128 v[244:247], v133 offset:60000
	s_waitcnt lgkmcnt(7)
	v_mfma_f32_32x32x16_bf16 v[48:63], v[112:115], v[232:235], v[48:63]
	s_waitcnt lgkmcnt(6)
	v_mfma_f32_32x32x16_bf16 v[32:47], v[112:115], v[236:239], v[32:47]
	v_mfma_f32_32x32x16_bf16 v[16:31], v[124:127], v[232:235], v[16:31]
	v_mfma_f32_32x32x16_bf16 v[0:15], v[124:127], v[236:239], v[0:15]
	global_load_dwordx4 v[112:115], v[64:65], off offset:384
	global_load_dwordx4 v[124:127], v[66:67], off offset:384
	s_waitcnt vmcnt(9)
	ds_write_b128 v132, v[80:83] offset:13824
	s_waitcnt vmcnt(8)
	ds_write_b128 v132, v[84:87] offset:32256
	s_waitcnt lgkmcnt(3)
	v_mfma_f32_32x32x16_bf16 v[48:63], v[116:119], v[240:243], v[48:63]
	s_waitcnt lgkmcnt(2)
	v_mfma_f32_32x32x16_bf16 v[32:47], v[116:119], v[244:247], v[32:47]
	v_mfma_f32_32x32x16_bf16 v[16:31], v[120:123], v[240:243], v[16:31]
	v_mfma_f32_32x32x16_bf16 v[0:15], v[120:123], v[244:247], v[0:15]
	s_waitcnt lgkmcnt(0)
	s_barrier
	global_load_dwordx4 v[80:83], v[76:77], off offset:512
	global_load_dwordx4 v[84:87], v[78:79], off offset:512
	ds_read_b128 v[116:119], v136
	ds_read_b128 v[120:123], v136 offset:4608
	ds_read_b128 v[232:235], v133 offset:18432
	ds_read_b128 v[236:239], v133 offset:23040
	s_waitcnt vmcnt(9)
	ds_write_b128 v132, v[88:91] offset:36864
	s_waitcnt vmcnt(8)
	ds_write_b128 v132, v[92:95] offset:55296
	ds_read_b128 v[88:91], v136 offset:32
	ds_read_b128 v[92:95], v136 offset:4640
	ds_read_b128 v[240:243], v133 offset:18464
	ds_read_b128 v[244:247], v133 offset:23072
	s_waitcnt lgkmcnt(7)
	v_mfma_f32_32x32x16_bf16 v[48:63], v[116:119], v[232:235], v[48:63]
	s_waitcnt lgkmcnt(6)
	v_mfma_f32_32x32x16_bf16 v[32:47], v[116:119], v[236:239], v[32:47]
	v_mfma_f32_32x32x16_bf16 v[16:31], v[120:123], v[232:235], v[16:31]
	v_mfma_f32_32x32x16_bf16 v[0:15], v[120:123], v[236:239], v[0:15]
	global_load_dwordx4 v[116:119], v[72:73], off offset:512
	global_load_dwordx4 v[120:123], v[74:75], off offset:512
	s_waitcnt vmcnt(9)
	ds_write_b128 v132, v[96:99] offset:41472
	s_waitcnt vmcnt(8)
	ds_write_b128 v132, v[100:103] offset:59904
	ds_read_b128 v[96:99], v136 offset:64
	ds_read_b128 v[100:103], v136 offset:4672
	ds_read_b128 v[232:235], v133 offset:18496
	ds_read_b128 v[236:239], v133 offset:23104
	s_waitcnt lgkmcnt(7)
	v_mfma_f32_32x32x16_bf16 v[48:63], v[88:91], v[240:243], v[48:63]
	s_waitcnt lgkmcnt(6)
	v_mfma_f32_32x32x16_bf16 v[32:47], v[88:91], v[244:247], v[32:47]
	v_mfma_f32_32x32x16_bf16 v[16:31], v[92:95], v[240:243], v[16:31]
	v_mfma_f32_32x32x16_bf16 v[0:15], v[92:95], v[244:247], v[0:15]
	global_load_dwordx4 v[88:91], v[68:69], off offset:512
	global_load_dwordx4 v[92:95], v[70:71], off offset:512
	s_waitcnt vmcnt(9)
	ds_write_b128 v132, v[104:107] offset:46080
	s_waitcnt vmcnt(8)
	ds_write_b128 v132, v[108:111] offset:64512
	ds_read_b128 v[104:107], v136 offset:96
	ds_read_b128 v[108:111], v136 offset:4704
	ds_read_b128 v[240:243], v133 offset:18528
	ds_read_b128 v[244:247], v133 offset:23136
	s_waitcnt lgkmcnt(7)
	v_mfma_f32_32x32x16_bf16 v[48:63], v[96:99], v[232:235], v[48:63]
	s_waitcnt lgkmcnt(6)
	v_mfma_f32_32x32x16_bf16 v[32:47], v[96:99], v[236:239], v[32:47]
	v_mfma_f32_32x32x16_bf16 v[16:31], v[100:103], v[232:235], v[16:31]
	v_mfma_f32_32x32x16_bf16 v[0:15], v[100:103], v[236:239], v[0:15]
	global_load_dwordx4 v[96:99], v[64:65], off offset:512
	global_load_dwordx4 v[100:103], v[66:67], off offset:512
	s_waitcnt vmcnt(9)
	ds_write_b128 v132, v[112:115] offset:50688
	s_waitcnt vmcnt(8)
	ds_write_b128 v137, v[124:127] offset:13824
	s_waitcnt lgkmcnt(3)
	v_mfma_f32_32x32x16_bf16 v[48:63], v[104:107], v[240:243], v[48:63]
	s_waitcnt lgkmcnt(2)
	v_mfma_f32_32x32x16_bf16 v[32:47], v[104:107], v[244:247], v[32:47]
	v_mfma_f32_32x32x16_bf16 v[16:31], v[108:111], v[240:243], v[16:31]
	v_mfma_f32_32x32x16_bf16 v[0:15], v[108:111], v[244:247], v[0:15]
	s_waitcnt lgkmcnt(0)
	s_barrier
; __device__ __forceinline__ void gemm_run(int tid, f32x16 (&acc)[2][2], GRegs& g, const GOp& o, int K, unsigned char* smem) {
;     ...
;   for (int k = 0; k < nk; k++) {
;     bf16r* cur = sbuf + (k & 1) * (256 * LDK);
;     bf16r* nxt = sbuf + ((k & 1) ^ 1) * (256 * LDK);
;     const bf16r* As = cur + (wm * 64 + fr) * LDK + fh * 8;
;     const bf16r* Bs = cur + 128 * LDK + (wn * 64 + fr) * LDK + fh * 8;
;     const bool wr = (k + 1 < nk), ld = (k + 2 < nk);
;     bf16x8 fa[2][2], fb[2][2];
;     fa[0][0] = *(const bf16x8*)(As);
;     fa[0][1] = *(const bf16x8*)(As + 32 * LDK);
;     fb[0][0] = *(const bf16x8*)(Bs);
;     fb[0][1] = *(const bf16x8*)(Bs + 32 * LDK);
; #pragma unroll
;     for (int i = 0; i < 4; i++) {
;       if (wr) {
;         *(u32x4*)(nxt + (r0 + i * 32) * LDK + sg * 8) = g.a[i];
;         *(u32x4*)(nxt + 128 * LDK + (r0 + i * 32) * LDK + sg * 8) = g.b[i];
;       }
;       if (ld) {
;         g.a[i] = *(const u32x4*)(Ap + (size_t)i * 32 * o.lda + (k + 2) * 64);
;         g.b[i] = *(const u32x4*)(Bp + o.bs.o[i] + (k + 2) * 64);
;       }
;       if (i < 3) {
;         fa[(i + 1) & 1][0] = *(const bf16x8*)(As + (i + 1) * 16);
;         fa[(i + 1) & 1][1] = *(const bf16x8*)(As + 32 * LDK + (i + 1) * 16);
;         fb[(i + 1) & 1][0] = *(const bf16x8*)(Bs + (i + 1) * 16);
;         fb[(i + 1) & 1][1] = *(const bf16x8*)(Bs + 32 * LDK + (i + 1) * 16);
;       }
;       __builtin_amdgcn_sched_barrier(0);
;       __builtin_amdgcn_s_setprio(1);
;       acc[0][0] = __builtin_amdgcn_mfma_f32_32x32x16_bf16(fa[i & 1][0], fb[i & 1][0], acc[0][0], 0, 0, 0);
;       acc[0][1] = __builtin_amdgcn_mfma_f32_32x32x16_bf16(fa[i & 1][0], fb[i & 1][1], acc[0][1], 0, 0, 0);
;       acc[1][0] = __builtin_amdgcn_mfma_f32_32x32x16_bf16(fa[i & 1][1], fb[i & 1][0], acc[1][0], 0, 0, 0);
;       acc[1][1] = __builtin_amdgcn_mfma_f32_32x32x16_bf16(fa[i & 1][1], fb[i & 1][1], acc[1][1], 0, 0, 0);
;       __builtin_amdgcn_s_setprio(0);
;     }
;     __syncthreads();
;   }
	global_load_dwordx4 v[104:107], v[76:77], off offset:640
	global_load_dwordx4 v[108:111], v[78:79], off offset:640
	ds_read_b128 v[112:115], v136 offset:36864
	ds_read_b128 v[124:127], v136 offset:41472
	ds_read_b128 v[232:235], v133 offset:55296
	ds_read_b128 v[236:239], v133 offset:59904
	s_waitcnt vmcnt(9)
	ds_write_b128 v132, v[80:83]
	s_waitcnt vmcnt(8)
	ds_write_b128 v132, v[84:87] offset:18432
	ds_read_b128 v[80:83], v136 offset:36896
	ds_read_b128 v[84:87], v136 offset:41504
	ds_read_b128 v[240:243], v133 offset:55328
	ds_read_b128 v[244:247], v133 offset:59936
	s_waitcnt lgkmcnt(7)
	v_mfma_f32_32x32x16_bf16 v[48:63], v[112:115], v[232:235], v[48:63]
	s_waitcnt lgkmcnt(6)
	v_mfma_f32_32x32x16_bf16 v[32:47], v[112:115], v[236:239], v[32:47]
	v_mfma_f32_32x32x16_bf16 v[16:31], v[124:127], v[232:235], v[16:31]
	v_mfma_f32_32x32x16_bf16 v[0:15], v[124:127], v[236:239], v[0:15]
	global_load_dwordx4 v[112:115], v[72:73], off offset:640
	global_load_dwordx4 v[124:127], v[74:75], off offset:640
	s_waitcnt vmcnt(9)
	ds_write_b128 v132, v[116:119] offset:4608
	s_waitcnt vmcnt(8)
	ds_write_b128 v132, v[120:123] offset:23040
	ds_read_b128 v[116:119], v136 offset:36928
	ds_read_b128 v[120:123], v136 offset:41536
	ds_read_b128 v[232:235], v133 offset:55360
	ds_read_b128 v[236:239], v133 offset:59968
	s_waitcnt lgkmcnt(7)
	v_mfma_f32_32x32x16_bf16 v[48:63], v[80:83], v[240:243], v[48:63]
	s_waitcnt lgkmcnt(6)
	v_mfma_f32_32x32x16_bf16 v[32:47], v[80:83], v[244:247], v[32:47]
	v_mfma_f32_32x32x16_bf16 v[16:31], v[84:87], v[240:243], v[16:31]
	v_mfma_f32_32x32x16_bf16 v[0:15], v[84:87], v[244:247], v[0:15]
	global_load_dwordx4 v[80:83], v[68:69], off offset:640
	global_load_dwordx4 v[84:87], v[70:71], off offset:640
	s_waitcnt vmcnt(9)
	ds_write_b128 v132, v[88:91] offset:9216
	s_waitcnt vmcnt(8)
	ds_write_b128 v132, v[92:95] offset:27648
	ds_read_b128 v[88:91], v136 offset:36960
	ds_read_b128 v[92:95], v136 offset:41568
	ds_read_b128 v[240:243], v133 offset:55392
	ds_read_b128 v[244:247], v133 offset:60000
	s_waitcnt lgkmcnt(7)
	v_mfma_f32_32x32x16_bf16 v[48:63], v[116:119], v[232:235], v[48:63]
	s_waitcnt lgkmcnt(6)
	v_mfma_f32_32x32x16_bf16 v[32:47], v[116:119], v[236:239], v[32:47]
	v_mfma_f32_32x32x16_bf16 v[16:31], v[120:123], v[232:235], v[16:31]
	v_mfma_f32_32x32x16_bf16 v[0:15], v[120:123], v[236:239], v[0:15]
	global_load_dwordx4 v[116:119], v[64:65], off offset:640
	global_load_dwordx4 v[120:123], v[66:67], off offset:640
	s_waitcnt vmcnt(9)
	ds_write_b128 v132, v[96:99] offset:13824
	s_waitcnt vmcnt(8)
	ds_write_b128 v132, v[100:103] offset:32256
	s_waitcnt lgkmcnt(3)
	v_mfma_f32_32x32x16_bf16 v[48:63], v[88:91], v[240:243], v[48:63]
	s_waitcnt lgkmcnt(2)
	v_mfma_f32_32x32x16_bf16 v[32:47], v[88:91], v[244:247], v[32:47]
	v_mfma_f32_32x32x16_bf16 v[16:31], v[92:95], v[240:243], v[16:31]
	v_mfma_f32_32x32x16_bf16 v[0:15], v[92:95], v[244:247], v[0:15]
	s_waitcnt lgkmcnt(0)
	s_barrier
	global_load_dwordx4 v[88:91], v[76:77], off offset:768
	global_load_dwordx4 v[92:95], v[78:79], off offset:768
	ds_read_b128 v[96:99], v136
	ds_read_b128 v[100:103], v136 offset:4608
	ds_read_b128 v[232:235], v133 offset:18432
	ds_read_b128 v[236:239], v133 offset:23040
	s_waitcnt vmcnt(9)
	ds_write_b128 v132, v[104:107] offset:36864
	s_waitcnt vmcnt(8)
	ds_write_b128 v132, v[108:111] offset:55296
	ds_read_b128 v[104:107], v136 offset:32
	ds_read_b128 v[108:111], v136 offset:4640
	ds_read_b128 v[240:243], v133 offset:18464
	ds_read_b128 v[244:247], v133 offset:23072
	s_waitcnt lgkmcnt(7)
	v_mfma_f32_32x32x16_bf16 v[48:63], v[96:99], v[232:235], v[48:63]
	s_waitcnt lgkmcnt(6)
	v_mfma_f32_32x32x16_bf16 v[32:47], v[96:99], v[236:239], v[32:47]
	v_mfma_f32_32x32x16_bf16 v[16:31], v[100:103], v[232:235], v[16:31]
	v_mfma_f32_32x32x16_bf16 v[0:15], v[100:103], v[236:239], v[0:15]
	global_load_dwordx4 v[96:99], v[72:73], off offset:768
	global_load_dwordx4 v[100:103], v[74:75], off offset:768
	s_waitcnt vmcnt(9)
	ds_write_b128 v132, v[112:115] offset:41472
	s_waitcnt vmcnt(8)
	ds_write_b128 v132, v[124:127] offset:59904
	ds_read_b128 v[112:115], v136 offset:64
	ds_read_b128 v[124:127], v136 offset:4672
	ds_read_b128 v[232:235], v133 offset:18496
	ds_read_b128 v[236:239], v133 offset:23104
	s_waitcnt lgkmcnt(7)
	v_mfma_f32_32x32x16_bf16 v[48:63], v[104:107], v[240:243], v[48:63]
	s_waitcnt lgkmcnt(6)
	v_mfma_f32_32x32x16_bf16 v[32:47], v[104:107], v[244:247], v[32:47]
	v_mfma_f32_32x32x16_bf16 v[16:31], v[108:111], v[240:243], v[16:31]
	v_mfma_f32_32x32x16_bf16 v[0:15], v[108:111], v[244:247], v[0:15]
	global_load_dwordx4 v[104:107], v[68:69], off offset:768
	global_load_dwordx4 v[108:111], v[70:71], off offset:768
	s_waitcnt vmcnt(9)
	ds_write_b128 v132, v[80:83] offset:46080
	s_waitcnt vmcnt(8)
	ds_write_b128 v132, v[84:87] offset:64512
	ds_read_b128 v[80:83], v136 offset:96
	ds_read_b128 v[84:87], v136 offset:4704
	ds_read_b128 v[240:243], v133 offset:18528
	ds_read_b128 v[244:247], v133 offset:23136
	s_waitcnt lgkmcnt(7)
	v_mfma_f32_32x32x16_bf16 v[48:63], v[112:115], v[232:235], v[48:63]
	s_waitcnt lgkmcnt(6)
	v_mfma_f32_32x32x16_bf16 v[32:47], v[112:115], v[236:239], v[32:47]
	v_mfma_f32_32x32x16_bf16 v[16:31], v[124:127], v[232:235], v[16:31]
	v_mfma_f32_32x32x16_bf16 v[0:15], v[124:127], v[236:239], v[0:15]
	global_load_dwordx4 v[112:115], v[64:65], off offset:768
	global_load_dwordx4 v[124:127], v[66:67], off offset:768
	s_waitcnt vmcnt(9)
	ds_write_b128 v132, v[116:119] offset:50688
	s_waitcnt vmcnt(8)
	ds_write_b128 v137, v[120:123] offset:13824
	s_waitcnt lgkmcnt(3)
	v_mfma_f32_32x32x16_bf16 v[48:63], v[80:83], v[240:243], v[48:63]
	s_waitcnt lgkmcnt(2)
	v_mfma_f32_32x32x16_bf16 v[32:47], v[80:83], v[244:247], v[32:47]
	v_mfma_f32_32x32x16_bf16 v[16:31], v[84:87], v[240:243], v[16:31]
	v_mfma_f32_32x32x16_bf16 v[0:15], v[84:87], v[244:247], v[0:15]
	s_waitcnt lgkmcnt(0)
	s_barrier
; __device__ __forceinline__ void gemm_run(int tid, f32x16 (&acc)[2][2], GRegs& g, const GOp& o, int K, unsigned char* smem) {
;     ...
;   for (int k = 0; k < nk; k++) {
;     bf16r* cur = sbuf + (k & 1) * (256 * LDK);
;     bf16r* nxt = sbuf + ((k & 1) ^ 1) * (256 * LDK);
;     const bf16r* As = cur + (wm * 64 + fr) * LDK + fh * 8;
;     const bf16r* Bs = cur + 128 * LDK + (wn * 64 + fr) * LDK + fh * 8;
;     const bool wr = (k + 1 < nk), ld = (k + 2 < nk);
;     bf16x8 fa[2][2], fb[2][2];
;     fa[0][0] = *(const bf16x8*)(As);
;     fa[0][1] = *(const bf16x8*)(As + 32 * LDK);
;     fb[0][0] = *(const bf16x8*)(Bs);
;     fb[0][1] = *(const bf16x8*)(Bs + 32 * LDK);
; #pragma unroll
;     for (int i = 0; i < 4; i++) {
;       if (wr) {
;         *(u32x4*)(nxt + (r0 + i * 32) * LDK + sg * 8) = g.a[i];
;         *(u32x4*)(nxt + 128 * LDK + (r0 + i * 32) * LDK + sg * 8) = g.b[i];
;       }
;       if (ld) {
;         g.a[i] = *(const u32x4*)(Ap + (size_t)i * 32 * o.lda + (k + 2) * 64);
;         g.b[i] = *(const u32x4*)(Bp + o.bs.o[i] + (k + 2) * 64);
;       }
;       if (i < 3) {
;         fa[(i + 1) & 1][0] = *(const bf16x8*)(As + (i + 1) * 16);
;         fa[(i + 1) & 1][1] = *(const bf16x8*)(As + 32 * LDK + (i + 1) * 16);
;         fb[(i + 1) & 1][0] = *(const bf16x8*)(Bs + (i + 1) * 16);
;         fb[(i + 1) & 1][1] = *(const bf16x8*)(Bs + 32 * LDK + (i + 1) * 16);
;       }
;       __builtin_amdgcn_sched_barrier(0);
;       __builtin_amdgcn_s_setprio(1);
;       acc[0][0] = __builtin_amdgcn_mfma_f32_32x32x16_bf16(fa[i & 1][0], fb[i & 1][0], acc[0][0], 0, 0, 0);
;       acc[0][1] = __builtin_amdgcn_mfma_f32_32x32x16_bf16(fa[i & 1][0], fb[i & 1][1], acc[0][1], 0, 0, 0);
;       acc[1][0] = __builtin_amdgcn_mfma_f32_32x32x16_bf16(fa[i & 1][1], fb[i & 1][0], acc[1][0], 0, 0, 0);
;       acc[1][1] = __builtin_amdgcn_mfma_f32_32x32x16_bf16(fa[i & 1][1], fb[i & 1][1], acc[1][1], 0, 0, 0);
;       __builtin_amdgcn_s_setprio(0);
;     }
;     __syncthreads();
;   }
	global_load_dwordx4 v[80:83], v[76:77], off offset:896
	global_load_dwordx4 v[84:87], v[78:79], off offset:896
	ds_read_b128 v[116:119], v136 offset:36864
	ds_read_b128 v[120:123], v136 offset:41472
	ds_read_b128 v[232:235], v133 offset:55296
	ds_read_b128 v[236:239], v133 offset:59904
	s_waitcnt vmcnt(9)
	ds_write_b128 v132, v[88:91]
	s_waitcnt vmcnt(8)
	ds_write_b128 v132, v[92:95] offset:18432
	ds_read_b128 v[88:91], v136 offset:36896
	ds_read_b128 v[92:95], v136 offset:41504
	ds_read_b128 v[240:243], v133 offset:55328
	ds_read_b128 v[244:247], v133 offset:59936
	s_waitcnt lgkmcnt(7)
	v_mfma_f32_32x32x16_bf16 v[48:63], v[116:119], v[232:235], v[48:63]
	s_waitcnt lgkmcnt(6)
	v_mfma_f32_32x32x16_bf16 v[32:47], v[116:119], v[236:239], v[32:47]
	v_mfma_f32_32x32x16_bf16 v[16:31], v[120:123], v[232:235], v[16:31]
	v_mfma_f32_32x32x16_bf16 v[0:15], v[120:123], v[236:239], v[0:15]
	global_load_dwordx4 v[116:119], v[72:73], off offset:896
	global_load_dwordx4 v[120:123], v[74:75], off offset:896
	s_waitcnt vmcnt(9)
	ds_write_b128 v132, v[96:99] offset:4608
	s_waitcnt vmcnt(8)
	ds_write_b128 v132, v[100:103] offset:23040
	ds_read_b128 v[96:99], v136 offset:36928
	ds_read_b128 v[100:103], v136 offset:41536
	ds_read_b128 v[232:235], v133 offset:55360
	ds_read_b128 v[236:239], v133 offset:59968
	s_waitcnt lgkmcnt(7)
	v_mfma_f32_32x32x16_bf16 v[48:63], v[88:91], v[240:243], v[48:63]
	s_waitcnt lgkmcnt(6)
	v_mfma_f32_32x32x16_bf16 v[32:47], v[88:91], v[244:247], v[32:47]
	v_mfma_f32_32x32x16_bf16 v[16:31], v[92:95], v[240:243], v[16:31]
	v_mfma_f32_32x32x16_bf16 v[0:15], v[92:95], v[244:247], v[0:15]
	global_load_dwordx4 v[88:91], v[68:69], off offset:896
	global_load_dwordx4 v[92:95], v[70:71], off offset:896
	s_waitcnt vmcnt(9)
	ds_write_b128 v132, v[104:107] offset:9216
	s_waitcnt vmcnt(8)
	ds_write_b128 v132, v[108:111] offset:27648
	ds_read_b128 v[104:107], v136 offset:36960
	ds_read_b128 v[108:111], v136 offset:41568
	ds_read_b128 v[240:243], v133 offset:55392
	ds_read_b128 v[244:247], v133 offset:60000
	s_waitcnt lgkmcnt(7)
	v_mfma_f32_32x32x16_bf16 v[48:63], v[96:99], v[232:235], v[48:63]
	s_waitcnt lgkmcnt(6)
	v_mfma_f32_32x32x16_bf16 v[32:47], v[96:99], v[236:239], v[32:47]
	v_mfma_f32_32x32x16_bf16 v[16:31], v[100:103], v[232:235], v[16:31]
	v_mfma_f32_32x32x16_bf16 v[0:15], v[100:103], v[236:239], v[0:15]
	global_load_dwordx4 v[96:99], v[64:65], off offset:896
	global_load_dwordx4 v[100:103], v[66:67], off offset:896
	s_waitcnt vmcnt(9)
	ds_write_b128 v132, v[112:115] offset:13824
	s_waitcnt vmcnt(8)
	ds_write_b128 v132, v[124:127] offset:32256
	s_waitcnt lgkmcnt(3)
	v_mfma_f32_32x32x16_bf16 v[48:63], v[104:107], v[240:243], v[48:63]
	s_waitcnt lgkmcnt(2)
	v_mfma_f32_32x32x16_bf16 v[32:47], v[104:107], v[244:247], v[32:47]
	v_mfma_f32_32x32x16_bf16 v[16:31], v[108:111], v[240:243], v[16:31]
	v_mfma_f32_32x32x16_bf16 v[0:15], v[108:111], v[244:247], v[0:15]
	s_waitcnt lgkmcnt(0)
	s_barrier
	global_load_dwordx4 v[104:107], v[76:77], off offset:1024
	global_load_dwordx4 v[108:111], v[78:79], off offset:1024
	ds_read_b128 v[112:115], v136
	ds_read_b128 v[124:127], v136 offset:4608
	ds_read_b128 v[232:235], v133 offset:18432
	ds_read_b128 v[236:239], v133 offset:23040
	s_waitcnt vmcnt(9)
	ds_write_b128 v132, v[80:83] offset:36864
	s_waitcnt vmcnt(8)
	ds_write_b128 v132, v[84:87] offset:55296
	ds_read_b128 v[80:83], v136 offset:32
	ds_read_b128 v[84:87], v136 offset:4640
	ds_read_b128 v[240:243], v133 offset:18464
	ds_read_b128 v[244:247], v133 offset:23072
	s_waitcnt lgkmcnt(7)
	v_mfma_f32_32x32x16_bf16 v[48:63], v[112:115], v[232:235], v[48:63]
	s_waitcnt lgkmcnt(6)
	v_mfma_f32_32x32x16_bf16 v[32:47], v[112:115], v[236:239], v[32:47]
	v_mfma_f32_32x32x16_bf16 v[16:31], v[124:127], v[232:235], v[16:31]
	v_mfma_f32_32x32x16_bf16 v[0:15], v[124:127], v[236:239], v[0:15]
	global_load_dwordx4 v[112:115], v[72:73], off offset:1024
	global_load_dwordx4 v[124:127], v[74:75], off offset:1024
	s_waitcnt vmcnt(9)
	ds_write_b128 v132, v[116:119] offset:41472
	s_waitcnt vmcnt(8)
	ds_write_b128 v132, v[120:123] offset:59904
	ds_read_b128 v[116:119], v136 offset:64
	ds_read_b128 v[120:123], v136 offset:4672
	ds_read_b128 v[232:235], v133 offset:18496
	ds_read_b128 v[236:239], v133 offset:23104
	s_waitcnt lgkmcnt(7)
	v_mfma_f32_32x32x16_bf16 v[48:63], v[80:83], v[240:243], v[48:63]
	s_waitcnt lgkmcnt(6)
	v_mfma_f32_32x32x16_bf16 v[32:47], v[80:83], v[244:247], v[32:47]
	v_mfma_f32_32x32x16_bf16 v[16:31], v[84:87], v[240:243], v[16:31]
	v_mfma_f32_32x32x16_bf16 v[0:15], v[84:87], v[244:247], v[0:15]
	global_load_dwordx4 v[80:83], v[68:69], off offset:1024
	global_load_dwordx4 v[84:87], v[70:71], off offset:1024
	s_waitcnt vmcnt(9)
	ds_write_b128 v132, v[88:91] offset:46080
	s_waitcnt vmcnt(8)
	ds_write_b128 v132, v[92:95] offset:64512
	ds_read_b128 v[88:91], v136 offset:96
	ds_read_b128 v[92:95], v136 offset:4704
	ds_read_b128 v[240:243], v133 offset:18528
	ds_read_b128 v[244:247], v133 offset:23136
	s_waitcnt lgkmcnt(7)
	v_mfma_f32_32x32x16_bf16 v[48:63], v[116:119], v[232:235], v[48:63]
	s_waitcnt lgkmcnt(6)
	v_mfma_f32_32x32x16_bf16 v[32:47], v[116:119], v[236:239], v[32:47]
	v_mfma_f32_32x32x16_bf16 v[16:31], v[120:123], v[232:235], v[16:31]
	v_mfma_f32_32x32x16_bf16 v[0:15], v[120:123], v[236:239], v[0:15]
	global_load_dwordx4 v[116:119], v[64:65], off offset:1024
	global_load_dwordx4 v[120:123], v[66:67], off offset:1024
	s_waitcnt vmcnt(9)
	ds_write_b128 v132, v[96:99] offset:50688
	s_waitcnt vmcnt(8)
	ds_write_b128 v137, v[100:103] offset:13824
	s_waitcnt lgkmcnt(3)
	v_mfma_f32_32x32x16_bf16 v[48:63], v[88:91], v[240:243], v[48:63]
	s_waitcnt lgkmcnt(2)
	v_mfma_f32_32x32x16_bf16 v[32:47], v[88:91], v[244:247], v[32:47]
	v_mfma_f32_32x32x16_bf16 v[16:31], v[92:95], v[240:243], v[16:31]
	v_mfma_f32_32x32x16_bf16 v[0:15], v[92:95], v[244:247], v[0:15]
	s_waitcnt lgkmcnt(0)
	s_barrier
; __device__ __forceinline__ void gemm_run(int tid, f32x16 (&acc)[2][2], GRegs& g, const GOp& o, int K, unsigned char* smem) {
;     ...
;   for (int k = 0; k < nk; k++) {
;     bf16r* cur = sbuf + (k & 1) * (256 * LDK);
;     bf16r* nxt = sbuf + ((k & 1) ^ 1) * (256 * LDK);
;     const bf16r* As = cur + (wm * 64 + fr) * LDK + fh * 8;
;     const bf16r* Bs = cur + 128 * LDK + (wn * 64 + fr) * LDK + fh * 8;
;     const bool wr = (k + 1 < nk), ld = (k + 2 < nk);
;     bf16x8 fa[2][2], fb[2][2];
;     fa[0][0] = *(const bf16x8*)(As);
;     fa[0][1] = *(const bf16x8*)(As + 32 * LDK);
;     fb[0][0] = *(const bf16x8*)(Bs);
;     fb[0][1] = *(const bf16x8*)(Bs + 32 * LDK);
; #pragma unroll
;     for (int i = 0; i < 4; i++) {
;       if (wr) {
;         *(u32x4*)(nxt + (r0 + i * 32) * LDK + sg * 8) = g.a[i];
;         *(u32x4*)(nxt + 128 * LDK + (r0 + i * 32) * LDK + sg * 8) = g.b[i];
;       }
;       if (ld) {
;         g.a[i] = *(const u32x4*)(Ap + (size_t)i * 32 * o.lda + (k + 2) * 64);
;         g.b[i] = *(const u32x4*)(Bp + o.bs.o[i] + (k + 2) * 64);
;       }
;       if (i < 3) {
;         fa[(i + 1) & 1][0] = *(const bf16x8*)(As + (i + 1) * 16);
;         fa[(i + 1) & 1][1] = *(const bf16x8*)(As + 32 * LDK + (i + 1) * 16);
;         fb[(i + 1) & 1][0] = *(const bf16x8*)(Bs + (i + 1) * 16);
;         fb[(i + 1) & 1][1] = *(const bf16x8*)(Bs + 32 * LDK + (i + 1) * 16);
;       }
;       __builtin_amdgcn_sched_barrier(0);
;       __builtin_amdgcn_s_setprio(1);
;       acc[0][0] = __builtin_amdgcn_mfma_f32_32x32x16_bf16(fa[i & 1][0], fb[i & 1][0], acc[0][0], 0, 0, 0);
;       acc[0][1] = __builtin_amdgcn_mfma_f32_32x32x16_bf16(fa[i & 1][0], fb[i & 1][1], acc[0][1], 0, 0, 0);
;       acc[1][0] = __builtin_amdgcn_mfma_f32_32x32x16_bf16(fa[i & 1][1], fb[i & 1][0], acc[1][0], 0, 0, 0);
;       acc[1][1] = __builtin_amdgcn_mfma_f32_32x32x16_bf16(fa[i & 1][1], fb[i & 1][1], acc[1][1], 0, 0, 0);
;       __builtin_amdgcn_s_setprio(0);
;     }
;     __syncthreads();
;   }
	global_load_dwordx4 v[88:91], v[76:77], off offset:1152
	global_load_dwordx4 v[92:95], v[78:79], off offset:1152
	ds_read_b128 v[96:99], v136 offset:36864
	ds_read_b128 v[100:103], v136 offset:41472
	ds_read_b128 v[232:235], v133 offset:55296
	ds_read_b128 v[236:239], v133 offset:59904
	s_waitcnt vmcnt(9)
	ds_write_b128 v132, v[104:107]
	s_waitcnt vmcnt(8)
	ds_write_b128 v132, v[108:111] offset:18432
	ds_read_b128 v[104:107], v136 offset:36896
	ds_read_b128 v[108:111], v136 offset:41504
	ds_read_b128 v[240:243], v133 offset:55328
	ds_read_b128 v[244:247], v133 offset:59936
	s_waitcnt lgkmcnt(7)
	v_mfma_f32_32x32x16_bf16 v[48:63], v[96:99], v[232:235], v[48:63]
	s_waitcnt lgkmcnt(6)
	v_mfma_f32_32x32x16_bf16 v[32:47], v[96:99], v[236:239], v[32:47]
	v_mfma_f32_32x32x16_bf16 v[16:31], v[100:103], v[232:235], v[16:31]
	v_mfma_f32_32x32x16_bf16 v[0:15], v[100:103], v[236:239], v[0:15]
	global_load_dwordx4 v[96:99], v[72:73], off offset:1152
	global_load_dwordx4 v[100:103], v[74:75], off offset:1152
	s_waitcnt vmcnt(9)
	ds_write_b128 v132, v[112:115] offset:4608
	s_waitcnt vmcnt(8)
	ds_write_b128 v132, v[124:127] offset:23040
	ds_read_b128 v[112:115], v136 offset:36928
	ds_read_b128 v[124:127], v136 offset:41536
	ds_read_b128 v[232:235], v133 offset:55360
	ds_read_b128 v[236:239], v133 offset:59968
	s_waitcnt lgkmcnt(7)
	v_mfma_f32_32x32x16_bf16 v[48:63], v[104:107], v[240:243], v[48:63]
	s_waitcnt lgkmcnt(6)
	v_mfma_f32_32x32x16_bf16 v[32:47], v[104:107], v[244:247], v[32:47]
	v_mfma_f32_32x32x16_bf16 v[16:31], v[108:111], v[240:243], v[16:31]
	v_mfma_f32_32x32x16_bf16 v[0:15], v[108:111], v[244:247], v[0:15]
	global_load_dwordx4 v[104:107], v[68:69], off offset:1152
	global_load_dwordx4 v[108:111], v[70:71], off offset:1152
	s_waitcnt vmcnt(9)
	ds_write_b128 v132, v[80:83] offset:9216
	s_waitcnt vmcnt(8)
	ds_write_b128 v132, v[84:87] offset:27648
	ds_read_b128 v[80:83], v136 offset:36960
	ds_read_b128 v[84:87], v136 offset:41568
	ds_read_b128 v[240:243], v133 offset:55392
	ds_read_b128 v[244:247], v133 offset:60000
	s_waitcnt lgkmcnt(7)
	v_mfma_f32_32x32x16_bf16 v[48:63], v[112:115], v[232:235], v[48:63]
	s_waitcnt lgkmcnt(6)
	v_mfma_f32_32x32x16_bf16 v[32:47], v[112:115], v[236:239], v[32:47]
	v_mfma_f32_32x32x16_bf16 v[16:31], v[124:127], v[232:235], v[16:31]
	v_mfma_f32_32x32x16_bf16 v[0:15], v[124:127], v[236:239], v[0:15]
	global_load_dwordx4 v[112:115], v[64:65], off offset:1152
	global_load_dwordx4 v[124:127], v[66:67], off offset:1152
	s_waitcnt vmcnt(9)
	ds_write_b128 v132, v[116:119] offset:13824
	s_waitcnt vmcnt(8)
	ds_write_b128 v132, v[120:123] offset:32256
	s_waitcnt lgkmcnt(3)
	v_mfma_f32_32x32x16_bf16 v[48:63], v[80:83], v[240:243], v[48:63]
	s_waitcnt lgkmcnt(2)
	v_mfma_f32_32x32x16_bf16 v[32:47], v[80:83], v[244:247], v[32:47]
	v_mfma_f32_32x32x16_bf16 v[16:31], v[84:87], v[240:243], v[16:31]
	v_mfma_f32_32x32x16_bf16 v[0:15], v[84:87], v[244:247], v[0:15]
	s_waitcnt lgkmcnt(0)
	s_barrier
	global_load_dwordx4 v[80:83], v[76:77], off offset:1280
	global_load_dwordx4 v[84:87], v[78:79], off offset:1280
	ds_read_b128 v[116:119], v136
	ds_read_b128 v[120:123], v136 offset:4608
	ds_read_b128 v[232:235], v133 offset:18432
	ds_read_b128 v[236:239], v133 offset:23040
	s_waitcnt vmcnt(9)
	ds_write_b128 v132, v[88:91] offset:36864
	s_waitcnt vmcnt(8)
	ds_write_b128 v132, v[92:95] offset:55296
	ds_read_b128 v[88:91], v136 offset:32
	ds_read_b128 v[92:95], v136 offset:4640
	ds_read_b128 v[240:243], v133 offset:18464
	ds_read_b128 v[244:247], v133 offset:23072
	s_waitcnt lgkmcnt(7)
	v_mfma_f32_32x32x16_bf16 v[48:63], v[116:119], v[232:235], v[48:63]
	s_waitcnt lgkmcnt(6)
	v_mfma_f32_32x32x16_bf16 v[32:47], v[116:119], v[236:239], v[32:47]
	v_mfma_f32_32x32x16_bf16 v[16:31], v[120:123], v[232:235], v[16:31]
	v_mfma_f32_32x32x16_bf16 v[0:15], v[120:123], v[236:239], v[0:15]
	global_load_dwordx4 v[116:119], v[72:73], off offset:1280
	global_load_dwordx4 v[120:123], v[74:75], off offset:1280
	s_waitcnt vmcnt(9)
	ds_write_b128 v132, v[96:99] offset:41472
	s_waitcnt vmcnt(8)
	ds_write_b128 v132, v[100:103] offset:59904
	ds_read_b128 v[96:99], v136 offset:64
	ds_read_b128 v[100:103], v136 offset:4672
	ds_read_b128 v[232:235], v133 offset:18496
	ds_read_b128 v[236:239], v133 offset:23104
	s_waitcnt lgkmcnt(7)
	v_mfma_f32_32x32x16_bf16 v[48:63], v[88:91], v[240:243], v[48:63]
	s_waitcnt lgkmcnt(6)
	v_mfma_f32_32x32x16_bf16 v[32:47], v[88:91], v[244:247], v[32:47]
	v_mfma_f32_32x32x16_bf16 v[16:31], v[92:95], v[240:243], v[16:31]
	v_mfma_f32_32x32x16_bf16 v[0:15], v[92:95], v[244:247], v[0:15]
	global_load_dwordx4 v[88:91], v[68:69], off offset:1280
	global_load_dwordx4 v[92:95], v[70:71], off offset:1280
	s_waitcnt vmcnt(9)
	ds_write_b128 v132, v[104:107] offset:46080
	s_waitcnt vmcnt(8)
	ds_write_b128 v132, v[108:111] offset:64512
	ds_read_b128 v[104:107], v136 offset:96
	ds_read_b128 v[108:111], v136 offset:4704
	ds_read_b128 v[240:243], v133 offset:18528
	ds_read_b128 v[244:247], v133 offset:23136
	s_waitcnt lgkmcnt(7)
	v_mfma_f32_32x32x16_bf16 v[48:63], v[96:99], v[232:235], v[48:63]
	s_waitcnt lgkmcnt(6)
	v_mfma_f32_32x32x16_bf16 v[32:47], v[96:99], v[236:239], v[32:47]
	v_mfma_f32_32x32x16_bf16 v[16:31], v[100:103], v[232:235], v[16:31]
	v_mfma_f32_32x32x16_bf16 v[0:15], v[100:103], v[236:239], v[0:15]
	global_load_dwordx4 v[96:99], v[64:65], off offset:1280
	global_load_dwordx4 v[100:103], v[66:67], off offset:1280
	s_waitcnt vmcnt(9)
	ds_write_b128 v132, v[112:115] offset:50688
	s_waitcnt vmcnt(8)
	ds_write_b128 v137, v[124:127] offset:13824
	s_waitcnt lgkmcnt(3)
	v_mfma_f32_32x32x16_bf16 v[48:63], v[104:107], v[240:243], v[48:63]
	s_waitcnt lgkmcnt(2)
	v_mfma_f32_32x32x16_bf16 v[32:47], v[104:107], v[244:247], v[32:47]
	v_mfma_f32_32x32x16_bf16 v[16:31], v[108:111], v[240:243], v[16:31]
	v_mfma_f32_32x32x16_bf16 v[0:15], v[108:111], v[244:247], v[0:15]
	s_waitcnt lgkmcnt(0)
	s_barrier
; __device__ __forceinline__ void gemm_run(int tid, f32x16 (&acc)[2][2], GRegs& g, const GOp& o, int K, unsigned char* smem) {
;     ...
;   for (int k = 0; k < nk; k++) {
;     bf16r* cur = sbuf + (k & 1) * (256 * LDK);
;     bf16r* nxt = sbuf + ((k & 1) ^ 1) * (256 * LDK);
;     const bf16r* As = cur + (wm * 64 + fr) * LDK + fh * 8;
;     const bf16r* Bs = cur + 128 * LDK + (wn * 64 + fr) * LDK + fh * 8;
;     const bool wr = (k + 1 < nk), ld = (k + 2 < nk);
;     bf16x8 fa[2][2], fb[2][2];
;     fa[0][0] = *(const bf16x8*)(As);
;     fa[0][1] = *(const bf16x8*)(As + 32 * LDK);
;     fb[0][0] = *(const bf16x8*)(Bs);
;     fb[0][1] = *(const bf16x8*)(Bs + 32 * LDK);
; #pragma unroll
;     for (int i = 0; i < 4; i++) {
;       if (wr) {
;         *(u32x4*)(nxt + (r0 + i * 32) * LDK + sg * 8) = g.a[i];
;         *(u32x4*)(nxt + 128 * LDK + (r0 + i * 32) * LDK + sg * 8) = g.b[i];
;       }
;       if (ld) {
;         g.a[i] = *(const u32x4*)(Ap + (size_t)i * 32 * o.lda + (k + 2) * 64);
;         g.b[i] = *(const u32x4*)(Bp + o.bs.o[i] + (k + 2) * 64);
;       }
;       if (i < 3) {
;         fa[(i + 1) & 1][0] = *(const bf16x8*)(As + (i + 1) * 16);
;         fa[(i + 1) & 1][1] = *(const bf16x8*)(As + 32 * LDK + (i + 1) * 16);
;         fb[(i + 1) & 1][0] = *(const bf16x8*)(Bs + (i + 1) * 16);
;         fb[(i + 1) & 1][1] = *(const bf16x8*)(Bs + 32 * LDK + (i + 1) * 16);
;       }
;       __builtin_amdgcn_sched_barrier(0);
;       __builtin_amdgcn_s_setprio(1);
;       acc[0][0] = __builtin_amdgcn_mfma_f32_32x32x16_bf16(fa[i & 1][0], fb[i & 1][0], acc[0][0], 0, 0, 0);
;       acc[0][1] = __builtin_amdgcn_mfma_f32_32x32x16_bf16(fa[i & 1][0], fb[i & 1][1], acc[0][1], 0, 0, 0);
;       acc[1][0] = __builtin_amdgcn_mfma_f32_32x32x16_bf16(fa[i & 1][1], fb[i & 1][0], acc[1][0], 0, 0, 0);
;       acc[1][1] = __builtin_amdgcn_mfma_f32_32x32x16_bf16(fa[i & 1][1], fb[i & 1][1], acc[1][1], 0, 0, 0);
;       __builtin_amdgcn_s_setprio(0);
;     }
;     __syncthreads();
;   }
	global_load_dwordx4 v[104:107], v[76:77], off offset:1408
	global_load_dwordx4 v[108:111], v[78:79], off offset:1408
	ds_read_b128 v[112:115], v136 offset:36864
	ds_read_b128 v[124:127], v136 offset:41472
	ds_read_b128 v[232:235], v133 offset:55296
	ds_read_b128 v[236:239], v133 offset:59904
	s_waitcnt vmcnt(9)
	ds_write_b128 v132, v[80:83]
	s_waitcnt vmcnt(8)
	ds_write_b128 v132, v[84:87] offset:18432
	ds_read_b128 v[80:83], v136 offset:36896
	ds_read_b128 v[84:87], v136 offset:41504
	ds_read_b128 v[240:243], v133 offset:55328
	ds_read_b128 v[244:247], v133 offset:59936
	s_waitcnt lgkmcnt(7)
	v_mfma_f32_32x32x16_bf16 v[48:63], v[112:115], v[232:235], v[48:63]
	s_waitcnt lgkmcnt(6)
	v_mfma_f32_32x32x16_bf16 v[32:47], v[112:115], v[236:239], v[32:47]
	v_mfma_f32_32x32x16_bf16 v[16:31], v[124:127], v[232:235], v[16:31]
	v_mfma_f32_32x32x16_bf16 v[0:15], v[124:127], v[236:239], v[0:15]
	global_load_dwordx4 v[112:115], v[72:73], off offset:1408
	global_load_dwordx4 v[124:127], v[74:75], off offset:1408
	s_waitcnt vmcnt(9)
	ds_write_b128 v132, v[116:119] offset:4608
	s_waitcnt vmcnt(8)
	ds_write_b128 v132, v[120:123] offset:23040
	ds_read_b128 v[116:119], v136 offset:36928
	ds_read_b128 v[120:123], v136 offset:41536
	ds_read_b128 v[232:235], v133 offset:55360
	ds_read_b128 v[236:239], v133 offset:59968
	s_waitcnt lgkmcnt(7)
	v_mfma_f32_32x32x16_bf16 v[48:63], v[80:83], v[240:243], v[48:63]
	s_waitcnt lgkmcnt(6)
	v_mfma_f32_32x32x16_bf16 v[32:47], v[80:83], v[244:247], v[32:47]
	v_mfma_f32_32x32x16_bf16 v[16:31], v[84:87], v[240:243], v[16:31]
	v_mfma_f32_32x32x16_bf16 v[0:15], v[84:87], v[244:247], v[0:15]
	global_load_dwordx4 v[80:83], v[68:69], off offset:1408
	global_load_dwordx4 v[84:87], v[70:71], off offset:1408
	s_waitcnt vmcnt(9)
	ds_write_b128 v132, v[88:91] offset:9216
	s_waitcnt vmcnt(8)
	ds_write_b128 v132, v[92:95] offset:27648
	ds_read_b128 v[88:91], v136 offset:36960
	ds_read_b128 v[92:95], v136 offset:41568
	ds_read_b128 v[240:243], v133 offset:55392
	ds_read_b128 v[244:247], v133 offset:60000
	s_waitcnt lgkmcnt(7)
	v_mfma_f32_32x32x16_bf16 v[48:63], v[116:119], v[232:235], v[48:63]
	s_waitcnt lgkmcnt(6)
	v_mfma_f32_32x32x16_bf16 v[32:47], v[116:119], v[236:239], v[32:47]
	v_mfma_f32_32x32x16_bf16 v[16:31], v[120:123], v[232:235], v[16:31]
	v_mfma_f32_32x32x16_bf16 v[0:15], v[120:123], v[236:239], v[0:15]
	global_load_dwordx4 v[116:119], v[64:65], off offset:1408
	global_load_dwordx4 v[120:123], v[66:67], off offset:1408
	s_waitcnt vmcnt(9)
	ds_write_b128 v132, v[96:99] offset:13824
	s_waitcnt vmcnt(8)
	ds_write_b128 v132, v[100:103] offset:32256
	s_waitcnt lgkmcnt(3)
	v_mfma_f32_32x32x16_bf16 v[48:63], v[88:91], v[240:243], v[48:63]
	s_waitcnt lgkmcnt(2)
	v_mfma_f32_32x32x16_bf16 v[32:47], v[88:91], v[244:247], v[32:47]
	v_mfma_f32_32x32x16_bf16 v[16:31], v[92:95], v[240:243], v[16:31]
	v_mfma_f32_32x32x16_bf16 v[0:15], v[92:95], v[244:247], v[0:15]
	s_waitcnt lgkmcnt(0)
	s_barrier
	global_load_dwordx4 v[88:91], v[76:77], off offset:1536
	global_load_dwordx4 v[92:95], v[78:79], off offset:1536
	ds_read_b128 v[96:99], v136
	ds_read_b128 v[100:103], v136 offset:4608
	ds_read_b128 v[232:235], v133 offset:18432
	ds_read_b128 v[236:239], v133 offset:23040
	s_waitcnt vmcnt(9)
	ds_write_b128 v132, v[104:107] offset:36864
	s_waitcnt vmcnt(8)
	ds_write_b128 v132, v[108:111] offset:55296
	ds_read_b128 v[104:107], v136 offset:32
	ds_read_b128 v[108:111], v136 offset:4640
	ds_read_b128 v[240:243], v133 offset:18464
	ds_read_b128 v[244:247], v133 offset:23072
	s_waitcnt lgkmcnt(7)
	v_mfma_f32_32x32x16_bf16 v[48:63], v[96:99], v[232:235], v[48:63]
	s_waitcnt lgkmcnt(6)
	v_mfma_f32_32x32x16_bf16 v[32:47], v[96:99], v[236:239], v[32:47]
	v_mfma_f32_32x32x16_bf16 v[16:31], v[100:103], v[232:235], v[16:31]
	v_mfma_f32_32x32x16_bf16 v[0:15], v[100:103], v[236:239], v[0:15]
	global_load_dwordx4 v[96:99], v[72:73], off offset:1536
	global_load_dwordx4 v[100:103], v[74:75], off offset:1536
	s_waitcnt vmcnt(9)
	ds_write_b128 v132, v[112:115] offset:41472
	s_waitcnt vmcnt(8)
	ds_write_b128 v132, v[124:127] offset:59904
	ds_read_b128 v[112:115], v136 offset:64
	ds_read_b128 v[124:127], v136 offset:4672
	ds_read_b128 v[232:235], v133 offset:18496
	ds_read_b128 v[236:239], v133 offset:23104
	s_waitcnt lgkmcnt(7)
	v_mfma_f32_32x32x16_bf16 v[48:63], v[104:107], v[240:243], v[48:63]
	s_waitcnt lgkmcnt(6)
	v_mfma_f32_32x32x16_bf16 v[32:47], v[104:107], v[244:247], v[32:47]
	v_mfma_f32_32x32x16_bf16 v[16:31], v[108:111], v[240:243], v[16:31]
	v_mfma_f32_32x32x16_bf16 v[0:15], v[108:111], v[244:247], v[0:15]
	global_load_dwordx4 v[104:107], v[68:69], off offset:1536
	global_load_dwordx4 v[108:111], v[70:71], off offset:1536
	s_waitcnt vmcnt(9)
	ds_write_b128 v132, v[80:83] offset:46080
	s_waitcnt vmcnt(8)
	ds_write_b128 v132, v[84:87] offset:64512
	ds_read_b128 v[80:83], v136 offset:96
	ds_read_b128 v[84:87], v136 offset:4704
	ds_read_b128 v[240:243], v133 offset:18528
	ds_read_b128 v[244:247], v133 offset:23136
	s_waitcnt lgkmcnt(7)
	v_mfma_f32_32x32x16_bf16 v[48:63], v[112:115], v[232:235], v[48:63]
	s_waitcnt lgkmcnt(6)
	v_mfma_f32_32x32x16_bf16 v[32:47], v[112:115], v[236:239], v[32:47]
	v_mfma_f32_32x32x16_bf16 v[16:31], v[124:127], v[232:235], v[16:31]
	v_mfma_f32_32x32x16_bf16 v[0:15], v[124:127], v[236:239], v[0:15]
	global_load_dwordx4 v[112:115], v[64:65], off offset:1536
	global_load_dwordx4 v[124:127], v[66:67], off offset:1536
	s_waitcnt vmcnt(9)
	ds_write_b128 v132, v[116:119] offset:50688
	s_waitcnt vmcnt(8)
	ds_write_b128 v137, v[120:123] offset:13824
	s_waitcnt lgkmcnt(3)
	v_mfma_f32_32x32x16_bf16 v[48:63], v[80:83], v[240:243], v[48:63]
	s_waitcnt lgkmcnt(2)
	v_mfma_f32_32x32x16_bf16 v[32:47], v[80:83], v[244:247], v[32:47]
	v_mfma_f32_32x32x16_bf16 v[16:31], v[84:87], v[240:243], v[16:31]
	v_mfma_f32_32x32x16_bf16 v[0:15], v[84:87], v[244:247], v[0:15]
	s_waitcnt lgkmcnt(0)
	s_barrier
; __device__ __forceinline__ void gemm_run(int tid, f32x16 (&acc)[2][2], GRegs& g, const GOp& o, int K, unsigned char* smem) {
;     ...
;   for (int k = 0; k < nk; k++) {
;     bf16r* cur = sbuf + (k & 1) * (256 * LDK);
;     bf16r* nxt = sbuf + ((k & 1) ^ 1) * (256 * LDK);
;     const bf16r* As = cur + (wm * 64 + fr) * LDK + fh * 8;
;     const bf16r* Bs = cur + 128 * LDK + (wn * 64 + fr) * LDK + fh * 8;
;     const bool wr = (k + 1 < nk), ld = (k + 2 < nk);
;     bf16x8 fa[2][2], fb[2][2];
;     fa[0][0] = *(const bf16x8*)(As);
;     fa[0][1] = *(const bf16x8*)(As + 32 * LDK);
;     fb[0][0] = *(const bf16x8*)(Bs);
;     fb[0][1] = *(const bf16x8*)(Bs + 32 * LDK);
; #pragma unroll
;     for (int i = 0; i < 4; i++) {
;       if (wr) {
;         *(u32x4*)(nxt + (r0 + i * 32) * LDK + sg * 8) = g.a[i];
;         *(u32x4*)(nxt + 128 * LDK + (r0 + i * 32) * LDK + sg * 8) = g.b[i];
;       }
;       if (ld) {
;         g.a[i] = *(const u32x4*)(Ap + (size_t)i * 32 * o.lda + (k + 2) * 64);
;         g.b[i] = *(const u32x4*)(Bp + o.bs.o[i] + (k + 2) * 64);
;       }
;       if (i < 3) {
;         fa[(i + 1) & 1][0] = *(const bf16x8*)(As + (i + 1) * 16);
;         fa[(i + 1) & 1][1] = *(const bf16x8*)(As + 32 * LDK + (i + 1) * 16);
;         fb[(i + 1) & 1][0] = *(const bf16x8*)(Bs + (i + 1) * 16);
;         fb[(i + 1) & 1][1] = *(const bf16x8*)(Bs + 32 * LDK + (i + 1) * 16);
;       }
;       __builtin_amdgcn_sched_barrier(0);
;       __builtin_amdgcn_s_setprio(1);
;       acc[0][0] = __builtin_amdgcn_mfma_f32_32x32x16_bf16(fa[i & 1][0], fb[i & 1][0], acc[0][0], 0, 0, 0);
;       acc[0][1] = __builtin_amdgcn_mfma_f32_32x32x16_bf16(fa[i & 1][0], fb[i & 1][1], acc[0][1], 0, 0, 0);
;       acc[1][0] = __builtin_amdgcn_mfma_f32_32x32x16_bf16(fa[i & 1][1], fb[i & 1][0], acc[1][0], 0, 0, 0);
;       acc[1][1] = __builtin_amdgcn_mfma_f32_32x32x16_bf16(fa[i & 1][1], fb[i & 1][1], acc[1][1], 0, 0, 0);
;       __builtin_amdgcn_s_setprio(0);
;     }
;     __syncthreads();
;   }
	global_load_dwordx4 v[80:83], v[76:77], off offset:1664
	global_load_dwordx4 v[84:87], v[78:79], off offset:1664
	ds_read_b128 v[116:119], v136 offset:36864
	ds_read_b128 v[120:123], v136 offset:41472
	ds_read_b128 v[232:235], v133 offset:55296
	ds_read_b128 v[236:239], v133 offset:59904
	s_waitcnt vmcnt(9)
	ds_write_b128 v132, v[88:91]
	s_waitcnt vmcnt(8)
	ds_write_b128 v132, v[92:95] offset:18432
	ds_read_b128 v[88:91], v136 offset:36896
	ds_read_b128 v[92:95], v136 offset:41504
	ds_read_b128 v[240:243], v133 offset:55328
	ds_read_b128 v[244:247], v133 offset:59936
	s_waitcnt lgkmcnt(7)
	v_mfma_f32_32x32x16_bf16 v[48:63], v[116:119], v[232:235], v[48:63]
	s_waitcnt lgkmcnt(6)
	v_mfma_f32_32x32x16_bf16 v[32:47], v[116:119], v[236:239], v[32:47]
	v_mfma_f32_32x32x16_bf16 v[16:31], v[120:123], v[232:235], v[16:31]
	v_mfma_f32_32x32x16_bf16 v[0:15], v[120:123], v[236:239], v[0:15]
	global_load_dwordx4 v[116:119], v[72:73], off offset:1664
	global_load_dwordx4 v[120:123], v[74:75], off offset:1664
	s_waitcnt vmcnt(9)
	ds_write_b128 v132, v[96:99] offset:4608
	s_waitcnt vmcnt(8)
	ds_write_b128 v132, v[100:103] offset:23040
	ds_read_b128 v[96:99], v136 offset:36928
	ds_read_b128 v[100:103], v136 offset:41536
	ds_read_b128 v[232:235], v133 offset:55360
	ds_read_b128 v[236:239], v133 offset:59968
	s_waitcnt lgkmcnt(7)
	v_mfma_f32_32x32x16_bf16 v[48:63], v[88:91], v[240:243], v[48:63]
	s_waitcnt lgkmcnt(6)
	v_mfma_f32_32x32x16_bf16 v[32:47], v[88:91], v[244:247], v[32:47]
	v_mfma_f32_32x32x16_bf16 v[16:31], v[92:95], v[240:243], v[16:31]
	v_mfma_f32_32x32x16_bf16 v[0:15], v[92:95], v[244:247], v[0:15]
	global_load_dwordx4 v[88:91], v[68:69], off offset:1664
	global_load_dwordx4 v[92:95], v[70:71], off offset:1664
	s_waitcnt vmcnt(9)
	ds_write_b128 v132, v[104:107] offset:9216
	s_waitcnt vmcnt(8)
	ds_write_b128 v132, v[108:111] offset:27648
	ds_read_b128 v[104:107], v136 offset:36960
	ds_read_b128 v[108:111], v136 offset:41568
	ds_read_b128 v[240:243], v133 offset:55392
	ds_read_b128 v[244:247], v133 offset:60000
	s_waitcnt lgkmcnt(7)
	v_mfma_f32_32x32x16_bf16 v[48:63], v[96:99], v[232:235], v[48:63]
	s_waitcnt lgkmcnt(6)
	v_mfma_f32_32x32x16_bf16 v[32:47], v[96:99], v[236:239], v[32:47]
	v_mfma_f32_32x32x16_bf16 v[16:31], v[100:103], v[232:235], v[16:31]
	v_mfma_f32_32x32x16_bf16 v[0:15], v[100:103], v[236:239], v[0:15]
	global_load_dwordx4 v[96:99], v[64:65], off offset:1664
	global_load_dwordx4 v[100:103], v[66:67], off offset:1664
	s_waitcnt vmcnt(9)
	ds_write_b128 v132, v[112:115] offset:13824
	s_waitcnt vmcnt(8)
	ds_write_b128 v132, v[124:127] offset:32256
	s_waitcnt lgkmcnt(3)
	v_mfma_f32_32x32x16_bf16 v[48:63], v[104:107], v[240:243], v[48:63]
	s_waitcnt lgkmcnt(2)
	v_mfma_f32_32x32x16_bf16 v[32:47], v[104:107], v[244:247], v[32:47]
	v_mfma_f32_32x32x16_bf16 v[16:31], v[108:111], v[240:243], v[16:31]
	v_mfma_f32_32x32x16_bf16 v[0:15], v[108:111], v[244:247], v[0:15]
	s_waitcnt lgkmcnt(0)
	s_barrier
	global_load_dwordx4 v[104:107], v[76:77], off offset:1792
	global_load_dwordx4 v[108:111], v[78:79], off offset:1792
	ds_read_b128 v[112:115], v136
	ds_read_b128 v[124:127], v136 offset:4608
	ds_read_b128 v[232:235], v133 offset:18432
	ds_read_b128 v[236:239], v133 offset:23040
	s_waitcnt vmcnt(9)
	ds_write_b128 v132, v[80:83] offset:36864
	s_waitcnt vmcnt(8)
	ds_write_b128 v132, v[84:87] offset:55296
	ds_read_b128 v[80:83], v136 offset:32
	ds_read_b128 v[84:87], v136 offset:4640
	ds_read_b128 v[240:243], v133 offset:18464
	ds_read_b128 v[244:247], v133 offset:23072
	s_waitcnt lgkmcnt(7)
	v_mfma_f32_32x32x16_bf16 v[48:63], v[112:115], v[232:235], v[48:63]
	s_waitcnt lgkmcnt(6)
	v_mfma_f32_32x32x16_bf16 v[32:47], v[112:115], v[236:239], v[32:47]
	v_mfma_f32_32x32x16_bf16 v[16:31], v[124:127], v[232:235], v[16:31]
	v_mfma_f32_32x32x16_bf16 v[0:15], v[124:127], v[236:239], v[0:15]
	global_load_dwordx4 v[112:115], v[72:73], off offset:1792
	global_load_dwordx4 v[124:127], v[74:75], off offset:1792
	s_waitcnt vmcnt(9)
	ds_write_b128 v132, v[116:119] offset:41472
	s_waitcnt vmcnt(8)
	ds_write_b128 v132, v[120:123] offset:59904
	ds_read_b128 v[116:119], v136 offset:64
	ds_read_b128 v[120:123], v136 offset:4672
	ds_read_b128 v[232:235], v133 offset:18496
	ds_read_b128 v[236:239], v133 offset:23104
	s_waitcnt lgkmcnt(7)
	v_mfma_f32_32x32x16_bf16 v[48:63], v[80:83], v[240:243], v[48:63]
	s_waitcnt lgkmcnt(6)
	v_mfma_f32_32x32x16_bf16 v[32:47], v[80:83], v[244:247], v[32:47]
	v_mfma_f32_32x32x16_bf16 v[16:31], v[84:87], v[240:243], v[16:31]
	v_mfma_f32_32x32x16_bf16 v[0:15], v[84:87], v[244:247], v[0:15]
	global_load_dwordx4 v[80:83], v[68:69], off offset:1792
	global_load_dwordx4 v[84:87], v[70:71], off offset:1792
	s_waitcnt vmcnt(9)
	ds_write_b128 v132, v[88:91] offset:46080
	s_waitcnt vmcnt(8)
	ds_write_b128 v132, v[92:95] offset:64512
	ds_read_b128 v[88:91], v136 offset:96
	ds_read_b128 v[92:95], v136 offset:4704
	ds_read_b128 v[240:243], v133 offset:18528
	ds_read_b128 v[244:247], v133 offset:23136
	s_waitcnt lgkmcnt(7)
	v_mfma_f32_32x32x16_bf16 v[48:63], v[116:119], v[232:235], v[48:63]
	s_waitcnt lgkmcnt(6)
	v_mfma_f32_32x32x16_bf16 v[32:47], v[116:119], v[236:239], v[32:47]
	v_mfma_f32_32x32x16_bf16 v[16:31], v[120:123], v[232:235], v[16:31]
	v_mfma_f32_32x32x16_bf16 v[0:15], v[120:123], v[236:239], v[0:15]
	global_load_dwordx4 v[232:235], v[64:65], off offset:1792
	global_load_dwordx4 v[236:239], v[66:67], off offset:1792
	s_waitcnt vmcnt(9)
	ds_write_b128 v132, v[96:99] offset:50688
	s_waitcnt vmcnt(8)
	ds_write_b128 v137, v[100:103] offset:13824
	s_waitcnt lgkmcnt(3)
	v_mfma_f32_32x32x16_bf16 v[48:63], v[88:91], v[240:243], v[48:63]
	s_waitcnt lgkmcnt(2)
	v_mfma_f32_32x32x16_bf16 v[32:47], v[88:91], v[244:247], v[32:47]
	v_mfma_f32_32x32x16_bf16 v[16:31], v[92:95], v[240:243], v[16:31]
	v_mfma_f32_32x32x16_bf16 v[0:15], v[92:95], v[244:247], v[0:15]
	s_waitcnt lgkmcnt(0)
	s_barrier
; __device__ __forceinline__ void gemm_run(int tid, f32x16 (&acc)[2][2], GRegs& g, const GOp& o, int K, unsigned char* smem) {
;     ...
;   for (int k = 0; k < nk; k++) {
;     bf16r* cur = sbuf + (k & 1) * (256 * LDK);
;     bf16r* nxt = sbuf + ((k & 1) ^ 1) * (256 * LDK);
;     const bf16r* As = cur + (wm * 64 + fr) * LDK + fh * 8;
;     const bf16r* Bs = cur + 128 * LDK + (wn * 64 + fr) * LDK + fh * 8;
;     const bool wr = (k + 1 < nk), ld = (k + 2 < nk);
;     bf16x8 fa[2][2], fb[2][2];
;     fa[0][0] = *(const bf16x8*)(As);
;     fa[0][1] = *(const bf16x8*)(As + 32 * LDK);
;     fb[0][0] = *(const bf16x8*)(Bs);
;     fb[0][1] = *(const bf16x8*)(Bs + 32 * LDK);
; #pragma unroll
;     for (int i = 0; i < 4; i++) {
;       if (wr) {
;         *(u32x4*)(nxt + (r0 + i * 32) * LDK + sg * 8) = g.a[i];
;         *(u32x4*)(nxt + 128 * LDK + (r0 + i * 32) * LDK + sg * 8) = g.b[i];
;       }
;       if (ld) {
;         g.a[i] = *(const u32x4*)(Ap + (size_t)i * 32 * o.lda + (k + 2) * 64);
;         g.b[i] = *(const u32x4*)(Bp + o.bs.o[i] + (k + 2) * 64);
;       }
;       if (i < 3) {
;         fa[(i + 1) & 1][0] = *(const bf16x8*)(As + (i + 1) * 16);
;         fa[(i + 1) & 1][1] = *(const bf16x8*)(As + 32 * LDK + (i + 1) * 16);
;         fb[(i + 1) & 1][0] = *(const bf16x8*)(Bs + (i + 1) * 16);
;         fb[(i + 1) & 1][1] = *(const bf16x8*)(Bs + 32 * LDK + (i + 1) * 16);
;       }
;       __builtin_amdgcn_sched_barrier(0);
;       __builtin_amdgcn_s_setprio(1);
;       acc[0][0] = __builtin_amdgcn_mfma_f32_32x32x16_bf16(fa[i & 1][0], fb[i & 1][0], acc[0][0], 0, 0, 0);
;       acc[0][1] = __builtin_amdgcn_mfma_f32_32x32x16_bf16(fa[i & 1][0], fb[i & 1][1], acc[0][1], 0, 0, 0);
;       acc[1][0] = __builtin_amdgcn_mfma_f32_32x32x16_bf16(fa[i & 1][1], fb[i & 1][0], acc[1][0], 0, 0, 0);
;       acc[1][1] = __builtin_amdgcn_mfma_f32_32x32x16_bf16(fa[i & 1][1], fb[i & 1][1], acc[1][1], 0, 0, 0);
;       __builtin_amdgcn_s_setprio(0);
;     }
;     __syncthreads();
;   }
	global_load_dwordx4 v[100:103], v[76:77], off offset:1920
	global_load_dwordx4 v[96:99], v[78:79], off offset:1920
	ds_read_b128 v[76:79], v136 offset:36864
	ds_read_b128 v[88:91], v136 offset:41472
	ds_read_b128 v[92:95], v133 offset:55296
	ds_read_b128 v[116:119], v133 offset:59904
	s_waitcnt vmcnt(9)
	ds_write_b128 v132, v[104:107]
	s_waitcnt vmcnt(8)
	ds_write_b128 v132, v[108:111] offset:18432
	ds_read_b128 v[120:123], v136 offset:36896
	ds_read_b128 v[240:243], v136 offset:41504
	ds_read_b128 v[244:247], v133 offset:55328
	ds_read_b128 v[248:251], v133 offset:59936
	s_waitcnt lgkmcnt(7)
	v_mfma_f32_32x32x16_bf16 v[48:63], v[76:79], v[92:95], v[48:63]
	s_waitcnt lgkmcnt(6)
	v_mfma_f32_32x32x16_bf16 v[32:47], v[76:79], v[116:119], v[32:47]
	v_mfma_f32_32x32x16_bf16 v[16:31], v[88:91], v[92:95], v[16:31]
	v_mfma_f32_32x32x16_bf16 v[0:15], v[88:91], v[116:119], v[0:15]
	global_load_dwordx4 v[108:111], v[72:73], off offset:1920
	global_load_dwordx4 v[104:107], v[74:75], off offset:1920
	s_waitcnt vmcnt(9)
	ds_write_b128 v132, v[112:115] offset:4608
	s_waitcnt vmcnt(8)
	ds_write_b128 v132, v[124:127] offset:23040
	ds_read_b128 v[72:75], v136 offset:36928
	ds_read_b128 v[76:79], v136 offset:41536
	ds_read_b128 v[88:91], v133 offset:55360
	ds_read_b128 v[92:95], v133 offset:59968
	s_waitcnt lgkmcnt(7)
	v_mfma_f32_32x32x16_bf16 v[48:63], v[120:123], v[244:247], v[48:63]
	s_waitcnt lgkmcnt(6)
	v_mfma_f32_32x32x16_bf16 v[32:47], v[120:123], v[248:251], v[32:47]
	v_mfma_f32_32x32x16_bf16 v[16:31], v[240:243], v[244:247], v[16:31]
	v_mfma_f32_32x32x16_bf16 v[0:15], v[240:243], v[248:251], v[0:15]
	global_load_dwordx4 v[116:119], v[68:69], off offset:1920
	global_load_dwordx4 v[112:115], v[70:71], off offset:1920
	s_waitcnt vmcnt(9)
	ds_write_b128 v132, v[80:83] offset:9216
	s_waitcnt vmcnt(8)
	ds_write_b128 v132, v[84:87] offset:27648
	ds_read_b128 v[68:71], v136 offset:36960
	ds_read_b128 v[80:83], v136 offset:41568
	ds_read_b128 v[84:87], v133 offset:55392
	ds_read_b128 v[240:243], v133 offset:60000
	s_waitcnt lgkmcnt(7)
	v_mfma_f32_32x32x16_bf16 v[48:63], v[72:75], v[88:91], v[48:63]
	s_waitcnt lgkmcnt(6)
	v_mfma_f32_32x32x16_bf16 v[32:47], v[72:75], v[92:95], v[32:47]
	v_mfma_f32_32x32x16_bf16 v[16:31], v[76:79], v[88:91], v[16:31]
	v_mfma_f32_32x32x16_bf16 v[0:15], v[76:79], v[92:95], v[0:15]
	global_load_dwordx4 v[124:127], v[64:65], off offset:1920
	global_load_dwordx4 v[120:123], v[66:67], off offset:1920
	s_waitcnt vmcnt(9)
	ds_write_b128 v132, v[232:235] offset:13824
	s_waitcnt vmcnt(8)
	ds_write_b128 v132, v[236:239] offset:32256
	s_waitcnt lgkmcnt(3)
	v_mfma_f32_32x32x16_bf16 v[48:63], v[68:71], v[84:87], v[48:63]
	s_waitcnt lgkmcnt(2)
	v_mfma_f32_32x32x16_bf16 v[32:47], v[68:71], v[240:243], v[32:47]
	v_mfma_f32_32x32x16_bf16 v[16:31], v[80:83], v[84:87], v[16:31]
	v_mfma_f32_32x32x16_bf16 v[0:15], v[80:83], v[240:243], v[0:15]
	s_waitcnt lgkmcnt(0)
	s_barrier
	ds_read_b128 v[64:67], v136
	ds_read_b128 v[68:71], v136 offset:4608
	ds_read_b128 v[72:75], v133 offset:18432
	ds_read_b128 v[76:79], v133 offset:23040
	s_waitcnt vmcnt(7)
	ds_write_b128 v132, v[100:103] offset:36864
	s_waitcnt vmcnt(6)
	ds_write_b128 v132, v[96:99] offset:55296
	ds_read_b128 v[80:83], v136 offset:32
	ds_read_b128 v[84:87], v136 offset:4640
	ds_read_b128 v[88:91], v133 offset:18464
	ds_read_b128 v[92:95], v133 offset:23072
	s_waitcnt lgkmcnt(7)
	v_mfma_f32_32x32x16_bf16 v[48:63], v[64:67], v[72:75], v[48:63]
	s_waitcnt lgkmcnt(6)
	v_mfma_f32_32x32x16_bf16 v[32:47], v[64:67], v[76:79], v[32:47]
	v_mfma_f32_32x32x16_bf16 v[16:31], v[68:71], v[72:75], v[16:31]
	v_mfma_f32_32x32x16_bf16 v[0:15], v[68:71], v[76:79], v[0:15]
	s_waitcnt vmcnt(5)
	ds_write_b128 v132, v[108:111] offset:41472
	s_waitcnt vmcnt(4)
	ds_write_b128 v132, v[104:107] offset:59904
	ds_read_b128 v[64:67], v136 offset:64
	ds_read_b128 v[68:71], v136 offset:4672
	ds_read_b128 v[72:75], v133 offset:18496
	ds_read_b128 v[76:79], v133 offset:23104
	s_waitcnt lgkmcnt(7)
	v_mfma_f32_32x32x16_bf16 v[48:63], v[80:83], v[88:91], v[48:63]
	s_waitcnt lgkmcnt(6)
	v_mfma_f32_32x32x16_bf16 v[32:47], v[80:83], v[92:95], v[32:47]
	v_mfma_f32_32x32x16_bf16 v[16:31], v[84:87], v[88:91], v[16:31]
	v_mfma_f32_32x32x16_bf16 v[0:15], v[84:87], v[92:95], v[0:15]
	s_waitcnt vmcnt(3)
	ds_write_b128 v132, v[116:119] offset:46080
	s_waitcnt vmcnt(2)
	ds_write_b128 v132, v[112:115] offset:64512
	ds_read_b128 v[80:83], v136 offset:96
	ds_read_b128 v[84:87], v136 offset:4704
	ds_read_b128 v[88:91], v133 offset:18528
	ds_read_b128 v[92:95], v133 offset:23136
	s_waitcnt lgkmcnt(7)
	v_mfma_f32_32x32x16_bf16 v[48:63], v[64:67], v[72:75], v[48:63]
	s_waitcnt lgkmcnt(6)
	v_mfma_f32_32x32x16_bf16 v[32:47], v[64:67], v[76:79], v[32:47]
	v_mfma_f32_32x32x16_bf16 v[16:31], v[68:71], v[72:75], v[16:31]
	v_mfma_f32_32x32x16_bf16 v[0:15], v[68:71], v[76:79], v[0:15]
	s_waitcnt vmcnt(1)
	ds_write_b128 v132, v[124:127] offset:50688
	s_waitcnt vmcnt(0)
	ds_write_b128 v137, v[120:123] offset:13824
	s_waitcnt lgkmcnt(3)
	v_mfma_f32_32x32x16_bf16 v[48:63], v[80:83], v[88:91], v[48:63]
	s_waitcnt lgkmcnt(2)
	v_mfma_f32_32x32x16_bf16 v[32:47], v[80:83], v[92:95], v[32:47]
	v_mfma_f32_32x32x16_bf16 v[16:31], v[84:87], v[88:91], v[16:31]
	v_mfma_f32_32x32x16_bf16 v[0:15], v[84:87], v[92:95], v[0:15]
	s_waitcnt lgkmcnt(0)
	s_barrier
; __device__ __forceinline__ void gemm_issue0(int tid, GRegs& g, const GOp& o) {
;   const int r0 = tid >> 3, sg = tid & 7;
;   const bf16r* Ap = o.A + (size_t)r0 * o.lda + sg * 8;
;   const bf16r* Bp = o.B + (size_t)r0 * o.ldb + sg * 8;
; #pragma unroll
;   for (int i = 0; i < 4; i++) {
;     g.a[i] = *(const u32x4*)(Ap + (size_t)i * 32 * o.lda);
;     g.b[i] = *(const u32x4*)(Bp + o.bs.o[i]);
;   }
; }
; __device__ __forceinline__ void gemm_run(int tid, f32x16 (&acc)[2][2], GRegs& g, const GOp& o, int K, unsigned char* smem) {
;     ...
;   for (int k = 0; k < nk; k++) {
;     bf16r* cur = sbuf + (k & 1) * (256 * LDK);
;     bf16r* nxt = sbuf + ((k & 1) ^ 1) * (256 * LDK);
;     const bf16r* As = cur + (wm * 64 + fr) * LDK + fh * 8;
;     const bf16r* Bs = cur + 128 * LDK + (wn * 64 + fr) * LDK + fh * 8;
;     const bool wr = (k + 1 < nk), ld = (k + 2 < nk);
;     bf16x8 fa[2][2], fb[2][2];
;     fa[0][0] = *(const bf16x8*)(As);
;     fa[0][1] = *(const bf16x8*)(As + 32 * LDK);
;     fb[0][0] = *(const bf16x8*)(Bs);
;     fb[0][1] = *(const bf16x8*)(Bs + 32 * LDK);
; #pragma unroll
;     for (int i = 0; i < 4; i++) {
;       if (wr) {
;         *(u32x4*)(nxt + (r0 + i * 32) * LDK + sg * 8) = g.a[i];
;         *(u32x4*)(nxt + 128 * LDK + (r0 + i * 32) * LDK + sg * 8) = g.b[i];
;       }
;       if (ld) {
;         g.a[i] = *(const u32x4*)(Ap + (size_t)i * 32 * o.lda + (k + 2) * 64);
;         g.b[i] = *(const u32x4*)(Bp + o.bs.o[i] + (k + 2) * 64);
;       }
;       if (i < 3) {
;         fa[(i + 1) & 1][0] = *(const bf16x8*)(As + (i + 1) * 16);
;         fa[(i + 1) & 1][1] = *(const bf16x8*)(As + 32 * LDK + (i + 1) * 16);
;         fb[(i + 1) & 1][0] = *(const bf16x8*)(Bs + (i + 1) * 16);
;         fb[(i + 1) & 1][1] = *(const bf16x8*)(Bs + 32 * LDK + (i + 1) * 16);
;       }
;       __builtin_amdgcn_sched_barrier(0);
;       __builtin_amdgcn_s_setprio(1);
;       acc[0][0] = __builtin_amdgcn_mfma_f32_32x32x16_bf16(fa[i & 1][0], fb[i & 1][0], acc[0][0], 0, 0, 0);
;       acc[0][1] = __builtin_amdgcn_mfma_f32_32x32x16_bf16(fa[i & 1][0], fb[i & 1][1], acc[0][1], 0, 0, 0);
;       acc[1][0] = __builtin_amdgcn_mfma_f32_32x32x16_bf16(fa[i & 1][1], fb[i & 1][0], acc[1][0], 0, 0, 0);
;       acc[1][1] = __builtin_amdgcn_mfma_f32_32x32x16_bf16(fa[i & 1][1], fb[i & 1][1], acc[1][1], 0, 0, 0);
;       __builtin_amdgcn_s_setprio(0);
;     }
;     __syncthreads();
	ds_read_b128 v[64:67], v136 offset:36864
	ds_read_b128 v[68:71], v136 offset:36896
	ds_read_b128 v[72:75], v136 offset:41472
	ds_read_b128 v[76:79], v136 offset:41504
	ds_read_b128 v[80:83], v133 offset:55296
	ds_read_b128 v[84:87], v133 offset:55328
	ds_read_b128 v[88:91], v133 offset:59904
	ds_read_b128 v[92:95], v133 offset:59936
	s_waitcnt lgkmcnt(3)
	v_mfma_f32_32x32x16_bf16 v[48:63], v[64:67], v[80:83], v[48:63]
	s_waitcnt lgkmcnt(1)
	v_mfma_f32_32x32x16_bf16 v[32:47], v[64:67], v[88:91], v[32:47]
	v_mfma_f32_32x32x16_bf16 v[16:31], v[72:75], v[80:83], v[16:31]
	v_mfma_f32_32x32x16_bf16 v[0:15], v[72:75], v[88:91], v[0:15]
	ds_read_b128 v[64:67], v136 offset:36928
	ds_read_b128 v[72:75], v136 offset:41536
	ds_read_b128 v[80:83], v133 offset:55360
	ds_read_b128 v[88:91], v133 offset:59968
	v_mfma_f32_32x32x16_bf16 v[48:63], v[68:71], v[84:87], v[48:63]
	s_waitcnt lgkmcnt(4)
	v_mfma_f32_32x32x16_bf16 v[32:47], v[68:71], v[92:95], v[32:47]
	v_mfma_f32_32x32x16_bf16 v[16:31], v[76:79], v[84:87], v[16:31]
	v_mfma_f32_32x32x16_bf16 v[0:15], v[76:79], v[92:95], v[0:15]
	ds_read_b128 v[68:71], v136 offset:36960
	ds_read_b128 v[76:79], v136 offset:41568
	ds_read_b128 v[84:87], v133 offset:55392
	ds_read_b128 v[92:95], v133 offset:60000
	s_waitcnt lgkmcnt(5)
	v_mfma_f32_32x32x16_bf16 v[48:63], v[64:67], v[80:83], v[48:63]
	s_waitcnt lgkmcnt(4)
	v_mfma_f32_32x32x16_bf16 v[32:47], v[64:67], v[88:91], v[32:47]
	v_mfma_f32_32x32x16_bf16 v[16:31], v[72:75], v[80:83], v[16:31]
	v_mfma_f32_32x32x16_bf16 v[0:15], v[72:75], v[88:91], v[0:15]
	s_waitcnt lgkmcnt(1)
	v_mfma_f32_32x32x16_bf16 v[48:63], v[68:71], v[84:87], v[48:63]
	s_waitcnt lgkmcnt(0)
	v_mfma_f32_32x32x16_bf16 v[32:47], v[68:71], v[92:95], v[32:47]
	v_mfma_f32_32x32x16_bf16 v[16:31], v[76:79], v[84:87], v[16:31]
	v_mfma_f32_32x32x16_bf16 v[0:15], v[76:79], v[92:95], v[0:15]
	s_cmp_eq_u32 s48, 3
	s_mov_b64 s[24:25], -1
	s_barrier
	s_cbranch_scc1 .LBB0_4799
	v_add_co_u32_e32 v64, vcc, 0xbdc0000, v228
	s_mov_b64 s[24:25], 0
	s_nop 0
	v_addc_co_u32_e32 v65, vcc, 0, v229, vcc
	v_add_co_u32_e32 v68, vcc, 0x8500000, v226
	global_load_dwordx4 v[64:67], v[64:65], off
	s_nop 0
	v_addc_co_u32_e32 v69, vcc, 0, v227, vcc
	v_add_co_u32_e32 v72, vcc, 0xbdd0000, v228
	global_load_dwordx4 v[68:71], v[68:69], off
	s_nop 0
	v_addc_co_u32_e32 v73, vcc, 0, v229, vcc
	v_add_co_u32_e32 v76, vcc, 0x8510000, v226
	global_load_dwordx4 v[72:75], v[72:73], off
	s_nop 0
	v_addc_co_u32_e32 v77, vcc, 0, v227, vcc
	v_add_co_u32_e32 v80, vcc, 0xbde0000, v228
	global_load_dwordx4 v[76:79], v[76:77], off
	s_nop 0
	v_addc_co_u32_e32 v81, vcc, 0, v229, vcc
	v_add_co_u32_e32 v84, vcc, 0x8520000, v226
	global_load_dwordx4 v[80:83], v[80:81], off
	s_nop 0
	v_addc_co_u32_e32 v85, vcc, 0, v227, vcc
	v_add_co_u32_e32 v88, vcc, 0xbdf0000, v228
	global_load_dwordx4 v[84:87], v[84:85], off
	s_nop 0
	v_addc_co_u32_e32 v89, vcc, 0, v229, vcc
	v_add_co_u32_e32 v92, vcc, 0x8530000, v226
	global_load_dwordx4 v[88:91], v[88:89], off
	s_nop 0
	v_addc_co_u32_e32 v93, vcc, 0, v227, vcc
	global_load_dwordx4 v[92:95], v[92:93], off
